# v31 + sc1 write-through on all GEMM-epilogue and norm-pass producer stores
# baseline (speedup 1.0000x reference)
; __device__ __forceinline__ float bflo(unsigned w) { return __uint_as_float(w << 16); }
; __device__ __forceinline__ float bfhi(unsigned w) { return __uint_as_float(w & 0xffff0000u); }
; __device__ __forceinline__ unsigned pkbf(float lo, float hi) { return pg8::cvt_pk_bf16(lo, hi); }
; __device__ __forceinline__ void norm_row(const float* src, const bf16_t* add, const float* gain, bf16_t* ob, float* of, int lane) {
;     f32x4 v[4]; float s = 0.f;
; #pragma unroll
;     for (int j = 0; j < 4; ++j) { v[j] = *((const f32x4*)src + lane + 64 * j);
;         if (add) { const u32x2 d = *((const u32x2*)add + lane + 64 * j); v[j][0] += bflo(d.x); v[j][1] += bfhi(d.x); v[j][2] += bflo(d.y); v[j][3] += bfhi(d.y); }
;         s += (v[j][0] * v[j][0] + v[j][1] * v[j][1]) + (v[j][2] * v[j][2] + v[j][3] * v[j][3]); }
;     const float rstd = 1.0f / sqrtf(wave_sum(s) * (1.f / DM) + NORM_EPS);
; #pragma unroll
;     for (int j = 0; j < 4; ++j) { const f32x4 g = *((const f32x4*)gain + lane + 64 * j); const f32x4 o = v[j] * rstd * g;
;         if (ob) { u32x2 w; w.x = pkbf(o[0], o[1]); w.y = pkbf(o[2], o[3]); *((u32x2*)ob + lane + 64 * j) = w; }
;         else *((f32x4*)of + lane + 64 * j) = o; }
; }
; __global__ void __launch_bounds__(512, 2) mega_fwd(const Args a) {
;     ...
;     for (int m = gw; m < T; m += NGW) norm_row(xrow(p, m), nullptr, p.in[2], XN + (size_t)m * DM, nullptr, lane);
.LBB0_71:
	s_add_i32 s0, s6, 0xffff8000
	s_cmp_lt_i32 s6, 0x8000
	s_cselect_b32 s1, s7, 0
	s_cselect_b32 s0, s6, s0
	s_cselect_b32 s8, s17, s19
	s_cselect_b32 s9, s16, s18
	s_lshl_b64 s[0:1], s[0:1], 12
	s_add_u32 s0, s9, s0
	s_addc_u32 s1, s8, s1
	global_load_dwordx4 v[14:17], v11, s[0:1] nt
	global_load_dwordx4 v[18:21], v11, s[0:1] offset:1024 nt
	global_load_dwordx4 v[22:25], v11, s[0:1] offset:2048 nt
	global_load_dwordx4 v[26:29], v11, s[0:1] offset:3072 nt
	global_load_dwordx4 v[30:33], v[2:3], off
	s_add_u32 s6, s6, s88
	s_addc_u32 s7, s7, s89
	s_cmp_gt_i32 s6, 0xbfff
	s_waitcnt vmcnt(4)
	v_pk_mul_f32 v[34:35], v[16:17], v[16:17]
	v_pk_mul_f32 v[36:37], v[14:15], v[14:15]
	s_waitcnt vmcnt(3)
	v_pk_mul_f32 v[38:39], v[20:21], v[20:21]
	v_pk_mul_f32 v[40:41], v[18:19], v[18:19]
	v_pk_mov_b32 v[46:47], v[36:37], v[34:35] op_sel:[1,0]
	v_mov_b32_e32 v37, v35
	v_pk_mov_b32 v[34:35], v[40:41], v[38:39] op_sel:[1,0]
	v_mov_b32_e32 v41, v39
	s_waitcnt vmcnt(1)
	v_mul_f32_e32 v45, v26, v26
	v_mul_f32_e32 v42, v23, v23
	v_mul_f32_e32 v44, v25, v25
	v_pk_add_f32 v[36:37], v[46:47], v[36:37]
	v_pk_add_f32 v[34:35], v[34:35], v[40:41]
	v_mul_f32_e32 v48, v27, v27
	v_mul_f32_e32 v49, v28, v28
	v_mul_f32_e32 v50, v29, v29
	v_pk_fma_f32 v[38:39], v[22:23], v[22:23], v[42:43] op_sel_hi:[1,1,0]
	v_pk_fma_f32 v[42:43], v[24:25], v[24:25], v[44:45] op_sel_hi:[1,1,0]
	v_pk_add_f32 v[36:37], v[36:37], v[36:37] op_sel:[0,1] op_sel_hi:[1,0]
	v_pk_add_f32 v[34:35], v[34:35], v[34:35] op_sel:[0,1] op_sel_hi:[1,0]
	v_mov_b32_e32 v39, v49
	v_mov_b32_e32 v43, v50
	v_mov_b32_e32 v37, v45
	v_mov_b32_e32 v35, v48
	v_pk_add_f32 v[38:39], v[38:39], v[42:43]
	v_pk_add_f32 v[34:35], v[36:37], v[34:35]
	s_nop 0
	v_pk_add_f32 v[34:35], v[34:35], v[38:39]
	s_nop 0
	v_add_f32_e32 v34, v34, v35
	ds_bpermute_b32 v35, v1, v34
	s_waitcnt lgkmcnt(0)
	v_add_f32_e32 v34, v34, v35
	ds_bpermute_b32 v35, v6, v34
	s_waitcnt lgkmcnt(0)
	v_add_f32_e32 v34, v34, v35
	ds_bpermute_b32 v35, v7, v34
	s_waitcnt lgkmcnt(0)
	v_add_f32_e32 v34, v34, v35
	ds_bpermute_b32 v35, v8, v34
	s_waitcnt lgkmcnt(0)
	v_add_f32_e32 v34, v34, v35
	ds_bpermute_b32 v35, v9, v34
	s_waitcnt lgkmcnt(0)
	v_add_f32_e32 v34, v34, v35
	ds_bpermute_b32 v35, v10, v34
	s_waitcnt lgkmcnt(0)
	v_add_f32_e32 v34, v34, v35
	v_fmamk_f32 v34, v34, 0x3a800000, v12
	v_mul_f32_e32 v35, 0x4f800000, v34
	v_cmp_gt_f32_e32 vcc, s3, v34
	s_nop 1
	v_cndmask_b32_e32 v34, v34, v35, vcc
	v_sqrt_f32_e32 v35, v34
	s_nop 0
	v_add_u32_e32 v36, -1, v35
	v_add_u32_e32 v37, 1, v35
	v_fma_f32 v38, -v36, v35, v34
	v_fma_f32 v39, -v37, v35, v34
	v_cmp_ge_f32_e64 s[0:1], 0, v38
	s_nop 1
	v_cndmask_b32_e64 v35, v35, v36, s[0:1]
	v_cmp_lt_f32_e64 s[0:1], 0, v39
	s_nop 1
	v_cndmask_b32_e64 v35, v35, v37, s[0:1]
	v_mul_f32_e32 v36, 0x37800000, v35
	v_cndmask_b32_e32 v35, v35, v36, vcc
	v_cmp_class_f32_e32 vcc, v34, v13
	s_nop 1
	v_cndmask_b32_e32 v34, v35, v34, vcc
	v_div_scale_f32 v35, s[0:1], v34, v34, 1.0
	v_rcp_f32_e32 v37, v35
	v_div_scale_f32 v36, vcc, 1.0, v34, 1.0
	v_fma_f32 v38, -v35, v37, 1.0
	v_fmac_f32_e32 v37, v38, v37
	v_mul_f32_e32 v38, v36, v37
	v_fma_f32 v39, -v35, v38, v36
	v_fmac_f32_e32 v38, v39, v37
	v_fma_f32 v35, -v35, v38, v36
	v_div_fmas_f32 v35, v35, v37, v38
	v_div_fixup_f32 v34, v35, v34, 1.0
	v_pk_mul_f32 v[14:15], v[14:15], v[34:35] op_sel_hi:[1,0]
	v_pk_mul_f32 v[16:17], v[16:17], v[34:35] op_sel_hi:[1,0]
	s_waitcnt vmcnt(0)
	v_pk_mul_f32 v[14:15], v[30:31], v[14:15]
	v_pk_mul_f32 v[16:17], v[32:33], v[16:17]
	v_cvt_pk_bf16_f32 v14, v14, v15
	v_pk_mul_f32 v[18:19], v[18:19], v[34:35] op_sel_hi:[1,0]
	v_cvt_pk_bf16_f32 v15, v16, v17
	global_store_dwordx2 v[4:5], v[14:15], off sc1
	global_load_dwordx4 v[14:17], v[2:3], off offset:1024
	v_pk_mul_f32 v[20:21], v[20:21], v[34:35] op_sel_hi:[1,0]
	s_waitcnt vmcnt(0)
	v_pk_mul_f32 v[14:15], v[14:15], v[18:19]
	v_pk_mul_f32 v[16:17], v[16:17], v[20:21]
	v_cvt_pk_bf16_f32 v14, v14, v15
	v_pk_mul_f32 v[18:19], v[22:23], v[34:35] op_sel_hi:[1,0]
	v_cvt_pk_bf16_f32 v15, v16, v17
	global_store_dwordx2 v[4:5], v[14:15], off offset:512 sc1
	global_load_dwordx4 v[14:17], v[2:3], off offset:2048
	v_pk_mul_f32 v[20:21], v[24:25], v[34:35] op_sel_hi:[1,0]
	s_waitcnt vmcnt(0)
	v_pk_mul_f32 v[14:15], v[14:15], v[18:19]
	v_pk_mul_f32 v[16:17], v[16:17], v[20:21]
	v_cvt_pk_bf16_f32 v14, v14, v15
	v_pk_mul_f32 v[18:19], v[26:27], v[34:35] op_sel_hi:[1,0]
	v_cvt_pk_bf16_f32 v15, v16, v17
	global_store_dwordx2 v[4:5], v[14:15], off offset:1024 sc1
	global_load_dwordx4 v[14:17], v[2:3], off offset:3072
	v_pk_mul_f32 v[20:21], v[28:29], v[34:35] op_sel_hi:[1,0]
	s_waitcnt vmcnt(0)
	v_pk_mul_f32 v[14:15], v[18:19], v[14:15]
	v_pk_mul_f32 v[16:17], v[20:21], v[16:17]
	v_cvt_pk_bf16_f32 v14, v14, v15
	s_nop 0
	v_cvt_pk_bf16_f32 v15, v16, v17
	global_store_dwordx2 v[4:5], v[14:15], off offset:1536 sc1
	v_lshl_add_u64 v[4:5], v[4:5], 0, s[4:5]
	s_cbranch_scc0 .LBB0_71

; __device__ __forceinline__ unsigned pkbf(float lo, float hi) { return pg8::cvt_pk_bf16(lo, hi); }
;     __device__ __forceinline__ void operator()(AccRef acc, const Unit& u, int wr, int wc, int fr, int fq) const {
;         asm volatile("" : "+v"(fr), "+v"(fq));
;         const int row0 = u.pm * 256 + wr * 64 + fr, col0 = u.pn * 256 + wc * 32 + 8 * fq;
; #pragma unroll
;         for (int ai = 0; ai < 2; ++ai)
; #pragma unroll
;             for (int m = 0; m < 4; ++m)
; #pragma unroll
;                 for (int bj = 0; bj < 2; ++bj) {
;                     const pg8::f32x4 v0 = acc[ai][bj][m][0] * s, v1 = acc[ai][bj][m][1] * s;
;                     u32x4 w; w.x = pkbf(v0[0], v0[1]); w.y = pkbf(v0[2], v0[3]); w.z = pkbf(v1[0], v1[1]); w.w = pkbf(v1[2], v1[3]);
;                     *(u32x4*)(O + (size_t)(row0 + ai * 128 + m * 16) * DM + col0 + bj * 128) = w; __builtin_amdgcn_sched_barrier(0); asm volatile("" ::: "memory");
;                 }
;     }
.LBB0_226:
	v_mov_b32_e32 v16, v129
	v_mov_b32_e32 v17, v154
	s_lshl_b32 s14, s90, 8
	s_lshl_b32 s15, s91, 8
	s_add_i32 s14, s14, s77
	s_or_b32 s15, s15, s78
	v_add_u32_e32 v16, s14, v16
	v_lshl_add_u32 v24, v17, 3, s15
	v_ashrrev_i32_e32 v17, 31, v16
	v_readlane_b32 s14, v237, 61
	v_lshlrev_b64 v[26:27], 11, v[16:17]
	v_readlane_b32 s15, v237, 62
	v_ashrrev_i32_e32 v25, 31, v24
	v_cvt_pk_bf16_f32 v16, v124, v125
	v_cvt_pk_bf16_f32 v17, v126, v127
	v_cvt_pk_bf16_f32 v18, v120, v121
	v_cvt_pk_bf16_f32 v19, v122, v123
	s_nop 0
	v_lshl_add_u64 v[26:27], s[14:15], 0, v[26:27]
	v_lshl_add_u64 v[24:25], v[24:25], 1, v[26:27]
	global_store_dwordx4 v[24:25], v[16:19], off sc1
	s_nop 1
	v_cvt_pk_bf16_f32 v16, v148, v149
	v_cvt_pk_bf16_f32 v17, v146, v147
	v_cvt_pk_bf16_f32 v18, v152, v153
	v_cvt_pk_bf16_f32 v19, v150, v151
	global_store_dwordx4 v[24:25], v[16:19], off offset:256 sc1
	s_mov_b64 s[14:15], 0x8000
	v_lshl_add_u64 v[26:27], v[24:25], 0, s[14:15]
	s_mov_b32 s14, 0x8000
	v_cvt_pk_bf16_f32 v16, v102, v103
	v_cvt_pk_bf16_f32 v17, v100, v101
	v_add_co_u32_e32 v100, vcc, s14, v24
	v_cvt_pk_bf16_f32 v18, v110, v111
	v_cvt_pk_bf16_f32 v19, v108, v109
	s_nop 1
	v_addc_co_u32_e32 v101, vcc, 0, v25, vcc
	global_store_dwordx4 v[100:101], v[16:19], off sc1
	s_nop 1
	v_cvt_pk_bf16_f32 v16, v114, v115
	v_cvt_pk_bf16_f32 v17, v112, v113
	v_cvt_pk_bf16_f32 v18, v118, v119
	v_cvt_pk_bf16_f32 v19, v116, v117
	global_store_dwordx4 v[26:27], v[16:19], off offset:256 sc1
	s_mov_b64 s[14:15], 0x10000
	v_lshl_add_u64 v[26:27], v[24:25], 0, s[14:15]
	s_mov_b32 s14, 0x10000
	v_cvt_pk_bf16_f32 v16, v86, v87
	v_cvt_pk_bf16_f32 v17, v84, v85
	v_add_co_u32_e32 v84, vcc, s14, v24
	v_cvt_pk_bf16_f32 v18, v94, v95
	v_cvt_pk_bf16_f32 v19, v92, v93
	s_nop 1
	v_addc_co_u32_e32 v85, vcc, 0, v25, vcc
	global_store_dwordx4 v[84:85], v[16:19], off sc1
	s_nop 1
	v_cvt_pk_bf16_f32 v16, v98, v99
	v_cvt_pk_bf16_f32 v17, v96, v97
	v_cvt_pk_bf16_f32 v18, v106, v107
	v_cvt_pk_bf16_f32 v19, v104, v105
	global_store_dwordx4 v[26:27], v[16:19], off offset:256 sc1
	s_mov_b64 s[14:15], 0x18000
	v_lshl_add_u64 v[26:27], v[24:25], 0, s[14:15]
	s_mov_b32 s14, 0x18000
	v_cvt_pk_bf16_f32 v16, v74, v75
	v_cvt_pk_bf16_f32 v17, v72, v73
	v_add_co_u32_e32 v72, vcc, s14, v24
	v_cvt_pk_bf16_f32 v18, v78, v79
	v_cvt_pk_bf16_f32 v19, v76, v77
	s_nop 1
	v_addc_co_u32_e32 v73, vcc, 0, v25, vcc
	global_store_dwordx4 v[72:73], v[16:19], off sc1
	s_nop 1
	v_cvt_pk_bf16_f32 v16, v68, v69
	v_cvt_pk_bf16_f32 v17, v70, v71
	v_cvt_pk_bf16_f32 v18, v64, v65
	v_cvt_pk_bf16_f32 v19, v66, v67
	global_store_dwordx4 v[26:27], v[16:19], off offset:256 sc1
	s_mov_b64 s[14:15], 0x40000
	v_lshl_add_u64 v[26:27], v[24:25], 0, s[14:15]
	s_mov_b32 s14, 0x40000
	v_cvt_pk_bf16_f32 v16, v60, v61
	v_cvt_pk_bf16_f32 v17, v62, v63
	v_cvt_pk_bf16_f32 v18, v56, v57
	v_add_co_u32_e32 v56, vcc, s14, v24
	v_cvt_pk_bf16_f32 v19, v58, v59
	s_nop 1
	v_addc_co_u32_e32 v57, vcc, 0, v25, vcc
	global_store_dwordx4 v[56:57], v[16:19], off sc1
	s_nop 1
	v_cvt_pk_bf16_f32 v16, v82, v83
	v_cvt_pk_bf16_f32 v17, v80, v81
	v_cvt_pk_bf16_f32 v18, v90, v91
	v_cvt_pk_bf16_f32 v19, v88, v89
	global_store_dwordx4 v[26:27], v[16:19], off offset:256 sc1
	s_mov_b64 s[14:15], 0x48000
	v_lshl_add_u64 v[26:27], v[24:25], 0, s[14:15]
	s_mov_b32 s14, 0x48000
	v_cvt_pk_bf16_f32 v16, v38, v39
	v_cvt_pk_bf16_f32 v17, v36, v37
	v_add_co_u32_e32 v36, vcc, s14, v24
	v_cvt_pk_bf16_f32 v18, v46, v47
	v_cvt_pk_bf16_f32 v19, v44, v45
	s_nop 1
	v_addc_co_u32_e32 v37, vcc, 0, v25, vcc
	global_store_dwordx4 v[36:37], v[16:19], off sc1
	s_nop 1
	v_cvt_pk_bf16_f32 v16, v50, v51
	v_cvt_pk_bf16_f32 v17, v48, v49
	v_cvt_pk_bf16_f32 v18, v54, v55
	v_cvt_pk_bf16_f32 v19, v52, v53
	global_store_dwordx4 v[26:27], v[16:19], off offset:256 sc1
	s_mov_b64 s[14:15], 0x50000
	s_nop 0
	v_cvt_pk_bf16_f32 v16, v22, v23
	v_cvt_pk_bf16_f32 v17, v20, v21
	v_lshl_add_u64 v[20:21], v[24:25], 0, s[14:15]
	s_mov_b32 s14, 0x50000
	v_add_co_u32_e32 v22, vcc, s14, v24
	v_cvt_pk_bf16_f32 v18, v30, v31
	v_cvt_pk_bf16_f32 v19, v28, v29
	s_nop 1
	v_addc_co_u32_e32 v23, vcc, 0, v25, vcc
	global_store_dwordx4 v[22:23], v[16:19], off sc1
	s_nop 1
	v_cvt_pk_bf16_f32 v16, v34, v35
	v_cvt_pk_bf16_f32 v17, v32, v33
	v_cvt_pk_bf16_f32 v18, v42, v43
	v_cvt_pk_bf16_f32 v19, v40, v41
	global_store_dwordx4 v[20:21], v[16:19], off offset:256 sc1
	s_mov_b64 s[14:15], 0x58000
	s_nop 0
	v_cvt_pk_bf16_f32 v16, v10, v11
	v_cvt_pk_bf16_f32 v17, v8, v9
	v_lshl_add_u64 v[8:9], v[24:25], 0, s[14:15]
	s_mov_b32 s14, 0x58000
	v_add_co_u32_e32 v10, vcc, s14, v24
	v_cvt_pk_bf16_f32 v18, v14, v15
	v_cvt_pk_bf16_f32 v19, v12, v13
	s_nop 1
	v_addc_co_u32_e32 v11, vcc, 0, v25, vcc
	global_store_dwordx4 v[10:11], v[16:19], off sc1
	v_cvt_pk_bf16_f32 v4, v4, v5
	v_cvt_pk_bf16_f32 v5, v6, v7
	v_cvt_pk_bf16_f32 v6, v0, v1
	v_cvt_pk_bf16_f32 v7, v2, v3
	global_store_dwordx4 v[8:9], v[4:7], off offset:256 sc1
	s_and_b64 vcc, exec, s[4:5]
	s_mov_b64 s[4:5], -1
	s_cbranch_vccnz .LBB0_213
	s_andn2_b64 vcc, exec, s[18:19]
	s_cbranch_vccnz .LBB0_212
	s_barrier
	s_branch .LBB0_212

; __device__ __forceinline__ float bflo(unsigned w) { return __uint_as_float(w << 16); }
; __device__ __forceinline__ float bfhi(unsigned w) { return __uint_as_float(w & 0xffff0000u); }
; __device__ __forceinline__ unsigned pkbf(float lo, float hi) { return pg8::cvt_pk_bf16(lo, hi); }
; __device__ __forceinline__ void norm_row(const float* src, const bf16_t* add, const float* gain, bf16_t* ob, float* of, int lane) {
;     f32x4 v[4]; float s = 0.f;
; #pragma unroll
;     for (int j = 0; j < 4; ++j) { v[j] = *((const f32x4*)src + lane + 64 * j);
;         if (add) { const u32x2 d = *((const u32x2*)add + lane + 64 * j); v[j][0] += bflo(d.x); v[j][1] += bfhi(d.x); v[j][2] += bflo(d.y); v[j][3] += bfhi(d.y); }
;         s += (v[j][0] * v[j][0] + v[j][1] * v[j][1]) + (v[j][2] * v[j][2] + v[j][3] * v[j][3]); }
;     const float rstd = 1.0f / sqrtf(wave_sum(s) * (1.f / DM) + NORM_EPS);
; #pragma unroll
;     for (int j = 0; j < 4; ++j) { const f32x4 g = *((const f32x4*)gain + lane + 64 * j); const f32x4 o = v[j] * rstd * g;
;         if (ob) { u32x2 w; w.x = pkbf(o[0], o[1]); w.y = pkbf(o[2], o[3]); *((u32x2*)ob + lane + 64 * j) = w; }
;         else *((f32x4*)of + lane + 64 * j) = o; }
; }
; __global__ void __launch_bounds__(512, 2) mega_fwd(const Args a) {
;     ...
;     for (int m = gw; m < T; m += NGW) norm_row(xrow(p, m), D1 + (size_t)m * DM, p.in[6], XN + (size_t)m * DM, nullptr, lane);
.LBB0_284:
	s_add_i32 s12, s6, 0xffff8000
	v_add_co_u32_e64 v16, s[0:1], s8, v2
	v_add_co_u32_e32 v14, vcc, s3, v2
	s_nop 0
	v_addc_co_u32_e64 v17, s[0:1], -1, v3, s[0:1]
	s_cmp_lt_i32 s6, 0x8000
	v_addc_co_u32_e32 v15, vcc, -1, v3, vcc
	s_cselect_b32 s1, s7, 0
	s_cselect_b32 s0, s6, s12
	global_load_dwordx2 v[34:35], v[14:15], off
	global_load_dwordx2 v[36:37], v[16:17], off offset:-3584
	s_cselect_b32 s12, s17, s19
	s_cselect_b32 s13, s16, s18
	s_lshl_b64 s[0:1], s[0:1], 12
	global_load_dwordx2 v[38:39], v[16:17], off offset:-3072
	global_load_dwordx2 v[40:41], v[16:17], off offset:-2560
	s_add_u32 s0, s13, s0
	s_addc_u32 s1, s12, s1
	global_load_dwordx4 v[14:17], v10, s[0:1] nt
	global_load_dwordx4 v[18:21], v10, s[0:1] offset:1024 nt
	global_load_dwordx4 v[22:25], v10, s[0:1] offset:2048 nt
	global_load_dwordx4 v[26:29], v10, s[0:1] offset:3072 nt
	global_load_dwordx4 v[30:33], v[0:1], off
	s_add_u32 s6, s6, s88
	s_addc_u32 s7, s7, s89
	s_cmp_gt_i32 s6, 0xbfff
	s_waitcnt vmcnt(8)
	v_lshlrev_b32_e32 v42, 16, v34
	v_and_b32_e32 v43, 0xffff0000, v34
	v_lshlrev_b32_e32 v34, 16, v35
	v_and_b32_e32 v35, 0xffff0000, v35
	s_waitcnt vmcnt(7)
	v_lshlrev_b32_e32 v44, 16, v36
	v_and_b32_e32 v45, 0xffff0000, v36
	v_lshlrev_b32_e32 v36, 16, v37
	v_and_b32_e32 v37, 0xffff0000, v37
	s_waitcnt vmcnt(5)
	v_lshlrev_b32_e32 v48, 16, v40
	v_and_b32_e32 v49, 0xffff0000, v40
	v_lshlrev_b32_e32 v40, 16, v41
	v_and_b32_e32 v41, 0xffff0000, v41
	s_waitcnt vmcnt(4)
	v_pk_add_f32 v[14:15], v[14:15], v[42:43]
	v_pk_add_f32 v[16:17], v[16:17], v[34:35]
	s_waitcnt vmcnt(3)
	v_pk_add_f32 v[18:19], v[18:19], v[44:45]
	v_pk_add_f32 v[20:21], v[20:21], v[36:37]
	v_lshlrev_b32_e32 v46, 16, v38
	v_and_b32_e32 v47, 0xffff0000, v38
	v_lshlrev_b32_e32 v38, 16, v39
	v_and_b32_e32 v39, 0xffff0000, v39
	s_waitcnt vmcnt(1)
	v_pk_add_f32 v[28:29], v[28:29], v[40:41]
	v_mov_b32_e32 v36, v15
	v_mov_b32_e32 v37, v17
	v_mov_b32_e32 v40, v19
	v_mov_b32_e32 v41, v21
	v_pk_add_f32 v[22:23], v[22:23], v[46:47]
	v_pk_add_f32 v[24:25], v[24:25], v[38:39]
	v_mov_b32_e32 v34, v14
	v_mov_b32_e32 v35, v16
	v_mov_b32_e32 v38, v18
	v_mov_b32_e32 v39, v20
	v_pk_mul_f32 v[36:37], v[36:37], v[36:37]
	v_pk_mul_f32 v[40:41], v[40:41], v[40:41]
	v_pk_add_f32 v[26:27], v[26:27], v[48:49]
	v_mul_f32_e32 v42, v23, v23
	v_mul_f32_e32 v44, v25, v25
	v_pk_fma_f32 v[34:35], v[34:35], v[34:35], v[36:37]
	v_pk_fma_f32 v[36:37], v[38:39], v[38:39], v[40:41]
	v_pk_mul_f32 v[46:47], v[26:27], v[26:27]
	v_pk_mul_f32 v[48:49], v[28:29], v[28:29]
	v_pk_fma_f32 v[42:43], v[22:23], v[22:23], v[42:43] op_sel_hi:[1,1,0]
	v_pk_fma_f32 v[44:45], v[24:25], v[24:25], v[44:45] op_sel_hi:[1,1,0]
	v_pk_add_f32 v[34:35], v[34:35], v[34:35] op_sel:[0,1] op_sel_hi:[1,0]
	v_pk_add_f32 v[36:37], v[36:37], v[36:37] op_sel:[0,1] op_sel_hi:[1,0]
	v_mov_b32_e32 v43, v48
	v_mov_b32_e32 v45, v49
	v_mov_b32_e32 v35, v46
	v_mov_b32_e32 v37, v47
	v_pk_add_f32 v[38:39], v[42:43], v[44:45]
	v_pk_add_f32 v[34:35], v[34:35], v[36:37]
	s_nop 0
	v_pk_add_f32 v[34:35], v[34:35], v[38:39]
	s_nop 0
	v_add_f32_e32 v13, v34, v35
	ds_bpermute_b32 v34, v4, v13
	s_waitcnt lgkmcnt(0)
	v_add_f32_e32 v13, v13, v34
	ds_bpermute_b32 v34, v5, v13
	s_waitcnt lgkmcnt(0)
	v_add_f32_e32 v13, v13, v34
	ds_bpermute_b32 v34, v6, v13
	s_waitcnt lgkmcnt(0)
	v_add_f32_e32 v13, v13, v34
	ds_bpermute_b32 v34, v7, v13
	s_waitcnt lgkmcnt(0)
	v_add_f32_e32 v13, v13, v34
	ds_bpermute_b32 v34, v8, v13
	s_waitcnt lgkmcnt(0)
	v_add_f32_e32 v13, v13, v34
	ds_bpermute_b32 v34, v9, v13
	s_waitcnt lgkmcnt(0)
	v_add_f32_e32 v13, v13, v34
	v_fmamk_f32 v13, v13, 0x3a800000, v11
	v_mul_f32_e32 v34, 0x4f800000, v13
	v_cmp_gt_f32_e32 vcc, s9, v13
	s_nop 1
	v_cndmask_b32_e32 v13, v13, v34, vcc
	v_sqrt_f32_e32 v34, v13
	s_nop 0
	v_add_u32_e32 v35, -1, v34
	v_add_u32_e32 v36, 1, v34
	v_fma_f32 v37, -v35, v34, v13
	v_fma_f32 v38, -v36, v34, v13
	v_cmp_ge_f32_e64 s[0:1], 0, v37
	s_nop 1
	v_cndmask_b32_e64 v34, v34, v35, s[0:1]
	v_cmp_lt_f32_e64 s[0:1], 0, v38
	s_nop 1
	v_cndmask_b32_e64 v34, v34, v36, s[0:1]
	v_mul_f32_e32 v35, 0x37800000, v34
	v_cndmask_b32_e32 v34, v34, v35, vcc
	v_cmp_class_f32_e32 vcc, v13, v12
	s_nop 1
	v_cndmask_b32_e32 v13, v34, v13, vcc
	v_div_scale_f32 v34, s[0:1], v13, v13, 1.0
	v_rcp_f32_e32 v36, v34
	v_div_scale_f32 v35, vcc, 1.0, v13, 1.0
	v_fma_f32 v37, -v34, v36, 1.0
	v_fmac_f32_e32 v36, v37, v36
	v_mul_f32_e32 v37, v35, v36
	v_fma_f32 v38, -v34, v37, v35
	v_fmac_f32_e32 v37, v38, v36
	v_fma_f32 v34, -v34, v37, v35
	v_div_fmas_f32 v34, v34, v36, v37
	v_div_fixup_f32 v34, v34, v13, 1.0
	v_pk_mul_f32 v[14:15], v[14:15], v[34:35] op_sel_hi:[1,0]
	v_pk_mul_f32 v[16:17], v[16:17], v[34:35] op_sel_hi:[1,0]
	s_waitcnt vmcnt(0)
	v_pk_mul_f32 v[14:15], v[30:31], v[14:15]
	v_pk_mul_f32 v[16:17], v[32:33], v[16:17]
	v_cvt_pk_bf16_f32 v14, v14, v15
	v_pk_mul_f32 v[18:19], v[18:19], v[34:35] op_sel_hi:[1,0]
	v_cvt_pk_bf16_f32 v15, v16, v17
	global_store_dwordx2 v[2:3], v[14:15], off sc1
	global_load_dwordx4 v[14:17], v[0:1], off offset:1024
	v_pk_mul_f32 v[20:21], v[20:21], v[34:35] op_sel_hi:[1,0]
	s_waitcnt vmcnt(0)
	v_pk_mul_f32 v[14:15], v[14:15], v[18:19]
	v_pk_mul_f32 v[16:17], v[16:17], v[20:21]
	v_cvt_pk_bf16_f32 v14, v14, v15
	v_pk_mul_f32 v[18:19], v[22:23], v[34:35] op_sel_hi:[1,0]
	v_cvt_pk_bf16_f32 v15, v16, v17
	global_store_dwordx2 v[2:3], v[14:15], off offset:512 sc1
	global_load_dwordx4 v[14:17], v[0:1], off offset:2048
	v_pk_mul_f32 v[20:21], v[24:25], v[34:35] op_sel_hi:[1,0]
	s_waitcnt vmcnt(0)
	v_pk_mul_f32 v[14:15], v[14:15], v[18:19]
	v_pk_mul_f32 v[16:17], v[16:17], v[20:21]
	v_cvt_pk_bf16_f32 v14, v14, v15
	v_pk_mul_f32 v[18:19], v[26:27], v[34:35] op_sel_hi:[1,0]
	v_cvt_pk_bf16_f32 v15, v16, v17
	global_store_dwordx2 v[2:3], v[14:15], off offset:1024 sc1
	global_load_dwordx4 v[14:17], v[0:1], off offset:3072
	v_pk_mul_f32 v[20:21], v[28:29], v[34:35] op_sel_hi:[1,0]
	s_waitcnt vmcnt(0)
	v_pk_mul_f32 v[14:15], v[18:19], v[14:15]
	v_pk_mul_f32 v[16:17], v[20:21], v[16:17]
	v_cvt_pk_bf16_f32 v14, v14, v15
	s_nop 0
	v_cvt_pk_bf16_f32 v15, v16, v17
	global_store_dwordx2 v[2:3], v[14:15], off offset:1536 sc1
	v_lshl_add_u64 v[2:3], v[2:3], 0, s[4:5]
	s_cbranch_scc0 .LBB0_284

; __device__ __forceinline__ unsigned pkbf(float lo, float hi) { return pg8::cvt_pk_bf16(lo, hi); }
;     __device__ __forceinline__ void operator()(AccRef acc, const Unit& u, int wr, int wc, int fr, int fq) const {
;         asm volatile("" : "+v"(fr), "+v"(fq));
;         bf16_t* base; int ldc, colt;
;         if (u.pn < 3) { base = ZA; ldc = 768; colt = u.pn * 256; } else if (u.pn < 9) { base = ZRKV; ldc = 1536; colt = (u.pn - 3) * 256; } else { base = ZL; ldc = 512; colt = (u.pn - 9) * 256; }
;         const int row0 = u.pm * 256 + wr * 64 + fr, col0 = colt + wc * 32 + 8 * fq;
; #pragma unroll
;         for (int ai = 0; ai < 2; ++ai)
; #pragma unroll
;             for (int m = 0; m < 4; ++m)
; #pragma unroll
;                 for (int bj = 0; bj < 2; ++bj) {
;                     const pg8::f32x4 v0 = acc[ai][bj][m][0], v1 = acc[ai][bj][m][1];
;                     u32x4 w; w.x = pkbf(v0[0], v0[1]); w.y = pkbf(v0[2], v0[3]); w.z = pkbf(v1[0], v1[1]); w.w = pkbf(v1[2], v1[3]);
;                     *(u32x4*)(base + (size_t)(row0 + ai * 128 + m * 16) * ldc + col0 + bj * 128) = w; __builtin_amdgcn_sched_barrier(0); asm volatile("" ::: "memory");
;                 }
;     }
.LBB0_360:
	s_lshl_b32 s20, s64, 8
	s_add_i32 s20, s20, s80
	s_add_i32 s17, s17, s81
	v_add_u32_e32 v156, s20, v152
	v_lshl_add_u32 v152, v151, 3, s17
	v_ashrrev_i32_e32 v153, 31, v152
	v_ashrrev_i32_e32 v151, 31, v156
	v_lshl_add_u64 v[152:153], v[152:153], 1, s[14:15]
	v_mul_lo_u32 v151, s8, v151
	v_mul_lo_u32 v157, s9, v156
	v_mad_u64_u32 v[154:155], s[14:15], s8, v156, 0
	v_add3_u32 v155, v155, v151, v157
	v_lshl_add_u64 v[154:155], v[154:155], 1, v[152:153]
	v_cvt_pk_bf16_f32 v124, v124, v125
	v_cvt_pk_bf16_f32 v125, v126, v127
	v_cvt_pk_bf16_f32 v126, v120, v121
	v_cvt_pk_bf16_f32 v127, v122, v123
	global_store_dwordx4 v[154:155], v[124:127], off sc1
	v_cvt_pk_bf16_f32 v116, v116, v117
	v_cvt_pk_bf16_f32 v117, v118, v119
	v_cvt_pk_bf16_f32 v118, v112, v113
	v_cvt_pk_bf16_f32 v119, v114, v115
	global_store_dwordx4 v[154:155], v[116:119], off offset:256 sc1
	v_add_u32_e32 v112, 16, v156
	v_ashrrev_i32_e32 v113, 31, v112
	v_mul_lo_u32 v114, s8, v113
	v_mul_lo_u32 v115, s9, v112
	v_mad_u64_u32 v[112:113], s[14:15], s8, v112, 0
	v_add3_u32 v113, v113, v114, v115
	v_lshl_add_u64 v[112:113], v[112:113], 1, v[152:153]
	v_cvt_pk_bf16_f32 v108, v108, v109
	v_cvt_pk_bf16_f32 v109, v110, v111
	v_cvt_pk_bf16_f32 v110, v104, v105
	v_cvt_pk_bf16_f32 v111, v106, v107
	global_store_dwordx4 v[112:113], v[108:111], off sc1
	v_cvt_pk_bf16_f32 v100, v100, v101
	v_cvt_pk_bf16_f32 v101, v102, v103
	v_cvt_pk_bf16_f32 v102, v96, v97
	v_cvt_pk_bf16_f32 v103, v98, v99
	global_store_dwordx4 v[112:113], v[100:103], off offset:256 sc1
	v_add_u32_e32 v96, 32, v156
	v_ashrrev_i32_e32 v97, 31, v96
	v_mul_lo_u32 v98, s8, v97
	v_mul_lo_u32 v99, s9, v96
	v_mad_u64_u32 v[96:97], s[14:15], s8, v96, 0
	v_add3_u32 v97, v97, v98, v99
	v_lshl_add_u64 v[96:97], v[96:97], 1, v[152:153]
	v_cvt_pk_bf16_f32 v92, v92, v93
	v_cvt_pk_bf16_f32 v93, v94, v95
	v_cvt_pk_bf16_f32 v94, v88, v89
	v_cvt_pk_bf16_f32 v95, v90, v91
	global_store_dwordx4 v[96:97], v[92:95], off sc1
	v_cvt_pk_bf16_f32 v84, v84, v85
	v_cvt_pk_bf16_f32 v85, v86, v87
	v_cvt_pk_bf16_f32 v86, v80, v81
	v_cvt_pk_bf16_f32 v87, v82, v83
	global_store_dwordx4 v[96:97], v[84:87], off offset:256 sc1
	v_add_u32_e32 v80, 48, v156
	v_ashrrev_i32_e32 v81, 31, v80
	v_mul_lo_u32 v82, s8, v81
	v_mul_lo_u32 v83, s9, v80
	v_mad_u64_u32 v[80:81], s[14:15], s8, v80, 0
	v_add3_u32 v81, v81, v82, v83
	v_lshl_add_u64 v[80:81], v[80:81], 1, v[152:153]
	v_cvt_pk_bf16_f32 v76, v76, v77
	v_cvt_pk_bf16_f32 v77, v78, v79
	v_cvt_pk_bf16_f32 v78, v72, v73
	v_cvt_pk_bf16_f32 v79, v74, v75
	global_store_dwordx4 v[80:81], v[76:79], off sc1
	v_cvt_pk_bf16_f32 v68, v68, v69
	v_cvt_pk_bf16_f32 v69, v70, v71
	v_cvt_pk_bf16_f32 v70, v64, v65
	v_cvt_pk_bf16_f32 v71, v66, v67
	global_store_dwordx4 v[80:81], v[68:71], off offset:256 sc1
	v_add_u32_e32 v64, 0x80, v156
	v_ashrrev_i32_e32 v65, 31, v64
	v_mul_lo_u32 v66, s8, v65
	v_mul_lo_u32 v67, s9, v64
	v_mad_u64_u32 v[64:65], s[14:15], s8, v64, 0
	v_add3_u32 v65, v65, v66, v67
	v_lshl_add_u64 v[64:65], v[64:65], 1, v[152:153]
	v_cvt_pk_bf16_f32 v60, v60, v61
	v_cvt_pk_bf16_f32 v61, v62, v63
	v_cvt_pk_bf16_f32 v62, v56, v57
	v_cvt_pk_bf16_f32 v63, v58, v59
	global_store_dwordx4 v[64:65], v[60:63], off sc1
	v_cvt_pk_bf16_f32 v52, v52, v53
	v_cvt_pk_bf16_f32 v53, v54, v55
	v_cvt_pk_bf16_f32 v54, v48, v49
	v_cvt_pk_bf16_f32 v55, v50, v51
	global_store_dwordx4 v[64:65], v[52:55], off offset:256 sc1
	v_add_u32_e32 v48, 0x90, v156
	v_ashrrev_i32_e32 v49, 31, v48
	v_mul_lo_u32 v50, s8, v49
	v_mul_lo_u32 v51, s9, v48
	v_mad_u64_u32 v[48:49], s[14:15], s8, v48, 0
	v_add3_u32 v49, v49, v50, v51
	v_lshl_add_u64 v[48:49], v[48:49], 1, v[152:153]
	v_cvt_pk_bf16_f32 v44, v44, v45
	v_cvt_pk_bf16_f32 v45, v46, v47
	v_cvt_pk_bf16_f32 v46, v40, v41
	v_cvt_pk_bf16_f32 v47, v42, v43
	global_store_dwordx4 v[48:49], v[44:47], off sc1
	v_cvt_pk_bf16_f32 v36, v36, v37
	v_cvt_pk_bf16_f32 v37, v38, v39
	v_cvt_pk_bf16_f32 v38, v32, v33
	v_cvt_pk_bf16_f32 v39, v34, v35
	global_store_dwordx4 v[48:49], v[36:39], off offset:256 sc1
	v_add_u32_e32 v32, 0xa0, v156
	v_ashrrev_i32_e32 v33, 31, v32
	v_mul_lo_u32 v34, s8, v33
	v_mul_lo_u32 v35, s9, v32
	v_mad_u64_u32 v[32:33], s[14:15], s8, v32, 0
	v_add3_u32 v33, v33, v34, v35
	v_lshl_add_u64 v[32:33], v[32:33], 1, v[152:153]
	v_cvt_pk_bf16_f32 v28, v28, v29
	v_cvt_pk_bf16_f32 v29, v30, v31
	v_cvt_pk_bf16_f32 v30, v24, v25
	v_cvt_pk_bf16_f32 v31, v26, v27
	global_store_dwordx4 v[32:33], v[28:31], off sc1
	v_cvt_pk_bf16_f32 v20, v20, v21
	v_cvt_pk_bf16_f32 v21, v22, v23
	v_cvt_pk_bf16_f32 v22, v16, v17
	v_cvt_pk_bf16_f32 v23, v18, v19
	global_store_dwordx4 v[32:33], v[20:23], off offset:256 sc1
	v_add_u32_e32 v16, 0xb0, v156
	v_ashrrev_i32_e32 v17, 31, v16
	v_mul_lo_u32 v18, s8, v17
	v_mul_lo_u32 v19, s9, v16
	v_mad_u64_u32 v[16:17], s[8:9], s8, v16, 0
	v_add3_u32 v17, v17, v18, v19
	v_lshl_add_u64 v[16:17], v[16:17], 1, v[152:153]
	v_cvt_pk_bf16_f32 v12, v12, v13
	v_cvt_pk_bf16_f32 v13, v14, v15
	v_cvt_pk_bf16_f32 v14, v8, v9
	v_cvt_pk_bf16_f32 v15, v10, v11
	global_store_dwordx4 v[16:17], v[12:15], off sc1
	v_cvt_pk_bf16_f32 v4, v4, v5
	v_cvt_pk_bf16_f32 v5, v6, v7
	v_cvt_pk_bf16_f32 v6, v0, v1
	v_cvt_pk_bf16_f32 v7, v2, v3
	global_store_dwordx4 v[16:17], v[4:7], off offset:256 sc1
	s_and_b64 vcc, exec, s[6:7]
	s_mov_b64 s[6:7], -1
	s_cbranch_vccnz .LBB0_342
	s_andn2_b64 vcc, exec, s[18:19]
	s_cbranch_vccnz .LBB0_341
	s_barrier
	s_branch .LBB0_341

; __device__ __forceinline__ unsigned pkbf(float lo, float hi) { return pg8::cvt_pk_bf16(lo, hi); }
;     __device__ __forceinline__ void operator()(AccRef acc, const Unit& u, int wr, int wc, int fr, int fq) const {
;         asm volatile("" : "+v"(fr), "+v"(fq));
;         const int row0 = u.pm * 256 + wr * 64 + fr, col0 = u.pn * 256 + wc * 32 + 8 * fq;
; #pragma unroll
;         for (int ai = 0; ai < 2; ++ai)
; #pragma unroll
;             for (int m = 0; m < 4; ++m)
; #pragma unroll
;                 for (int bj = 0; bj < 2; ++bj) {
;                     const pg8::f32x4 v0 = acc[ai][bj][m][0], v1 = acc[ai][bj][m][1];
;                     u32x4 w; w.x = pkbf(v0[0], v0[1]); w.y = pkbf(v0[2], v0[3]); w.z = pkbf(v1[0], v1[1]); w.w = pkbf(v1[2], v1[3]);
;                     *(u32x4*)(O + (size_t)(row0 + ai * 128 + m * 16) * ldc + col0 + bj * 128) = w;
;                 }
;     }
.LBB0_520:
	s_lshl_b32 s14, s71, 8
	v_mov_b32_e32 v150, v145
	v_mov_b32_e32 v151, v144
	s_add_i32 s14, s14, s67
	v_cvt_pk_bf16_f32 v124, v124, v125
	v_cvt_pk_bf16_f32 v125, v126, v127
	v_cvt_pk_bf16_f32 v126, v120, v121
	v_mov_b64_e32 v[120:121], s[48:49]
	v_add_u32_e32 v152, s14, v151
	s_lshl_b32 s14, s25, 8
	s_or_b32 s14, s14, s68
	v_lshl_add_u32 v150, v150, 3, s14
	v_ashrrev_i32_e32 v151, 31, v150
	v_cvt_pk_bf16_f32 v127, v122, v123
	v_mad_i64_i32 v[122:123], s[14:15], v152, s24, v[120:121]
	v_lshlrev_b64 v[150:151], 1, v[150:151]
	v_lshl_add_u64 v[122:123], v[122:123], 0, v[150:151]
	global_store_dwordx4 v[122:123], v[124:127], off sc1
	v_cvt_pk_bf16_f32 v116, v116, v117
	v_cvt_pk_bf16_f32 v117, v118, v119
	v_cvt_pk_bf16_f32 v118, v112, v113
	v_add_u32_e32 v112, 16, v152
	v_cvt_pk_bf16_f32 v119, v114, v115
	global_store_dwordx4 v[122:123], v[116:119], off offset:256 sc1
	v_cvt_pk_bf16_f32 v108, v108, v109
	v_cvt_pk_bf16_f32 v109, v110, v111
	v_cvt_pk_bf16_f32 v110, v104, v105
	v_mad_i64_i32 v[104:105], s[14:15], v112, s24, v[120:121]
	v_lshl_add_u64 v[104:105], v[104:105], 0, v[150:151]
	v_cvt_pk_bf16_f32 v111, v106, v107
	global_store_dwordx4 v[104:105], v[108:111], off sc1
	v_cvt_pk_bf16_f32 v100, v100, v101
	v_cvt_pk_bf16_f32 v101, v102, v103
	v_cvt_pk_bf16_f32 v102, v96, v97
	v_add_u32_e32 v96, 32, v152
	v_cvt_pk_bf16_f32 v103, v98, v99
	global_store_dwordx4 v[104:105], v[100:103], off offset:256 sc1
	v_cvt_pk_bf16_f32 v92, v92, v93
	v_cvt_pk_bf16_f32 v93, v94, v95
	v_cvt_pk_bf16_f32 v94, v88, v89
	v_mad_i64_i32 v[88:89], s[14:15], v96, s24, v[120:121]
	v_lshl_add_u64 v[88:89], v[88:89], 0, v[150:151]
	v_cvt_pk_bf16_f32 v95, v90, v91
	global_store_dwordx4 v[88:89], v[92:95], off sc1
	v_cvt_pk_bf16_f32 v84, v84, v85
	v_cvt_pk_bf16_f32 v85, v86, v87
	v_cvt_pk_bf16_f32 v86, v80, v81
	v_add_u32_e32 v80, 48, v152
	v_cvt_pk_bf16_f32 v87, v82, v83
	global_store_dwordx4 v[88:89], v[84:87], off offset:256 sc1
	v_cvt_pk_bf16_f32 v76, v76, v77
	v_cvt_pk_bf16_f32 v77, v78, v79
	v_cvt_pk_bf16_f32 v78, v72, v73
	v_mad_i64_i32 v[72:73], s[14:15], v80, s24, v[120:121]
	v_lshl_add_u64 v[72:73], v[72:73], 0, v[150:151]
	v_cvt_pk_bf16_f32 v79, v74, v75
	global_store_dwordx4 v[72:73], v[76:79], off sc1
	v_cvt_pk_bf16_f32 v68, v68, v69
	v_cvt_pk_bf16_f32 v69, v70, v71
	v_cvt_pk_bf16_f32 v70, v64, v65
	v_add_u32_e32 v64, 0x80, v152
	v_cvt_pk_bf16_f32 v71, v66, v67
	global_store_dwordx4 v[72:73], v[68:71], off offset:256 sc1
	v_cvt_pk_bf16_f32 v60, v60, v61
	v_cvt_pk_bf16_f32 v61, v62, v63
	v_cvt_pk_bf16_f32 v62, v56, v57
	v_mad_i64_i32 v[56:57], s[14:15], v64, s24, v[120:121]
	v_lshl_add_u64 v[56:57], v[56:57], 0, v[150:151]
	v_cvt_pk_bf16_f32 v63, v58, v59
	global_store_dwordx4 v[56:57], v[60:63], off sc1
	v_cvt_pk_bf16_f32 v52, v52, v53
	v_cvt_pk_bf16_f32 v53, v54, v55
	v_cvt_pk_bf16_f32 v54, v48, v49
	v_add_u32_e32 v48, 0x90, v152
	v_cvt_pk_bf16_f32 v55, v50, v51
	global_store_dwordx4 v[56:57], v[52:55], off offset:256 sc1
	v_cvt_pk_bf16_f32 v44, v44, v45
	v_cvt_pk_bf16_f32 v45, v46, v47
	v_cvt_pk_bf16_f32 v46, v40, v41
	v_mad_i64_i32 v[40:41], s[14:15], v48, s24, v[120:121]
	v_lshl_add_u64 v[40:41], v[40:41], 0, v[150:151]
	v_cvt_pk_bf16_f32 v47, v42, v43
	global_store_dwordx4 v[40:41], v[44:47], off sc1
	v_cvt_pk_bf16_f32 v36, v36, v37
	v_cvt_pk_bf16_f32 v37, v38, v39
	v_cvt_pk_bf16_f32 v38, v32, v33
	v_add_u32_e32 v32, 0xa0, v152
	v_cvt_pk_bf16_f32 v39, v34, v35
	global_store_dwordx4 v[40:41], v[36:39], off offset:256 sc1
	v_cvt_pk_bf16_f32 v28, v28, v29
	v_cvt_pk_bf16_f32 v29, v30, v31
	v_cvt_pk_bf16_f32 v30, v24, v25
	v_mad_i64_i32 v[24:25], s[14:15], v32, s24, v[120:121]
	v_lshl_add_u64 v[24:25], v[24:25], 0, v[150:151]
	v_cvt_pk_bf16_f32 v31, v26, v27
	global_store_dwordx4 v[24:25], v[28:31], off sc1
	v_cvt_pk_bf16_f32 v20, v20, v21
	v_cvt_pk_bf16_f32 v21, v22, v23
	v_cvt_pk_bf16_f32 v22, v16, v17
	v_add_u32_e32 v16, 0xb0, v152
	v_cvt_pk_bf16_f32 v23, v18, v19
	global_store_dwordx4 v[24:25], v[20:23], off offset:256 sc1
	v_cvt_pk_bf16_f32 v12, v12, v13
	v_cvt_pk_bf16_f32 v13, v14, v15
	v_cvt_pk_bf16_f32 v14, v8, v9
	v_mad_i64_i32 v[8:9], s[14:15], v16, s24, v[120:121]
	v_lshl_add_u64 v[8:9], v[8:9], 0, v[150:151]
	s_and_b64 vcc, exec, s[6:7]
	s_mov_b64 s[6:7], -1
	v_cvt_pk_bf16_f32 v15, v10, v11
	global_store_dwordx4 v[8:9], v[12:15], off sc1
	v_cvt_pk_bf16_f32 v4, v4, v5
	v_cvt_pk_bf16_f32 v5, v6, v7
	v_cvt_pk_bf16_f32 v6, v0, v1
	v_cvt_pk_bf16_f32 v7, v2, v3
	global_store_dwordx4 v[8:9], v[4:7], off offset:256 sc1
	s_cbranch_vccnz .LBB0_508
	s_andn2_b64 vcc, exec, s[12:13]
	s_cbranch_vccnz .LBB0_507
	s_barrier
	s_branch .LBB0_507

; __device__ __forceinline__ unsigned pkbf(float lo, float hi) { return pg8::cvt_pk_bf16(lo, hi); }
;     __device__ __forceinline__ void operator()(AccRef acc, const Unit& u, int wr, int wc, int fr, int fq) const {
;         asm volatile("" : "+v"(fr), "+v"(fq));
;         const int row0 = u.pm * 256 + wr * 64 + fr;
;         const bool isk = u.pn < 2; bf16_t* base = isk ? K : V; const int ldc = isk ? 768 : 512;
; #pragma unroll
;         for (int bj = 0; bj < 2; ++bj) {
;             const int c0 = (u.pn & 1) * 256 + bj * 128 + wc * 32 + 8 * fq;
;             const int cc = isk ? (c0 >> 6) * 96 + (c0 & 63) : c0;
; #pragma unroll
;             for (int ai = 0; ai < 2; ++ai)
; #pragma unroll
;                 for (int m = 0; m < 4; ++m) {
;                     const pg8::f32x4 v0 = acc[ai][bj][m][0], v1 = acc[ai][bj][m][1];
;                     u32x4 w; w.x = pkbf(v0[0], v0[1]); w.y = pkbf(v0[2], v0[3]); w.z = pkbf(v1[0], v1[1]); w.w = pkbf(v1[2], v1[3]);
;                     *(u32x4*)(base + (size_t)(row0 + ai * 128 + m * 16) * ldc + cc) = w;
;                 }
;         }
;     }
.LBB0_541:
	s_lshl_b32 s4, s75, 8
	s_add_i32 s4, s4, s71
	s_cmp_lt_i32 s90, 2
	v_mov_b32_e32 v150, v144
	v_mov_b32_e32 v151, v145
	s_cselect_b64 vcc, -1, 0
	v_cvt_pk_bf16_f32 v124, v124, v125
	v_cvt_pk_bf16_f32 v125, v126, v127
	v_cvt_pk_bf16_f32 v126, v120, v121
	v_cvt_pk_bf16_f32 v127, v122, v123
	s_nop 0
	v_add_u32_e32 v154, s4, v150
	s_and_b64 s[4:5], vcc, exec
	s_movk_i32 s4, 0x200
	s_cselect_b32 s26, 0x300, s4
	s_cselect_b32 s5, s89, s80
	s_cselect_b32 s4, s81, s35
	s_lshl_b32 s14, s90, 8
	s_and_b32 s14, s14, 0x100
	s_or_b32 s14, s14, s72
	v_lshl_add_u32 v151, v151, 3, s14
	v_ashrrev_i32_e32 v152, 6, v151
	v_and_b32_e32 v150, 56, v151
	v_mad_u64_u32 v[152:153], s[14:15], v152, s64, v[150:151]
	v_cndmask_b32_e32 v152, v151, v152, vcc
	v_ashrrev_i32_e32 v153, 31, v152
	v_mad_i64_i32 v[120:121], s[14:15], s26, v154, 0
	v_lshl_add_u64 v[152:153], v[152:153], 1, s[4:5]
	v_lshlrev_b64 v[120:121], 1, v[120:121]
	v_lshl_add_u64 v[122:123], v[152:153], 0, v[120:121]
	global_store_dwordx4 v[122:123], v[124:127], off sc1
	v_cvt_pk_bf16_f32 v116, v116, v117
	v_cvt_pk_bf16_f32 v117, v118, v119
	v_cvt_pk_bf16_f32 v118, v112, v113
	v_add_u32_e32 v112, 16, v154
	v_mad_i64_i32 v[112:113], s[14:15], s26, v112, 0
	v_lshlrev_b64 v[112:113], 1, v[112:113]
	v_cvt_pk_bf16_f32 v119, v114, v115
	v_lshl_add_u64 v[114:115], v[152:153], 0, v[112:113]
	global_store_dwordx4 v[114:115], v[116:119], off sc1
	v_cvt_pk_bf16_f32 v108, v108, v109
	v_cvt_pk_bf16_f32 v109, v110, v111
	v_cvt_pk_bf16_f32 v110, v104, v105
	v_add_u32_e32 v104, 32, v154
	v_mad_i64_i32 v[104:105], s[14:15], s26, v104, 0
	v_lshlrev_b64 v[104:105], 1, v[104:105]
	v_cvt_pk_bf16_f32 v111, v106, v107
	v_lshl_add_u64 v[106:107], v[152:153], 0, v[104:105]
	global_store_dwordx4 v[106:107], v[108:111], off sc1
	v_cvt_pk_bf16_f32 v100, v100, v101
	v_cvt_pk_bf16_f32 v101, v102, v103
	v_cvt_pk_bf16_f32 v102, v96, v97
	v_add_u32_e32 v96, 48, v154
	v_mad_i64_i32 v[96:97], s[14:15], s26, v96, 0
	v_lshlrev_b64 v[96:97], 1, v[96:97]
	v_cvt_pk_bf16_f32 v103, v98, v99
	v_lshl_add_u64 v[98:99], v[152:153], 0, v[96:97]
	global_store_dwordx4 v[98:99], v[100:103], off sc1
	v_add_u32_e32 v98, 0x80, v154
	v_cvt_pk_bf16_f32 v92, v92, v93
	v_cvt_pk_bf16_f32 v93, v94, v95
	v_cvt_pk_bf16_f32 v94, v88, v89
	v_mad_i64_i32 v[88:89], s[14:15], s26, v98, 0
	v_lshlrev_b64 v[88:89], 1, v[88:89]
	v_cvt_pk_bf16_f32 v95, v90, v91
	v_lshl_add_u64 v[90:91], v[152:153], 0, v[88:89]
	global_store_dwordx4 v[90:91], v[92:95], off sc1
	v_cvt_pk_bf16_f32 v84, v84, v85
	v_cvt_pk_bf16_f32 v85, v86, v87
	v_cvt_pk_bf16_f32 v86, v80, v81
	v_add_u32_e32 v80, 0x90, v154
	v_mad_i64_i32 v[80:81], s[14:15], s26, v80, 0
	v_lshlrev_b64 v[80:81], 1, v[80:81]
	v_cvt_pk_bf16_f32 v87, v82, v83
	v_lshl_add_u64 v[82:83], v[152:153], 0, v[80:81]
	global_store_dwordx4 v[82:83], v[84:87], off sc1
	v_cvt_pk_bf16_f32 v76, v76, v77
	v_cvt_pk_bf16_f32 v77, v78, v79
	v_cvt_pk_bf16_f32 v78, v72, v73
	v_add_u32_e32 v72, 0xa0, v154
	v_mad_i64_i32 v[72:73], s[14:15], s26, v72, 0
	v_lshlrev_b64 v[72:73], 1, v[72:73]
	v_cvt_pk_bf16_f32 v79, v74, v75
	v_lshl_add_u64 v[74:75], v[152:153], 0, v[72:73]
	global_store_dwordx4 v[74:75], v[76:79], off sc1
	v_cvt_pk_bf16_f32 v68, v68, v69
	v_cvt_pk_bf16_f32 v69, v70, v71
	v_cvt_pk_bf16_f32 v70, v64, v65
	v_add_u32_e32 v64, 0xb0, v154
	v_mad_i64_i32 v[64:65], s[14:15], s26, v64, 0
	v_lshlrev_b64 v[64:65], 1, v[64:65]
	v_cvt_pk_bf16_f32 v71, v66, v67
	v_lshl_add_u64 v[66:67], v[152:153], 0, v[64:65]
	global_store_dwordx4 v[66:67], v[68:71], off sc1
	v_cvt_pk_bf16_f32 v60, v60, v61
	v_cvt_pk_bf16_f32 v61, v62, v63
	v_cvt_pk_bf16_f32 v62, v56, v57
	v_cvt_pk_bf16_f32 v63, v58, v59
	s_nop 1
	v_add_u32_e32 v68, 0x80, v151
	v_ashrrev_i32_e32 v66, 6, v68
	v_mad_u64_u32 v[66:67], s[14:15], v66, s64, v[150:151]
	v_cndmask_b32_e32 v66, v68, v66, vcc
	v_ashrrev_i32_e32 v67, 31, v66
	v_lshl_add_u64 v[66:67], v[66:67], 1, s[4:5]
	v_lshl_add_u64 v[56:57], v[66:67], 0, v[120:121]
	global_store_dwordx4 v[56:57], v[60:63], off sc1
	v_cvt_pk_bf16_f32 v52, v52, v53
	v_cvt_pk_bf16_f32 v53, v54, v55
	v_cvt_pk_bf16_f32 v54, v48, v49
	v_lshl_add_u64 v[48:49], v[66:67], 0, v[112:113]
	v_cvt_pk_bf16_f32 v55, v50, v51
	global_store_dwordx4 v[48:49], v[52:55], off sc1
	v_cvt_pk_bf16_f32 v44, v44, v45
	v_cvt_pk_bf16_f32 v45, v46, v47
	v_cvt_pk_bf16_f32 v46, v40, v41
	v_lshl_add_u64 v[40:41], v[66:67], 0, v[104:105]
	v_cvt_pk_bf16_f32 v47, v42, v43
	global_store_dwordx4 v[40:41], v[44:47], off sc1
	v_cvt_pk_bf16_f32 v36, v36, v37
	v_cvt_pk_bf16_f32 v37, v38, v39
	v_cvt_pk_bf16_f32 v38, v32, v33
	v_lshl_add_u64 v[32:33], v[66:67], 0, v[96:97]
	v_cvt_pk_bf16_f32 v39, v34, v35
	global_store_dwordx4 v[32:33], v[36:39], off sc1
	v_cvt_pk_bf16_f32 v28, v28, v29
	v_cvt_pk_bf16_f32 v29, v30, v31
	v_cvt_pk_bf16_f32 v30, v24, v25
	v_lshl_add_u64 v[24:25], v[66:67], 0, v[88:89]
	v_cvt_pk_bf16_f32 v31, v26, v27
	global_store_dwordx4 v[24:25], v[28:31], off sc1
	v_cvt_pk_bf16_f32 v20, v20, v21
	v_cvt_pk_bf16_f32 v21, v22, v23
	v_cvt_pk_bf16_f32 v22, v16, v17
	v_lshl_add_u64 v[16:17], v[66:67], 0, v[80:81]
	v_cvt_pk_bf16_f32 v23, v18, v19
	global_store_dwordx4 v[16:17], v[20:23], off sc1
	v_cvt_pk_bf16_f32 v12, v12, v13
	v_cvt_pk_bf16_f32 v13, v14, v15
	v_cvt_pk_bf16_f32 v14, v8, v9
	v_lshl_add_u64 v[8:9], v[66:67], 0, v[72:73]
	v_cvt_pk_bf16_f32 v15, v10, v11
	global_store_dwordx4 v[8:9], v[12:15], off sc1
	v_cvt_pk_bf16_f32 v4, v4, v5
	v_cvt_pk_bf16_f32 v5, v6, v7
	v_cvt_pk_bf16_f32 v6, v0, v1
	v_lshl_add_u64 v[0:1], v[66:67], 0, v[64:65]
	s_and_b64 vcc, exec, s[8:9]
	s_mov_b64 s[4:5], -1
	v_cvt_pk_bf16_f32 v7, v2, v3
	global_store_dwordx4 v[0:1], v[4:7], off sc1
	s_cbranch_vccnz .LBB0_529
	s_andn2_b64 vcc, exec, s[16:17]
	s_cbranch_vccnz .LBB0_528
	s_barrier
	s_branch .LBB0_528

; __device__ __forceinline__ unsigned pkbf(float lo, float hi) { return pg8::cvt_pk_bf16(lo, hi); }
;     template <int MODE> __device__ __forceinline__ void run(AccRef acc, const Unit& u, int wr, int wc, int fr, int fq) const {
;     ...
;                     } else {
;                         w.x = pkbf(x[0], x[1]); w.y = pkbf(x[2], x[3]); w.z = pkbf(x[4], x[5]); w.w = pkbf(x[6], x[7]);
;                         *(u32x4*)(MIX + (size_t)row * 1024 + 512 + cc) = w;
;                     }
;                     __builtin_amdgcn_sched_barrier(0); asm volatile("" ::: "memory");
;                 }
;         }
;     }
;     __device__ __forceinline__ void operator()(AccRef acc, const Unit& u, int wr, int wc, int fr, int fq) const {
;         asm volatile("" : "+v"(fr), "+v"(fq));
;         const int seg = seg0 + (u.pn >> 1);
;         if (seg < 2) run<0>(acc, u, wr, wc, fr, fq); else if (seg < 4) run<1>(acc, u, wr, wc, fr, fq); else run<2>(acc, u, wr, wc, fr, fq);
.LBB0_816:
	s_ashr_i32 s18, s69, 1
	v_mov_b32_e32 v181, v165
	v_mov_b32_e32 v180, v174
	s_cmp_gt_i32 s18, 1
	s_mov_b64 s[0:1], -1
	s_cbranch_scc0 .LBB0_823
	s_lshl_b32 s19, s91, 8
	s_cmp_gt_u32 s18, 3
	v_lshlrev_b32_e32 v128, 3, v180
	s_cbranch_scc0 .LBB0_819
	s_add_i32 s0, s19, s87
	v_add_u32_e32 v134, s0, v181
	s_lshl_b32 s0, s69, 8
	s_and_b32 s0, s0, 0x100
	v_add_f32_e32 v132, 0, v124
	v_add_f32_e32 v130, 0, v121
	v_add_f32_e32 v133, 0, v125
	v_add_f32_e32 v131, 0, v122
	v_add_f32_e32 v135, 0, v126
	s_or_b32 s0, s0, s35
	v_add_f32_e32 v129, 0, v120
	v_add_f32_e32 v138, 0, v123
	v_add_f32_e32 v139, 0, v127
	v_cvt_pk_bf16_f32 v130, v129, v130
	v_cvt_pk_bf16_f32 v131, v131, v138
	v_cvt_pk_bf16_f32 v132, v132, v133
	v_cvt_pk_bf16_f32 v133, v135, v139
	v_ashrrev_i32_e32 v135, 31, v134
	v_add_u32_e32 v136, s0, v128
	v_lshlrev_b64 v[134:135], 11, v[134:135]
	v_ashrrev_i32_e32 v137, 31, v136
	v_lshl_add_u64 v[134:135], s[76:77], 0, v[134:135]
	v_lshl_add_u64 v[134:135], v[136:137], 1, v[134:135]
	global_store_dwordx4 v[134:135], v[130:133], off offset:1024 sc1
	s_nop 1
	v_add_f32_e32 v132, 0, v112
	v_add_f32_e32 v130, 0, v117
	v_add_f32_e32 v133, 0, v113
	v_add_f32_e32 v131, 0, v118
	v_add_f32_e32 v136, 0, v114
	v_add_f32_e32 v137, 0, v119
	s_mov_b64 s[0:1], 0x8000
	v_add_f32_e32 v129, 0, v116
	v_add_f32_e32 v138, 0, v115
	v_cvt_pk_bf16_f32 v130, v129, v130
	v_cvt_pk_bf16_f32 v131, v131, v137
	v_cvt_pk_bf16_f32 v132, v132, v133
	v_cvt_pk_bf16_f32 v133, v136, v138
	v_lshl_add_u64 v[136:137], v[134:135], 0, s[0:1]
	global_store_dwordx4 v[136:137], v[130:133], off offset:1024 sc1
	s_nop 1
	v_add_f32_e32 v132, 0, v104
	v_add_f32_e32 v130, 0, v109
	v_add_f32_e32 v133, 0, v105
	v_add_f32_e32 v131, 0, v110
	v_add_f32_e32 v138, 0, v106
	v_add_f32_e32 v139, 0, v111
	v_add_f32_e32 v129, 0, v108
	v_add_f32_e32 v156, 0, v107
	v_cvt_pk_bf16_f32 v130, v129, v130
	v_cvt_pk_bf16_f32 v131, v131, v139
	v_cvt_pk_bf16_f32 v132, v132, v133
	v_cvt_pk_bf16_f32 v133, v138, v156
	v_lshl_add_u64 v[138:139], v[134:135], 0, s[60:61]
	global_store_dwordx4 v[138:139], v[130:133], off offset:1024 sc1
	s_nop 1
	v_add_f32_e32 v132, 0, v96
	v_add_f32_e32 v130, 0, v101
	v_add_f32_e32 v133, 0, v97
	v_add_f32_e32 v131, 0, v102
	v_add_f32_e32 v156, 0, v98
	v_add_f32_e32 v157, 0, v103
	s_mov_b64 s[0:1], 0x18000
	v_add_f32_e32 v129, 0, v100
	v_add_f32_e32 v158, 0, v99
	v_cvt_pk_bf16_f32 v130, v129, v130
	v_cvt_pk_bf16_f32 v131, v131, v157
	v_cvt_pk_bf16_f32 v132, v132, v133
	v_cvt_pk_bf16_f32 v133, v156, v158
	v_lshl_add_u64 v[156:157], v[134:135], 0, s[0:1]
	global_store_dwordx4 v[156:157], v[130:133], off offset:1024 sc1
	s_nop 1
	v_add_f32_e32 v132, 0, v88
	v_add_f32_e32 v130, 0, v93
	v_add_f32_e32 v133, 0, v89
	v_add_f32_e32 v131, 0, v94
	v_add_f32_e32 v158, 0, v90
	v_add_f32_e32 v159, 0, v95
	s_mov_b64 s[0:1], 0x40000
	v_add_f32_e32 v129, 0, v92
	v_add_f32_e32 v160, 0, v91
	v_cvt_pk_bf16_f32 v130, v129, v130
	v_cvt_pk_bf16_f32 v131, v131, v159
	v_cvt_pk_bf16_f32 v132, v132, v133
	v_cvt_pk_bf16_f32 v133, v158, v160
	v_lshl_add_u64 v[158:159], v[134:135], 0, s[0:1]
	global_store_dwordx4 v[158:159], v[130:133], off offset:1024 sc1
	s_nop 1
	v_add_f32_e32 v132, 0, v80
	v_add_f32_e32 v130, 0, v85
	v_add_f32_e32 v133, 0, v81
	v_add_f32_e32 v131, 0, v86
	v_add_f32_e32 v160, 0, v82
	v_add_f32_e32 v161, 0, v87
	s_mov_b64 s[0:1], 0x48000
	v_add_f32_e32 v129, 0, v84
	v_add_f32_e32 v162, 0, v83
	v_cvt_pk_bf16_f32 v130, v129, v130
	v_cvt_pk_bf16_f32 v131, v131, v161
	v_cvt_pk_bf16_f32 v132, v132, v133
	v_cvt_pk_bf16_f32 v133, v160, v162
	v_lshl_add_u64 v[160:161], v[134:135], 0, s[0:1]
	global_store_dwordx4 v[160:161], v[130:133], off offset:1024 sc1
	s_nop 1
	v_add_f32_e32 v132, 0, v72
	v_add_f32_e32 v130, 0, v77
	v_add_f32_e32 v133, 0, v73
	v_add_f32_e32 v131, 0, v78
	v_add_f32_e32 v162, 0, v74
	v_add_f32_e32 v163, 0, v79
	s_mov_b64 s[0:1], 0x50000
	v_add_f32_e32 v129, 0, v76
	v_add_f32_e32 v168, 0, v75
	v_cvt_pk_bf16_f32 v130, v129, v130
	v_cvt_pk_bf16_f32 v131, v131, v163
	v_cvt_pk_bf16_f32 v132, v132, v133
	v_cvt_pk_bf16_f32 v133, v162, v168
	v_lshl_add_u64 v[162:163], v[134:135], 0, s[0:1]
	global_store_dwordx4 v[162:163], v[130:133], off offset:1024 sc1
	s_nop 1
	v_add_f32_e32 v132, 0, v64
	v_add_f32_e32 v130, 0, v69
	v_add_f32_e32 v133, 0, v65
	v_add_f32_e32 v131, 0, v70
	v_add_f32_e32 v168, 0, v66
	v_add_f32_e32 v169, 0, v71
	s_mov_b64 s[0:1], 0x58000
	v_add_f32_e32 v129, 0, v68
	v_add_f32_e32 v170, 0, v67
	v_cvt_pk_bf16_f32 v130, v129, v130
	v_cvt_pk_bf16_f32 v131, v131, v169
	v_cvt_pk_bf16_f32 v132, v132, v133
	v_cvt_pk_bf16_f32 v133, v168, v170
	v_lshl_add_u64 v[168:169], v[134:135], 0, s[0:1]
	global_store_dwordx4 v[168:169], v[130:133], off offset:1024 sc1
	s_nop 1
	v_add_f32_e32 v132, 0, v56
	v_add_f32_e32 v130, 0, v61
	v_add_f32_e32 v133, 0, v57
	v_add_f32_e32 v131, 0, v62
	v_add_f32_e32 v129, 0, v60
	v_add_f32_e32 v170, 0, v58
	v_add_f32_e32 v171, 0, v63
	v_add_f32_e32 v172, 0, v59
	v_cvt_pk_bf16_f32 v130, v129, v130
	v_cvt_pk_bf16_f32 v131, v131, v171
	v_cvt_pk_bf16_f32 v132, v132, v133
	v_cvt_pk_bf16_f32 v133, v170, v172
	global_store_dwordx4 v[134:135], v[130:133], off offset:1280 sc1
	s_nop 1
	v_add_f32_e32 v132, 0, v48
	v_add_f32_e32 v130, 0, v53
	v_add_f32_e32 v133, 0, v49
	v_add_f32_e32 v131, 0, v54
	v_add_f32_e32 v129, 0, v52
	v_add_f32_e32 v134, 0, v50
	v_add_f32_e32 v135, 0, v55
	v_add_f32_e32 v170, 0, v51
	v_cvt_pk_bf16_f32 v130, v129, v130
	v_cvt_pk_bf16_f32 v131, v131, v135
	v_cvt_pk_bf16_f32 v132, v132, v133
	v_cvt_pk_bf16_f32 v133, v134, v170
	global_store_dwordx4 v[136:137], v[130:133], off offset:1280 sc1
	s_nop 1
	v_add_f32_e32 v132, 0, v40
; __device__ __forceinline__ unsigned pkbf(float lo, float hi) { return pg8::cvt_pk_bf16(lo, hi); }
;     template <int MODE> __device__ __forceinline__ void run(AccRef acc, const Unit& u, int wr, int wc, int fr, int fq) const {
;         const int row0 = u.pm * 256 + wr * 64 + fr, seg = seg0 + (u.pn >> 1);
; #pragma unroll
;         for (int bj = 0; bj < 2; ++bj) {
;             const int cc = (u.pn & 1) * 256 + bj * 128 + wc * 32 + 8 * fq;
;             float bias[8];
;             if (MODE < 2) { const float* bp = (MODE == 0 ? w0 + seg * 512 : a0 + (seg - 2) * 512) + cc; const f32x4 b0 = *(const f32x4*)bp, b1 = *(const f32x4*)(bp + 4);
;                 bias[0] = b0[0]; bias[1] = b0[1]; bias[2] = b0[2]; bias[3] = b0[3]; bias[4] = b1[0]; bias[5] = b1[1]; bias[6] = b1[2]; bias[7] = b1[3]; }
;     ...
;                     } else {
;                         w.x = pkbf(x[0], x[1]); w.y = pkbf(x[2], x[3]); w.z = pkbf(x[4], x[5]); w.w = pkbf(x[6], x[7]);
;                         *(u32x4*)(MIX + (size_t)row * 1024 + 512 + cc) = w;
;                     }
;                     __builtin_amdgcn_sched_barrier(0); asm volatile("" ::: "memory");
;                 }
;         }
;     }
;     __device__ __forceinline__ void operator()(AccRef acc, const Unit& u, int wr, int wc, int fr, int fq) const {
;         asm volatile("" : "+v"(fr), "+v"(fq));
;         const int seg = seg0 + (u.pn >> 1);
;         if (seg < 2) run<0>(acc, u, wr, wc, fr, fq); else if (seg < 4) run<1>(acc, u, wr, wc, fr, fq); else run<2>(acc, u, wr, wc, fr, fq);
	v_add_f32_e32 v130, 0, v45
	v_add_f32_e32 v133, 0, v41
	v_add_f32_e32 v131, 0, v46
	v_add_f32_e32 v129, 0, v44
	v_add_f32_e32 v134, 0, v42
	v_add_f32_e32 v135, 0, v47
	v_add_f32_e32 v136, 0, v43
	v_cvt_pk_bf16_f32 v130, v129, v130
	v_cvt_pk_bf16_f32 v131, v131, v135
	v_cvt_pk_bf16_f32 v132, v132, v133
	v_cvt_pk_bf16_f32 v133, v134, v136
	global_store_dwordx4 v[138:139], v[130:133], off offset:1280 sc1
	s_nop 1
	v_add_f32_e32 v132, 0, v32
	v_add_f32_e32 v130, 0, v37
	v_add_f32_e32 v133, 0, v33
	v_add_f32_e32 v131, 0, v38
	v_add_f32_e32 v129, 0, v36
	v_add_f32_e32 v134, 0, v34
	v_add_f32_e32 v135, 0, v39
	v_add_f32_e32 v136, 0, v35
	v_cvt_pk_bf16_f32 v130, v129, v130
	v_cvt_pk_bf16_f32 v131, v131, v135
	v_cvt_pk_bf16_f32 v132, v132, v133
	v_cvt_pk_bf16_f32 v133, v134, v136
	global_store_dwordx4 v[156:157], v[130:133], off offset:1280 sc1
	s_nop 1
	v_add_f32_e32 v132, 0, v24
	v_add_f32_e32 v130, 0, v29
	v_add_f32_e32 v133, 0, v25
	v_add_f32_e32 v131, 0, v30
	v_add_f32_e32 v129, 0, v28
	v_add_f32_e32 v134, 0, v26
	v_add_f32_e32 v135, 0, v31
	v_add_f32_e32 v136, 0, v27
	v_cvt_pk_bf16_f32 v130, v129, v130
	v_cvt_pk_bf16_f32 v131, v131, v135
	v_cvt_pk_bf16_f32 v132, v132, v133
	v_cvt_pk_bf16_f32 v133, v134, v136
	global_store_dwordx4 v[158:159], v[130:133], off offset:1280 sc1
	s_nop 1
	v_add_f32_e32 v132, 0, v16
	v_add_f32_e32 v130, 0, v21
	v_add_f32_e32 v133, 0, v17
	v_add_f32_e32 v131, 0, v22
	v_add_f32_e32 v129, 0, v20
	v_add_f32_e32 v134, 0, v18
	v_add_f32_e32 v135, 0, v23
	v_add_f32_e32 v136, 0, v19
	v_cvt_pk_bf16_f32 v130, v129, v130
	v_cvt_pk_bf16_f32 v131, v131, v135
	v_cvt_pk_bf16_f32 v132, v132, v133
	v_cvt_pk_bf16_f32 v133, v134, v136
	global_store_dwordx4 v[160:161], v[130:133], off offset:1280 sc1
	s_nop 1
	v_add_f32_e32 v132, 0, v8
	v_add_f32_e32 v130, 0, v13
	v_add_f32_e32 v133, 0, v9
	v_add_f32_e32 v131, 0, v14
	v_add_f32_e32 v129, 0, v12
	v_add_f32_e32 v134, 0, v10
	v_add_f32_e32 v135, 0, v15
	v_add_f32_e32 v136, 0, v11
	v_cvt_pk_bf16_f32 v130, v129, v130
	v_cvt_pk_bf16_f32 v131, v131, v135
	v_cvt_pk_bf16_f32 v132, v132, v133
	v_cvt_pk_bf16_f32 v133, v134, v136
	global_store_dwordx4 v[162:163], v[130:133], off offset:1280 sc1
	s_nop 1
	v_add_f32_e32 v132, 0, v0
	v_add_f32_e32 v130, 0, v5
	v_add_f32_e32 v133, 0, v1
	v_add_f32_e32 v131, 0, v6
	v_add_f32_e32 v129, 0, v4
	v_add_f32_e32 v134, 0, v2
	v_add_f32_e32 v135, 0, v7
	v_add_f32_e32 v136, 0, v3
	v_cvt_pk_bf16_f32 v130, v129, v130
	v_cvt_pk_bf16_f32 v131, v131, v135
	v_cvt_pk_bf16_f32 v132, v132, v133
	v_cvt_pk_bf16_f32 v133, v134, v136
	global_store_dwordx4 v[168:169], v[130:133], off offset:1280 sc1
	s_mov_b64 s[0:1], 0
.LBB0_819:
	s_andn2_b64 vcc, exec, s[0:1]
	s_cbranch_vccnz .LBB0_821
	s_lshl_b32 s26, s69, 8
	s_and_b32 s0, s26, 0xfffffe00
	s_add_i32 s24, s0, 0xfffffc00
	s_add_i32 s19, s19, s87
	s_ashr_i32 s25, s24, 31
	v_add_u32_e32 v160, s19, v181
	s_and_b32 s19, s26, 0x100
	s_ashr_i32 s1, s0, 31
	s_or_b32 s19, s19, s35
	s_lshl_b64 s[24:25], s[24:25], 2
	v_readlane_b32 s36, v237, 37
	v_add_u32_e32 v158, s19, v128
	v_readlane_b32 s37, v237, 38
	s_add_u32 s24, s36, s24
	s_addc_u32 s25, s37, s25
	v_ashrrev_i32_e32 v159, 31, v158
	v_lshl_add_u64 v[156:157], v[158:159], 2, s[24:25]
	global_load_dwordx4 v[128:131], v[156:157], off offset:16
	global_load_dwordx4 v[132:135], v[156:157], off
	v_readlane_b32 s38, v237, 39
	v_readlane_b32 s39, v237, 40
	v_readlane_b32 s40, v237, 41
	v_readlane_b32 s41, v237, 42
	v_readlane_b32 s42, v237, 43
	v_readlane_b32 s43, v237, 44
	v_readlane_b32 s44, v237, 45
	v_readlane_b32 s45, v237, 46
	v_readlane_b32 s46, v237, 47
	v_readlane_b32 s47, v237, 48
	v_readlane_b32 s48, v237, 49
	v_readlane_b32 s49, v237, 50
	v_readlane_b32 s50, v237, 51
	v_readlane_b32 s51, v237, 52
	v_readlane_b32 s36, v236, 5
	v_readlane_b32 s48, v236, 17
	v_readlane_b32 s49, v236, 18
	v_readlane_b32 s38, v236, 7
	v_readlane_b32 s39, v236, 8
	v_readlane_b32 s46, v236, 15
	v_readlane_b32 s47, v236, 16
	v_readlane_b32 s37, v236, 6
	v_readlane_b32 s40, v236, 9
	v_readlane_b32 s41, v236, 10
	v_readlane_b32 s42, v236, 11
	v_readlane_b32 s43, v236, 12
	v_readlane_b32 s44, v236, 13
	v_readlane_b32 s45, v236, 14
	v_readlane_b32 s50, v236, 19
	v_readlane_b32 s51, v236, 20
	s_mov_b32 s47, 0x20000
	s_mov_b32 s46, 0x10000
	s_mov_b32 s39, 0x30000
	s_movk_i32 s38, 0x61
	s_waitcnt vmcnt(0)
; __device__ __forceinline__ float fsigmoid(float x) { return __builtin_amdgcn_rcpf(1.f + __builtin_amdgcn_exp2f(-1.4426950408889634f * x)); }
;     template <int MODE> __device__ __forceinline__ void run(AccRef acc, const Unit& u, int wr, int wc, int fr, int fq) const {
;     ...
;             if (MODE < 2) { const float* bp = (MODE == 0 ? w0 + seg * 512 : a0 + (seg - 2) * 512) + cc; const f32x4 b0 = *(const f32x4*)bp, b1 = *(const f32x4*)(bp + 4);
;                 bias[0] = b0[0]; bias[1] = b0[1]; bias[2] = b0[2]; bias[3] = b0[3]; bias[4] = b1[0]; bias[5] = b1[1]; bias[6] = b1[2]; bias[7] = b1[3]; }
;             else {
; #pragma unroll
;                 for (int e = 0; e < 8; ++e) bias[e] = 0.f; }
; #pragma unroll
;             for (int ai = 0; ai < 2; ++ai)
; #pragma unroll
;                 for (int m = 0; m < 4; ++m) {
;                     const int row = row0 + ai * 128 + m * 16;
;                     float x[8];
; #pragma unroll
;                     for (int e = 0; e < 4; ++e) { x[e] = acc[ai][bj][m][0][e] + bias[e]; x[4 + e] = acc[ai][bj][m][1][e] + bias[4 + e]; }
;                     u32x4 w;
;                     if (MODE == 0) {
; #pragma unroll
;                         for (int e = 0; e < 8; ++e) { const float sp = __logf(1.f + __expf(-x[e])); x[e] = __expf(-__expf(-sp - 0.5f)); }
;                         w.x = pkh(x[0], x[1]); w.y = pkh(x[2], x[3]); w.z = pkh(x[4], x[5]); w.w = pkh(x[6], x[7]);
;                         *(u32x4*)(WA + (size_t)row * 2048 + seg * 512 + cc) = w;
;                     } else if (MODE == 1) {
; #pragma unroll
;                         for (int e = 0; e < 8; ++e) x[e] = fsigmoid(x[e]);
;                         w.x = pkh(x[0], x[1]); w.y = pkh(x[2], x[3]); w.z = pkh(x[4], x[5]); w.w = pkh(x[6], x[7]);
;                         *(u32x4*)(WA + (size_t)row * 2048 + seg * 512 + cc) = w;
	v_add_f32_e32 v137, v124, v128
	v_mul_f32_e32 v137, 0xbfb8aa3b, v137
	v_exp_f32_e32 v137, v137
	v_add_f32_e32 v139, v125, v129
	v_add_f32_e32 v162, v126, v130
	v_add_f32_e32 v161, v122, v134
	v_add_f32_e32 v137, 1.0, v137
	v_rcp_f32_e32 v169, v137
	v_mul_f32_e32 v137, 0xbfb8aa3b, v139
	v_exp_f32_e32 v137, v137
	v_add_f32_e32 v163, v123, v135
	v_mul_f32_e32 v161, 0xbfb8aa3b, v161
	v_mul_f32_e32 v163, 0xbfb8aa3b, v163
	v_add_f32_e32 v137, 1.0, v137
	v_rcp_f32_e32 v139, v137
	v_mul_f32_e32 v137, 0xbfb8aa3b, v162
	v_exp_f32_e32 v137, v137
	v_exp_f32_e32 v161, v161
	v_exp_f32_e32 v163, v163
	v_add_f32_e32 v136, v120, v132
	v_add_f32_e32 v138, v121, v133
	v_add_f32_e32 v168, v127, v131
	v_add_f32_e32 v137, 1.0, v137
	v_mul_f32_e32 v136, 0xbfb8aa3b, v136
	v_mul_f32_e32 v138, 0xbfb8aa3b, v138
	v_rcp_f32_e32 v162, v137
	v_mul_f32_e32 v137, 0xbfb8aa3b, v168
	v_exp_f32_e32 v136, v136
	v_exp_f32_e32 v138, v138
	v_add_f32_e32 v161, 1.0, v161
	v_add_f32_e32 v163, 1.0, v163
	v_exp_f32_e32 v137, v137
	v_rcp_f32_e32 v161, v161
	v_rcp_f32_e32 v163, v163
	v_add_f32_e32 v136, 1.0, v136
	v_add_f32_e32 v138, 1.0, v138
	v_add_f32_e32 v137, 1.0, v137
	v_rcp_f32_e32 v136, v136
	v_rcp_f32_e32 v138, v138
	v_rcp_f32_e32 v168, v137
	v_cvt_pk_f16_f32 v137, v161, v163
	v_ashrrev_i32_e32 v161, 31, v160
	v_lshlrev_b64 v[160:161], 12, v[160:161]
	v_lshl_add_u64 v[160:161], s[48:49], 0, v[160:161]
	v_lshl_add_u64 v[160:161], s[0:1], 1, v[160:161]
	v_cvt_pk_f16_f32 v136, v136, v138
	v_cvt_pk_f16_f32 v138, v169, v139
	v_cvt_pk_f16_f32 v139, v162, v168
	v_lshl_add_u64 v[158:159], v[158:159], 1, v[160:161]
	global_store_dwordx4 v[158:159], v[136:139], off sc1
	v_add_f32_e32 v160, v118, v134
	v_add_f32_e32 v162, v119, v135
	v_mul_f32_e32 v160, 0xbfb8aa3b, v160
	v_exp_f32_e32 v160, v160
	v_mul_f32_e32 v162, 0xbfb8aa3b, v162
	v_exp_f32_e32 v162, v162
	v_add_f32_e32 v136, v116, v132
	v_add_f32_e32 v160, 1.0, v160
	v_add_f32_e32 v138, v117, v133
	v_add_f32_e32 v161, v114, v130
	v_rcp_f32_e32 v168, v160
	v_add_f32_e32 v160, 1.0, v162
	v_add_f32_e32 v137, v112, v128
	v_add_f32_e32 v139, v113, v129
	v_mul_f32_e32 v136, 0xbfb8aa3b, v136
	v_mul_f32_e32 v138, 0xbfb8aa3b, v138
	v_add_f32_e32 v163, v115, v131
	v_rcp_f32_e32 v162, v160
	v_mul_f32_e32 v160, 0xbfb8aa3b, v161
	v_exp_f32_e32 v136, v136
	v_exp_f32_e32 v138, v138
	v_mul_f32_e32 v137, 0xbfb8aa3b, v137
	v_mul_f32_e32 v139, 0xbfb8aa3b, v139
	v_exp_f32_e32 v160, v160
	v_mul_f32_e32 v161, 0xbfb8aa3b, v163
	v_exp_f32_e32 v137, v137
	v_exp_f32_e32 v139, v139
	v_exp_f32_e32 v161, v161
	v_add_f32_e32 v136, 1.0, v136
	v_add_f32_e32 v138, 1.0, v138
	v_add_f32_e32 v160, 1.0, v160
	v_rcp_f32_e32 v136, v136
	v_rcp_f32_e32 v138, v138
	v_add_f32_e32 v137, 1.0, v137
	v_add_f32_e32 v139, 1.0, v139
	v_rcp_f32_e32 v163, v160
	v_add_f32_e32 v160, 1.0, v161
	v_rcp_f32_e32 v137, v137
	v_rcp_f32_e32 v139, v139
	v_rcp_f32_e32 v169, v160
	v_cvt_pk_f16_f32 v160, v136, v138
	v_add_co_u32_e32 v138, vcc, s46, v158
	v_cvt_pk_f16_f32 v161, v168, v162
	v_cvt_pk_f16_f32 v162, v137, v139
	v_cvt_pk_f16_f32 v163, v163, v169
	v_addc_co_u32_e32 v139, vcc, 0, v159, vcc
	v_lshl_add_u64 v[136:137], v[158:159], 0, s[60:61]
	global_store_dwordx4 v[138:139], v[160:163], off sc1
	s_nop 1
	v_add_f32_e32 v161, v105, v129
	v_add_f32_e32 v162, v110, v134
	v_add_f32_e32 v163, v106, v130
	v_add_f32_e32 v168, v111, v135
	v_mul_f32_e32 v161, 0xbfb8aa3b, v161
	v_add_f32_e32 v138, v108, v132
	v_add_f32_e32 v139, v104, v128
	v_add_f32_e32 v160, v109, v133
	v_add_f32_e32 v169, v107, v131
	v_mul_f32_e32 v162, 0xbfb8aa3b, v162
	v_mul_f32_e32 v168, 0xbfb8aa3b, v168
	v_exp_f32_e32 v161, v161
	v_mul_f32_e32 v163, 0xbfb8aa3b, v163
	v_mul_f32_e32 v138, 0xbfb8aa3b, v138
	v_mul_f32_e32 v160, 0xbfb8aa3b, v160
	v_exp_f32_e32 v162, v162
	v_exp_f32_e32 v168, v168
	v_mul_f32_e32 v139, 0xbfb8aa3b, v139
	v_exp_f32_e32 v163, v163
	v_mul_f32_e32 v169, 0xbfb8aa3b, v169
	v_exp_f32_e32 v138, v138
	v_exp_f32_e32 v160, v160
	v_exp_f32_e32 v139, v139
	v_exp_f32_e32 v169, v169
	v_add_f32_e32 v161, 1.0, v161
	v_add_f32_e32 v162, 1.0, v162
	v_add_f32_e32 v168, 1.0, v168
	v_rcp_f32_e32 v170, v161
	v_add_f32_e32 v161, 1.0, v163
	v_add_f32_e32 v138, 1.0, v138
	v_add_f32_e32 v160, 1.0, v160
	v_rcp_f32_e32 v162, v162
	v_rcp_f32_e32 v168, v168
	v_add_f32_e32 v139, 1.0, v139
	v_rcp_f32_e32 v163, v161
	v_add_f32_e32 v161, 1.0, v169
	v_rcp_f32_e32 v138, v138
	v_rcp_f32_e32 v160, v160
	v_rcp_f32_e32 v139, v139
	v_rcp_f32_e32 v169, v161
	v_cvt_pk_f16_f32 v161, v162, v168
	v_add_co_u32_e32 v168, vcc, s47, v158
	v_cvt_pk_f16_f32 v160, v138, v160
	v_cvt_pk_f16_f32 v162, v139, v170
	v_cvt_pk_f16_f32 v163, v163, v169
	s_mov_b64 s[0:1], 0x20000
	v_addc_co_u32_e32 v169, vcc, 0, v159, vcc
	v_lshl_add_u64 v[138:139], v[158:159], 0, s[0:1]
	global_store_dwordx4 v[168:169], v[160:163], off sc1
	v_add_f32_e32 v168, v102, v134
	v_add_f32_e32 v170, v103, v135
	v_mul_f32_e32 v168, 0xbfb8aa3b, v168
	v_exp_f32_e32 v168, v168
	v_mul_f32_e32 v170, 0xbfb8aa3b, v170
	v_exp_f32_e32 v170, v170
	v_add_f32_e32 v160, v100, v132
	v_add_f32_e32 v168, 1.0, v168
	v_add_f32_e32 v162, v101, v133
	v_add_f32_e32 v169, v98, v130
	v_rcp_f32_e32 v172, v168
	v_add_f32_e32 v168, 1.0, v170
	v_add_f32_e32 v161, v96, v128
	v_add_f32_e32 v163, v97, v129
	v_mul_f32_e32 v160, 0xbfb8aa3b, v160
	v_mul_f32_e32 v162, 0xbfb8aa3b, v162
	v_add_f32_e32 v171, v99, v131
	v_rcp_f32_e32 v170, v168
	v_mul_f32_e32 v168, 0xbfb8aa3b, v169
	v_exp_f32_e32 v160, v160
	v_exp_f32_e32 v162, v162
	v_mul_f32_e32 v161, 0xbfb8aa3b, v161
	v_mul_f32_e32 v163, 0xbfb8aa3b, v163
	v_exp_f32_e32 v168, v168
	v_mul_f32_e32 v169, 0xbfb8aa3b, v171
	v_exp_f32_e32 v161, v161
	v_exp_f32_e32 v163, v163
; __device__ __forceinline__ float fsigmoid(float x) { return __builtin_amdgcn_rcpf(1.f + __builtin_amdgcn_exp2f(-1.4426950408889634f * x)); }
;     template <int MODE> __device__ __forceinline__ void run(AccRef acc, const Unit& u, int wr, int wc, int fr, int fq) const {
;     ...
;                     for (int e = 0; e < 4; ++e) { x[e] = acc[ai][bj][m][0][e] + bias[e]; x[4 + e] = acc[ai][bj][m][1][e] + bias[4 + e]; }
;                     u32x4 w;
;                     if (MODE == 0) {
; #pragma unroll
;                         for (int e = 0; e < 8; ++e) { const float sp = __logf(1.f + __expf(-x[e])); x[e] = __expf(-__expf(-sp - 0.5f)); }
;                         w.x = pkh(x[0], x[1]); w.y = pkh(x[2], x[3]); w.z = pkh(x[4], x[5]); w.w = pkh(x[6], x[7]);
;                         *(u32x4*)(WA + (size_t)row * 2048 + seg * 512 + cc) = w;
;                     } else if (MODE == 1) {
; #pragma unroll
;                         for (int e = 0; e < 8; ++e) x[e] = fsigmoid(x[e]);
;                         w.x = pkh(x[0], x[1]); w.y = pkh(x[2], x[3]); w.z = pkh(x[4], x[5]); w.w = pkh(x[6], x[7]);
;                         *(u32x4*)(WA + (size_t)row * 2048 + seg * 512 + cc) = w;
	v_exp_f32_e32 v169, v169
	v_add_f32_e32 v160, 1.0, v160
	v_add_f32_e32 v162, 1.0, v162
	v_add_f32_e32 v168, 1.0, v168
	v_rcp_f32_e32 v160, v160
	v_rcp_f32_e32 v162, v162
	v_add_f32_e32 v161, 1.0, v161
	v_add_f32_e32 v163, 1.0, v163
	v_rcp_f32_e32 v171, v168
	v_add_f32_e32 v168, 1.0, v169
	v_rcp_f32_e32 v161, v161
	v_rcp_f32_e32 v163, v163
	v_rcp_f32_e32 v173, v168
	v_cvt_pk_f16_f32 v168, v160, v162
	v_add_co_u32_e32 v162, vcc, s39, v158
	v_cvt_pk_f16_f32 v169, v172, v170
	v_cvt_pk_f16_f32 v170, v161, v163
	v_cvt_pk_f16_f32 v171, v171, v173
	s_mov_b64 s[0:1], 0x30000
	v_addc_co_u32_e32 v163, vcc, 0, v159, vcc
	v_lshl_add_u64 v[160:161], v[158:159], 0, s[0:1]
	global_store_dwordx4 v[162:163], v[168:171], off sc1
	v_add_f32_e32 v162, v92, v132
	v_add_f32_e32 v163, v88, v128
	v_add_f32_e32 v168, v93, v133
	v_add_f32_e32 v169, v89, v129
	v_add_f32_e32 v170, v94, v134
	v_add_f32_e32 v172, v95, v135
	v_add_f32_e32 v171, v90, v130
	v_mul_f32_e32 v162, 0xbfb8aa3b, v162
	v_mul_f32_e32 v168, 0xbfb8aa3b, v168
	v_mul_f32_e32 v170, 0xbfb8aa3b, v170
	v_mul_f32_e32 v172, 0xbfb8aa3b, v172
	v_mul_f32_e32 v163, 0xbfb8aa3b, v163
	v_mul_f32_e32 v169, 0xbfb8aa3b, v169
	v_exp_f32_e32 v162, v162
	v_exp_f32_e32 v168, v168
	v_add_f32_e32 v173, v91, v131
	v_exp_f32_e32 v170, v170
	v_exp_f32_e32 v172, v172
	v_exp_f32_e32 v163, v163
	v_exp_f32_e32 v169, v169
	v_mul_f32_e32 v171, 0xbfb8aa3b, v171
	v_exp_f32_e32 v171, v171
	v_mul_f32_e32 v173, 0xbfb8aa3b, v173
	v_exp_f32_e32 v173, v173
	v_add_f32_e32 v162, 1.0, v162
	v_add_f32_e32 v168, 1.0, v168
	v_add_f32_e32 v170, 1.0, v170
	v_add_f32_e32 v172, 1.0, v172
	v_add_f32_e32 v163, 1.0, v163
	v_add_f32_e32 v169, 1.0, v169
	v_rcp_f32_e32 v162, v162
	v_rcp_f32_e32 v168, v168
	v_rcp_f32_e32 v170, v170
	v_rcp_f32_e32 v172, v172
	v_rcp_f32_e32 v163, v163
	v_rcp_f32_e32 v182, v169
	v_add_f32_e32 v169, 1.0, v171
	v_rcp_f32_e32 v171, v169
	v_add_f32_e32 v169, 1.0, v173
	v_rcp_f32_e32 v173, v169
	s_mov_b64 s[0:1], 0x80000
	v_cvt_pk_f16_f32 v168, v162, v168
	v_cvt_pk_f16_f32 v169, v170, v172
	v_cvt_pk_f16_f32 v170, v163, v182
	v_lshl_add_u64 v[162:163], v[158:159], 0, s[0:1]
	s_mov_b32 s0, 0x80000
	v_add_co_u32_e32 v172, vcc, s0, v158
	v_cvt_pk_f16_f32 v171, v171, v173
	s_nop 0
	v_addc_co_u32_e32 v173, vcc, 0, v159, vcc
	global_store_dwordx4 v[172:173], v[168:171], off sc1
	s_nop 1
	v_add_f32_e32 v171, v81, v129
	v_add_f32_e32 v172, v86, v134
	v_add_f32_e32 v173, v82, v130
	v_add_f32_e32 v182, v87, v135
	v_mul_f32_e32 v171, 0xbfb8aa3b, v171
	v_add_f32_e32 v168, v84, v132
	v_add_f32_e32 v169, v80, v128
	v_add_f32_e32 v170, v85, v133
	v_add_f32_e32 v183, v83, v131
	v_mul_f32_e32 v172, 0xbfb8aa3b, v172
	v_mul_f32_e32 v182, 0xbfb8aa3b, v182
	v_exp_f32_e32 v171, v171
	v_mul_f32_e32 v173, 0xbfb8aa3b, v173
	v_mul_f32_e32 v168, 0xbfb8aa3b, v168
	v_mul_f32_e32 v170, 0xbfb8aa3b, v170
	v_exp_f32_e32 v172, v172
	v_exp_f32_e32 v182, v182
	v_mul_f32_e32 v169, 0xbfb8aa3b, v169
	v_exp_f32_e32 v173, v173
	v_mul_f32_e32 v183, 0xbfb8aa3b, v183
	v_exp_f32_e32 v168, v168
	v_exp_f32_e32 v170, v170
	v_exp_f32_e32 v169, v169
	v_exp_f32_e32 v183, v183
	v_add_f32_e32 v171, 1.0, v171
	v_add_f32_e32 v172, 1.0, v172
	v_add_f32_e32 v182, 1.0, v182
	v_rcp_f32_e32 v184, v171
	v_add_f32_e32 v171, 1.0, v173
	v_add_f32_e32 v168, 1.0, v168
	v_add_f32_e32 v170, 1.0, v170
	v_rcp_f32_e32 v172, v172
	v_rcp_f32_e32 v182, v182
	v_add_f32_e32 v169, 1.0, v169
	v_rcp_f32_e32 v173, v171
	v_add_f32_e32 v171, 1.0, v183
	v_rcp_f32_e32 v168, v168
	v_rcp_f32_e32 v170, v170
	v_rcp_f32_e32 v169, v169
	v_rcp_f32_e32 v183, v171
	v_cvt_pk_f16_f32 v171, v172, v182
	v_add_co_u32_e32 v182, vcc, s62, v158
	v_cvt_pk_f16_f32 v170, v168, v170
	v_cvt_pk_f16_f32 v172, v169, v184
	v_cvt_pk_f16_f32 v173, v173, v183
	s_mov_b64 s[0:1], 0x90000
	v_addc_co_u32_e32 v183, vcc, 0, v159, vcc
	v_lshl_add_u64 v[168:169], v[158:159], 0, s[0:1]
	global_store_dwordx4 v[182:183], v[170:173], off sc1
	v_add_f32_e32 v182, v78, v134
	v_add_f32_e32 v184, v79, v135
	v_mul_f32_e32 v182, 0xbfb8aa3b, v182
	v_exp_f32_e32 v182, v182
	v_mul_f32_e32 v184, 0xbfb8aa3b, v184
	v_exp_f32_e32 v184, v184
	v_add_f32_e32 v170, v76, v132
	v_add_f32_e32 v182, 1.0, v182
	v_add_f32_e32 v172, v77, v133
	v_add_f32_e32 v183, v74, v130
	v_rcp_f32_e32 v186, v182
	v_add_f32_e32 v182, 1.0, v184
	v_add_f32_e32 v171, v72, v128
	v_add_f32_e32 v173, v73, v129
	v_mul_f32_e32 v170, 0xbfb8aa3b, v170
	v_mul_f32_e32 v172, 0xbfb8aa3b, v172
	v_add_f32_e32 v185, v75, v131
	v_rcp_f32_e32 v184, v182
	v_mul_f32_e32 v182, 0xbfb8aa3b, v183
	v_exp_f32_e32 v170, v170
	v_exp_f32_e32 v172, v172
	v_mul_f32_e32 v171, 0xbfb8aa3b, v171
	v_mul_f32_e32 v173, 0xbfb8aa3b, v173
	v_exp_f32_e32 v182, v182
	v_mul_f32_e32 v183, 0xbfb8aa3b, v185
	v_exp_f32_e32 v171, v171
	v_exp_f32_e32 v173, v173
	v_exp_f32_e32 v183, v183
	v_add_f32_e32 v170, 1.0, v170
	v_add_f32_e32 v172, 1.0, v172
	v_add_f32_e32 v182, 1.0, v182
	v_rcp_f32_e32 v170, v170
	v_rcp_f32_e32 v172, v172
	v_add_f32_e32 v171, 1.0, v171
	v_add_f32_e32 v173, 1.0, v173
	v_rcp_f32_e32 v185, v182
	v_add_f32_e32 v182, 1.0, v183
	v_rcp_f32_e32 v171, v171
	v_rcp_f32_e32 v173, v173
	v_rcp_f32_e32 v187, v182
	v_cvt_pk_f16_f32 v182, v170, v172
	v_add_co_u32_e32 v172, vcc, s63, v158
	v_cvt_pk_f16_f32 v183, v186, v184
	v_cvt_pk_f16_f32 v184, v171, v173
	v_cvt_pk_f16_f32 v185, v185, v187
	v_addc_co_u32_e32 v173, vcc, 0, v159, vcc
	v_lshl_add_u64 v[170:171], v[158:159], 0, s[70:71]
	global_store_dwordx4 v[172:173], v[182:185], off sc1
	v_add_f32_e32 v128, v64, v128
	v_add_f32_e32 v129, v65, v129
	v_mul_f32_e32 v128, 0xbfb8aa3b, v128
	v_exp_f32_e32 v128, v128
	v_mul_f32_e32 v129, 0xbfb8aa3b, v129
	v_exp_f32_e32 v129, v129
; __device__ __forceinline__ float fsigmoid(float x) { return __builtin_amdgcn_rcpf(1.f + __builtin_amdgcn_exp2f(-1.4426950408889634f * x)); }
;     template <int MODE> __device__ __forceinline__ void run(AccRef acc, const Unit& u, int wr, int wc, int fr, int fq) const {
;     ...
;             if (MODE < 2) { const float* bp = (MODE == 0 ? w0 + seg * 512 : a0 + (seg - 2) * 512) + cc; const f32x4 b0 = *(const f32x4*)bp, b1 = *(const f32x4*)(bp + 4);
;                 bias[0] = b0[0]; bias[1] = b0[1]; bias[2] = b0[2]; bias[3] = b0[3]; bias[4] = b1[0]; bias[5] = b1[1]; bias[6] = b1[2]; bias[7] = b1[3]; }
;             else {
; #pragma unroll
;                 for (int e = 0; e < 8; ++e) bias[e] = 0.f; }
; #pragma unroll
;             for (int ai = 0; ai < 2; ++ai)
; #pragma unroll
;                 for (int m = 0; m < 4; ++m) {
;                     const int row = row0 + ai * 128 + m * 16;
;                     float x[8];
; #pragma unroll
;                     for (int e = 0; e < 4; ++e) { x[e] = acc[ai][bj][m][0][e] + bias[e]; x[4 + e] = acc[ai][bj][m][1][e] + bias[4 + e]; }
;                     u32x4 w;
;                     if (MODE == 0) {
; #pragma unroll
;                         for (int e = 0; e < 8; ++e) { const float sp = __logf(1.f + __expf(-x[e])); x[e] = __expf(-__expf(-sp - 0.5f)); }
;                         w.x = pkh(x[0], x[1]); w.y = pkh(x[2], x[3]); w.z = pkh(x[4], x[5]); w.w = pkh(x[6], x[7]);
;                         *(u32x4*)(WA + (size_t)row * 2048 + seg * 512 + cc) = w;
;                     } else if (MODE == 1) {
; #pragma unroll
;                         for (int e = 0; e < 8; ++e) x[e] = fsigmoid(x[e]);
;                         w.x = pkh(x[0], x[1]); w.y = pkh(x[2], x[3]); w.z = pkh(x[4], x[5]); w.w = pkh(x[6], x[7]);
;                         *(u32x4*)(WA + (size_t)row * 2048 + seg * 512 + cc) = w;
	v_add_f32_e32 v132, v68, v132
	v_add_f32_e32 v133, v69, v133
	v_add_f32_e32 v130, v66, v130
	v_add_f32_e32 v128, 1.0, v128
	v_add_f32_e32 v134, v70, v134
	v_add_f32_e32 v135, v71, v135
	v_mul_f32_e32 v132, 0xbfb8aa3b, v132
	v_mul_f32_e32 v133, 0xbfb8aa3b, v133
	v_add_f32_e32 v131, v67, v131
	v_rcp_f32_e32 v172, v128
	v_add_f32_e32 v128, 1.0, v129
	v_mul_f32_e32 v129, 0xbfb8aa3b, v130
	v_exp_f32_e32 v132, v132
	v_exp_f32_e32 v133, v133
	v_mul_f32_e32 v134, 0xbfb8aa3b, v134
	v_mul_f32_e32 v135, 0xbfb8aa3b, v135
	v_exp_f32_e32 v129, v129
	v_mul_f32_e32 v130, 0xbfb8aa3b, v131
	v_exp_f32_e32 v134, v134
	v_exp_f32_e32 v135, v135
	v_exp_f32_e32 v130, v130
	v_add_f32_e32 v132, 1.0, v132
	v_add_f32_e32 v133, 1.0, v133
	v_rcp_f32_e32 v131, v128
	v_add_f32_e32 v128, 1.0, v129
	v_rcp_f32_e32 v132, v132
	v_rcp_f32_e32 v133, v133
	v_add_f32_e32 v134, 1.0, v134
	v_add_f32_e32 v135, 1.0, v135
	v_rcp_f32_e32 v173, v128
	v_add_f32_e32 v128, 1.0, v130
	v_rcp_f32_e32 v134, v134
	v_rcp_f32_e32 v135, v135
	v_rcp_f32_e32 v182, v128
	v_cvt_pk_f16_f32 v128, v132, v133
	v_add_co_u32_e32 v132, vcc, s90, v158
	v_cvt_pk_f16_f32 v129, v134, v135
	v_cvt_pk_f16_f32 v130, v172, v131
	v_cvt_pk_f16_f32 v131, v173, v182
	v_addc_co_u32_e32 v133, vcc, 0, v159, vcc
	v_lshl_add_u64 v[172:173], v[158:159], 0, s[94:95]
	global_store_dwordx4 v[132:133], v[128:131], off sc1
	global_load_dwordx4 v[132:135], v[156:157], off offset:512
	global_load_dwordx4 v[128:131], v[156:157], off offset:528
	s_waitcnt vmcnt(0)
	v_add_f32_e32 v156, v60, v132
	v_add_f32_e32 v157, v56, v128
	v_add_f32_e32 v182, v61, v133
	v_add_f32_e32 v183, v57, v129
	v_add_f32_e32 v184, v62, v134
	v_add_f32_e32 v185, v58, v130
	v_add_f32_e32 v186, v63, v135
	v_add_f32_e32 v187, v59, v131
	v_mul_f32_e32 v156, 0xbfb8aa3b, v156
	v_mul_f32_e32 v182, 0xbfb8aa3b, v182
	v_mul_f32_e32 v184, 0xbfb8aa3b, v184
	v_mul_f32_e32 v186, 0xbfb8aa3b, v186
	v_mul_f32_e32 v157, 0xbfb8aa3b, v157
	v_mul_f32_e32 v183, 0xbfb8aa3b, v183
	v_mul_f32_e32 v185, 0xbfb8aa3b, v185
	v_mul_f32_e32 v187, 0xbfb8aa3b, v187
	v_exp_f32_e32 v156, v156
	v_exp_f32_e32 v182, v182
	v_exp_f32_e32 v184, v184
	v_exp_f32_e32 v186, v186
	v_exp_f32_e32 v157, v157
	v_exp_f32_e32 v183, v183
	v_exp_f32_e32 v185, v185
	v_exp_f32_e32 v187, v187
	v_add_f32_e32 v156, 1.0, v156
	v_add_f32_e32 v182, 1.0, v182
	v_add_f32_e32 v184, 1.0, v184
	v_add_f32_e32 v186, 1.0, v186
	v_add_f32_e32 v157, 1.0, v157
	v_add_f32_e32 v183, 1.0, v183
	v_add_f32_e32 v185, 1.0, v185
	v_add_f32_e32 v187, 1.0, v187
	v_rcp_f32_e32 v156, v156
	v_rcp_f32_e32 v182, v182
	v_rcp_f32_e32 v184, v184
	v_rcp_f32_e32 v186, v186
	v_rcp_f32_e32 v157, v157
	v_rcp_f32_e32 v188, v183
	v_rcp_f32_e32 v185, v185
	v_rcp_f32_e32 v187, v187
	v_cvt_pk_f16_f32 v182, v156, v182
	v_cvt_pk_f16_f32 v183, v184, v186
	v_cvt_pk_f16_f32 v184, v157, v188
	v_cvt_pk_f16_f32 v185, v185, v187
	global_store_dwordx4 v[158:159], v[182:185], off offset:256 sc1
	v_add_f32_e32 v157, v48, v128
	v_add_f32_e32 v159, v49, v129
	v_mul_f32_e32 v157, 0xbfb8aa3b, v157
	v_exp_f32_e32 v157, v157
	v_mul_f32_e32 v159, 0xbfb8aa3b, v159
	v_exp_f32_e32 v159, v159
	v_add_f32_e32 v183, v50, v130
	v_add_f32_e32 v157, 1.0, v157
	v_add_f32_e32 v156, v52, v132
	v_add_f32_e32 v158, v53, v133
	v_add_f32_e32 v182, v54, v134
	v_add_f32_e32 v184, v55, v135
	v_add_f32_e32 v185, v51, v131
	v_rcp_f32_e32 v186, v157
	v_add_f32_e32 v157, 1.0, v159
	v_mul_f32_e32 v159, 0xbfb8aa3b, v183
	v_mul_f32_e32 v156, 0xbfb8aa3b, v156
	v_mul_f32_e32 v158, 0xbfb8aa3b, v158
	v_mul_f32_e32 v182, 0xbfb8aa3b, v182
	v_mul_f32_e32 v184, 0xbfb8aa3b, v184
	v_exp_f32_e32 v159, v159
	v_mul_f32_e32 v183, 0xbfb8aa3b, v185
	v_exp_f32_e32 v156, v156
	v_exp_f32_e32 v158, v158
	v_exp_f32_e32 v182, v182
	v_exp_f32_e32 v184, v184
	v_exp_f32_e32 v183, v183
	v_rcp_f32_e32 v185, v157
	v_add_f32_e32 v157, 1.0, v159
	v_add_f32_e32 v156, 1.0, v156
	v_add_f32_e32 v158, 1.0, v158
	v_add_f32_e32 v182, 1.0, v182
	v_add_f32_e32 v184, 1.0, v184
	v_rcp_f32_e32 v159, v157
	v_add_f32_e32 v157, 1.0, v183
	v_rcp_f32_e32 v156, v156
	v_rcp_f32_e32 v158, v158
	v_rcp_f32_e32 v182, v182
	v_rcp_f32_e32 v184, v184
	v_rcp_f32_e32 v183, v157
	v_cvt_pk_f16_f32 v156, v156, v158
	v_cvt_pk_f16_f32 v157, v182, v184
	v_cvt_pk_f16_f32 v158, v186, v185
	v_cvt_pk_f16_f32 v159, v159, v183
	global_store_dwordx4 v[136:137], v[156:159], off offset:256 sc1
	s_nop 1
	v_add_f32_e32 v157, v41, v129
	v_add_f32_e32 v159, v42, v130
	v_mul_f32_e32 v157, 0xbfb8aa3b, v157
	v_add_f32_e32 v136, v44, v132
	v_add_f32_e32 v137, v40, v128
	v_add_f32_e32 v156, v45, v133
	v_add_f32_e32 v158, v46, v134
	v_add_f32_e32 v182, v47, v135
	v_add_f32_e32 v183, v43, v131
	v_exp_f32_e32 v157, v157
	v_mul_f32_e32 v159, 0xbfb8aa3b, v159
	v_mul_f32_e32 v136, 0xbfb8aa3b, v136
	v_mul_f32_e32 v156, 0xbfb8aa3b, v156
	v_mul_f32_e32 v158, 0xbfb8aa3b, v158
	v_mul_f32_e32 v182, 0xbfb8aa3b, v182
	v_mul_f32_e32 v137, 0xbfb8aa3b, v137
	v_exp_f32_e32 v159, v159
	v_mul_f32_e32 v183, 0xbfb8aa3b, v183
	v_exp_f32_e32 v136, v136
	v_exp_f32_e32 v156, v156
	v_exp_f32_e32 v158, v158
	v_exp_f32_e32 v182, v182
	v_exp_f32_e32 v137, v137
	v_exp_f32_e32 v183, v183
	v_add_f32_e32 v157, 1.0, v157
	v_rcp_f32_e32 v184, v157
	v_add_f32_e32 v157, 1.0, v159
	v_add_f32_e32 v136, 1.0, v136
	v_add_f32_e32 v156, 1.0, v156
	v_add_f32_e32 v158, 1.0, v158
	v_add_f32_e32 v182, 1.0, v182
	v_add_f32_e32 v137, 1.0, v137
	v_rcp_f32_e32 v159, v157
	v_add_f32_e32 v157, 1.0, v183
	v_rcp_f32_e32 v136, v136
	v_rcp_f32_e32 v156, v156
	v_rcp_f32_e32 v158, v158
	v_rcp_f32_e32 v182, v182
	v_rcp_f32_e32 v137, v137
	v_rcp_f32_e32 v183, v157
	v_cvt_pk_f16_f32 v156, v136, v156
	v_cvt_pk_f16_f32 v157, v158, v182
; __device__ __forceinline__ float fsigmoid(float x) { return __builtin_amdgcn_rcpf(1.f + __builtin_amdgcn_exp2f(-1.4426950408889634f * x)); }
;     template <int MODE> __device__ __forceinline__ void run(AccRef acc, const Unit& u, int wr, int wc, int fr, int fq) const {
;     ...
;                     for (int e = 0; e < 4; ++e) { x[e] = acc[ai][bj][m][0][e] + bias[e]; x[4 + e] = acc[ai][bj][m][1][e] + bias[4 + e]; }
;                     u32x4 w;
;                     if (MODE == 0) {
; #pragma unroll
;                         for (int e = 0; e < 8; ++e) { const float sp = __logf(1.f + __expf(-x[e])); x[e] = __expf(-__expf(-sp - 0.5f)); }
;                         w.x = pkh(x[0], x[1]); w.y = pkh(x[2], x[3]); w.z = pkh(x[4], x[5]); w.w = pkh(x[6], x[7]);
;                         *(u32x4*)(WA + (size_t)row * 2048 + seg * 512 + cc) = w;
;                     } else if (MODE == 1) {
; #pragma unroll
;                         for (int e = 0; e < 8; ++e) x[e] = fsigmoid(x[e]);
;                         w.x = pkh(x[0], x[1]); w.y = pkh(x[2], x[3]); w.z = pkh(x[4], x[5]); w.w = pkh(x[6], x[7]);
;                         *(u32x4*)(WA + (size_t)row * 2048 + seg * 512 + cc) = w;
	v_cvt_pk_f16_f32 v158, v137, v184
	v_cvt_pk_f16_f32 v159, v159, v183
	global_store_dwordx4 v[138:139], v[156:159], off offset:256 sc1
	v_add_f32_e32 v137, v32, v128
	v_add_f32_e32 v139, v33, v129
	v_mul_f32_e32 v137, 0xbfb8aa3b, v137
	v_exp_f32_e32 v137, v137
	v_mul_f32_e32 v139, 0xbfb8aa3b, v139
	v_exp_f32_e32 v139, v139
	v_add_f32_e32 v157, v34, v130
	v_add_f32_e32 v137, 1.0, v137
	v_add_f32_e32 v136, v36, v132
	v_add_f32_e32 v138, v37, v133
	v_add_f32_e32 v156, v38, v134
	v_add_f32_e32 v158, v39, v135
	v_add_f32_e32 v159, v35, v131
	v_rcp_f32_e32 v182, v137
	v_add_f32_e32 v137, 1.0, v139
	v_mul_f32_e32 v139, 0xbfb8aa3b, v157
	v_mul_f32_e32 v136, 0xbfb8aa3b, v136
	v_mul_f32_e32 v138, 0xbfb8aa3b, v138
	v_mul_f32_e32 v156, 0xbfb8aa3b, v156
	v_mul_f32_e32 v158, 0xbfb8aa3b, v158
	v_exp_f32_e32 v139, v139
	v_mul_f32_e32 v157, 0xbfb8aa3b, v159
	v_exp_f32_e32 v136, v136
	v_exp_f32_e32 v138, v138
	v_exp_f32_e32 v156, v156
	v_exp_f32_e32 v158, v158
	v_exp_f32_e32 v157, v157
	v_rcp_f32_e32 v159, v137
	v_add_f32_e32 v137, 1.0, v139
	v_add_f32_e32 v136, 1.0, v136
	v_add_f32_e32 v138, 1.0, v138
	v_add_f32_e32 v156, 1.0, v156
	v_add_f32_e32 v158, 1.0, v158
	v_rcp_f32_e32 v139, v137
	v_add_f32_e32 v137, 1.0, v157
	v_rcp_f32_e32 v136, v136
	v_rcp_f32_e32 v138, v138
	v_rcp_f32_e32 v156, v156
	v_rcp_f32_e32 v158, v158
	v_rcp_f32_e32 v157, v137
	v_cvt_pk_f16_f32 v136, v136, v138
	v_cvt_pk_f16_f32 v137, v156, v158
	v_cvt_pk_f16_f32 v138, v182, v159
	v_cvt_pk_f16_f32 v139, v139, v157
	global_store_dwordx4 v[160:161], v[136:139], off offset:256 sc1
	s_nop 1
	v_add_f32_e32 v137, v24, v128
	v_add_f32_e32 v139, v25, v129
	v_mul_f32_e32 v137, 0xbfb8aa3b, v137
	v_exp_f32_e32 v137, v137
	v_mul_f32_e32 v139, 0xbfb8aa3b, v139
	v_exp_f32_e32 v139, v139
	v_add_f32_e32 v157, v26, v130
	v_add_f32_e32 v137, 1.0, v137
	v_add_f32_e32 v136, v28, v132
	v_add_f32_e32 v138, v29, v133
	v_add_f32_e32 v156, v30, v134
	v_add_f32_e32 v158, v31, v135
	v_add_f32_e32 v159, v27, v131
	v_rcp_f32_e32 v160, v137
	v_add_f32_e32 v137, 1.0, v139
	v_mul_f32_e32 v139, 0xbfb8aa3b, v157
	v_mul_f32_e32 v136, 0xbfb8aa3b, v136
	v_mul_f32_e32 v138, 0xbfb8aa3b, v138
	v_mul_f32_e32 v156, 0xbfb8aa3b, v156
	v_mul_f32_e32 v158, 0xbfb8aa3b, v158
	v_exp_f32_e32 v139, v139
	v_mul_f32_e32 v157, 0xbfb8aa3b, v159
	v_exp_f32_e32 v136, v136
	v_exp_f32_e32 v138, v138
	v_exp_f32_e32 v156, v156
	v_exp_f32_e32 v158, v158
	v_exp_f32_e32 v157, v157
	v_rcp_f32_e32 v159, v137
	v_add_f32_e32 v137, 1.0, v139
	v_add_f32_e32 v136, 1.0, v136
	v_add_f32_e32 v138, 1.0, v138
	v_add_f32_e32 v156, 1.0, v156
	v_add_f32_e32 v158, 1.0, v158
	v_rcp_f32_e32 v139, v137
	v_add_f32_e32 v137, 1.0, v157
	v_rcp_f32_e32 v136, v136
	v_rcp_f32_e32 v138, v138
	v_rcp_f32_e32 v156, v156
	v_rcp_f32_e32 v158, v158
	v_rcp_f32_e32 v157, v137
	v_cvt_pk_f16_f32 v136, v136, v138
	v_cvt_pk_f16_f32 v137, v156, v158
	v_cvt_pk_f16_f32 v138, v160, v159
	v_cvt_pk_f16_f32 v139, v139, v157
	global_store_dwordx4 v[162:163], v[136:139], off offset:256 sc1
	s_nop 1
	v_add_f32_e32 v137, v16, v128
	v_add_f32_e32 v139, v17, v129
	v_mul_f32_e32 v137, 0xbfb8aa3b, v137
	v_exp_f32_e32 v137, v137
	v_mul_f32_e32 v139, 0xbfb8aa3b, v139
	v_exp_f32_e32 v139, v139
	v_add_f32_e32 v157, v18, v130
	v_add_f32_e32 v137, 1.0, v137
	v_add_f32_e32 v136, v20, v132
	v_add_f32_e32 v138, v21, v133
	v_add_f32_e32 v156, v22, v134
	v_add_f32_e32 v158, v23, v135
	v_add_f32_e32 v159, v19, v131
	v_rcp_f32_e32 v160, v137
	v_add_f32_e32 v137, 1.0, v139
	v_mul_f32_e32 v139, 0xbfb8aa3b, v157
	v_mul_f32_e32 v136, 0xbfb8aa3b, v136
	v_mul_f32_e32 v138, 0xbfb8aa3b, v138
	v_mul_f32_e32 v156, 0xbfb8aa3b, v156
; __device__ __forceinline__ float fsigmoid(float x) { return __builtin_amdgcn_rcpf(1.f + __builtin_amdgcn_exp2f(-1.4426950408889634f * x)); }
;     template <int MODE> __device__ __forceinline__ void run(AccRef acc, const Unit& u, int wr, int wc, int fr, int fq) const {
;     ...
;                     for (int e = 0; e < 4; ++e) { x[e] = acc[ai][bj][m][0][e] + bias[e]; x[4 + e] = acc[ai][bj][m][1][e] + bias[4 + e]; }
;                     u32x4 w;
;                     if (MODE == 0) {
; #pragma unroll
;                         for (int e = 0; e < 8; ++e) { const float sp = __logf(1.f + __expf(-x[e])); x[e] = __expf(-__expf(-sp - 0.5f)); }
;                         w.x = pkh(x[0], x[1]); w.y = pkh(x[2], x[3]); w.z = pkh(x[4], x[5]); w.w = pkh(x[6], x[7]);
;                         *(u32x4*)(WA + (size_t)row * 2048 + seg * 512 + cc) = w;
;                     } else if (MODE == 1) {
; #pragma unroll
;                         for (int e = 0; e < 8; ++e) x[e] = fsigmoid(x[e]);
;                         w.x = pkh(x[0], x[1]); w.y = pkh(x[2], x[3]); w.z = pkh(x[4], x[5]); w.w = pkh(x[6], x[7]);
;                         *(u32x4*)(WA + (size_t)row * 2048 + seg * 512 + cc) = w;
	v_mul_f32_e32 v158, 0xbfb8aa3b, v158
	v_exp_f32_e32 v139, v139
	v_mul_f32_e32 v157, 0xbfb8aa3b, v159
	v_exp_f32_e32 v136, v136
	v_exp_f32_e32 v138, v138
	v_exp_f32_e32 v156, v156
	v_exp_f32_e32 v158, v158
	v_exp_f32_e32 v157, v157
	v_rcp_f32_e32 v159, v137
	v_add_f32_e32 v137, 1.0, v139
	v_add_f32_e32 v136, 1.0, v136
	v_add_f32_e32 v138, 1.0, v138
	v_add_f32_e32 v156, 1.0, v156
	v_add_f32_e32 v158, 1.0, v158
	v_rcp_f32_e32 v139, v137
	v_add_f32_e32 v137, 1.0, v157
	v_rcp_f32_e32 v136, v136
	v_rcp_f32_e32 v138, v138
	v_rcp_f32_e32 v156, v156
	v_rcp_f32_e32 v158, v158
	v_rcp_f32_e32 v157, v137
	v_cvt_pk_f16_f32 v136, v136, v138
	v_cvt_pk_f16_f32 v137, v156, v158
	v_cvt_pk_f16_f32 v138, v160, v159
	v_cvt_pk_f16_f32 v139, v139, v157
	global_store_dwordx4 v[168:169], v[136:139], off offset:256 sc1
	s_nop 1
	v_add_f32_e32 v137, v8, v128
	v_add_f32_e32 v139, v9, v129
	v_mul_f32_e32 v137, 0xbfb8aa3b, v137
	v_exp_f32_e32 v137, v137
	v_mul_f32_e32 v139, 0xbfb8aa3b, v139
	v_exp_f32_e32 v139, v139
	v_add_f32_e32 v157, v10, v130
	v_add_f32_e32 v137, 1.0, v137
	v_add_f32_e32 v136, v12, v132
	v_add_f32_e32 v138, v13, v133
	v_add_f32_e32 v156, v14, v134
	v_add_f32_e32 v158, v15, v135
	v_add_f32_e32 v159, v11, v131
	v_rcp_f32_e32 v160, v137
	v_add_f32_e32 v137, 1.0, v139
	v_mul_f32_e32 v139, 0xbfb8aa3b, v157
	v_mul_f32_e32 v136, 0xbfb8aa3b, v136
	v_mul_f32_e32 v138, 0xbfb8aa3b, v138
	v_mul_f32_e32 v156, 0xbfb8aa3b, v156
	v_mul_f32_e32 v158, 0xbfb8aa3b, v158
	v_exp_f32_e32 v139, v139
	v_mul_f32_e32 v157, 0xbfb8aa3b, v159
	v_exp_f32_e32 v136, v136
	v_exp_f32_e32 v138, v138
	v_exp_f32_e32 v156, v156
	v_exp_f32_e32 v158, v158
	v_exp_f32_e32 v157, v157
	v_rcp_f32_e32 v159, v137
	v_add_f32_e32 v137, 1.0, v139
	v_add_f32_e32 v136, 1.0, v136
	v_add_f32_e32 v138, 1.0, v138
	v_add_f32_e32 v156, 1.0, v156
	v_add_f32_e32 v158, 1.0, v158
	v_rcp_f32_e32 v139, v137
	v_add_f32_e32 v137, 1.0, v157
	v_rcp_f32_e32 v136, v136
	v_rcp_f32_e32 v138, v138
	v_rcp_f32_e32 v156, v156
	v_rcp_f32_e32 v158, v158
	v_rcp_f32_e32 v157, v137
	v_cvt_pk_f16_f32 v136, v136, v138
	v_cvt_pk_f16_f32 v137, v156, v158
	v_cvt_pk_f16_f32 v138, v160, v159
	v_cvt_pk_f16_f32 v139, v139, v157
	global_store_dwordx4 v[170:171], v[136:139], off offset:256 sc1
	v_add_f32_e32 v128, v0, v128
	v_add_f32_e32 v129, v1, v129
	v_mul_f32_e32 v128, 0xbfb8aa3b, v128
	v_exp_f32_e32 v128, v128
	v_mul_f32_e32 v129, 0xbfb8aa3b, v129
	v_exp_f32_e32 v129, v129
	v_add_f32_e32 v130, v2, v130
	v_add_f32_e32 v128, 1.0, v128
	v_add_f32_e32 v132, v4, v132
	v_add_f32_e32 v133, v5, v133
	v_add_f32_e32 v134, v6, v134
	v_add_f32_e32 v135, v7, v135
	v_add_f32_e32 v131, v3, v131
	v_rcp_f32_e32 v136, v128
	v_add_f32_e32 v128, 1.0, v129
	v_mul_f32_e32 v129, 0xbfb8aa3b, v130
	v_mul_f32_e32 v132, 0xbfb8aa3b, v132
	v_mul_f32_e32 v133, 0xbfb8aa3b, v133
	v_mul_f32_e32 v134, 0xbfb8aa3b, v134
	v_mul_f32_e32 v135, 0xbfb8aa3b, v135
	v_exp_f32_e32 v129, v129
	v_mul_f32_e32 v130, 0xbfb8aa3b, v131
	v_exp_f32_e32 v132, v132
	v_exp_f32_e32 v133, v133
	v_exp_f32_e32 v134, v134
	v_exp_f32_e32 v135, v135
	v_exp_f32_e32 v130, v130
	v_rcp_f32_e32 v131, v128
	v_add_f32_e32 v128, 1.0, v129
	v_add_f32_e32 v132, 1.0, v132
	v_add_f32_e32 v133, 1.0, v133
	v_add_f32_e32 v134, 1.0, v134
	v_add_f32_e32 v135, 1.0, v135
	v_rcp_f32_e32 v137, v128
	v_add_f32_e32 v128, 1.0, v130
	v_rcp_f32_e32 v132, v132
	v_rcp_f32_e32 v133, v133
	v_rcp_f32_e32 v134, v134
	v_rcp_f32_e32 v135, v135
	v_rcp_f32_e32 v138, v128
	v_cvt_pk_f16_f32 v128, v132, v133
	v_cvt_pk_f16_f32 v129, v134, v135
	v_cvt_pk_f16_f32 v130, v136, v131
	v_cvt_pk_f16_f32 v131, v137, v138
	global_store_dwordx4 v[172:173], v[128:131], off offset:256 sc1

;     template <int MODE> __device__ __forceinline__ void run(AccRef acc, const Unit& u, int wr, int wc, int fr, int fq) const {
;         const int row0 = u.pm * 256 + wr * 64 + fr, seg = seg0 + (u.pn >> 1);
; #pragma unroll
;         for (int bj = 0; bj < 2; ++bj) {
;             const int cc = (u.pn & 1) * 256 + bj * 128 + wc * 32 + 8 * fq;
;             float bias[8];
;             if (MODE < 2) { const float* bp = (MODE == 0 ? w0 + seg * 512 : a0 + (seg - 2) * 512) + cc; const f32x4 b0 = *(const f32x4*)bp, b1 = *(const f32x4*)(bp + 4);
;                 bias[0] = b0[0]; bias[1] = b0[1]; bias[2] = b0[2]; bias[3] = b0[3]; bias[4] = b1[0]; bias[5] = b1[1]; bias[6] = b1[2]; bias[7] = b1[3]; }
;             else {
; #pragma unroll
;                 for (int e = 0; e < 8; ++e) bias[e] = 0.f; }
; #pragma unroll
;             for (int ai = 0; ai < 2; ++ai)
; #pragma unroll
;                 for (int m = 0; m < 4; ++m) {
;                     const int row = row0 + ai * 128 + m * 16;
;                     float x[8];
; #pragma unroll
;                     for (int e = 0; e < 4; ++e) { x[e] = acc[ai][bj][m][0][e] + bias[e]; x[4 + e] = acc[ai][bj][m][1][e] + bias[4 + e]; }
;                     u32x4 w;
;                     if (MODE == 0) {
; #pragma unroll
;                         for (int e = 0; e < 8; ++e) { const float sp = __logf(1.f + __expf(-x[e])); x[e] = __expf(-__expf(-sp - 0.5f)); }
;                         w.x = pkh(x[0], x[1]); w.y = pkh(x[2], x[3]); w.z = pkh(x[4], x[5]); w.w = pkh(x[6], x[7]);
;                         *(u32x4*)(WA + (size_t)row * 2048 + seg * 512 + cc) = w;
.LBB0_824:
	s_lshl_b32 s0, s91, 8
	s_add_i32 s0, s0, s87
	v_add_u32_e32 v138, s0, v181
	s_lshl_b32 s0, s69, 8
	s_lshl_b32 s74, s18, 9
	s_and_b32 s0, s0, 0x100
	s_ashr_i32 s75, s74, 31
	s_or_b32 s0, s0, s35
	v_readlane_b32 s16, v237, 21
	v_lshl_add_u32 v156, v180, 3, s0
	s_lshl_b64 s[0:1], s[74:75], 2
	v_readlane_b32 s28, v237, 33
	v_readlane_b32 s29, v237, 34
	s_add_u32 s0, s28, s0
	s_addc_u32 s1, s29, s1
	v_ashrrev_i32_e32 v157, 31, v156
	v_lshl_add_u64 v[136:137], v[156:157], 2, s[0:1]
	global_load_dwordx4 v[128:131], v[136:137], off offset:16
	global_load_dwordx4 v[132:135], v[136:137], off
	v_readlane_b32 s22, v237, 27
	v_readlane_b32 s23, v237, 28
	v_readlane_b32 s22, v236, 21
	v_readlane_b32 s23, v236, 22
	v_readlane_b32 s17, v237, 22
	v_readlane_b32 s18, v237, 23
	v_readlane_b32 s19, v237, 24
	v_readlane_b32 s20, v237, 25
	v_readlane_b32 s21, v237, 26
	v_readlane_b32 s24, v237, 29
	v_readlane_b32 s25, v237, 30
	v_readlane_b32 s26, v237, 31
	v_readlane_b32 s27, v237, 32
	v_readlane_b32 s30, v237, 35
	v_readlane_b32 s31, v237, 36
	s_waitcnt vmcnt(0)
	v_add_f32_e32 v139, v124, v128
	v_add_f32_e32 v120, v120, v132
	v_mul_f32_e32 v120, 0xbfb8aa3b, v120
	v_exp_f32_e32 v120, v120
	v_add_f32_e32 v159, v122, v134
	v_add_f32_e32 v158, v121, v133
	v_add_f32_e32 v124, v126, v130
	v_add_f32_e32 v120, 1.0, v120
	v_cmp_gt_f32_e32 vcc, s64, v120
	v_add_f32_e32 v126, v123, v135
	v_add_f32_e32 v121, v127, v131
	v_cndmask_b32_e64 v122, 0, 32, vcc
	v_ldexp_f32 v120, v120, v122
	v_log_f32_e32 v120, v120
	v_mul_f32_e32 v126, 0xbfb8aa3b, v126
	v_exp_f32_e32 v126, v126
	v_add_f32_e32 v125, v125, v129
	v_mul_f32_e32 v122, 0x3f317217, v120
	v_fma_f32 v122, v120, s65, -v122
	v_fmac_f32_e32 v122, 0x3377d1cf, v120
	v_fmac_f32_e32 v122, 0x3f317217, v120
	v_cmp_lt_f32_e64 s[0:1], |v120|, s66
	v_add_f32_e32 v126, 1.0, v126
	v_mul_f32_e32 v125, 0xbfb8aa3b, v125
	v_cndmask_b32_e64 v120, v120, v122, s[0:1]
	v_cndmask_b32_e32 v122, 0, v179, vcc
	v_sub_f32_e32 v120, v120, v122
	v_mul_f32_e32 v122, 0xbfb8aa3b, v158
	v_exp_f32_e32 v122, v122
	v_exp_f32_e32 v125, v125
	v_mul_f32_e32 v124, 0xbfb8aa3b, v124
	v_exp_f32_e32 v124, v124
	v_add_f32_e32 v122, 1.0, v122
	v_cmp_gt_f32_e32 vcc, s64, v122
	v_add_f32_e32 v125, 1.0, v125
	v_add_f32_e32 v124, 1.0, v124
	v_cndmask_b32_e64 v123, 0, 32, vcc
	v_ldexp_f32 v122, v122, v123
	v_log_f32_e32 v122, v122
	v_mul_f32_e32 v121, 0xbfb8aa3b, v121
	v_exp_f32_e32 v121, v121
	v_sub_f32_e32 v120, -0.5, v120
	v_mul_f32_e32 v123, 0x3f317217, v122
	v_fma_f32 v123, v122, s65, -v123
	v_fmac_f32_e32 v123, 0x3377d1cf, v122
	v_fmac_f32_e32 v123, 0x3f317217, v122
	v_cmp_lt_f32_e64 s[0:1], |v122|, s66
	v_add_f32_e32 v121, 1.0, v121
	v_mul_f32_e32 v120, 0x3fb8aa3b, v120
	v_cndmask_b32_e64 v122, v122, v123, s[0:1]
	v_cndmask_b32_e32 v123, 0, v179, vcc
	v_sub_f32_e32 v122, v122, v123
	v_mul_f32_e32 v123, 0xbfb8aa3b, v159
	v_exp_f32_e32 v123, v123
	v_sub_f32_e32 v122, -0.5, v122
	v_mul_f32_e32 v122, 0x3fb8aa3b, v122
	v_exp_f32_e32 v120, v120
	v_add_f32_e32 v123, 1.0, v123
	v_cmp_gt_f32_e32 vcc, s64, v123
	v_exp_f32_e32 v122, v122
	v_mul_f32_e32 v120, 0xbfb8aa3b, v120
	v_cndmask_b32_e64 v127, 0, 32, vcc
	v_ldexp_f32 v123, v123, v127
	v_log_f32_e32 v123, v123
	v_mul_f32_e32 v122, 0xbfb8aa3b, v122
	v_exp_f32_e32 v120, v120
	v_exp_f32_e32 v122, v122
	v_mul_f32_e32 v127, 0x3f317217, v123
	v_fma_f32 v127, v123, s65, -v127
	v_fmac_f32_e32 v127, 0x3377d1cf, v123
	v_fmac_f32_e32 v127, 0x3f317217, v123
	v_cmp_lt_f32_e64 s[0:1], |v123|, s66
	v_cvt_pk_f16_f32 v122, v120, v122
	s_nop 0
	v_cndmask_b32_e64 v123, v123, v127, s[0:1]
	v_cndmask_b32_e32 v127, 0, v179, vcc
	v_cmp_gt_f32_e32 vcc, s64, v126
	v_sub_f32_e32 v123, v123, v127
	v_sub_f32_e32 v123, -0.5, v123
	v_cndmask_b32_e64 v127, 0, 32, vcc
	v_ldexp_f32 v126, v126, v127
	v_log_f32_e32 v126, v126
	v_mul_f32_e32 v123, 0x3fb8aa3b, v123
	v_exp_f32_e32 v123, v123
	v_mul_f32_e32 v127, 0x3f317217, v126
	v_fma_f32 v127, v126, s65, -v127
	v_fmac_f32_e32 v127, 0x3377d1cf, v126
	v_fmac_f32_e32 v127, 0x3f317217, v126
	v_cmp_lt_f32_e64 s[0:1], |v126|, s66
	v_mul_f32_e32 v123, 0xbfb8aa3b, v123
	v_exp_f32_e32 v123, v123
	v_cndmask_b32_e64 v126, v126, v127, s[0:1]
	v_cndmask_b32_e32 v127, 0, v179, vcc
	v_sub_f32_e32 v126, v126, v127
	v_mul_f32_e32 v127, 0xbfb8aa3b, v139
	v_exp_f32_e32 v127, v127
	v_sub_f32_e32 v126, -0.5, v126
	v_mul_f32_e32 v126, 0x3fb8aa3b, v126
	v_exp_f32_e32 v126, v126
	v_add_f32_e32 v127, 1.0, v127
	v_cmp_gt_f32_e32 vcc, s64, v127
	v_mul_f32_e32 v126, 0xbfb8aa3b, v126
	s_nop 0
	v_cndmask_b32_e64 v139, 0, 32, vcc
	v_ldexp_f32 v127, v127, v139
	v_log_f32_e32 v127, v127
	v_exp_f32_e32 v126, v126
	v_mul_f32_e32 v139, 0x3f317217, v127
	v_fma_f32 v139, v127, s65, -v139
	v_fmac_f32_e32 v139, 0x3377d1cf, v127
	v_fmac_f32_e32 v139, 0x3f317217, v127
	v_cmp_lt_f32_e64 s[0:1], |v127|, s66
	v_cvt_pk_f16_f32 v123, v123, v126
	s_nop 0
	v_cndmask_b32_e64 v127, v127, v139, s[0:1]
	v_cndmask_b32_e32 v139, 0, v179, vcc
	v_cmp_gt_f32_e32 vcc, s64, v125
	v_sub_f32_e32 v127, v127, v139
	v_sub_f32_e32 v127, -0.5, v127
	v_cndmask_b32_e64 v139, 0, 32, vcc
	v_ldexp_f32 v125, v125, v139
	v_log_f32_e32 v125, v125
	v_mul_f32_e32 v127, 0x3fb8aa3b, v127
	v_exp_f32_e32 v127, v127
	v_mul_f32_e32 v139, 0x3f317217, v125
	v_fma_f32 v139, v125, s65, -v139
	v_fmac_f32_e32 v139, 0x3377d1cf, v125
	v_fmac_f32_e32 v139, 0x3f317217, v125
	v_cmp_lt_f32_e64 s[0:1], |v125|, s66
	v_mul_f32_e32 v127, 0xbfb8aa3b, v127
	v_exp_f32_e32 v127, v127
	v_cndmask_b32_e64 v125, v125, v139, s[0:1]
	v_cndmask_b32_e32 v139, 0, v179, vcc
	v_cmp_gt_f32_e32 vcc, s64, v124
	v_sub_f32_e32 v125, v125, v139
	v_sub_f32_e32 v125, -0.5, v125
	v_cndmask_b32_e64 v139, 0, 32, vcc
;     template <int MODE> __device__ __forceinline__ void run(AccRef acc, const Unit& u, int wr, int wc, int fr, int fq) const {
;     ...
;                     for (int e = 0; e < 4; ++e) { x[e] = acc[ai][bj][m][0][e] + bias[e]; x[4 + e] = acc[ai][bj][m][1][e] + bias[4 + e]; }
;                     u32x4 w;
;                     if (MODE == 0) {
; #pragma unroll
;                         for (int e = 0; e < 8; ++e) { const float sp = __logf(1.f + __expf(-x[e])); x[e] = __expf(-__expf(-sp - 0.5f)); }
;                         w.x = pkh(x[0], x[1]); w.y = pkh(x[2], x[3]); w.z = pkh(x[4], x[5]); w.w = pkh(x[6], x[7]);
;                         *(u32x4*)(WA + (size_t)row * 2048 + seg * 512 + cc) = w;
	v_ldexp_f32 v124, v124, v139
	v_log_f32_e32 v124, v124
	v_mul_f32_e32 v125, 0x3fb8aa3b, v125
	v_exp_f32_e32 v125, v125
	v_mul_f32_e32 v139, 0x3f317217, v124
	v_fma_f32 v139, v124, s65, -v139
	v_fmac_f32_e32 v139, 0x3377d1cf, v124
	v_fmac_f32_e32 v139, 0x3f317217, v124
	v_cmp_lt_f32_e64 s[0:1], |v124|, s66
	v_mul_f32_e32 v125, 0xbfb8aa3b, v125
	v_exp_f32_e32 v125, v125
	v_cndmask_b32_e64 v124, v124, v139, s[0:1]
	v_cndmask_b32_e32 v139, 0, v179, vcc
	v_sub_f32_e32 v124, v124, v139
	v_sub_f32_e32 v124, -0.5, v124
	v_mul_f32_e32 v124, 0x3fb8aa3b, v124
	v_exp_f32_e32 v124, v124
	v_cmp_gt_f32_e32 vcc, s64, v121
	v_mul_f32_e32 v124, 0xbfb8aa3b, v124
	v_exp_f32_e32 v139, v124
	v_cndmask_b32_e64 v124, 0, 32, vcc
	v_ldexp_f32 v121, v121, v124
	v_log_f32_e32 v121, v121
	s_nop 0
	v_mul_f32_e32 v124, 0x3f317217, v121
	v_fma_f32 v124, v121, s65, -v124
	v_fmac_f32_e32 v124, 0x3377d1cf, v121
	v_fmac_f32_e32 v124, 0x3f317217, v121
	v_cmp_lt_f32_e64 s[0:1], |v121|, s66
	s_nop 1
	v_cndmask_b32_e64 v121, v121, v124, s[0:1]
	v_cndmask_b32_e32 v124, 0, v179, vcc
	v_sub_f32_e32 v121, v121, v124
	v_sub_f32_e32 v121, -0.5, v121
	v_mul_f32_e32 v121, 0x3fb8aa3b, v121
	v_exp_f32_e32 v121, v121
	v_cvt_pk_f16_f32 v124, v127, v125
	v_mul_f32_e32 v121, 0xbfb8aa3b, v121
	v_exp_f32_e32 v121, v121
	s_nop 0
	v_cvt_pk_f16_f32 v125, v139, v121
	v_ashrrev_i32_e32 v139, 31, v138
	v_lshlrev_b64 v[120:121], 12, v[138:139]
	v_lshl_add_u64 v[120:121], s[48:49], 0, v[120:121]
	v_lshl_add_u64 v[120:121], s[74:75], 1, v[120:121]
	v_lshl_add_u64 v[120:121], v[156:157], 1, v[120:121]
	global_store_dwordx4 v[120:121], v[122:125], off sc1
	v_add_f32_e32 v116, v116, v132
	v_mul_f32_e32 v116, 0xbfb8aa3b, v116
	v_exp_f32_e32 v116, v116
	v_add_f32_e32 v117, v117, v133
	v_mul_f32_e32 v117, 0xbfb8aa3b, v117
	v_exp_f32_e32 v117, v117
	v_add_f32_e32 v116, 1.0, v116
	v_cmp_gt_f32_e32 vcc, s64, v116
	v_add_f32_e32 v118, v118, v134
	v_add_f32_e32 v117, 1.0, v117
	v_cndmask_b32_e64 v122, 0, 32, vcc
	v_ldexp_f32 v116, v116, v122
	v_log_f32_e32 v116, v116
	v_mul_f32_e32 v118, 0xbfb8aa3b, v118
	v_exp_f32_e32 v118, v118
	v_add_f32_e32 v119, v119, v135
	v_mul_f32_e32 v122, 0x3f317217, v116
	v_fma_f32 v122, v116, s65, -v122
	v_fmac_f32_e32 v122, 0x3377d1cf, v116
	v_fmac_f32_e32 v122, 0x3f317217, v116
	v_cmp_lt_f32_e64 s[0:1], |v116|, s66
	v_add_f32_e32 v118, 1.0, v118
	v_mul_f32_e32 v119, 0xbfb8aa3b, v119
	v_cndmask_b32_e64 v116, v116, v122, s[0:1]
	v_cndmask_b32_e32 v122, 0, v179, vcc
	v_cmp_gt_f32_e32 vcc, s64, v117
	v_sub_f32_e32 v116, v116, v122
	v_exp_f32_e32 v119, v119
	v_cndmask_b32_e64 v122, 0, 32, vcc
	v_ldexp_f32 v117, v117, v122
	v_log_f32_e32 v117, v117
	v_add_f32_e32 v119, 1.0, v119
	v_add_f32_e32 v112, v112, v128
	v_mul_f32_e32 v112, 0xbfb8aa3b, v112
	v_mul_f32_e32 v122, 0x3f317217, v117
	v_fma_f32 v122, v117, s65, -v122
	v_fmac_f32_e32 v122, 0x3377d1cf, v117
	v_fmac_f32_e32 v122, 0x3f317217, v117
	v_cmp_lt_f32_e64 s[0:1], |v117|, s66
	v_exp_f32_e32 v112, v112
	v_add_f32_e32 v113, v113, v129
	v_cndmask_b32_e64 v117, v117, v122, s[0:1]
	v_cndmask_b32_e32 v122, 0, v179, vcc
	v_cmp_gt_f32_e32 vcc, s64, v118
	v_sub_f32_e32 v117, v117, v122
	v_add_f32_e32 v112, 1.0, v112
	v_cndmask_b32_e64 v122, 0, 32, vcc
	v_ldexp_f32 v118, v118, v122
	v_log_f32_e32 v118, v118
	v_mul_f32_e32 v113, 0xbfb8aa3b, v113
	v_exp_f32_e32 v113, v113
	v_add_f32_e32 v114, v114, v130
	v_mul_f32_e32 v122, 0x3f317217, v118
	v_fma_f32 v122, v118, s65, -v122
	v_fmac_f32_e32 v122, 0x3377d1cf, v118
	v_fmac_f32_e32 v122, 0x3f317217, v118
	v_cmp_lt_f32_e64 s[0:1], |v118|, s66
	v_add_f32_e32 v113, 1.0, v113
	v_mul_f32_e32 v114, 0xbfb8aa3b, v114
	v_cndmask_b32_e64 v118, v118, v122, s[0:1]
	v_cndmask_b32_e32 v122, 0, v179, vcc
	v_cmp_gt_f32_e32 vcc, s64, v119
	v_sub_f32_e32 v118, v118, v122
	v_exp_f32_e32 v114, v114
	v_cndmask_b32_e64 v122, 0, 32, vcc
	v_ldexp_f32 v119, v119, v122
	v_log_f32_e32 v119, v119
	v_add_f32_e32 v114, 1.0, v114
	v_add_f32_e32 v115, v115, v131
	v_mul_f32_e32 v115, 0xbfb8aa3b, v115
	v_mul_f32_e32 v122, 0x3f317217, v119
	v_fma_f32 v122, v119, s65, -v122
	v_fmac_f32_e32 v122, 0x3377d1cf, v119
	v_fmac_f32_e32 v122, 0x3f317217, v119
	v_cmp_lt_f32_e64 s[0:1], |v119|, s66
	v_exp_f32_e32 v115, v115
	v_sub_f32_e32 v118, -0.5, v118
	v_cndmask_b32_e64 v119, v119, v122, s[0:1]
	v_cndmask_b32_e32 v122, 0, v179, vcc
	v_cmp_gt_f32_e32 vcc, s64, v112
	v_sub_f32_e32 v119, v119, v122
	v_add_f32_e32 v115, 1.0, v115
	v_cndmask_b32_e64 v122, 0, 32, vcc
	v_ldexp_f32 v112, v112, v122
	v_log_f32_e32 v112, v112
	v_sub_f32_e32 v119, -0.5, v119
	v_sub_f32_e32 v116, -0.5, v116
	v_sub_f32_e32 v117, -0.5, v117
	v_mul_f32_e32 v122, 0x3f317217, v112
	v_fma_f32 v122, v112, s65, -v122
	v_fmac_f32_e32 v122, 0x3377d1cf, v112
	v_fmac_f32_e32 v122, 0x3f317217, v112
	v_cmp_lt_f32_e64 s[0:1], |v112|, s66
	v_mul_f32_e32 v118, 0x3fb8aa3b, v118
	v_mul_f32_e32 v119, 0x3fb8aa3b, v119
	v_cndmask_b32_e64 v112, v112, v122, s[0:1]
	v_cndmask_b32_e32 v122, 0, v179, vcc
	v_cmp_gt_f32_e32 vcc, s64, v113
	v_sub_f32_e32 v112, v112, v122
	v_sub_f32_e32 v112, -0.5, v112
	v_cndmask_b32_e64 v122, 0, 32, vcc
	v_ldexp_f32 v113, v113, v122
	v_log_f32_e32 v113, v113
	v_mul_f32_e32 v116, 0x3fb8aa3b, v116
	v_mul_f32_e32 v117, 0x3fb8aa3b, v117
	v_exp_f32_e32 v118, v118
	v_mul_f32_e32 v122, 0x3f317217, v113
	v_fma_f32 v122, v113, s65, -v122
	v_fmac_f32_e32 v122, 0x3377d1cf, v113
	v_fmac_f32_e32 v122, 0x3f317217, v113
	v_cmp_lt_f32_e64 s[0:1], |v113|, s66
	v_exp_f32_e32 v119, v119
	v_mul_f32_e32 v112, 0x3fb8aa3b, v112
	v_cndmask_b32_e64 v113, v113, v122, s[0:1]
	v_cndmask_b32_e32 v122, 0, v179, vcc
	v_cmp_gt_f32_e32 vcc, s64, v114
	v_sub_f32_e32 v113, v113, v122
;     template <int MODE> __device__ __forceinline__ void run(AccRef acc, const Unit& u, int wr, int wc, int fr, int fq) const {
;     ...
;                     for (int e = 0; e < 4; ++e) { x[e] = acc[ai][bj][m][0][e] + bias[e]; x[4 + e] = acc[ai][bj][m][1][e] + bias[4 + e]; }
;                     u32x4 w;
;                     if (MODE == 0) {
; #pragma unroll
;                         for (int e = 0; e < 8; ++e) { const float sp = __logf(1.f + __expf(-x[e])); x[e] = __expf(-__expf(-sp - 0.5f)); }
;                         w.x = pkh(x[0], x[1]); w.y = pkh(x[2], x[3]); w.z = pkh(x[4], x[5]); w.w = pkh(x[6], x[7]);
;                         *(u32x4*)(WA + (size_t)row * 2048 + seg * 512 + cc) = w;
	v_sub_f32_e32 v113, -0.5, v113
	v_cndmask_b32_e64 v122, 0, 32, vcc
	v_ldexp_f32 v114, v114, v122
	v_log_f32_e32 v114, v114
	v_mul_f32_e32 v113, 0x3fb8aa3b, v113
	v_exp_f32_e32 v116, v116
	v_exp_f32_e32 v117, v117
	v_mul_f32_e32 v122, 0x3f317217, v114
	v_fma_f32 v122, v114, s65, -v122
	v_fmac_f32_e32 v122, 0x3377d1cf, v114
	v_fmac_f32_e32 v122, 0x3f317217, v114
	v_cmp_lt_f32_e64 s[0:1], |v114|, s66
	v_exp_f32_e32 v112, v112
	v_exp_f32_e32 v113, v113
	v_cndmask_b32_e64 v114, v114, v122, s[0:1]
	v_cndmask_b32_e32 v122, 0, v179, vcc
	v_cmp_gt_f32_e32 vcc, s64, v115
	v_sub_f32_e32 v114, v114, v122
	v_sub_f32_e32 v114, -0.5, v114
	v_cndmask_b32_e64 v122, 0, 32, vcc
	v_ldexp_f32 v115, v115, v122
	v_log_f32_e32 v115, v115
	v_mul_f32_e32 v114, 0x3fb8aa3b, v114
	v_exp_f32_e32 v114, v114
	v_mul_f32_e32 v118, 0xbfb8aa3b, v118
	v_mul_f32_e32 v122, 0x3f317217, v115
	v_fma_f32 v122, v115, s65, -v122
	v_fmac_f32_e32 v122, 0x3377d1cf, v115
	v_fmac_f32_e32 v122, 0x3f317217, v115
	v_cmp_lt_f32_e64 s[0:1], |v115|, s66
	v_mul_f32_e32 v119, 0xbfb8aa3b, v119
	v_mul_f32_e32 v114, 0xbfb8aa3b, v114
	v_cndmask_b32_e64 v115, v115, v122, s[0:1]
	v_cndmask_b32_e32 v122, 0, v179, vcc
	v_sub_f32_e32 v115, v115, v122
	v_sub_f32_e32 v115, -0.5, v115
	v_mul_f32_e32 v115, 0x3fb8aa3b, v115
	v_exp_f32_e32 v115, v115
	v_mul_f32_e32 v116, 0xbfb8aa3b, v116
	v_mul_f32_e32 v117, 0xbfb8aa3b, v117
	v_exp_f32_e32 v118, v118
	v_exp_f32_e32 v119, v119
	v_mul_f32_e32 v112, 0xbfb8aa3b, v112
	v_mul_f32_e32 v113, 0xbfb8aa3b, v113
	v_exp_f32_e32 v122, v114
	v_mul_f32_e32 v114, 0xbfb8aa3b, v115
	v_exp_f32_e32 v116, v116
	v_exp_f32_e32 v117, v117
	v_exp_f32_e32 v112, v112
	v_exp_f32_e32 v113, v113
	v_exp_f32_e32 v123, v114
	v_cvt_pk_f16_f32 v115, v118, v119
	v_add_co_u32_e32 v118, vcc, s46, v120
	v_cvt_pk_f16_f32 v114, v116, v117
	v_cvt_pk_f16_f32 v116, v112, v113
	v_cvt_pk_f16_f32 v117, v122, v123
	v_addc_co_u32_e32 v119, vcc, 0, v121, vcc
	v_lshl_add_u64 v[112:113], v[120:121], 0, s[60:61]
	global_store_dwordx4 v[118:119], v[114:117], off sc1
	v_add_f32_e32 v108, v108, v132
	v_mul_f32_e32 v108, 0xbfb8aa3b, v108
	v_exp_f32_e32 v108, v108
	v_add_f32_e32 v109, v109, v133
	v_mul_f32_e32 v109, 0xbfb8aa3b, v109
	v_exp_f32_e32 v109, v109
	v_add_f32_e32 v108, 1.0, v108
	v_cmp_gt_f32_e32 vcc, s64, v108
	v_add_f32_e32 v110, v110, v134
	v_add_f32_e32 v109, 1.0, v109
	v_cndmask_b32_e64 v114, 0, 32, vcc
	v_ldexp_f32 v108, v108, v114
	v_log_f32_e32 v108, v108
	v_mul_f32_e32 v110, 0xbfb8aa3b, v110
	v_exp_f32_e32 v110, v110
	v_add_f32_e32 v111, v111, v135
	v_mul_f32_e32 v114, 0x3f317217, v108
	v_fma_f32 v114, v108, s65, -v114
	v_fmac_f32_e32 v114, 0x3377d1cf, v108
	v_fmac_f32_e32 v114, 0x3f317217, v108
	v_cmp_lt_f32_e64 s[0:1], |v108|, s66
	v_add_f32_e32 v110, 1.0, v110
	v_mul_f32_e32 v111, 0xbfb8aa3b, v111
	v_cndmask_b32_e64 v108, v108, v114, s[0:1]
	v_cndmask_b32_e32 v114, 0, v179, vcc
	v_cmp_gt_f32_e32 vcc, s64, v109
	v_sub_f32_e32 v108, v108, v114
	v_exp_f32_e32 v111, v111
	v_cndmask_b32_e64 v114, 0, 32, vcc
	v_ldexp_f32 v109, v109, v114
	v_log_f32_e32 v109, v109
	v_add_f32_e32 v111, 1.0, v111
	v_add_f32_e32 v104, v104, v128
	v_mul_f32_e32 v104, 0xbfb8aa3b, v104
	v_mul_f32_e32 v114, 0x3f317217, v109
	v_fma_f32 v114, v109, s65, -v114
	v_fmac_f32_e32 v114, 0x3377d1cf, v109
	v_fmac_f32_e32 v114, 0x3f317217, v109
	v_cmp_lt_f32_e64 s[0:1], |v109|, s66
	v_exp_f32_e32 v104, v104
	v_add_f32_e32 v105, v105, v129
	v_cndmask_b32_e64 v109, v109, v114, s[0:1]
	v_cndmask_b32_e32 v114, 0, v179, vcc
	v_cmp_gt_f32_e32 vcc, s64, v110
	v_sub_f32_e32 v109, v109, v114
	v_add_f32_e32 v104, 1.0, v104
	v_cndmask_b32_e64 v114, 0, 32, vcc
	v_ldexp_f32 v110, v110, v114
	v_log_f32_e32 v110, v110
	v_mul_f32_e32 v105, 0xbfb8aa3b, v105
	v_exp_f32_e32 v105, v105
	v_add_f32_e32 v106, v106, v130
	v_mul_f32_e32 v114, 0x3f317217, v110
	v_fma_f32 v114, v110, s65, -v114
	v_fmac_f32_e32 v114, 0x3377d1cf, v110
	v_fmac_f32_e32 v114, 0x3f317217, v110
	v_cmp_lt_f32_e64 s[0:1], |v110|, s66
	v_add_f32_e32 v105, 1.0, v105
	v_mul_f32_e32 v106, 0xbfb8aa3b, v106
	v_cndmask_b32_e64 v110, v110, v114, s[0:1]
	v_cndmask_b32_e32 v114, 0, v179, vcc
	v_cmp_gt_f32_e32 vcc, s64, v111
	v_sub_f32_e32 v110, v110, v114
	v_exp_f32_e32 v106, v106
	v_cndmask_b32_e64 v114, 0, 32, vcc
	v_ldexp_f32 v111, v111, v114
	v_log_f32_e32 v111, v111
	v_add_f32_e32 v106, 1.0, v106
	v_add_f32_e32 v107, v107, v131
	v_mul_f32_e32 v107, 0xbfb8aa3b, v107
	v_mul_f32_e32 v114, 0x3f317217, v111
	v_fma_f32 v114, v111, s65, -v114
	v_fmac_f32_e32 v114, 0x3377d1cf, v111
	v_fmac_f32_e32 v114, 0x3f317217, v111
	v_cmp_lt_f32_e64 s[0:1], |v111|, s66
	v_exp_f32_e32 v107, v107
	v_sub_f32_e32 v110, -0.5, v110
	v_cndmask_b32_e64 v111, v111, v114, s[0:1]
	v_cndmask_b32_e32 v114, 0, v179, vcc
	v_cmp_gt_f32_e32 vcc, s64, v104
	v_sub_f32_e32 v111, v111, v114
	v_add_f32_e32 v107, 1.0, v107
	v_cndmask_b32_e64 v114, 0, 32, vcc
	v_ldexp_f32 v104, v104, v114
	v_log_f32_e32 v104, v104
	v_sub_f32_e32 v111, -0.5, v111
	v_sub_f32_e32 v108, -0.5, v108
	v_sub_f32_e32 v109, -0.5, v109
	v_mul_f32_e32 v114, 0x3f317217, v104
	v_fma_f32 v114, v104, s65, -v114
	v_fmac_f32_e32 v114, 0x3377d1cf, v104
	v_fmac_f32_e32 v114, 0x3f317217, v104
	v_cmp_lt_f32_e64 s[0:1], |v104|, s66
	v_mul_f32_e32 v110, 0x3fb8aa3b, v110
	v_mul_f32_e32 v111, 0x3fb8aa3b, v111
	v_cndmask_b32_e64 v104, v104, v114, s[0:1]
	v_cndmask_b32_e32 v114, 0, v179, vcc
	v_cmp_gt_f32_e32 vcc, s64, v105
	v_sub_f32_e32 v104, v104, v114
	v_sub_f32_e32 v104, -0.5, v104
	v_cndmask_b32_e64 v114, 0, 32, vcc
	v_ldexp_f32 v105, v105, v114
	v_log_f32_e32 v105, v105
	v_mul_f32_e32 v108, 0x3fb8aa3b, v108
	v_mul_f32_e32 v109, 0x3fb8aa3b, v109
	v_exp_f32_e32 v110, v110
;     template <int MODE> __device__ __forceinline__ void run(AccRef acc, const Unit& u, int wr, int wc, int fr, int fq) const {
;     ...
;                     for (int e = 0; e < 4; ++e) { x[e] = acc[ai][bj][m][0][e] + bias[e]; x[4 + e] = acc[ai][bj][m][1][e] + bias[4 + e]; }
;                     u32x4 w;
;                     if (MODE == 0) {
; #pragma unroll
;                         for (int e = 0; e < 8; ++e) { const float sp = __logf(1.f + __expf(-x[e])); x[e] = __expf(-__expf(-sp - 0.5f)); }
;                         w.x = pkh(x[0], x[1]); w.y = pkh(x[2], x[3]); w.z = pkh(x[4], x[5]); w.w = pkh(x[6], x[7]);
;                         *(u32x4*)(WA + (size_t)row * 2048 + seg * 512 + cc) = w;
	v_mul_f32_e32 v114, 0x3f317217, v105
	v_fma_f32 v114, v105, s65, -v114
	v_fmac_f32_e32 v114, 0x3377d1cf, v105
	v_fmac_f32_e32 v114, 0x3f317217, v105
	v_cmp_lt_f32_e64 s[0:1], |v105|, s66
	v_exp_f32_e32 v111, v111
	v_mul_f32_e32 v104, 0x3fb8aa3b, v104
	v_cndmask_b32_e64 v105, v105, v114, s[0:1]
	v_cndmask_b32_e32 v114, 0, v179, vcc
	v_cmp_gt_f32_e32 vcc, s64, v106
	v_sub_f32_e32 v105, v105, v114
	v_sub_f32_e32 v105, -0.5, v105
	v_cndmask_b32_e64 v114, 0, 32, vcc
	v_ldexp_f32 v106, v106, v114
	v_log_f32_e32 v106, v106
	v_mul_f32_e32 v105, 0x3fb8aa3b, v105
	v_exp_f32_e32 v108, v108
	v_exp_f32_e32 v109, v109
	v_mul_f32_e32 v114, 0x3f317217, v106
	v_fma_f32 v114, v106, s65, -v114
	v_fmac_f32_e32 v114, 0x3377d1cf, v106
	v_fmac_f32_e32 v114, 0x3f317217, v106
	v_cmp_lt_f32_e64 s[0:1], |v106|, s66
	v_exp_f32_e32 v104, v104
	v_exp_f32_e32 v105, v105
	v_cndmask_b32_e64 v106, v106, v114, s[0:1]
	v_cndmask_b32_e32 v114, 0, v179, vcc
	v_cmp_gt_f32_e32 vcc, s64, v107
	v_sub_f32_e32 v106, v106, v114
	v_sub_f32_e32 v106, -0.5, v106
	v_cndmask_b32_e64 v114, 0, 32, vcc
	v_ldexp_f32 v107, v107, v114
	v_log_f32_e32 v107, v107
	v_mul_f32_e32 v106, 0x3fb8aa3b, v106
	v_exp_f32_e32 v106, v106
	v_mul_f32_e32 v110, 0xbfb8aa3b, v110
	v_mul_f32_e32 v114, 0x3f317217, v107
	v_fma_f32 v114, v107, s65, -v114
	v_fmac_f32_e32 v114, 0x3377d1cf, v107
	v_fmac_f32_e32 v114, 0x3f317217, v107
	v_cmp_lt_f32_e64 s[0:1], |v107|, s66
	v_mul_f32_e32 v111, 0xbfb8aa3b, v111
	v_mul_f32_e32 v106, 0xbfb8aa3b, v106
	v_cndmask_b32_e64 v107, v107, v114, s[0:1]
	v_cndmask_b32_e32 v114, 0, v179, vcc
	v_sub_f32_e32 v107, v107, v114
	v_sub_f32_e32 v107, -0.5, v107
	v_mul_f32_e32 v107, 0x3fb8aa3b, v107
	v_exp_f32_e32 v107, v107
	v_mul_f32_e32 v108, 0xbfb8aa3b, v108
	v_mul_f32_e32 v109, 0xbfb8aa3b, v109
	v_exp_f32_e32 v110, v110
	v_exp_f32_e32 v111, v111
	v_mul_f32_e32 v104, 0xbfb8aa3b, v104
	v_mul_f32_e32 v105, 0xbfb8aa3b, v105
	v_exp_f32_e32 v114, v106
	v_mul_f32_e32 v106, 0xbfb8aa3b, v107
	v_exp_f32_e32 v108, v108
	v_exp_f32_e32 v109, v109
	v_exp_f32_e32 v104, v104
	v_exp_f32_e32 v105, v105
	v_exp_f32_e32 v115, v106
	v_cvt_pk_f16_f32 v107, v110, v111
	v_add_co_u32_e32 v110, vcc, s47, v120
	v_cvt_pk_f16_f32 v106, v108, v109
	v_cvt_pk_f16_f32 v108, v104, v105
	v_cvt_pk_f16_f32 v109, v114, v115
	s_mov_b64 s[0:1], 0x20000
	v_addc_co_u32_e32 v111, vcc, 0, v121, vcc
	v_lshl_add_u64 v[104:105], v[120:121], 0, s[0:1]
	global_store_dwordx4 v[110:111], v[106:109], off sc1
	v_add_f32_e32 v100, v100, v132
	v_mul_f32_e32 v100, 0xbfb8aa3b, v100
	v_exp_f32_e32 v100, v100
	v_add_f32_e32 v101, v101, v133
	v_mul_f32_e32 v101, 0xbfb8aa3b, v101
	v_exp_f32_e32 v101, v101
	v_add_f32_e32 v100, 1.0, v100
	v_cmp_gt_f32_e32 vcc, s64, v100
	v_add_f32_e32 v102, v102, v134
	v_add_f32_e32 v101, 1.0, v101
	v_cndmask_b32_e64 v106, 0, 32, vcc
	v_ldexp_f32 v100, v100, v106
	v_log_f32_e32 v100, v100
	v_mul_f32_e32 v102, 0xbfb8aa3b, v102
	v_exp_f32_e32 v102, v102
	v_add_f32_e32 v103, v103, v135
	v_mul_f32_e32 v106, 0x3f317217, v100
	v_fma_f32 v106, v100, s65, -v106
	v_fmac_f32_e32 v106, 0x3377d1cf, v100
	v_fmac_f32_e32 v106, 0x3f317217, v100
	v_cmp_lt_f32_e64 s[0:1], |v100|, s66
	v_add_f32_e32 v102, 1.0, v102
	v_mul_f32_e32 v103, 0xbfb8aa3b, v103
	v_cndmask_b32_e64 v100, v100, v106, s[0:1]
	v_cndmask_b32_e32 v106, 0, v179, vcc
	v_cmp_gt_f32_e32 vcc, s64, v101
	v_sub_f32_e32 v100, v100, v106
	v_exp_f32_e32 v103, v103
	v_cndmask_b32_e64 v106, 0, 32, vcc
	v_ldexp_f32 v101, v101, v106
	v_log_f32_e32 v101, v101
	v_add_f32_e32 v103, 1.0, v103
	v_add_f32_e32 v96, v96, v128
	v_mul_f32_e32 v96, 0xbfb8aa3b, v96
	v_mul_f32_e32 v106, 0x3f317217, v101
	v_fma_f32 v106, v101, s65, -v106
	v_fmac_f32_e32 v106, 0x3377d1cf, v101
	v_fmac_f32_e32 v106, 0x3f317217, v101
	v_cmp_lt_f32_e64 s[0:1], |v101|, s66
	v_exp_f32_e32 v96, v96
	v_add_f32_e32 v97, v97, v129
	v_cndmask_b32_e64 v101, v101, v106, s[0:1]
	v_cndmask_b32_e32 v106, 0, v179, vcc
	v_cmp_gt_f32_e32 vcc, s64, v102
	v_sub_f32_e32 v101, v101, v106
	v_add_f32_e32 v96, 1.0, v96
	v_cndmask_b32_e64 v106, 0, 32, vcc
	v_ldexp_f32 v102, v102, v106
	v_log_f32_e32 v102, v102
	v_mul_f32_e32 v97, 0xbfb8aa3b, v97
	v_exp_f32_e32 v97, v97
	v_add_f32_e32 v98, v98, v130
	v_mul_f32_e32 v106, 0x3f317217, v102
	v_fma_f32 v106, v102, s65, -v106
	v_fmac_f32_e32 v106, 0x3377d1cf, v102
	v_fmac_f32_e32 v106, 0x3f317217, v102
	v_cmp_lt_f32_e64 s[0:1], |v102|, s66
	v_add_f32_e32 v97, 1.0, v97
	v_mul_f32_e32 v98, 0xbfb8aa3b, v98
	v_cndmask_b32_e64 v102, v102, v106, s[0:1]
	v_cndmask_b32_e32 v106, 0, v179, vcc
	v_cmp_gt_f32_e32 vcc, s64, v103
	v_sub_f32_e32 v102, v102, v106
	v_exp_f32_e32 v98, v98
	v_cndmask_b32_e64 v106, 0, 32, vcc
	v_ldexp_f32 v103, v103, v106
	v_log_f32_e32 v103, v103
	v_add_f32_e32 v98, 1.0, v98
	v_add_f32_e32 v99, v99, v131
	v_mul_f32_e32 v99, 0xbfb8aa3b, v99
	v_mul_f32_e32 v106, 0x3f317217, v103
	v_fma_f32 v106, v103, s65, -v106
	v_fmac_f32_e32 v106, 0x3377d1cf, v103
	v_fmac_f32_e32 v106, 0x3f317217, v103
	v_cmp_lt_f32_e64 s[0:1], |v103|, s66
	v_exp_f32_e32 v99, v99
	v_sub_f32_e32 v102, -0.5, v102
	v_cndmask_b32_e64 v103, v103, v106, s[0:1]
	v_cndmask_b32_e32 v106, 0, v179, vcc
	v_cmp_gt_f32_e32 vcc, s64, v96
	v_sub_f32_e32 v103, v103, v106
	v_add_f32_e32 v99, 1.0, v99
	v_cndmask_b32_e64 v106, 0, 32, vcc
	v_ldexp_f32 v96, v96, v106
	v_log_f32_e32 v96, v96
	v_sub_f32_e32 v103, -0.5, v103
	v_sub_f32_e32 v100, -0.5, v100
	v_sub_f32_e32 v101, -0.5, v101
	v_mul_f32_e32 v106, 0x3f317217, v96
	v_fma_f32 v106, v96, s65, -v106
	v_fmac_f32_e32 v106, 0x3377d1cf, v96
	v_fmac_f32_e32 v106, 0x3f317217, v96
	v_cmp_lt_f32_e64 s[0:1], |v96|, s66
	v_mul_f32_e32 v102, 0x3fb8aa3b, v102
	v_mul_f32_e32 v103, 0x3fb8aa3b, v103
;     template <int MODE> __device__ __forceinline__ void run(AccRef acc, const Unit& u, int wr, int wc, int fr, int fq) const {
;     ...
;                     for (int e = 0; e < 4; ++e) { x[e] = acc[ai][bj][m][0][e] + bias[e]; x[4 + e] = acc[ai][bj][m][1][e] + bias[4 + e]; }
;                     u32x4 w;
;                     if (MODE == 0) {
; #pragma unroll
;                         for (int e = 0; e < 8; ++e) { const float sp = __logf(1.f + __expf(-x[e])); x[e] = __expf(-__expf(-sp - 0.5f)); }
;                         w.x = pkh(x[0], x[1]); w.y = pkh(x[2], x[3]); w.z = pkh(x[4], x[5]); w.w = pkh(x[6], x[7]);
;                         *(u32x4*)(WA + (size_t)row * 2048 + seg * 512 + cc) = w;
	v_cndmask_b32_e64 v96, v96, v106, s[0:1]
	v_cndmask_b32_e32 v106, 0, v179, vcc
	v_cmp_gt_f32_e32 vcc, s64, v97
	v_sub_f32_e32 v96, v96, v106
	v_sub_f32_e32 v96, -0.5, v96
	v_cndmask_b32_e64 v106, 0, 32, vcc
	v_ldexp_f32 v97, v97, v106
	v_log_f32_e32 v97, v97
	v_mul_f32_e32 v100, 0x3fb8aa3b, v100
	v_mul_f32_e32 v101, 0x3fb8aa3b, v101
	v_exp_f32_e32 v102, v102
	v_mul_f32_e32 v106, 0x3f317217, v97
	v_fma_f32 v106, v97, s65, -v106
	v_fmac_f32_e32 v106, 0x3377d1cf, v97
	v_fmac_f32_e32 v106, 0x3f317217, v97
	v_cmp_lt_f32_e64 s[0:1], |v97|, s66
	v_exp_f32_e32 v103, v103
	v_mul_f32_e32 v96, 0x3fb8aa3b, v96
	v_cndmask_b32_e64 v97, v97, v106, s[0:1]
	v_cndmask_b32_e32 v106, 0, v179, vcc
	v_cmp_gt_f32_e32 vcc, s64, v98
	v_sub_f32_e32 v97, v97, v106
	v_sub_f32_e32 v97, -0.5, v97
	v_cndmask_b32_e64 v106, 0, 32, vcc
	v_ldexp_f32 v98, v98, v106
	v_log_f32_e32 v98, v98
	v_mul_f32_e32 v97, 0x3fb8aa3b, v97
	v_exp_f32_e32 v100, v100
	v_exp_f32_e32 v101, v101
	v_mul_f32_e32 v106, 0x3f317217, v98
	v_fma_f32 v106, v98, s65, -v106
	v_fmac_f32_e32 v106, 0x3377d1cf, v98
	v_fmac_f32_e32 v106, 0x3f317217, v98
	v_cmp_lt_f32_e64 s[0:1], |v98|, s66
	v_exp_f32_e32 v96, v96
	v_exp_f32_e32 v97, v97
	v_cndmask_b32_e64 v98, v98, v106, s[0:1]
	v_cndmask_b32_e32 v106, 0, v179, vcc
	v_cmp_gt_f32_e32 vcc, s64, v99
	v_sub_f32_e32 v98, v98, v106
	v_sub_f32_e32 v98, -0.5, v98
	v_cndmask_b32_e64 v106, 0, 32, vcc
	v_ldexp_f32 v99, v99, v106
	v_log_f32_e32 v99, v99
	v_mul_f32_e32 v98, 0x3fb8aa3b, v98
	v_exp_f32_e32 v98, v98
	v_mul_f32_e32 v102, 0xbfb8aa3b, v102
	v_mul_f32_e32 v106, 0x3f317217, v99
	v_fma_f32 v106, v99, s65, -v106
	v_fmac_f32_e32 v106, 0x3377d1cf, v99
	v_fmac_f32_e32 v106, 0x3f317217, v99
	v_cmp_lt_f32_e64 s[0:1], |v99|, s66
	v_mul_f32_e32 v103, 0xbfb8aa3b, v103
	v_mul_f32_e32 v98, 0xbfb8aa3b, v98
	v_cndmask_b32_e64 v99, v99, v106, s[0:1]
	v_cndmask_b32_e32 v106, 0, v179, vcc
	v_sub_f32_e32 v99, v99, v106
	v_sub_f32_e32 v99, -0.5, v99
	v_mul_f32_e32 v99, 0x3fb8aa3b, v99
	v_exp_f32_e32 v99, v99
	v_mul_f32_e32 v100, 0xbfb8aa3b, v100
	v_mul_f32_e32 v101, 0xbfb8aa3b, v101
	v_exp_f32_e32 v102, v102
	v_exp_f32_e32 v103, v103
	v_mul_f32_e32 v96, 0xbfb8aa3b, v96
	v_mul_f32_e32 v97, 0xbfb8aa3b, v97
	v_exp_f32_e32 v106, v98
	v_mul_f32_e32 v98, 0xbfb8aa3b, v99
	v_exp_f32_e32 v100, v100
	v_exp_f32_e32 v101, v101
	v_exp_f32_e32 v96, v96
	v_exp_f32_e32 v97, v97
	v_exp_f32_e32 v107, v98
	v_cvt_pk_f16_f32 v99, v102, v103
	v_add_co_u32_e32 v102, vcc, s39, v120
	v_cvt_pk_f16_f32 v98, v100, v101
	v_cvt_pk_f16_f32 v100, v96, v97
	v_cvt_pk_f16_f32 v101, v106, v107
	s_mov_b64 s[0:1], 0x30000
	v_addc_co_u32_e32 v103, vcc, 0, v121, vcc
	v_lshl_add_u64 v[96:97], v[120:121], 0, s[0:1]
	global_store_dwordx4 v[102:103], v[98:101], off sc1
	v_add_f32_e32 v92, v92, v132
	v_mul_f32_e32 v92, 0xbfb8aa3b, v92
	v_exp_f32_e32 v92, v92
	v_add_f32_e32 v93, v93, v133
	v_mul_f32_e32 v93, 0xbfb8aa3b, v93
	v_exp_f32_e32 v93, v93
	v_add_f32_e32 v92, 1.0, v92
	v_cmp_gt_f32_e32 vcc, s64, v92
	v_add_f32_e32 v94, v94, v134
	v_add_f32_e32 v93, 1.0, v93
	v_cndmask_b32_e64 v98, 0, 32, vcc
	v_ldexp_f32 v92, v92, v98
	v_log_f32_e32 v92, v92
	v_mul_f32_e32 v94, 0xbfb8aa3b, v94
	v_exp_f32_e32 v94, v94
	v_add_f32_e32 v95, v95, v135
	v_mul_f32_e32 v98, 0x3f317217, v92
	v_fma_f32 v98, v92, s65, -v98
	v_fmac_f32_e32 v98, 0x3377d1cf, v92
	v_fmac_f32_e32 v98, 0x3f317217, v92
	v_cmp_lt_f32_e64 s[0:1], |v92|, s66
	v_add_f32_e32 v94, 1.0, v94
	v_mul_f32_e32 v95, 0xbfb8aa3b, v95
	v_cndmask_b32_e64 v92, v92, v98, s[0:1]
	v_cndmask_b32_e32 v98, 0, v179, vcc
	v_cmp_gt_f32_e32 vcc, s64, v93
	v_sub_f32_e32 v92, v92, v98
	v_exp_f32_e32 v95, v95
	v_cndmask_b32_e64 v98, 0, 32, vcc
	v_ldexp_f32 v93, v93, v98
	v_log_f32_e32 v93, v93
	v_add_f32_e32 v95, 1.0, v95
	v_add_f32_e32 v88, v88, v128
	v_mul_f32_e32 v88, 0xbfb8aa3b, v88
	v_mul_f32_e32 v98, 0x3f317217, v93
	v_fma_f32 v98, v93, s65, -v98
	v_fmac_f32_e32 v98, 0x3377d1cf, v93
	v_fmac_f32_e32 v98, 0x3f317217, v93
	v_cmp_lt_f32_e64 s[0:1], |v93|, s66
	v_exp_f32_e32 v88, v88
	v_add_f32_e32 v89, v89, v129
	v_cndmask_b32_e64 v93, v93, v98, s[0:1]
	v_cndmask_b32_e32 v98, 0, v179, vcc
	v_cmp_gt_f32_e32 vcc, s64, v94
	v_sub_f32_e32 v93, v93, v98
	v_add_f32_e32 v88, 1.0, v88
	v_cndmask_b32_e64 v98, 0, 32, vcc
	v_ldexp_f32 v94, v94, v98
	v_log_f32_e32 v94, v94
	v_mul_f32_e32 v89, 0xbfb8aa3b, v89
	v_exp_f32_e32 v89, v89
	v_add_f32_e32 v90, v90, v130
	v_mul_f32_e32 v98, 0x3f317217, v94
	v_fma_f32 v98, v94, s65, -v98
	v_fmac_f32_e32 v98, 0x3377d1cf, v94
	v_fmac_f32_e32 v98, 0x3f317217, v94
	v_cmp_lt_f32_e64 s[0:1], |v94|, s66
	v_add_f32_e32 v89, 1.0, v89
	v_mul_f32_e32 v90, 0xbfb8aa3b, v90
	v_cndmask_b32_e64 v94, v94, v98, s[0:1]
	v_cndmask_b32_e32 v98, 0, v179, vcc
	v_cmp_gt_f32_e32 vcc, s64, v95
	v_sub_f32_e32 v94, v94, v98
	v_exp_f32_e32 v90, v90
	v_cndmask_b32_e64 v98, 0, 32, vcc
	v_ldexp_f32 v95, v95, v98
	v_log_f32_e32 v95, v95
	v_add_f32_e32 v90, 1.0, v90
	v_add_f32_e32 v91, v91, v131
	v_mul_f32_e32 v91, 0xbfb8aa3b, v91
	v_mul_f32_e32 v98, 0x3f317217, v95
	v_fma_f32 v98, v95, s65, -v98
	v_fmac_f32_e32 v98, 0x3377d1cf, v95
	v_fmac_f32_e32 v98, 0x3f317217, v95
	v_cmp_lt_f32_e64 s[0:1], |v95|, s66
	v_exp_f32_e32 v91, v91
	v_sub_f32_e32 v92, -0.5, v92
	v_cndmask_b32_e64 v95, v95, v98, s[0:1]
	v_cndmask_b32_e32 v98, 0, v179, vcc
	v_cmp_gt_f32_e32 vcc, s64, v88
	v_sub_f32_e32 v95, v95, v98
	v_add_f32_e32 v91, 1.0, v91
	v_cndmask_b32_e64 v98, 0, 32, vcc
	v_ldexp_f32 v88, v88, v98
	v_log_f32_e32 v88, v88
	v_sub_f32_e32 v93, -0.5, v93
	v_mul_f32_e32 v92, 0x3fb8aa3b, v92
	v_mul_f32_e32 v93, 0x3fb8aa3b, v93
	v_mul_f32_e32 v98, 0x3f317217, v88
	v_fma_f32 v98, v88, s65, -v98
	v_fmac_f32_e32 v98, 0x3377d1cf, v88
;     template <int MODE> __device__ __forceinline__ void run(AccRef acc, const Unit& u, int wr, int wc, int fr, int fq) const {
;     ...
;                     for (int e = 0; e < 4; ++e) { x[e] = acc[ai][bj][m][0][e] + bias[e]; x[4 + e] = acc[ai][bj][m][1][e] + bias[4 + e]; }
;                     u32x4 w;
;                     if (MODE == 0) {
; #pragma unroll
;                         for (int e = 0; e < 8; ++e) { const float sp = __logf(1.f + __expf(-x[e])); x[e] = __expf(-__expf(-sp - 0.5f)); }
;                         w.x = pkh(x[0], x[1]); w.y = pkh(x[2], x[3]); w.z = pkh(x[4], x[5]); w.w = pkh(x[6], x[7]);
;                         *(u32x4*)(WA + (size_t)row * 2048 + seg * 512 + cc) = w;
	v_fmac_f32_e32 v98, 0x3f317217, v88
	v_cmp_lt_f32_e64 s[0:1], |v88|, s66
	v_sub_f32_e32 v94, -0.5, v94
	v_sub_f32_e32 v95, -0.5, v95
	v_cndmask_b32_e64 v88, v88, v98, s[0:1]
	v_cndmask_b32_e32 v98, 0, v179, vcc
	v_cmp_gt_f32_e32 vcc, s64, v89
	v_sub_f32_e32 v88, v88, v98
	v_sub_f32_e32 v88, -0.5, v88
	v_cndmask_b32_e64 v98, 0, 32, vcc
	v_ldexp_f32 v89, v89, v98
	v_log_f32_e32 v89, v89
	v_mul_f32_e32 v88, 0x3fb8aa3b, v88
	v_exp_f32_e32 v92, v92
	v_exp_f32_e32 v93, v93
	v_mul_f32_e32 v98, 0x3f317217, v89
	v_fma_f32 v98, v89, s65, -v98
	v_fmac_f32_e32 v98, 0x3377d1cf, v89
	v_fmac_f32_e32 v98, 0x3f317217, v89
	v_cmp_lt_f32_e64 s[0:1], |v89|, s66
	v_mul_f32_e32 v94, 0x3fb8aa3b, v94
	v_mul_f32_e32 v95, 0x3fb8aa3b, v95
	v_cndmask_b32_e64 v89, v89, v98, s[0:1]
	v_cndmask_b32_e32 v98, 0, v179, vcc
	v_cmp_gt_f32_e32 vcc, s64, v90
	v_sub_f32_e32 v89, v89, v98
	v_sub_f32_e32 v89, -0.5, v89
	v_cndmask_b32_e64 v98, 0, 32, vcc
	v_ldexp_f32 v90, v90, v98
	v_log_f32_e32 v90, v90
	v_mul_f32_e32 v89, 0x3fb8aa3b, v89
	v_exp_f32_e32 v88, v88
	v_exp_f32_e32 v89, v89
	v_mul_f32_e32 v98, 0x3f317217, v90
	v_fma_f32 v98, v90, s65, -v98
	v_fmac_f32_e32 v98, 0x3377d1cf, v90
	v_fmac_f32_e32 v98, 0x3f317217, v90
	v_cmp_lt_f32_e64 s[0:1], |v90|, s66
	v_exp_f32_e32 v94, v94
	v_exp_f32_e32 v95, v95
	v_cndmask_b32_e64 v90, v90, v98, s[0:1]
	v_cndmask_b32_e32 v98, 0, v179, vcc
	v_cmp_gt_f32_e32 vcc, s64, v91
	v_sub_f32_e32 v90, v90, v98
	v_sub_f32_e32 v90, -0.5, v90
	v_cndmask_b32_e64 v98, 0, 32, vcc
	v_ldexp_f32 v91, v91, v98
	v_log_f32_e32 v91, v91
	v_mul_f32_e32 v90, 0x3fb8aa3b, v90
	v_exp_f32_e32 v90, v90
	v_mul_f32_e32 v92, 0xbfb8aa3b, v92
	v_mul_f32_e32 v98, 0x3f317217, v91
	v_fma_f32 v98, v91, s65, -v98
	v_fmac_f32_e32 v98, 0x3377d1cf, v91
	v_fmac_f32_e32 v98, 0x3f317217, v91
	v_cmp_lt_f32_e64 s[0:1], |v91|, s66
	v_mul_f32_e32 v93, 0xbfb8aa3b, v93
	v_mul_f32_e32 v88, 0xbfb8aa3b, v88
	v_cndmask_b32_e64 v91, v91, v98, s[0:1]
	v_cndmask_b32_e32 v98, 0, v179, vcc
	v_sub_f32_e32 v91, v91, v98
	v_sub_f32_e32 v91, -0.5, v91
	v_mul_f32_e32 v91, 0x3fb8aa3b, v91
	v_exp_f32_e32 v91, v91
	v_mul_f32_e32 v89, 0xbfb8aa3b, v89
	v_exp_f32_e32 v92, v92
	v_exp_f32_e32 v93, v93
	v_mul_f32_e32 v94, 0xbfb8aa3b, v94
	v_mul_f32_e32 v95, 0xbfb8aa3b, v95
	v_exp_f32_e32 v88, v88
	v_exp_f32_e32 v89, v89
	v_mul_f32_e32 v90, 0xbfb8aa3b, v90
	v_exp_f32_e32 v94, v94
	v_exp_f32_e32 v95, v95
	v_exp_f32_e32 v98, v90
	v_mul_f32_e32 v90, 0xbfb8aa3b, v91
	v_exp_f32_e32 v99, v90
	s_mov_b64 s[0:1], 0x80000
	v_cvt_pk_f16_f32 v90, v92, v93
	v_cvt_pk_f16_f32 v92, v88, v89
	v_lshl_add_u64 v[88:89], v[120:121], 0, s[0:1]
	s_mov_b32 s0, 0x80000
	v_cvt_pk_f16_f32 v91, v94, v95
	v_add_co_u32_e32 v94, vcc, s0, v120
	v_cvt_pk_f16_f32 v93, v98, v99
	s_nop 0
	v_addc_co_u32_e32 v95, vcc, 0, v121, vcc
	global_store_dwordx4 v[94:95], v[90:93], off sc1
	v_add_f32_e32 v84, v84, v132
	v_mul_f32_e32 v84, 0xbfb8aa3b, v84
	v_exp_f32_e32 v84, v84
	v_add_f32_e32 v85, v85, v133
	v_mul_f32_e32 v85, 0xbfb8aa3b, v85
	v_exp_f32_e32 v85, v85
	v_add_f32_e32 v84, 1.0, v84
	v_cmp_gt_f32_e32 vcc, s64, v84
	v_add_f32_e32 v86, v86, v134
	v_add_f32_e32 v85, 1.0, v85
	v_cndmask_b32_e64 v90, 0, 32, vcc
	v_ldexp_f32 v84, v84, v90
	v_log_f32_e32 v84, v84
	v_mul_f32_e32 v86, 0xbfb8aa3b, v86
	v_exp_f32_e32 v86, v86
	v_add_f32_e32 v87, v87, v135
	v_mul_f32_e32 v90, 0x3f317217, v84
	v_fma_f32 v90, v84, s65, -v90
	v_fmac_f32_e32 v90, 0x3377d1cf, v84
	v_fmac_f32_e32 v90, 0x3f317217, v84
	v_cmp_lt_f32_e64 s[0:1], |v84|, s66
	v_add_f32_e32 v86, 1.0, v86
	v_mul_f32_e32 v87, 0xbfb8aa3b, v87
	v_cndmask_b32_e64 v84, v84, v90, s[0:1]
	v_cndmask_b32_e32 v90, 0, v179, vcc
	v_cmp_gt_f32_e32 vcc, s64, v85
	v_sub_f32_e32 v84, v84, v90
	v_exp_f32_e32 v87, v87
	v_cndmask_b32_e64 v90, 0, 32, vcc
	v_ldexp_f32 v85, v85, v90
	v_log_f32_e32 v85, v85
	v_add_f32_e32 v87, 1.0, v87
	v_add_f32_e32 v80, v80, v128
	v_mul_f32_e32 v80, 0xbfb8aa3b, v80
	v_mul_f32_e32 v90, 0x3f317217, v85
	v_fma_f32 v90, v85, s65, -v90
	v_fmac_f32_e32 v90, 0x3377d1cf, v85
	v_fmac_f32_e32 v90, 0x3f317217, v85
	v_cmp_lt_f32_e64 s[0:1], |v85|, s66
	v_exp_f32_e32 v80, v80
	v_add_f32_e32 v81, v81, v129
	v_cndmask_b32_e64 v85, v85, v90, s[0:1]
	v_cndmask_b32_e32 v90, 0, v179, vcc
	v_cmp_gt_f32_e32 vcc, s64, v86
	v_sub_f32_e32 v85, v85, v90
	v_add_f32_e32 v80, 1.0, v80
	v_cndmask_b32_e64 v90, 0, 32, vcc
	v_ldexp_f32 v86, v86, v90
	v_log_f32_e32 v86, v86
	v_mul_f32_e32 v81, 0xbfb8aa3b, v81
	v_exp_f32_e32 v81, v81
	v_add_f32_e32 v82, v82, v130
	v_mul_f32_e32 v90, 0x3f317217, v86
	v_fma_f32 v90, v86, s65, -v90
	v_fmac_f32_e32 v90, 0x3377d1cf, v86
	v_fmac_f32_e32 v90, 0x3f317217, v86
	v_cmp_lt_f32_e64 s[0:1], |v86|, s66
	v_add_f32_e32 v81, 1.0, v81
	v_mul_f32_e32 v82, 0xbfb8aa3b, v82
	v_cndmask_b32_e64 v86, v86, v90, s[0:1]
	v_cndmask_b32_e32 v90, 0, v179, vcc
	v_cmp_gt_f32_e32 vcc, s64, v87
	v_sub_f32_e32 v86, v86, v90
	v_exp_f32_e32 v82, v82
	v_cndmask_b32_e64 v90, 0, 32, vcc
	v_ldexp_f32 v87, v87, v90
	v_log_f32_e32 v87, v87
	v_add_f32_e32 v82, 1.0, v82
	v_add_f32_e32 v83, v83, v131
	v_mul_f32_e32 v83, 0xbfb8aa3b, v83
	v_mul_f32_e32 v90, 0x3f317217, v87
	v_fma_f32 v90, v87, s65, -v90
	v_fmac_f32_e32 v90, 0x3377d1cf, v87
	v_fmac_f32_e32 v90, 0x3f317217, v87
	v_cmp_lt_f32_e64 s[0:1], |v87|, s66
	v_exp_f32_e32 v83, v83
	v_sub_f32_e32 v86, -0.5, v86
	v_cndmask_b32_e64 v87, v87, v90, s[0:1]
	v_cndmask_b32_e32 v90, 0, v179, vcc
	v_cmp_gt_f32_e32 vcc, s64, v80
	v_sub_f32_e32 v87, v87, v90
	v_add_f32_e32 v83, 1.0, v83
	v_cndmask_b32_e64 v90, 0, 32, vcc
	v_ldexp_f32 v80, v80, v90
	v_log_f32_e32 v80, v80
	v_sub_f32_e32 v87, -0.5, v87
	v_sub_f32_e32 v84, -0.5, v84
	v_sub_f32_e32 v85, -0.5, v85
;     template <int MODE> __device__ __forceinline__ void run(AccRef acc, const Unit& u, int wr, int wc, int fr, int fq) const {
;     ...
;                     for (int e = 0; e < 4; ++e) { x[e] = acc[ai][bj][m][0][e] + bias[e]; x[4 + e] = acc[ai][bj][m][1][e] + bias[4 + e]; }
;                     u32x4 w;
;                     if (MODE == 0) {
; #pragma unroll
;                         for (int e = 0; e < 8; ++e) { const float sp = __logf(1.f + __expf(-x[e])); x[e] = __expf(-__expf(-sp - 0.5f)); }
;                         w.x = pkh(x[0], x[1]); w.y = pkh(x[2], x[3]); w.z = pkh(x[4], x[5]); w.w = pkh(x[6], x[7]);
;                         *(u32x4*)(WA + (size_t)row * 2048 + seg * 512 + cc) = w;
	v_mul_f32_e32 v90, 0x3f317217, v80
	v_fma_f32 v90, v80, s65, -v90
	v_fmac_f32_e32 v90, 0x3377d1cf, v80
	v_fmac_f32_e32 v90, 0x3f317217, v80
	v_cmp_lt_f32_e64 s[0:1], |v80|, s66
	v_mul_f32_e32 v86, 0x3fb8aa3b, v86
	v_mul_f32_e32 v87, 0x3fb8aa3b, v87
	v_cndmask_b32_e64 v80, v80, v90, s[0:1]
	v_cndmask_b32_e32 v90, 0, v179, vcc
	v_cmp_gt_f32_e32 vcc, s64, v81
	v_sub_f32_e32 v80, v80, v90
	v_sub_f32_e32 v80, -0.5, v80
	v_cndmask_b32_e64 v90, 0, 32, vcc
	v_ldexp_f32 v81, v81, v90
	v_log_f32_e32 v81, v81
	v_mul_f32_e32 v84, 0x3fb8aa3b, v84
	v_mul_f32_e32 v85, 0x3fb8aa3b, v85
	v_exp_f32_e32 v86, v86
	v_mul_f32_e32 v90, 0x3f317217, v81
	v_fma_f32 v90, v81, s65, -v90
	v_fmac_f32_e32 v90, 0x3377d1cf, v81
	v_fmac_f32_e32 v90, 0x3f317217, v81
	v_cmp_lt_f32_e64 s[0:1], |v81|, s66
	v_exp_f32_e32 v87, v87
	v_mul_f32_e32 v80, 0x3fb8aa3b, v80
	v_cndmask_b32_e64 v81, v81, v90, s[0:1]
	v_cndmask_b32_e32 v90, 0, v179, vcc
	v_cmp_gt_f32_e32 vcc, s64, v82
	v_sub_f32_e32 v81, v81, v90
	v_sub_f32_e32 v81, -0.5, v81
	v_cndmask_b32_e64 v90, 0, 32, vcc
	v_ldexp_f32 v82, v82, v90
	v_log_f32_e32 v82, v82
	v_mul_f32_e32 v81, 0x3fb8aa3b, v81
	v_exp_f32_e32 v84, v84
	v_exp_f32_e32 v85, v85
	v_mul_f32_e32 v90, 0x3f317217, v82
	v_fma_f32 v90, v82, s65, -v90
	v_fmac_f32_e32 v90, 0x3377d1cf, v82
	v_fmac_f32_e32 v90, 0x3f317217, v82
	v_cmp_lt_f32_e64 s[0:1], |v82|, s66
	v_exp_f32_e32 v80, v80
	v_exp_f32_e32 v81, v81
	v_cndmask_b32_e64 v82, v82, v90, s[0:1]
	v_cndmask_b32_e32 v90, 0, v179, vcc
	v_cmp_gt_f32_e32 vcc, s64, v83
	v_sub_f32_e32 v82, v82, v90
	v_sub_f32_e32 v82, -0.5, v82
	v_cndmask_b32_e64 v90, 0, 32, vcc
	v_ldexp_f32 v83, v83, v90
	v_log_f32_e32 v83, v83
	v_mul_f32_e32 v82, 0x3fb8aa3b, v82
	v_exp_f32_e32 v82, v82
	v_mul_f32_e32 v86, 0xbfb8aa3b, v86
	v_mul_f32_e32 v90, 0x3f317217, v83
	v_fma_f32 v90, v83, s65, -v90
	v_fmac_f32_e32 v90, 0x3377d1cf, v83
	v_fmac_f32_e32 v90, 0x3f317217, v83
	v_cmp_lt_f32_e64 s[0:1], |v83|, s66
	v_mul_f32_e32 v87, 0xbfb8aa3b, v87
	v_mul_f32_e32 v82, 0xbfb8aa3b, v82
	v_cndmask_b32_e64 v83, v83, v90, s[0:1]
	v_cndmask_b32_e32 v90, 0, v179, vcc
	v_sub_f32_e32 v83, v83, v90
	v_sub_f32_e32 v83, -0.5, v83
	v_mul_f32_e32 v83, 0x3fb8aa3b, v83
	v_exp_f32_e32 v83, v83
	v_mul_f32_e32 v84, 0xbfb8aa3b, v84
	v_mul_f32_e32 v85, 0xbfb8aa3b, v85
	v_exp_f32_e32 v86, v86
	v_exp_f32_e32 v87, v87
	v_mul_f32_e32 v80, 0xbfb8aa3b, v80
	v_mul_f32_e32 v81, 0xbfb8aa3b, v81
	v_exp_f32_e32 v90, v82
	v_mul_f32_e32 v82, 0xbfb8aa3b, v83
	v_exp_f32_e32 v84, v84
	v_exp_f32_e32 v85, v85
	v_exp_f32_e32 v80, v80
	v_exp_f32_e32 v81, v81
	v_exp_f32_e32 v91, v82
	v_cvt_pk_f16_f32 v83, v86, v87
	v_add_co_u32_e32 v86, vcc, s62, v120
	v_cvt_pk_f16_f32 v82, v84, v85
	v_cvt_pk_f16_f32 v84, v80, v81
	v_cvt_pk_f16_f32 v85, v90, v91
	s_mov_b64 s[0:1], 0x90000
	v_addc_co_u32_e32 v87, vcc, 0, v121, vcc
	v_lshl_add_u64 v[80:81], v[120:121], 0, s[0:1]
	global_store_dwordx4 v[86:87], v[82:85], off sc1
	v_add_f32_e32 v76, v76, v132
	v_mul_f32_e32 v76, 0xbfb8aa3b, v76
	v_exp_f32_e32 v76, v76
	v_add_f32_e32 v77, v77, v133
	v_mul_f32_e32 v77, 0xbfb8aa3b, v77
	v_exp_f32_e32 v77, v77
	v_add_f32_e32 v76, 1.0, v76
	v_cmp_gt_f32_e32 vcc, s64, v76
	v_add_f32_e32 v78, v78, v134
	v_add_f32_e32 v77, 1.0, v77
	v_cndmask_b32_e64 v82, 0, 32, vcc
	v_ldexp_f32 v76, v76, v82
	v_log_f32_e32 v76, v76
	v_mul_f32_e32 v78, 0xbfb8aa3b, v78
	v_exp_f32_e32 v78, v78
	v_add_f32_e32 v79, v79, v135
	v_mul_f32_e32 v82, 0x3f317217, v76
	v_fma_f32 v82, v76, s65, -v82
	v_fmac_f32_e32 v82, 0x3377d1cf, v76
	v_fmac_f32_e32 v82, 0x3f317217, v76
	v_cmp_lt_f32_e64 s[0:1], |v76|, s66
	v_add_f32_e32 v78, 1.0, v78
	v_mul_f32_e32 v79, 0xbfb8aa3b, v79
	v_cndmask_b32_e64 v76, v76, v82, s[0:1]
	v_cndmask_b32_e32 v82, 0, v179, vcc
	v_cmp_gt_f32_e32 vcc, s64, v77
	v_sub_f32_e32 v76, v76, v82
	v_exp_f32_e32 v79, v79
	v_cndmask_b32_e64 v82, 0, 32, vcc
	v_ldexp_f32 v77, v77, v82
	v_log_f32_e32 v77, v77
	v_add_f32_e32 v79, 1.0, v79
	v_add_f32_e32 v72, v72, v128
	v_mul_f32_e32 v72, 0xbfb8aa3b, v72
	v_mul_f32_e32 v82, 0x3f317217, v77
	v_fma_f32 v82, v77, s65, -v82
	v_fmac_f32_e32 v82, 0x3377d1cf, v77
	v_fmac_f32_e32 v82, 0x3f317217, v77
	v_cmp_lt_f32_e64 s[0:1], |v77|, s66
	v_exp_f32_e32 v72, v72
	v_add_f32_e32 v73, v73, v129
	v_cndmask_b32_e64 v77, v77, v82, s[0:1]
	v_cndmask_b32_e32 v82, 0, v179, vcc
	v_cmp_gt_f32_e32 vcc, s64, v78
	v_sub_f32_e32 v77, v77, v82
	v_add_f32_e32 v72, 1.0, v72
	v_cndmask_b32_e64 v82, 0, 32, vcc
	v_ldexp_f32 v78, v78, v82
	v_log_f32_e32 v78, v78
	v_mul_f32_e32 v73, 0xbfb8aa3b, v73
	v_exp_f32_e32 v73, v73
	v_add_f32_e32 v74, v74, v130
	v_mul_f32_e32 v82, 0x3f317217, v78
	v_fma_f32 v82, v78, s65, -v82
	v_fmac_f32_e32 v82, 0x3377d1cf, v78
	v_fmac_f32_e32 v82, 0x3f317217, v78
	v_cmp_lt_f32_e64 s[0:1], |v78|, s66
	v_add_f32_e32 v73, 1.0, v73
	v_mul_f32_e32 v74, 0xbfb8aa3b, v74
	v_cndmask_b32_e64 v78, v78, v82, s[0:1]
	v_cndmask_b32_e32 v82, 0, v179, vcc
	v_cmp_gt_f32_e32 vcc, s64, v79
	v_sub_f32_e32 v78, v78, v82
	v_exp_f32_e32 v74, v74
	v_cndmask_b32_e64 v82, 0, 32, vcc
	v_ldexp_f32 v79, v79, v82
	v_log_f32_e32 v79, v79
	v_add_f32_e32 v74, 1.0, v74
	v_add_f32_e32 v75, v75, v131
	v_mul_f32_e32 v75, 0xbfb8aa3b, v75
	v_mul_f32_e32 v82, 0x3f317217, v79
	v_fma_f32 v82, v79, s65, -v82
	v_fmac_f32_e32 v82, 0x3377d1cf, v79
	v_fmac_f32_e32 v82, 0x3f317217, v79
	v_cmp_lt_f32_e64 s[0:1], |v79|, s66
	v_exp_f32_e32 v75, v75
	v_sub_f32_e32 v78, -0.5, v78
	v_cndmask_b32_e64 v79, v79, v82, s[0:1]
	v_cndmask_b32_e32 v82, 0, v179, vcc
	v_cmp_gt_f32_e32 vcc, s64, v72
	v_sub_f32_e32 v79, v79, v82
	v_add_f32_e32 v75, 1.0, v75
	v_cndmask_b32_e64 v82, 0, 32, vcc
	v_ldexp_f32 v72, v72, v82
	v_log_f32_e32 v72, v72
	v_sub_f32_e32 v79, -0.5, v79
;     template <int MODE> __device__ __forceinline__ void run(AccRef acc, const Unit& u, int wr, int wc, int fr, int fq) const {
;     ...
;                     for (int e = 0; e < 4; ++e) { x[e] = acc[ai][bj][m][0][e] + bias[e]; x[4 + e] = acc[ai][bj][m][1][e] + bias[4 + e]; }
;                     u32x4 w;
;                     if (MODE == 0) {
; #pragma unroll
;                         for (int e = 0; e < 8; ++e) { const float sp = __logf(1.f + __expf(-x[e])); x[e] = __expf(-__expf(-sp - 0.5f)); }
;                         w.x = pkh(x[0], x[1]); w.y = pkh(x[2], x[3]); w.z = pkh(x[4], x[5]); w.w = pkh(x[6], x[7]);
;                         *(u32x4*)(WA + (size_t)row * 2048 + seg * 512 + cc) = w;
	v_sub_f32_e32 v76, -0.5, v76
	v_sub_f32_e32 v77, -0.5, v77
	v_mul_f32_e32 v82, 0x3f317217, v72
	v_fma_f32 v82, v72, s65, -v82
	v_fmac_f32_e32 v82, 0x3377d1cf, v72
	v_fmac_f32_e32 v82, 0x3f317217, v72
	v_cmp_lt_f32_e64 s[0:1], |v72|, s66
	v_mul_f32_e32 v78, 0x3fb8aa3b, v78
	v_mul_f32_e32 v79, 0x3fb8aa3b, v79
	v_cndmask_b32_e64 v72, v72, v82, s[0:1]
	v_cndmask_b32_e32 v82, 0, v179, vcc
	v_cmp_gt_f32_e32 vcc, s64, v73
	v_sub_f32_e32 v72, v72, v82
	v_sub_f32_e32 v72, -0.5, v72
	v_cndmask_b32_e64 v82, 0, 32, vcc
	v_ldexp_f32 v73, v73, v82
	v_log_f32_e32 v73, v73
	v_mul_f32_e32 v76, 0x3fb8aa3b, v76
	v_mul_f32_e32 v77, 0x3fb8aa3b, v77
	v_exp_f32_e32 v78, v78
	v_mul_f32_e32 v82, 0x3f317217, v73
	v_fma_f32 v82, v73, s65, -v82
	v_fmac_f32_e32 v82, 0x3377d1cf, v73
	v_fmac_f32_e32 v82, 0x3f317217, v73
	v_cmp_lt_f32_e64 s[0:1], |v73|, s66
	v_exp_f32_e32 v79, v79
	v_mul_f32_e32 v72, 0x3fb8aa3b, v72
	v_cndmask_b32_e64 v73, v73, v82, s[0:1]
	v_cndmask_b32_e32 v82, 0, v179, vcc
	v_cmp_gt_f32_e32 vcc, s64, v74
	v_sub_f32_e32 v73, v73, v82
	v_sub_f32_e32 v73, -0.5, v73
	v_cndmask_b32_e64 v82, 0, 32, vcc
	v_ldexp_f32 v74, v74, v82
	v_log_f32_e32 v74, v74
	v_mul_f32_e32 v73, 0x3fb8aa3b, v73
	v_exp_f32_e32 v76, v76
	v_exp_f32_e32 v77, v77
	v_mul_f32_e32 v82, 0x3f317217, v74
	v_fma_f32 v82, v74, s65, -v82
	v_fmac_f32_e32 v82, 0x3377d1cf, v74
	v_fmac_f32_e32 v82, 0x3f317217, v74
	v_cmp_lt_f32_e64 s[0:1], |v74|, s66
	v_exp_f32_e32 v72, v72
	v_exp_f32_e32 v73, v73
	v_cndmask_b32_e64 v74, v74, v82, s[0:1]
	v_cndmask_b32_e32 v82, 0, v179, vcc
	v_cmp_gt_f32_e32 vcc, s64, v75
	v_sub_f32_e32 v74, v74, v82
	v_sub_f32_e32 v74, -0.5, v74
	v_cndmask_b32_e64 v82, 0, 32, vcc
	v_ldexp_f32 v75, v75, v82
	v_log_f32_e32 v75, v75
	v_mul_f32_e32 v74, 0x3fb8aa3b, v74
	v_exp_f32_e32 v74, v74
	v_mul_f32_e32 v78, 0xbfb8aa3b, v78
	v_mul_f32_e32 v82, 0x3f317217, v75
	v_fma_f32 v82, v75, s65, -v82
	v_fmac_f32_e32 v82, 0x3377d1cf, v75
	v_fmac_f32_e32 v82, 0x3f317217, v75
	v_cmp_lt_f32_e64 s[0:1], |v75|, s66
	v_mul_f32_e32 v79, 0xbfb8aa3b, v79
	v_mul_f32_e32 v74, 0xbfb8aa3b, v74
	v_cndmask_b32_e64 v75, v75, v82, s[0:1]
	v_cndmask_b32_e32 v82, 0, v179, vcc
	v_sub_f32_e32 v75, v75, v82
	v_sub_f32_e32 v75, -0.5, v75
	v_mul_f32_e32 v75, 0x3fb8aa3b, v75
	v_exp_f32_e32 v75, v75
	v_mul_f32_e32 v76, 0xbfb8aa3b, v76
	v_mul_f32_e32 v77, 0xbfb8aa3b, v77
	v_exp_f32_e32 v78, v78
	v_exp_f32_e32 v79, v79
	v_mul_f32_e32 v72, 0xbfb8aa3b, v72
	v_mul_f32_e32 v73, 0xbfb8aa3b, v73
	v_exp_f32_e32 v82, v74
	v_mul_f32_e32 v74, 0xbfb8aa3b, v75
	v_exp_f32_e32 v76, v76
	v_exp_f32_e32 v77, v77
	v_exp_f32_e32 v72, v72
	v_exp_f32_e32 v73, v73
	v_exp_f32_e32 v83, v74
	v_cvt_pk_f16_f32 v75, v78, v79
	v_add_co_u32_e32 v78, vcc, s63, v120
	v_cvt_pk_f16_f32 v74, v76, v77
	v_cvt_pk_f16_f32 v76, v72, v73
	v_cvt_pk_f16_f32 v77, v82, v83
	v_addc_co_u32_e32 v79, vcc, 0, v121, vcc
	v_lshl_add_u64 v[72:73], v[120:121], 0, s[70:71]
	global_store_dwordx4 v[78:79], v[74:77], off sc1
	v_add_f32_e32 v68, v68, v132
	v_mul_f32_e32 v68, 0xbfb8aa3b, v68
	v_exp_f32_e32 v68, v68
	v_add_f32_e32 v69, v69, v133
	v_mul_f32_e32 v69, 0xbfb8aa3b, v69
	v_exp_f32_e32 v69, v69
	v_add_f32_e32 v68, 1.0, v68
	v_cmp_gt_f32_e32 vcc, s64, v68
	v_add_f32_e32 v70, v70, v134
	v_add_f32_e32 v69, 1.0, v69
	v_cndmask_b32_e64 v74, 0, 32, vcc
	v_ldexp_f32 v68, v68, v74
	v_log_f32_e32 v68, v68
	v_mul_f32_e32 v70, 0xbfb8aa3b, v70
	v_exp_f32_e32 v70, v70
	v_add_f32_e32 v71, v71, v135
	v_mul_f32_e32 v74, 0x3f317217, v68
	v_fma_f32 v74, v68, s65, -v74
	v_fmac_f32_e32 v74, 0x3377d1cf, v68
	v_fmac_f32_e32 v74, 0x3f317217, v68
	v_cmp_lt_f32_e64 s[0:1], |v68|, s66
	v_add_f32_e32 v70, 1.0, v70
	v_mul_f32_e32 v71, 0xbfb8aa3b, v71
	v_cndmask_b32_e64 v68, v68, v74, s[0:1]
	v_cndmask_b32_e32 v74, 0, v179, vcc
	v_cmp_gt_f32_e32 vcc, s64, v69
	v_sub_f32_e32 v68, v68, v74
	v_exp_f32_e32 v71, v71
	v_cndmask_b32_e64 v74, 0, 32, vcc
	v_ldexp_f32 v69, v69, v74
	v_log_f32_e32 v69, v69
	v_add_f32_e32 v71, 1.0, v71
	v_add_f32_e32 v64, v64, v128
	v_mul_f32_e32 v64, 0xbfb8aa3b, v64
	v_mul_f32_e32 v74, 0x3f317217, v69
	v_fma_f32 v74, v69, s65, -v74
	v_fmac_f32_e32 v74, 0x3377d1cf, v69
	v_fmac_f32_e32 v74, 0x3f317217, v69
	v_cmp_lt_f32_e64 s[0:1], |v69|, s66
	v_exp_f32_e32 v64, v64
	v_add_f32_e32 v65, v65, v129
	v_cndmask_b32_e64 v69, v69, v74, s[0:1]
	v_cndmask_b32_e32 v74, 0, v179, vcc
	v_cmp_gt_f32_e32 vcc, s64, v70
	v_sub_f32_e32 v69, v69, v74
	v_add_f32_e32 v64, 1.0, v64
	v_cndmask_b32_e64 v74, 0, 32, vcc
	v_ldexp_f32 v70, v70, v74
	v_log_f32_e32 v70, v70
	v_mul_f32_e32 v65, 0xbfb8aa3b, v65
	v_exp_f32_e32 v65, v65
	v_add_f32_e32 v66, v66, v130
	v_mul_f32_e32 v74, 0x3f317217, v70
	v_fma_f32 v74, v70, s65, -v74
	v_fmac_f32_e32 v74, 0x3377d1cf, v70
	v_fmac_f32_e32 v74, 0x3f317217, v70
	v_cmp_lt_f32_e64 s[0:1], |v70|, s66
	v_add_f32_e32 v65, 1.0, v65
	v_mul_f32_e32 v66, 0xbfb8aa3b, v66
	v_cndmask_b32_e64 v70, v70, v74, s[0:1]
	v_cndmask_b32_e32 v74, 0, v179, vcc
	v_cmp_gt_f32_e32 vcc, s64, v71
	v_sub_f32_e32 v70, v70, v74
	v_exp_f32_e32 v66, v66
	v_cndmask_b32_e64 v74, 0, 32, vcc
	v_ldexp_f32 v71, v71, v74
	v_log_f32_e32 v71, v71
	v_add_f32_e32 v66, 1.0, v66
	v_add_f32_e32 v67, v67, v131
	v_mul_f32_e32 v67, 0xbfb8aa3b, v67
	v_mul_f32_e32 v74, 0x3f317217, v71
	v_fma_f32 v74, v71, s65, -v74
	v_fmac_f32_e32 v74, 0x3377d1cf, v71
	v_fmac_f32_e32 v74, 0x3f317217, v71
	v_cmp_lt_f32_e64 s[0:1], |v71|, s66
	v_exp_f32_e32 v67, v67
	v_sub_f32_e32 v68, -0.5, v68
	v_cndmask_b32_e64 v71, v71, v74, s[0:1]
	v_cndmask_b32_e32 v74, 0, v179, vcc
	v_cmp_gt_f32_e32 vcc, s64, v64
	v_sub_f32_e32 v71, v71, v74
	v_sub_f32_e32 v69, -0.5, v69
	v_cndmask_b32_e64 v74, 0, 32, vcc
	v_ldexp_f32 v64, v64, v74
;     template <int MODE> __device__ __forceinline__ void run(AccRef acc, const Unit& u, int wr, int wc, int fr, int fq) const {
;     ...
;             if (MODE < 2) { const float* bp = (MODE == 0 ? w0 + seg * 512 : a0 + (seg - 2) * 512) + cc; const f32x4 b0 = *(const f32x4*)bp, b1 = *(const f32x4*)(bp + 4);
;                 bias[0] = b0[0]; bias[1] = b0[1]; bias[2] = b0[2]; bias[3] = b0[3]; bias[4] = b1[0]; bias[5] = b1[1]; bias[6] = b1[2]; bias[7] = b1[3]; }
;             else {
; #pragma unroll
;                 for (int e = 0; e < 8; ++e) bias[e] = 0.f; }
; #pragma unroll
;             for (int ai = 0; ai < 2; ++ai)
; #pragma unroll
;                 for (int m = 0; m < 4; ++m) {
;                     const int row = row0 + ai * 128 + m * 16;
;                     float x[8];
; #pragma unroll
;                     for (int e = 0; e < 4; ++e) { x[e] = acc[ai][bj][m][0][e] + bias[e]; x[4 + e] = acc[ai][bj][m][1][e] + bias[4 + e]; }
;                     u32x4 w;
;                     if (MODE == 0) {
; #pragma unroll
;                         for (int e = 0; e < 8; ++e) { const float sp = __logf(1.f + __expf(-x[e])); x[e] = __expf(-__expf(-sp - 0.5f)); }
;                         w.x = pkh(x[0], x[1]); w.y = pkh(x[2], x[3]); w.z = pkh(x[4], x[5]); w.w = pkh(x[6], x[7]);
;                         *(u32x4*)(WA + (size_t)row * 2048 + seg * 512 + cc) = w;
	v_log_f32_e32 v64, v64
	v_mul_f32_e32 v68, 0x3fb8aa3b, v68
	v_mul_f32_e32 v69, 0x3fb8aa3b, v69
	v_sub_f32_e32 v70, -0.5, v70
	v_mul_f32_e32 v74, 0x3f317217, v64
	v_fma_f32 v74, v64, s65, -v74
	v_fmac_f32_e32 v74, 0x3377d1cf, v64
	v_fmac_f32_e32 v74, 0x3f317217, v64
	v_cmp_lt_f32_e64 s[0:1], |v64|, s66
	v_sub_f32_e32 v71, -0.5, v71
	v_exp_f32_e32 v68, v68
	v_cndmask_b32_e64 v64, v64, v74, s[0:1]
	v_cndmask_b32_e32 v74, 0, v179, vcc
	v_cmp_gt_f32_e32 vcc, s64, v65
	v_sub_f32_e32 v64, v64, v74
	v_sub_f32_e32 v64, -0.5, v64
	v_cndmask_b32_e64 v74, 0, 32, vcc
	v_ldexp_f32 v65, v65, v74
	v_log_f32_e32 v65, v65
	v_mul_f32_e32 v64, 0x3fb8aa3b, v64
	v_exp_f32_e32 v64, v64
	v_exp_f32_e32 v69, v69
	v_mul_f32_e32 v74, 0x3f317217, v65
	v_fma_f32 v74, v65, s65, -v74
	v_fmac_f32_e32 v74, 0x3377d1cf, v65
	v_fmac_f32_e32 v74, 0x3f317217, v65
	v_cmp_lt_f32_e64 s[0:1], |v65|, s66
	v_mul_f32_e32 v64, 0xbfb8aa3b, v64
	v_mul_f32_e32 v70, 0x3fb8aa3b, v70
	v_cndmask_b32_e64 v65, v65, v74, s[0:1]
	v_cndmask_b32_e32 v74, 0, v179, vcc
	v_sub_f32_e32 v65, v65, v74
	v_cmp_gt_f32_e32 vcc, s64, v66
	v_sub_f32_e32 v65, -0.5, v65
	v_mul_f32_e32 v65, 0x3fb8aa3b, v65
	v_cndmask_b32_e64 v74, 0, 32, vcc
	v_ldexp_f32 v66, v66, v74
	v_exp_f32_e32 v65, v65
	v_log_f32_e32 v66, v66
	v_exp_f32_e32 v74, v64
	v_mul_f32_e32 v71, 0x3fb8aa3b, v71
	v_mul_f32_e32 v64, 0xbfb8aa3b, v65
	v_mul_f32_e32 v65, 0x3f317217, v66
	v_fma_f32 v65, v66, s65, -v65
	v_fmac_f32_e32 v65, 0x3377d1cf, v66
	v_fmac_f32_e32 v65, 0x3f317217, v66
	v_cmp_lt_f32_e64 s[0:1], |v66|, s66
	v_exp_f32_e32 v70, v70
	v_exp_f32_e32 v71, v71
	v_cndmask_b32_e64 v65, v66, v65, s[0:1]
	v_cndmask_b32_e32 v66, 0, v179, vcc
	v_sub_f32_e32 v65, v65, v66
	v_add_f32_e32 v66, 1.0, v67
	v_cmp_gt_f32_e32 vcc, s64, v66
	v_sub_f32_e32 v65, -0.5, v65
	v_mul_f32_e32 v65, 0x3fb8aa3b, v65
	v_cndmask_b32_e64 v67, 0, 32, vcc
	v_ldexp_f32 v66, v66, v67
	v_log_f32_e32 v66, v66
	v_exp_f32_e32 v65, v65
	v_mul_f32_e32 v68, 0xbfb8aa3b, v68
	v_mul_f32_e32 v69, 0xbfb8aa3b, v69
	v_mul_f32_e32 v67, 0x3f317217, v66
	v_fma_f32 v67, v66, s65, -v67
	v_fmac_f32_e32 v67, 0x3377d1cf, v66
	v_fmac_f32_e32 v67, 0x3f317217, v66
	v_cmp_lt_f32_e64 s[0:1], |v66|, s66
	v_exp_f32_e32 v68, v68
	v_exp_f32_e32 v69, v69
	v_cndmask_b32_e64 v66, v66, v67, s[0:1]
	v_cndmask_b32_e32 v67, 0, v179, vcc
	v_sub_f32_e32 v66, v66, v67
	v_sub_f32_e32 v66, -0.5, v66
	v_mul_f32_e32 v66, 0x3fb8aa3b, v66
	v_exp_f32_e32 v66, v66
	v_exp_f32_e32 v67, v64
	v_mul_f32_e32 v64, 0xbfb8aa3b, v65
	v_mul_f32_e32 v70, 0xbfb8aa3b, v70
	v_mul_f32_e32 v71, 0xbfb8aa3b, v71
	v_exp_f32_e32 v75, v64
	v_mul_f32_e32 v64, 0xbfb8aa3b, v66
	v_exp_f32_e32 v70, v70
	v_exp_f32_e32 v71, v71
	v_exp_f32_e32 v76, v64
	v_cvt_pk_f16_f32 v64, v68, v69
	v_add_co_u32_e32 v68, vcc, s90, v120
	v_cvt_pk_f16_f32 v65, v70, v71
	v_cvt_pk_f16_f32 v66, v74, v67
	v_cvt_pk_f16_f32 v67, v75, v76
	v_addc_co_u32_e32 v69, vcc, 0, v121, vcc
	v_lshl_add_u64 v[74:75], v[120:121], 0, s[94:95]
	global_store_dwordx4 v[68:69], v[64:67], off sc1
	global_load_dwordx4 v[64:67], v[136:137], off offset:528
	global_load_dwordx4 v[68:71], v[136:137], off offset:512
	s_waitcnt vmcnt(0)
	v_add_f32_e32 v77, v56, v64
	v_add_f32_e32 v76, v60, v68
	v_mul_f32_e32 v56, 0xbfb8aa3b, v76
	v_exp_f32_e32 v56, v56
	v_add_f32_e32 v60, v58, v66
	v_add_f32_e32 v61, v61, v69
	v_add_f32_e32 v78, v57, v65
	v_add_f32_e32 v56, 1.0, v56
	v_cmp_gt_f32_e32 vcc, s64, v56
	v_add_f32_e32 v57, v59, v67
	v_add_f32_e32 v62, v62, v70
	v_cndmask_b32_e64 v58, 0, 32, vcc
	v_ldexp_f32 v56, v56, v58
	v_log_f32_e32 v56, v56
	v_add_f32_e32 v63, v63, v71
	v_mul_f32_e32 v60, 0xbfb8aa3b, v60
	v_exp_f32_e32 v60, v60
	v_mul_f32_e32 v58, 0x3f317217, v56
	v_fma_f32 v58, v56, s65, -v58
	v_fmac_f32_e32 v58, 0x3377d1cf, v56
	v_fmac_f32_e32 v58, 0x3f317217, v56
	v_cmp_lt_f32_e64 s[0:1], |v56|, s66
	v_add_f32_e32 v60, 1.0, v60
	v_mul_f32_e32 v57, 0xbfb8aa3b, v57
	v_cndmask_b32_e64 v56, v56, v58, s[0:1]
	v_cndmask_b32_e32 v58, 0, v179, vcc
	v_sub_f32_e32 v56, v56, v58
	v_mul_f32_e32 v58, 0xbfb8aa3b, v61
	v_exp_f32_e32 v58, v58
	v_exp_f32_e32 v57, v57
	v_sub_f32_e32 v56, -0.5, v56
	v_mul_f32_e32 v56, 0x3fb8aa3b, v56
	v_add_f32_e32 v58, 1.0, v58
	v_cmp_gt_f32_e32 vcc, s64, v58
	v_add_f32_e32 v57, 1.0, v57
	v_exp_f32_e32 v56, v56
	v_cndmask_b32_e64 v59, 0, 32, vcc
	v_ldexp_f32 v58, v58, v59
	v_log_f32_e32 v58, v58
	v_mul_f32_e32 v56, 0xbfb8aa3b, v56
	v_exp_f32_e32 v56, v56
	v_mul_f32_e32 v59, 0x3f317217, v58
	v_fma_f32 v59, v58, s65, -v59
	v_fmac_f32_e32 v59, 0x3377d1cf, v58
	v_fmac_f32_e32 v59, 0x3f317217, v58
	v_cmp_lt_f32_e64 s[0:1], |v58|, s66
	s_nop 1
	v_cndmask_b32_e64 v58, v58, v59, s[0:1]
	v_cndmask_b32_e32 v59, 0, v179, vcc
	v_sub_f32_e32 v58, v58, v59
	v_mul_f32_e32 v59, 0xbfb8aa3b, v62
	v_exp_f32_e32 v59, v59
	v_sub_f32_e32 v58, -0.5, v58
	v_mul_f32_e32 v58, 0x3fb8aa3b, v58
	v_exp_f32_e32 v58, v58
	v_add_f32_e32 v59, 1.0, v59
	v_cmp_gt_f32_e32 vcc, s64, v59
	v_mul_f32_e32 v58, 0xbfb8aa3b, v58
	s_nop 0
	v_cndmask_b32_e64 v61, 0, 32, vcc
	v_ldexp_f32 v59, v59, v61
	v_log_f32_e32 v59, v59
	v_exp_f32_e32 v58, v58
	v_mul_f32_e32 v61, 0x3f317217, v59
	v_fma_f32 v61, v59, s65, -v61
	v_fmac_f32_e32 v61, 0x3377d1cf, v59
	v_fmac_f32_e32 v61, 0x3f317217, v59
	v_cmp_lt_f32_e64 s[0:1], |v59|, s66
	v_cvt_pk_f16_f32 v56, v56, v58
	s_nop 0
	v_cndmask_b32_e64 v59, v59, v61, s[0:1]
	v_cndmask_b32_e32 v61, 0, v179, vcc
	v_sub_f32_e32 v59, v59, v61
	v_mul_f32_e32 v61, 0xbfb8aa3b, v63
	v_exp_f32_e32 v61, v61
	v_sub_f32_e32 v59, -0.5, v59
	v_mul_f32_e32 v59, 0x3fb8aa3b, v59
	v_exp_f32_e32 v59, v59
	v_add_f32_e32 v61, 1.0, v61
	v_cmp_gt_f32_e32 vcc, s64, v61
	v_mul_f32_e32 v59, 0xbfb8aa3b, v59
	s_nop 0
;     template <int MODE> __device__ __forceinline__ void run(AccRef acc, const Unit& u, int wr, int wc, int fr, int fq) const {
;     ...
;                     for (int e = 0; e < 4; ++e) { x[e] = acc[ai][bj][m][0][e] + bias[e]; x[4 + e] = acc[ai][bj][m][1][e] + bias[4 + e]; }
;                     u32x4 w;
;                     if (MODE == 0) {
; #pragma unroll
;                         for (int e = 0; e < 8; ++e) { const float sp = __logf(1.f + __expf(-x[e])); x[e] = __expf(-__expf(-sp - 0.5f)); }
;                         w.x = pkh(x[0], x[1]); w.y = pkh(x[2], x[3]); w.z = pkh(x[4], x[5]); w.w = pkh(x[6], x[7]);
;                         *(u32x4*)(WA + (size_t)row * 2048 + seg * 512 + cc) = w;
	v_cndmask_b32_e64 v62, 0, 32, vcc
	v_ldexp_f32 v61, v61, v62
	v_log_f32_e32 v61, v61
	v_exp_f32_e32 v59, v59
	v_mul_f32_e32 v62, 0x3f317217, v61
	v_fma_f32 v62, v61, s65, -v62
	v_fmac_f32_e32 v62, 0x3377d1cf, v61
	v_fmac_f32_e32 v62, 0x3f317217, v61
	v_cmp_lt_f32_e64 s[0:1], |v61|, s66
	s_nop 1
	v_cndmask_b32_e64 v61, v61, v62, s[0:1]
	v_cndmask_b32_e32 v62, 0, v179, vcc
	v_sub_f32_e32 v61, v61, v62
	v_mul_f32_e32 v62, 0xbfb8aa3b, v77
	v_exp_f32_e32 v62, v62
	v_sub_f32_e32 v61, -0.5, v61
	v_mul_f32_e32 v61, 0x3fb8aa3b, v61
	v_exp_f32_e32 v61, v61
	v_add_f32_e32 v62, 1.0, v62
	v_cmp_gt_f32_e32 vcc, s64, v62
	v_mul_f32_e32 v61, 0xbfb8aa3b, v61
	s_nop 0
	v_cndmask_b32_e64 v63, 0, 32, vcc
	v_ldexp_f32 v62, v62, v63
	v_log_f32_e32 v62, v62
	v_exp_f32_e32 v61, v61
	v_mul_f32_e32 v63, 0x3f317217, v62
	v_fma_f32 v63, v62, s65, -v63
	v_fmac_f32_e32 v63, 0x3377d1cf, v62
	v_fmac_f32_e32 v63, 0x3f317217, v62
	v_cmp_lt_f32_e64 s[0:1], |v62|, s66
	s_nop 1
	v_cndmask_b32_e64 v62, v62, v63, s[0:1]
	v_cndmask_b32_e32 v63, 0, v179, vcc
	v_sub_f32_e32 v62, v62, v63
	v_mul_f32_e32 v63, 0xbfb8aa3b, v78
	v_exp_f32_e32 v63, v63
	v_sub_f32_e32 v62, -0.5, v62
	v_mul_f32_e32 v62, 0x3fb8aa3b, v62
	v_exp_f32_e32 v62, v62
	v_add_f32_e32 v63, 1.0, v63
	v_cmp_gt_f32_e32 vcc, s64, v63
	v_mul_f32_e32 v62, 0xbfb8aa3b, v62
	s_nop 0
	v_cndmask_b32_e64 v76, 0, 32, vcc
	v_ldexp_f32 v63, v63, v76
	v_log_f32_e32 v63, v63
	v_exp_f32_e32 v62, v62
	v_mul_f32_e32 v76, 0x3f317217, v63
	v_fma_f32 v76, v63, s65, -v76
	v_fmac_f32_e32 v76, 0x3377d1cf, v63
	v_fmac_f32_e32 v76, 0x3f317217, v63
	v_cmp_lt_f32_e64 s[0:1], |v63|, s66
	s_nop 1
	v_cndmask_b32_e64 v63, v63, v76, s[0:1]
	v_cndmask_b32_e32 v76, 0, v179, vcc
	v_cmp_gt_f32_e32 vcc, s64, v60
	v_sub_f32_e32 v63, v63, v76
	v_sub_f32_e32 v63, -0.5, v63
	v_cndmask_b32_e64 v76, 0, 32, vcc
	v_ldexp_f32 v60, v60, v76
	v_log_f32_e32 v60, v60
	v_mul_f32_e32 v63, 0x3fb8aa3b, v63
	v_exp_f32_e32 v63, v63
	v_mul_f32_e32 v76, 0x3f317217, v60
	v_fma_f32 v76, v60, s65, -v76
	v_fmac_f32_e32 v76, 0x3377d1cf, v60
	v_fmac_f32_e32 v76, 0x3f317217, v60
	v_cmp_lt_f32_e64 s[0:1], |v60|, s66
	v_mul_f32_e32 v63, 0xbfb8aa3b, v63
	v_exp_f32_e32 v63, v63
	v_cndmask_b32_e64 v60, v60, v76, s[0:1]
	v_cndmask_b32_e32 v76, 0, v179, vcc
	v_cmp_gt_f32_e32 vcc, s64, v57
	v_sub_f32_e32 v60, v60, v76
	v_sub_f32_e32 v60, -0.5, v60
	v_cndmask_b32_e64 v76, 0, 32, vcc
	v_ldexp_f32 v57, v57, v76
	v_log_f32_e32 v57, v57
	v_mul_f32_e32 v60, 0x3fb8aa3b, v60
	v_exp_f32_e32 v60, v60
	v_cvt_pk_f16_f32 v58, v62, v63
	v_mul_f32_e32 v76, 0x3f317217, v57
	v_fma_f32 v76, v57, s65, -v76
	v_fmac_f32_e32 v76, 0x3377d1cf, v57
	v_fmac_f32_e32 v76, 0x3f317217, v57
	v_cmp_lt_f32_e64 s[0:1], |v57|, s66
	v_mul_f32_e32 v60, 0xbfb8aa3b, v60
	v_exp_f32_e32 v60, v60
	v_cndmask_b32_e64 v57, v57, v76, s[0:1]
	v_cndmask_b32_e32 v76, 0, v179, vcc
	v_sub_f32_e32 v57, v57, v76
	v_sub_f32_e32 v57, -0.5, v57
	v_mul_f32_e32 v57, 0x3fb8aa3b, v57
	v_exp_f32_e32 v57, v57
	s_nop 0
	v_mul_f32_e32 v57, 0xbfb8aa3b, v57
	v_exp_f32_e32 v76, v57
	v_cvt_pk_f16_f32 v57, v59, v61
	v_cvt_pk_f16_f32 v59, v60, v76
	global_store_dwordx4 v[120:121], v[56:59], off offset:256 sc1
	v_add_f32_e32 v52, v52, v68
	v_mul_f32_e32 v52, 0xbfb8aa3b, v52
	v_exp_f32_e32 v52, v52
	v_add_f32_e32 v53, v53, v69
	v_mul_f32_e32 v53, 0xbfb8aa3b, v53
	v_exp_f32_e32 v53, v53
	v_add_f32_e32 v52, 1.0, v52
	v_cmp_gt_f32_e32 vcc, s64, v52
	v_add_f32_e32 v54, v54, v70
	v_add_f32_e32 v53, 1.0, v53
	v_cndmask_b32_e64 v56, 0, 32, vcc
	v_ldexp_f32 v52, v52, v56
	v_log_f32_e32 v52, v52
	v_mul_f32_e32 v54, 0xbfb8aa3b, v54
	v_exp_f32_e32 v54, v54
	v_add_f32_e32 v55, v55, v71
	v_mul_f32_e32 v56, 0x3f317217, v52
	v_fma_f32 v56, v52, s65, -v56
	v_fmac_f32_e32 v56, 0x3377d1cf, v52
	v_fmac_f32_e32 v56, 0x3f317217, v52
	v_cmp_lt_f32_e64 s[0:1], |v52|, s66
	v_add_f32_e32 v54, 1.0, v54
	v_mul_f32_e32 v55, 0xbfb8aa3b, v55
	v_cndmask_b32_e64 v52, v52, v56, s[0:1]
	v_cndmask_b32_e32 v56, 0, v179, vcc
	v_cmp_gt_f32_e32 vcc, s64, v53
	v_sub_f32_e32 v52, v52, v56
	v_exp_f32_e32 v55, v55
	v_cndmask_b32_e64 v56, 0, 32, vcc
	v_ldexp_f32 v53, v53, v56
	v_log_f32_e32 v53, v53
	v_add_f32_e32 v55, 1.0, v55
	v_add_f32_e32 v48, v48, v64
	v_mul_f32_e32 v48, 0xbfb8aa3b, v48
	v_mul_f32_e32 v56, 0x3f317217, v53
	v_fma_f32 v56, v53, s65, -v56
	v_fmac_f32_e32 v56, 0x3377d1cf, v53
	v_fmac_f32_e32 v56, 0x3f317217, v53
	v_cmp_lt_f32_e64 s[0:1], |v53|, s66
	v_exp_f32_e32 v48, v48
	v_add_f32_e32 v49, v49, v65
	v_cndmask_b32_e64 v53, v53, v56, s[0:1]
	v_cndmask_b32_e32 v56, 0, v179, vcc
	v_cmp_gt_f32_e32 vcc, s64, v54
	v_sub_f32_e32 v53, v53, v56
	v_add_f32_e32 v48, 1.0, v48
	v_cndmask_b32_e64 v56, 0, 32, vcc
	v_ldexp_f32 v54, v54, v56
	v_log_f32_e32 v54, v54
	v_mul_f32_e32 v49, 0xbfb8aa3b, v49
	v_exp_f32_e32 v49, v49
	v_add_f32_e32 v50, v50, v66
	v_mul_f32_e32 v56, 0x3f317217, v54
	v_fma_f32 v56, v54, s65, -v56
	v_fmac_f32_e32 v56, 0x3377d1cf, v54
	v_fmac_f32_e32 v56, 0x3f317217, v54
	v_cmp_lt_f32_e64 s[0:1], |v54|, s66
	v_add_f32_e32 v49, 1.0, v49
	v_mul_f32_e32 v50, 0xbfb8aa3b, v50
	v_cndmask_b32_e64 v54, v54, v56, s[0:1]
	v_cndmask_b32_e32 v56, 0, v179, vcc
	v_cmp_gt_f32_e32 vcc, s64, v55
	v_sub_f32_e32 v54, v54, v56
	v_exp_f32_e32 v50, v50
	v_cndmask_b32_e64 v56, 0, 32, vcc
	v_ldexp_f32 v55, v55, v56
	v_log_f32_e32 v55, v55
	v_add_f32_e32 v50, 1.0, v50
	v_add_f32_e32 v51, v51, v67
	v_mul_f32_e32 v51, 0xbfb8aa3b, v51
	v_mul_f32_e32 v56, 0x3f317217, v55
	v_fma_f32 v56, v55, s65, -v56
	v_fmac_f32_e32 v56, 0x3377d1cf, v55
	v_fmac_f32_e32 v56, 0x3f317217, v55
	v_cmp_lt_f32_e64 s[0:1], |v55|, s66
	v_exp_f32_e32 v51, v51
	v_sub_f32_e32 v52, -0.5, v52
	v_cndmask_b32_e64 v55, v55, v56, s[0:1]
;     template <int MODE> __device__ __forceinline__ void run(AccRef acc, const Unit& u, int wr, int wc, int fr, int fq) const {
;     ...
;                     for (int e = 0; e < 4; ++e) { x[e] = acc[ai][bj][m][0][e] + bias[e]; x[4 + e] = acc[ai][bj][m][1][e] + bias[4 + e]; }
;                     u32x4 w;
;                     if (MODE == 0) {
; #pragma unroll
;                         for (int e = 0; e < 8; ++e) { const float sp = __logf(1.f + __expf(-x[e])); x[e] = __expf(-__expf(-sp - 0.5f)); }
;                         w.x = pkh(x[0], x[1]); w.y = pkh(x[2], x[3]); w.z = pkh(x[4], x[5]); w.w = pkh(x[6], x[7]);
;                         *(u32x4*)(WA + (size_t)row * 2048 + seg * 512 + cc) = w;
	v_cndmask_b32_e32 v56, 0, v179, vcc
	v_cmp_gt_f32_e32 vcc, s64, v48
	v_sub_f32_e32 v55, v55, v56
	v_sub_f32_e32 v53, -0.5, v53
	v_cndmask_b32_e64 v56, 0, 32, vcc
	v_ldexp_f32 v48, v48, v56
	v_log_f32_e32 v48, v48
	v_sub_f32_e32 v54, -0.5, v54
	v_sub_f32_e32 v55, -0.5, v55
	v_mul_f32_e32 v52, 0x3fb8aa3b, v52
	v_mul_f32_e32 v56, 0x3f317217, v48
	v_fma_f32 v56, v48, s65, -v56
	v_fmac_f32_e32 v56, 0x3377d1cf, v48
	v_fmac_f32_e32 v56, 0x3f317217, v48
	v_cmp_lt_f32_e64 s[0:1], |v48|, s66
	v_mul_f32_e32 v53, 0x3fb8aa3b, v53
	v_mul_f32_e32 v54, 0x3fb8aa3b, v54
	v_cndmask_b32_e64 v48, v48, v56, s[0:1]
	v_cndmask_b32_e32 v56, 0, v179, vcc
	v_cmp_gt_f32_e32 vcc, s64, v49
	v_sub_f32_e32 v48, v48, v56
	v_sub_f32_e32 v48, -0.5, v48
	v_cndmask_b32_e64 v56, 0, 32, vcc
	v_ldexp_f32 v49, v49, v56
	v_log_f32_e32 v49, v49
	v_mul_f32_e32 v48, 0x3fb8aa3b, v48
	v_exp_f32_e32 v48, v48
	v_mul_f32_e32 v55, 0x3fb8aa3b, v55
	v_mul_f32_e32 v56, 0x3f317217, v49
	v_fma_f32 v56, v49, s65, -v56
	v_fmac_f32_e32 v56, 0x3377d1cf, v49
	v_fmac_f32_e32 v56, 0x3f317217, v49
	v_cmp_lt_f32_e64 s[0:1], |v49|, s66
	v_mul_f32_e32 v48, 0xbfb8aa3b, v48
	v_exp_f32_e32 v52, v52
	v_cndmask_b32_e64 v49, v49, v56, s[0:1]
	v_cndmask_b32_e32 v56, 0, v179, vcc
	v_sub_f32_e32 v49, v49, v56
	v_cmp_gt_f32_e32 vcc, s64, v50
	v_sub_f32_e32 v49, -0.5, v49
	v_mul_f32_e32 v49, 0x3fb8aa3b, v49
	v_cndmask_b32_e64 v56, 0, 32, vcc
	v_ldexp_f32 v50, v50, v56
	v_exp_f32_e32 v49, v49
	v_log_f32_e32 v50, v50
	v_exp_f32_e32 v56, v48
	v_exp_f32_e32 v53, v53
	v_mul_f32_e32 v48, 0xbfb8aa3b, v49
	v_mul_f32_e32 v49, 0x3f317217, v50
	v_fma_f32 v49, v50, s65, -v49
	v_fmac_f32_e32 v49, 0x3377d1cf, v50
	v_fmac_f32_e32 v49, 0x3f317217, v50
	v_cmp_lt_f32_e64 s[0:1], |v50|, s66
	v_exp_f32_e32 v54, v54
	v_exp_f32_e32 v55, v55
	v_cndmask_b32_e64 v49, v50, v49, s[0:1]
	v_cndmask_b32_e32 v50, 0, v179, vcc
	v_sub_f32_e32 v49, v49, v50
	v_add_f32_e32 v50, 1.0, v51
	v_cmp_gt_f32_e32 vcc, s64, v50
	v_sub_f32_e32 v49, -0.5, v49
	v_mul_f32_e32 v49, 0x3fb8aa3b, v49
	v_cndmask_b32_e64 v51, 0, 32, vcc
	v_ldexp_f32 v50, v50, v51
	v_log_f32_e32 v50, v50
	v_exp_f32_e32 v49, v49
	v_mul_f32_e32 v52, 0xbfb8aa3b, v52
	v_mul_f32_e32 v53, 0xbfb8aa3b, v53
	v_mul_f32_e32 v51, 0x3f317217, v50
	v_fma_f32 v51, v50, s65, -v51
	v_fmac_f32_e32 v51, 0x3377d1cf, v50
	v_fmac_f32_e32 v51, 0x3f317217, v50
	v_cmp_lt_f32_e64 s[0:1], |v50|, s66
	v_mul_f32_e32 v54, 0xbfb8aa3b, v54
	v_mul_f32_e32 v55, 0xbfb8aa3b, v55
	v_cndmask_b32_e64 v50, v50, v51, s[0:1]
	v_cndmask_b32_e32 v51, 0, v179, vcc
	v_sub_f32_e32 v50, v50, v51
	v_sub_f32_e32 v50, -0.5, v50
	v_mul_f32_e32 v50, 0x3fb8aa3b, v50
	v_exp_f32_e32 v50, v50
	v_exp_f32_e32 v51, v48
	v_mul_f32_e32 v48, 0xbfb8aa3b, v49
	v_exp_f32_e32 v57, v48
	v_mul_f32_e32 v48, 0xbfb8aa3b, v50
	v_exp_f32_e32 v52, v52
	v_exp_f32_e32 v53, v53
	v_exp_f32_e32 v54, v54
	v_exp_f32_e32 v55, v55
	v_exp_f32_e32 v58, v48
	v_cvt_pk_f16_f32 v48, v52, v53
	v_cvt_pk_f16_f32 v49, v54, v55
	v_cvt_pk_f16_f32 v50, v56, v51
	v_cvt_pk_f16_f32 v51, v57, v58
	global_store_dwordx4 v[112:113], v[48:51], off offset:256 sc1
	v_add_f32_e32 v44, v44, v68
	v_mul_f32_e32 v44, 0xbfb8aa3b, v44
	v_exp_f32_e32 v44, v44
	v_add_f32_e32 v45, v45, v69
	v_mul_f32_e32 v45, 0xbfb8aa3b, v45
	v_exp_f32_e32 v45, v45
	v_add_f32_e32 v44, 1.0, v44
	v_cmp_gt_f32_e32 vcc, s64, v44
	v_add_f32_e32 v46, v46, v70
	v_add_f32_e32 v45, 1.0, v45
	v_cndmask_b32_e64 v48, 0, 32, vcc
	v_ldexp_f32 v44, v44, v48
	v_log_f32_e32 v44, v44
	v_mul_f32_e32 v46, 0xbfb8aa3b, v46
	v_exp_f32_e32 v46, v46
	v_add_f32_e32 v47, v47, v71
	v_mul_f32_e32 v48, 0x3f317217, v44
	v_fma_f32 v48, v44, s65, -v48
	v_fmac_f32_e32 v48, 0x3377d1cf, v44
	v_fmac_f32_e32 v48, 0x3f317217, v44
	v_cmp_lt_f32_e64 s[0:1], |v44|, s66
	v_add_f32_e32 v46, 1.0, v46
	v_mul_f32_e32 v47, 0xbfb8aa3b, v47
	v_cndmask_b32_e64 v44, v44, v48, s[0:1]
	v_cndmask_b32_e32 v48, 0, v179, vcc
	v_cmp_gt_f32_e32 vcc, s64, v45
	v_sub_f32_e32 v44, v44, v48
	v_exp_f32_e32 v47, v47
	v_cndmask_b32_e64 v48, 0, 32, vcc
	v_ldexp_f32 v45, v45, v48
	v_log_f32_e32 v45, v45
	v_add_f32_e32 v47, 1.0, v47
	v_add_f32_e32 v40, v40, v64
	v_mul_f32_e32 v40, 0xbfb8aa3b, v40
	v_mul_f32_e32 v48, 0x3f317217, v45
	v_fma_f32 v48, v45, s65, -v48
	v_fmac_f32_e32 v48, 0x3377d1cf, v45
	v_fmac_f32_e32 v48, 0x3f317217, v45
	v_cmp_lt_f32_e64 s[0:1], |v45|, s66
	v_exp_f32_e32 v40, v40
	v_add_f32_e32 v41, v41, v65
	v_cndmask_b32_e64 v45, v45, v48, s[0:1]
	v_cndmask_b32_e32 v48, 0, v179, vcc
	v_cmp_gt_f32_e32 vcc, s64, v46
	v_sub_f32_e32 v45, v45, v48
	v_add_f32_e32 v40, 1.0, v40
	v_cndmask_b32_e64 v48, 0, 32, vcc
	v_ldexp_f32 v46, v46, v48
	v_log_f32_e32 v46, v46
	v_mul_f32_e32 v41, 0xbfb8aa3b, v41
	v_exp_f32_e32 v41, v41
	v_add_f32_e32 v42, v42, v66
	v_mul_f32_e32 v48, 0x3f317217, v46
	v_fma_f32 v48, v46, s65, -v48
	v_fmac_f32_e32 v48, 0x3377d1cf, v46
	v_fmac_f32_e32 v48, 0x3f317217, v46
	v_cmp_lt_f32_e64 s[0:1], |v46|, s66
	v_add_f32_e32 v41, 1.0, v41
	v_mul_f32_e32 v42, 0xbfb8aa3b, v42
	v_cndmask_b32_e64 v46, v46, v48, s[0:1]
	v_cndmask_b32_e32 v48, 0, v179, vcc
	v_cmp_gt_f32_e32 vcc, s64, v47
	v_sub_f32_e32 v46, v46, v48
	v_exp_f32_e32 v42, v42
	v_cndmask_b32_e64 v48, 0, 32, vcc
	v_ldexp_f32 v47, v47, v48
	v_log_f32_e32 v47, v47
	v_add_f32_e32 v42, 1.0, v42
	v_add_f32_e32 v43, v43, v67
	v_mul_f32_e32 v43, 0xbfb8aa3b, v43
	v_mul_f32_e32 v48, 0x3f317217, v47
	v_fma_f32 v48, v47, s65, -v48
	v_fmac_f32_e32 v48, 0x3377d1cf, v47
	v_fmac_f32_e32 v48, 0x3f317217, v47
	v_cmp_lt_f32_e64 s[0:1], |v47|, s66
	v_exp_f32_e32 v43, v43
	v_sub_f32_e32 v44, -0.5, v44
	v_cndmask_b32_e64 v47, v47, v48, s[0:1]
	v_cndmask_b32_e32 v48, 0, v179, vcc
	v_cmp_gt_f32_e32 vcc, s64, v40
;     template <int MODE> __device__ __forceinline__ void run(AccRef acc, const Unit& u, int wr, int wc, int fr, int fq) const {
;     ...
;                     for (int e = 0; e < 4; ++e) { x[e] = acc[ai][bj][m][0][e] + bias[e]; x[4 + e] = acc[ai][bj][m][1][e] + bias[4 + e]; }
;                     u32x4 w;
;                     if (MODE == 0) {
; #pragma unroll
;                         for (int e = 0; e < 8; ++e) { const float sp = __logf(1.f + __expf(-x[e])); x[e] = __expf(-__expf(-sp - 0.5f)); }
;                         w.x = pkh(x[0], x[1]); w.y = pkh(x[2], x[3]); w.z = pkh(x[4], x[5]); w.w = pkh(x[6], x[7]);
;                         *(u32x4*)(WA + (size_t)row * 2048 + seg * 512 + cc) = w;
	v_sub_f32_e32 v47, v47, v48
	v_sub_f32_e32 v45, -0.5, v45
	v_cndmask_b32_e64 v48, 0, 32, vcc
	v_ldexp_f32 v40, v40, v48
	v_log_f32_e32 v40, v40
	v_sub_f32_e32 v46, -0.5, v46
	v_sub_f32_e32 v47, -0.5, v47
	v_mul_f32_e32 v44, 0x3fb8aa3b, v44
	v_mul_f32_e32 v48, 0x3f317217, v40
	v_fma_f32 v48, v40, s65, -v48
	v_fmac_f32_e32 v48, 0x3377d1cf, v40
	v_fmac_f32_e32 v48, 0x3f317217, v40
	v_cmp_lt_f32_e64 s[0:1], |v40|, s66
	v_mul_f32_e32 v45, 0x3fb8aa3b, v45
	v_mul_f32_e32 v46, 0x3fb8aa3b, v46
	v_cndmask_b32_e64 v40, v40, v48, s[0:1]
	v_cndmask_b32_e32 v48, 0, v179, vcc
	v_cmp_gt_f32_e32 vcc, s64, v41
	v_sub_f32_e32 v40, v40, v48
	v_sub_f32_e32 v40, -0.5, v40
	v_cndmask_b32_e64 v48, 0, 32, vcc
	v_ldexp_f32 v41, v41, v48
	v_log_f32_e32 v41, v41
	v_mul_f32_e32 v40, 0x3fb8aa3b, v40
	v_exp_f32_e32 v40, v40
	v_mul_f32_e32 v47, 0x3fb8aa3b, v47
	v_mul_f32_e32 v48, 0x3f317217, v41
	v_fma_f32 v48, v41, s65, -v48
	v_fmac_f32_e32 v48, 0x3377d1cf, v41
	v_fmac_f32_e32 v48, 0x3f317217, v41
	v_cmp_lt_f32_e64 s[0:1], |v41|, s66
	v_mul_f32_e32 v40, 0xbfb8aa3b, v40
	v_exp_f32_e32 v44, v44
	v_cndmask_b32_e64 v41, v41, v48, s[0:1]
	v_cndmask_b32_e32 v48, 0, v179, vcc
	v_sub_f32_e32 v41, v41, v48
	v_cmp_gt_f32_e32 vcc, s64, v42
	v_sub_f32_e32 v41, -0.5, v41
	v_mul_f32_e32 v41, 0x3fb8aa3b, v41
	v_cndmask_b32_e64 v48, 0, 32, vcc
	v_ldexp_f32 v42, v42, v48
	v_exp_f32_e32 v41, v41
	v_log_f32_e32 v42, v42
	v_exp_f32_e32 v48, v40
	v_exp_f32_e32 v45, v45
	v_mul_f32_e32 v40, 0xbfb8aa3b, v41
	v_mul_f32_e32 v41, 0x3f317217, v42
	v_fma_f32 v41, v42, s65, -v41
	v_fmac_f32_e32 v41, 0x3377d1cf, v42
	v_fmac_f32_e32 v41, 0x3f317217, v42
	v_cmp_lt_f32_e64 s[0:1], |v42|, s66
	v_exp_f32_e32 v46, v46
	v_exp_f32_e32 v47, v47
	v_cndmask_b32_e64 v41, v42, v41, s[0:1]
	v_cndmask_b32_e32 v42, 0, v179, vcc
	v_sub_f32_e32 v41, v41, v42
	v_add_f32_e32 v42, 1.0, v43
	v_cmp_gt_f32_e32 vcc, s64, v42
	v_sub_f32_e32 v41, -0.5, v41
	v_mul_f32_e32 v41, 0x3fb8aa3b, v41
	v_cndmask_b32_e64 v43, 0, 32, vcc
	v_ldexp_f32 v42, v42, v43
	v_log_f32_e32 v42, v42
	v_exp_f32_e32 v41, v41
	v_mul_f32_e32 v44, 0xbfb8aa3b, v44
	v_mul_f32_e32 v45, 0xbfb8aa3b, v45
	v_mul_f32_e32 v43, 0x3f317217, v42
	v_fma_f32 v43, v42, s65, -v43
	v_fmac_f32_e32 v43, 0x3377d1cf, v42
	v_fmac_f32_e32 v43, 0x3f317217, v42
	v_cmp_lt_f32_e64 s[0:1], |v42|, s66
	v_mul_f32_e32 v46, 0xbfb8aa3b, v46
	v_mul_f32_e32 v47, 0xbfb8aa3b, v47
	v_cndmask_b32_e64 v42, v42, v43, s[0:1]
	v_cndmask_b32_e32 v43, 0, v179, vcc
	v_sub_f32_e32 v42, v42, v43
	v_sub_f32_e32 v42, -0.5, v42
	v_mul_f32_e32 v42, 0x3fb8aa3b, v42
	v_exp_f32_e32 v42, v42
	v_exp_f32_e32 v43, v40
	v_mul_f32_e32 v40, 0xbfb8aa3b, v41
	v_exp_f32_e32 v49, v40
	v_mul_f32_e32 v40, 0xbfb8aa3b, v42
	v_exp_f32_e32 v44, v44
	v_exp_f32_e32 v45, v45
	v_exp_f32_e32 v46, v46
	v_exp_f32_e32 v47, v47
	v_exp_f32_e32 v50, v40
	v_cvt_pk_f16_f32 v40, v44, v45
	v_cvt_pk_f16_f32 v41, v46, v47
	v_cvt_pk_f16_f32 v42, v48, v43
	v_cvt_pk_f16_f32 v43, v49, v50
	global_store_dwordx4 v[104:105], v[40:43], off offset:256 sc1
	v_add_f32_e32 v36, v36, v68
	v_mul_f32_e32 v36, 0xbfb8aa3b, v36
	v_exp_f32_e32 v36, v36
	v_add_f32_e32 v37, v37, v69
	v_mul_f32_e32 v37, 0xbfb8aa3b, v37
	v_exp_f32_e32 v37, v37
	v_add_f32_e32 v36, 1.0, v36
	v_cmp_gt_f32_e32 vcc, s64, v36
	v_add_f32_e32 v38, v38, v70
	v_add_f32_e32 v37, 1.0, v37
	v_cndmask_b32_e64 v40, 0, 32, vcc
	v_ldexp_f32 v36, v36, v40
	v_log_f32_e32 v36, v36
	v_mul_f32_e32 v38, 0xbfb8aa3b, v38
	v_exp_f32_e32 v38, v38
	v_add_f32_e32 v39, v39, v71
	v_mul_f32_e32 v40, 0x3f317217, v36
	v_fma_f32 v40, v36, s65, -v40
	v_fmac_f32_e32 v40, 0x3377d1cf, v36
	v_fmac_f32_e32 v40, 0x3f317217, v36
	v_cmp_lt_f32_e64 s[0:1], |v36|, s66
	v_add_f32_e32 v38, 1.0, v38
	v_mul_f32_e32 v39, 0xbfb8aa3b, v39
	v_cndmask_b32_e64 v36, v36, v40, s[0:1]
	v_cndmask_b32_e32 v40, 0, v179, vcc
	v_cmp_gt_f32_e32 vcc, s64, v37
	v_sub_f32_e32 v36, v36, v40
	v_exp_f32_e32 v39, v39
	v_cndmask_b32_e64 v40, 0, 32, vcc
	v_ldexp_f32 v37, v37, v40
	v_log_f32_e32 v37, v37
	v_add_f32_e32 v39, 1.0, v39
	v_add_f32_e32 v32, v32, v64
	v_mul_f32_e32 v32, 0xbfb8aa3b, v32
	v_mul_f32_e32 v40, 0x3f317217, v37
	v_fma_f32 v40, v37, s65, -v40
	v_fmac_f32_e32 v40, 0x3377d1cf, v37
	v_fmac_f32_e32 v40, 0x3f317217, v37
	v_cmp_lt_f32_e64 s[0:1], |v37|, s66
	v_exp_f32_e32 v32, v32
	v_add_f32_e32 v33, v33, v65
	v_cndmask_b32_e64 v37, v37, v40, s[0:1]
	v_cndmask_b32_e32 v40, 0, v179, vcc
	v_cmp_gt_f32_e32 vcc, s64, v38
	v_sub_f32_e32 v37, v37, v40
	v_add_f32_e32 v32, 1.0, v32
	v_cndmask_b32_e64 v40, 0, 32, vcc
	v_ldexp_f32 v38, v38, v40
	v_log_f32_e32 v38, v38
	v_mul_f32_e32 v33, 0xbfb8aa3b, v33
	v_exp_f32_e32 v33, v33
	v_add_f32_e32 v34, v34, v66
	v_mul_f32_e32 v40, 0x3f317217, v38
	v_fma_f32 v40, v38, s65, -v40
	v_fmac_f32_e32 v40, 0x3377d1cf, v38
	v_fmac_f32_e32 v40, 0x3f317217, v38
	v_cmp_lt_f32_e64 s[0:1], |v38|, s66
	v_add_f32_e32 v33, 1.0, v33
	v_mul_f32_e32 v34, 0xbfb8aa3b, v34
	v_cndmask_b32_e64 v38, v38, v40, s[0:1]
	v_cndmask_b32_e32 v40, 0, v179, vcc
	v_cmp_gt_f32_e32 vcc, s64, v39
	v_sub_f32_e32 v38, v38, v40
	v_exp_f32_e32 v34, v34
	v_cndmask_b32_e64 v40, 0, 32, vcc
	v_ldexp_f32 v39, v39, v40
	v_log_f32_e32 v39, v39
	v_add_f32_e32 v34, 1.0, v34
	v_add_f32_e32 v35, v35, v67
	v_mul_f32_e32 v35, 0xbfb8aa3b, v35
	v_mul_f32_e32 v40, 0x3f317217, v39
	v_fma_f32 v40, v39, s65, -v40
	v_fmac_f32_e32 v40, 0x3377d1cf, v39
	v_fmac_f32_e32 v40, 0x3f317217, v39
	v_cmp_lt_f32_e64 s[0:1], |v39|, s66
	v_exp_f32_e32 v35, v35
	v_sub_f32_e32 v36, -0.5, v36
	v_cndmask_b32_e64 v39, v39, v40, s[0:1]
	v_cndmask_b32_e32 v40, 0, v179, vcc
	v_cmp_gt_f32_e32 vcc, s64, v32
	v_sub_f32_e32 v39, v39, v40
	v_sub_f32_e32 v37, -0.5, v37
	v_cndmask_b32_e64 v40, 0, 32, vcc
;     template <int MODE> __device__ __forceinline__ void run(AccRef acc, const Unit& u, int wr, int wc, int fr, int fq) const {
;     ...
;                     for (int e = 0; e < 4; ++e) { x[e] = acc[ai][bj][m][0][e] + bias[e]; x[4 + e] = acc[ai][bj][m][1][e] + bias[4 + e]; }
;                     u32x4 w;
;                     if (MODE == 0) {
; #pragma unroll
;                         for (int e = 0; e < 8; ++e) { const float sp = __logf(1.f + __expf(-x[e])); x[e] = __expf(-__expf(-sp - 0.5f)); }
;                         w.x = pkh(x[0], x[1]); w.y = pkh(x[2], x[3]); w.z = pkh(x[4], x[5]); w.w = pkh(x[6], x[7]);
;                         *(u32x4*)(WA + (size_t)row * 2048 + seg * 512 + cc) = w;
	v_ldexp_f32 v32, v32, v40
	v_log_f32_e32 v32, v32
	v_sub_f32_e32 v38, -0.5, v38
	v_sub_f32_e32 v39, -0.5, v39
	v_mul_f32_e32 v36, 0x3fb8aa3b, v36
	v_mul_f32_e32 v40, 0x3f317217, v32
	v_fma_f32 v40, v32, s65, -v40
	v_fmac_f32_e32 v40, 0x3377d1cf, v32
	v_fmac_f32_e32 v40, 0x3f317217, v32
	v_cmp_lt_f32_e64 s[0:1], |v32|, s66
	v_mul_f32_e32 v37, 0x3fb8aa3b, v37
	v_mul_f32_e32 v38, 0x3fb8aa3b, v38
	v_cndmask_b32_e64 v32, v32, v40, s[0:1]
	v_cndmask_b32_e32 v40, 0, v179, vcc
	v_cmp_gt_f32_e32 vcc, s64, v33
	v_sub_f32_e32 v32, v32, v40
	v_sub_f32_e32 v32, -0.5, v32
	v_cndmask_b32_e64 v40, 0, 32, vcc
	v_ldexp_f32 v33, v33, v40
	v_log_f32_e32 v33, v33
	v_mul_f32_e32 v32, 0x3fb8aa3b, v32
	v_exp_f32_e32 v32, v32
	v_mul_f32_e32 v39, 0x3fb8aa3b, v39
	v_mul_f32_e32 v40, 0x3f317217, v33
	v_fma_f32 v40, v33, s65, -v40
	v_fmac_f32_e32 v40, 0x3377d1cf, v33
	v_fmac_f32_e32 v40, 0x3f317217, v33
	v_cmp_lt_f32_e64 s[0:1], |v33|, s66
	v_mul_f32_e32 v32, 0xbfb8aa3b, v32
	v_exp_f32_e32 v36, v36
	v_cndmask_b32_e64 v33, v33, v40, s[0:1]
	v_cndmask_b32_e32 v40, 0, v179, vcc
	v_sub_f32_e32 v33, v33, v40
	v_cmp_gt_f32_e32 vcc, s64, v34
	v_sub_f32_e32 v33, -0.5, v33
	v_mul_f32_e32 v33, 0x3fb8aa3b, v33
	v_cndmask_b32_e64 v40, 0, 32, vcc
	v_ldexp_f32 v34, v34, v40
	v_exp_f32_e32 v33, v33
	v_log_f32_e32 v34, v34
	v_exp_f32_e32 v40, v32
	v_exp_f32_e32 v37, v37
	v_mul_f32_e32 v32, 0xbfb8aa3b, v33
	v_mul_f32_e32 v33, 0x3f317217, v34
	v_fma_f32 v33, v34, s65, -v33
	v_fmac_f32_e32 v33, 0x3377d1cf, v34
	v_fmac_f32_e32 v33, 0x3f317217, v34
	v_cmp_lt_f32_e64 s[0:1], |v34|, s66
	v_exp_f32_e32 v38, v38
	v_exp_f32_e32 v39, v39
	v_cndmask_b32_e64 v33, v34, v33, s[0:1]
	v_cndmask_b32_e32 v34, 0, v179, vcc
	v_sub_f32_e32 v33, v33, v34
	v_add_f32_e32 v34, 1.0, v35
	v_cmp_gt_f32_e32 vcc, s64, v34
	v_sub_f32_e32 v33, -0.5, v33
	v_mul_f32_e32 v33, 0x3fb8aa3b, v33
	v_cndmask_b32_e64 v35, 0, 32, vcc
	v_ldexp_f32 v34, v34, v35
	v_log_f32_e32 v34, v34
	v_exp_f32_e32 v33, v33
	v_mul_f32_e32 v36, 0xbfb8aa3b, v36
	v_mul_f32_e32 v37, 0xbfb8aa3b, v37
	v_mul_f32_e32 v35, 0x3f317217, v34
	v_fma_f32 v35, v34, s65, -v35
	v_fmac_f32_e32 v35, 0x3377d1cf, v34
	v_fmac_f32_e32 v35, 0x3f317217, v34
	v_cmp_lt_f32_e64 s[0:1], |v34|, s66
	v_mul_f32_e32 v38, 0xbfb8aa3b, v38
	v_mul_f32_e32 v39, 0xbfb8aa3b, v39
	v_cndmask_b32_e64 v34, v34, v35, s[0:1]
	v_cndmask_b32_e32 v35, 0, v179, vcc
	v_sub_f32_e32 v34, v34, v35
	v_sub_f32_e32 v34, -0.5, v34
	v_mul_f32_e32 v34, 0x3fb8aa3b, v34
	v_exp_f32_e32 v34, v34
	v_exp_f32_e32 v35, v32
	v_mul_f32_e32 v32, 0xbfb8aa3b, v33
	v_exp_f32_e32 v41, v32
	v_mul_f32_e32 v32, 0xbfb8aa3b, v34
	v_exp_f32_e32 v36, v36
	v_exp_f32_e32 v37, v37
	v_exp_f32_e32 v38, v38
	v_exp_f32_e32 v39, v39
	v_exp_f32_e32 v42, v32
	v_cvt_pk_f16_f32 v32, v36, v37
	v_cvt_pk_f16_f32 v33, v38, v39
	v_cvt_pk_f16_f32 v34, v40, v35
	v_cvt_pk_f16_f32 v35, v41, v42
	global_store_dwordx4 v[96:97], v[32:35], off offset:256 sc1
	v_add_f32_e32 v28, v28, v68
	v_mul_f32_e32 v28, 0xbfb8aa3b, v28
	v_exp_f32_e32 v28, v28
	v_add_f32_e32 v29, v29, v69
	v_mul_f32_e32 v29, 0xbfb8aa3b, v29
	v_exp_f32_e32 v29, v29
	v_add_f32_e32 v28, 1.0, v28
	v_cmp_gt_f32_e32 vcc, s64, v28
	v_add_f32_e32 v30, v30, v70
	v_add_f32_e32 v29, 1.0, v29
	v_cndmask_b32_e64 v32, 0, 32, vcc
	v_ldexp_f32 v28, v28, v32
	v_log_f32_e32 v28, v28
	v_mul_f32_e32 v30, 0xbfb8aa3b, v30
	v_exp_f32_e32 v30, v30
	v_add_f32_e32 v31, v31, v71
	v_mul_f32_e32 v32, 0x3f317217, v28
	v_fma_f32 v32, v28, s65, -v32
	v_fmac_f32_e32 v32, 0x3377d1cf, v28
	v_fmac_f32_e32 v32, 0x3f317217, v28
	v_cmp_lt_f32_e64 s[0:1], |v28|, s66
	v_add_f32_e32 v30, 1.0, v30
	v_mul_f32_e32 v31, 0xbfb8aa3b, v31
	v_cndmask_b32_e64 v28, v28, v32, s[0:1]
	v_cndmask_b32_e32 v32, 0, v179, vcc
	v_cmp_gt_f32_e32 vcc, s64, v29
	v_sub_f32_e32 v28, v28, v32
	v_exp_f32_e32 v31, v31
	v_cndmask_b32_e64 v32, 0, 32, vcc
	v_ldexp_f32 v29, v29, v32
	v_log_f32_e32 v29, v29
	v_add_f32_e32 v31, 1.0, v31
	v_add_f32_e32 v24, v24, v64
	v_mul_f32_e32 v24, 0xbfb8aa3b, v24
	v_mul_f32_e32 v32, 0x3f317217, v29
	v_fma_f32 v32, v29, s65, -v32
	v_fmac_f32_e32 v32, 0x3377d1cf, v29
	v_fmac_f32_e32 v32, 0x3f317217, v29
	v_cmp_lt_f32_e64 s[0:1], |v29|, s66
	v_exp_f32_e32 v24, v24
	v_add_f32_e32 v25, v25, v65
	v_cndmask_b32_e64 v29, v29, v32, s[0:1]
	v_cndmask_b32_e32 v32, 0, v179, vcc
	v_cmp_gt_f32_e32 vcc, s64, v30
	v_sub_f32_e32 v29, v29, v32
	v_add_f32_e32 v24, 1.0, v24
	v_cndmask_b32_e64 v32, 0, 32, vcc
	v_ldexp_f32 v30, v30, v32
	v_log_f32_e32 v30, v30
	v_mul_f32_e32 v25, 0xbfb8aa3b, v25
	v_exp_f32_e32 v25, v25
	v_add_f32_e32 v26, v26, v66
	v_mul_f32_e32 v32, 0x3f317217, v30
	v_fma_f32 v32, v30, s65, -v32
	v_fmac_f32_e32 v32, 0x3377d1cf, v30
	v_fmac_f32_e32 v32, 0x3f317217, v30
	v_cmp_lt_f32_e64 s[0:1], |v30|, s66
	v_add_f32_e32 v25, 1.0, v25
	v_mul_f32_e32 v26, 0xbfb8aa3b, v26
	v_cndmask_b32_e64 v30, v30, v32, s[0:1]
	v_cndmask_b32_e32 v32, 0, v179, vcc
	v_cmp_gt_f32_e32 vcc, s64, v31
	v_sub_f32_e32 v30, v30, v32
	v_exp_f32_e32 v26, v26
	v_cndmask_b32_e64 v32, 0, 32, vcc
	v_ldexp_f32 v31, v31, v32
	v_log_f32_e32 v31, v31
	v_add_f32_e32 v26, 1.0, v26
	v_add_f32_e32 v27, v27, v67
	v_mul_f32_e32 v27, 0xbfb8aa3b, v27
	v_mul_f32_e32 v32, 0x3f317217, v31
	v_fma_f32 v32, v31, s65, -v32
	v_fmac_f32_e32 v32, 0x3377d1cf, v31
	v_fmac_f32_e32 v32, 0x3f317217, v31
	v_cmp_lt_f32_e64 s[0:1], |v31|, s66
	v_exp_f32_e32 v27, v27
	v_sub_f32_e32 v28, -0.5, v28
	v_cndmask_b32_e64 v31, v31, v32, s[0:1]
	v_cndmask_b32_e32 v32, 0, v179, vcc
	v_cmp_gt_f32_e32 vcc, s64, v24
	v_sub_f32_e32 v31, v31, v32
	v_sub_f32_e32 v29, -0.5, v29
	v_cndmask_b32_e64 v32, 0, 32, vcc
	v_ldexp_f32 v24, v24, v32
	v_log_f32_e32 v24, v24
	v_sub_f32_e32 v30, -0.5, v30
;     template <int MODE> __device__ __forceinline__ void run(AccRef acc, const Unit& u, int wr, int wc, int fr, int fq) const {
;     ...
;                     for (int e = 0; e < 4; ++e) { x[e] = acc[ai][bj][m][0][e] + bias[e]; x[4 + e] = acc[ai][bj][m][1][e] + bias[4 + e]; }
;                     u32x4 w;
;                     if (MODE == 0) {
; #pragma unroll
;                         for (int e = 0; e < 8; ++e) { const float sp = __logf(1.f + __expf(-x[e])); x[e] = __expf(-__expf(-sp - 0.5f)); }
;                         w.x = pkh(x[0], x[1]); w.y = pkh(x[2], x[3]); w.z = pkh(x[4], x[5]); w.w = pkh(x[6], x[7]);
;                         *(u32x4*)(WA + (size_t)row * 2048 + seg * 512 + cc) = w;
	v_sub_f32_e32 v31, -0.5, v31
	v_mul_f32_e32 v28, 0x3fb8aa3b, v28
	v_mul_f32_e32 v32, 0x3f317217, v24
	v_fma_f32 v32, v24, s65, -v32
	v_fmac_f32_e32 v32, 0x3377d1cf, v24
	v_fmac_f32_e32 v32, 0x3f317217, v24
	v_cmp_lt_f32_e64 s[0:1], |v24|, s66
	v_mul_f32_e32 v29, 0x3fb8aa3b, v29
	v_mul_f32_e32 v30, 0x3fb8aa3b, v30
	v_cndmask_b32_e64 v24, v24, v32, s[0:1]
	v_cndmask_b32_e32 v32, 0, v179, vcc
	v_cmp_gt_f32_e32 vcc, s64, v25
	v_sub_f32_e32 v24, v24, v32
	v_sub_f32_e32 v24, -0.5, v24
	v_cndmask_b32_e64 v32, 0, 32, vcc
	v_ldexp_f32 v25, v25, v32
	v_log_f32_e32 v25, v25
	v_mul_f32_e32 v24, 0x3fb8aa3b, v24
	v_exp_f32_e32 v24, v24
	v_mul_f32_e32 v31, 0x3fb8aa3b, v31
	v_mul_f32_e32 v32, 0x3f317217, v25
	v_fma_f32 v32, v25, s65, -v32
	v_fmac_f32_e32 v32, 0x3377d1cf, v25
	v_fmac_f32_e32 v32, 0x3f317217, v25
	v_cmp_lt_f32_e64 s[0:1], |v25|, s66
	v_mul_f32_e32 v24, 0xbfb8aa3b, v24
	v_exp_f32_e32 v28, v28
	v_cndmask_b32_e64 v25, v25, v32, s[0:1]
	v_cndmask_b32_e32 v32, 0, v179, vcc
	v_sub_f32_e32 v25, v25, v32
	v_cmp_gt_f32_e32 vcc, s64, v26
	v_sub_f32_e32 v25, -0.5, v25
	v_mul_f32_e32 v25, 0x3fb8aa3b, v25
	v_cndmask_b32_e64 v32, 0, 32, vcc
	v_ldexp_f32 v26, v26, v32
	v_exp_f32_e32 v25, v25
	v_log_f32_e32 v26, v26
	v_exp_f32_e32 v32, v24
	v_exp_f32_e32 v29, v29
	v_mul_f32_e32 v24, 0xbfb8aa3b, v25
	v_mul_f32_e32 v25, 0x3f317217, v26
	v_fma_f32 v25, v26, s65, -v25
	v_fmac_f32_e32 v25, 0x3377d1cf, v26
	v_fmac_f32_e32 v25, 0x3f317217, v26
	v_cmp_lt_f32_e64 s[0:1], |v26|, s66
	v_exp_f32_e32 v30, v30
	v_exp_f32_e32 v31, v31
	v_cndmask_b32_e64 v25, v26, v25, s[0:1]
	v_cndmask_b32_e32 v26, 0, v179, vcc
	v_sub_f32_e32 v25, v25, v26
	v_add_f32_e32 v26, 1.0, v27
	v_cmp_gt_f32_e32 vcc, s64, v26
	v_sub_f32_e32 v25, -0.5, v25
	v_mul_f32_e32 v25, 0x3fb8aa3b, v25
	v_cndmask_b32_e64 v27, 0, 32, vcc
	v_ldexp_f32 v26, v26, v27
	v_log_f32_e32 v26, v26
	v_exp_f32_e32 v25, v25
	v_mul_f32_e32 v28, 0xbfb8aa3b, v28
	v_mul_f32_e32 v29, 0xbfb8aa3b, v29
	v_mul_f32_e32 v27, 0x3f317217, v26
	v_fma_f32 v27, v26, s65, -v27
	v_fmac_f32_e32 v27, 0x3377d1cf, v26
	v_fmac_f32_e32 v27, 0x3f317217, v26
	v_cmp_lt_f32_e64 s[0:1], |v26|, s66
	v_mul_f32_e32 v30, 0xbfb8aa3b, v30
	v_mul_f32_e32 v31, 0xbfb8aa3b, v31
	v_cndmask_b32_e64 v26, v26, v27, s[0:1]
	v_cndmask_b32_e32 v27, 0, v179, vcc
	v_sub_f32_e32 v26, v26, v27
	v_sub_f32_e32 v26, -0.5, v26
	v_mul_f32_e32 v26, 0x3fb8aa3b, v26
	v_exp_f32_e32 v26, v26
	v_exp_f32_e32 v27, v24
	v_mul_f32_e32 v24, 0xbfb8aa3b, v25
	v_exp_f32_e32 v33, v24
	v_mul_f32_e32 v24, 0xbfb8aa3b, v26
	v_exp_f32_e32 v28, v28
	v_exp_f32_e32 v29, v29
	v_exp_f32_e32 v30, v30
	v_exp_f32_e32 v31, v31
	v_exp_f32_e32 v34, v24
	v_cvt_pk_f16_f32 v24, v28, v29
	v_cvt_pk_f16_f32 v25, v30, v31
	v_cvt_pk_f16_f32 v26, v32, v27
	v_cvt_pk_f16_f32 v27, v33, v34
	global_store_dwordx4 v[88:89], v[24:27], off offset:256 sc1
	v_add_f32_e32 v20, v20, v68
	v_mul_f32_e32 v20, 0xbfb8aa3b, v20
	v_exp_f32_e32 v20, v20
	v_add_f32_e32 v21, v21, v69
	v_mul_f32_e32 v21, 0xbfb8aa3b, v21
	v_exp_f32_e32 v21, v21
	v_add_f32_e32 v20, 1.0, v20
	v_cmp_gt_f32_e32 vcc, s64, v20
	v_add_f32_e32 v22, v22, v70
	v_add_f32_e32 v21, 1.0, v21
	v_cndmask_b32_e64 v24, 0, 32, vcc
	v_ldexp_f32 v20, v20, v24
	v_log_f32_e32 v20, v20
	v_mul_f32_e32 v22, 0xbfb8aa3b, v22
	v_exp_f32_e32 v22, v22
	v_add_f32_e32 v23, v23, v71
	v_mul_f32_e32 v24, 0x3f317217, v20
	v_fma_f32 v24, v20, s65, -v24
	v_fmac_f32_e32 v24, 0x3377d1cf, v20
	v_fmac_f32_e32 v24, 0x3f317217, v20
	v_cmp_lt_f32_e64 s[0:1], |v20|, s66
	v_add_f32_e32 v22, 1.0, v22
	v_mul_f32_e32 v23, 0xbfb8aa3b, v23
	v_cndmask_b32_e64 v20, v20, v24, s[0:1]
	v_cndmask_b32_e32 v24, 0, v179, vcc
	v_cmp_gt_f32_e32 vcc, s64, v21
	v_sub_f32_e32 v20, v20, v24
	v_exp_f32_e32 v23, v23
	v_cndmask_b32_e64 v24, 0, 32, vcc
	v_ldexp_f32 v21, v21, v24
	v_log_f32_e32 v21, v21
	v_add_f32_e32 v23, 1.0, v23
	v_add_f32_e32 v16, v16, v64
	v_mul_f32_e32 v16, 0xbfb8aa3b, v16
	v_mul_f32_e32 v24, 0x3f317217, v21
	v_fma_f32 v24, v21, s65, -v24
	v_fmac_f32_e32 v24, 0x3377d1cf, v21
	v_fmac_f32_e32 v24, 0x3f317217, v21
	v_cmp_lt_f32_e64 s[0:1], |v21|, s66
	v_exp_f32_e32 v16, v16
	v_add_f32_e32 v17, v17, v65
	v_cndmask_b32_e64 v21, v21, v24, s[0:1]
	v_cndmask_b32_e32 v24, 0, v179, vcc
	v_cmp_gt_f32_e32 vcc, s64, v22
	v_sub_f32_e32 v21, v21, v24
	v_add_f32_e32 v16, 1.0, v16
	v_cndmask_b32_e64 v24, 0, 32, vcc
	v_ldexp_f32 v22, v22, v24
	v_log_f32_e32 v22, v22
	v_mul_f32_e32 v17, 0xbfb8aa3b, v17
	v_exp_f32_e32 v17, v17
	v_add_f32_e32 v18, v18, v66
	v_mul_f32_e32 v24, 0x3f317217, v22
	v_fma_f32 v24, v22, s65, -v24
	v_fmac_f32_e32 v24, 0x3377d1cf, v22
	v_fmac_f32_e32 v24, 0x3f317217, v22
	v_cmp_lt_f32_e64 s[0:1], |v22|, s66
	v_add_f32_e32 v17, 1.0, v17
	v_mul_f32_e32 v18, 0xbfb8aa3b, v18
	v_cndmask_b32_e64 v22, v22, v24, s[0:1]
	v_cndmask_b32_e32 v24, 0, v179, vcc
	v_cmp_gt_f32_e32 vcc, s64, v23
	v_sub_f32_e32 v22, v22, v24
	v_exp_f32_e32 v18, v18
	v_cndmask_b32_e64 v24, 0, 32, vcc
	v_ldexp_f32 v23, v23, v24
	v_log_f32_e32 v23, v23
	v_add_f32_e32 v18, 1.0, v18
	v_add_f32_e32 v19, v19, v67
	v_mul_f32_e32 v19, 0xbfb8aa3b, v19
	v_mul_f32_e32 v24, 0x3f317217, v23
	v_fma_f32 v24, v23, s65, -v24
	v_fmac_f32_e32 v24, 0x3377d1cf, v23
	v_fmac_f32_e32 v24, 0x3f317217, v23
	v_cmp_lt_f32_e64 s[0:1], |v23|, s66
	v_exp_f32_e32 v19, v19
	v_sub_f32_e32 v20, -0.5, v20
	v_cndmask_b32_e64 v23, v23, v24, s[0:1]
	v_cndmask_b32_e32 v24, 0, v179, vcc
	v_cmp_gt_f32_e32 vcc, s64, v16
	v_sub_f32_e32 v23, v23, v24
	v_sub_f32_e32 v21, -0.5, v21
	v_cndmask_b32_e64 v24, 0, 32, vcc
	v_ldexp_f32 v16, v16, v24
	v_log_f32_e32 v16, v16
	v_sub_f32_e32 v22, -0.5, v22
	v_sub_f32_e32 v23, -0.5, v23
	v_mul_f32_e32 v20, 0x3fb8aa3b, v20
;     template <int MODE> __device__ __forceinline__ void run(AccRef acc, const Unit& u, int wr, int wc, int fr, int fq) const {
;     ...
;                     for (int e = 0; e < 4; ++e) { x[e] = acc[ai][bj][m][0][e] + bias[e]; x[4 + e] = acc[ai][bj][m][1][e] + bias[4 + e]; }
;                     u32x4 w;
;                     if (MODE == 0) {
; #pragma unroll
;                         for (int e = 0; e < 8; ++e) { const float sp = __logf(1.f + __expf(-x[e])); x[e] = __expf(-__expf(-sp - 0.5f)); }
;                         w.x = pkh(x[0], x[1]); w.y = pkh(x[2], x[3]); w.z = pkh(x[4], x[5]); w.w = pkh(x[6], x[7]);
;                         *(u32x4*)(WA + (size_t)row * 2048 + seg * 512 + cc) = w;
	v_mul_f32_e32 v24, 0x3f317217, v16
	v_fma_f32 v24, v16, s65, -v24
	v_fmac_f32_e32 v24, 0x3377d1cf, v16
	v_fmac_f32_e32 v24, 0x3f317217, v16
	v_cmp_lt_f32_e64 s[0:1], |v16|, s66
	v_mul_f32_e32 v21, 0x3fb8aa3b, v21
	v_mul_f32_e32 v22, 0x3fb8aa3b, v22
	v_cndmask_b32_e64 v16, v16, v24, s[0:1]
	v_cndmask_b32_e32 v24, 0, v179, vcc
	v_cmp_gt_f32_e32 vcc, s64, v17
	v_sub_f32_e32 v16, v16, v24
	v_sub_f32_e32 v16, -0.5, v16
	v_cndmask_b32_e64 v24, 0, 32, vcc
	v_ldexp_f32 v17, v17, v24
	v_log_f32_e32 v17, v17
	v_mul_f32_e32 v16, 0x3fb8aa3b, v16
	v_exp_f32_e32 v16, v16
	v_mul_f32_e32 v23, 0x3fb8aa3b, v23
	v_mul_f32_e32 v24, 0x3f317217, v17
	v_fma_f32 v24, v17, s65, -v24
	v_fmac_f32_e32 v24, 0x3377d1cf, v17
	v_fmac_f32_e32 v24, 0x3f317217, v17
	v_cmp_lt_f32_e64 s[0:1], |v17|, s66
	v_mul_f32_e32 v16, 0xbfb8aa3b, v16
	v_exp_f32_e32 v20, v20
	v_cndmask_b32_e64 v17, v17, v24, s[0:1]
	v_cndmask_b32_e32 v24, 0, v179, vcc
	v_sub_f32_e32 v17, v17, v24
	v_cmp_gt_f32_e32 vcc, s64, v18
	v_sub_f32_e32 v17, -0.5, v17
	v_mul_f32_e32 v17, 0x3fb8aa3b, v17
	v_cndmask_b32_e64 v24, 0, 32, vcc
	v_ldexp_f32 v18, v18, v24
	v_exp_f32_e32 v17, v17
	v_log_f32_e32 v18, v18
	v_exp_f32_e32 v24, v16
	v_exp_f32_e32 v21, v21
	v_mul_f32_e32 v16, 0xbfb8aa3b, v17
	v_mul_f32_e32 v17, 0x3f317217, v18
	v_fma_f32 v17, v18, s65, -v17
	v_fmac_f32_e32 v17, 0x3377d1cf, v18
	v_fmac_f32_e32 v17, 0x3f317217, v18
	v_cmp_lt_f32_e64 s[0:1], |v18|, s66
	v_exp_f32_e32 v22, v22
	v_exp_f32_e32 v23, v23
	v_cndmask_b32_e64 v17, v18, v17, s[0:1]
	v_cndmask_b32_e32 v18, 0, v179, vcc
	v_sub_f32_e32 v17, v17, v18
	v_add_f32_e32 v18, 1.0, v19
	v_cmp_gt_f32_e32 vcc, s64, v18
	v_sub_f32_e32 v17, -0.5, v17
	v_mul_f32_e32 v17, 0x3fb8aa3b, v17
	v_cndmask_b32_e64 v19, 0, 32, vcc
	v_ldexp_f32 v18, v18, v19
	v_log_f32_e32 v18, v18
	v_exp_f32_e32 v17, v17
	v_mul_f32_e32 v20, 0xbfb8aa3b, v20
	v_mul_f32_e32 v21, 0xbfb8aa3b, v21
	v_mul_f32_e32 v19, 0x3f317217, v18
	v_fma_f32 v19, v18, s65, -v19
	v_fmac_f32_e32 v19, 0x3377d1cf, v18
	v_fmac_f32_e32 v19, 0x3f317217, v18
	v_cmp_lt_f32_e64 s[0:1], |v18|, s66
	v_mul_f32_e32 v22, 0xbfb8aa3b, v22
	v_mul_f32_e32 v23, 0xbfb8aa3b, v23
	v_cndmask_b32_e64 v18, v18, v19, s[0:1]
	v_cndmask_b32_e32 v19, 0, v179, vcc
	v_sub_f32_e32 v18, v18, v19
	v_sub_f32_e32 v18, -0.5, v18
	v_mul_f32_e32 v18, 0x3fb8aa3b, v18
	v_exp_f32_e32 v18, v18
	v_exp_f32_e32 v19, v16
	v_mul_f32_e32 v16, 0xbfb8aa3b, v17
	v_exp_f32_e32 v25, v16
	v_mul_f32_e32 v16, 0xbfb8aa3b, v18
	v_exp_f32_e32 v20, v20
	v_exp_f32_e32 v21, v21
	v_exp_f32_e32 v22, v22
	v_exp_f32_e32 v23, v23
	v_exp_f32_e32 v26, v16
	v_cvt_pk_f16_f32 v16, v20, v21
	v_cvt_pk_f16_f32 v17, v22, v23
	v_cvt_pk_f16_f32 v18, v24, v19
	v_cvt_pk_f16_f32 v19, v25, v26
	global_store_dwordx4 v[80:81], v[16:19], off offset:256 sc1
	v_add_f32_e32 v12, v12, v68
	v_mul_f32_e32 v12, 0xbfb8aa3b, v12
	v_exp_f32_e32 v12, v12
	v_add_f32_e32 v13, v13, v69
	v_mul_f32_e32 v13, 0xbfb8aa3b, v13
	v_exp_f32_e32 v13, v13
	v_add_f32_e32 v12, 1.0, v12
	v_cmp_gt_f32_e32 vcc, s64, v12
	v_add_f32_e32 v14, v14, v70
	v_add_f32_e32 v13, 1.0, v13
	v_cndmask_b32_e64 v16, 0, 32, vcc
	v_ldexp_f32 v12, v12, v16
	v_log_f32_e32 v12, v12
	v_mul_f32_e32 v14, 0xbfb8aa3b, v14
	v_exp_f32_e32 v14, v14
	v_add_f32_e32 v15, v15, v71
	v_mul_f32_e32 v16, 0x3f317217, v12
	v_fma_f32 v16, v12, s65, -v16
	v_fmac_f32_e32 v16, 0x3377d1cf, v12
	v_fmac_f32_e32 v16, 0x3f317217, v12
	v_cmp_lt_f32_e64 s[0:1], |v12|, s66
	v_add_f32_e32 v14, 1.0, v14
	v_mul_f32_e32 v15, 0xbfb8aa3b, v15
	v_cndmask_b32_e64 v12, v12, v16, s[0:1]
	v_cndmask_b32_e32 v16, 0, v179, vcc
	v_cmp_gt_f32_e32 vcc, s64, v13
	v_sub_f32_e32 v12, v12, v16
	v_exp_f32_e32 v15, v15
	v_cndmask_b32_e64 v16, 0, 32, vcc
	v_ldexp_f32 v13, v13, v16
	v_log_f32_e32 v13, v13
	v_add_f32_e32 v15, 1.0, v15
	v_add_f32_e32 v8, v8, v64
	v_mul_f32_e32 v8, 0xbfb8aa3b, v8
	v_mul_f32_e32 v16, 0x3f317217, v13
	v_fma_f32 v16, v13, s65, -v16
	v_fmac_f32_e32 v16, 0x3377d1cf, v13
	v_fmac_f32_e32 v16, 0x3f317217, v13
	v_cmp_lt_f32_e64 s[0:1], |v13|, s66
	v_exp_f32_e32 v8, v8
	v_add_f32_e32 v9, v9, v65
	v_cndmask_b32_e64 v13, v13, v16, s[0:1]
	v_cndmask_b32_e32 v16, 0, v179, vcc
	v_cmp_gt_f32_e32 vcc, s64, v14
	v_sub_f32_e32 v13, v13, v16
	v_add_f32_e32 v8, 1.0, v8
	v_cndmask_b32_e64 v16, 0, 32, vcc
	v_ldexp_f32 v14, v14, v16
	v_log_f32_e32 v14, v14
	v_mul_f32_e32 v9, 0xbfb8aa3b, v9
	v_exp_f32_e32 v9, v9
	v_add_f32_e32 v10, v10, v66
	v_mul_f32_e32 v16, 0x3f317217, v14
	v_fma_f32 v16, v14, s65, -v16
	v_fmac_f32_e32 v16, 0x3377d1cf, v14
	v_fmac_f32_e32 v16, 0x3f317217, v14
	v_cmp_lt_f32_e64 s[0:1], |v14|, s66
	v_add_f32_e32 v9, 1.0, v9
	v_mul_f32_e32 v10, 0xbfb8aa3b, v10
	v_cndmask_b32_e64 v14, v14, v16, s[0:1]
	v_cndmask_b32_e32 v16, 0, v179, vcc
	v_cmp_gt_f32_e32 vcc, s64, v15
	v_sub_f32_e32 v14, v14, v16
	v_exp_f32_e32 v10, v10
	v_cndmask_b32_e64 v16, 0, 32, vcc
	v_ldexp_f32 v15, v15, v16
	v_log_f32_e32 v15, v15
	v_add_f32_e32 v10, 1.0, v10
	v_add_f32_e32 v11, v11, v67
	v_mul_f32_e32 v11, 0xbfb8aa3b, v11
	v_mul_f32_e32 v16, 0x3f317217, v15
	v_fma_f32 v16, v15, s65, -v16
	v_fmac_f32_e32 v16, 0x3377d1cf, v15
	v_fmac_f32_e32 v16, 0x3f317217, v15
	v_cmp_lt_f32_e64 s[0:1], |v15|, s66
	v_exp_f32_e32 v11, v11
	v_sub_f32_e32 v12, -0.5, v12
	v_cndmask_b32_e64 v15, v15, v16, s[0:1]
	v_cndmask_b32_e32 v16, 0, v179, vcc
	v_cmp_gt_f32_e32 vcc, s64, v8
	v_sub_f32_e32 v15, v15, v16
	v_sub_f32_e32 v13, -0.5, v13
	v_cndmask_b32_e64 v16, 0, 32, vcc
	v_ldexp_f32 v8, v8, v16
	v_log_f32_e32 v8, v8
	v_sub_f32_e32 v14, -0.5, v14
	v_sub_f32_e32 v15, -0.5, v15
	v_mul_f32_e32 v12, 0x3fb8aa3b, v12
	v_mul_f32_e32 v16, 0x3f317217, v8
	v_fma_f32 v16, v8, s65, -v16
	v_fmac_f32_e32 v16, 0x3377d1cf, v8
;     template <int MODE> __device__ __forceinline__ void run(AccRef acc, const Unit& u, int wr, int wc, int fr, int fq) const {
;     ...
;                     for (int e = 0; e < 4; ++e) { x[e] = acc[ai][bj][m][0][e] + bias[e]; x[4 + e] = acc[ai][bj][m][1][e] + bias[4 + e]; }
;                     u32x4 w;
;                     if (MODE == 0) {
; #pragma unroll
;                         for (int e = 0; e < 8; ++e) { const float sp = __logf(1.f + __expf(-x[e])); x[e] = __expf(-__expf(-sp - 0.5f)); }
;                         w.x = pkh(x[0], x[1]); w.y = pkh(x[2], x[3]); w.z = pkh(x[4], x[5]); w.w = pkh(x[6], x[7]);
;                         *(u32x4*)(WA + (size_t)row * 2048 + seg * 512 + cc) = w;
	v_fmac_f32_e32 v16, 0x3f317217, v8
	v_cmp_lt_f32_e64 s[0:1], |v8|, s66
	v_mul_f32_e32 v13, 0x3fb8aa3b, v13
	v_mul_f32_e32 v14, 0x3fb8aa3b, v14
	v_cndmask_b32_e64 v8, v8, v16, s[0:1]
	v_cndmask_b32_e32 v16, 0, v179, vcc
	v_cmp_gt_f32_e32 vcc, s64, v9
	v_sub_f32_e32 v8, v8, v16
	v_sub_f32_e32 v8, -0.5, v8
	v_cndmask_b32_e64 v16, 0, 32, vcc
	v_ldexp_f32 v9, v9, v16
	v_log_f32_e32 v9, v9
	v_mul_f32_e32 v8, 0x3fb8aa3b, v8
	v_exp_f32_e32 v8, v8
	v_mul_f32_e32 v15, 0x3fb8aa3b, v15
	v_mul_f32_e32 v16, 0x3f317217, v9
	v_fma_f32 v16, v9, s65, -v16
	v_fmac_f32_e32 v16, 0x3377d1cf, v9
	v_fmac_f32_e32 v16, 0x3f317217, v9
	v_cmp_lt_f32_e64 s[0:1], |v9|, s66
	v_mul_f32_e32 v8, 0xbfb8aa3b, v8
	v_exp_f32_e32 v12, v12
	v_cndmask_b32_e64 v9, v9, v16, s[0:1]
	v_cndmask_b32_e32 v16, 0, v179, vcc
	v_sub_f32_e32 v9, v9, v16
	v_cmp_gt_f32_e32 vcc, s64, v10
	v_sub_f32_e32 v9, -0.5, v9
	v_mul_f32_e32 v9, 0x3fb8aa3b, v9
	v_cndmask_b32_e64 v16, 0, 32, vcc
	v_ldexp_f32 v10, v10, v16
	v_exp_f32_e32 v9, v9
	v_log_f32_e32 v10, v10
	v_exp_f32_e32 v16, v8
	v_exp_f32_e32 v13, v13
	v_mul_f32_e32 v8, 0xbfb8aa3b, v9
	v_mul_f32_e32 v9, 0x3f317217, v10
	v_fma_f32 v9, v10, s65, -v9
	v_fmac_f32_e32 v9, 0x3377d1cf, v10
	v_fmac_f32_e32 v9, 0x3f317217, v10
	v_cmp_lt_f32_e64 s[0:1], |v10|, s66
	v_exp_f32_e32 v14, v14
	v_exp_f32_e32 v15, v15
	v_cndmask_b32_e64 v9, v10, v9, s[0:1]
	v_cndmask_b32_e32 v10, 0, v179, vcc
	v_sub_f32_e32 v9, v9, v10
	v_add_f32_e32 v10, 1.0, v11
	v_cmp_gt_f32_e32 vcc, s64, v10
	v_sub_f32_e32 v9, -0.5, v9
	v_mul_f32_e32 v9, 0x3fb8aa3b, v9
	v_cndmask_b32_e64 v11, 0, 32, vcc
	v_ldexp_f32 v10, v10, v11
	v_log_f32_e32 v10, v10
	v_exp_f32_e32 v9, v9
	v_mul_f32_e32 v12, 0xbfb8aa3b, v12
	v_mul_f32_e32 v13, 0xbfb8aa3b, v13
	v_mul_f32_e32 v11, 0x3f317217, v10
	v_fma_f32 v11, v10, s65, -v11
	v_fmac_f32_e32 v11, 0x3377d1cf, v10
	v_fmac_f32_e32 v11, 0x3f317217, v10
	v_cmp_lt_f32_e64 s[0:1], |v10|, s66
	v_mul_f32_e32 v14, 0xbfb8aa3b, v14
	v_mul_f32_e32 v15, 0xbfb8aa3b, v15
	v_cndmask_b32_e64 v10, v10, v11, s[0:1]
	v_cndmask_b32_e32 v11, 0, v179, vcc
	v_sub_f32_e32 v10, v10, v11
	v_sub_f32_e32 v10, -0.5, v10
	v_mul_f32_e32 v10, 0x3fb8aa3b, v10
	v_exp_f32_e32 v10, v10
	v_exp_f32_e32 v11, v8
	v_mul_f32_e32 v8, 0xbfb8aa3b, v9
	v_exp_f32_e32 v17, v8
	v_mul_f32_e32 v8, 0xbfb8aa3b, v10
	v_exp_f32_e32 v12, v12
	v_exp_f32_e32 v13, v13
	v_exp_f32_e32 v14, v14
	v_exp_f32_e32 v15, v15
	v_exp_f32_e32 v18, v8
	v_cvt_pk_f16_f32 v8, v12, v13
	v_cvt_pk_f16_f32 v9, v14, v15
	v_cvt_pk_f16_f32 v10, v16, v11
	v_cvt_pk_f16_f32 v11, v17, v18
	global_store_dwordx4 v[72:73], v[8:11], off offset:256 sc1
	v_add_f32_e32 v4, v4, v68
	v_mul_f32_e32 v4, 0xbfb8aa3b, v4
	v_exp_f32_e32 v4, v4
	v_add_f32_e32 v5, v5, v69
	v_mul_f32_e32 v5, 0xbfb8aa3b, v5
	v_exp_f32_e32 v5, v5
	v_add_f32_e32 v4, 1.0, v4
	v_cmp_gt_f32_e32 vcc, s64, v4
	v_add_f32_e32 v6, v6, v70
	v_add_f32_e32 v5, 1.0, v5
	v_cndmask_b32_e64 v8, 0, 32, vcc
	v_ldexp_f32 v4, v4, v8
	v_log_f32_e32 v4, v4
	v_mul_f32_e32 v6, 0xbfb8aa3b, v6
	v_exp_f32_e32 v6, v6
	v_add_f32_e32 v7, v7, v71
	v_mul_f32_e32 v8, 0x3f317217, v4
	v_fma_f32 v8, v4, s65, -v8
	v_fmac_f32_e32 v8, 0x3377d1cf, v4
	v_fmac_f32_e32 v8, 0x3f317217, v4
	v_cmp_lt_f32_e64 s[0:1], |v4|, s66
	v_add_f32_e32 v6, 1.0, v6
	v_mul_f32_e32 v7, 0xbfb8aa3b, v7
	v_cndmask_b32_e64 v4, v4, v8, s[0:1]
	v_cndmask_b32_e32 v8, 0, v179, vcc
	v_cmp_gt_f32_e32 vcc, s64, v5
	v_sub_f32_e32 v4, v4, v8
	v_exp_f32_e32 v7, v7
	v_cndmask_b32_e64 v8, 0, 32, vcc
	v_ldexp_f32 v5, v5, v8
	v_log_f32_e32 v5, v5
	v_add_f32_e32 v7, 1.0, v7
	v_add_f32_e32 v0, v0, v64
	v_mul_f32_e32 v0, 0xbfb8aa3b, v0
	v_mul_f32_e32 v8, 0x3f317217, v5
	v_fma_f32 v8, v5, s65, -v8
	v_fmac_f32_e32 v8, 0x3377d1cf, v5
	v_fmac_f32_e32 v8, 0x3f317217, v5
	v_cmp_lt_f32_e64 s[0:1], |v5|, s66
	v_exp_f32_e32 v0, v0
	v_add_f32_e32 v1, v1, v65
	v_cndmask_b32_e64 v5, v5, v8, s[0:1]
	v_cndmask_b32_e32 v8, 0, v179, vcc
	v_cmp_gt_f32_e32 vcc, s64, v6
	v_sub_f32_e32 v5, v5, v8
; template <class Epi, class Sched, bool ALIGN_EPI = false, bool SP2 = false>
; __device__ __forceinline__ void gemm_phase(PG8_LAS unsigned char* lds, const Gemm g, const Sched& S, const Epi& E) {
;     ...
;         if (!has_next) break;
;     template <int MODE> __device__ __forceinline__ void run(AccRef acc, const Unit& u, int wr, int wc, int fr, int fq) const {
;     ...
;                     for (int e = 0; e < 4; ++e) { x[e] = acc[ai][bj][m][0][e] + bias[e]; x[4 + e] = acc[ai][bj][m][1][e] + bias[4 + e]; }
;                     u32x4 w;
;                     if (MODE == 0) {
; #pragma unroll
;                         for (int e = 0; e < 8; ++e) { const float sp = __logf(1.f + __expf(-x[e])); x[e] = __expf(-__expf(-sp - 0.5f)); }
;                         w.x = pkh(x[0], x[1]); w.y = pkh(x[2], x[3]); w.z = pkh(x[4], x[5]); w.w = pkh(x[6], x[7]);
;                         *(u32x4*)(WA + (size_t)row * 2048 + seg * 512 + cc) = w;
	v_add_f32_e32 v0, 1.0, v0
	v_cndmask_b32_e64 v8, 0, 32, vcc
	v_ldexp_f32 v6, v6, v8
	v_log_f32_e32 v6, v6
	v_mul_f32_e32 v1, 0xbfb8aa3b, v1
	v_exp_f32_e32 v1, v1
	v_add_f32_e32 v2, v2, v66
	v_mul_f32_e32 v8, 0x3f317217, v6
	v_fma_f32 v8, v6, s65, -v8
	v_fmac_f32_e32 v8, 0x3377d1cf, v6
	v_fmac_f32_e32 v8, 0x3f317217, v6
	v_cmp_lt_f32_e64 s[0:1], |v6|, s66
	v_add_f32_e32 v1, 1.0, v1
	v_mul_f32_e32 v2, 0xbfb8aa3b, v2
	v_cndmask_b32_e64 v6, v6, v8, s[0:1]
	v_cndmask_b32_e32 v8, 0, v179, vcc
	v_cmp_gt_f32_e32 vcc, s64, v7
	v_sub_f32_e32 v6, v6, v8
	v_exp_f32_e32 v2, v2
	v_cndmask_b32_e64 v8, 0, 32, vcc
	v_ldexp_f32 v7, v7, v8
	v_log_f32_e32 v7, v7
	v_add_f32_e32 v2, 1.0, v2
	v_add_f32_e32 v3, v3, v67
	v_mul_f32_e32 v3, 0xbfb8aa3b, v3
	v_mul_f32_e32 v8, 0x3f317217, v7
	v_fma_f32 v8, v7, s65, -v8
	v_fmac_f32_e32 v8, 0x3377d1cf, v7
	v_fmac_f32_e32 v8, 0x3f317217, v7
	v_cmp_lt_f32_e64 s[0:1], |v7|, s66
	v_exp_f32_e32 v3, v3
	v_sub_f32_e32 v4, -0.5, v4
	v_cndmask_b32_e64 v7, v7, v8, s[0:1]
	v_cndmask_b32_e32 v8, 0, v179, vcc
	v_cmp_gt_f32_e32 vcc, s64, v0
	v_sub_f32_e32 v7, v7, v8
	v_sub_f32_e32 v5, -0.5, v5
	v_cndmask_b32_e64 v8, 0, 32, vcc
	v_ldexp_f32 v0, v0, v8
	v_log_f32_e32 v0, v0
	v_sub_f32_e32 v6, -0.5, v6
	v_sub_f32_e32 v7, -0.5, v7
	v_mul_f32_e32 v4, 0x3fb8aa3b, v4
	v_mul_f32_e32 v8, 0x3f317217, v0
	v_fma_f32 v8, v0, s65, -v8
	v_fmac_f32_e32 v8, 0x3377d1cf, v0
	v_fmac_f32_e32 v8, 0x3f317217, v0
	v_cmp_lt_f32_e64 s[0:1], |v0|, s66
	v_mul_f32_e32 v5, 0x3fb8aa3b, v5
	v_mul_f32_e32 v6, 0x3fb8aa3b, v6
	v_cndmask_b32_e64 v0, v0, v8, s[0:1]
	v_cndmask_b32_e32 v8, 0, v179, vcc
	v_cmp_gt_f32_e32 vcc, s64, v1
	v_sub_f32_e32 v0, v0, v8
	v_sub_f32_e32 v0, -0.5, v0
	v_cndmask_b32_e64 v8, 0, 32, vcc
	v_ldexp_f32 v1, v1, v8
	v_log_f32_e32 v1, v1
	v_mul_f32_e32 v0, 0x3fb8aa3b, v0
	v_exp_f32_e32 v0, v0
	v_mul_f32_e32 v7, 0x3fb8aa3b, v7
	v_mul_f32_e32 v8, 0x3f317217, v1
	v_fma_f32 v8, v1, s65, -v8
	v_fmac_f32_e32 v8, 0x3377d1cf, v1
	v_fmac_f32_e32 v8, 0x3f317217, v1
	v_cmp_lt_f32_e64 s[0:1], |v1|, s66
	v_mul_f32_e32 v0, 0xbfb8aa3b, v0
	v_exp_f32_e32 v4, v4
	v_cndmask_b32_e64 v1, v1, v8, s[0:1]
	v_cndmask_b32_e32 v8, 0, v179, vcc
	v_sub_f32_e32 v1, v1, v8
	v_cmp_gt_f32_e32 vcc, s64, v2
	v_sub_f32_e32 v1, -0.5, v1
	v_mul_f32_e32 v1, 0x3fb8aa3b, v1
	v_cndmask_b32_e64 v8, 0, 32, vcc
	v_ldexp_f32 v2, v2, v8
	v_exp_f32_e32 v1, v1
	v_log_f32_e32 v2, v2
	v_exp_f32_e32 v8, v0
	v_exp_f32_e32 v5, v5
	v_mul_f32_e32 v0, 0xbfb8aa3b, v1
	v_mul_f32_e32 v1, 0x3f317217, v2
	v_fma_f32 v1, v2, s65, -v1
	v_fmac_f32_e32 v1, 0x3377d1cf, v2
	v_fmac_f32_e32 v1, 0x3f317217, v2
	v_cmp_lt_f32_e64 s[0:1], |v2|, s66
	v_exp_f32_e32 v6, v6
	v_exp_f32_e32 v7, v7
	v_cndmask_b32_e64 v1, v2, v1, s[0:1]
	v_cndmask_b32_e32 v2, 0, v179, vcc
	v_sub_f32_e32 v1, v1, v2
	v_add_f32_e32 v2, 1.0, v3
	v_cmp_gt_f32_e32 vcc, s64, v2
	v_sub_f32_e32 v1, -0.5, v1
	v_mul_f32_e32 v1, 0x3fb8aa3b, v1
	v_cndmask_b32_e64 v3, 0, 32, vcc
	v_ldexp_f32 v2, v2, v3
	v_log_f32_e32 v2, v2
	v_exp_f32_e32 v1, v1
	v_mul_f32_e32 v4, 0xbfb8aa3b, v4
	v_mul_f32_e32 v5, 0xbfb8aa3b, v5
	v_mul_f32_e32 v3, 0x3f317217, v2
	v_fma_f32 v3, v2, s65, -v3
	v_fmac_f32_e32 v3, 0x3377d1cf, v2
	v_fmac_f32_e32 v3, 0x3f317217, v2
	v_cmp_lt_f32_e64 s[0:1], |v2|, s66
	v_mul_f32_e32 v6, 0xbfb8aa3b, v6
	v_mul_f32_e32 v7, 0xbfb8aa3b, v7
	v_cndmask_b32_e64 v2, v2, v3, s[0:1]
	v_cndmask_b32_e32 v3, 0, v179, vcc
	v_sub_f32_e32 v2, v2, v3
	v_sub_f32_e32 v2, -0.5, v2
	v_mul_f32_e32 v2, 0x3fb8aa3b, v2
	v_exp_f32_e32 v2, v2
	v_exp_f32_e32 v3, v0
	v_mul_f32_e32 v0, 0xbfb8aa3b, v1
	v_exp_f32_e32 v9, v0
	v_mul_f32_e32 v0, 0xbfb8aa3b, v2
	v_exp_f32_e32 v4, v4
	v_exp_f32_e32 v5, v5
	v_exp_f32_e32 v6, v6
	v_exp_f32_e32 v7, v7
	v_exp_f32_e32 v10, v0
	v_cvt_pk_f16_f32 v0, v4, v5
	v_cvt_pk_f16_f32 v1, v6, v7
	v_cvt_pk_f16_f32 v2, v8, v3
	v_cvt_pk_f16_f32 v3, v9, v10
	global_store_dwordx4 v[74:75], v[0:3], off offset:256 sc1
	s_and_b64 vcc, exec, s[6:7]
	s_mov_b64 s[0:1], -1
	s_cbranch_vccnz .LBB0_804

; __device__ __forceinline__ unsigned pkbf(float lo, float hi) { return pg8::cvt_pk_bf16(lo, hi); }
; __device__ __forceinline__ float fsigmoid(float x) { return __builtin_amdgcn_rcpf(1.f + __builtin_amdgcn_exp2f(-1.4426950408889634f * x)); }
;     template <int MODE> __device__ __forceinline__ void run(AccRef acc, const Unit& u, int wr, int wc, int fr, int fq) const {
;     ...
; #pragma unroll
;             for (int ai = 0; ai < 2; ++ai)
; #pragma unroll
;                 for (int m = 0; m < 4; ++m) {
;                     const int row = row0 + ai * 128 + m * 16;
;                     float x[8];
; #pragma unroll
;                     for (int e = 0; e < 4; ++e) { x[e] = acc[ai][bj][m][0][e] + bias[e]; x[4 + e] = acc[ai][bj][m][1][e] + bias[4 + e]; }
;                     u32x4 w;
;                     if (MODE == 0) {
; #pragma unroll
;                         for (int e = 0; e < 8; ++e) { const float sp = __logf(1.f + __expf(-x[e])); x[e] = __expf(-__expf(-sp - 0.5f)); }
;                         w.x = pkh(x[0], x[1]); w.y = pkh(x[2], x[3]); w.z = pkh(x[4], x[5]); w.w = pkh(x[6], x[7]);
;                         *(u32x4*)(WA + (size_t)row * 2048 + seg * 512 + cc) = w;
;                     } else if (MODE == 1) {
; #pragma unroll
;                         for (int e = 0; e < 8; ++e) x[e] = fsigmoid(x[e]);
;                         w.x = pkh(x[0], x[1]); w.y = pkh(x[2], x[3]); w.z = pkh(x[4], x[5]); w.w = pkh(x[6], x[7]);
;                         *(u32x4*)(WA + (size_t)row * 2048 + seg * 512 + cc) = w;
;                     } else {
;                         w.x = pkbf(x[0], x[1]); w.y = pkbf(x[2], x[3]); w.z = pkbf(x[4], x[5]); w.w = pkbf(x[6], x[7]);
;                         *(u32x4*)(MIX + (size_t)row * 1024 + 512 + cc) = w;
;                     }
;                     __builtin_amdgcn_sched_barrier(0); asm volatile("" ::: "memory");
.LBB0_845:
	s_ashr_i32 s0, s67, 1
	s_add_i32 s4, s0, 2
	v_mov_b32_e32 v180, v174
	v_mov_b32_e32 v181, v165
	s_cmp_gt_i32 s0, -1
	s_mov_b64 s[0:1], -1
	s_cbranch_scc0 .LBB0_852
	s_lshl_b32 s5, s65, 8
	s_cmp_gt_u32 s4, 3
	v_lshlrev_b32_e32 v128, 3, v180
	s_cbranch_scc0 .LBB0_848
	s_add_i32 s0, s5, s35
	v_add_u32_e32 v134, s0, v181
	s_lshl_b32 s0, s67, 8
	s_and_b32 s0, s0, 0x100
	v_add_f32_e32 v132, 0, v124
	v_add_f32_e32 v130, 0, v121
	v_add_f32_e32 v133, 0, v125
	v_add_f32_e32 v131, 0, v122
	v_add_f32_e32 v135, 0, v126
	s_or_b32 s0, s0, s87
	v_add_f32_e32 v129, 0, v120
	v_add_f32_e32 v138, 0, v123
	v_add_f32_e32 v139, 0, v127
	v_cvt_pk_bf16_f32 v130, v129, v130
	v_cvt_pk_bf16_f32 v131, v131, v138
	v_cvt_pk_bf16_f32 v132, v132, v133
	v_cvt_pk_bf16_f32 v133, v135, v139
	v_ashrrev_i32_e32 v135, 31, v134
	v_add_u32_e32 v136, s0, v128
	v_lshlrev_b64 v[134:135], 11, v[134:135]
	v_ashrrev_i32_e32 v137, 31, v136
	v_lshl_add_u64 v[134:135], s[76:77], 0, v[134:135]
	v_lshl_add_u64 v[134:135], v[136:137], 1, v[134:135]
	global_store_dwordx4 v[134:135], v[130:133], off offset:1024 sc1
	s_nop 1
	v_add_f32_e32 v132, 0, v112
	v_add_f32_e32 v130, 0, v117
	v_add_f32_e32 v133, 0, v113
	v_add_f32_e32 v131, 0, v118
	v_add_f32_e32 v136, 0, v114
	v_add_f32_e32 v137, 0, v119
	s_mov_b64 s[0:1], 0x8000
	v_add_f32_e32 v129, 0, v116
	v_add_f32_e32 v138, 0, v115
	v_cvt_pk_bf16_f32 v130, v129, v130
	v_cvt_pk_bf16_f32 v131, v131, v137
	v_cvt_pk_bf16_f32 v132, v132, v133
	v_cvt_pk_bf16_f32 v133, v136, v138
	v_lshl_add_u64 v[136:137], v[134:135], 0, s[0:1]
	global_store_dwordx4 v[136:137], v[130:133], off offset:1024 sc1
	s_nop 1
	v_add_f32_e32 v132, 0, v104
	v_add_f32_e32 v130, 0, v109
	v_add_f32_e32 v133, 0, v105
	v_add_f32_e32 v131, 0, v110
	v_add_f32_e32 v138, 0, v106
	v_add_f32_e32 v139, 0, v111
	v_add_f32_e32 v129, 0, v108
	v_add_f32_e32 v156, 0, v107
	v_cvt_pk_bf16_f32 v130, v129, v130
	v_cvt_pk_bf16_f32 v131, v131, v139
	v_cvt_pk_bf16_f32 v132, v132, v133
	v_cvt_pk_bf16_f32 v133, v138, v156
	v_lshl_add_u64 v[138:139], v[134:135], 0, s[58:59]
	global_store_dwordx4 v[138:139], v[130:133], off offset:1024 sc1
	s_nop 1
	v_add_f32_e32 v132, 0, v96
	v_add_f32_e32 v130, 0, v101
	v_add_f32_e32 v133, 0, v97
	v_add_f32_e32 v131, 0, v102
	v_add_f32_e32 v156, 0, v98
	v_add_f32_e32 v157, 0, v103
	s_mov_b64 s[0:1], 0x18000
	v_add_f32_e32 v129, 0, v100
	v_add_f32_e32 v158, 0, v99
	v_cvt_pk_bf16_f32 v130, v129, v130
	v_cvt_pk_bf16_f32 v131, v131, v157
	v_cvt_pk_bf16_f32 v132, v132, v133
	v_cvt_pk_bf16_f32 v133, v156, v158
	v_lshl_add_u64 v[156:157], v[134:135], 0, s[0:1]
	global_store_dwordx4 v[156:157], v[130:133], off offset:1024 sc1
	s_nop 1
	v_add_f32_e32 v132, 0, v88
	v_add_f32_e32 v130, 0, v93
	v_add_f32_e32 v133, 0, v89
	v_add_f32_e32 v131, 0, v94
	v_add_f32_e32 v158, 0, v90
	v_add_f32_e32 v159, 0, v95
	s_mov_b64 s[0:1], 0x40000
	v_add_f32_e32 v129, 0, v92
	v_add_f32_e32 v160, 0, v91
	v_cvt_pk_bf16_f32 v130, v129, v130
	v_cvt_pk_bf16_f32 v131, v131, v159
	v_cvt_pk_bf16_f32 v132, v132, v133
	v_cvt_pk_bf16_f32 v133, v158, v160
	v_lshl_add_u64 v[158:159], v[134:135], 0, s[0:1]
	global_store_dwordx4 v[158:159], v[130:133], off offset:1024 sc1
	s_nop 1
	v_add_f32_e32 v132, 0, v80
	v_add_f32_e32 v130, 0, v85
	v_add_f32_e32 v133, 0, v81
	v_add_f32_e32 v131, 0, v86
	v_add_f32_e32 v160, 0, v82
	v_add_f32_e32 v161, 0, v87
	s_mov_b64 s[0:1], 0x48000
	v_add_f32_e32 v129, 0, v84
	v_add_f32_e32 v162, 0, v83
	v_cvt_pk_bf16_f32 v130, v129, v130
	v_cvt_pk_bf16_f32 v131, v131, v161
	v_cvt_pk_bf16_f32 v132, v132, v133
	v_cvt_pk_bf16_f32 v133, v160, v162
	v_lshl_add_u64 v[160:161], v[134:135], 0, s[0:1]
	global_store_dwordx4 v[160:161], v[130:133], off offset:1024 sc1
	s_nop 1
	v_add_f32_e32 v132, 0, v72
	v_add_f32_e32 v130, 0, v77
	v_add_f32_e32 v133, 0, v73
	v_add_f32_e32 v131, 0, v78
	v_add_f32_e32 v162, 0, v74
	v_add_f32_e32 v163, 0, v79
	s_mov_b64 s[0:1], 0x50000
	v_add_f32_e32 v129, 0, v76
	v_add_f32_e32 v168, 0, v75
	v_cvt_pk_bf16_f32 v130, v129, v130
	v_cvt_pk_bf16_f32 v131, v131, v163
	v_cvt_pk_bf16_f32 v132, v132, v133
	v_cvt_pk_bf16_f32 v133, v162, v168
	v_lshl_add_u64 v[162:163], v[134:135], 0, s[0:1]
	global_store_dwordx4 v[162:163], v[130:133], off offset:1024 sc1
	s_nop 1
	v_add_f32_e32 v132, 0, v64
	v_add_f32_e32 v130, 0, v69
	v_add_f32_e32 v133, 0, v65
	v_add_f32_e32 v131, 0, v70
	v_add_f32_e32 v168, 0, v66
	v_add_f32_e32 v169, 0, v71
	s_mov_b64 s[0:1], 0x58000
	v_add_f32_e32 v129, 0, v68
	v_add_f32_e32 v170, 0, v67
	v_cvt_pk_bf16_f32 v130, v129, v130
	v_cvt_pk_bf16_f32 v131, v131, v169
	v_cvt_pk_bf16_f32 v132, v132, v133
	v_cvt_pk_bf16_f32 v133, v168, v170
	v_lshl_add_u64 v[168:169], v[134:135], 0, s[0:1]
	global_store_dwordx4 v[168:169], v[130:133], off offset:1024 sc1
	s_nop 1
	v_add_f32_e32 v132, 0, v56
	v_add_f32_e32 v130, 0, v61
	v_add_f32_e32 v133, 0, v57
	v_add_f32_e32 v131, 0, v62
	v_add_f32_e32 v129, 0, v60
	v_add_f32_e32 v170, 0, v58
	v_add_f32_e32 v171, 0, v63
	v_add_f32_e32 v172, 0, v59
	v_cvt_pk_bf16_f32 v130, v129, v130
	v_cvt_pk_bf16_f32 v131, v131, v171
	v_cvt_pk_bf16_f32 v132, v132, v133
	v_cvt_pk_bf16_f32 v133, v170, v172
	global_store_dwordx4 v[134:135], v[130:133], off offset:1280 sc1
	s_nop 1
	v_add_f32_e32 v132, 0, v48
	v_add_f32_e32 v130, 0, v53
	v_add_f32_e32 v133, 0, v49
	v_add_f32_e32 v131, 0, v54
	v_add_f32_e32 v129, 0, v52
	v_add_f32_e32 v134, 0, v50
	v_add_f32_e32 v135, 0, v55
	v_add_f32_e32 v170, 0, v51
	v_cvt_pk_bf16_f32 v130, v129, v130
	v_cvt_pk_bf16_f32 v131, v131, v135
	v_cvt_pk_bf16_f32 v132, v132, v133
	v_cvt_pk_bf16_f32 v133, v134, v170
	global_store_dwordx4 v[136:137], v[130:133], off offset:1280 sc1
	s_nop 1
	v_add_f32_e32 v132, 0, v40
; __device__ __forceinline__ unsigned pkbf(float lo, float hi) { return pg8::cvt_pk_bf16(lo, hi); }
; __device__ __forceinline__ float fsigmoid(float x) { return __builtin_amdgcn_rcpf(1.f + __builtin_amdgcn_exp2f(-1.4426950408889634f * x)); }
;     template <int MODE> __device__ __forceinline__ void run(AccRef acc, const Unit& u, int wr, int wc, int fr, int fq) const {
;     ...
;                     } else if (MODE == 1) {
; #pragma unroll
;                         for (int e = 0; e < 8; ++e) x[e] = fsigmoid(x[e]);
;                         w.x = pkh(x[0], x[1]); w.y = pkh(x[2], x[3]); w.z = pkh(x[4], x[5]); w.w = pkh(x[6], x[7]);
;                         *(u32x4*)(WA + (size_t)row * 2048 + seg * 512 + cc) = w;
;                     } else {
;                         w.x = pkbf(x[0], x[1]); w.y = pkbf(x[2], x[3]); w.z = pkbf(x[4], x[5]); w.w = pkbf(x[6], x[7]);
;                         *(u32x4*)(MIX + (size_t)row * 1024 + 512 + cc) = w;
	v_add_f32_e32 v130, 0, v45
	v_add_f32_e32 v133, 0, v41
	v_add_f32_e32 v131, 0, v46
	v_add_f32_e32 v129, 0, v44
	v_add_f32_e32 v134, 0, v42
	v_add_f32_e32 v135, 0, v47
	v_add_f32_e32 v136, 0, v43
	v_cvt_pk_bf16_f32 v130, v129, v130
	v_cvt_pk_bf16_f32 v131, v131, v135
	v_cvt_pk_bf16_f32 v132, v132, v133
	v_cvt_pk_bf16_f32 v133, v134, v136
	global_store_dwordx4 v[138:139], v[130:133], off offset:1280 sc1
	s_nop 1
	v_add_f32_e32 v132, 0, v32
	v_add_f32_e32 v130, 0, v37
	v_add_f32_e32 v133, 0, v33
	v_add_f32_e32 v131, 0, v38
	v_add_f32_e32 v129, 0, v36
	v_add_f32_e32 v134, 0, v34
	v_add_f32_e32 v135, 0, v39
	v_add_f32_e32 v136, 0, v35
	v_cvt_pk_bf16_f32 v130, v129, v130
	v_cvt_pk_bf16_f32 v131, v131, v135
	v_cvt_pk_bf16_f32 v132, v132, v133
	v_cvt_pk_bf16_f32 v133, v134, v136
	global_store_dwordx4 v[156:157], v[130:133], off offset:1280 sc1
	s_nop 1
	v_add_f32_e32 v132, 0, v24
	v_add_f32_e32 v130, 0, v29
	v_add_f32_e32 v133, 0, v25
	v_add_f32_e32 v131, 0, v30
	v_add_f32_e32 v129, 0, v28
	v_add_f32_e32 v134, 0, v26
	v_add_f32_e32 v135, 0, v31
	v_add_f32_e32 v136, 0, v27
	v_cvt_pk_bf16_f32 v130, v129, v130
	v_cvt_pk_bf16_f32 v131, v131, v135
	v_cvt_pk_bf16_f32 v132, v132, v133
	v_cvt_pk_bf16_f32 v133, v134, v136
	global_store_dwordx4 v[158:159], v[130:133], off offset:1280 sc1
	s_nop 1
	v_add_f32_e32 v132, 0, v16
	v_add_f32_e32 v130, 0, v21
	v_add_f32_e32 v133, 0, v17
	v_add_f32_e32 v131, 0, v22
	v_add_f32_e32 v129, 0, v20
	v_add_f32_e32 v134, 0, v18
	v_add_f32_e32 v135, 0, v23
	v_add_f32_e32 v136, 0, v19
	v_cvt_pk_bf16_f32 v130, v129, v130
	v_cvt_pk_bf16_f32 v131, v131, v135
	v_cvt_pk_bf16_f32 v132, v132, v133
	v_cvt_pk_bf16_f32 v133, v134, v136
	global_store_dwordx4 v[160:161], v[130:133], off offset:1280 sc1
	s_nop 1
	v_add_f32_e32 v132, 0, v8
	v_add_f32_e32 v130, 0, v13
	v_add_f32_e32 v133, 0, v9
	v_add_f32_e32 v131, 0, v14
	v_add_f32_e32 v129, 0, v12
	v_add_f32_e32 v134, 0, v10
	v_add_f32_e32 v135, 0, v15
	v_add_f32_e32 v136, 0, v11
	v_cvt_pk_bf16_f32 v130, v129, v130
	v_cvt_pk_bf16_f32 v131, v131, v135
	v_cvt_pk_bf16_f32 v132, v132, v133
	v_cvt_pk_bf16_f32 v133, v134, v136
	global_store_dwordx4 v[162:163], v[130:133], off offset:1280 sc1
	s_nop 1
	v_add_f32_e32 v132, 0, v0
	v_add_f32_e32 v130, 0, v5
	v_add_f32_e32 v133, 0, v1
	v_add_f32_e32 v131, 0, v6
	v_add_f32_e32 v129, 0, v4
	v_add_f32_e32 v134, 0, v2
	v_add_f32_e32 v135, 0, v7
	v_add_f32_e32 v136, 0, v3
	v_cvt_pk_bf16_f32 v130, v129, v130
	v_cvt_pk_bf16_f32 v131, v131, v135
	v_cvt_pk_bf16_f32 v132, v132, v133
	v_cvt_pk_bf16_f32 v133, v134, v136
	global_store_dwordx4 v[168:169], v[130:133], off offset:1280 sc1
	s_mov_b64 s[0:1], 0
.LBB0_848:
	s_andn2_b64 vcc, exec, s[0:1]
	s_cbranch_vccnz .LBB0_850
	s_lshl_b32 s14, s67, 8
	s_and_b32 s0, s14, 0xfffffe00
	s_add_i32 s5, s5, s35
	s_ashr_i32 s1, s0, 31
	v_add_u32_e32 v160, s5, v181
	s_and_b32 s5, s14, 0x100
	s_or_b32 s5, s5, s87
	s_lshl_b64 s[14:15], s[0:1], 2
	v_readlane_b32 s36, v237, 37
	v_add_u32_e32 v158, s5, v128
	v_readlane_b32 s37, v237, 38
	s_add_u32 s14, s36, s14
	s_addc_u32 s15, s37, s15
	v_ashrrev_i32_e32 v159, 31, v158
	v_lshl_add_u64 v[156:157], v[158:159], 2, s[14:15]
	global_load_dwordx4 v[128:131], v[156:157], off offset:16
	global_load_dwordx4 v[132:135], v[156:157], off
	v_readlane_b32 s38, v237, 39
	v_readlane_b32 s39, v237, 40
	v_readlane_b32 s40, v237, 41
	v_readlane_b32 s41, v237, 42
	v_readlane_b32 s42, v237, 43
	v_readlane_b32 s43, v237, 44
	v_readlane_b32 s44, v237, 45
	v_readlane_b32 s45, v237, 46
	v_readlane_b32 s46, v237, 47
	v_readlane_b32 s47, v237, 48
	v_readlane_b32 s48, v237, 49
	v_readlane_b32 s49, v237, 50
	v_readlane_b32 s50, v237, 51
	v_readlane_b32 s51, v237, 52
	v_readlane_b32 s36, v236, 5
	v_readlane_b32 s48, v236, 17
	v_readlane_b32 s49, v236, 18
	v_readlane_b32 s38, v236, 7
	v_readlane_b32 s46, v236, 15
	v_readlane_b32 s47, v236, 16
	v_readlane_b32 s37, v236, 6
	v_readlane_b32 s40, v236, 9
	v_readlane_b32 s41, v236, 10
	v_readlane_b32 s42, v236, 11
	v_readlane_b32 s43, v236, 12
	v_readlane_b32 s44, v236, 13
	v_readlane_b32 s45, v236, 14
	v_readlane_b32 s50, v236, 19
	v_readlane_b32 s51, v236, 20
	s_mov_b64 s[46:47], 0x20000
	s_movk_i32 s38, 0x61
	v_readlane_b32 s39, v236, 8
	s_waitcnt vmcnt(0)
	v_add_f32_e32 v137, v124, v128
	v_mul_f32_e32 v137, 0xbfb8aa3b, v137
	v_exp_f32_e32 v137, v137
	v_add_f32_e32 v139, v125, v129
	v_add_f32_e32 v162, v126, v130
	v_add_f32_e32 v161, v122, v134
	v_add_f32_e32 v137, 1.0, v137
	v_rcp_f32_e32 v169, v137
	v_mul_f32_e32 v137, 0xbfb8aa3b, v139
	v_exp_f32_e32 v137, v137
	v_add_f32_e32 v163, v123, v135
	v_mul_f32_e32 v161, 0xbfb8aa3b, v161
	v_mul_f32_e32 v163, 0xbfb8aa3b, v163
	v_add_f32_e32 v137, 1.0, v137
	v_rcp_f32_e32 v139, v137
	v_mul_f32_e32 v137, 0xbfb8aa3b, v162
	v_exp_f32_e32 v137, v137
	v_exp_f32_e32 v161, v161
	v_exp_f32_e32 v163, v163
	v_add_f32_e32 v136, v120, v132
	v_add_f32_e32 v138, v121, v133
	v_add_f32_e32 v168, v127, v131
	v_add_f32_e32 v137, 1.0, v137
	v_mul_f32_e32 v136, 0xbfb8aa3b, v136
	v_mul_f32_e32 v138, 0xbfb8aa3b, v138
	v_rcp_f32_e32 v162, v137
	v_mul_f32_e32 v137, 0xbfb8aa3b, v168
	v_exp_f32_e32 v136, v136
	v_exp_f32_e32 v138, v138
	v_add_f32_e32 v161, 1.0, v161
	v_add_f32_e32 v163, 1.0, v163
	v_exp_f32_e32 v137, v137
	v_rcp_f32_e32 v161, v161
	v_rcp_f32_e32 v163, v163
	v_add_f32_e32 v136, 1.0, v136
	v_add_f32_e32 v138, 1.0, v138
	v_add_f32_e32 v137, 1.0, v137
	v_rcp_f32_e32 v136, v136
	v_rcp_f32_e32 v138, v138
	v_rcp_f32_e32 v168, v137
	v_cvt_pk_f16_f32 v137, v161, v163
	v_ashrrev_i32_e32 v161, 31, v160
	v_lshlrev_b64 v[160:161], 12, v[160:161]
	v_lshl_add_u64 v[160:161], s[48:49], 0, v[160:161]
	v_lshl_add_u64 v[160:161], s[0:1], 1, v[160:161]
; __device__ __forceinline__ float fsigmoid(float x) { return __builtin_amdgcn_rcpf(1.f + __builtin_amdgcn_exp2f(-1.4426950408889634f * x)); }
;     template <int MODE> __device__ __forceinline__ void run(AccRef acc, const Unit& u, int wr, int wc, int fr, int fq) const {
;     ...
;                     } else if (MODE == 1) {
; #pragma unroll
;                         for (int e = 0; e < 8; ++e) x[e] = fsigmoid(x[e]);
;                         w.x = pkh(x[0], x[1]); w.y = pkh(x[2], x[3]); w.z = pkh(x[4], x[5]); w.w = pkh(x[6], x[7]);
;                         *(u32x4*)(WA + (size_t)row * 2048 + seg * 512 + cc) = w;
	v_cvt_pk_f16_f32 v136, v136, v138
	v_cvt_pk_f16_f32 v138, v169, v139
	v_cvt_pk_f16_f32 v139, v162, v168
	v_lshl_add_u64 v[158:159], v[158:159], 1, v[160:161]
	global_store_dwordx4 v[158:159], v[136:139], off offset:2048 sc1
	v_add_f32_e32 v160, v118, v134
	v_add_f32_e32 v162, v119, v135
	v_mul_f32_e32 v160, 0xbfb8aa3b, v160
	v_exp_f32_e32 v160, v160
	v_mul_f32_e32 v162, 0xbfb8aa3b, v162
	v_exp_f32_e32 v162, v162
	v_add_f32_e32 v161, v114, v130
	v_add_f32_e32 v160, 1.0, v160
	v_rcp_f32_e32 v168, v160
	v_add_f32_e32 v160, 1.0, v162
	v_add_f32_e32 v136, v116, v132
	v_add_f32_e32 v137, v112, v128
	v_add_f32_e32 v138, v117, v133
	v_add_f32_e32 v139, v113, v129
	v_add_f32_e32 v163, v115, v131
	v_rcp_f32_e32 v162, v160
	v_mul_f32_e32 v160, 0xbfb8aa3b, v161
	v_mul_f32_e32 v136, 0xbfb8aa3b, v136
	v_mul_f32_e32 v138, 0xbfb8aa3b, v138
	v_mul_f32_e32 v137, 0xbfb8aa3b, v137
	v_mul_f32_e32 v139, 0xbfb8aa3b, v139
	v_exp_f32_e32 v160, v160
	v_mul_f32_e32 v161, 0xbfb8aa3b, v163
	v_exp_f32_e32 v136, v136
	v_exp_f32_e32 v138, v138
	v_exp_f32_e32 v137, v137
	v_exp_f32_e32 v139, v139
	v_exp_f32_e32 v161, v161
	v_add_f32_e32 v160, 1.0, v160
	v_add_f32_e32 v136, 1.0, v136
	v_add_f32_e32 v138, 1.0, v138
	v_add_f32_e32 v137, 1.0, v137
	v_add_f32_e32 v139, 1.0, v139
	v_rcp_f32_e32 v163, v160
	v_add_f32_e32 v160, 1.0, v161
	v_rcp_f32_e32 v136, v136
	v_rcp_f32_e32 v138, v138
	v_rcp_f32_e32 v137, v137
	v_rcp_f32_e32 v139, v139
	v_rcp_f32_e32 v169, v160
	v_cvt_pk_f16_f32 v160, v136, v138
	v_cvt_pk_f16_f32 v161, v168, v162
	v_cvt_pk_f16_f32 v162, v137, v139
	v_cvt_pk_f16_f32 v163, v163, v169
	v_lshl_add_u64 v[136:137], v[158:159], 0, s[58:59]
	global_store_dwordx4 v[136:137], v[160:163], off offset:2048 sc1
	s_nop 1
	v_add_f32_e32 v161, v105, v129
	v_add_f32_e32 v163, v106, v130
	v_mul_f32_e32 v161, 0xbfb8aa3b, v161
	v_add_f32_e32 v138, v108, v132
	v_add_f32_e32 v139, v104, v128
	v_add_f32_e32 v160, v109, v133
	v_add_f32_e32 v162, v110, v134
	v_add_f32_e32 v168, v111, v135
	v_add_f32_e32 v169, v107, v131
	v_exp_f32_e32 v161, v161
	v_mul_f32_e32 v163, 0xbfb8aa3b, v163
	v_mul_f32_e32 v138, 0xbfb8aa3b, v138
	v_mul_f32_e32 v160, 0xbfb8aa3b, v160
	v_mul_f32_e32 v162, 0xbfb8aa3b, v162
	v_mul_f32_e32 v168, 0xbfb8aa3b, v168
	v_mul_f32_e32 v139, 0xbfb8aa3b, v139
	v_exp_f32_e32 v163, v163
	v_mul_f32_e32 v169, 0xbfb8aa3b, v169
	v_exp_f32_e32 v138, v138
	v_exp_f32_e32 v160, v160
	v_exp_f32_e32 v162, v162
	v_exp_f32_e32 v168, v168
	v_exp_f32_e32 v139, v139
	v_exp_f32_e32 v169, v169
	v_add_f32_e32 v161, 1.0, v161
	v_rcp_f32_e32 v170, v161
	v_add_f32_e32 v161, 1.0, v163
	v_add_f32_e32 v138, 1.0, v138
	v_add_f32_e32 v160, 1.0, v160
	v_add_f32_e32 v162, 1.0, v162
	v_add_f32_e32 v168, 1.0, v168
	v_add_f32_e32 v139, 1.0, v139
	v_rcp_f32_e32 v163, v161
	v_add_f32_e32 v161, 1.0, v169
	v_rcp_f32_e32 v138, v138
	v_rcp_f32_e32 v160, v160
	v_rcp_f32_e32 v162, v162
	v_rcp_f32_e32 v168, v168
	v_rcp_f32_e32 v139, v139
	v_rcp_f32_e32 v169, v161
	v_cvt_pk_f16_f32 v160, v138, v160
	v_cvt_pk_f16_f32 v161, v162, v168
	v_cvt_pk_f16_f32 v162, v139, v170
	v_cvt_pk_f16_f32 v163, v163, v169
	v_lshl_add_u64 v[138:139], v[158:159], 0, s[46:47]
	global_store_dwordx4 v[138:139], v[160:163], off offset:2048 sc1
	v_add_f32_e32 v168, v102, v134
	v_add_f32_e32 v170, v103, v135
	v_mul_f32_e32 v168, 0xbfb8aa3b, v168
	v_exp_f32_e32 v168, v168
	v_mul_f32_e32 v170, 0xbfb8aa3b, v170
	v_exp_f32_e32 v170, v170
	v_add_f32_e32 v169, v98, v130
	v_add_f32_e32 v168, 1.0, v168
	v_rcp_f32_e32 v172, v168
	v_add_f32_e32 v168, 1.0, v170
	v_add_f32_e32 v160, v100, v132
	v_add_f32_e32 v161, v96, v128
	v_add_f32_e32 v162, v101, v133
	v_add_f32_e32 v163, v97, v129
	v_add_f32_e32 v171, v99, v131
	v_rcp_f32_e32 v170, v168
	v_mul_f32_e32 v168, 0xbfb8aa3b, v169
	v_mul_f32_e32 v160, 0xbfb8aa3b, v160
	v_mul_f32_e32 v162, 0xbfb8aa3b, v162
	v_mul_f32_e32 v161, 0xbfb8aa3b, v161
	v_mul_f32_e32 v163, 0xbfb8aa3b, v163
	v_exp_f32_e32 v168, v168
	v_mul_f32_e32 v169, 0xbfb8aa3b, v171
	v_exp_f32_e32 v160, v160
	v_exp_f32_e32 v162, v162
	v_exp_f32_e32 v161, v161
	v_exp_f32_e32 v163, v163
	v_exp_f32_e32 v169, v169
	v_add_f32_e32 v168, 1.0, v168
	v_add_f32_e32 v160, 1.0, v160
	v_add_f32_e32 v162, 1.0, v162
	v_add_f32_e32 v161, 1.0, v161
	v_add_f32_e32 v163, 1.0, v163
	v_rcp_f32_e32 v171, v168
	v_add_f32_e32 v168, 1.0, v169
	v_rcp_f32_e32 v160, v160
	v_rcp_f32_e32 v162, v162
	v_rcp_f32_e32 v161, v161
	v_rcp_f32_e32 v163, v163
	v_rcp_f32_e32 v173, v168
	s_mov_b64 s[0:1], 0x30000
	v_cvt_pk_f16_f32 v168, v160, v162
	v_cvt_pk_f16_f32 v169, v172, v170
	v_cvt_pk_f16_f32 v170, v161, v163
	v_cvt_pk_f16_f32 v171, v171, v173
	v_lshl_add_u64 v[160:161], v[158:159], 0, s[0:1]
	global_store_dwordx4 v[160:161], v[168:171], off offset:2048 sc1
	s_nop 1
	v_add_f32_e32 v169, v89, v129
	v_add_f32_e32 v171, v90, v130
	v_mul_f32_e32 v169, 0xbfb8aa3b, v169
	v_add_f32_e32 v162, v92, v132
	v_add_f32_e32 v163, v88, v128
	v_add_f32_e32 v168, v93, v133
	v_add_f32_e32 v170, v94, v134
	v_add_f32_e32 v172, v95, v135
	v_add_f32_e32 v173, v91, v131
	v_exp_f32_e32 v169, v169
	v_mul_f32_e32 v171, 0xbfb8aa3b, v171
	v_mul_f32_e32 v162, 0xbfb8aa3b, v162
	v_mul_f32_e32 v168, 0xbfb8aa3b, v168
	v_mul_f32_e32 v170, 0xbfb8aa3b, v170
	v_mul_f32_e32 v172, 0xbfb8aa3b, v172
	v_mul_f32_e32 v163, 0xbfb8aa3b, v163
	v_exp_f32_e32 v171, v171
	v_mul_f32_e32 v173, 0xbfb8aa3b, v173
	v_exp_f32_e32 v162, v162
	v_exp_f32_e32 v168, v168
	v_exp_f32_e32 v170, v170
	v_exp_f32_e32 v172, v172
	v_exp_f32_e32 v163, v163
	v_exp_f32_e32 v173, v173
	v_add_f32_e32 v169, 1.0, v169
	v_rcp_f32_e32 v182, v169
	v_add_f32_e32 v169, 1.0, v171
	v_add_f32_e32 v162, 1.0, v162
	v_add_f32_e32 v168, 1.0, v168
	v_add_f32_e32 v170, 1.0, v170
; __device__ __forceinline__ float fsigmoid(float x) { return __builtin_amdgcn_rcpf(1.f + __builtin_amdgcn_exp2f(-1.4426950408889634f * x)); }
;     template <int MODE> __device__ __forceinline__ void run(AccRef acc, const Unit& u, int wr, int wc, int fr, int fq) const {
;     ...
;                     } else if (MODE == 1) {
; #pragma unroll
;                         for (int e = 0; e < 8; ++e) x[e] = fsigmoid(x[e]);
;                         w.x = pkh(x[0], x[1]); w.y = pkh(x[2], x[3]); w.z = pkh(x[4], x[5]); w.w = pkh(x[6], x[7]);
;                         *(u32x4*)(WA + (size_t)row * 2048 + seg * 512 + cc) = w;
	v_add_f32_e32 v172, 1.0, v172
	v_add_f32_e32 v163, 1.0, v163
	v_rcp_f32_e32 v171, v169
	v_add_f32_e32 v169, 1.0, v173
	v_rcp_f32_e32 v162, v162
	v_rcp_f32_e32 v168, v168
	v_rcp_f32_e32 v170, v170
	v_rcp_f32_e32 v172, v172
	v_rcp_f32_e32 v163, v163
	v_rcp_f32_e32 v173, v169
	s_mov_b64 s[0:1], 0x80000
	v_cvt_pk_f16_f32 v168, v162, v168
	v_cvt_pk_f16_f32 v169, v170, v172
	v_cvt_pk_f16_f32 v170, v163, v182
	v_cvt_pk_f16_f32 v171, v171, v173
	v_lshl_add_u64 v[162:163], v[158:159], 0, s[0:1]
	global_store_dwordx4 v[162:163], v[168:171], off offset:2048 sc1
	s_nop 1
	v_add_f32_e32 v171, v81, v129
	v_add_f32_e32 v173, v82, v130
	v_mul_f32_e32 v171, 0xbfb8aa3b, v171
	v_add_f32_e32 v168, v84, v132
	v_add_f32_e32 v169, v80, v128
	v_add_f32_e32 v170, v85, v133
	v_add_f32_e32 v172, v86, v134
	v_add_f32_e32 v182, v87, v135
	v_add_f32_e32 v183, v83, v131
	v_exp_f32_e32 v171, v171
	v_mul_f32_e32 v173, 0xbfb8aa3b, v173
	v_mul_f32_e32 v168, 0xbfb8aa3b, v168
	v_mul_f32_e32 v170, 0xbfb8aa3b, v170
	v_mul_f32_e32 v172, 0xbfb8aa3b, v172
	v_mul_f32_e32 v182, 0xbfb8aa3b, v182
	v_mul_f32_e32 v169, 0xbfb8aa3b, v169
	v_exp_f32_e32 v173, v173
	v_mul_f32_e32 v183, 0xbfb8aa3b, v183
	v_exp_f32_e32 v168, v168
	v_exp_f32_e32 v170, v170
	v_exp_f32_e32 v172, v172
	v_exp_f32_e32 v182, v182
	v_exp_f32_e32 v169, v169
	v_exp_f32_e32 v183, v183
	v_add_f32_e32 v171, 1.0, v171
	v_rcp_f32_e32 v184, v171
	v_add_f32_e32 v171, 1.0, v173
	v_add_f32_e32 v168, 1.0, v168
	v_add_f32_e32 v170, 1.0, v170
	v_add_f32_e32 v172, 1.0, v172
	v_add_f32_e32 v182, 1.0, v182
	v_add_f32_e32 v169, 1.0, v169
	v_rcp_f32_e32 v173, v171
	v_add_f32_e32 v171, 1.0, v183
	v_rcp_f32_e32 v168, v168
	v_rcp_f32_e32 v170, v170
	v_rcp_f32_e32 v172, v172
	v_rcp_f32_e32 v182, v182
	v_rcp_f32_e32 v169, v169
	v_rcp_f32_e32 v183, v171
	s_mov_b64 s[0:1], 0x90000
	v_cvt_pk_f16_f32 v170, v168, v170
	v_cvt_pk_f16_f32 v171, v172, v182
	v_cvt_pk_f16_f32 v172, v169, v184
	v_cvt_pk_f16_f32 v173, v173, v183
	v_lshl_add_u64 v[168:169], v[158:159], 0, s[0:1]
	global_store_dwordx4 v[168:169], v[170:173], off offset:2048 sc1
	v_add_f32_e32 v182, v78, v134
	v_add_f32_e32 v184, v79, v135
	v_mul_f32_e32 v182, 0xbfb8aa3b, v182
	v_exp_f32_e32 v182, v182
	v_mul_f32_e32 v184, 0xbfb8aa3b, v184
	v_exp_f32_e32 v184, v184
	v_add_f32_e32 v183, v74, v130
	v_add_f32_e32 v182, 1.0, v182
	v_rcp_f32_e32 v186, v182
	v_add_f32_e32 v182, 1.0, v184
	v_add_f32_e32 v170, v76, v132
	v_add_f32_e32 v171, v72, v128
	v_add_f32_e32 v172, v77, v133
	v_add_f32_e32 v173, v73, v129
	v_add_f32_e32 v185, v75, v131
	v_rcp_f32_e32 v184, v182
	v_mul_f32_e32 v182, 0xbfb8aa3b, v183
	v_mul_f32_e32 v170, 0xbfb8aa3b, v170
	v_mul_f32_e32 v172, 0xbfb8aa3b, v172
	v_mul_f32_e32 v171, 0xbfb8aa3b, v171
	v_mul_f32_e32 v173, 0xbfb8aa3b, v173
	v_exp_f32_e32 v182, v182
	v_mul_f32_e32 v183, 0xbfb8aa3b, v185
	v_exp_f32_e32 v170, v170
	v_exp_f32_e32 v172, v172
	v_exp_f32_e32 v171, v171
	v_exp_f32_e32 v173, v173
	v_exp_f32_e32 v183, v183
	v_add_f32_e32 v182, 1.0, v182
	v_add_f32_e32 v170, 1.0, v170
	v_add_f32_e32 v172, 1.0, v172
	v_add_f32_e32 v171, 1.0, v171
	v_add_f32_e32 v173, 1.0, v173
	v_rcp_f32_e32 v185, v182
	v_add_f32_e32 v182, 1.0, v183
	v_rcp_f32_e32 v170, v170
	v_rcp_f32_e32 v172, v172
	v_rcp_f32_e32 v171, v171
	v_rcp_f32_e32 v173, v173
	v_rcp_f32_e32 v187, v182
	s_mov_b64 s[0:1], 0xa0000
	v_cvt_pk_f16_f32 v182, v170, v172
	v_cvt_pk_f16_f32 v183, v186, v184
	v_cvt_pk_f16_f32 v184, v171, v173
	v_cvt_pk_f16_f32 v185, v185, v187
	v_lshl_add_u64 v[170:171], v[158:159], 0, s[0:1]
	global_store_dwordx4 v[170:171], v[182:185], off offset:2048 sc1
	v_add_f32_e32 v128, v64, v128
	v_add_f32_e32 v129, v65, v129
	v_mul_f32_e32 v128, 0xbfb8aa3b, v128
	v_exp_f32_e32 v128, v128
	v_mul_f32_e32 v129, 0xbfb8aa3b, v129
	v_exp_f32_e32 v129, v129
	v_add_f32_e32 v130, v66, v130
	v_add_f32_e32 v128, 1.0, v128
	v_add_f32_e32 v132, v68, v132
	v_add_f32_e32 v133, v69, v133
	v_add_f32_e32 v134, v70, v134
	v_add_f32_e32 v135, v71, v135
	v_add_f32_e32 v131, v67, v131
	v_rcp_f32_e32 v172, v128
	v_add_f32_e32 v128, 1.0, v129
	v_mul_f32_e32 v129, 0xbfb8aa3b, v130
	v_mul_f32_e32 v132, 0xbfb8aa3b, v132
	v_mul_f32_e32 v133, 0xbfb8aa3b, v133
	v_mul_f32_e32 v134, 0xbfb8aa3b, v134
	v_mul_f32_e32 v135, 0xbfb8aa3b, v135
	v_exp_f32_e32 v129, v129
	v_mul_f32_e32 v130, 0xbfb8aa3b, v131
	v_exp_f32_e32 v132, v132
	v_exp_f32_e32 v133, v133
	v_exp_f32_e32 v134, v134
	v_exp_f32_e32 v135, v135
	v_exp_f32_e32 v130, v130
	v_rcp_f32_e32 v131, v128
	v_add_f32_e32 v128, 1.0, v129
	v_add_f32_e32 v132, 1.0, v132
	v_add_f32_e32 v133, 1.0, v133
	v_add_f32_e32 v134, 1.0, v134
	v_add_f32_e32 v135, 1.0, v135
	v_rcp_f32_e32 v173, v128
	v_add_f32_e32 v128, 1.0, v130
	v_rcp_f32_e32 v132, v132
	v_rcp_f32_e32 v133, v133
	v_rcp_f32_e32 v134, v134
	v_rcp_f32_e32 v135, v135
	v_rcp_f32_e32 v182, v128
	v_cvt_pk_f16_f32 v128, v132, v133
	v_cvt_pk_f16_f32 v129, v134, v135
	v_cvt_pk_f16_f32 v130, v172, v131
	v_cvt_pk_f16_f32 v131, v173, v182
	v_lshl_add_u64 v[172:173], v[158:159], 0, s[70:71]
	global_store_dwordx4 v[172:173], v[128:131], off offset:2048 sc1
	global_load_dwordx4 v[132:135], v[156:157], off offset:512
	global_load_dwordx4 v[128:131], v[156:157], off offset:528
	s_waitcnt vmcnt(0)
; __device__ __forceinline__ float fsigmoid(float x) { return __builtin_amdgcn_rcpf(1.f + __builtin_amdgcn_exp2f(-1.4426950408889634f * x)); }
;     template <int MODE> __device__ __forceinline__ void run(AccRef acc, const Unit& u, int wr, int wc, int fr, int fq) const {
;     ...
;                     } else if (MODE == 1) {
; #pragma unroll
;                         for (int e = 0; e < 8; ++e) x[e] = fsigmoid(x[e]);
;                         w.x = pkh(x[0], x[1]); w.y = pkh(x[2], x[3]); w.z = pkh(x[4], x[5]); w.w = pkh(x[6], x[7]);
;                         *(u32x4*)(WA + (size_t)row * 2048 + seg * 512 + cc) = w;
	v_add_f32_e32 v156, v60, v132
	v_add_f32_e32 v157, v56, v128
	v_add_f32_e32 v182, v61, v133
	v_add_f32_e32 v183, v57, v129
	v_add_f32_e32 v184, v62, v134
	v_add_f32_e32 v185, v58, v130
	v_add_f32_e32 v186, v63, v135
	v_add_f32_e32 v187, v59, v131
	v_mul_f32_e32 v156, 0xbfb8aa3b, v156
	v_mul_f32_e32 v182, 0xbfb8aa3b, v182
	v_mul_f32_e32 v184, 0xbfb8aa3b, v184
	v_mul_f32_e32 v186, 0xbfb8aa3b, v186
	v_mul_f32_e32 v157, 0xbfb8aa3b, v157
	v_mul_f32_e32 v183, 0xbfb8aa3b, v183
	v_mul_f32_e32 v185, 0xbfb8aa3b, v185
	v_mul_f32_e32 v187, 0xbfb8aa3b, v187
	v_exp_f32_e32 v156, v156
	v_exp_f32_e32 v182, v182
	v_exp_f32_e32 v184, v184
	v_exp_f32_e32 v186, v186
	v_exp_f32_e32 v157, v157
	v_exp_f32_e32 v183, v183
	v_exp_f32_e32 v185, v185
	v_exp_f32_e32 v187, v187
	v_add_f32_e32 v156, 1.0, v156
	v_add_f32_e32 v182, 1.0, v182
	v_add_f32_e32 v184, 1.0, v184
	v_add_f32_e32 v186, 1.0, v186
	v_add_f32_e32 v157, 1.0, v157
	v_add_f32_e32 v183, 1.0, v183
	v_add_f32_e32 v185, 1.0, v185
	v_add_f32_e32 v187, 1.0, v187
	v_rcp_f32_e32 v156, v156
	v_rcp_f32_e32 v182, v182
	v_rcp_f32_e32 v184, v184
	v_rcp_f32_e32 v186, v186
	v_rcp_f32_e32 v157, v157
	v_rcp_f32_e32 v188, v183
	v_rcp_f32_e32 v185, v185
	v_rcp_f32_e32 v187, v187
	v_cvt_pk_f16_f32 v182, v156, v182
	v_cvt_pk_f16_f32 v183, v184, v186
	v_cvt_pk_f16_f32 v184, v157, v188
	v_cvt_pk_f16_f32 v185, v185, v187
	global_store_dwordx4 v[158:159], v[182:185], off offset:2304 sc1
	v_add_f32_e32 v157, v48, v128
	v_add_f32_e32 v159, v49, v129
	v_mul_f32_e32 v157, 0xbfb8aa3b, v157
	v_exp_f32_e32 v157, v157
	v_mul_f32_e32 v159, 0xbfb8aa3b, v159
	v_exp_f32_e32 v159, v159
	v_add_f32_e32 v183, v50, v130
	v_add_f32_e32 v157, 1.0, v157
	v_add_f32_e32 v156, v52, v132
	v_add_f32_e32 v158, v53, v133
	v_add_f32_e32 v182, v54, v134
	v_add_f32_e32 v184, v55, v135
	v_add_f32_e32 v185, v51, v131
	v_rcp_f32_e32 v186, v157
	v_add_f32_e32 v157, 1.0, v159
	v_mul_f32_e32 v159, 0xbfb8aa3b, v183
	v_mul_f32_e32 v156, 0xbfb8aa3b, v156
	v_mul_f32_e32 v158, 0xbfb8aa3b, v158
	v_mul_f32_e32 v182, 0xbfb8aa3b, v182
	v_mul_f32_e32 v184, 0xbfb8aa3b, v184
	v_exp_f32_e32 v159, v159
	v_mul_f32_e32 v183, 0xbfb8aa3b, v185
	v_exp_f32_e32 v156, v156
	v_exp_f32_e32 v158, v158
	v_exp_f32_e32 v182, v182
	v_exp_f32_e32 v184, v184
	v_exp_f32_e32 v183, v183
	v_rcp_f32_e32 v185, v157
	v_add_f32_e32 v157, 1.0, v159
	v_add_f32_e32 v156, 1.0, v156
	v_add_f32_e32 v158, 1.0, v158
	v_add_f32_e32 v182, 1.0, v182
	v_add_f32_e32 v184, 1.0, v184
	v_rcp_f32_e32 v159, v157
	v_add_f32_e32 v157, 1.0, v183
	v_rcp_f32_e32 v156, v156
	v_rcp_f32_e32 v158, v158
	v_rcp_f32_e32 v182, v182
	v_rcp_f32_e32 v184, v184
	v_rcp_f32_e32 v183, v157
	v_cvt_pk_f16_f32 v156, v156, v158
	v_cvt_pk_f16_f32 v157, v182, v184
	v_cvt_pk_f16_f32 v158, v186, v185
	v_cvt_pk_f16_f32 v159, v159, v183
	global_store_dwordx4 v[136:137], v[156:159], off offset:2304 sc1
	s_nop 1
	v_add_f32_e32 v157, v41, v129
	v_add_f32_e32 v159, v42, v130
	v_mul_f32_e32 v157, 0xbfb8aa3b, v157
	v_add_f32_e32 v136, v44, v132
	v_add_f32_e32 v137, v40, v128
	v_add_f32_e32 v156, v45, v133
	v_add_f32_e32 v158, v46, v134
	v_add_f32_e32 v182, v47, v135
	v_add_f32_e32 v183, v43, v131
	v_exp_f32_e32 v157, v157
	v_mul_f32_e32 v159, 0xbfb8aa3b, v159
	v_mul_f32_e32 v136, 0xbfb8aa3b, v136
	v_mul_f32_e32 v156, 0xbfb8aa3b, v156
	v_mul_f32_e32 v158, 0xbfb8aa3b, v158
	v_mul_f32_e32 v182, 0xbfb8aa3b, v182
	v_mul_f32_e32 v137, 0xbfb8aa3b, v137
	v_exp_f32_e32 v159, v159
	v_mul_f32_e32 v183, 0xbfb8aa3b, v183
	v_exp_f32_e32 v136, v136
	v_exp_f32_e32 v156, v156
	v_exp_f32_e32 v158, v158
	v_exp_f32_e32 v182, v182
	v_exp_f32_e32 v137, v137
	v_exp_f32_e32 v183, v183
	v_add_f32_e32 v157, 1.0, v157
	v_rcp_f32_e32 v184, v157
	v_add_f32_e32 v157, 1.0, v159
	v_add_f32_e32 v136, 1.0, v136
	v_add_f32_e32 v156, 1.0, v156
	v_add_f32_e32 v158, 1.0, v158
	v_add_f32_e32 v182, 1.0, v182
	v_add_f32_e32 v137, 1.0, v137
	v_rcp_f32_e32 v159, v157
	v_add_f32_e32 v157, 1.0, v183
	v_rcp_f32_e32 v136, v136
	v_rcp_f32_e32 v156, v156
	v_rcp_f32_e32 v158, v158
	v_rcp_f32_e32 v182, v182
	v_rcp_f32_e32 v137, v137
	v_rcp_f32_e32 v183, v157
	v_cvt_pk_f16_f32 v156, v136, v156
	v_cvt_pk_f16_f32 v157, v158, v182
	v_cvt_pk_f16_f32 v158, v137, v184
	v_cvt_pk_f16_f32 v159, v159, v183
	global_store_dwordx4 v[138:139], v[156:159], off offset:2304 sc1
	v_add_f32_e32 v137, v32, v128
	v_add_f32_e32 v139, v33, v129
	v_mul_f32_e32 v137, 0xbfb8aa3b, v137
	v_exp_f32_e32 v137, v137
	v_mul_f32_e32 v139, 0xbfb8aa3b, v139
	v_exp_f32_e32 v139, v139
	v_add_f32_e32 v157, v34, v130
	v_add_f32_e32 v137, 1.0, v137
	v_add_f32_e32 v136, v36, v132
	v_add_f32_e32 v138, v37, v133
	v_add_f32_e32 v156, v38, v134
	v_add_f32_e32 v158, v39, v135
	v_add_f32_e32 v159, v35, v131
	v_rcp_f32_e32 v182, v137
	v_add_f32_e32 v137, 1.0, v139
	v_mul_f32_e32 v139, 0xbfb8aa3b, v157
	v_mul_f32_e32 v136, 0xbfb8aa3b, v136
	v_mul_f32_e32 v138, 0xbfb8aa3b, v138
	v_mul_f32_e32 v156, 0xbfb8aa3b, v156
	v_mul_f32_e32 v158, 0xbfb8aa3b, v158
	v_exp_f32_e32 v139, v139
	v_mul_f32_e32 v157, 0xbfb8aa3b, v159
	v_exp_f32_e32 v136, v136
	v_exp_f32_e32 v138, v138
	v_exp_f32_e32 v156, v156
	v_exp_f32_e32 v158, v158
	v_exp_f32_e32 v157, v157
	v_rcp_f32_e32 v159, v137
	v_add_f32_e32 v137, 1.0, v139
	v_add_f32_e32 v136, 1.0, v136
	v_add_f32_e32 v138, 1.0, v138
	v_add_f32_e32 v156, 1.0, v156
	v_add_f32_e32 v158, 1.0, v158
	v_rcp_f32_e32 v139, v137
	v_add_f32_e32 v137, 1.0, v157
	v_rcp_f32_e32 v136, v136
	v_rcp_f32_e32 v138, v138
	v_rcp_f32_e32 v156, v156
	v_rcp_f32_e32 v158, v158
	v_rcp_f32_e32 v157, v137
	v_cvt_pk_f16_f32 v136, v136, v138
	v_cvt_pk_f16_f32 v137, v156, v158
	v_cvt_pk_f16_f32 v138, v182, v159
	v_cvt_pk_f16_f32 v139, v139, v157
; __device__ __forceinline__ float fsigmoid(float x) { return __builtin_amdgcn_rcpf(1.f + __builtin_amdgcn_exp2f(-1.4426950408889634f * x)); }
;     template <int MODE> __device__ __forceinline__ void run(AccRef acc, const Unit& u, int wr, int wc, int fr, int fq) const {
;     ...
;                     } else if (MODE == 1) {
; #pragma unroll
;                         for (int e = 0; e < 8; ++e) x[e] = fsigmoid(x[e]);
;                         w.x = pkh(x[0], x[1]); w.y = pkh(x[2], x[3]); w.z = pkh(x[4], x[5]); w.w = pkh(x[6], x[7]);
;                         *(u32x4*)(WA + (size_t)row * 2048 + seg * 512 + cc) = w;
	global_store_dwordx4 v[160:161], v[136:139], off offset:2304 sc1
	s_nop 1
	v_add_f32_e32 v137, v24, v128
	v_add_f32_e32 v139, v25, v129
	v_mul_f32_e32 v137, 0xbfb8aa3b, v137
	v_exp_f32_e32 v137, v137
	v_mul_f32_e32 v139, 0xbfb8aa3b, v139
	v_exp_f32_e32 v139, v139
	v_add_f32_e32 v157, v26, v130
	v_add_f32_e32 v137, 1.0, v137
	v_add_f32_e32 v136, v28, v132
	v_add_f32_e32 v138, v29, v133
	v_add_f32_e32 v156, v30, v134
	v_add_f32_e32 v158, v31, v135
	v_add_f32_e32 v159, v27, v131
	v_rcp_f32_e32 v160, v137
	v_add_f32_e32 v137, 1.0, v139
	v_mul_f32_e32 v139, 0xbfb8aa3b, v157
	v_mul_f32_e32 v136, 0xbfb8aa3b, v136
	v_mul_f32_e32 v138, 0xbfb8aa3b, v138
	v_mul_f32_e32 v156, 0xbfb8aa3b, v156
	v_mul_f32_e32 v158, 0xbfb8aa3b, v158
	v_exp_f32_e32 v139, v139
	v_mul_f32_e32 v157, 0xbfb8aa3b, v159
	v_exp_f32_e32 v136, v136
	v_exp_f32_e32 v138, v138
	v_exp_f32_e32 v156, v156
	v_exp_f32_e32 v158, v158
	v_exp_f32_e32 v157, v157
	v_rcp_f32_e32 v159, v137
	v_add_f32_e32 v137, 1.0, v139
	v_add_f32_e32 v136, 1.0, v136
	v_add_f32_e32 v138, 1.0, v138
	v_add_f32_e32 v156, 1.0, v156
	v_add_f32_e32 v158, 1.0, v158
	v_rcp_f32_e32 v139, v137
	v_add_f32_e32 v137, 1.0, v157
	v_rcp_f32_e32 v136, v136
	v_rcp_f32_e32 v138, v138
	v_rcp_f32_e32 v156, v156
	v_rcp_f32_e32 v158, v158
	v_rcp_f32_e32 v157, v137
	v_cvt_pk_f16_f32 v136, v136, v138
	v_cvt_pk_f16_f32 v137, v156, v158
	v_cvt_pk_f16_f32 v138, v160, v159
	v_cvt_pk_f16_f32 v139, v139, v157
	global_store_dwordx4 v[162:163], v[136:139], off offset:2304 sc1
	s_nop 1
	v_add_f32_e32 v137, v16, v128
	v_add_f32_e32 v139, v17, v129
	v_mul_f32_e32 v137, 0xbfb8aa3b, v137
	v_exp_f32_e32 v137, v137
	v_mul_f32_e32 v139, 0xbfb8aa3b, v139
	v_exp_f32_e32 v139, v139
	v_add_f32_e32 v157, v18, v130
	v_add_f32_e32 v137, 1.0, v137
	v_add_f32_e32 v136, v20, v132
	v_add_f32_e32 v138, v21, v133
	v_add_f32_e32 v156, v22, v134
	v_add_f32_e32 v158, v23, v135
	v_add_f32_e32 v159, v19, v131
	v_rcp_f32_e32 v160, v137
	v_add_f32_e32 v137, 1.0, v139
	v_mul_f32_e32 v139, 0xbfb8aa3b, v157
	v_mul_f32_e32 v136, 0xbfb8aa3b, v136
	v_mul_f32_e32 v138, 0xbfb8aa3b, v138
	v_mul_f32_e32 v156, 0xbfb8aa3b, v156
	v_mul_f32_e32 v158, 0xbfb8aa3b, v158
	v_exp_f32_e32 v139, v139
	v_mul_f32_e32 v157, 0xbfb8aa3b, v159
	v_exp_f32_e32 v136, v136
	v_exp_f32_e32 v138, v138
	v_exp_f32_e32 v156, v156
	v_exp_f32_e32 v158, v158
	v_exp_f32_e32 v157, v157
	v_rcp_f32_e32 v159, v137
	v_add_f32_e32 v137, 1.0, v139
	v_add_f32_e32 v136, 1.0, v136
	v_add_f32_e32 v138, 1.0, v138
	v_add_f32_e32 v156, 1.0, v156
	v_add_f32_e32 v158, 1.0, v158
	v_rcp_f32_e32 v139, v137
	v_add_f32_e32 v137, 1.0, v157
	v_rcp_f32_e32 v136, v136
	v_rcp_f32_e32 v138, v138
	v_rcp_f32_e32 v156, v156
	v_rcp_f32_e32 v158, v158
	v_rcp_f32_e32 v157, v137
	v_cvt_pk_f16_f32 v136, v136, v138
	v_cvt_pk_f16_f32 v137, v156, v158
	v_cvt_pk_f16_f32 v138, v160, v159
	v_cvt_pk_f16_f32 v139, v139, v157
	global_store_dwordx4 v[168:169], v[136:139], off offset:2304 sc1
	s_nop 1
	v_add_f32_e32 v137, v8, v128
	v_add_f32_e32 v139, v9, v129
	v_mul_f32_e32 v137, 0xbfb8aa3b, v137
	v_exp_f32_e32 v137, v137
	v_mul_f32_e32 v139, 0xbfb8aa3b, v139
	v_exp_f32_e32 v139, v139
	v_add_f32_e32 v157, v10, v130
	v_add_f32_e32 v137, 1.0, v137
	v_add_f32_e32 v136, v12, v132
	v_add_f32_e32 v138, v13, v133
	v_add_f32_e32 v156, v14, v134
	v_add_f32_e32 v158, v15, v135
	v_add_f32_e32 v159, v11, v131
	v_rcp_f32_e32 v160, v137
	v_add_f32_e32 v137, 1.0, v139
	v_mul_f32_e32 v139, 0xbfb8aa3b, v157
	v_mul_f32_e32 v136, 0xbfb8aa3b, v136
	v_mul_f32_e32 v138, 0xbfb8aa3b, v138
	v_mul_f32_e32 v156, 0xbfb8aa3b, v156
	v_mul_f32_e32 v158, 0xbfb8aa3b, v158
	v_exp_f32_e32 v139, v139
	v_mul_f32_e32 v157, 0xbfb8aa3b, v159
	v_exp_f32_e32 v136, v136
	v_exp_f32_e32 v138, v138
	v_exp_f32_e32 v156, v156
	v_exp_f32_e32 v158, v158
	v_exp_f32_e32 v157, v157
	v_rcp_f32_e32 v159, v137
	v_add_f32_e32 v137, 1.0, v139
	v_add_f32_e32 v136, 1.0, v136
	v_add_f32_e32 v138, 1.0, v138
	v_add_f32_e32 v156, 1.0, v156
	v_add_f32_e32 v158, 1.0, v158
	v_rcp_f32_e32 v139, v137
	v_add_f32_e32 v137, 1.0, v157
	v_rcp_f32_e32 v136, v136
	v_rcp_f32_e32 v138, v138
	v_rcp_f32_e32 v156, v156
	v_rcp_f32_e32 v158, v158
	v_rcp_f32_e32 v157, v137
	v_cvt_pk_f16_f32 v136, v136, v138
	v_cvt_pk_f16_f32 v137, v156, v158
	v_cvt_pk_f16_f32 v138, v160, v159
	v_cvt_pk_f16_f32 v139, v139, v157
	global_store_dwordx4 v[170:171], v[136:139], off offset:2304 sc1
	v_add_f32_e32 v128, v0, v128
	v_add_f32_e32 v129, v1, v129
	v_mul_f32_e32 v128, 0xbfb8aa3b, v128
	v_exp_f32_e32 v128, v128
	v_mul_f32_e32 v129, 0xbfb8aa3b, v129
	v_exp_f32_e32 v129, v129
	v_add_f32_e32 v130, v2, v130
	v_add_f32_e32 v128, 1.0, v128
	v_add_f32_e32 v132, v4, v132
	v_add_f32_e32 v133, v5, v133
	v_add_f32_e32 v134, v6, v134
	v_add_f32_e32 v135, v7, v135
	v_add_f32_e32 v131, v3, v131
	v_rcp_f32_e32 v136, v128
	v_add_f32_e32 v128, 1.0, v129
	v_mul_f32_e32 v129, 0xbfb8aa3b, v130
	v_mul_f32_e32 v132, 0xbfb8aa3b, v132
	v_mul_f32_e32 v133, 0xbfb8aa3b, v133
	v_mul_f32_e32 v134, 0xbfb8aa3b, v134
	v_mul_f32_e32 v135, 0xbfb8aa3b, v135
	v_exp_f32_e32 v129, v129
	v_mul_f32_e32 v130, 0xbfb8aa3b, v131
	v_exp_f32_e32 v132, v132
	v_exp_f32_e32 v133, v133
	v_exp_f32_e32 v134, v134
	v_exp_f32_e32 v135, v135
	v_exp_f32_e32 v130, v130
	v_rcp_f32_e32 v131, v128
	v_add_f32_e32 v128, 1.0, v129
	v_add_f32_e32 v132, 1.0, v132
	v_add_f32_e32 v133, 1.0, v133
	v_add_f32_e32 v134, 1.0, v134
	v_add_f32_e32 v135, 1.0, v135
	v_rcp_f32_e32 v137, v128
	v_add_f32_e32 v128, 1.0, v130
	v_rcp_f32_e32 v132, v132
	v_rcp_f32_e32 v133, v133
	v_rcp_f32_e32 v134, v134
	v_rcp_f32_e32 v135, v135
	v_rcp_f32_e32 v138, v128
	v_cvt_pk_f16_f32 v128, v132, v133
	v_cvt_pk_f16_f32 v129, v134, v135
	v_cvt_pk_f16_f32 v130, v136, v131
	v_cvt_pk_f16_f32 v131, v137, v138
	global_store_dwordx4 v[172:173], v[128:131], off offset:2304 sc1

;     template <int MODE> __device__ __forceinline__ void run(AccRef acc, const Unit& u, int wr, int wc, int fr, int fq) const {
;     ...
;             if (MODE < 2) { const float* bp = (MODE == 0 ? w0 + seg * 512 : a0 + (seg - 2) * 512) + cc; const f32x4 b0 = *(const f32x4*)bp, b1 = *(const f32x4*)(bp + 4);
;                 bias[0] = b0[0]; bias[1] = b0[1]; bias[2] = b0[2]; bias[3] = b0[3]; bias[4] = b1[0]; bias[5] = b1[1]; bias[6] = b1[2]; bias[7] = b1[3]; }
;     ...
;                     for (int e = 0; e < 4; ++e) { x[e] = acc[ai][bj][m][0][e] + bias[e]; x[4 + e] = acc[ai][bj][m][1][e] + bias[4 + e]; }
;     ...
;                     if (MODE == 0) {
; #pragma unroll
;                         for (int e = 0; e < 8; ++e) { const float sp = __logf(1.f + __expf(-x[e])); x[e] = __expf(-__expf(-sp - 0.5f)); }
;                         w.x = pkh(x[0], x[1]); w.y = pkh(x[2], x[3]); w.z = pkh(x[4], x[5]); w.w = pkh(x[6], x[7]);
;                         *(u32x4*)(WA + (size_t)row * 2048 + seg * 512 + cc) = w;
.LBB0_853:
	s_lshl_b32 s0, s65, 8
	s_add_i32 s0, s0, s35
	v_add_u32_e32 v138, s0, v181
	s_lshl_b32 s0, s67, 8
	s_lshl_b32 s4, s4, 9
	s_and_b32 s0, s0, 0x100
	s_ashr_i32 s5, s4, 31
	s_or_b32 s0, s0, s87
	v_readlane_b32 s16, v237, 21
	v_lshl_add_u32 v156, v180, 3, s0
	s_lshl_b64 s[0:1], s[4:5], 2
	v_readlane_b32 s28, v237, 33
	v_readlane_b32 s29, v237, 34
	s_add_u32 s0, s28, s0
	s_addc_u32 s1, s29, s1
	v_ashrrev_i32_e32 v157, 31, v156
	v_lshl_add_u64 v[136:137], v[156:157], 2, s[0:1]
	global_load_dwordx4 v[128:131], v[136:137], off offset:16
	global_load_dwordx4 v[132:135], v[136:137], off
	v_readlane_b32 s22, v237, 27
	v_readlane_b32 s23, v237, 28
	v_readlane_b32 s22, v236, 21
	v_readlane_b32 s23, v236, 22
	v_readlane_b32 s17, v237, 22
	v_readlane_b32 s18, v237, 23
	v_readlane_b32 s19, v237, 24
	v_readlane_b32 s20, v237, 25
	v_readlane_b32 s21, v237, 26
	v_readlane_b32 s24, v237, 29
	v_readlane_b32 s25, v237, 30
	v_readlane_b32 s26, v237, 31
	v_readlane_b32 s27, v237, 32
	v_readlane_b32 s30, v237, 35
	v_readlane_b32 s31, v237, 36
	s_waitcnt vmcnt(0)
	v_add_f32_e32 v139, v124, v128
	v_add_f32_e32 v120, v120, v132
	v_mul_f32_e32 v120, 0xbfb8aa3b, v120
	v_exp_f32_e32 v120, v120
	v_add_f32_e32 v159, v122, v134
	v_add_f32_e32 v158, v121, v133
	v_add_f32_e32 v124, v126, v130
	v_add_f32_e32 v120, 1.0, v120
	v_cmp_gt_f32_e32 vcc, s61, v120
	v_add_f32_e32 v126, v123, v135
	v_add_f32_e32 v121, v127, v131
	v_cndmask_b32_e64 v122, 0, 32, vcc
	v_ldexp_f32 v120, v120, v122
	v_log_f32_e32 v120, v120
	v_mul_f32_e32 v126, 0xbfb8aa3b, v126
	v_exp_f32_e32 v126, v126
	v_add_f32_e32 v125, v125, v129
	v_mul_f32_e32 v122, 0x3f317217, v120
	v_fma_f32 v122, v120, s62, -v122
	v_fmac_f32_e32 v122, 0x3377d1cf, v120
	v_fmac_f32_e32 v122, 0x3f317217, v120
	v_cmp_lt_f32_e64 s[0:1], |v120|, s63
	v_add_f32_e32 v126, 1.0, v126
	v_mul_f32_e32 v125, 0xbfb8aa3b, v125
	v_cndmask_b32_e64 v120, v120, v122, s[0:1]
	v_cndmask_b32_e32 v122, 0, v179, vcc
	v_sub_f32_e32 v120, v120, v122
	v_mul_f32_e32 v122, 0xbfb8aa3b, v158
	v_exp_f32_e32 v122, v122
	v_exp_f32_e32 v125, v125
	v_mul_f32_e32 v124, 0xbfb8aa3b, v124
	v_exp_f32_e32 v124, v124
	v_add_f32_e32 v122, 1.0, v122
	v_cmp_gt_f32_e32 vcc, s61, v122
	v_add_f32_e32 v125, 1.0, v125
	v_add_f32_e32 v124, 1.0, v124
	v_cndmask_b32_e64 v123, 0, 32, vcc
	v_ldexp_f32 v122, v122, v123
	v_log_f32_e32 v122, v122
	v_mul_f32_e32 v121, 0xbfb8aa3b, v121
	v_exp_f32_e32 v121, v121
	v_sub_f32_e32 v120, -0.5, v120
	v_mul_f32_e32 v123, 0x3f317217, v122
	v_fma_f32 v123, v122, s62, -v123
	v_fmac_f32_e32 v123, 0x3377d1cf, v122
	v_fmac_f32_e32 v123, 0x3f317217, v122
	v_cmp_lt_f32_e64 s[0:1], |v122|, s63
	v_add_f32_e32 v121, 1.0, v121
	v_mul_f32_e32 v120, 0x3fb8aa3b, v120
	v_cndmask_b32_e64 v122, v122, v123, s[0:1]
	v_cndmask_b32_e32 v123, 0, v179, vcc
	v_sub_f32_e32 v122, v122, v123
	v_mul_f32_e32 v123, 0xbfb8aa3b, v159
	v_exp_f32_e32 v123, v123
	v_sub_f32_e32 v122, -0.5, v122
	v_mul_f32_e32 v122, 0x3fb8aa3b, v122
	v_exp_f32_e32 v120, v120
	v_add_f32_e32 v123, 1.0, v123
	v_cmp_gt_f32_e32 vcc, s61, v123
	v_exp_f32_e32 v122, v122
	v_mul_f32_e32 v120, 0xbfb8aa3b, v120
	v_cndmask_b32_e64 v127, 0, 32, vcc
	v_ldexp_f32 v123, v123, v127
	v_log_f32_e32 v123, v123
	v_mul_f32_e32 v122, 0xbfb8aa3b, v122
	v_exp_f32_e32 v120, v120
	v_exp_f32_e32 v122, v122
	v_mul_f32_e32 v127, 0x3f317217, v123
	v_fma_f32 v127, v123, s62, -v127
	v_fmac_f32_e32 v127, 0x3377d1cf, v123
	v_fmac_f32_e32 v127, 0x3f317217, v123
	v_cmp_lt_f32_e64 s[0:1], |v123|, s63
	v_cvt_pk_f16_f32 v122, v120, v122
	s_nop 0
	v_cndmask_b32_e64 v123, v123, v127, s[0:1]
	v_cndmask_b32_e32 v127, 0, v179, vcc
	v_cmp_gt_f32_e32 vcc, s61, v126
	v_sub_f32_e32 v123, v123, v127
	v_sub_f32_e32 v123, -0.5, v123
	v_cndmask_b32_e64 v127, 0, 32, vcc
	v_ldexp_f32 v126, v126, v127
	v_log_f32_e32 v126, v126
	v_mul_f32_e32 v123, 0x3fb8aa3b, v123
	v_exp_f32_e32 v123, v123
	v_mul_f32_e32 v127, 0x3f317217, v126
	v_fma_f32 v127, v126, s62, -v127
	v_fmac_f32_e32 v127, 0x3377d1cf, v126
	v_fmac_f32_e32 v127, 0x3f317217, v126
	v_cmp_lt_f32_e64 s[0:1], |v126|, s63
	v_mul_f32_e32 v123, 0xbfb8aa3b, v123
	v_exp_f32_e32 v123, v123
	v_cndmask_b32_e64 v126, v126, v127, s[0:1]
	v_cndmask_b32_e32 v127, 0, v179, vcc
	v_sub_f32_e32 v126, v126, v127
	v_mul_f32_e32 v127, 0xbfb8aa3b, v139
	v_exp_f32_e32 v127, v127
	v_sub_f32_e32 v126, -0.5, v126
	v_mul_f32_e32 v126, 0x3fb8aa3b, v126
	v_exp_f32_e32 v126, v126
	v_add_f32_e32 v127, 1.0, v127
	v_cmp_gt_f32_e32 vcc, s61, v127
	v_mul_f32_e32 v126, 0xbfb8aa3b, v126
	s_nop 0
	v_cndmask_b32_e64 v139, 0, 32, vcc
	v_ldexp_f32 v127, v127, v139
	v_log_f32_e32 v127, v127
	v_exp_f32_e32 v126, v126
	v_mul_f32_e32 v139, 0x3f317217, v127
	v_fma_f32 v139, v127, s62, -v139
	v_fmac_f32_e32 v139, 0x3377d1cf, v127
	v_fmac_f32_e32 v139, 0x3f317217, v127
	v_cmp_lt_f32_e64 s[0:1], |v127|, s63
	v_cvt_pk_f16_f32 v123, v123, v126
	s_nop 0
	v_cndmask_b32_e64 v127, v127, v139, s[0:1]
	v_cndmask_b32_e32 v139, 0, v179, vcc
	v_cmp_gt_f32_e32 vcc, s61, v125
	v_sub_f32_e32 v127, v127, v139
	v_sub_f32_e32 v127, -0.5, v127
	v_cndmask_b32_e64 v139, 0, 32, vcc
	v_ldexp_f32 v125, v125, v139
	v_log_f32_e32 v125, v125
	v_mul_f32_e32 v127, 0x3fb8aa3b, v127
	v_exp_f32_e32 v127, v127
	v_mul_f32_e32 v139, 0x3f317217, v125
	v_fma_f32 v139, v125, s62, -v139
	v_fmac_f32_e32 v139, 0x3377d1cf, v125
	v_fmac_f32_e32 v139, 0x3f317217, v125
	v_cmp_lt_f32_e64 s[0:1], |v125|, s63
	v_mul_f32_e32 v127, 0xbfb8aa3b, v127
	v_exp_f32_e32 v127, v127
	v_cndmask_b32_e64 v125, v125, v139, s[0:1]
	v_cndmask_b32_e32 v139, 0, v179, vcc
	v_cmp_gt_f32_e32 vcc, s61, v124
	v_sub_f32_e32 v125, v125, v139
	v_sub_f32_e32 v125, -0.5, v125
	v_cndmask_b32_e64 v139, 0, 32, vcc
;     template <int MODE> __device__ __forceinline__ void run(AccRef acc, const Unit& u, int wr, int wc, int fr, int fq) const {
;     ...
;                     for (int e = 0; e < 4; ++e) { x[e] = acc[ai][bj][m][0][e] + bias[e]; x[4 + e] = acc[ai][bj][m][1][e] + bias[4 + e]; }
;     ...
;                     if (MODE == 0) {
; #pragma unroll
;                         for (int e = 0; e < 8; ++e) { const float sp = __logf(1.f + __expf(-x[e])); x[e] = __expf(-__expf(-sp - 0.5f)); }
;                         w.x = pkh(x[0], x[1]); w.y = pkh(x[2], x[3]); w.z = pkh(x[4], x[5]); w.w = pkh(x[6], x[7]);
;                         *(u32x4*)(WA + (size_t)row * 2048 + seg * 512 + cc) = w;
	v_ldexp_f32 v124, v124, v139
	v_log_f32_e32 v124, v124
	v_mul_f32_e32 v125, 0x3fb8aa3b, v125
	v_exp_f32_e32 v125, v125
	v_mul_f32_e32 v139, 0x3f317217, v124
	v_fma_f32 v139, v124, s62, -v139
	v_fmac_f32_e32 v139, 0x3377d1cf, v124
	v_fmac_f32_e32 v139, 0x3f317217, v124
	v_cmp_lt_f32_e64 s[0:1], |v124|, s63
	v_mul_f32_e32 v125, 0xbfb8aa3b, v125
	v_exp_f32_e32 v125, v125
	v_cndmask_b32_e64 v124, v124, v139, s[0:1]
	v_cndmask_b32_e32 v139, 0, v179, vcc
	v_sub_f32_e32 v124, v124, v139
	v_sub_f32_e32 v124, -0.5, v124
	v_mul_f32_e32 v124, 0x3fb8aa3b, v124
	v_exp_f32_e32 v124, v124
	v_cmp_gt_f32_e32 vcc, s61, v121
	v_mul_f32_e32 v124, 0xbfb8aa3b, v124
	v_exp_f32_e32 v139, v124
	v_cndmask_b32_e64 v124, 0, 32, vcc
	v_ldexp_f32 v121, v121, v124
	v_log_f32_e32 v121, v121
	s_nop 0
	v_mul_f32_e32 v124, 0x3f317217, v121
	v_fma_f32 v124, v121, s62, -v124
	v_fmac_f32_e32 v124, 0x3377d1cf, v121
	v_fmac_f32_e32 v124, 0x3f317217, v121
	v_cmp_lt_f32_e64 s[0:1], |v121|, s63
	s_nop 1
	v_cndmask_b32_e64 v121, v121, v124, s[0:1]
	v_cndmask_b32_e32 v124, 0, v179, vcc
	v_sub_f32_e32 v121, v121, v124
	v_sub_f32_e32 v121, -0.5, v121
	v_mul_f32_e32 v121, 0x3fb8aa3b, v121
	v_exp_f32_e32 v121, v121
	v_cvt_pk_f16_f32 v124, v127, v125
	v_mul_f32_e32 v121, 0xbfb8aa3b, v121
	v_exp_f32_e32 v121, v121
	s_nop 0
	v_cvt_pk_f16_f32 v125, v139, v121
	v_ashrrev_i32_e32 v139, 31, v138
	v_lshlrev_b64 v[120:121], 12, v[138:139]
	v_lshl_add_u64 v[120:121], s[48:49], 0, v[120:121]
	v_lshl_add_u64 v[120:121], s[4:5], 1, v[120:121]
	v_lshl_add_u64 v[120:121], v[156:157], 1, v[120:121]
	global_store_dwordx4 v[120:121], v[122:125], off sc1
	v_add_f32_e32 v116, v116, v132
	v_mul_f32_e32 v116, 0xbfb8aa3b, v116
	v_exp_f32_e32 v116, v116
	v_add_f32_e32 v117, v117, v133
	v_mul_f32_e32 v117, 0xbfb8aa3b, v117
	v_exp_f32_e32 v117, v117
	v_add_f32_e32 v116, 1.0, v116
	v_cmp_gt_f32_e32 vcc, s61, v116
	v_add_f32_e32 v118, v118, v134
	v_add_f32_e32 v117, 1.0, v117
	v_cndmask_b32_e64 v122, 0, 32, vcc
	v_ldexp_f32 v116, v116, v122
	v_log_f32_e32 v116, v116
	v_mul_f32_e32 v118, 0xbfb8aa3b, v118
	v_exp_f32_e32 v118, v118
	v_add_f32_e32 v119, v119, v135
	v_mul_f32_e32 v122, 0x3f317217, v116
	v_fma_f32 v122, v116, s62, -v122
	v_fmac_f32_e32 v122, 0x3377d1cf, v116
	v_fmac_f32_e32 v122, 0x3f317217, v116
	v_cmp_lt_f32_e64 s[0:1], |v116|, s63
	v_add_f32_e32 v118, 1.0, v118
	v_mul_f32_e32 v119, 0xbfb8aa3b, v119
	v_cndmask_b32_e64 v116, v116, v122, s[0:1]
	v_cndmask_b32_e32 v122, 0, v179, vcc
	v_cmp_gt_f32_e32 vcc, s61, v117
	v_sub_f32_e32 v116, v116, v122
	v_exp_f32_e32 v119, v119
	v_cndmask_b32_e64 v122, 0, 32, vcc
	v_ldexp_f32 v117, v117, v122
	v_log_f32_e32 v117, v117
	v_add_f32_e32 v119, 1.0, v119
	v_add_f32_e32 v112, v112, v128
	v_mul_f32_e32 v112, 0xbfb8aa3b, v112
	v_mul_f32_e32 v122, 0x3f317217, v117
	v_fma_f32 v122, v117, s62, -v122
	v_fmac_f32_e32 v122, 0x3377d1cf, v117
	v_fmac_f32_e32 v122, 0x3f317217, v117
	v_cmp_lt_f32_e64 s[0:1], |v117|, s63
	v_exp_f32_e32 v112, v112
	v_add_f32_e32 v113, v113, v129
	v_cndmask_b32_e64 v117, v117, v122, s[0:1]
	v_cndmask_b32_e32 v122, 0, v179, vcc
	v_cmp_gt_f32_e32 vcc, s61, v118
	v_sub_f32_e32 v117, v117, v122
	v_add_f32_e32 v112, 1.0, v112
	v_cndmask_b32_e64 v122, 0, 32, vcc
	v_ldexp_f32 v118, v118, v122
	v_log_f32_e32 v118, v118
	v_mul_f32_e32 v113, 0xbfb8aa3b, v113
	v_exp_f32_e32 v113, v113
	v_add_f32_e32 v114, v114, v130
	v_mul_f32_e32 v122, 0x3f317217, v118
	v_fma_f32 v122, v118, s62, -v122
	v_fmac_f32_e32 v122, 0x3377d1cf, v118
	v_fmac_f32_e32 v122, 0x3f317217, v118
	v_cmp_lt_f32_e64 s[0:1], |v118|, s63
	v_add_f32_e32 v113, 1.0, v113
	v_mul_f32_e32 v114, 0xbfb8aa3b, v114
	v_cndmask_b32_e64 v118, v118, v122, s[0:1]
	v_cndmask_b32_e32 v122, 0, v179, vcc
	v_cmp_gt_f32_e32 vcc, s61, v119
	v_sub_f32_e32 v118, v118, v122
	v_exp_f32_e32 v114, v114
	v_cndmask_b32_e64 v122, 0, 32, vcc
	v_ldexp_f32 v119, v119, v122
	v_log_f32_e32 v119, v119
	v_add_f32_e32 v114, 1.0, v114
	v_add_f32_e32 v115, v115, v131
	v_mul_f32_e32 v115, 0xbfb8aa3b, v115
	v_mul_f32_e32 v122, 0x3f317217, v119
	v_fma_f32 v122, v119, s62, -v122
	v_fmac_f32_e32 v122, 0x3377d1cf, v119
	v_fmac_f32_e32 v122, 0x3f317217, v119
	v_cmp_lt_f32_e64 s[0:1], |v119|, s63
	v_exp_f32_e32 v115, v115
	v_sub_f32_e32 v118, -0.5, v118
	v_cndmask_b32_e64 v119, v119, v122, s[0:1]
	v_cndmask_b32_e32 v122, 0, v179, vcc
	v_cmp_gt_f32_e32 vcc, s61, v112
	v_sub_f32_e32 v119, v119, v122
	v_add_f32_e32 v115, 1.0, v115
	v_cndmask_b32_e64 v122, 0, 32, vcc
	v_ldexp_f32 v112, v112, v122
	v_log_f32_e32 v112, v112
	v_sub_f32_e32 v119, -0.5, v119
	v_sub_f32_e32 v116, -0.5, v116
	v_sub_f32_e32 v117, -0.5, v117
	v_mul_f32_e32 v122, 0x3f317217, v112
	v_fma_f32 v122, v112, s62, -v122
	v_fmac_f32_e32 v122, 0x3377d1cf, v112
	v_fmac_f32_e32 v122, 0x3f317217, v112
	v_cmp_lt_f32_e64 s[0:1], |v112|, s63
	v_mul_f32_e32 v118, 0x3fb8aa3b, v118
	v_mul_f32_e32 v119, 0x3fb8aa3b, v119
	v_cndmask_b32_e64 v112, v112, v122, s[0:1]
	v_cndmask_b32_e32 v122, 0, v179, vcc
	v_cmp_gt_f32_e32 vcc, s61, v113
	v_sub_f32_e32 v112, v112, v122
	v_sub_f32_e32 v112, -0.5, v112
	v_cndmask_b32_e64 v122, 0, 32, vcc
	v_ldexp_f32 v113, v113, v122
	v_log_f32_e32 v113, v113
	v_mul_f32_e32 v116, 0x3fb8aa3b, v116
	v_mul_f32_e32 v117, 0x3fb8aa3b, v117
	v_exp_f32_e32 v118, v118
	v_mul_f32_e32 v122, 0x3f317217, v113
	v_fma_f32 v122, v113, s62, -v122
	v_fmac_f32_e32 v122, 0x3377d1cf, v113
	v_fmac_f32_e32 v122, 0x3f317217, v113
	v_cmp_lt_f32_e64 s[0:1], |v113|, s63
	v_exp_f32_e32 v119, v119
	v_mul_f32_e32 v112, 0x3fb8aa3b, v112
	v_cndmask_b32_e64 v113, v113, v122, s[0:1]
	v_cndmask_b32_e32 v122, 0, v179, vcc
	v_cmp_gt_f32_e32 vcc, s61, v114
	v_sub_f32_e32 v113, v113, v122
;     template <int MODE> __device__ __forceinline__ void run(AccRef acc, const Unit& u, int wr, int wc, int fr, int fq) const {
;     ...
;                     for (int e = 0; e < 4; ++e) { x[e] = acc[ai][bj][m][0][e] + bias[e]; x[4 + e] = acc[ai][bj][m][1][e] + bias[4 + e]; }
;     ...
;                     if (MODE == 0) {
; #pragma unroll
;                         for (int e = 0; e < 8; ++e) { const float sp = __logf(1.f + __expf(-x[e])); x[e] = __expf(-__expf(-sp - 0.5f)); }
;                         w.x = pkh(x[0], x[1]); w.y = pkh(x[2], x[3]); w.z = pkh(x[4], x[5]); w.w = pkh(x[6], x[7]);
;                         *(u32x4*)(WA + (size_t)row * 2048 + seg * 512 + cc) = w;
	v_sub_f32_e32 v113, -0.5, v113
	v_cndmask_b32_e64 v122, 0, 32, vcc
	v_ldexp_f32 v114, v114, v122
	v_log_f32_e32 v114, v114
	v_mul_f32_e32 v113, 0x3fb8aa3b, v113
	v_exp_f32_e32 v116, v116
	v_exp_f32_e32 v117, v117
	v_mul_f32_e32 v122, 0x3f317217, v114
	v_fma_f32 v122, v114, s62, -v122
	v_fmac_f32_e32 v122, 0x3377d1cf, v114
	v_fmac_f32_e32 v122, 0x3f317217, v114
	v_cmp_lt_f32_e64 s[0:1], |v114|, s63
	v_exp_f32_e32 v112, v112
	v_exp_f32_e32 v113, v113
	v_cndmask_b32_e64 v114, v114, v122, s[0:1]
	v_cndmask_b32_e32 v122, 0, v179, vcc
	v_cmp_gt_f32_e32 vcc, s61, v115
	v_sub_f32_e32 v114, v114, v122
	v_sub_f32_e32 v114, -0.5, v114
	v_cndmask_b32_e64 v122, 0, 32, vcc
	v_ldexp_f32 v115, v115, v122
	v_log_f32_e32 v115, v115
	v_mul_f32_e32 v114, 0x3fb8aa3b, v114
	v_exp_f32_e32 v114, v114
	v_mul_f32_e32 v118, 0xbfb8aa3b, v118
	v_mul_f32_e32 v122, 0x3f317217, v115
	v_fma_f32 v122, v115, s62, -v122
	v_fmac_f32_e32 v122, 0x3377d1cf, v115
	v_fmac_f32_e32 v122, 0x3f317217, v115
	v_cmp_lt_f32_e64 s[0:1], |v115|, s63
	v_mul_f32_e32 v119, 0xbfb8aa3b, v119
	v_mul_f32_e32 v114, 0xbfb8aa3b, v114
	v_cndmask_b32_e64 v115, v115, v122, s[0:1]
	v_cndmask_b32_e32 v122, 0, v179, vcc
	v_sub_f32_e32 v115, v115, v122
	v_sub_f32_e32 v115, -0.5, v115
	v_mul_f32_e32 v115, 0x3fb8aa3b, v115
	v_exp_f32_e32 v115, v115
	v_mul_f32_e32 v116, 0xbfb8aa3b, v116
	v_mul_f32_e32 v117, 0xbfb8aa3b, v117
	v_exp_f32_e32 v118, v118
	v_exp_f32_e32 v119, v119
	v_mul_f32_e32 v112, 0xbfb8aa3b, v112
	v_mul_f32_e32 v113, 0xbfb8aa3b, v113
	v_exp_f32_e32 v122, v114
	v_mul_f32_e32 v114, 0xbfb8aa3b, v115
	v_exp_f32_e32 v116, v116
	v_exp_f32_e32 v117, v117
	v_exp_f32_e32 v112, v112
	v_exp_f32_e32 v113, v113
	v_exp_f32_e32 v123, v114
	s_mov_b32 s0, 0x10000
	v_cvt_pk_f16_f32 v115, v118, v119
	v_add_co_u32_e32 v118, vcc, s0, v120
	v_cvt_pk_f16_f32 v114, v116, v117
	v_cvt_pk_f16_f32 v116, v112, v113
	v_cvt_pk_f16_f32 v117, v122, v123
	v_addc_co_u32_e32 v119, vcc, 0, v121, vcc
	v_lshl_add_u64 v[112:113], v[120:121], 0, s[58:59]
	global_store_dwordx4 v[118:119], v[114:117], off sc1
	v_add_f32_e32 v108, v108, v132
	v_mul_f32_e32 v108, 0xbfb8aa3b, v108
	v_exp_f32_e32 v108, v108
	v_add_f32_e32 v109, v109, v133
	v_mul_f32_e32 v109, 0xbfb8aa3b, v109
	v_exp_f32_e32 v109, v109
	v_add_f32_e32 v108, 1.0, v108
	v_cmp_gt_f32_e32 vcc, s61, v108
	v_add_f32_e32 v110, v110, v134
	v_add_f32_e32 v109, 1.0, v109
	v_cndmask_b32_e64 v114, 0, 32, vcc
	v_ldexp_f32 v108, v108, v114
	v_log_f32_e32 v108, v108
	v_mul_f32_e32 v110, 0xbfb8aa3b, v110
	v_exp_f32_e32 v110, v110
	v_add_f32_e32 v111, v111, v135
	v_mul_f32_e32 v114, 0x3f317217, v108
	v_fma_f32 v114, v108, s62, -v114
	v_fmac_f32_e32 v114, 0x3377d1cf, v108
	v_fmac_f32_e32 v114, 0x3f317217, v108
	v_cmp_lt_f32_e64 s[0:1], |v108|, s63
	v_add_f32_e32 v110, 1.0, v110
	v_mul_f32_e32 v111, 0xbfb8aa3b, v111
	v_cndmask_b32_e64 v108, v108, v114, s[0:1]
	v_cndmask_b32_e32 v114, 0, v179, vcc
	v_cmp_gt_f32_e32 vcc, s61, v109
	v_sub_f32_e32 v108, v108, v114
	v_exp_f32_e32 v111, v111
	v_cndmask_b32_e64 v114, 0, 32, vcc
	v_ldexp_f32 v109, v109, v114
	v_log_f32_e32 v109, v109
	v_add_f32_e32 v111, 1.0, v111
	v_add_f32_e32 v104, v104, v128
	v_mul_f32_e32 v104, 0xbfb8aa3b, v104
	v_mul_f32_e32 v114, 0x3f317217, v109
	v_fma_f32 v114, v109, s62, -v114
	v_fmac_f32_e32 v114, 0x3377d1cf, v109
	v_fmac_f32_e32 v114, 0x3f317217, v109
	v_cmp_lt_f32_e64 s[0:1], |v109|, s63
	v_exp_f32_e32 v104, v104
	v_add_f32_e32 v105, v105, v129
	v_cndmask_b32_e64 v109, v109, v114, s[0:1]
	v_cndmask_b32_e32 v114, 0, v179, vcc
	v_cmp_gt_f32_e32 vcc, s61, v110
	v_sub_f32_e32 v109, v109, v114
	v_add_f32_e32 v104, 1.0, v104
	v_cndmask_b32_e64 v114, 0, 32, vcc
	v_ldexp_f32 v110, v110, v114
	v_log_f32_e32 v110, v110
	v_mul_f32_e32 v105, 0xbfb8aa3b, v105
	v_exp_f32_e32 v105, v105
	v_add_f32_e32 v106, v106, v130
	v_mul_f32_e32 v114, 0x3f317217, v110
	v_fma_f32 v114, v110, s62, -v114
	v_fmac_f32_e32 v114, 0x3377d1cf, v110
	v_fmac_f32_e32 v114, 0x3f317217, v110
	v_cmp_lt_f32_e64 s[0:1], |v110|, s63
	v_add_f32_e32 v105, 1.0, v105
	v_mul_f32_e32 v106, 0xbfb8aa3b, v106
	v_cndmask_b32_e64 v110, v110, v114, s[0:1]
	v_cndmask_b32_e32 v114, 0, v179, vcc
	v_cmp_gt_f32_e32 vcc, s61, v111
	v_sub_f32_e32 v110, v110, v114
	v_exp_f32_e32 v106, v106
	v_cndmask_b32_e64 v114, 0, 32, vcc
	v_ldexp_f32 v111, v111, v114
	v_log_f32_e32 v111, v111
	v_add_f32_e32 v106, 1.0, v106
	v_add_f32_e32 v107, v107, v131
	v_mul_f32_e32 v107, 0xbfb8aa3b, v107
	v_mul_f32_e32 v114, 0x3f317217, v111
	v_fma_f32 v114, v111, s62, -v114
	v_fmac_f32_e32 v114, 0x3377d1cf, v111
	v_fmac_f32_e32 v114, 0x3f317217, v111
	v_cmp_lt_f32_e64 s[0:1], |v111|, s63
	v_exp_f32_e32 v107, v107
	v_sub_f32_e32 v110, -0.5, v110
	v_cndmask_b32_e64 v111, v111, v114, s[0:1]
	v_cndmask_b32_e32 v114, 0, v179, vcc
	v_cmp_gt_f32_e32 vcc, s61, v104
	v_sub_f32_e32 v111, v111, v114
	v_add_f32_e32 v107, 1.0, v107
	v_cndmask_b32_e64 v114, 0, 32, vcc
	v_ldexp_f32 v104, v104, v114
	v_log_f32_e32 v104, v104
	v_sub_f32_e32 v111, -0.5, v111
	v_sub_f32_e32 v108, -0.5, v108
	v_sub_f32_e32 v109, -0.5, v109
	v_mul_f32_e32 v114, 0x3f317217, v104
	v_fma_f32 v114, v104, s62, -v114
	v_fmac_f32_e32 v114, 0x3377d1cf, v104
	v_fmac_f32_e32 v114, 0x3f317217, v104
	v_cmp_lt_f32_e64 s[0:1], |v104|, s63
	v_mul_f32_e32 v110, 0x3fb8aa3b, v110
	v_mul_f32_e32 v111, 0x3fb8aa3b, v111
	v_cndmask_b32_e64 v104, v104, v114, s[0:1]
	v_cndmask_b32_e32 v114, 0, v179, vcc
	v_cmp_gt_f32_e32 vcc, s61, v105
	v_sub_f32_e32 v104, v104, v114
	v_sub_f32_e32 v104, -0.5, v104
	v_cndmask_b32_e64 v114, 0, 32, vcc
	v_ldexp_f32 v105, v105, v114
	v_log_f32_e32 v105, v105
	v_mul_f32_e32 v108, 0x3fb8aa3b, v108
	v_mul_f32_e32 v109, 0x3fb8aa3b, v109
;     template <int MODE> __device__ __forceinline__ void run(AccRef acc, const Unit& u, int wr, int wc, int fr, int fq) const {
;     ...
;                     for (int e = 0; e < 4; ++e) { x[e] = acc[ai][bj][m][0][e] + bias[e]; x[4 + e] = acc[ai][bj][m][1][e] + bias[4 + e]; }
;     ...
;                     if (MODE == 0) {
; #pragma unroll
;                         for (int e = 0; e < 8; ++e) { const float sp = __logf(1.f + __expf(-x[e])); x[e] = __expf(-__expf(-sp - 0.5f)); }
;                         w.x = pkh(x[0], x[1]); w.y = pkh(x[2], x[3]); w.z = pkh(x[4], x[5]); w.w = pkh(x[6], x[7]);
;                         *(u32x4*)(WA + (size_t)row * 2048 + seg * 512 + cc) = w;
	v_exp_f32_e32 v110, v110
	v_mul_f32_e32 v114, 0x3f317217, v105
	v_fma_f32 v114, v105, s62, -v114
	v_fmac_f32_e32 v114, 0x3377d1cf, v105
	v_fmac_f32_e32 v114, 0x3f317217, v105
	v_cmp_lt_f32_e64 s[0:1], |v105|, s63
	v_exp_f32_e32 v111, v111
	v_mul_f32_e32 v104, 0x3fb8aa3b, v104
	v_cndmask_b32_e64 v105, v105, v114, s[0:1]
	v_cndmask_b32_e32 v114, 0, v179, vcc
	v_cmp_gt_f32_e32 vcc, s61, v106
	v_sub_f32_e32 v105, v105, v114
	v_sub_f32_e32 v105, -0.5, v105
	v_cndmask_b32_e64 v114, 0, 32, vcc
	v_ldexp_f32 v106, v106, v114
	v_log_f32_e32 v106, v106
	v_mul_f32_e32 v105, 0x3fb8aa3b, v105
	v_exp_f32_e32 v108, v108
	v_exp_f32_e32 v109, v109
	v_mul_f32_e32 v114, 0x3f317217, v106
	v_fma_f32 v114, v106, s62, -v114
	v_fmac_f32_e32 v114, 0x3377d1cf, v106
	v_fmac_f32_e32 v114, 0x3f317217, v106
	v_cmp_lt_f32_e64 s[0:1], |v106|, s63
	v_exp_f32_e32 v104, v104
	v_exp_f32_e32 v105, v105
	v_cndmask_b32_e64 v106, v106, v114, s[0:1]
	v_cndmask_b32_e32 v114, 0, v179, vcc
	v_cmp_gt_f32_e32 vcc, s61, v107
	v_sub_f32_e32 v106, v106, v114
	v_sub_f32_e32 v106, -0.5, v106
	v_cndmask_b32_e64 v114, 0, 32, vcc
	v_ldexp_f32 v107, v107, v114
	v_log_f32_e32 v107, v107
	v_mul_f32_e32 v106, 0x3fb8aa3b, v106
	v_exp_f32_e32 v106, v106
	v_mul_f32_e32 v110, 0xbfb8aa3b, v110
	v_mul_f32_e32 v114, 0x3f317217, v107
	v_fma_f32 v114, v107, s62, -v114
	v_fmac_f32_e32 v114, 0x3377d1cf, v107
	v_fmac_f32_e32 v114, 0x3f317217, v107
	v_cmp_lt_f32_e64 s[0:1], |v107|, s63
	v_mul_f32_e32 v111, 0xbfb8aa3b, v111
	v_mul_f32_e32 v106, 0xbfb8aa3b, v106
	v_cndmask_b32_e64 v107, v107, v114, s[0:1]
	v_cndmask_b32_e32 v114, 0, v179, vcc
	v_sub_f32_e32 v107, v107, v114
	v_sub_f32_e32 v107, -0.5, v107
	v_mul_f32_e32 v107, 0x3fb8aa3b, v107
	v_exp_f32_e32 v107, v107
	v_mul_f32_e32 v108, 0xbfb8aa3b, v108
	v_mul_f32_e32 v109, 0xbfb8aa3b, v109
	v_exp_f32_e32 v110, v110
	v_exp_f32_e32 v111, v111
	v_mul_f32_e32 v104, 0xbfb8aa3b, v104
	v_mul_f32_e32 v105, 0xbfb8aa3b, v105
	v_exp_f32_e32 v114, v106
	v_mul_f32_e32 v106, 0xbfb8aa3b, v107
	v_exp_f32_e32 v108, v108
	v_exp_f32_e32 v109, v109
	v_exp_f32_e32 v104, v104
	v_exp_f32_e32 v105, v105
	v_exp_f32_e32 v115, v106
	s_mov_b32 s0, 0x20000
	v_cvt_pk_f16_f32 v107, v110, v111
	v_add_co_u32_e32 v110, vcc, s0, v120
	v_cvt_pk_f16_f32 v106, v108, v109
	v_cvt_pk_f16_f32 v108, v104, v105
	v_cvt_pk_f16_f32 v109, v114, v115
	v_addc_co_u32_e32 v111, vcc, 0, v121, vcc
	v_lshl_add_u64 v[104:105], v[120:121], 0, s[46:47]
	global_store_dwordx4 v[110:111], v[106:109], off sc1
	v_add_f32_e32 v100, v100, v132
	v_mul_f32_e32 v100, 0xbfb8aa3b, v100
	v_exp_f32_e32 v100, v100
	v_add_f32_e32 v101, v101, v133
	v_mul_f32_e32 v101, 0xbfb8aa3b, v101
	v_exp_f32_e32 v101, v101
	v_add_f32_e32 v100, 1.0, v100
	v_cmp_gt_f32_e32 vcc, s61, v100
	v_add_f32_e32 v102, v102, v134
	v_add_f32_e32 v101, 1.0, v101
	v_cndmask_b32_e64 v106, 0, 32, vcc
	v_ldexp_f32 v100, v100, v106
	v_log_f32_e32 v100, v100
	v_mul_f32_e32 v102, 0xbfb8aa3b, v102
	v_exp_f32_e32 v102, v102
	v_add_f32_e32 v103, v103, v135
	v_mul_f32_e32 v106, 0x3f317217, v100
	v_fma_f32 v106, v100, s62, -v106
	v_fmac_f32_e32 v106, 0x3377d1cf, v100
	v_fmac_f32_e32 v106, 0x3f317217, v100
	v_cmp_lt_f32_e64 s[0:1], |v100|, s63
	v_add_f32_e32 v102, 1.0, v102
	v_mul_f32_e32 v103, 0xbfb8aa3b, v103
	v_cndmask_b32_e64 v100, v100, v106, s[0:1]
	v_cndmask_b32_e32 v106, 0, v179, vcc
	v_cmp_gt_f32_e32 vcc, s61, v101
	v_sub_f32_e32 v100, v100, v106
	v_exp_f32_e32 v103, v103
	v_cndmask_b32_e64 v106, 0, 32, vcc
	v_ldexp_f32 v101, v101, v106
	v_log_f32_e32 v101, v101
	v_add_f32_e32 v103, 1.0, v103
	v_add_f32_e32 v96, v96, v128
	v_mul_f32_e32 v96, 0xbfb8aa3b, v96
	v_mul_f32_e32 v106, 0x3f317217, v101
	v_fma_f32 v106, v101, s62, -v106
	v_fmac_f32_e32 v106, 0x3377d1cf, v101
	v_fmac_f32_e32 v106, 0x3f317217, v101
	v_cmp_lt_f32_e64 s[0:1], |v101|, s63
	v_exp_f32_e32 v96, v96
	v_add_f32_e32 v97, v97, v129
	v_cndmask_b32_e64 v101, v101, v106, s[0:1]
	v_cndmask_b32_e32 v106, 0, v179, vcc
	v_cmp_gt_f32_e32 vcc, s61, v102
	v_sub_f32_e32 v101, v101, v106
	v_add_f32_e32 v96, 1.0, v96
	v_cndmask_b32_e64 v106, 0, 32, vcc
	v_ldexp_f32 v102, v102, v106
	v_log_f32_e32 v102, v102
	v_mul_f32_e32 v97, 0xbfb8aa3b, v97
	v_exp_f32_e32 v97, v97
	v_add_f32_e32 v98, v98, v130
	v_mul_f32_e32 v106, 0x3f317217, v102
	v_fma_f32 v106, v102, s62, -v106
	v_fmac_f32_e32 v106, 0x3377d1cf, v102
	v_fmac_f32_e32 v106, 0x3f317217, v102
	v_cmp_lt_f32_e64 s[0:1], |v102|, s63
	v_add_f32_e32 v97, 1.0, v97
	v_mul_f32_e32 v98, 0xbfb8aa3b, v98
	v_cndmask_b32_e64 v102, v102, v106, s[0:1]
	v_cndmask_b32_e32 v106, 0, v179, vcc
	v_cmp_gt_f32_e32 vcc, s61, v103
	v_sub_f32_e32 v102, v102, v106
	v_exp_f32_e32 v98, v98
	v_cndmask_b32_e64 v106, 0, 32, vcc
	v_ldexp_f32 v103, v103, v106
	v_log_f32_e32 v103, v103
	v_add_f32_e32 v98, 1.0, v98
	v_add_f32_e32 v99, v99, v131
	v_mul_f32_e32 v99, 0xbfb8aa3b, v99
	v_mul_f32_e32 v106, 0x3f317217, v103
	v_fma_f32 v106, v103, s62, -v106
	v_fmac_f32_e32 v106, 0x3377d1cf, v103
	v_fmac_f32_e32 v106, 0x3f317217, v103
	v_cmp_lt_f32_e64 s[0:1], |v103|, s63
	v_exp_f32_e32 v99, v99
	v_sub_f32_e32 v100, -0.5, v100
	v_cndmask_b32_e64 v103, v103, v106, s[0:1]
	v_cndmask_b32_e32 v106, 0, v179, vcc
	v_cmp_gt_f32_e32 vcc, s61, v96
	v_sub_f32_e32 v103, v103, v106
	v_add_f32_e32 v99, 1.0, v99
	v_cndmask_b32_e64 v106, 0, 32, vcc
	v_ldexp_f32 v96, v96, v106
	v_log_f32_e32 v96, v96
	v_sub_f32_e32 v101, -0.5, v101
	v_mul_f32_e32 v100, 0x3fb8aa3b, v100
	v_mul_f32_e32 v101, 0x3fb8aa3b, v101
	v_mul_f32_e32 v106, 0x3f317217, v96
	v_fma_f32 v106, v96, s62, -v106
	v_fmac_f32_e32 v106, 0x3377d1cf, v96
	v_fmac_f32_e32 v106, 0x3f317217, v96
	v_cmp_lt_f32_e64 s[0:1], |v96|, s63
	v_sub_f32_e32 v102, -0.5, v102
;     template <int MODE> __device__ __forceinline__ void run(AccRef acc, const Unit& u, int wr, int wc, int fr, int fq) const {
;     ...
;                     for (int e = 0; e < 4; ++e) { x[e] = acc[ai][bj][m][0][e] + bias[e]; x[4 + e] = acc[ai][bj][m][1][e] + bias[4 + e]; }
;     ...
;                     if (MODE == 0) {
; #pragma unroll
;                         for (int e = 0; e < 8; ++e) { const float sp = __logf(1.f + __expf(-x[e])); x[e] = __expf(-__expf(-sp - 0.5f)); }
;                         w.x = pkh(x[0], x[1]); w.y = pkh(x[2], x[3]); w.z = pkh(x[4], x[5]); w.w = pkh(x[6], x[7]);
;                         *(u32x4*)(WA + (size_t)row * 2048 + seg * 512 + cc) = w;
	v_sub_f32_e32 v103, -0.5, v103
	v_cndmask_b32_e64 v96, v96, v106, s[0:1]
	v_cndmask_b32_e32 v106, 0, v179, vcc
	v_cmp_gt_f32_e32 vcc, s61, v97
	v_sub_f32_e32 v96, v96, v106
	v_sub_f32_e32 v96, -0.5, v96
	v_cndmask_b32_e64 v106, 0, 32, vcc
	v_ldexp_f32 v97, v97, v106
	v_log_f32_e32 v97, v97
	v_mul_f32_e32 v96, 0x3fb8aa3b, v96
	v_exp_f32_e32 v100, v100
	v_exp_f32_e32 v101, v101
	v_mul_f32_e32 v106, 0x3f317217, v97
	v_fma_f32 v106, v97, s62, -v106
	v_fmac_f32_e32 v106, 0x3377d1cf, v97
	v_fmac_f32_e32 v106, 0x3f317217, v97
	v_cmp_lt_f32_e64 s[0:1], |v97|, s63
	v_mul_f32_e32 v102, 0x3fb8aa3b, v102
	v_mul_f32_e32 v103, 0x3fb8aa3b, v103
	v_cndmask_b32_e64 v97, v97, v106, s[0:1]
	v_cndmask_b32_e32 v106, 0, v179, vcc
	v_cmp_gt_f32_e32 vcc, s61, v98
	v_sub_f32_e32 v97, v97, v106
	v_sub_f32_e32 v97, -0.5, v97
	v_cndmask_b32_e64 v106, 0, 32, vcc
	v_ldexp_f32 v98, v98, v106
	v_log_f32_e32 v98, v98
	v_mul_f32_e32 v97, 0x3fb8aa3b, v97
	v_exp_f32_e32 v96, v96
	v_exp_f32_e32 v97, v97
	v_mul_f32_e32 v106, 0x3f317217, v98
	v_fma_f32 v106, v98, s62, -v106
	v_fmac_f32_e32 v106, 0x3377d1cf, v98
	v_fmac_f32_e32 v106, 0x3f317217, v98
	v_cmp_lt_f32_e64 s[0:1], |v98|, s63
	v_exp_f32_e32 v102, v102
	v_exp_f32_e32 v103, v103
	v_cndmask_b32_e64 v98, v98, v106, s[0:1]
	v_cndmask_b32_e32 v106, 0, v179, vcc
	v_cmp_gt_f32_e32 vcc, s61, v99
	v_sub_f32_e32 v98, v98, v106
	v_sub_f32_e32 v98, -0.5, v98
	v_cndmask_b32_e64 v106, 0, 32, vcc
	v_ldexp_f32 v99, v99, v106
	v_log_f32_e32 v99, v99
	v_mul_f32_e32 v98, 0x3fb8aa3b, v98
	v_exp_f32_e32 v98, v98
	v_mul_f32_e32 v100, 0xbfb8aa3b, v100
	v_mul_f32_e32 v106, 0x3f317217, v99
	v_fma_f32 v106, v99, s62, -v106
	v_fmac_f32_e32 v106, 0x3377d1cf, v99
	v_fmac_f32_e32 v106, 0x3f317217, v99
	v_cmp_lt_f32_e64 s[0:1], |v99|, s63
	v_mul_f32_e32 v101, 0xbfb8aa3b, v101
	v_mul_f32_e32 v96, 0xbfb8aa3b, v96
	v_cndmask_b32_e64 v99, v99, v106, s[0:1]
	v_cndmask_b32_e32 v106, 0, v179, vcc
	v_sub_f32_e32 v99, v99, v106
	v_sub_f32_e32 v99, -0.5, v99
	v_mul_f32_e32 v99, 0x3fb8aa3b, v99
	v_exp_f32_e32 v99, v99
	v_mul_f32_e32 v97, 0xbfb8aa3b, v97
	v_exp_f32_e32 v100, v100
	v_exp_f32_e32 v101, v101
	v_mul_f32_e32 v102, 0xbfb8aa3b, v102
	v_mul_f32_e32 v103, 0xbfb8aa3b, v103
	v_exp_f32_e32 v96, v96
	v_exp_f32_e32 v97, v97
	v_mul_f32_e32 v98, 0xbfb8aa3b, v98
	v_exp_f32_e32 v102, v102
	v_exp_f32_e32 v103, v103
	v_exp_f32_e32 v106, v98
	v_mul_f32_e32 v98, 0xbfb8aa3b, v99
	v_exp_f32_e32 v107, v98
	s_mov_b64 s[0:1], 0x30000
	v_cvt_pk_f16_f32 v98, v100, v101
	v_cvt_pk_f16_f32 v100, v96, v97
	v_lshl_add_u64 v[96:97], v[120:121], 0, s[0:1]
	s_mov_b32 s0, 0x30000
	v_cvt_pk_f16_f32 v99, v102, v103
	v_add_co_u32_e32 v102, vcc, s0, v120
	v_cvt_pk_f16_f32 v101, v106, v107
	s_nop 0
	v_addc_co_u32_e32 v103, vcc, 0, v121, vcc
	global_store_dwordx4 v[102:103], v[98:101], off sc1
	v_add_f32_e32 v92, v92, v132
	v_mul_f32_e32 v92, 0xbfb8aa3b, v92
	v_exp_f32_e32 v92, v92
	v_add_f32_e32 v93, v93, v133
	v_mul_f32_e32 v93, 0xbfb8aa3b, v93
	v_exp_f32_e32 v93, v93
	v_add_f32_e32 v92, 1.0, v92
	v_cmp_gt_f32_e32 vcc, s61, v92
	v_add_f32_e32 v94, v94, v134
	v_add_f32_e32 v93, 1.0, v93
	v_cndmask_b32_e64 v98, 0, 32, vcc
	v_ldexp_f32 v92, v92, v98
	v_log_f32_e32 v92, v92
	v_mul_f32_e32 v94, 0xbfb8aa3b, v94
	v_exp_f32_e32 v94, v94
	v_add_f32_e32 v95, v95, v135
	v_mul_f32_e32 v98, 0x3f317217, v92
	v_fma_f32 v98, v92, s62, -v98
	v_fmac_f32_e32 v98, 0x3377d1cf, v92
	v_fmac_f32_e32 v98, 0x3f317217, v92
	v_cmp_lt_f32_e64 s[0:1], |v92|, s63
	v_add_f32_e32 v94, 1.0, v94
	v_mul_f32_e32 v95, 0xbfb8aa3b, v95
	v_cndmask_b32_e64 v92, v92, v98, s[0:1]
	v_cndmask_b32_e32 v98, 0, v179, vcc
	v_cmp_gt_f32_e32 vcc, s61, v93
	v_sub_f32_e32 v92, v92, v98
	v_exp_f32_e32 v95, v95
	v_cndmask_b32_e64 v98, 0, 32, vcc
	v_ldexp_f32 v93, v93, v98
	v_log_f32_e32 v93, v93
	v_add_f32_e32 v95, 1.0, v95
	v_add_f32_e32 v88, v88, v128
	v_mul_f32_e32 v88, 0xbfb8aa3b, v88
	v_mul_f32_e32 v98, 0x3f317217, v93
	v_fma_f32 v98, v93, s62, -v98
	v_fmac_f32_e32 v98, 0x3377d1cf, v93
	v_fmac_f32_e32 v98, 0x3f317217, v93
	v_cmp_lt_f32_e64 s[0:1], |v93|, s63
	v_exp_f32_e32 v88, v88
	v_add_f32_e32 v89, v89, v129
	v_cndmask_b32_e64 v93, v93, v98, s[0:1]
	v_cndmask_b32_e32 v98, 0, v179, vcc
	v_cmp_gt_f32_e32 vcc, s61, v94
	v_sub_f32_e32 v93, v93, v98
	v_add_f32_e32 v88, 1.0, v88
	v_cndmask_b32_e64 v98, 0, 32, vcc
	v_ldexp_f32 v94, v94, v98
	v_log_f32_e32 v94, v94
	v_mul_f32_e32 v89, 0xbfb8aa3b, v89
	v_exp_f32_e32 v89, v89
	v_add_f32_e32 v90, v90, v130
	v_mul_f32_e32 v98, 0x3f317217, v94
	v_fma_f32 v98, v94, s62, -v98
	v_fmac_f32_e32 v98, 0x3377d1cf, v94
	v_fmac_f32_e32 v98, 0x3f317217, v94
	v_cmp_lt_f32_e64 s[0:1], |v94|, s63
	v_add_f32_e32 v89, 1.0, v89
	v_mul_f32_e32 v90, 0xbfb8aa3b, v90
	v_cndmask_b32_e64 v94, v94, v98, s[0:1]
	v_cndmask_b32_e32 v98, 0, v179, vcc
	v_cmp_gt_f32_e32 vcc, s61, v95
	v_sub_f32_e32 v94, v94, v98
	v_exp_f32_e32 v90, v90
	v_cndmask_b32_e64 v98, 0, 32, vcc
	v_ldexp_f32 v95, v95, v98
	v_log_f32_e32 v95, v95
	v_add_f32_e32 v90, 1.0, v90
	v_add_f32_e32 v91, v91, v131
	v_mul_f32_e32 v91, 0xbfb8aa3b, v91
	v_mul_f32_e32 v98, 0x3f317217, v95
	v_fma_f32 v98, v95, s62, -v98
	v_fmac_f32_e32 v98, 0x3377d1cf, v95
	v_fmac_f32_e32 v98, 0x3f317217, v95
	v_cmp_lt_f32_e64 s[0:1], |v95|, s63
	v_exp_f32_e32 v91, v91
	v_sub_f32_e32 v92, -0.5, v92
	v_cndmask_b32_e64 v95, v95, v98, s[0:1]
	v_cndmask_b32_e32 v98, 0, v179, vcc
	v_cmp_gt_f32_e32 vcc, s61, v88
	v_sub_f32_e32 v95, v95, v98
	v_add_f32_e32 v91, 1.0, v91
	v_cndmask_b32_e64 v98, 0, 32, vcc
	v_ldexp_f32 v88, v88, v98
	v_log_f32_e32 v88, v88
	v_sub_f32_e32 v93, -0.5, v93
	v_mul_f32_e32 v92, 0x3fb8aa3b, v92
	v_mul_f32_e32 v93, 0x3fb8aa3b, v93
	v_mul_f32_e32 v98, 0x3f317217, v88
;     template <int MODE> __device__ __forceinline__ void run(AccRef acc, const Unit& u, int wr, int wc, int fr, int fq) const {
;     ...
;                     for (int e = 0; e < 4; ++e) { x[e] = acc[ai][bj][m][0][e] + bias[e]; x[4 + e] = acc[ai][bj][m][1][e] + bias[4 + e]; }
;     ...
;                     if (MODE == 0) {
; #pragma unroll
;                         for (int e = 0; e < 8; ++e) { const float sp = __logf(1.f + __expf(-x[e])); x[e] = __expf(-__expf(-sp - 0.5f)); }
;                         w.x = pkh(x[0], x[1]); w.y = pkh(x[2], x[3]); w.z = pkh(x[4], x[5]); w.w = pkh(x[6], x[7]);
;                         *(u32x4*)(WA + (size_t)row * 2048 + seg * 512 + cc) = w;
	v_fma_f32 v98, v88, s62, -v98
	v_fmac_f32_e32 v98, 0x3377d1cf, v88
	v_fmac_f32_e32 v98, 0x3f317217, v88
	v_cmp_lt_f32_e64 s[0:1], |v88|, s63
	v_sub_f32_e32 v94, -0.5, v94
	v_sub_f32_e32 v95, -0.5, v95
	v_cndmask_b32_e64 v88, v88, v98, s[0:1]
	v_cndmask_b32_e32 v98, 0, v179, vcc
	v_cmp_gt_f32_e32 vcc, s61, v89
	v_sub_f32_e32 v88, v88, v98
	v_sub_f32_e32 v88, -0.5, v88
	v_cndmask_b32_e64 v98, 0, 32, vcc
	v_ldexp_f32 v89, v89, v98
	v_log_f32_e32 v89, v89
	v_mul_f32_e32 v88, 0x3fb8aa3b, v88
	v_exp_f32_e32 v92, v92
	v_exp_f32_e32 v93, v93
	v_mul_f32_e32 v98, 0x3f317217, v89
	v_fma_f32 v98, v89, s62, -v98
	v_fmac_f32_e32 v98, 0x3377d1cf, v89
	v_fmac_f32_e32 v98, 0x3f317217, v89
	v_cmp_lt_f32_e64 s[0:1], |v89|, s63
	v_mul_f32_e32 v94, 0x3fb8aa3b, v94
	v_mul_f32_e32 v95, 0x3fb8aa3b, v95
	v_cndmask_b32_e64 v89, v89, v98, s[0:1]
	v_cndmask_b32_e32 v98, 0, v179, vcc
	v_cmp_gt_f32_e32 vcc, s61, v90
	v_sub_f32_e32 v89, v89, v98
	v_sub_f32_e32 v89, -0.5, v89
	v_cndmask_b32_e64 v98, 0, 32, vcc
	v_ldexp_f32 v90, v90, v98
	v_log_f32_e32 v90, v90
	v_mul_f32_e32 v89, 0x3fb8aa3b, v89
	v_exp_f32_e32 v88, v88
	v_exp_f32_e32 v89, v89
	v_mul_f32_e32 v98, 0x3f317217, v90
	v_fma_f32 v98, v90, s62, -v98
	v_fmac_f32_e32 v98, 0x3377d1cf, v90
	v_fmac_f32_e32 v98, 0x3f317217, v90
	v_cmp_lt_f32_e64 s[0:1], |v90|, s63
	v_exp_f32_e32 v94, v94
	v_exp_f32_e32 v95, v95
	v_cndmask_b32_e64 v90, v90, v98, s[0:1]
	v_cndmask_b32_e32 v98, 0, v179, vcc
	v_cmp_gt_f32_e32 vcc, s61, v91
	v_sub_f32_e32 v90, v90, v98
	v_sub_f32_e32 v90, -0.5, v90
	v_cndmask_b32_e64 v98, 0, 32, vcc
	v_ldexp_f32 v91, v91, v98
	v_log_f32_e32 v91, v91
	v_mul_f32_e32 v90, 0x3fb8aa3b, v90
	v_exp_f32_e32 v90, v90
	v_mul_f32_e32 v92, 0xbfb8aa3b, v92
	v_mul_f32_e32 v98, 0x3f317217, v91
	v_fma_f32 v98, v91, s62, -v98
	v_fmac_f32_e32 v98, 0x3377d1cf, v91
	v_fmac_f32_e32 v98, 0x3f317217, v91
	v_cmp_lt_f32_e64 s[0:1], |v91|, s63
	v_mul_f32_e32 v93, 0xbfb8aa3b, v93
	v_mul_f32_e32 v88, 0xbfb8aa3b, v88
	v_cndmask_b32_e64 v91, v91, v98, s[0:1]
	v_cndmask_b32_e32 v98, 0, v179, vcc
	v_sub_f32_e32 v91, v91, v98
	v_sub_f32_e32 v91, -0.5, v91
	v_mul_f32_e32 v91, 0x3fb8aa3b, v91
	v_exp_f32_e32 v91, v91
	v_mul_f32_e32 v89, 0xbfb8aa3b, v89
	v_exp_f32_e32 v92, v92
	v_exp_f32_e32 v93, v93
	v_mul_f32_e32 v94, 0xbfb8aa3b, v94
	v_mul_f32_e32 v95, 0xbfb8aa3b, v95
	v_exp_f32_e32 v88, v88
	v_exp_f32_e32 v89, v89
	v_mul_f32_e32 v90, 0xbfb8aa3b, v90
	v_exp_f32_e32 v94, v94
	v_exp_f32_e32 v95, v95
	v_exp_f32_e32 v98, v90
	v_mul_f32_e32 v90, 0xbfb8aa3b, v91
	v_exp_f32_e32 v99, v90
	s_mov_b64 s[0:1], 0x80000
	v_cvt_pk_f16_f32 v90, v92, v93
	v_cvt_pk_f16_f32 v92, v88, v89
	v_lshl_add_u64 v[88:89], v[120:121], 0, s[0:1]
	s_mov_b32 s0, 0x80000
	v_cvt_pk_f16_f32 v91, v94, v95
	v_add_co_u32_e32 v94, vcc, s0, v120
	v_cvt_pk_f16_f32 v93, v98, v99
	s_nop 0
	v_addc_co_u32_e32 v95, vcc, 0, v121, vcc
	global_store_dwordx4 v[94:95], v[90:93], off sc1
	v_add_f32_e32 v84, v84, v132
	v_mul_f32_e32 v84, 0xbfb8aa3b, v84
	v_exp_f32_e32 v84, v84
	v_add_f32_e32 v85, v85, v133
	v_mul_f32_e32 v85, 0xbfb8aa3b, v85
	v_exp_f32_e32 v85, v85
	v_add_f32_e32 v84, 1.0, v84
	v_cmp_gt_f32_e32 vcc, s61, v84
	v_add_f32_e32 v86, v86, v134
	v_add_f32_e32 v85, 1.0, v85
	v_cndmask_b32_e64 v90, 0, 32, vcc
	v_ldexp_f32 v84, v84, v90
	v_log_f32_e32 v84, v84
	v_mul_f32_e32 v86, 0xbfb8aa3b, v86
	v_exp_f32_e32 v86, v86
	v_add_f32_e32 v87, v87, v135
	v_mul_f32_e32 v90, 0x3f317217, v84
	v_fma_f32 v90, v84, s62, -v90
	v_fmac_f32_e32 v90, 0x3377d1cf, v84
	v_fmac_f32_e32 v90, 0x3f317217, v84
	v_cmp_lt_f32_e64 s[0:1], |v84|, s63
	v_add_f32_e32 v86, 1.0, v86
	v_mul_f32_e32 v87, 0xbfb8aa3b, v87
	v_cndmask_b32_e64 v84, v84, v90, s[0:1]
	v_cndmask_b32_e32 v90, 0, v179, vcc
	v_cmp_gt_f32_e32 vcc, s61, v85
	v_sub_f32_e32 v84, v84, v90
	v_exp_f32_e32 v87, v87
	v_cndmask_b32_e64 v90, 0, 32, vcc
	v_ldexp_f32 v85, v85, v90
	v_log_f32_e32 v85, v85
	v_add_f32_e32 v87, 1.0, v87
	v_add_f32_e32 v80, v80, v128
	v_mul_f32_e32 v80, 0xbfb8aa3b, v80
	v_mul_f32_e32 v90, 0x3f317217, v85
	v_fma_f32 v90, v85, s62, -v90
	v_fmac_f32_e32 v90, 0x3377d1cf, v85
	v_fmac_f32_e32 v90, 0x3f317217, v85
	v_cmp_lt_f32_e64 s[0:1], |v85|, s63
	v_exp_f32_e32 v80, v80
	v_add_f32_e32 v81, v81, v129
	v_cndmask_b32_e64 v85, v85, v90, s[0:1]
	v_cndmask_b32_e32 v90, 0, v179, vcc
	v_cmp_gt_f32_e32 vcc, s61, v86
	v_sub_f32_e32 v85, v85, v90
	v_add_f32_e32 v80, 1.0, v80
	v_cndmask_b32_e64 v90, 0, 32, vcc
	v_ldexp_f32 v86, v86, v90
	v_log_f32_e32 v86, v86
	v_mul_f32_e32 v81, 0xbfb8aa3b, v81
	v_exp_f32_e32 v81, v81
	v_add_f32_e32 v82, v82, v130
	v_mul_f32_e32 v90, 0x3f317217, v86
	v_fma_f32 v90, v86, s62, -v90
	v_fmac_f32_e32 v90, 0x3377d1cf, v86
	v_fmac_f32_e32 v90, 0x3f317217, v86
	v_cmp_lt_f32_e64 s[0:1], |v86|, s63
	v_add_f32_e32 v81, 1.0, v81
	v_mul_f32_e32 v82, 0xbfb8aa3b, v82
	v_cndmask_b32_e64 v86, v86, v90, s[0:1]
	v_cndmask_b32_e32 v90, 0, v179, vcc
	v_cmp_gt_f32_e32 vcc, s61, v87
	v_sub_f32_e32 v86, v86, v90
	v_exp_f32_e32 v82, v82
	v_cndmask_b32_e64 v90, 0, 32, vcc
	v_ldexp_f32 v87, v87, v90
	v_log_f32_e32 v87, v87
	v_add_f32_e32 v82, 1.0, v82
	v_add_f32_e32 v83, v83, v131
	v_mul_f32_e32 v83, 0xbfb8aa3b, v83
	v_mul_f32_e32 v90, 0x3f317217, v87
	v_fma_f32 v90, v87, s62, -v90
	v_fmac_f32_e32 v90, 0x3377d1cf, v87
	v_fmac_f32_e32 v90, 0x3f317217, v87
	v_cmp_lt_f32_e64 s[0:1], |v87|, s63
	v_exp_f32_e32 v83, v83
	v_sub_f32_e32 v84, -0.5, v84
	v_cndmask_b32_e64 v87, v87, v90, s[0:1]
	v_cndmask_b32_e32 v90, 0, v179, vcc
	v_cmp_gt_f32_e32 vcc, s61, v80
	v_sub_f32_e32 v87, v87, v90
	v_add_f32_e32 v83, 1.0, v83
	v_cndmask_b32_e64 v90, 0, 32, vcc
	v_ldexp_f32 v80, v80, v90
	v_log_f32_e32 v80, v80
	v_sub_f32_e32 v85, -0.5, v85
;     template <int MODE> __device__ __forceinline__ void run(AccRef acc, const Unit& u, int wr, int wc, int fr, int fq) const {
;     ...
;                     for (int e = 0; e < 4; ++e) { x[e] = acc[ai][bj][m][0][e] + bias[e]; x[4 + e] = acc[ai][bj][m][1][e] + bias[4 + e]; }
;     ...
;                     if (MODE == 0) {
; #pragma unroll
;                         for (int e = 0; e < 8; ++e) { const float sp = __logf(1.f + __expf(-x[e])); x[e] = __expf(-__expf(-sp - 0.5f)); }
;                         w.x = pkh(x[0], x[1]); w.y = pkh(x[2], x[3]); w.z = pkh(x[4], x[5]); w.w = pkh(x[6], x[7]);
;                         *(u32x4*)(WA + (size_t)row * 2048 + seg * 512 + cc) = w;
	v_mul_f32_e32 v84, 0x3fb8aa3b, v84
	v_mul_f32_e32 v85, 0x3fb8aa3b, v85
	v_mul_f32_e32 v90, 0x3f317217, v80
	v_fma_f32 v90, v80, s62, -v90
	v_fmac_f32_e32 v90, 0x3377d1cf, v80
	v_fmac_f32_e32 v90, 0x3f317217, v80
	v_cmp_lt_f32_e64 s[0:1], |v80|, s63
	v_sub_f32_e32 v86, -0.5, v86
	v_sub_f32_e32 v87, -0.5, v87
	v_cndmask_b32_e64 v80, v80, v90, s[0:1]
	v_cndmask_b32_e32 v90, 0, v179, vcc
	v_cmp_gt_f32_e32 vcc, s61, v81
	v_sub_f32_e32 v80, v80, v90
	v_sub_f32_e32 v80, -0.5, v80
	v_cndmask_b32_e64 v90, 0, 32, vcc
	v_ldexp_f32 v81, v81, v90
	v_log_f32_e32 v81, v81
	v_mul_f32_e32 v80, 0x3fb8aa3b, v80
	v_exp_f32_e32 v84, v84
	v_exp_f32_e32 v85, v85
	v_mul_f32_e32 v90, 0x3f317217, v81
	v_fma_f32 v90, v81, s62, -v90
	v_fmac_f32_e32 v90, 0x3377d1cf, v81
	v_fmac_f32_e32 v90, 0x3f317217, v81
	v_cmp_lt_f32_e64 s[0:1], |v81|, s63
	v_mul_f32_e32 v86, 0x3fb8aa3b, v86
	v_mul_f32_e32 v87, 0x3fb8aa3b, v87
	v_cndmask_b32_e64 v81, v81, v90, s[0:1]
	v_cndmask_b32_e32 v90, 0, v179, vcc
	v_cmp_gt_f32_e32 vcc, s61, v82
	v_sub_f32_e32 v81, v81, v90
	v_sub_f32_e32 v81, -0.5, v81
	v_cndmask_b32_e64 v90, 0, 32, vcc
	v_ldexp_f32 v82, v82, v90
	v_log_f32_e32 v82, v82
	v_mul_f32_e32 v81, 0x3fb8aa3b, v81
	v_exp_f32_e32 v80, v80
	v_exp_f32_e32 v81, v81
	v_mul_f32_e32 v90, 0x3f317217, v82
	v_fma_f32 v90, v82, s62, -v90
	v_fmac_f32_e32 v90, 0x3377d1cf, v82
	v_fmac_f32_e32 v90, 0x3f317217, v82
	v_cmp_lt_f32_e64 s[0:1], |v82|, s63
	v_exp_f32_e32 v86, v86
	v_exp_f32_e32 v87, v87
	v_cndmask_b32_e64 v82, v82, v90, s[0:1]
	v_cndmask_b32_e32 v90, 0, v179, vcc
	v_cmp_gt_f32_e32 vcc, s61, v83
	v_sub_f32_e32 v82, v82, v90
	v_sub_f32_e32 v82, -0.5, v82
	v_cndmask_b32_e64 v90, 0, 32, vcc
	v_ldexp_f32 v83, v83, v90
	v_log_f32_e32 v83, v83
	v_mul_f32_e32 v82, 0x3fb8aa3b, v82
	v_exp_f32_e32 v82, v82
	v_mul_f32_e32 v84, 0xbfb8aa3b, v84
	v_mul_f32_e32 v90, 0x3f317217, v83
	v_fma_f32 v90, v83, s62, -v90
	v_fmac_f32_e32 v90, 0x3377d1cf, v83
	v_fmac_f32_e32 v90, 0x3f317217, v83
	v_cmp_lt_f32_e64 s[0:1], |v83|, s63
	v_mul_f32_e32 v85, 0xbfb8aa3b, v85
	v_mul_f32_e32 v80, 0xbfb8aa3b, v80
	v_cndmask_b32_e64 v83, v83, v90, s[0:1]
	v_cndmask_b32_e32 v90, 0, v179, vcc
	v_sub_f32_e32 v83, v83, v90
	v_sub_f32_e32 v83, -0.5, v83
	v_mul_f32_e32 v83, 0x3fb8aa3b, v83
	v_exp_f32_e32 v83, v83
	v_mul_f32_e32 v81, 0xbfb8aa3b, v81
	v_exp_f32_e32 v84, v84
	v_exp_f32_e32 v85, v85
	v_mul_f32_e32 v86, 0xbfb8aa3b, v86
	v_mul_f32_e32 v87, 0xbfb8aa3b, v87
	v_exp_f32_e32 v80, v80
	v_exp_f32_e32 v81, v81
	v_mul_f32_e32 v82, 0xbfb8aa3b, v82
	v_exp_f32_e32 v86, v86
	v_exp_f32_e32 v87, v87
	v_exp_f32_e32 v90, v82
	v_mul_f32_e32 v82, 0xbfb8aa3b, v83
	v_exp_f32_e32 v91, v82
	s_mov_b64 s[0:1], 0x90000
	v_cvt_pk_f16_f32 v82, v84, v85
	v_cvt_pk_f16_f32 v84, v80, v81
	v_lshl_add_u64 v[80:81], v[120:121], 0, s[0:1]
	s_mov_b32 s0, 0x90000
	v_cvt_pk_f16_f32 v83, v86, v87
	v_add_co_u32_e32 v86, vcc, s0, v120
	v_cvt_pk_f16_f32 v85, v90, v91
	s_nop 0
	v_addc_co_u32_e32 v87, vcc, 0, v121, vcc
	global_store_dwordx4 v[86:87], v[82:85], off sc1
	v_add_f32_e32 v76, v76, v132
	v_mul_f32_e32 v76, 0xbfb8aa3b, v76
	v_exp_f32_e32 v76, v76
	v_add_f32_e32 v77, v77, v133
	v_mul_f32_e32 v77, 0xbfb8aa3b, v77
	v_exp_f32_e32 v77, v77
	v_add_f32_e32 v76, 1.0, v76
	v_cmp_gt_f32_e32 vcc, s61, v76
	v_add_f32_e32 v78, v78, v134
	v_add_f32_e32 v77, 1.0, v77
	v_cndmask_b32_e64 v82, 0, 32, vcc
	v_ldexp_f32 v76, v76, v82
	v_log_f32_e32 v76, v76
	v_mul_f32_e32 v78, 0xbfb8aa3b, v78
	v_exp_f32_e32 v78, v78
	v_add_f32_e32 v79, v79, v135
	v_mul_f32_e32 v82, 0x3f317217, v76
	v_fma_f32 v82, v76, s62, -v82
	v_fmac_f32_e32 v82, 0x3377d1cf, v76
	v_fmac_f32_e32 v82, 0x3f317217, v76
	v_cmp_lt_f32_e64 s[0:1], |v76|, s63
	v_add_f32_e32 v78, 1.0, v78
	v_mul_f32_e32 v79, 0xbfb8aa3b, v79
	v_cndmask_b32_e64 v76, v76, v82, s[0:1]
	v_cndmask_b32_e32 v82, 0, v179, vcc
	v_cmp_gt_f32_e32 vcc, s61, v77
	v_sub_f32_e32 v76, v76, v82
	v_exp_f32_e32 v79, v79
	v_cndmask_b32_e64 v82, 0, 32, vcc
	v_ldexp_f32 v77, v77, v82
	v_log_f32_e32 v77, v77
	v_add_f32_e32 v79, 1.0, v79
	v_add_f32_e32 v72, v72, v128
	v_mul_f32_e32 v72, 0xbfb8aa3b, v72
	v_mul_f32_e32 v82, 0x3f317217, v77
	v_fma_f32 v82, v77, s62, -v82
	v_fmac_f32_e32 v82, 0x3377d1cf, v77
	v_fmac_f32_e32 v82, 0x3f317217, v77
	v_cmp_lt_f32_e64 s[0:1], |v77|, s63
	v_exp_f32_e32 v72, v72
	v_add_f32_e32 v73, v73, v129
	v_cndmask_b32_e64 v77, v77, v82, s[0:1]
	v_cndmask_b32_e32 v82, 0, v179, vcc
	v_cmp_gt_f32_e32 vcc, s61, v78
	v_sub_f32_e32 v77, v77, v82
	v_add_f32_e32 v72, 1.0, v72
	v_cndmask_b32_e64 v82, 0, 32, vcc
	v_ldexp_f32 v78, v78, v82
	v_log_f32_e32 v78, v78
	v_mul_f32_e32 v73, 0xbfb8aa3b, v73
	v_exp_f32_e32 v73, v73
	v_add_f32_e32 v74, v74, v130
	v_mul_f32_e32 v82, 0x3f317217, v78
	v_fma_f32 v82, v78, s62, -v82
	v_fmac_f32_e32 v82, 0x3377d1cf, v78
	v_fmac_f32_e32 v82, 0x3f317217, v78
	v_cmp_lt_f32_e64 s[0:1], |v78|, s63
	v_add_f32_e32 v73, 1.0, v73
	v_mul_f32_e32 v74, 0xbfb8aa3b, v74
	v_cndmask_b32_e64 v78, v78, v82, s[0:1]
	v_cndmask_b32_e32 v82, 0, v179, vcc
	v_cmp_gt_f32_e32 vcc, s61, v79
	v_sub_f32_e32 v78, v78, v82
	v_exp_f32_e32 v74, v74
	v_cndmask_b32_e64 v82, 0, 32, vcc
	v_ldexp_f32 v79, v79, v82
	v_log_f32_e32 v79, v79
	v_add_f32_e32 v74, 1.0, v74
	v_add_f32_e32 v75, v75, v131
	v_mul_f32_e32 v75, 0xbfb8aa3b, v75
	v_mul_f32_e32 v82, 0x3f317217, v79
	v_fma_f32 v82, v79, s62, -v82
	v_fmac_f32_e32 v82, 0x3377d1cf, v79
	v_fmac_f32_e32 v82, 0x3f317217, v79
	v_cmp_lt_f32_e64 s[0:1], |v79|, s63
	v_exp_f32_e32 v75, v75
	v_sub_f32_e32 v76, -0.5, v76
	v_cndmask_b32_e64 v79, v79, v82, s[0:1]
	v_cndmask_b32_e32 v82, 0, v179, vcc
	v_cmp_gt_f32_e32 vcc, s61, v72
	v_sub_f32_e32 v79, v79, v82
	v_add_f32_e32 v75, 1.0, v75
;     template <int MODE> __device__ __forceinline__ void run(AccRef acc, const Unit& u, int wr, int wc, int fr, int fq) const {
;     ...
;                     for (int e = 0; e < 4; ++e) { x[e] = acc[ai][bj][m][0][e] + bias[e]; x[4 + e] = acc[ai][bj][m][1][e] + bias[4 + e]; }
;     ...
;                     if (MODE == 0) {
; #pragma unroll
;                         for (int e = 0; e < 8; ++e) { const float sp = __logf(1.f + __expf(-x[e])); x[e] = __expf(-__expf(-sp - 0.5f)); }
;                         w.x = pkh(x[0], x[1]); w.y = pkh(x[2], x[3]); w.z = pkh(x[4], x[5]); w.w = pkh(x[6], x[7]);
;                         *(u32x4*)(WA + (size_t)row * 2048 + seg * 512 + cc) = w;
	v_cndmask_b32_e64 v82, 0, 32, vcc
	v_ldexp_f32 v72, v72, v82
	v_log_f32_e32 v72, v72
	v_sub_f32_e32 v77, -0.5, v77
	v_mul_f32_e32 v76, 0x3fb8aa3b, v76
	v_mul_f32_e32 v77, 0x3fb8aa3b, v77
	v_mul_f32_e32 v82, 0x3f317217, v72
	v_fma_f32 v82, v72, s62, -v82
	v_fmac_f32_e32 v82, 0x3377d1cf, v72
	v_fmac_f32_e32 v82, 0x3f317217, v72
	v_cmp_lt_f32_e64 s[0:1], |v72|, s63
	v_sub_f32_e32 v78, -0.5, v78
	v_sub_f32_e32 v79, -0.5, v79
	v_cndmask_b32_e64 v72, v72, v82, s[0:1]
	v_cndmask_b32_e32 v82, 0, v179, vcc
	v_cmp_gt_f32_e32 vcc, s61, v73
	v_sub_f32_e32 v72, v72, v82
	v_sub_f32_e32 v72, -0.5, v72
	v_cndmask_b32_e64 v82, 0, 32, vcc
	v_ldexp_f32 v73, v73, v82
	v_log_f32_e32 v73, v73
	v_mul_f32_e32 v72, 0x3fb8aa3b, v72
	v_exp_f32_e32 v76, v76
	v_exp_f32_e32 v77, v77
	v_mul_f32_e32 v82, 0x3f317217, v73
	v_fma_f32 v82, v73, s62, -v82
	v_fmac_f32_e32 v82, 0x3377d1cf, v73
	v_fmac_f32_e32 v82, 0x3f317217, v73
	v_cmp_lt_f32_e64 s[0:1], |v73|, s63
	v_mul_f32_e32 v78, 0x3fb8aa3b, v78
	v_mul_f32_e32 v79, 0x3fb8aa3b, v79
	v_cndmask_b32_e64 v73, v73, v82, s[0:1]
	v_cndmask_b32_e32 v82, 0, v179, vcc
	v_cmp_gt_f32_e32 vcc, s61, v74
	v_sub_f32_e32 v73, v73, v82
	v_sub_f32_e32 v73, -0.5, v73
	v_cndmask_b32_e64 v82, 0, 32, vcc
	v_ldexp_f32 v74, v74, v82
	v_log_f32_e32 v74, v74
	v_mul_f32_e32 v73, 0x3fb8aa3b, v73
	v_exp_f32_e32 v72, v72
	v_exp_f32_e32 v73, v73
	v_mul_f32_e32 v82, 0x3f317217, v74
	v_fma_f32 v82, v74, s62, -v82
	v_fmac_f32_e32 v82, 0x3377d1cf, v74
	v_fmac_f32_e32 v82, 0x3f317217, v74
	v_cmp_lt_f32_e64 s[0:1], |v74|, s63
	v_exp_f32_e32 v78, v78
	v_exp_f32_e32 v79, v79
	v_cndmask_b32_e64 v74, v74, v82, s[0:1]
	v_cndmask_b32_e32 v82, 0, v179, vcc
	v_cmp_gt_f32_e32 vcc, s61, v75
	v_sub_f32_e32 v74, v74, v82
	v_sub_f32_e32 v74, -0.5, v74
	v_cndmask_b32_e64 v82, 0, 32, vcc
	v_ldexp_f32 v75, v75, v82
	v_log_f32_e32 v75, v75
	v_mul_f32_e32 v74, 0x3fb8aa3b, v74
	v_exp_f32_e32 v74, v74
	v_mul_f32_e32 v76, 0xbfb8aa3b, v76
	v_mul_f32_e32 v82, 0x3f317217, v75
	v_fma_f32 v82, v75, s62, -v82
	v_fmac_f32_e32 v82, 0x3377d1cf, v75
	v_fmac_f32_e32 v82, 0x3f317217, v75
	v_cmp_lt_f32_e64 s[0:1], |v75|, s63
	v_mul_f32_e32 v77, 0xbfb8aa3b, v77
	v_mul_f32_e32 v72, 0xbfb8aa3b, v72
	v_cndmask_b32_e64 v75, v75, v82, s[0:1]
	v_cndmask_b32_e32 v82, 0, v179, vcc
	v_sub_f32_e32 v75, v75, v82
	v_sub_f32_e32 v75, -0.5, v75
	v_mul_f32_e32 v75, 0x3fb8aa3b, v75
	v_exp_f32_e32 v75, v75
	v_mul_f32_e32 v73, 0xbfb8aa3b, v73
	v_exp_f32_e32 v76, v76
	v_exp_f32_e32 v77, v77
	v_mul_f32_e32 v78, 0xbfb8aa3b, v78
	v_mul_f32_e32 v79, 0xbfb8aa3b, v79
	v_exp_f32_e32 v72, v72
	v_exp_f32_e32 v73, v73
	v_mul_f32_e32 v74, 0xbfb8aa3b, v74
	v_exp_f32_e32 v78, v78
	v_exp_f32_e32 v79, v79
	v_exp_f32_e32 v82, v74
	v_mul_f32_e32 v74, 0xbfb8aa3b, v75
	v_exp_f32_e32 v83, v74
	s_mov_b64 s[0:1], 0xa0000
	v_cvt_pk_f16_f32 v74, v76, v77
	v_cvt_pk_f16_f32 v76, v72, v73
	v_lshl_add_u64 v[72:73], v[120:121], 0, s[0:1]
	s_mov_b32 s0, 0xa0000
	v_cvt_pk_f16_f32 v75, v78, v79
	v_add_co_u32_e32 v78, vcc, s0, v120
	v_cvt_pk_f16_f32 v77, v82, v83
	s_nop 0
	v_addc_co_u32_e32 v79, vcc, 0, v121, vcc
	global_store_dwordx4 v[78:79], v[74:77], off sc1
	v_add_f32_e32 v68, v68, v132
	v_mul_f32_e32 v68, 0xbfb8aa3b, v68
	v_exp_f32_e32 v68, v68
	v_add_f32_e32 v69, v69, v133
	v_mul_f32_e32 v69, 0xbfb8aa3b, v69
	v_exp_f32_e32 v69, v69
	v_add_f32_e32 v68, 1.0, v68
	v_cmp_gt_f32_e32 vcc, s61, v68
	v_add_f32_e32 v70, v70, v134
	v_add_f32_e32 v69, 1.0, v69
	v_cndmask_b32_e64 v74, 0, 32, vcc
	v_ldexp_f32 v68, v68, v74
	v_log_f32_e32 v68, v68
	v_mul_f32_e32 v70, 0xbfb8aa3b, v70
	v_exp_f32_e32 v70, v70
	v_add_f32_e32 v71, v71, v135
	v_mul_f32_e32 v74, 0x3f317217, v68
	v_fma_f32 v74, v68, s62, -v74
	v_fmac_f32_e32 v74, 0x3377d1cf, v68
	v_fmac_f32_e32 v74, 0x3f317217, v68
	v_cmp_lt_f32_e64 s[0:1], |v68|, s63
	v_add_f32_e32 v70, 1.0, v70
	v_mul_f32_e32 v71, 0xbfb8aa3b, v71
	v_cndmask_b32_e64 v68, v68, v74, s[0:1]
	v_cndmask_b32_e32 v74, 0, v179, vcc
	v_cmp_gt_f32_e32 vcc, s61, v69
	v_sub_f32_e32 v68, v68, v74
	v_exp_f32_e32 v71, v71
	v_cndmask_b32_e64 v74, 0, 32, vcc
	v_ldexp_f32 v69, v69, v74
	v_log_f32_e32 v69, v69
	v_add_f32_e32 v71, 1.0, v71
	v_add_f32_e32 v64, v64, v128
	v_mul_f32_e32 v64, 0xbfb8aa3b, v64
	v_mul_f32_e32 v74, 0x3f317217, v69
	v_fma_f32 v74, v69, s62, -v74
	v_fmac_f32_e32 v74, 0x3377d1cf, v69
	v_fmac_f32_e32 v74, 0x3f317217, v69
	v_cmp_lt_f32_e64 s[0:1], |v69|, s63
	v_exp_f32_e32 v64, v64
	v_add_f32_e32 v65, v65, v129
	v_cndmask_b32_e64 v69, v69, v74, s[0:1]
	v_cndmask_b32_e32 v74, 0, v179, vcc
	v_cmp_gt_f32_e32 vcc, s61, v70
	v_sub_f32_e32 v69, v69, v74
	v_add_f32_e32 v64, 1.0, v64
	v_cndmask_b32_e64 v74, 0, 32, vcc
	v_ldexp_f32 v70, v70, v74
	v_log_f32_e32 v70, v70
	v_mul_f32_e32 v65, 0xbfb8aa3b, v65
	v_exp_f32_e32 v65, v65
	v_add_f32_e32 v66, v66, v130
	v_mul_f32_e32 v74, 0x3f317217, v70
	v_fma_f32 v74, v70, s62, -v74
	v_fmac_f32_e32 v74, 0x3377d1cf, v70
	v_fmac_f32_e32 v74, 0x3f317217, v70
	v_cmp_lt_f32_e64 s[0:1], |v70|, s63
	v_add_f32_e32 v65, 1.0, v65
	v_mul_f32_e32 v66, 0xbfb8aa3b, v66
	v_cndmask_b32_e64 v70, v70, v74, s[0:1]
	v_cndmask_b32_e32 v74, 0, v179, vcc
	v_cmp_gt_f32_e32 vcc, s61, v71
	v_sub_f32_e32 v70, v70, v74
	v_exp_f32_e32 v66, v66
	v_cndmask_b32_e64 v74, 0, 32, vcc
	v_ldexp_f32 v71, v71, v74
	v_log_f32_e32 v71, v71
	v_add_f32_e32 v66, 1.0, v66
	v_add_f32_e32 v67, v67, v131
	v_mul_f32_e32 v67, 0xbfb8aa3b, v67
	v_mul_f32_e32 v74, 0x3f317217, v71
	v_fma_f32 v74, v71, s62, -v74
	v_fmac_f32_e32 v74, 0x3377d1cf, v71
	v_fmac_f32_e32 v74, 0x3f317217, v71
	v_cmp_lt_f32_e64 s[0:1], |v71|, s63
	v_exp_f32_e32 v67, v67
	v_sub_f32_e32 v68, -0.5, v68
	v_cndmask_b32_e64 v71, v71, v74, s[0:1]
	v_cndmask_b32_e32 v74, 0, v179, vcc
;     template <int MODE> __device__ __forceinline__ void run(AccRef acc, const Unit& u, int wr, int wc, int fr, int fq) const {
;     ...
;             if (MODE < 2) { const float* bp = (MODE == 0 ? w0 + seg * 512 : a0 + (seg - 2) * 512) + cc; const f32x4 b0 = *(const f32x4*)bp, b1 = *(const f32x4*)(bp + 4);
;                 bias[0] = b0[0]; bias[1] = b0[1]; bias[2] = b0[2]; bias[3] = b0[3]; bias[4] = b1[0]; bias[5] = b1[1]; bias[6] = b1[2]; bias[7] = b1[3]; }
;     ...
;                     for (int e = 0; e < 4; ++e) { x[e] = acc[ai][bj][m][0][e] + bias[e]; x[4 + e] = acc[ai][bj][m][1][e] + bias[4 + e]; }
;     ...
;                     if (MODE == 0) {
; #pragma unroll
;                         for (int e = 0; e < 8; ++e) { const float sp = __logf(1.f + __expf(-x[e])); x[e] = __expf(-__expf(-sp - 0.5f)); }
;                         w.x = pkh(x[0], x[1]); w.y = pkh(x[2], x[3]); w.z = pkh(x[4], x[5]); w.w = pkh(x[6], x[7]);
;                         *(u32x4*)(WA + (size_t)row * 2048 + seg * 512 + cc) = w;
	v_cmp_gt_f32_e32 vcc, s61, v64
	v_sub_f32_e32 v71, v71, v74
	v_sub_f32_e32 v69, -0.5, v69
	v_cndmask_b32_e64 v74, 0, 32, vcc
	v_ldexp_f32 v64, v64, v74
	v_log_f32_e32 v64, v64
	v_mul_f32_e32 v68, 0x3fb8aa3b, v68
	v_mul_f32_e32 v69, 0x3fb8aa3b, v69
	v_sub_f32_e32 v70, -0.5, v70
	v_mul_f32_e32 v74, 0x3f317217, v64
	v_fma_f32 v74, v64, s62, -v74
	v_fmac_f32_e32 v74, 0x3377d1cf, v64
	v_fmac_f32_e32 v74, 0x3f317217, v64
	v_cmp_lt_f32_e64 s[0:1], |v64|, s63
	v_sub_f32_e32 v71, -0.5, v71
	v_exp_f32_e32 v68, v68
	v_cndmask_b32_e64 v64, v64, v74, s[0:1]
	v_cndmask_b32_e32 v74, 0, v179, vcc
	v_cmp_gt_f32_e32 vcc, s61, v65
	v_sub_f32_e32 v64, v64, v74
	v_sub_f32_e32 v64, -0.5, v64
	v_cndmask_b32_e64 v74, 0, 32, vcc
	v_ldexp_f32 v65, v65, v74
	v_log_f32_e32 v65, v65
	v_mul_f32_e32 v64, 0x3fb8aa3b, v64
	v_exp_f32_e32 v64, v64
	v_exp_f32_e32 v69, v69
	v_mul_f32_e32 v74, 0x3f317217, v65
	v_fma_f32 v74, v65, s62, -v74
	v_fmac_f32_e32 v74, 0x3377d1cf, v65
	v_fmac_f32_e32 v74, 0x3f317217, v65
	v_cmp_lt_f32_e64 s[0:1], |v65|, s63
	v_mul_f32_e32 v64, 0xbfb8aa3b, v64
	v_mul_f32_e32 v70, 0x3fb8aa3b, v70
	v_cndmask_b32_e64 v65, v65, v74, s[0:1]
	v_cndmask_b32_e32 v74, 0, v179, vcc
	v_sub_f32_e32 v65, v65, v74
	v_cmp_gt_f32_e32 vcc, s61, v66
	v_sub_f32_e32 v65, -0.5, v65
	v_mul_f32_e32 v65, 0x3fb8aa3b, v65
	v_cndmask_b32_e64 v74, 0, 32, vcc
	v_ldexp_f32 v66, v66, v74
	v_exp_f32_e32 v65, v65
	v_log_f32_e32 v66, v66
	v_exp_f32_e32 v74, v64
	v_mul_f32_e32 v71, 0x3fb8aa3b, v71
	v_mul_f32_e32 v64, 0xbfb8aa3b, v65
	v_mul_f32_e32 v65, 0x3f317217, v66
	v_fma_f32 v65, v66, s62, -v65
	v_fmac_f32_e32 v65, 0x3377d1cf, v66
	v_fmac_f32_e32 v65, 0x3f317217, v66
	v_cmp_lt_f32_e64 s[0:1], |v66|, s63
	v_exp_f32_e32 v70, v70
	v_exp_f32_e32 v71, v71
	v_cndmask_b32_e64 v65, v66, v65, s[0:1]
	v_cndmask_b32_e32 v66, 0, v179, vcc
	v_sub_f32_e32 v65, v65, v66
	v_add_f32_e32 v66, 1.0, v67
	v_cmp_gt_f32_e32 vcc, s61, v66
	v_sub_f32_e32 v65, -0.5, v65
	v_mul_f32_e32 v65, 0x3fb8aa3b, v65
	v_cndmask_b32_e64 v67, 0, 32, vcc
	v_ldexp_f32 v66, v66, v67
	v_log_f32_e32 v66, v66
	v_exp_f32_e32 v65, v65
	v_mul_f32_e32 v68, 0xbfb8aa3b, v68
	v_mul_f32_e32 v69, 0xbfb8aa3b, v69
	v_mul_f32_e32 v67, 0x3f317217, v66
	v_fma_f32 v67, v66, s62, -v67
	v_fmac_f32_e32 v67, 0x3377d1cf, v66
	v_fmac_f32_e32 v67, 0x3f317217, v66
	v_cmp_lt_f32_e64 s[0:1], |v66|, s63
	v_exp_f32_e32 v68, v68
	v_exp_f32_e32 v69, v69
	v_cndmask_b32_e64 v66, v66, v67, s[0:1]
	v_cndmask_b32_e32 v67, 0, v179, vcc
	v_sub_f32_e32 v66, v66, v67
	v_sub_f32_e32 v66, -0.5, v66
	v_mul_f32_e32 v66, 0x3fb8aa3b, v66
	v_exp_f32_e32 v66, v66
	v_exp_f32_e32 v67, v64
	v_mul_f32_e32 v64, 0xbfb8aa3b, v65
	v_mul_f32_e32 v70, 0xbfb8aa3b, v70
	v_mul_f32_e32 v71, 0xbfb8aa3b, v71
	v_exp_f32_e32 v75, v64
	v_mul_f32_e32 v64, 0xbfb8aa3b, v66
	v_exp_f32_e32 v70, v70
	v_exp_f32_e32 v71, v71
	v_exp_f32_e32 v76, v64
	s_mov_b32 s0, 0xb0000
	v_cvt_pk_f16_f32 v64, v68, v69
	v_add_co_u32_e32 v68, vcc, s0, v120
	v_cvt_pk_f16_f32 v65, v70, v71
	v_cvt_pk_f16_f32 v66, v74, v67
	v_cvt_pk_f16_f32 v67, v75, v76
	v_addc_co_u32_e32 v69, vcc, 0, v121, vcc
	v_lshl_add_u64 v[74:75], v[120:121], 0, s[70:71]
	global_store_dwordx4 v[68:69], v[64:67], off sc1
	global_load_dwordx4 v[64:67], v[136:137], off offset:528
	global_load_dwordx4 v[68:71], v[136:137], off offset:512
	s_waitcnt vmcnt(0)
	v_add_f32_e32 v77, v56, v64
	v_add_f32_e32 v76, v60, v68
	v_mul_f32_e32 v56, 0xbfb8aa3b, v76
	v_exp_f32_e32 v56, v56
	v_add_f32_e32 v60, v58, v66
	v_add_f32_e32 v61, v61, v69
	v_add_f32_e32 v78, v57, v65
	v_add_f32_e32 v56, 1.0, v56
	v_cmp_gt_f32_e32 vcc, s61, v56
	v_add_f32_e32 v57, v59, v67
	v_add_f32_e32 v62, v62, v70
	v_cndmask_b32_e64 v58, 0, 32, vcc
	v_ldexp_f32 v56, v56, v58
	v_log_f32_e32 v56, v56
	v_add_f32_e32 v63, v63, v71
	v_mul_f32_e32 v60, 0xbfb8aa3b, v60
	v_exp_f32_e32 v60, v60
	v_mul_f32_e32 v58, 0x3f317217, v56
	v_fma_f32 v58, v56, s62, -v58
	v_fmac_f32_e32 v58, 0x3377d1cf, v56
	v_fmac_f32_e32 v58, 0x3f317217, v56
	v_cmp_lt_f32_e64 s[0:1], |v56|, s63
	v_add_f32_e32 v60, 1.0, v60
	v_mul_f32_e32 v57, 0xbfb8aa3b, v57
	v_cndmask_b32_e64 v56, v56, v58, s[0:1]
	v_cndmask_b32_e32 v58, 0, v179, vcc
	v_sub_f32_e32 v56, v56, v58
	v_mul_f32_e32 v58, 0xbfb8aa3b, v61
	v_exp_f32_e32 v58, v58
	v_exp_f32_e32 v57, v57
	v_sub_f32_e32 v56, -0.5, v56
	v_mul_f32_e32 v56, 0x3fb8aa3b, v56
	v_add_f32_e32 v58, 1.0, v58
	v_cmp_gt_f32_e32 vcc, s61, v58
	v_add_f32_e32 v57, 1.0, v57
	v_exp_f32_e32 v56, v56
	v_cndmask_b32_e64 v59, 0, 32, vcc
	v_ldexp_f32 v58, v58, v59
	v_log_f32_e32 v58, v58
	v_mul_f32_e32 v56, 0xbfb8aa3b, v56
	v_exp_f32_e32 v56, v56
	v_mul_f32_e32 v59, 0x3f317217, v58
	v_fma_f32 v59, v58, s62, -v59
	v_fmac_f32_e32 v59, 0x3377d1cf, v58
	v_fmac_f32_e32 v59, 0x3f317217, v58
	v_cmp_lt_f32_e64 s[0:1], |v58|, s63
	s_nop 1
	v_cndmask_b32_e64 v58, v58, v59, s[0:1]
	v_cndmask_b32_e32 v59, 0, v179, vcc
	v_sub_f32_e32 v58, v58, v59
	v_mul_f32_e32 v59, 0xbfb8aa3b, v62
	v_exp_f32_e32 v59, v59
	v_sub_f32_e32 v58, -0.5, v58
	v_mul_f32_e32 v58, 0x3fb8aa3b, v58
	v_exp_f32_e32 v58, v58
	v_add_f32_e32 v59, 1.0, v59
	v_cmp_gt_f32_e32 vcc, s61, v59
	v_mul_f32_e32 v58, 0xbfb8aa3b, v58
	s_nop 0
	v_cndmask_b32_e64 v61, 0, 32, vcc
	v_ldexp_f32 v59, v59, v61
	v_log_f32_e32 v59, v59
	v_exp_f32_e32 v58, v58
	v_mul_f32_e32 v61, 0x3f317217, v59
	v_fma_f32 v61, v59, s62, -v61
	v_fmac_f32_e32 v61, 0x3377d1cf, v59
	v_fmac_f32_e32 v61, 0x3f317217, v59
	v_cmp_lt_f32_e64 s[0:1], |v59|, s63
	v_cvt_pk_f16_f32 v56, v56, v58
	s_nop 0
	v_cndmask_b32_e64 v59, v59, v61, s[0:1]
	v_cndmask_b32_e32 v61, 0, v179, vcc
	v_sub_f32_e32 v59, v59, v61
	v_mul_f32_e32 v61, 0xbfb8aa3b, v63
	v_exp_f32_e32 v61, v61
	v_sub_f32_e32 v59, -0.5, v59
;     template <int MODE> __device__ __forceinline__ void run(AccRef acc, const Unit& u, int wr, int wc, int fr, int fq) const {
;     ...
;                     for (int e = 0; e < 4; ++e) { x[e] = acc[ai][bj][m][0][e] + bias[e]; x[4 + e] = acc[ai][bj][m][1][e] + bias[4 + e]; }
;     ...
;                     if (MODE == 0) {
; #pragma unroll
;                         for (int e = 0; e < 8; ++e) { const float sp = __logf(1.f + __expf(-x[e])); x[e] = __expf(-__expf(-sp - 0.5f)); }
;                         w.x = pkh(x[0], x[1]); w.y = pkh(x[2], x[3]); w.z = pkh(x[4], x[5]); w.w = pkh(x[6], x[7]);
;                         *(u32x4*)(WA + (size_t)row * 2048 + seg * 512 + cc) = w;
	v_mul_f32_e32 v59, 0x3fb8aa3b, v59
	v_exp_f32_e32 v59, v59
	v_add_f32_e32 v61, 1.0, v61
	v_cmp_gt_f32_e32 vcc, s61, v61
	v_mul_f32_e32 v59, 0xbfb8aa3b, v59
	s_nop 0
	v_cndmask_b32_e64 v62, 0, 32, vcc
	v_ldexp_f32 v61, v61, v62
	v_log_f32_e32 v61, v61
	v_exp_f32_e32 v59, v59
	v_mul_f32_e32 v62, 0x3f317217, v61
	v_fma_f32 v62, v61, s62, -v62
	v_fmac_f32_e32 v62, 0x3377d1cf, v61
	v_fmac_f32_e32 v62, 0x3f317217, v61
	v_cmp_lt_f32_e64 s[0:1], |v61|, s63
	s_nop 1
	v_cndmask_b32_e64 v61, v61, v62, s[0:1]
	v_cndmask_b32_e32 v62, 0, v179, vcc
	v_sub_f32_e32 v61, v61, v62
	v_mul_f32_e32 v62, 0xbfb8aa3b, v77
	v_exp_f32_e32 v62, v62
	v_sub_f32_e32 v61, -0.5, v61
	v_mul_f32_e32 v61, 0x3fb8aa3b, v61
	v_exp_f32_e32 v61, v61
	v_add_f32_e32 v62, 1.0, v62
	v_cmp_gt_f32_e32 vcc, s61, v62
	v_mul_f32_e32 v61, 0xbfb8aa3b, v61
	s_nop 0
	v_cndmask_b32_e64 v63, 0, 32, vcc
	v_ldexp_f32 v62, v62, v63
	v_log_f32_e32 v62, v62
	v_exp_f32_e32 v61, v61
	v_mul_f32_e32 v63, 0x3f317217, v62
	v_fma_f32 v63, v62, s62, -v63
	v_fmac_f32_e32 v63, 0x3377d1cf, v62
	v_fmac_f32_e32 v63, 0x3f317217, v62
	v_cmp_lt_f32_e64 s[0:1], |v62|, s63
	s_nop 1
	v_cndmask_b32_e64 v62, v62, v63, s[0:1]
	v_cndmask_b32_e32 v63, 0, v179, vcc
	v_sub_f32_e32 v62, v62, v63
	v_mul_f32_e32 v63, 0xbfb8aa3b, v78
	v_exp_f32_e32 v63, v63
	v_sub_f32_e32 v62, -0.5, v62
	v_mul_f32_e32 v62, 0x3fb8aa3b, v62
	v_exp_f32_e32 v62, v62
	v_add_f32_e32 v63, 1.0, v63
	v_cmp_gt_f32_e32 vcc, s61, v63
	v_mul_f32_e32 v62, 0xbfb8aa3b, v62
	s_nop 0
	v_cndmask_b32_e64 v76, 0, 32, vcc
	v_ldexp_f32 v63, v63, v76
	v_log_f32_e32 v63, v63
	v_exp_f32_e32 v62, v62
	v_mul_f32_e32 v76, 0x3f317217, v63
	v_fma_f32 v76, v63, s62, -v76
	v_fmac_f32_e32 v76, 0x3377d1cf, v63
	v_fmac_f32_e32 v76, 0x3f317217, v63
	v_cmp_lt_f32_e64 s[0:1], |v63|, s63
	s_nop 1
	v_cndmask_b32_e64 v63, v63, v76, s[0:1]
	v_cndmask_b32_e32 v76, 0, v179, vcc
	v_cmp_gt_f32_e32 vcc, s61, v60
	v_sub_f32_e32 v63, v63, v76
	v_sub_f32_e32 v63, -0.5, v63
	v_cndmask_b32_e64 v76, 0, 32, vcc
	v_ldexp_f32 v60, v60, v76
	v_log_f32_e32 v60, v60
	v_mul_f32_e32 v63, 0x3fb8aa3b, v63
	v_exp_f32_e32 v63, v63
	v_mul_f32_e32 v76, 0x3f317217, v60
	v_fma_f32 v76, v60, s62, -v76
	v_fmac_f32_e32 v76, 0x3377d1cf, v60
	v_fmac_f32_e32 v76, 0x3f317217, v60
	v_cmp_lt_f32_e64 s[0:1], |v60|, s63
	v_mul_f32_e32 v63, 0xbfb8aa3b, v63
	v_exp_f32_e32 v63, v63
	v_cndmask_b32_e64 v60, v60, v76, s[0:1]
	v_cndmask_b32_e32 v76, 0, v179, vcc
	v_cmp_gt_f32_e32 vcc, s61, v57
	v_sub_f32_e32 v60, v60, v76
	v_sub_f32_e32 v60, -0.5, v60
	v_cndmask_b32_e64 v76, 0, 32, vcc
	v_ldexp_f32 v57, v57, v76
	v_log_f32_e32 v57, v57
	v_mul_f32_e32 v60, 0x3fb8aa3b, v60
	v_exp_f32_e32 v60, v60
	v_cvt_pk_f16_f32 v58, v62, v63
	v_mul_f32_e32 v76, 0x3f317217, v57
	v_fma_f32 v76, v57, s62, -v76
	v_fmac_f32_e32 v76, 0x3377d1cf, v57
	v_fmac_f32_e32 v76, 0x3f317217, v57
	v_cmp_lt_f32_e64 s[0:1], |v57|, s63
	v_mul_f32_e32 v60, 0xbfb8aa3b, v60
	v_exp_f32_e32 v60, v60
	v_cndmask_b32_e64 v57, v57, v76, s[0:1]
	v_cndmask_b32_e32 v76, 0, v179, vcc
	v_sub_f32_e32 v57, v57, v76
	v_sub_f32_e32 v57, -0.5, v57
	v_mul_f32_e32 v57, 0x3fb8aa3b, v57
	v_exp_f32_e32 v57, v57
	s_nop 0
	v_mul_f32_e32 v57, 0xbfb8aa3b, v57
	v_exp_f32_e32 v76, v57
	v_cvt_pk_f16_f32 v57, v59, v61
	v_cvt_pk_f16_f32 v59, v60, v76
	global_store_dwordx4 v[120:121], v[56:59], off offset:256 sc1
	v_add_f32_e32 v52, v52, v68
	v_mul_f32_e32 v52, 0xbfb8aa3b, v52
	v_exp_f32_e32 v52, v52
	v_add_f32_e32 v53, v53, v69
	v_mul_f32_e32 v53, 0xbfb8aa3b, v53
	v_exp_f32_e32 v53, v53
	v_add_f32_e32 v52, 1.0, v52
	v_cmp_gt_f32_e32 vcc, s61, v52
	v_add_f32_e32 v54, v54, v70
	v_add_f32_e32 v53, 1.0, v53
	v_cndmask_b32_e64 v56, 0, 32, vcc
	v_ldexp_f32 v52, v52, v56
	v_log_f32_e32 v52, v52
	v_mul_f32_e32 v54, 0xbfb8aa3b, v54
	v_exp_f32_e32 v54, v54
	v_add_f32_e32 v55, v55, v71
	v_mul_f32_e32 v56, 0x3f317217, v52
	v_fma_f32 v56, v52, s62, -v56
	v_fmac_f32_e32 v56, 0x3377d1cf, v52
	v_fmac_f32_e32 v56, 0x3f317217, v52
	v_cmp_lt_f32_e64 s[0:1], |v52|, s63
	v_add_f32_e32 v54, 1.0, v54
	v_mul_f32_e32 v55, 0xbfb8aa3b, v55
	v_cndmask_b32_e64 v52, v52, v56, s[0:1]
	v_cndmask_b32_e32 v56, 0, v179, vcc
	v_cmp_gt_f32_e32 vcc, s61, v53
	v_sub_f32_e32 v52, v52, v56
	v_exp_f32_e32 v55, v55
	v_cndmask_b32_e64 v56, 0, 32, vcc
	v_ldexp_f32 v53, v53, v56
	v_log_f32_e32 v53, v53
	v_add_f32_e32 v55, 1.0, v55
	v_add_f32_e32 v48, v48, v64
	v_mul_f32_e32 v48, 0xbfb8aa3b, v48
	v_mul_f32_e32 v56, 0x3f317217, v53
	v_fma_f32 v56, v53, s62, -v56
	v_fmac_f32_e32 v56, 0x3377d1cf, v53
	v_fmac_f32_e32 v56, 0x3f317217, v53
	v_cmp_lt_f32_e64 s[0:1], |v53|, s63
	v_exp_f32_e32 v48, v48
	v_add_f32_e32 v49, v49, v65
	v_cndmask_b32_e64 v53, v53, v56, s[0:1]
	v_cndmask_b32_e32 v56, 0, v179, vcc
	v_cmp_gt_f32_e32 vcc, s61, v54
	v_sub_f32_e32 v53, v53, v56
	v_add_f32_e32 v48, 1.0, v48
	v_cndmask_b32_e64 v56, 0, 32, vcc
	v_ldexp_f32 v54, v54, v56
	v_log_f32_e32 v54, v54
	v_mul_f32_e32 v49, 0xbfb8aa3b, v49
	v_exp_f32_e32 v49, v49
	v_add_f32_e32 v50, v50, v66
	v_mul_f32_e32 v56, 0x3f317217, v54
	v_fma_f32 v56, v54, s62, -v56
	v_fmac_f32_e32 v56, 0x3377d1cf, v54
	v_fmac_f32_e32 v56, 0x3f317217, v54
	v_cmp_lt_f32_e64 s[0:1], |v54|, s63
	v_add_f32_e32 v49, 1.0, v49
	v_mul_f32_e32 v50, 0xbfb8aa3b, v50
	v_cndmask_b32_e64 v54, v54, v56, s[0:1]
	v_cndmask_b32_e32 v56, 0, v179, vcc
	v_cmp_gt_f32_e32 vcc, s61, v55
	v_sub_f32_e32 v54, v54, v56
	v_exp_f32_e32 v50, v50
	v_cndmask_b32_e64 v56, 0, 32, vcc
	v_ldexp_f32 v55, v55, v56
	v_log_f32_e32 v55, v55
	v_add_f32_e32 v50, 1.0, v50
	v_add_f32_e32 v51, v51, v67
	v_mul_f32_e32 v51, 0xbfb8aa3b, v51
	v_mul_f32_e32 v56, 0x3f317217, v55
	v_fma_f32 v56, v55, s62, -v56
	v_fmac_f32_e32 v56, 0x3377d1cf, v55
;     template <int MODE> __device__ __forceinline__ void run(AccRef acc, const Unit& u, int wr, int wc, int fr, int fq) const {
;     ...
;                     for (int e = 0; e < 4; ++e) { x[e] = acc[ai][bj][m][0][e] + bias[e]; x[4 + e] = acc[ai][bj][m][1][e] + bias[4 + e]; }
;     ...
;                     if (MODE == 0) {
; #pragma unroll
;                         for (int e = 0; e < 8; ++e) { const float sp = __logf(1.f + __expf(-x[e])); x[e] = __expf(-__expf(-sp - 0.5f)); }
;                         w.x = pkh(x[0], x[1]); w.y = pkh(x[2], x[3]); w.z = pkh(x[4], x[5]); w.w = pkh(x[6], x[7]);
;                         *(u32x4*)(WA + (size_t)row * 2048 + seg * 512 + cc) = w;
	v_fmac_f32_e32 v56, 0x3f317217, v55
	v_cmp_lt_f32_e64 s[0:1], |v55|, s63
	v_exp_f32_e32 v51, v51
	v_sub_f32_e32 v52, -0.5, v52
	v_cndmask_b32_e64 v55, v55, v56, s[0:1]
	v_cndmask_b32_e32 v56, 0, v179, vcc
	v_cmp_gt_f32_e32 vcc, s61, v48
	v_sub_f32_e32 v55, v55, v56
	v_sub_f32_e32 v53, -0.5, v53
	v_cndmask_b32_e64 v56, 0, 32, vcc
	v_ldexp_f32 v48, v48, v56
	v_log_f32_e32 v48, v48
	v_sub_f32_e32 v54, -0.5, v54
	v_sub_f32_e32 v55, -0.5, v55
	v_mul_f32_e32 v52, 0x3fb8aa3b, v52
	v_mul_f32_e32 v56, 0x3f317217, v48
	v_fma_f32 v56, v48, s62, -v56
	v_fmac_f32_e32 v56, 0x3377d1cf, v48
	v_fmac_f32_e32 v56, 0x3f317217, v48
	v_cmp_lt_f32_e64 s[0:1], |v48|, s63
	v_mul_f32_e32 v53, 0x3fb8aa3b, v53
	v_mul_f32_e32 v54, 0x3fb8aa3b, v54
	v_cndmask_b32_e64 v48, v48, v56, s[0:1]
	v_cndmask_b32_e32 v56, 0, v179, vcc
	v_cmp_gt_f32_e32 vcc, s61, v49
	v_sub_f32_e32 v48, v48, v56
	v_sub_f32_e32 v48, -0.5, v48
	v_cndmask_b32_e64 v56, 0, 32, vcc
	v_ldexp_f32 v49, v49, v56
	v_log_f32_e32 v49, v49
	v_mul_f32_e32 v48, 0x3fb8aa3b, v48
	v_exp_f32_e32 v48, v48
	v_mul_f32_e32 v55, 0x3fb8aa3b, v55
	v_mul_f32_e32 v56, 0x3f317217, v49
	v_fma_f32 v56, v49, s62, -v56
	v_fmac_f32_e32 v56, 0x3377d1cf, v49
	v_fmac_f32_e32 v56, 0x3f317217, v49
	v_cmp_lt_f32_e64 s[0:1], |v49|, s63
	v_mul_f32_e32 v48, 0xbfb8aa3b, v48
	v_exp_f32_e32 v52, v52
	v_cndmask_b32_e64 v49, v49, v56, s[0:1]
	v_cndmask_b32_e32 v56, 0, v179, vcc
	v_sub_f32_e32 v49, v49, v56
	v_cmp_gt_f32_e32 vcc, s61, v50
	v_sub_f32_e32 v49, -0.5, v49
	v_mul_f32_e32 v49, 0x3fb8aa3b, v49
	v_cndmask_b32_e64 v56, 0, 32, vcc
	v_ldexp_f32 v50, v50, v56
	v_exp_f32_e32 v49, v49
	v_log_f32_e32 v50, v50
	v_exp_f32_e32 v56, v48
	v_exp_f32_e32 v53, v53
	v_mul_f32_e32 v48, 0xbfb8aa3b, v49
	v_mul_f32_e32 v49, 0x3f317217, v50
	v_fma_f32 v49, v50, s62, -v49
	v_fmac_f32_e32 v49, 0x3377d1cf, v50
	v_fmac_f32_e32 v49, 0x3f317217, v50
	v_cmp_lt_f32_e64 s[0:1], |v50|, s63
	v_exp_f32_e32 v54, v54
	v_exp_f32_e32 v55, v55
	v_cndmask_b32_e64 v49, v50, v49, s[0:1]
	v_cndmask_b32_e32 v50, 0, v179, vcc
	v_sub_f32_e32 v49, v49, v50
	v_add_f32_e32 v50, 1.0, v51
	v_cmp_gt_f32_e32 vcc, s61, v50
	v_sub_f32_e32 v49, -0.5, v49
	v_mul_f32_e32 v49, 0x3fb8aa3b, v49
	v_cndmask_b32_e64 v51, 0, 32, vcc
	v_ldexp_f32 v50, v50, v51
	v_log_f32_e32 v50, v50
	v_exp_f32_e32 v49, v49
	v_mul_f32_e32 v52, 0xbfb8aa3b, v52
	v_mul_f32_e32 v53, 0xbfb8aa3b, v53
	v_mul_f32_e32 v51, 0x3f317217, v50
	v_fma_f32 v51, v50, s62, -v51
	v_fmac_f32_e32 v51, 0x3377d1cf, v50
	v_fmac_f32_e32 v51, 0x3f317217, v50
	v_cmp_lt_f32_e64 s[0:1], |v50|, s63
	v_mul_f32_e32 v54, 0xbfb8aa3b, v54
	v_mul_f32_e32 v55, 0xbfb8aa3b, v55
	v_cndmask_b32_e64 v50, v50, v51, s[0:1]
	v_cndmask_b32_e32 v51, 0, v179, vcc
	v_sub_f32_e32 v50, v50, v51
	v_sub_f32_e32 v50, -0.5, v50
	v_mul_f32_e32 v50, 0x3fb8aa3b, v50
	v_exp_f32_e32 v50, v50
	v_exp_f32_e32 v51, v48
	v_mul_f32_e32 v48, 0xbfb8aa3b, v49
	v_exp_f32_e32 v57, v48
	v_mul_f32_e32 v48, 0xbfb8aa3b, v50
	v_exp_f32_e32 v52, v52
	v_exp_f32_e32 v53, v53
	v_exp_f32_e32 v54, v54
	v_exp_f32_e32 v55, v55
	v_exp_f32_e32 v58, v48
	v_cvt_pk_f16_f32 v48, v52, v53
	v_cvt_pk_f16_f32 v49, v54, v55
	v_cvt_pk_f16_f32 v50, v56, v51
	v_cvt_pk_f16_f32 v51, v57, v58
	global_store_dwordx4 v[112:113], v[48:51], off offset:256 sc1
	v_add_f32_e32 v44, v44, v68
	v_mul_f32_e32 v44, 0xbfb8aa3b, v44
	v_exp_f32_e32 v44, v44
	v_add_f32_e32 v45, v45, v69
	v_mul_f32_e32 v45, 0xbfb8aa3b, v45
	v_exp_f32_e32 v45, v45
	v_add_f32_e32 v44, 1.0, v44
	v_cmp_gt_f32_e32 vcc, s61, v44
	v_add_f32_e32 v46, v46, v70
	v_add_f32_e32 v45, 1.0, v45
	v_cndmask_b32_e64 v48, 0, 32, vcc
	v_ldexp_f32 v44, v44, v48
	v_log_f32_e32 v44, v44
	v_mul_f32_e32 v46, 0xbfb8aa3b, v46
	v_exp_f32_e32 v46, v46
	v_add_f32_e32 v47, v47, v71
	v_mul_f32_e32 v48, 0x3f317217, v44
	v_fma_f32 v48, v44, s62, -v48
	v_fmac_f32_e32 v48, 0x3377d1cf, v44
	v_fmac_f32_e32 v48, 0x3f317217, v44
	v_cmp_lt_f32_e64 s[0:1], |v44|, s63
	v_add_f32_e32 v46, 1.0, v46
	v_mul_f32_e32 v47, 0xbfb8aa3b, v47
	v_cndmask_b32_e64 v44, v44, v48, s[0:1]
	v_cndmask_b32_e32 v48, 0, v179, vcc
	v_cmp_gt_f32_e32 vcc, s61, v45
	v_sub_f32_e32 v44, v44, v48
	v_exp_f32_e32 v47, v47
	v_cndmask_b32_e64 v48, 0, 32, vcc
	v_ldexp_f32 v45, v45, v48
	v_log_f32_e32 v45, v45
	v_add_f32_e32 v47, 1.0, v47
	v_add_f32_e32 v40, v40, v64
	v_mul_f32_e32 v40, 0xbfb8aa3b, v40
	v_mul_f32_e32 v48, 0x3f317217, v45
	v_fma_f32 v48, v45, s62, -v48
	v_fmac_f32_e32 v48, 0x3377d1cf, v45
	v_fmac_f32_e32 v48, 0x3f317217, v45
	v_cmp_lt_f32_e64 s[0:1], |v45|, s63
	v_exp_f32_e32 v40, v40
	v_add_f32_e32 v41, v41, v65
	v_cndmask_b32_e64 v45, v45, v48, s[0:1]
	v_cndmask_b32_e32 v48, 0, v179, vcc
	v_cmp_gt_f32_e32 vcc, s61, v46
	v_sub_f32_e32 v45, v45, v48
	v_add_f32_e32 v40, 1.0, v40
	v_cndmask_b32_e64 v48, 0, 32, vcc
	v_ldexp_f32 v46, v46, v48
	v_log_f32_e32 v46, v46
	v_mul_f32_e32 v41, 0xbfb8aa3b, v41
	v_exp_f32_e32 v41, v41
	v_add_f32_e32 v42, v42, v66
	v_mul_f32_e32 v48, 0x3f317217, v46
	v_fma_f32 v48, v46, s62, -v48
	v_fmac_f32_e32 v48, 0x3377d1cf, v46
	v_fmac_f32_e32 v48, 0x3f317217, v46
	v_cmp_lt_f32_e64 s[0:1], |v46|, s63
	v_add_f32_e32 v41, 1.0, v41
	v_mul_f32_e32 v42, 0xbfb8aa3b, v42
	v_cndmask_b32_e64 v46, v46, v48, s[0:1]
	v_cndmask_b32_e32 v48, 0, v179, vcc
	v_cmp_gt_f32_e32 vcc, s61, v47
	v_sub_f32_e32 v46, v46, v48
	v_exp_f32_e32 v42, v42
	v_cndmask_b32_e64 v48, 0, 32, vcc
	v_ldexp_f32 v47, v47, v48
	v_log_f32_e32 v47, v47
	v_add_f32_e32 v42, 1.0, v42
	v_add_f32_e32 v43, v43, v67
	v_mul_f32_e32 v43, 0xbfb8aa3b, v43
	v_mul_f32_e32 v48, 0x3f317217, v47
	v_fma_f32 v48, v47, s62, -v48
	v_fmac_f32_e32 v48, 0x3377d1cf, v47
	v_fmac_f32_e32 v48, 0x3f317217, v47
	v_cmp_lt_f32_e64 s[0:1], |v47|, s63
;     template <int MODE> __device__ __forceinline__ void run(AccRef acc, const Unit& u, int wr, int wc, int fr, int fq) const {
;     ...
;                     for (int e = 0; e < 4; ++e) { x[e] = acc[ai][bj][m][0][e] + bias[e]; x[4 + e] = acc[ai][bj][m][1][e] + bias[4 + e]; }
;     ...
;                     if (MODE == 0) {
; #pragma unroll
;                         for (int e = 0; e < 8; ++e) { const float sp = __logf(1.f + __expf(-x[e])); x[e] = __expf(-__expf(-sp - 0.5f)); }
;                         w.x = pkh(x[0], x[1]); w.y = pkh(x[2], x[3]); w.z = pkh(x[4], x[5]); w.w = pkh(x[6], x[7]);
;                         *(u32x4*)(WA + (size_t)row * 2048 + seg * 512 + cc) = w;
	v_exp_f32_e32 v43, v43
	v_sub_f32_e32 v44, -0.5, v44
	v_cndmask_b32_e64 v47, v47, v48, s[0:1]
	v_cndmask_b32_e32 v48, 0, v179, vcc
	v_cmp_gt_f32_e32 vcc, s61, v40
	v_sub_f32_e32 v47, v47, v48
	v_sub_f32_e32 v45, -0.5, v45
	v_cndmask_b32_e64 v48, 0, 32, vcc
	v_ldexp_f32 v40, v40, v48
	v_log_f32_e32 v40, v40
	v_sub_f32_e32 v46, -0.5, v46
	v_sub_f32_e32 v47, -0.5, v47
	v_mul_f32_e32 v44, 0x3fb8aa3b, v44
	v_mul_f32_e32 v48, 0x3f317217, v40
	v_fma_f32 v48, v40, s62, -v48
	v_fmac_f32_e32 v48, 0x3377d1cf, v40
	v_fmac_f32_e32 v48, 0x3f317217, v40
	v_cmp_lt_f32_e64 s[0:1], |v40|, s63
	v_mul_f32_e32 v45, 0x3fb8aa3b, v45
	v_mul_f32_e32 v46, 0x3fb8aa3b, v46
	v_cndmask_b32_e64 v40, v40, v48, s[0:1]
	v_cndmask_b32_e32 v48, 0, v179, vcc
	v_cmp_gt_f32_e32 vcc, s61, v41
	v_sub_f32_e32 v40, v40, v48
	v_sub_f32_e32 v40, -0.5, v40
	v_cndmask_b32_e64 v48, 0, 32, vcc
	v_ldexp_f32 v41, v41, v48
	v_log_f32_e32 v41, v41
	v_mul_f32_e32 v40, 0x3fb8aa3b, v40
	v_exp_f32_e32 v40, v40
	v_mul_f32_e32 v47, 0x3fb8aa3b, v47
	v_mul_f32_e32 v48, 0x3f317217, v41
	v_fma_f32 v48, v41, s62, -v48
	v_fmac_f32_e32 v48, 0x3377d1cf, v41
	v_fmac_f32_e32 v48, 0x3f317217, v41
	v_cmp_lt_f32_e64 s[0:1], |v41|, s63
	v_mul_f32_e32 v40, 0xbfb8aa3b, v40
	v_exp_f32_e32 v44, v44
	v_cndmask_b32_e64 v41, v41, v48, s[0:1]
	v_cndmask_b32_e32 v48, 0, v179, vcc
	v_sub_f32_e32 v41, v41, v48
	v_cmp_gt_f32_e32 vcc, s61, v42
	v_sub_f32_e32 v41, -0.5, v41
	v_mul_f32_e32 v41, 0x3fb8aa3b, v41
	v_cndmask_b32_e64 v48, 0, 32, vcc
	v_ldexp_f32 v42, v42, v48
	v_exp_f32_e32 v41, v41
	v_log_f32_e32 v42, v42
	v_exp_f32_e32 v48, v40
	v_exp_f32_e32 v45, v45
	v_mul_f32_e32 v40, 0xbfb8aa3b, v41
	v_mul_f32_e32 v41, 0x3f317217, v42
	v_fma_f32 v41, v42, s62, -v41
	v_fmac_f32_e32 v41, 0x3377d1cf, v42
	v_fmac_f32_e32 v41, 0x3f317217, v42
	v_cmp_lt_f32_e64 s[0:1], |v42|, s63
	v_exp_f32_e32 v46, v46
	v_exp_f32_e32 v47, v47
	v_cndmask_b32_e64 v41, v42, v41, s[0:1]
	v_cndmask_b32_e32 v42, 0, v179, vcc
	v_sub_f32_e32 v41, v41, v42
	v_add_f32_e32 v42, 1.0, v43
	v_cmp_gt_f32_e32 vcc, s61, v42
	v_sub_f32_e32 v41, -0.5, v41
	v_mul_f32_e32 v41, 0x3fb8aa3b, v41
	v_cndmask_b32_e64 v43, 0, 32, vcc
	v_ldexp_f32 v42, v42, v43
	v_log_f32_e32 v42, v42
	v_exp_f32_e32 v41, v41
	v_mul_f32_e32 v44, 0xbfb8aa3b, v44
	v_mul_f32_e32 v45, 0xbfb8aa3b, v45
	v_mul_f32_e32 v43, 0x3f317217, v42
	v_fma_f32 v43, v42, s62, -v43
	v_fmac_f32_e32 v43, 0x3377d1cf, v42
	v_fmac_f32_e32 v43, 0x3f317217, v42
	v_cmp_lt_f32_e64 s[0:1], |v42|, s63
	v_mul_f32_e32 v46, 0xbfb8aa3b, v46
	v_mul_f32_e32 v47, 0xbfb8aa3b, v47
	v_cndmask_b32_e64 v42, v42, v43, s[0:1]
	v_cndmask_b32_e32 v43, 0, v179, vcc
	v_sub_f32_e32 v42, v42, v43
	v_sub_f32_e32 v42, -0.5, v42
	v_mul_f32_e32 v42, 0x3fb8aa3b, v42
	v_exp_f32_e32 v42, v42
	v_exp_f32_e32 v43, v40
	v_mul_f32_e32 v40, 0xbfb8aa3b, v41
	v_exp_f32_e32 v49, v40
	v_mul_f32_e32 v40, 0xbfb8aa3b, v42
	v_exp_f32_e32 v44, v44
	v_exp_f32_e32 v45, v45
	v_exp_f32_e32 v46, v46
	v_exp_f32_e32 v47, v47
	v_exp_f32_e32 v50, v40
	v_cvt_pk_f16_f32 v40, v44, v45
	v_cvt_pk_f16_f32 v41, v46, v47
	v_cvt_pk_f16_f32 v42, v48, v43
	v_cvt_pk_f16_f32 v43, v49, v50
	global_store_dwordx4 v[104:105], v[40:43], off offset:256 sc1
	v_add_f32_e32 v36, v36, v68
	v_mul_f32_e32 v36, 0xbfb8aa3b, v36
	v_exp_f32_e32 v36, v36
	v_add_f32_e32 v37, v37, v69
	v_mul_f32_e32 v37, 0xbfb8aa3b, v37
	v_exp_f32_e32 v37, v37
	v_add_f32_e32 v36, 1.0, v36
	v_cmp_gt_f32_e32 vcc, s61, v36
	v_add_f32_e32 v38, v38, v70
	v_add_f32_e32 v37, 1.0, v37
	v_cndmask_b32_e64 v40, 0, 32, vcc
	v_ldexp_f32 v36, v36, v40
	v_log_f32_e32 v36, v36
	v_mul_f32_e32 v38, 0xbfb8aa3b, v38
	v_exp_f32_e32 v38, v38
	v_add_f32_e32 v39, v39, v71
	v_mul_f32_e32 v40, 0x3f317217, v36
	v_fma_f32 v40, v36, s62, -v40
	v_fmac_f32_e32 v40, 0x3377d1cf, v36
	v_fmac_f32_e32 v40, 0x3f317217, v36
	v_cmp_lt_f32_e64 s[0:1], |v36|, s63
	v_add_f32_e32 v38, 1.0, v38
	v_mul_f32_e32 v39, 0xbfb8aa3b, v39
	v_cndmask_b32_e64 v36, v36, v40, s[0:1]
	v_cndmask_b32_e32 v40, 0, v179, vcc
	v_cmp_gt_f32_e32 vcc, s61, v37
	v_sub_f32_e32 v36, v36, v40
	v_exp_f32_e32 v39, v39
	v_cndmask_b32_e64 v40, 0, 32, vcc
	v_ldexp_f32 v37, v37, v40
	v_log_f32_e32 v37, v37
	v_add_f32_e32 v39, 1.0, v39
	v_add_f32_e32 v32, v32, v64
	v_mul_f32_e32 v32, 0xbfb8aa3b, v32
	v_mul_f32_e32 v40, 0x3f317217, v37
	v_fma_f32 v40, v37, s62, -v40
	v_fmac_f32_e32 v40, 0x3377d1cf, v37
	v_fmac_f32_e32 v40, 0x3f317217, v37
	v_cmp_lt_f32_e64 s[0:1], |v37|, s63
	v_exp_f32_e32 v32, v32
	v_add_f32_e32 v33, v33, v65
	v_cndmask_b32_e64 v37, v37, v40, s[0:1]
	v_cndmask_b32_e32 v40, 0, v179, vcc
	v_cmp_gt_f32_e32 vcc, s61, v38
	v_sub_f32_e32 v37, v37, v40
	v_add_f32_e32 v32, 1.0, v32
	v_cndmask_b32_e64 v40, 0, 32, vcc
	v_ldexp_f32 v38, v38, v40
	v_log_f32_e32 v38, v38
	v_mul_f32_e32 v33, 0xbfb8aa3b, v33
	v_exp_f32_e32 v33, v33
	v_add_f32_e32 v34, v34, v66
	v_mul_f32_e32 v40, 0x3f317217, v38
	v_fma_f32 v40, v38, s62, -v40
	v_fmac_f32_e32 v40, 0x3377d1cf, v38
	v_fmac_f32_e32 v40, 0x3f317217, v38
	v_cmp_lt_f32_e64 s[0:1], |v38|, s63
	v_add_f32_e32 v33, 1.0, v33
	v_mul_f32_e32 v34, 0xbfb8aa3b, v34
	v_cndmask_b32_e64 v38, v38, v40, s[0:1]
	v_cndmask_b32_e32 v40, 0, v179, vcc
	v_cmp_gt_f32_e32 vcc, s61, v39
	v_sub_f32_e32 v38, v38, v40
	v_exp_f32_e32 v34, v34
	v_cndmask_b32_e64 v40, 0, 32, vcc
	v_ldexp_f32 v39, v39, v40
	v_log_f32_e32 v39, v39
	v_add_f32_e32 v34, 1.0, v34
	v_add_f32_e32 v35, v35, v67
	v_mul_f32_e32 v35, 0xbfb8aa3b, v35
	v_mul_f32_e32 v40, 0x3f317217, v39
	v_fma_f32 v40, v39, s62, -v40
	v_fmac_f32_e32 v40, 0x3377d1cf, v39
	v_fmac_f32_e32 v40, 0x3f317217, v39
	v_cmp_lt_f32_e64 s[0:1], |v39|, s63
	v_exp_f32_e32 v35, v35
	v_sub_f32_e32 v36, -0.5, v36
	v_cndmask_b32_e64 v39, v39, v40, s[0:1]
;     template <int MODE> __device__ __forceinline__ void run(AccRef acc, const Unit& u, int wr, int wc, int fr, int fq) const {
;     ...
;                     for (int e = 0; e < 4; ++e) { x[e] = acc[ai][bj][m][0][e] + bias[e]; x[4 + e] = acc[ai][bj][m][1][e] + bias[4 + e]; }
;     ...
;                     if (MODE == 0) {
; #pragma unroll
;                         for (int e = 0; e < 8; ++e) { const float sp = __logf(1.f + __expf(-x[e])); x[e] = __expf(-__expf(-sp - 0.5f)); }
;                         w.x = pkh(x[0], x[1]); w.y = pkh(x[2], x[3]); w.z = pkh(x[4], x[5]); w.w = pkh(x[6], x[7]);
;                         *(u32x4*)(WA + (size_t)row * 2048 + seg * 512 + cc) = w;
	v_cndmask_b32_e32 v40, 0, v179, vcc
	v_cmp_gt_f32_e32 vcc, s61, v32
	v_sub_f32_e32 v39, v39, v40
	v_sub_f32_e32 v37, -0.5, v37
	v_cndmask_b32_e64 v40, 0, 32, vcc
	v_ldexp_f32 v32, v32, v40
	v_log_f32_e32 v32, v32
	v_sub_f32_e32 v38, -0.5, v38
	v_sub_f32_e32 v39, -0.5, v39
	v_mul_f32_e32 v36, 0x3fb8aa3b, v36
	v_mul_f32_e32 v40, 0x3f317217, v32
	v_fma_f32 v40, v32, s62, -v40
	v_fmac_f32_e32 v40, 0x3377d1cf, v32
	v_fmac_f32_e32 v40, 0x3f317217, v32
	v_cmp_lt_f32_e64 s[0:1], |v32|, s63
	v_mul_f32_e32 v37, 0x3fb8aa3b, v37
	v_mul_f32_e32 v38, 0x3fb8aa3b, v38
	v_cndmask_b32_e64 v32, v32, v40, s[0:1]
	v_cndmask_b32_e32 v40, 0, v179, vcc
	v_cmp_gt_f32_e32 vcc, s61, v33
	v_sub_f32_e32 v32, v32, v40
	v_sub_f32_e32 v32, -0.5, v32
	v_cndmask_b32_e64 v40, 0, 32, vcc
	v_ldexp_f32 v33, v33, v40
	v_log_f32_e32 v33, v33
	v_mul_f32_e32 v32, 0x3fb8aa3b, v32
	v_exp_f32_e32 v32, v32
	v_mul_f32_e32 v39, 0x3fb8aa3b, v39
	v_mul_f32_e32 v40, 0x3f317217, v33
	v_fma_f32 v40, v33, s62, -v40
	v_fmac_f32_e32 v40, 0x3377d1cf, v33
	v_fmac_f32_e32 v40, 0x3f317217, v33
	v_cmp_lt_f32_e64 s[0:1], |v33|, s63
	v_mul_f32_e32 v32, 0xbfb8aa3b, v32
	v_exp_f32_e32 v36, v36
	v_cndmask_b32_e64 v33, v33, v40, s[0:1]
	v_cndmask_b32_e32 v40, 0, v179, vcc
	v_sub_f32_e32 v33, v33, v40
	v_cmp_gt_f32_e32 vcc, s61, v34
	v_sub_f32_e32 v33, -0.5, v33
	v_mul_f32_e32 v33, 0x3fb8aa3b, v33
	v_cndmask_b32_e64 v40, 0, 32, vcc
	v_ldexp_f32 v34, v34, v40
	v_exp_f32_e32 v33, v33
	v_log_f32_e32 v34, v34
	v_exp_f32_e32 v40, v32
	v_exp_f32_e32 v37, v37
	v_mul_f32_e32 v32, 0xbfb8aa3b, v33
	v_mul_f32_e32 v33, 0x3f317217, v34
	v_fma_f32 v33, v34, s62, -v33
	v_fmac_f32_e32 v33, 0x3377d1cf, v34
	v_fmac_f32_e32 v33, 0x3f317217, v34
	v_cmp_lt_f32_e64 s[0:1], |v34|, s63
	v_exp_f32_e32 v38, v38
	v_exp_f32_e32 v39, v39
	v_cndmask_b32_e64 v33, v34, v33, s[0:1]
	v_cndmask_b32_e32 v34, 0, v179, vcc
	v_sub_f32_e32 v33, v33, v34
	v_add_f32_e32 v34, 1.0, v35
	v_cmp_gt_f32_e32 vcc, s61, v34
	v_sub_f32_e32 v33, -0.5, v33
	v_mul_f32_e32 v33, 0x3fb8aa3b, v33
	v_cndmask_b32_e64 v35, 0, 32, vcc
	v_ldexp_f32 v34, v34, v35
	v_log_f32_e32 v34, v34
	v_exp_f32_e32 v33, v33
	v_mul_f32_e32 v36, 0xbfb8aa3b, v36
	v_mul_f32_e32 v37, 0xbfb8aa3b, v37
	v_mul_f32_e32 v35, 0x3f317217, v34
	v_fma_f32 v35, v34, s62, -v35
	v_fmac_f32_e32 v35, 0x3377d1cf, v34
	v_fmac_f32_e32 v35, 0x3f317217, v34
	v_cmp_lt_f32_e64 s[0:1], |v34|, s63
	v_mul_f32_e32 v38, 0xbfb8aa3b, v38
	v_mul_f32_e32 v39, 0xbfb8aa3b, v39
	v_cndmask_b32_e64 v34, v34, v35, s[0:1]
	v_cndmask_b32_e32 v35, 0, v179, vcc
	v_sub_f32_e32 v34, v34, v35
	v_sub_f32_e32 v34, -0.5, v34
	v_mul_f32_e32 v34, 0x3fb8aa3b, v34
	v_exp_f32_e32 v34, v34
	v_exp_f32_e32 v35, v32
	v_mul_f32_e32 v32, 0xbfb8aa3b, v33
	v_exp_f32_e32 v41, v32
	v_mul_f32_e32 v32, 0xbfb8aa3b, v34
	v_exp_f32_e32 v36, v36
	v_exp_f32_e32 v37, v37
	v_exp_f32_e32 v38, v38
	v_exp_f32_e32 v39, v39
	v_exp_f32_e32 v42, v32
	v_cvt_pk_f16_f32 v32, v36, v37
	v_cvt_pk_f16_f32 v33, v38, v39
	v_cvt_pk_f16_f32 v34, v40, v35
	v_cvt_pk_f16_f32 v35, v41, v42
	global_store_dwordx4 v[96:97], v[32:35], off offset:256 sc1
	v_add_f32_e32 v28, v28, v68
	v_mul_f32_e32 v28, 0xbfb8aa3b, v28
	v_exp_f32_e32 v28, v28
	v_add_f32_e32 v29, v29, v69
	v_mul_f32_e32 v29, 0xbfb8aa3b, v29
	v_exp_f32_e32 v29, v29
	v_add_f32_e32 v28, 1.0, v28
	v_cmp_gt_f32_e32 vcc, s61, v28
	v_add_f32_e32 v30, v30, v70
	v_add_f32_e32 v29, 1.0, v29
	v_cndmask_b32_e64 v32, 0, 32, vcc
	v_ldexp_f32 v28, v28, v32
	v_log_f32_e32 v28, v28
	v_mul_f32_e32 v30, 0xbfb8aa3b, v30
	v_exp_f32_e32 v30, v30
	v_add_f32_e32 v31, v31, v71
	v_mul_f32_e32 v32, 0x3f317217, v28
	v_fma_f32 v32, v28, s62, -v32
	v_fmac_f32_e32 v32, 0x3377d1cf, v28
	v_fmac_f32_e32 v32, 0x3f317217, v28
	v_cmp_lt_f32_e64 s[0:1], |v28|, s63
	v_add_f32_e32 v30, 1.0, v30
	v_mul_f32_e32 v31, 0xbfb8aa3b, v31
	v_cndmask_b32_e64 v28, v28, v32, s[0:1]
	v_cndmask_b32_e32 v32, 0, v179, vcc
	v_cmp_gt_f32_e32 vcc, s61, v29
	v_sub_f32_e32 v28, v28, v32
	v_exp_f32_e32 v31, v31
	v_cndmask_b32_e64 v32, 0, 32, vcc
	v_ldexp_f32 v29, v29, v32
	v_log_f32_e32 v29, v29
	v_add_f32_e32 v31, 1.0, v31
	v_add_f32_e32 v24, v24, v64
	v_mul_f32_e32 v24, 0xbfb8aa3b, v24
	v_mul_f32_e32 v32, 0x3f317217, v29
	v_fma_f32 v32, v29, s62, -v32
	v_fmac_f32_e32 v32, 0x3377d1cf, v29
	v_fmac_f32_e32 v32, 0x3f317217, v29
	v_cmp_lt_f32_e64 s[0:1], |v29|, s63
	v_exp_f32_e32 v24, v24
	v_add_f32_e32 v25, v25, v65
	v_cndmask_b32_e64 v29, v29, v32, s[0:1]
	v_cndmask_b32_e32 v32, 0, v179, vcc
	v_cmp_gt_f32_e32 vcc, s61, v30
	v_sub_f32_e32 v29, v29, v32
	v_add_f32_e32 v24, 1.0, v24
	v_cndmask_b32_e64 v32, 0, 32, vcc
	v_ldexp_f32 v30, v30, v32
	v_log_f32_e32 v30, v30
	v_mul_f32_e32 v25, 0xbfb8aa3b, v25
	v_exp_f32_e32 v25, v25
	v_add_f32_e32 v26, v26, v66
	v_mul_f32_e32 v32, 0x3f317217, v30
	v_fma_f32 v32, v30, s62, -v32
	v_fmac_f32_e32 v32, 0x3377d1cf, v30
	v_fmac_f32_e32 v32, 0x3f317217, v30
	v_cmp_lt_f32_e64 s[0:1], |v30|, s63
	v_add_f32_e32 v25, 1.0, v25
	v_mul_f32_e32 v26, 0xbfb8aa3b, v26
	v_cndmask_b32_e64 v30, v30, v32, s[0:1]
	v_cndmask_b32_e32 v32, 0, v179, vcc
	v_cmp_gt_f32_e32 vcc, s61, v31
	v_sub_f32_e32 v30, v30, v32
	v_exp_f32_e32 v26, v26
	v_cndmask_b32_e64 v32, 0, 32, vcc
	v_ldexp_f32 v31, v31, v32
	v_log_f32_e32 v31, v31
	v_add_f32_e32 v26, 1.0, v26
	v_add_f32_e32 v27, v27, v67
	v_mul_f32_e32 v27, 0xbfb8aa3b, v27
	v_mul_f32_e32 v32, 0x3f317217, v31
	v_fma_f32 v32, v31, s62, -v32
	v_fmac_f32_e32 v32, 0x3377d1cf, v31
	v_fmac_f32_e32 v32, 0x3f317217, v31
	v_cmp_lt_f32_e64 s[0:1], |v31|, s63
	v_exp_f32_e32 v27, v27
	v_sub_f32_e32 v28, -0.5, v28
	v_cndmask_b32_e64 v31, v31, v32, s[0:1]
	v_cndmask_b32_e32 v32, 0, v179, vcc
	v_cmp_gt_f32_e32 vcc, s61, v24
;     template <int MODE> __device__ __forceinline__ void run(AccRef acc, const Unit& u, int wr, int wc, int fr, int fq) const {
;     ...
;                     for (int e = 0; e < 4; ++e) { x[e] = acc[ai][bj][m][0][e] + bias[e]; x[4 + e] = acc[ai][bj][m][1][e] + bias[4 + e]; }
;     ...
;                     if (MODE == 0) {
; #pragma unroll
;                         for (int e = 0; e < 8; ++e) { const float sp = __logf(1.f + __expf(-x[e])); x[e] = __expf(-__expf(-sp - 0.5f)); }
;                         w.x = pkh(x[0], x[1]); w.y = pkh(x[2], x[3]); w.z = pkh(x[4], x[5]); w.w = pkh(x[6], x[7]);
;                         *(u32x4*)(WA + (size_t)row * 2048 + seg * 512 + cc) = w;
	v_sub_f32_e32 v31, v31, v32
	v_sub_f32_e32 v29, -0.5, v29
	v_cndmask_b32_e64 v32, 0, 32, vcc
	v_ldexp_f32 v24, v24, v32
	v_log_f32_e32 v24, v24
	v_sub_f32_e32 v30, -0.5, v30
	v_sub_f32_e32 v31, -0.5, v31
	v_mul_f32_e32 v28, 0x3fb8aa3b, v28
	v_mul_f32_e32 v32, 0x3f317217, v24
	v_fma_f32 v32, v24, s62, -v32
	v_fmac_f32_e32 v32, 0x3377d1cf, v24
	v_fmac_f32_e32 v32, 0x3f317217, v24
	v_cmp_lt_f32_e64 s[0:1], |v24|, s63
	v_mul_f32_e32 v29, 0x3fb8aa3b, v29
	v_mul_f32_e32 v30, 0x3fb8aa3b, v30
	v_cndmask_b32_e64 v24, v24, v32, s[0:1]
	v_cndmask_b32_e32 v32, 0, v179, vcc
	v_cmp_gt_f32_e32 vcc, s61, v25
	v_sub_f32_e32 v24, v24, v32
	v_sub_f32_e32 v24, -0.5, v24
	v_cndmask_b32_e64 v32, 0, 32, vcc
	v_ldexp_f32 v25, v25, v32
	v_log_f32_e32 v25, v25
	v_mul_f32_e32 v24, 0x3fb8aa3b, v24
	v_exp_f32_e32 v24, v24
	v_mul_f32_e32 v31, 0x3fb8aa3b, v31
	v_mul_f32_e32 v32, 0x3f317217, v25
	v_fma_f32 v32, v25, s62, -v32
	v_fmac_f32_e32 v32, 0x3377d1cf, v25
	v_fmac_f32_e32 v32, 0x3f317217, v25
	v_cmp_lt_f32_e64 s[0:1], |v25|, s63
	v_mul_f32_e32 v24, 0xbfb8aa3b, v24
	v_exp_f32_e32 v28, v28
	v_cndmask_b32_e64 v25, v25, v32, s[0:1]
	v_cndmask_b32_e32 v32, 0, v179, vcc
	v_sub_f32_e32 v25, v25, v32
	v_cmp_gt_f32_e32 vcc, s61, v26
	v_sub_f32_e32 v25, -0.5, v25
	v_mul_f32_e32 v25, 0x3fb8aa3b, v25
	v_cndmask_b32_e64 v32, 0, 32, vcc
	v_ldexp_f32 v26, v26, v32
	v_exp_f32_e32 v25, v25
	v_log_f32_e32 v26, v26
	v_exp_f32_e32 v32, v24
	v_exp_f32_e32 v29, v29
	v_mul_f32_e32 v24, 0xbfb8aa3b, v25
	v_mul_f32_e32 v25, 0x3f317217, v26
	v_fma_f32 v25, v26, s62, -v25
	v_fmac_f32_e32 v25, 0x3377d1cf, v26
	v_fmac_f32_e32 v25, 0x3f317217, v26
	v_cmp_lt_f32_e64 s[0:1], |v26|, s63
	v_exp_f32_e32 v30, v30
	v_exp_f32_e32 v31, v31
	v_cndmask_b32_e64 v25, v26, v25, s[0:1]
	v_cndmask_b32_e32 v26, 0, v179, vcc
	v_sub_f32_e32 v25, v25, v26
	v_add_f32_e32 v26, 1.0, v27
	v_cmp_gt_f32_e32 vcc, s61, v26
	v_sub_f32_e32 v25, -0.5, v25
	v_mul_f32_e32 v25, 0x3fb8aa3b, v25
	v_cndmask_b32_e64 v27, 0, 32, vcc
	v_ldexp_f32 v26, v26, v27
	v_log_f32_e32 v26, v26
	v_exp_f32_e32 v25, v25
	v_mul_f32_e32 v28, 0xbfb8aa3b, v28
	v_mul_f32_e32 v29, 0xbfb8aa3b, v29
	v_mul_f32_e32 v27, 0x3f317217, v26
	v_fma_f32 v27, v26, s62, -v27
	v_fmac_f32_e32 v27, 0x3377d1cf, v26
	v_fmac_f32_e32 v27, 0x3f317217, v26
	v_cmp_lt_f32_e64 s[0:1], |v26|, s63
	v_mul_f32_e32 v30, 0xbfb8aa3b, v30
	v_mul_f32_e32 v31, 0xbfb8aa3b, v31
	v_cndmask_b32_e64 v26, v26, v27, s[0:1]
	v_cndmask_b32_e32 v27, 0, v179, vcc
	v_sub_f32_e32 v26, v26, v27
	v_sub_f32_e32 v26, -0.5, v26
	v_mul_f32_e32 v26, 0x3fb8aa3b, v26
	v_exp_f32_e32 v26, v26
	v_exp_f32_e32 v27, v24
	v_mul_f32_e32 v24, 0xbfb8aa3b, v25
	v_exp_f32_e32 v33, v24
	v_mul_f32_e32 v24, 0xbfb8aa3b, v26
	v_exp_f32_e32 v28, v28
	v_exp_f32_e32 v29, v29
	v_exp_f32_e32 v30, v30
	v_exp_f32_e32 v31, v31
	v_exp_f32_e32 v34, v24
	v_cvt_pk_f16_f32 v24, v28, v29
	v_cvt_pk_f16_f32 v25, v30, v31
	v_cvt_pk_f16_f32 v26, v32, v27
	v_cvt_pk_f16_f32 v27, v33, v34
	global_store_dwordx4 v[88:89], v[24:27], off offset:256 sc1
	v_add_f32_e32 v20, v20, v68
	v_mul_f32_e32 v20, 0xbfb8aa3b, v20
	v_exp_f32_e32 v20, v20
	v_add_f32_e32 v21, v21, v69
	v_mul_f32_e32 v21, 0xbfb8aa3b, v21
	v_exp_f32_e32 v21, v21
	v_add_f32_e32 v20, 1.0, v20
	v_cmp_gt_f32_e32 vcc, s61, v20
	v_add_f32_e32 v22, v22, v70
	v_add_f32_e32 v21, 1.0, v21
	v_cndmask_b32_e64 v24, 0, 32, vcc
	v_ldexp_f32 v20, v20, v24
	v_log_f32_e32 v20, v20
	v_mul_f32_e32 v22, 0xbfb8aa3b, v22
	v_exp_f32_e32 v22, v22
	v_add_f32_e32 v23, v23, v71
	v_mul_f32_e32 v24, 0x3f317217, v20
	v_fma_f32 v24, v20, s62, -v24
	v_fmac_f32_e32 v24, 0x3377d1cf, v20
	v_fmac_f32_e32 v24, 0x3f317217, v20
	v_cmp_lt_f32_e64 s[0:1], |v20|, s63
	v_add_f32_e32 v22, 1.0, v22
	v_mul_f32_e32 v23, 0xbfb8aa3b, v23
	v_cndmask_b32_e64 v20, v20, v24, s[0:1]
	v_cndmask_b32_e32 v24, 0, v179, vcc
	v_cmp_gt_f32_e32 vcc, s61, v21
	v_sub_f32_e32 v20, v20, v24
	v_exp_f32_e32 v23, v23
	v_cndmask_b32_e64 v24, 0, 32, vcc
	v_ldexp_f32 v21, v21, v24
	v_log_f32_e32 v21, v21
	v_add_f32_e32 v23, 1.0, v23
	v_add_f32_e32 v16, v16, v64
	v_mul_f32_e32 v16, 0xbfb8aa3b, v16
	v_mul_f32_e32 v24, 0x3f317217, v21
	v_fma_f32 v24, v21, s62, -v24
	v_fmac_f32_e32 v24, 0x3377d1cf, v21
	v_fmac_f32_e32 v24, 0x3f317217, v21
	v_cmp_lt_f32_e64 s[0:1], |v21|, s63
	v_exp_f32_e32 v16, v16
	v_add_f32_e32 v17, v17, v65
	v_cndmask_b32_e64 v21, v21, v24, s[0:1]
	v_cndmask_b32_e32 v24, 0, v179, vcc
	v_cmp_gt_f32_e32 vcc, s61, v22
	v_sub_f32_e32 v21, v21, v24
	v_add_f32_e32 v16, 1.0, v16
	v_cndmask_b32_e64 v24, 0, 32, vcc
	v_ldexp_f32 v22, v22, v24
	v_log_f32_e32 v22, v22
	v_mul_f32_e32 v17, 0xbfb8aa3b, v17
	v_exp_f32_e32 v17, v17
	v_add_f32_e32 v18, v18, v66
	v_mul_f32_e32 v24, 0x3f317217, v22
	v_fma_f32 v24, v22, s62, -v24
	v_fmac_f32_e32 v24, 0x3377d1cf, v22
	v_fmac_f32_e32 v24, 0x3f317217, v22
	v_cmp_lt_f32_e64 s[0:1], |v22|, s63
	v_add_f32_e32 v17, 1.0, v17
	v_mul_f32_e32 v18, 0xbfb8aa3b, v18
	v_cndmask_b32_e64 v22, v22, v24, s[0:1]
	v_cndmask_b32_e32 v24, 0, v179, vcc
	v_cmp_gt_f32_e32 vcc, s61, v23
	v_sub_f32_e32 v22, v22, v24
	v_exp_f32_e32 v18, v18
	v_cndmask_b32_e64 v24, 0, 32, vcc
	v_ldexp_f32 v23, v23, v24
	v_log_f32_e32 v23, v23
	v_add_f32_e32 v18, 1.0, v18
	v_add_f32_e32 v19, v19, v67
	v_mul_f32_e32 v19, 0xbfb8aa3b, v19
	v_mul_f32_e32 v24, 0x3f317217, v23
	v_fma_f32 v24, v23, s62, -v24
	v_fmac_f32_e32 v24, 0x3377d1cf, v23
	v_fmac_f32_e32 v24, 0x3f317217, v23
	v_cmp_lt_f32_e64 s[0:1], |v23|, s63
	v_exp_f32_e32 v19, v19
	v_sub_f32_e32 v20, -0.5, v20
	v_cndmask_b32_e64 v23, v23, v24, s[0:1]
	v_cndmask_b32_e32 v24, 0, v179, vcc
	v_cmp_gt_f32_e32 vcc, s61, v16
	v_sub_f32_e32 v23, v23, v24
	v_sub_f32_e32 v21, -0.5, v21
	v_cndmask_b32_e64 v24, 0, 32, vcc
;     template <int MODE> __device__ __forceinline__ void run(AccRef acc, const Unit& u, int wr, int wc, int fr, int fq) const {
;     ...
;                     for (int e = 0; e < 4; ++e) { x[e] = acc[ai][bj][m][0][e] + bias[e]; x[4 + e] = acc[ai][bj][m][1][e] + bias[4 + e]; }
;     ...
;                     if (MODE == 0) {
; #pragma unroll
;                         for (int e = 0; e < 8; ++e) { const float sp = __logf(1.f + __expf(-x[e])); x[e] = __expf(-__expf(-sp - 0.5f)); }
;                         w.x = pkh(x[0], x[1]); w.y = pkh(x[2], x[3]); w.z = pkh(x[4], x[5]); w.w = pkh(x[6], x[7]);
;                         *(u32x4*)(WA + (size_t)row * 2048 + seg * 512 + cc) = w;
	v_ldexp_f32 v16, v16, v24
	v_log_f32_e32 v16, v16
	v_sub_f32_e32 v22, -0.5, v22
	v_sub_f32_e32 v23, -0.5, v23
	v_mul_f32_e32 v20, 0x3fb8aa3b, v20
	v_mul_f32_e32 v24, 0x3f317217, v16
	v_fma_f32 v24, v16, s62, -v24
	v_fmac_f32_e32 v24, 0x3377d1cf, v16
	v_fmac_f32_e32 v24, 0x3f317217, v16
	v_cmp_lt_f32_e64 s[0:1], |v16|, s63
	v_mul_f32_e32 v21, 0x3fb8aa3b, v21
	v_mul_f32_e32 v22, 0x3fb8aa3b, v22
	v_cndmask_b32_e64 v16, v16, v24, s[0:1]
	v_cndmask_b32_e32 v24, 0, v179, vcc
	v_cmp_gt_f32_e32 vcc, s61, v17
	v_sub_f32_e32 v16, v16, v24
	v_sub_f32_e32 v16, -0.5, v16
	v_cndmask_b32_e64 v24, 0, 32, vcc
	v_ldexp_f32 v17, v17, v24
	v_log_f32_e32 v17, v17
	v_mul_f32_e32 v16, 0x3fb8aa3b, v16
	v_exp_f32_e32 v16, v16
	v_mul_f32_e32 v23, 0x3fb8aa3b, v23
	v_mul_f32_e32 v24, 0x3f317217, v17
	v_fma_f32 v24, v17, s62, -v24
	v_fmac_f32_e32 v24, 0x3377d1cf, v17
	v_fmac_f32_e32 v24, 0x3f317217, v17
	v_cmp_lt_f32_e64 s[0:1], |v17|, s63
	v_mul_f32_e32 v16, 0xbfb8aa3b, v16
	v_exp_f32_e32 v20, v20
	v_cndmask_b32_e64 v17, v17, v24, s[0:1]
	v_cndmask_b32_e32 v24, 0, v179, vcc
	v_sub_f32_e32 v17, v17, v24
	v_cmp_gt_f32_e32 vcc, s61, v18
	v_sub_f32_e32 v17, -0.5, v17
	v_mul_f32_e32 v17, 0x3fb8aa3b, v17
	v_cndmask_b32_e64 v24, 0, 32, vcc
	v_ldexp_f32 v18, v18, v24
	v_exp_f32_e32 v17, v17
	v_log_f32_e32 v18, v18
	v_exp_f32_e32 v24, v16
	v_exp_f32_e32 v21, v21
	v_mul_f32_e32 v16, 0xbfb8aa3b, v17
	v_mul_f32_e32 v17, 0x3f317217, v18
	v_fma_f32 v17, v18, s62, -v17
	v_fmac_f32_e32 v17, 0x3377d1cf, v18
	v_fmac_f32_e32 v17, 0x3f317217, v18
	v_cmp_lt_f32_e64 s[0:1], |v18|, s63
	v_exp_f32_e32 v22, v22
	v_exp_f32_e32 v23, v23
	v_cndmask_b32_e64 v17, v18, v17, s[0:1]
	v_cndmask_b32_e32 v18, 0, v179, vcc
	v_sub_f32_e32 v17, v17, v18
	v_add_f32_e32 v18, 1.0, v19
	v_cmp_gt_f32_e32 vcc, s61, v18
	v_sub_f32_e32 v17, -0.5, v17
	v_mul_f32_e32 v17, 0x3fb8aa3b, v17
	v_cndmask_b32_e64 v19, 0, 32, vcc
	v_ldexp_f32 v18, v18, v19
	v_log_f32_e32 v18, v18
	v_exp_f32_e32 v17, v17
	v_mul_f32_e32 v20, 0xbfb8aa3b, v20
	v_mul_f32_e32 v21, 0xbfb8aa3b, v21
	v_mul_f32_e32 v19, 0x3f317217, v18
	v_fma_f32 v19, v18, s62, -v19
	v_fmac_f32_e32 v19, 0x3377d1cf, v18
	v_fmac_f32_e32 v19, 0x3f317217, v18
	v_cmp_lt_f32_e64 s[0:1], |v18|, s63
	v_mul_f32_e32 v22, 0xbfb8aa3b, v22
	v_mul_f32_e32 v23, 0xbfb8aa3b, v23
	v_cndmask_b32_e64 v18, v18, v19, s[0:1]
	v_cndmask_b32_e32 v19, 0, v179, vcc
	v_sub_f32_e32 v18, v18, v19
	v_sub_f32_e32 v18, -0.5, v18
	v_mul_f32_e32 v18, 0x3fb8aa3b, v18
	v_exp_f32_e32 v18, v18
	v_exp_f32_e32 v19, v16
	v_mul_f32_e32 v16, 0xbfb8aa3b, v17
	v_exp_f32_e32 v25, v16
	v_mul_f32_e32 v16, 0xbfb8aa3b, v18
	v_exp_f32_e32 v20, v20
	v_exp_f32_e32 v21, v21
	v_exp_f32_e32 v22, v22
	v_exp_f32_e32 v23, v23
	v_exp_f32_e32 v26, v16
	v_cvt_pk_f16_f32 v16, v20, v21
	v_cvt_pk_f16_f32 v17, v22, v23
	v_cvt_pk_f16_f32 v18, v24, v19
	v_cvt_pk_f16_f32 v19, v25, v26
	global_store_dwordx4 v[80:81], v[16:19], off offset:256 sc1
	v_add_f32_e32 v12, v12, v68
	v_mul_f32_e32 v12, 0xbfb8aa3b, v12
	v_exp_f32_e32 v12, v12
	v_add_f32_e32 v13, v13, v69
	v_mul_f32_e32 v13, 0xbfb8aa3b, v13
	v_exp_f32_e32 v13, v13
	v_add_f32_e32 v12, 1.0, v12
	v_cmp_gt_f32_e32 vcc, s61, v12
	v_add_f32_e32 v14, v14, v70
	v_add_f32_e32 v13, 1.0, v13
	v_cndmask_b32_e64 v16, 0, 32, vcc
	v_ldexp_f32 v12, v12, v16
	v_log_f32_e32 v12, v12
	v_mul_f32_e32 v14, 0xbfb8aa3b, v14
	v_exp_f32_e32 v14, v14
	v_add_f32_e32 v15, v15, v71
	v_mul_f32_e32 v16, 0x3f317217, v12
	v_fma_f32 v16, v12, s62, -v16
	v_fmac_f32_e32 v16, 0x3377d1cf, v12
	v_fmac_f32_e32 v16, 0x3f317217, v12
	v_cmp_lt_f32_e64 s[0:1], |v12|, s63
	v_add_f32_e32 v14, 1.0, v14
	v_mul_f32_e32 v15, 0xbfb8aa3b, v15
	v_cndmask_b32_e64 v12, v12, v16, s[0:1]
	v_cndmask_b32_e32 v16, 0, v179, vcc
	v_cmp_gt_f32_e32 vcc, s61, v13
	v_sub_f32_e32 v12, v12, v16
	v_exp_f32_e32 v15, v15
	v_cndmask_b32_e64 v16, 0, 32, vcc
	v_ldexp_f32 v13, v13, v16
	v_log_f32_e32 v13, v13
	v_add_f32_e32 v15, 1.0, v15
	v_add_f32_e32 v8, v8, v64
	v_mul_f32_e32 v8, 0xbfb8aa3b, v8
	v_mul_f32_e32 v16, 0x3f317217, v13
	v_fma_f32 v16, v13, s62, -v16
	v_fmac_f32_e32 v16, 0x3377d1cf, v13
	v_fmac_f32_e32 v16, 0x3f317217, v13
	v_cmp_lt_f32_e64 s[0:1], |v13|, s63
	v_exp_f32_e32 v8, v8
	v_add_f32_e32 v9, v9, v65
	v_cndmask_b32_e64 v13, v13, v16, s[0:1]
	v_cndmask_b32_e32 v16, 0, v179, vcc
	v_cmp_gt_f32_e32 vcc, s61, v14
	v_sub_f32_e32 v13, v13, v16
	v_add_f32_e32 v8, 1.0, v8
	v_cndmask_b32_e64 v16, 0, 32, vcc
	v_ldexp_f32 v14, v14, v16
	v_log_f32_e32 v14, v14
	v_mul_f32_e32 v9, 0xbfb8aa3b, v9
	v_exp_f32_e32 v9, v9
	v_add_f32_e32 v10, v10, v66
	v_mul_f32_e32 v16, 0x3f317217, v14
	v_fma_f32 v16, v14, s62, -v16
	v_fmac_f32_e32 v16, 0x3377d1cf, v14
	v_fmac_f32_e32 v16, 0x3f317217, v14
	v_cmp_lt_f32_e64 s[0:1], |v14|, s63
	v_add_f32_e32 v9, 1.0, v9
	v_mul_f32_e32 v10, 0xbfb8aa3b, v10
	v_cndmask_b32_e64 v14, v14, v16, s[0:1]
	v_cndmask_b32_e32 v16, 0, v179, vcc
	v_cmp_gt_f32_e32 vcc, s61, v15
	v_sub_f32_e32 v14, v14, v16
	v_exp_f32_e32 v10, v10
	v_cndmask_b32_e64 v16, 0, 32, vcc
	v_ldexp_f32 v15, v15, v16
	v_log_f32_e32 v15, v15
	v_add_f32_e32 v10, 1.0, v10
	v_add_f32_e32 v11, v11, v67
	v_mul_f32_e32 v11, 0xbfb8aa3b, v11
	v_mul_f32_e32 v16, 0x3f317217, v15
	v_fma_f32 v16, v15, s62, -v16
	v_fmac_f32_e32 v16, 0x3377d1cf, v15
	v_fmac_f32_e32 v16, 0x3f317217, v15
	v_cmp_lt_f32_e64 s[0:1], |v15|, s63
	v_exp_f32_e32 v11, v11
	v_sub_f32_e32 v12, -0.5, v12
	v_cndmask_b32_e64 v15, v15, v16, s[0:1]
	v_cndmask_b32_e32 v16, 0, v179, vcc
	v_cmp_gt_f32_e32 vcc, s61, v8
	v_sub_f32_e32 v15, v15, v16
	v_sub_f32_e32 v13, -0.5, v13
	v_cndmask_b32_e64 v16, 0, 32, vcc
	v_ldexp_f32 v8, v8, v16
	v_log_f32_e32 v8, v8
	v_sub_f32_e32 v14, -0.5, v14
	v_sub_f32_e32 v15, -0.5, v15
;     template <int MODE> __device__ __forceinline__ void run(AccRef acc, const Unit& u, int wr, int wc, int fr, int fq) const {
;     ...
;                     for (int e = 0; e < 4; ++e) { x[e] = acc[ai][bj][m][0][e] + bias[e]; x[4 + e] = acc[ai][bj][m][1][e] + bias[4 + e]; }
;                     u32x4 w;
;                     if (MODE == 0) {
; #pragma unroll
;                         for (int e = 0; e < 8; ++e) { const float sp = __logf(1.f + __expf(-x[e])); x[e] = __expf(-__expf(-sp - 0.5f)); }
;                         w.x = pkh(x[0], x[1]); w.y = pkh(x[2], x[3]); w.z = pkh(x[4], x[5]); w.w = pkh(x[6], x[7]);
;                         *(u32x4*)(WA + (size_t)row * 2048 + seg * 512 + cc) = w;
	v_mul_f32_e32 v12, 0x3fb8aa3b, v12
	v_mul_f32_e32 v16, 0x3f317217, v8
	v_fma_f32 v16, v8, s62, -v16
	v_fmac_f32_e32 v16, 0x3377d1cf, v8
	v_fmac_f32_e32 v16, 0x3f317217, v8
	v_cmp_lt_f32_e64 s[0:1], |v8|, s63
	v_mul_f32_e32 v13, 0x3fb8aa3b, v13
	v_mul_f32_e32 v14, 0x3fb8aa3b, v14
	v_cndmask_b32_e64 v8, v8, v16, s[0:1]
	v_cndmask_b32_e32 v16, 0, v179, vcc
	v_cmp_gt_f32_e32 vcc, s61, v9
	v_sub_f32_e32 v8, v8, v16
	v_sub_f32_e32 v8, -0.5, v8
	v_cndmask_b32_e64 v16, 0, 32, vcc
	v_ldexp_f32 v9, v9, v16
	v_log_f32_e32 v9, v9
	v_mul_f32_e32 v8, 0x3fb8aa3b, v8
	v_exp_f32_e32 v8, v8
	v_mul_f32_e32 v15, 0x3fb8aa3b, v15
	v_mul_f32_e32 v16, 0x3f317217, v9
	v_fma_f32 v16, v9, s62, -v16
	v_fmac_f32_e32 v16, 0x3377d1cf, v9
	v_fmac_f32_e32 v16, 0x3f317217, v9
	v_cmp_lt_f32_e64 s[0:1], |v9|, s63
	v_mul_f32_e32 v8, 0xbfb8aa3b, v8
	v_exp_f32_e32 v12, v12
	v_cndmask_b32_e64 v9, v9, v16, s[0:1]
	v_cndmask_b32_e32 v16, 0, v179, vcc
	v_sub_f32_e32 v9, v9, v16
	v_cmp_gt_f32_e32 vcc, s61, v10
	v_sub_f32_e32 v9, -0.5, v9
	v_mul_f32_e32 v9, 0x3fb8aa3b, v9
	v_cndmask_b32_e64 v16, 0, 32, vcc
	v_ldexp_f32 v10, v10, v16
	v_exp_f32_e32 v9, v9
	v_log_f32_e32 v10, v10
	v_exp_f32_e32 v16, v8
	v_exp_f32_e32 v13, v13
	v_mul_f32_e32 v8, 0xbfb8aa3b, v9
	v_mul_f32_e32 v9, 0x3f317217, v10
	v_fma_f32 v9, v10, s62, -v9
	v_fmac_f32_e32 v9, 0x3377d1cf, v10
	v_fmac_f32_e32 v9, 0x3f317217, v10
	v_cmp_lt_f32_e64 s[0:1], |v10|, s63
	v_exp_f32_e32 v14, v14
	v_exp_f32_e32 v15, v15
	v_cndmask_b32_e64 v9, v10, v9, s[0:1]
	v_cndmask_b32_e32 v10, 0, v179, vcc
	v_sub_f32_e32 v9, v9, v10
	v_add_f32_e32 v10, 1.0, v11
	v_cmp_gt_f32_e32 vcc, s61, v10
	v_sub_f32_e32 v9, -0.5, v9
	v_mul_f32_e32 v9, 0x3fb8aa3b, v9
	v_cndmask_b32_e64 v11, 0, 32, vcc
	v_ldexp_f32 v10, v10, v11
	v_log_f32_e32 v10, v10
	v_exp_f32_e32 v9, v9
	v_mul_f32_e32 v12, 0xbfb8aa3b, v12
	v_mul_f32_e32 v13, 0xbfb8aa3b, v13
	v_mul_f32_e32 v11, 0x3f317217, v10
	v_fma_f32 v11, v10, s62, -v11
	v_fmac_f32_e32 v11, 0x3377d1cf, v10
	v_fmac_f32_e32 v11, 0x3f317217, v10
	v_cmp_lt_f32_e64 s[0:1], |v10|, s63
	v_mul_f32_e32 v14, 0xbfb8aa3b, v14
	v_mul_f32_e32 v15, 0xbfb8aa3b, v15
	v_cndmask_b32_e64 v10, v10, v11, s[0:1]
	v_cndmask_b32_e32 v11, 0, v179, vcc
	v_sub_f32_e32 v10, v10, v11
	v_sub_f32_e32 v10, -0.5, v10
	v_mul_f32_e32 v10, 0x3fb8aa3b, v10
	v_exp_f32_e32 v10, v10
	v_exp_f32_e32 v11, v8
	v_mul_f32_e32 v8, 0xbfb8aa3b, v9
	v_exp_f32_e32 v17, v8
	v_mul_f32_e32 v8, 0xbfb8aa3b, v10
	v_exp_f32_e32 v12, v12
	v_exp_f32_e32 v13, v13
	v_exp_f32_e32 v14, v14
	v_exp_f32_e32 v15, v15
	v_exp_f32_e32 v18, v8
	v_cvt_pk_f16_f32 v8, v12, v13
	v_cvt_pk_f16_f32 v9, v14, v15
	v_cvt_pk_f16_f32 v10, v16, v11
	v_cvt_pk_f16_f32 v11, v17, v18
	global_store_dwordx4 v[72:73], v[8:11], off offset:256 sc1
	v_add_f32_e32 v4, v4, v68
	v_mul_f32_e32 v4, 0xbfb8aa3b, v4
	v_exp_f32_e32 v4, v4
	v_add_f32_e32 v5, v5, v69
	v_mul_f32_e32 v5, 0xbfb8aa3b, v5
	v_exp_f32_e32 v5, v5
	v_add_f32_e32 v4, 1.0, v4
	v_cmp_gt_f32_e32 vcc, s61, v4
	v_add_f32_e32 v6, v6, v70
	v_add_f32_e32 v5, 1.0, v5
	v_cndmask_b32_e64 v8, 0, 32, vcc
	v_ldexp_f32 v4, v4, v8
	v_log_f32_e32 v4, v4
	v_mul_f32_e32 v6, 0xbfb8aa3b, v6
	v_exp_f32_e32 v6, v6
	v_add_f32_e32 v7, v7, v71
	v_mul_f32_e32 v8, 0x3f317217, v4
	v_fma_f32 v8, v4, s62, -v8
	v_fmac_f32_e32 v8, 0x3377d1cf, v4
	v_fmac_f32_e32 v8, 0x3f317217, v4
	v_cmp_lt_f32_e64 s[0:1], |v4|, s63
	v_add_f32_e32 v6, 1.0, v6
	v_mul_f32_e32 v7, 0xbfb8aa3b, v7
	v_cndmask_b32_e64 v4, v4, v8, s[0:1]
	v_cndmask_b32_e32 v8, 0, v179, vcc
	v_cmp_gt_f32_e32 vcc, s61, v5
	v_sub_f32_e32 v4, v4, v8
	v_exp_f32_e32 v7, v7
	v_cndmask_b32_e64 v8, 0, 32, vcc
	v_ldexp_f32 v5, v5, v8
	v_log_f32_e32 v5, v5
	v_add_f32_e32 v7, 1.0, v7
	v_add_f32_e32 v0, v0, v64
	v_mul_f32_e32 v0, 0xbfb8aa3b, v0
	v_mul_f32_e32 v8, 0x3f317217, v5
	v_fma_f32 v8, v5, s62, -v8
	v_fmac_f32_e32 v8, 0x3377d1cf, v5
	v_fmac_f32_e32 v8, 0x3f317217, v5
	v_cmp_lt_f32_e64 s[0:1], |v5|, s63
	v_exp_f32_e32 v0, v0
	v_add_f32_e32 v1, v1, v65
	v_cndmask_b32_e64 v5, v5, v8, s[0:1]
	v_cndmask_b32_e32 v8, 0, v179, vcc
;     template <int MODE> __device__ __forceinline__ void run(AccRef acc, const Unit& u, int wr, int wc, int fr, int fq) const {
;     ...
;                     for (int e = 0; e < 4; ++e) { x[e] = acc[ai][bj][m][0][e] + bias[e]; x[4 + e] = acc[ai][bj][m][1][e] + bias[4 + e]; }
;                     u32x4 w;
;                     if (MODE == 0) {
; #pragma unroll
;                         for (int e = 0; e < 8; ++e) { const float sp = __logf(1.f + __expf(-x[e])); x[e] = __expf(-__expf(-sp - 0.5f)); }
;                         w.x = pkh(x[0], x[1]); w.y = pkh(x[2], x[3]); w.z = pkh(x[4], x[5]); w.w = pkh(x[6], x[7]);
;                         *(u32x4*)(WA + (size_t)row * 2048 + seg * 512 + cc) = w;
	v_cmp_gt_f32_e32 vcc, s61, v6
	v_sub_f32_e32 v5, v5, v8
	v_add_f32_e32 v0, 1.0, v0
	v_cndmask_b32_e64 v8, 0, 32, vcc
	v_ldexp_f32 v6, v6, v8
	v_log_f32_e32 v6, v6
	v_mul_f32_e32 v1, 0xbfb8aa3b, v1
	v_exp_f32_e32 v1, v1
	v_add_f32_e32 v2, v2, v66
	v_mul_f32_e32 v8, 0x3f317217, v6
	v_fma_f32 v8, v6, s62, -v8
	v_fmac_f32_e32 v8, 0x3377d1cf, v6
	v_fmac_f32_e32 v8, 0x3f317217, v6
	v_cmp_lt_f32_e64 s[0:1], |v6|, s63
	v_add_f32_e32 v1, 1.0, v1
	v_mul_f32_e32 v2, 0xbfb8aa3b, v2
	v_cndmask_b32_e64 v6, v6, v8, s[0:1]
	v_cndmask_b32_e32 v8, 0, v179, vcc
	v_cmp_gt_f32_e32 vcc, s61, v7
	v_sub_f32_e32 v6, v6, v8
	v_exp_f32_e32 v2, v2
	v_cndmask_b32_e64 v8, 0, 32, vcc
	v_ldexp_f32 v7, v7, v8
	v_log_f32_e32 v7, v7
	v_add_f32_e32 v2, 1.0, v2
	v_add_f32_e32 v3, v3, v67
	v_mul_f32_e32 v3, 0xbfb8aa3b, v3
	v_mul_f32_e32 v8, 0x3f317217, v7
	v_fma_f32 v8, v7, s62, -v8
	v_fmac_f32_e32 v8, 0x3377d1cf, v7
	v_fmac_f32_e32 v8, 0x3f317217, v7
	v_cmp_lt_f32_e64 s[0:1], |v7|, s63
	v_exp_f32_e32 v3, v3
	v_sub_f32_e32 v4, -0.5, v4
	v_cndmask_b32_e64 v7, v7, v8, s[0:1]
	v_cndmask_b32_e32 v8, 0, v179, vcc
	v_cmp_gt_f32_e32 vcc, s61, v0
	v_sub_f32_e32 v7, v7, v8
	v_sub_f32_e32 v5, -0.5, v5
	v_cndmask_b32_e64 v8, 0, 32, vcc
	v_ldexp_f32 v0, v0, v8
	v_log_f32_e32 v0, v0
	v_sub_f32_e32 v6, -0.5, v6
	v_sub_f32_e32 v7, -0.5, v7
	v_mul_f32_e32 v4, 0x3fb8aa3b, v4
	v_mul_f32_e32 v8, 0x3f317217, v0
	v_fma_f32 v8, v0, s62, -v8
	v_fmac_f32_e32 v8, 0x3377d1cf, v0
	v_fmac_f32_e32 v8, 0x3f317217, v0
	v_cmp_lt_f32_e64 s[0:1], |v0|, s63
	v_mul_f32_e32 v5, 0x3fb8aa3b, v5
	v_mul_f32_e32 v6, 0x3fb8aa3b, v6
	v_cndmask_b32_e64 v0, v0, v8, s[0:1]
	v_cndmask_b32_e32 v8, 0, v179, vcc
	v_cmp_gt_f32_e32 vcc, s61, v1
	v_sub_f32_e32 v0, v0, v8
	v_sub_f32_e32 v0, -0.5, v0
	v_cndmask_b32_e64 v8, 0, 32, vcc
	v_ldexp_f32 v1, v1, v8
	v_log_f32_e32 v1, v1
	v_mul_f32_e32 v0, 0x3fb8aa3b, v0
	v_exp_f32_e32 v0, v0
	v_mul_f32_e32 v7, 0x3fb8aa3b, v7
	v_mul_f32_e32 v8, 0x3f317217, v1
	v_fma_f32 v8, v1, s62, -v8
	v_fmac_f32_e32 v8, 0x3377d1cf, v1
	v_fmac_f32_e32 v8, 0x3f317217, v1
	v_cmp_lt_f32_e64 s[0:1], |v1|, s63
	v_mul_f32_e32 v0, 0xbfb8aa3b, v0
	v_exp_f32_e32 v4, v4
	v_cndmask_b32_e64 v1, v1, v8, s[0:1]
	v_cndmask_b32_e32 v8, 0, v179, vcc
	v_sub_f32_e32 v1, v1, v8
	v_cmp_gt_f32_e32 vcc, s61, v2
	v_sub_f32_e32 v1, -0.5, v1
	v_mul_f32_e32 v1, 0x3fb8aa3b, v1
	v_cndmask_b32_e64 v8, 0, 32, vcc
	v_ldexp_f32 v2, v2, v8
	v_exp_f32_e32 v1, v1
	v_log_f32_e32 v2, v2
	v_exp_f32_e32 v8, v0
	v_exp_f32_e32 v5, v5
	v_mul_f32_e32 v0, 0xbfb8aa3b, v1
	v_mul_f32_e32 v1, 0x3f317217, v2
	v_fma_f32 v1, v2, s62, -v1
	v_fmac_f32_e32 v1, 0x3377d1cf, v2
	v_fmac_f32_e32 v1, 0x3f317217, v2
	v_cmp_lt_f32_e64 s[0:1], |v2|, s63
	v_exp_f32_e32 v6, v6
	v_exp_f32_e32 v7, v7
	v_cndmask_b32_e64 v1, v2, v1, s[0:1]
	v_cndmask_b32_e32 v2, 0, v179, vcc
	v_sub_f32_e32 v1, v1, v2
	v_add_f32_e32 v2, 1.0, v3
	v_cmp_gt_f32_e32 vcc, s61, v2
	v_sub_f32_e32 v1, -0.5, v1
	v_mul_f32_e32 v1, 0x3fb8aa3b, v1
	v_cndmask_b32_e64 v3, 0, 32, vcc
	v_ldexp_f32 v2, v2, v3
	v_log_f32_e32 v2, v2
	v_exp_f32_e32 v1, v1
	v_mul_f32_e32 v4, 0xbfb8aa3b, v4
	v_mul_f32_e32 v5, 0xbfb8aa3b, v5
	v_mul_f32_e32 v3, 0x3f317217, v2
	v_fma_f32 v3, v2, s62, -v3
	v_fmac_f32_e32 v3, 0x3377d1cf, v2
	v_fmac_f32_e32 v3, 0x3f317217, v2
	v_cmp_lt_f32_e64 s[0:1], |v2|, s63
	v_mul_f32_e32 v6, 0xbfb8aa3b, v6
	v_mul_f32_e32 v7, 0xbfb8aa3b, v7
	v_cndmask_b32_e64 v2, v2, v3, s[0:1]
	v_cndmask_b32_e32 v3, 0, v179, vcc
	v_sub_f32_e32 v2, v2, v3
	v_sub_f32_e32 v2, -0.5, v2
	v_mul_f32_e32 v2, 0x3fb8aa3b, v2
	v_exp_f32_e32 v2, v2
	v_exp_f32_e32 v3, v0
	v_mul_f32_e32 v0, 0xbfb8aa3b, v1
	v_exp_f32_e32 v9, v0
	v_mul_f32_e32 v0, 0xbfb8aa3b, v2
	v_exp_f32_e32 v4, v4
	v_exp_f32_e32 v5, v5
	v_exp_f32_e32 v6, v6
	v_exp_f32_e32 v7, v7
	v_exp_f32_e32 v10, v0
	v_cvt_pk_f16_f32 v0, v4, v5
	v_cvt_pk_f16_f32 v1, v6, v7
	v_cvt_pk_f16_f32 v2, v8, v3
	v_cvt_pk_f16_f32 v3, v9, v10
	global_store_dwordx4 v[74:75], v[0:3], off offset:256 sc1
	s_and_b64 vcc, exec, s[6:7]
	s_mov_b64 s[0:1], -1
	s_cbranch_vccnz .LBB0_833

; __device__ __forceinline__ unsigned pkbf(float lo, float hi) { return pg8::cvt_pk_bf16(lo, hi); }
; __device__ __forceinline__ float fsigmoid(float x) { return __builtin_amdgcn_rcpf(1.f + __builtin_amdgcn_exp2f(-1.4426950408889634f * x)); }
;     template <int MODE> __device__ __forceinline__ void run(AccRef acc, const Unit& u, int wr, int wc, int fr, int fq) const {
;     ...
;                     for (int e = 0; e < 4; ++e) { x[e] = acc[ai][bj][m][0][e] + bias[e]; x[4 + e] = acc[ai][bj][m][1][e] + bias[4 + e]; }
;                     u32x4 w;
;                     if (MODE == 0) {
; #pragma unroll
;                         for (int e = 0; e < 8; ++e) { const float sp = __logf(1.f + __expf(-x[e])); x[e] = __expf(-__expf(-sp - 0.5f)); }
;                         w.x = pkh(x[0], x[1]); w.y = pkh(x[2], x[3]); w.z = pkh(x[4], x[5]); w.w = pkh(x[6], x[7]);
;                         *(u32x4*)(WA + (size_t)row * 2048 + seg * 512 + cc) = w;
;                     } else if (MODE == 1) {
; #pragma unroll
;                         for (int e = 0; e < 8; ++e) x[e] = fsigmoid(x[e]);
;                         w.x = pkh(x[0], x[1]); w.y = pkh(x[2], x[3]); w.z = pkh(x[4], x[5]); w.w = pkh(x[6], x[7]);
;                         *(u32x4*)(WA + (size_t)row * 2048 + seg * 512 + cc) = w;
;                     } else {
;                         w.x = pkbf(x[0], x[1]); w.y = pkbf(x[2], x[3]); w.z = pkbf(x[4], x[5]); w.w = pkbf(x[6], x[7]);
;                         *(u32x4*)(MIX + (size_t)row * 1024 + 512 + cc) = w;
.LBB0_874:
	s_ashr_i32 s4, s69, 1
	v_mov_b32_e32 v181, v165
	v_mov_b32_e32 v180, v174
	s_cmp_gt_i32 s4, -3
	s_mov_b64 s[0:1], -1
	s_cbranch_scc0 .LBB0_881
	s_lshl_b32 s5, s62, 8
	s_cmp_lt_u32 s4, -4
	v_lshlrev_b32_e32 v128, 3, v180
	s_cbranch_scc0 .LBB0_877
	s_add_i32 s0, s5, s3
	v_add_u32_e32 v134, s0, v181
	s_lshl_b32 s0, s69, 8
	s_and_b32 s0, s0, 0x100
	v_add_f32_e32 v132, 0, v124
	v_add_f32_e32 v130, 0, v121
	v_add_f32_e32 v133, 0, v125
	v_add_f32_e32 v131, 0, v122
	v_add_f32_e32 v135, 0, v126
	s_or_b32 s0, s0, s35
	v_add_f32_e32 v129, 0, v120
	v_add_f32_e32 v138, 0, v123
	v_add_f32_e32 v139, 0, v127
	v_cvt_pk_bf16_f32 v130, v129, v130
	v_cvt_pk_bf16_f32 v131, v131, v138
	v_cvt_pk_bf16_f32 v132, v132, v133
	v_cvt_pk_bf16_f32 v133, v135, v139
	v_ashrrev_i32_e32 v135, 31, v134
	v_add_u32_e32 v136, s0, v128
	v_lshlrev_b64 v[134:135], 11, v[134:135]
	v_ashrrev_i32_e32 v137, 31, v136
	v_lshl_add_u64 v[134:135], s[76:77], 0, v[134:135]
	v_lshl_add_u64 v[134:135], v[136:137], 1, v[134:135]
	global_store_dwordx4 v[134:135], v[130:133], off offset:1024 sc1
	s_nop 1
	v_add_f32_e32 v132, 0, v112
	v_add_f32_e32 v130, 0, v117
	v_add_f32_e32 v133, 0, v113
	v_add_f32_e32 v131, 0, v118
	v_add_f32_e32 v136, 0, v114
	v_add_f32_e32 v137, 0, v119
	s_mov_b64 s[0:1], 0x8000
	v_add_f32_e32 v129, 0, v116
	v_add_f32_e32 v138, 0, v115
	v_cvt_pk_bf16_f32 v130, v129, v130
	v_cvt_pk_bf16_f32 v131, v131, v137
	v_cvt_pk_bf16_f32 v132, v132, v133
	v_cvt_pk_bf16_f32 v133, v136, v138
	v_lshl_add_u64 v[136:137], v[134:135], 0, s[0:1]
	global_store_dwordx4 v[136:137], v[130:133], off offset:1024 sc1
	s_nop 1
	v_add_f32_e32 v132, 0, v104
	v_add_f32_e32 v130, 0, v109
	v_add_f32_e32 v133, 0, v105
	v_add_f32_e32 v131, 0, v110
	v_add_f32_e32 v138, 0, v106
	v_add_f32_e32 v139, 0, v111
	v_add_f32_e32 v129, 0, v108
	v_add_f32_e32 v156, 0, v107
	v_cvt_pk_bf16_f32 v130, v129, v130
	v_cvt_pk_bf16_f32 v131, v131, v139
	v_cvt_pk_bf16_f32 v132, v132, v133
	v_cvt_pk_bf16_f32 v133, v138, v156
	v_lshl_add_u64 v[138:139], v[134:135], 0, s[58:59]
	global_store_dwordx4 v[138:139], v[130:133], off offset:1024 sc1
	s_nop 1
	v_add_f32_e32 v132, 0, v96
	v_add_f32_e32 v130, 0, v101
	v_add_f32_e32 v133, 0, v97
	v_add_f32_e32 v131, 0, v102
	v_add_f32_e32 v156, 0, v98
	v_add_f32_e32 v157, 0, v103
	s_mov_b64 s[0:1], 0x18000
	v_add_f32_e32 v129, 0, v100
	v_add_f32_e32 v158, 0, v99
	v_cvt_pk_bf16_f32 v130, v129, v130
	v_cvt_pk_bf16_f32 v131, v131, v157
	v_cvt_pk_bf16_f32 v132, v132, v133
	v_cvt_pk_bf16_f32 v133, v156, v158
	v_lshl_add_u64 v[156:157], v[134:135], 0, s[0:1]
	global_store_dwordx4 v[156:157], v[130:133], off offset:1024 sc1
	s_nop 1
	v_add_f32_e32 v132, 0, v88
	v_add_f32_e32 v130, 0, v93
	v_add_f32_e32 v133, 0, v89
	v_add_f32_e32 v131, 0, v94
	v_add_f32_e32 v158, 0, v90
	v_add_f32_e32 v159, 0, v95
	s_mov_b64 s[0:1], 0x40000
	v_add_f32_e32 v129, 0, v92
	v_add_f32_e32 v160, 0, v91
	v_cvt_pk_bf16_f32 v130, v129, v130
	v_cvt_pk_bf16_f32 v131, v131, v159
	v_cvt_pk_bf16_f32 v132, v132, v133
	v_cvt_pk_bf16_f32 v133, v158, v160
	v_lshl_add_u64 v[158:159], v[134:135], 0, s[0:1]
	global_store_dwordx4 v[158:159], v[130:133], off offset:1024 sc1
	s_nop 1
	v_add_f32_e32 v132, 0, v80
	v_add_f32_e32 v130, 0, v85
	v_add_f32_e32 v133, 0, v81
	v_add_f32_e32 v131, 0, v86
	v_add_f32_e32 v160, 0, v82
	v_add_f32_e32 v161, 0, v87
	s_mov_b64 s[0:1], 0x48000
	v_add_f32_e32 v129, 0, v84
	v_add_f32_e32 v162, 0, v83
	v_cvt_pk_bf16_f32 v130, v129, v130
	v_cvt_pk_bf16_f32 v131, v131, v161
	v_cvt_pk_bf16_f32 v132, v132, v133
	v_cvt_pk_bf16_f32 v133, v160, v162
	v_lshl_add_u64 v[160:161], v[134:135], 0, s[0:1]
	global_store_dwordx4 v[160:161], v[130:133], off offset:1024 sc1
	s_nop 1
	v_add_f32_e32 v132, 0, v72
	v_add_f32_e32 v130, 0, v77
	v_add_f32_e32 v133, 0, v73
	v_add_f32_e32 v131, 0, v78
	v_add_f32_e32 v162, 0, v74
	v_add_f32_e32 v163, 0, v79
	s_mov_b64 s[0:1], 0x50000
	v_add_f32_e32 v129, 0, v76
	v_add_f32_e32 v168, 0, v75
	v_cvt_pk_bf16_f32 v130, v129, v130
	v_cvt_pk_bf16_f32 v131, v131, v163
	v_cvt_pk_bf16_f32 v132, v132, v133
	v_cvt_pk_bf16_f32 v133, v162, v168
	v_lshl_add_u64 v[162:163], v[134:135], 0, s[0:1]
	global_store_dwordx4 v[162:163], v[130:133], off offset:1024 sc1
	s_nop 1
	v_add_f32_e32 v132, 0, v64
	v_add_f32_e32 v130, 0, v69
	v_add_f32_e32 v133, 0, v65
	v_add_f32_e32 v131, 0, v70
	v_add_f32_e32 v168, 0, v66
	v_add_f32_e32 v169, 0, v71
	s_mov_b64 s[0:1], 0x58000
	v_add_f32_e32 v129, 0, v68
	v_add_f32_e32 v170, 0, v67
	v_cvt_pk_bf16_f32 v130, v129, v130
	v_cvt_pk_bf16_f32 v131, v131, v169
	v_cvt_pk_bf16_f32 v132, v132, v133
	v_cvt_pk_bf16_f32 v133, v168, v170
	v_lshl_add_u64 v[168:169], v[134:135], 0, s[0:1]
	global_store_dwordx4 v[168:169], v[130:133], off offset:1024 sc1
	s_nop 1
	v_add_f32_e32 v132, 0, v56
	v_add_f32_e32 v130, 0, v61
	v_add_f32_e32 v133, 0, v57
	v_add_f32_e32 v131, 0, v62
	v_add_f32_e32 v129, 0, v60
	v_add_f32_e32 v170, 0, v58
	v_add_f32_e32 v171, 0, v63
	v_add_f32_e32 v172, 0, v59
	v_cvt_pk_bf16_f32 v130, v129, v130
	v_cvt_pk_bf16_f32 v131, v131, v171
	v_cvt_pk_bf16_f32 v132, v132, v133
	v_cvt_pk_bf16_f32 v133, v170, v172
	global_store_dwordx4 v[134:135], v[130:133], off offset:1280 sc1
	s_nop 1
	v_add_f32_e32 v132, 0, v48
	v_add_f32_e32 v130, 0, v53
	v_add_f32_e32 v133, 0, v49
	v_add_f32_e32 v131, 0, v54
	v_add_f32_e32 v129, 0, v52
	v_add_f32_e32 v134, 0, v50
	v_add_f32_e32 v135, 0, v55
	v_add_f32_e32 v170, 0, v51
	v_cvt_pk_bf16_f32 v130, v129, v130
	v_cvt_pk_bf16_f32 v131, v131, v135
	v_cvt_pk_bf16_f32 v132, v132, v133
	v_cvt_pk_bf16_f32 v133, v134, v170
	global_store_dwordx4 v[136:137], v[130:133], off offset:1280 sc1
	s_nop 1
	v_add_f32_e32 v132, 0, v40
	v_add_f32_e32 v130, 0, v45
; __device__ __forceinline__ unsigned pkbf(float lo, float hi) { return pg8::cvt_pk_bf16(lo, hi); }
;     template <int MODE> __device__ __forceinline__ void run(AccRef acc, const Unit& u, int wr, int wc, int fr, int fq) const {
;     ...
;             if (MODE < 2) { const float* bp = (MODE == 0 ? w0 + seg * 512 : a0 + (seg - 2) * 512) + cc; const f32x4 b0 = *(const f32x4*)bp, b1 = *(const f32x4*)(bp + 4);
;                 bias[0] = b0[0]; bias[1] = b0[1]; bias[2] = b0[2]; bias[3] = b0[3]; bias[4] = b1[0]; bias[5] = b1[1]; bias[6] = b1[2]; bias[7] = b1[3]; }
;     ...
;                         w.x = pkbf(x[0], x[1]); w.y = pkbf(x[2], x[3]); w.z = pkbf(x[4], x[5]); w.w = pkbf(x[6], x[7]);
;                         *(u32x4*)(MIX + (size_t)row * 1024 + 512 + cc) = w;
	v_add_f32_e32 v133, 0, v41
	v_add_f32_e32 v131, 0, v46
	v_add_f32_e32 v129, 0, v44
	v_add_f32_e32 v134, 0, v42
	v_add_f32_e32 v135, 0, v47
	v_add_f32_e32 v136, 0, v43
	v_cvt_pk_bf16_f32 v130, v129, v130
	v_cvt_pk_bf16_f32 v131, v131, v135
	v_cvt_pk_bf16_f32 v132, v132, v133
	v_cvt_pk_bf16_f32 v133, v134, v136
	global_store_dwordx4 v[138:139], v[130:133], off offset:1280 sc1
	s_nop 1
	v_add_f32_e32 v132, 0, v32
	v_add_f32_e32 v130, 0, v37
	v_add_f32_e32 v133, 0, v33
	v_add_f32_e32 v131, 0, v38
	v_add_f32_e32 v129, 0, v36
	v_add_f32_e32 v134, 0, v34
	v_add_f32_e32 v135, 0, v39
	v_add_f32_e32 v136, 0, v35
	v_cvt_pk_bf16_f32 v130, v129, v130
	v_cvt_pk_bf16_f32 v131, v131, v135
	v_cvt_pk_bf16_f32 v132, v132, v133
	v_cvt_pk_bf16_f32 v133, v134, v136
	global_store_dwordx4 v[156:157], v[130:133], off offset:1280 sc1
	s_nop 1
	v_add_f32_e32 v132, 0, v24
	v_add_f32_e32 v130, 0, v29
	v_add_f32_e32 v133, 0, v25
	v_add_f32_e32 v131, 0, v30
	v_add_f32_e32 v129, 0, v28
	v_add_f32_e32 v134, 0, v26
	v_add_f32_e32 v135, 0, v31
	v_add_f32_e32 v136, 0, v27
	v_cvt_pk_bf16_f32 v130, v129, v130
	v_cvt_pk_bf16_f32 v131, v131, v135
	v_cvt_pk_bf16_f32 v132, v132, v133
	v_cvt_pk_bf16_f32 v133, v134, v136
	global_store_dwordx4 v[158:159], v[130:133], off offset:1280 sc1
	s_nop 1
	v_add_f32_e32 v132, 0, v16
	v_add_f32_e32 v130, 0, v21
	v_add_f32_e32 v133, 0, v17
	v_add_f32_e32 v131, 0, v22
	v_add_f32_e32 v129, 0, v20
	v_add_f32_e32 v134, 0, v18
	v_add_f32_e32 v135, 0, v23
	v_add_f32_e32 v136, 0, v19
	v_cvt_pk_bf16_f32 v130, v129, v130
	v_cvt_pk_bf16_f32 v131, v131, v135
	v_cvt_pk_bf16_f32 v132, v132, v133
	v_cvt_pk_bf16_f32 v133, v134, v136
	global_store_dwordx4 v[160:161], v[130:133], off offset:1280 sc1
	s_nop 1
	v_add_f32_e32 v132, 0, v8
	v_add_f32_e32 v130, 0, v13
	v_add_f32_e32 v133, 0, v9
	v_add_f32_e32 v131, 0, v14
	v_add_f32_e32 v129, 0, v12
	v_add_f32_e32 v134, 0, v10
	v_add_f32_e32 v135, 0, v15
	v_add_f32_e32 v136, 0, v11
	v_cvt_pk_bf16_f32 v130, v129, v130
	v_cvt_pk_bf16_f32 v131, v131, v135
	v_cvt_pk_bf16_f32 v132, v132, v133
	v_cvt_pk_bf16_f32 v133, v134, v136
	global_store_dwordx4 v[162:163], v[130:133], off offset:1280 sc1
	s_nop 1
	v_add_f32_e32 v132, 0, v0
	v_add_f32_e32 v130, 0, v5
	v_add_f32_e32 v133, 0, v1
	v_add_f32_e32 v131, 0, v6
	v_add_f32_e32 v129, 0, v4
	v_add_f32_e32 v134, 0, v2
	v_add_f32_e32 v135, 0, v7
	v_add_f32_e32 v136, 0, v3
	v_cvt_pk_bf16_f32 v130, v129, v130
	v_cvt_pk_bf16_f32 v131, v131, v135
	v_cvt_pk_bf16_f32 v132, v132, v133
	v_cvt_pk_bf16_f32 v133, v134, v136
	global_store_dwordx4 v[168:169], v[130:133], off offset:1280 sc1
	s_mov_b64 s[0:1], 0
.LBB0_877:
	s_andn2_b64 vcc, exec, s[0:1]
	s_cbranch_vccnz .LBB0_879
	s_lshl_b32 s24, s69, 8
	s_and_b32 s1, s24, 0xfffffe00
	s_add_i32 s14, s1, 0x400
	s_add_i32 s5, s5, s3
	s_add_i32 s0, s1, 0x800
	s_ashr_i32 s15, s14, 31
	v_add_u32_e32 v160, s5, v181
	s_and_b32 s5, s24, 0x100
	s_ashr_i32 s1, s0, 31
	s_or_b32 s5, s5, s35
	s_lshl_b64 s[14:15], s[14:15], 2
	v_readlane_b32 s36, v237, 37
	v_add_u32_e32 v158, s5, v128
	v_readlane_b32 s37, v237, 38
	s_add_u32 s14, s36, s14
	s_addc_u32 s15, s37, s15
	v_ashrrev_i32_e32 v159, 31, v158
	v_lshl_add_u64 v[156:157], v[158:159], 2, s[14:15]
	global_load_dwordx4 v[128:131], v[156:157], off offset:16
	global_load_dwordx4 v[132:135], v[156:157], off
	v_readlane_b32 s38, v237, 39
	v_readlane_b32 s39, v237, 40
	v_readlane_b32 s40, v237, 41
	v_readlane_b32 s41, v237, 42
	v_readlane_b32 s42, v237, 43
	v_readlane_b32 s43, v237, 44
	v_readlane_b32 s44, v237, 45
	v_readlane_b32 s45, v237, 46
	v_readlane_b32 s46, v237, 47
	v_readlane_b32 s47, v237, 48
	v_readlane_b32 s48, v237, 49
	v_readlane_b32 s49, v237, 50
	v_readlane_b32 s50, v237, 51
	v_readlane_b32 s51, v237, 52
	v_readlane_b32 s36, v236, 5
	v_readlane_b32 s48, v236, 17
	v_readlane_b32 s49, v236, 18
	v_readlane_b32 s38, v236, 7
	v_readlane_b32 s39, v236, 8
	v_readlane_b32 s46, v236, 15
	v_readlane_b32 s47, v236, 16
	v_readlane_b32 s37, v236, 6
	v_readlane_b32 s40, v236, 9
	v_readlane_b32 s41, v236, 10
	v_readlane_b32 s42, v236, 11
	v_readlane_b32 s43, v236, 12
	v_readlane_b32 s44, v236, 13
	v_readlane_b32 s45, v236, 14
	v_readlane_b32 s50, v236, 19
	v_readlane_b32 s51, v236, 20
	s_mov_b64 s[46:47], 0x20000
	s_mov_b32 s39, 0x10000
	s_mov_b32 s38, 0x30000
	s_waitcnt vmcnt(0)
; __device__ __forceinline__ float fsigmoid(float x) { return __builtin_amdgcn_rcpf(1.f + __builtin_amdgcn_exp2f(-1.4426950408889634f * x)); }
;     template <int MODE> __device__ __forceinline__ void run(AccRef acc, const Unit& u, int wr, int wc, int fr, int fq) const {
;     ...
;                     for (int e = 0; e < 4; ++e) { x[e] = acc[ai][bj][m][0][e] + bias[e]; x[4 + e] = acc[ai][bj][m][1][e] + bias[4 + e]; }
;                     u32x4 w;
;                     if (MODE == 0) {
; #pragma unroll
;                         for (int e = 0; e < 8; ++e) { const float sp = __logf(1.f + __expf(-x[e])); x[e] = __expf(-__expf(-sp - 0.5f)); }
;                         w.x = pkh(x[0], x[1]); w.y = pkh(x[2], x[3]); w.z = pkh(x[4], x[5]); w.w = pkh(x[6], x[7]);
;                         *(u32x4*)(WA + (size_t)row * 2048 + seg * 512 + cc) = w;
;                     } else if (MODE == 1) {
; #pragma unroll
;                         for (int e = 0; e < 8; ++e) x[e] = fsigmoid(x[e]);
;                         w.x = pkh(x[0], x[1]); w.y = pkh(x[2], x[3]); w.z = pkh(x[4], x[5]); w.w = pkh(x[6], x[7]);
;                         *(u32x4*)(WA + (size_t)row * 2048 + seg * 512 + cc) = w;
	v_add_f32_e32 v137, v124, v128
	v_mul_f32_e32 v137, 0xbfb8aa3b, v137
	v_exp_f32_e32 v137, v137
	v_add_f32_e32 v139, v125, v129
	v_add_f32_e32 v162, v126, v130
	v_add_f32_e32 v161, v122, v134
	v_add_f32_e32 v137, 1.0, v137
	v_rcp_f32_e32 v169, v137
	v_mul_f32_e32 v137, 0xbfb8aa3b, v139
	v_exp_f32_e32 v137, v137
	v_add_f32_e32 v163, v123, v135
	v_mul_f32_e32 v161, 0xbfb8aa3b, v161
	v_mul_f32_e32 v163, 0xbfb8aa3b, v163
	v_add_f32_e32 v137, 1.0, v137
	v_rcp_f32_e32 v139, v137
	v_mul_f32_e32 v137, 0xbfb8aa3b, v162
	v_exp_f32_e32 v137, v137
	v_exp_f32_e32 v161, v161
	v_exp_f32_e32 v163, v163
	v_add_f32_e32 v136, v120, v132
	v_add_f32_e32 v138, v121, v133
	v_add_f32_e32 v168, v127, v131
	v_add_f32_e32 v137, 1.0, v137
	v_mul_f32_e32 v136, 0xbfb8aa3b, v136
	v_mul_f32_e32 v138, 0xbfb8aa3b, v138
	v_rcp_f32_e32 v162, v137
	v_mul_f32_e32 v137, 0xbfb8aa3b, v168
	v_exp_f32_e32 v136, v136
	v_exp_f32_e32 v138, v138
	v_add_f32_e32 v161, 1.0, v161
	v_add_f32_e32 v163, 1.0, v163
	v_exp_f32_e32 v137, v137
	v_rcp_f32_e32 v161, v161
	v_rcp_f32_e32 v163, v163
	v_add_f32_e32 v136, 1.0, v136
	v_add_f32_e32 v138, 1.0, v138
	v_add_f32_e32 v137, 1.0, v137
	v_rcp_f32_e32 v136, v136
	v_rcp_f32_e32 v138, v138
	v_rcp_f32_e32 v168, v137
	v_cvt_pk_f16_f32 v137, v161, v163
	v_ashrrev_i32_e32 v161, 31, v160
	v_lshlrev_b64 v[160:161], 12, v[160:161]
	v_lshl_add_u64 v[160:161], s[48:49], 0, v[160:161]
	v_lshl_add_u64 v[160:161], s[0:1], 1, v[160:161]
	v_cvt_pk_f16_f32 v136, v136, v138
	v_cvt_pk_f16_f32 v138, v169, v139
	v_cvt_pk_f16_f32 v139, v162, v168
	v_lshl_add_u64 v[158:159], v[158:159], 1, v[160:161]
	global_store_dwordx4 v[158:159], v[136:139], off sc1
	v_add_f32_e32 v160, v118, v134
	v_add_f32_e32 v162, v119, v135
	v_mul_f32_e32 v160, 0xbfb8aa3b, v160
	v_exp_f32_e32 v160, v160
	v_mul_f32_e32 v162, 0xbfb8aa3b, v162
	v_exp_f32_e32 v162, v162
	v_add_f32_e32 v136, v116, v132
	v_add_f32_e32 v160, 1.0, v160
	v_add_f32_e32 v138, v117, v133
	v_add_f32_e32 v161, v114, v130
	v_rcp_f32_e32 v168, v160
	v_add_f32_e32 v160, 1.0, v162
	v_add_f32_e32 v137, v112, v128
	v_add_f32_e32 v139, v113, v129
	v_mul_f32_e32 v136, 0xbfb8aa3b, v136
	v_mul_f32_e32 v138, 0xbfb8aa3b, v138
	v_add_f32_e32 v163, v115, v131
	v_rcp_f32_e32 v162, v160
	v_mul_f32_e32 v160, 0xbfb8aa3b, v161
	v_exp_f32_e32 v136, v136
	v_exp_f32_e32 v138, v138
	v_mul_f32_e32 v137, 0xbfb8aa3b, v137
	v_mul_f32_e32 v139, 0xbfb8aa3b, v139
	v_exp_f32_e32 v160, v160
	v_mul_f32_e32 v161, 0xbfb8aa3b, v163
	v_exp_f32_e32 v137, v137
	v_exp_f32_e32 v139, v139
	v_exp_f32_e32 v161, v161
	v_add_f32_e32 v136, 1.0, v136
	v_add_f32_e32 v138, 1.0, v138
	v_add_f32_e32 v160, 1.0, v160
	v_rcp_f32_e32 v136, v136
	v_rcp_f32_e32 v138, v138
	v_add_f32_e32 v137, 1.0, v137
	v_add_f32_e32 v139, 1.0, v139
	v_rcp_f32_e32 v163, v160
	v_add_f32_e32 v160, 1.0, v161
	v_rcp_f32_e32 v137, v137
	v_rcp_f32_e32 v139, v139
	v_rcp_f32_e32 v169, v160
	v_cvt_pk_f16_f32 v160, v136, v138
	v_add_co_u32_e32 v138, vcc, s39, v158
	v_cvt_pk_f16_f32 v161, v168, v162
	v_cvt_pk_f16_f32 v162, v137, v139
	v_cvt_pk_f16_f32 v163, v163, v169
	v_addc_co_u32_e32 v139, vcc, 0, v159, vcc
	v_lshl_add_u64 v[136:137], v[158:159], 0, s[58:59]
	global_store_dwordx4 v[138:139], v[160:163], off sc1
	s_nop 1
	v_add_f32_e32 v161, v105, v129
	v_add_f32_e32 v162, v110, v134
	v_add_f32_e32 v163, v106, v130
	v_add_f32_e32 v168, v111, v135
	v_mul_f32_e32 v161, 0xbfb8aa3b, v161
	v_add_f32_e32 v138, v108, v132
	v_add_f32_e32 v139, v104, v128
	v_add_f32_e32 v160, v109, v133
	v_add_f32_e32 v169, v107, v131
	v_mul_f32_e32 v162, 0xbfb8aa3b, v162
	v_mul_f32_e32 v168, 0xbfb8aa3b, v168
	v_exp_f32_e32 v161, v161
	v_mul_f32_e32 v163, 0xbfb8aa3b, v163
	v_mul_f32_e32 v138, 0xbfb8aa3b, v138
	v_mul_f32_e32 v160, 0xbfb8aa3b, v160
	v_exp_f32_e32 v162, v162
	v_exp_f32_e32 v168, v168
	v_mul_f32_e32 v139, 0xbfb8aa3b, v139
	v_exp_f32_e32 v163, v163
	v_mul_f32_e32 v169, 0xbfb8aa3b, v169
	v_exp_f32_e32 v138, v138
	v_exp_f32_e32 v160, v160
	v_exp_f32_e32 v139, v139
	v_exp_f32_e32 v169, v169
	v_add_f32_e32 v161, 1.0, v161
	v_add_f32_e32 v162, 1.0, v162
	v_add_f32_e32 v168, 1.0, v168
	v_rcp_f32_e32 v170, v161
	v_add_f32_e32 v161, 1.0, v163
	v_add_f32_e32 v138, 1.0, v138
	v_add_f32_e32 v160, 1.0, v160
	v_rcp_f32_e32 v162, v162
	v_rcp_f32_e32 v168, v168
	v_add_f32_e32 v139, 1.0, v139
	v_rcp_f32_e32 v163, v161
	v_add_f32_e32 v161, 1.0, v169
	v_rcp_f32_e32 v138, v138
	v_rcp_f32_e32 v160, v160
	v_rcp_f32_e32 v139, v139
	v_rcp_f32_e32 v169, v161
	s_mov_b32 s0, 0x20000
	v_cvt_pk_f16_f32 v161, v162, v168
	v_add_co_u32_e32 v168, vcc, s0, v158
	v_cvt_pk_f16_f32 v160, v138, v160
	v_cvt_pk_f16_f32 v162, v139, v170
	v_cvt_pk_f16_f32 v163, v163, v169
	v_addc_co_u32_e32 v169, vcc, 0, v159, vcc
	v_lshl_add_u64 v[138:139], v[158:159], 0, s[46:47]
	global_store_dwordx4 v[168:169], v[160:163], off sc1
	v_add_f32_e32 v168, v102, v134
	v_add_f32_e32 v170, v103, v135
	v_mul_f32_e32 v168, 0xbfb8aa3b, v168
	v_exp_f32_e32 v168, v168
	v_mul_f32_e32 v170, 0xbfb8aa3b, v170
	v_exp_f32_e32 v170, v170
	v_add_f32_e32 v160, v100, v132
	v_add_f32_e32 v168, 1.0, v168
	v_add_f32_e32 v162, v101, v133
	v_add_f32_e32 v169, v98, v130
	v_rcp_f32_e32 v172, v168
	v_add_f32_e32 v168, 1.0, v170
	v_add_f32_e32 v161, v96, v128
	v_add_f32_e32 v163, v97, v129
	v_mul_f32_e32 v160, 0xbfb8aa3b, v160
	v_mul_f32_e32 v162, 0xbfb8aa3b, v162
	v_add_f32_e32 v171, v99, v131
	v_rcp_f32_e32 v170, v168
	v_mul_f32_e32 v168, 0xbfb8aa3b, v169
	v_exp_f32_e32 v160, v160
	v_exp_f32_e32 v162, v162
	v_mul_f32_e32 v161, 0xbfb8aa3b, v161
	v_mul_f32_e32 v163, 0xbfb8aa3b, v163
	v_exp_f32_e32 v168, v168
	v_mul_f32_e32 v169, 0xbfb8aa3b, v171
	v_exp_f32_e32 v161, v161
	v_exp_f32_e32 v163, v163
; __device__ __forceinline__ float fsigmoid(float x) { return __builtin_amdgcn_rcpf(1.f + __builtin_amdgcn_exp2f(-1.4426950408889634f * x)); }
;     template <int MODE> __device__ __forceinline__ void run(AccRef acc, const Unit& u, int wr, int wc, int fr, int fq) const {
;     ...
; #pragma unroll
;                         for (int e = 0; e < 8; ++e) x[e] = fsigmoid(x[e]);
;                         w.x = pkh(x[0], x[1]); w.y = pkh(x[2], x[3]); w.z = pkh(x[4], x[5]); w.w = pkh(x[6], x[7]);
;                         *(u32x4*)(WA + (size_t)row * 2048 + seg * 512 + cc) = w;
	v_exp_f32_e32 v169, v169
	v_add_f32_e32 v160, 1.0, v160
	v_add_f32_e32 v162, 1.0, v162
	v_add_f32_e32 v168, 1.0, v168
	v_rcp_f32_e32 v160, v160
	v_rcp_f32_e32 v162, v162
	v_add_f32_e32 v161, 1.0, v161
	v_add_f32_e32 v163, 1.0, v163
	v_rcp_f32_e32 v171, v168
	v_add_f32_e32 v168, 1.0, v169
	v_rcp_f32_e32 v161, v161
	v_rcp_f32_e32 v163, v163
	v_rcp_f32_e32 v173, v168
	v_cvt_pk_f16_f32 v168, v160, v162
	v_add_co_u32_e32 v162, vcc, s38, v158
	v_cvt_pk_f16_f32 v169, v172, v170
	v_cvt_pk_f16_f32 v170, v161, v163
	v_cvt_pk_f16_f32 v171, v171, v173
	s_mov_b64 s[0:1], 0x30000
	v_addc_co_u32_e32 v163, vcc, 0, v159, vcc
	v_lshl_add_u64 v[160:161], v[158:159], 0, s[0:1]
	global_store_dwordx4 v[162:163], v[168:171], off sc1
	v_add_f32_e32 v162, v92, v132
	v_add_f32_e32 v163, v88, v128
	v_add_f32_e32 v168, v93, v133
	v_add_f32_e32 v169, v89, v129
	v_add_f32_e32 v170, v94, v134
	v_add_f32_e32 v172, v95, v135
	v_add_f32_e32 v171, v90, v130
	v_mul_f32_e32 v162, 0xbfb8aa3b, v162
	v_mul_f32_e32 v168, 0xbfb8aa3b, v168
	v_mul_f32_e32 v170, 0xbfb8aa3b, v170
	v_mul_f32_e32 v172, 0xbfb8aa3b, v172
	v_mul_f32_e32 v163, 0xbfb8aa3b, v163
	v_mul_f32_e32 v169, 0xbfb8aa3b, v169
	v_exp_f32_e32 v162, v162
	v_exp_f32_e32 v168, v168
	v_add_f32_e32 v173, v91, v131
	v_exp_f32_e32 v170, v170
	v_exp_f32_e32 v172, v172
	v_exp_f32_e32 v163, v163
	v_exp_f32_e32 v169, v169
	v_mul_f32_e32 v171, 0xbfb8aa3b, v171
	v_exp_f32_e32 v171, v171
	v_mul_f32_e32 v173, 0xbfb8aa3b, v173
	v_exp_f32_e32 v173, v173
	v_add_f32_e32 v162, 1.0, v162
	v_add_f32_e32 v168, 1.0, v168
	v_add_f32_e32 v170, 1.0, v170
	v_add_f32_e32 v172, 1.0, v172
	v_add_f32_e32 v163, 1.0, v163
	v_add_f32_e32 v169, 1.0, v169
	v_rcp_f32_e32 v162, v162
	v_rcp_f32_e32 v168, v168
	v_rcp_f32_e32 v170, v170
	v_rcp_f32_e32 v172, v172
	v_rcp_f32_e32 v163, v163
	v_rcp_f32_e32 v182, v169
	v_add_f32_e32 v169, 1.0, v171
	v_rcp_f32_e32 v171, v169
	v_add_f32_e32 v169, 1.0, v173
	v_rcp_f32_e32 v173, v169
	s_mov_b64 s[0:1], 0x80000
	v_cvt_pk_f16_f32 v168, v162, v168
	v_cvt_pk_f16_f32 v169, v170, v172
	v_cvt_pk_f16_f32 v170, v163, v182
	v_lshl_add_u64 v[162:163], v[158:159], 0, s[0:1]
	s_mov_b32 s0, 0x80000
	v_add_co_u32_e32 v172, vcc, s0, v158
	v_cvt_pk_f16_f32 v171, v171, v173
	s_nop 0
	v_addc_co_u32_e32 v173, vcc, 0, v159, vcc
	global_store_dwordx4 v[172:173], v[168:171], off sc1
	s_nop 1
	v_add_f32_e32 v168, v84, v132
	v_add_f32_e32 v169, v80, v128
	v_add_f32_e32 v170, v85, v133
	v_add_f32_e32 v171, v81, v129
	v_add_f32_e32 v172, v86, v134
	v_add_f32_e32 v182, v87, v135
	v_add_f32_e32 v173, v82, v130
	v_mul_f32_e32 v168, 0xbfb8aa3b, v168
	v_mul_f32_e32 v170, 0xbfb8aa3b, v170
	v_mul_f32_e32 v172, 0xbfb8aa3b, v172
	v_mul_f32_e32 v182, 0xbfb8aa3b, v182
	v_mul_f32_e32 v169, 0xbfb8aa3b, v169
	v_mul_f32_e32 v171, 0xbfb8aa3b, v171
	v_exp_f32_e32 v168, v168
	v_exp_f32_e32 v170, v170
	v_add_f32_e32 v183, v83, v131
	v_exp_f32_e32 v172, v172
	v_exp_f32_e32 v182, v182
	v_exp_f32_e32 v169, v169
	v_exp_f32_e32 v171, v171
	v_mul_f32_e32 v173, 0xbfb8aa3b, v173
	v_exp_f32_e32 v173, v173
	v_mul_f32_e32 v183, 0xbfb8aa3b, v183
	v_exp_f32_e32 v183, v183
	v_add_f32_e32 v168, 1.0, v168
	v_add_f32_e32 v170, 1.0, v170
	v_add_f32_e32 v172, 1.0, v172
	v_add_f32_e32 v182, 1.0, v182
	v_add_f32_e32 v169, 1.0, v169
	v_add_f32_e32 v171, 1.0, v171
	v_rcp_f32_e32 v168, v168
	v_rcp_f32_e32 v170, v170
	v_rcp_f32_e32 v172, v172
	v_rcp_f32_e32 v182, v182
	v_rcp_f32_e32 v169, v169
	v_rcp_f32_e32 v184, v171
	v_add_f32_e32 v171, 1.0, v173
	v_rcp_f32_e32 v173, v171
	v_add_f32_e32 v171, 1.0, v183
	v_rcp_f32_e32 v183, v171
	s_mov_b64 s[0:1], 0x90000
	v_cvt_pk_f16_f32 v170, v168, v170
	v_cvt_pk_f16_f32 v171, v172, v182
	v_cvt_pk_f16_f32 v172, v169, v184
	v_lshl_add_u64 v[168:169], v[158:159], 0, s[0:1]
	s_mov_b32 s0, 0x90000
	v_add_co_u32_e32 v182, vcc, s0, v158
	v_cvt_pk_f16_f32 v173, v173, v183
	s_nop 0
	v_addc_co_u32_e32 v183, vcc, 0, v159, vcc
	global_store_dwordx4 v[182:183], v[170:173], off sc1
	v_add_f32_e32 v182, v78, v134
	v_add_f32_e32 v184, v79, v135
	v_mul_f32_e32 v182, 0xbfb8aa3b, v182
	v_exp_f32_e32 v182, v182
	v_mul_f32_e32 v184, 0xbfb8aa3b, v184
	v_exp_f32_e32 v184, v184
	v_add_f32_e32 v170, v76, v132
	v_add_f32_e32 v182, 1.0, v182
	v_add_f32_e32 v172, v77, v133
	v_add_f32_e32 v183, v74, v130
	v_rcp_f32_e32 v186, v182
	v_add_f32_e32 v182, 1.0, v184
	v_add_f32_e32 v171, v72, v128
	v_add_f32_e32 v173, v73, v129
	v_mul_f32_e32 v170, 0xbfb8aa3b, v170
	v_mul_f32_e32 v172, 0xbfb8aa3b, v172
	v_add_f32_e32 v185, v75, v131
	v_rcp_f32_e32 v184, v182
	v_mul_f32_e32 v182, 0xbfb8aa3b, v183
	v_exp_f32_e32 v170, v170
	v_exp_f32_e32 v172, v172
	v_mul_f32_e32 v171, 0xbfb8aa3b, v171
	v_mul_f32_e32 v173, 0xbfb8aa3b, v173
	v_exp_f32_e32 v182, v182
	v_mul_f32_e32 v183, 0xbfb8aa3b, v185
	v_exp_f32_e32 v171, v171
	v_exp_f32_e32 v173, v173
	v_exp_f32_e32 v183, v183
	v_add_f32_e32 v170, 1.0, v170
	v_add_f32_e32 v172, 1.0, v172
	v_add_f32_e32 v182, 1.0, v182
	v_rcp_f32_e32 v170, v170
	v_rcp_f32_e32 v172, v172
	v_add_f32_e32 v171, 1.0, v171
	v_add_f32_e32 v173, 1.0, v173
	v_rcp_f32_e32 v185, v182
	v_add_f32_e32 v182, 1.0, v183
	v_rcp_f32_e32 v171, v171
	v_rcp_f32_e32 v173, v173
	v_rcp_f32_e32 v187, v182
	v_cvt_pk_f16_f32 v182, v170, v172
	v_add_co_u32_e32 v172, vcc, s71, v158
	v_cvt_pk_f16_f32 v183, v186, v184
	v_cvt_pk_f16_f32 v184, v171, v173
	v_cvt_pk_f16_f32 v185, v185, v187
	s_mov_b64 s[0:1], 0xa0000
	v_addc_co_u32_e32 v173, vcc, 0, v159, vcc
	v_lshl_add_u64 v[170:171], v[158:159], 0, s[0:1]
	global_store_dwordx4 v[172:173], v[182:185], off sc1
	v_add_f32_e32 v128, v64, v128
	v_add_f32_e32 v129, v65, v129
	v_mul_f32_e32 v128, 0xbfb8aa3b, v128
	v_exp_f32_e32 v128, v128
; __device__ __forceinline__ float fsigmoid(float x) { return __builtin_amdgcn_rcpf(1.f + __builtin_amdgcn_exp2f(-1.4426950408889634f * x)); }
;     template <int MODE> __device__ __forceinline__ void run(AccRef acc, const Unit& u, int wr, int wc, int fr, int fq) const {
;     ...
;             if (MODE < 2) { const float* bp = (MODE == 0 ? w0 + seg * 512 : a0 + (seg - 2) * 512) + cc; const f32x4 b0 = *(const f32x4*)bp, b1 = *(const f32x4*)(bp + 4);
;                 bias[0] = b0[0]; bias[1] = b0[1]; bias[2] = b0[2]; bias[3] = b0[3]; bias[4] = b1[0]; bias[5] = b1[1]; bias[6] = b1[2]; bias[7] = b1[3]; }
;     ...
; #pragma unroll
;                         for (int e = 0; e < 8; ++e) x[e] = fsigmoid(x[e]);
;                         w.x = pkh(x[0], x[1]); w.y = pkh(x[2], x[3]); w.z = pkh(x[4], x[5]); w.w = pkh(x[6], x[7]);
;                         *(u32x4*)(WA + (size_t)row * 2048 + seg * 512 + cc) = w;
	v_mul_f32_e32 v129, 0xbfb8aa3b, v129
	v_exp_f32_e32 v129, v129
	v_add_f32_e32 v132, v68, v132
	v_add_f32_e32 v133, v69, v133
	v_add_f32_e32 v130, v66, v130
	v_add_f32_e32 v128, 1.0, v128
	v_add_f32_e32 v134, v70, v134
	v_add_f32_e32 v135, v71, v135
	v_mul_f32_e32 v132, 0xbfb8aa3b, v132
	v_mul_f32_e32 v133, 0xbfb8aa3b, v133
	v_add_f32_e32 v131, v67, v131
	v_rcp_f32_e32 v172, v128
	v_add_f32_e32 v128, 1.0, v129
	v_mul_f32_e32 v129, 0xbfb8aa3b, v130
	v_exp_f32_e32 v132, v132
	v_exp_f32_e32 v133, v133
	v_mul_f32_e32 v134, 0xbfb8aa3b, v134
	v_mul_f32_e32 v135, 0xbfb8aa3b, v135
	v_exp_f32_e32 v129, v129
	v_mul_f32_e32 v130, 0xbfb8aa3b, v131
	v_exp_f32_e32 v134, v134
	v_exp_f32_e32 v135, v135
	v_exp_f32_e32 v130, v130
	v_add_f32_e32 v132, 1.0, v132
	v_add_f32_e32 v133, 1.0, v133
	v_rcp_f32_e32 v131, v128
	v_add_f32_e32 v128, 1.0, v129
	v_rcp_f32_e32 v132, v132
	v_rcp_f32_e32 v133, v133
	v_add_f32_e32 v134, 1.0, v134
	v_add_f32_e32 v135, 1.0, v135
	v_rcp_f32_e32 v173, v128
	v_add_f32_e32 v128, 1.0, v130
	v_rcp_f32_e32 v134, v134
	v_rcp_f32_e32 v135, v135
	v_rcp_f32_e32 v182, v128
	v_cvt_pk_f16_f32 v128, v132, v133
	v_add_co_u32_e32 v132, vcc, s64, v158
	v_cvt_pk_f16_f32 v129, v134, v135
	v_cvt_pk_f16_f32 v130, v172, v131
	v_cvt_pk_f16_f32 v131, v173, v182
	s_mov_b64 s[0:1], 0xb0000
	v_addc_co_u32_e32 v133, vcc, 0, v159, vcc
	v_lshl_add_u64 v[172:173], v[158:159], 0, s[0:1]
	global_store_dwordx4 v[132:133], v[128:131], off sc1
	global_load_dwordx4 v[132:135], v[156:157], off offset:512
	global_load_dwordx4 v[128:131], v[156:157], off offset:528
	s_waitcnt vmcnt(0)
	v_add_f32_e32 v156, v60, v132
	v_add_f32_e32 v157, v56, v128
	v_add_f32_e32 v182, v61, v133
	v_add_f32_e32 v183, v57, v129
	v_add_f32_e32 v184, v62, v134
	v_add_f32_e32 v185, v58, v130
	v_add_f32_e32 v186, v63, v135
	v_add_f32_e32 v187, v59, v131
	v_mul_f32_e32 v156, 0xbfb8aa3b, v156
	v_mul_f32_e32 v182, 0xbfb8aa3b, v182
	v_mul_f32_e32 v184, 0xbfb8aa3b, v184
	v_mul_f32_e32 v186, 0xbfb8aa3b, v186
	v_mul_f32_e32 v157, 0xbfb8aa3b, v157
	v_mul_f32_e32 v183, 0xbfb8aa3b, v183
	v_mul_f32_e32 v185, 0xbfb8aa3b, v185
	v_mul_f32_e32 v187, 0xbfb8aa3b, v187
	v_exp_f32_e32 v156, v156
	v_exp_f32_e32 v182, v182
	v_exp_f32_e32 v184, v184
	v_exp_f32_e32 v186, v186
	v_exp_f32_e32 v157, v157
	v_exp_f32_e32 v183, v183
	v_exp_f32_e32 v185, v185
	v_exp_f32_e32 v187, v187
	v_add_f32_e32 v156, 1.0, v156
	v_add_f32_e32 v182, 1.0, v182
	v_add_f32_e32 v184, 1.0, v184
	v_add_f32_e32 v186, 1.0, v186
	v_add_f32_e32 v157, 1.0, v157
	v_add_f32_e32 v183, 1.0, v183
	v_add_f32_e32 v185, 1.0, v185
	v_add_f32_e32 v187, 1.0, v187
	v_rcp_f32_e32 v156, v156
	v_rcp_f32_e32 v182, v182
	v_rcp_f32_e32 v184, v184
	v_rcp_f32_e32 v186, v186
	v_rcp_f32_e32 v157, v157
	v_rcp_f32_e32 v188, v183
	v_rcp_f32_e32 v185, v185
	v_rcp_f32_e32 v187, v187
	v_cvt_pk_f16_f32 v182, v156, v182
	v_cvt_pk_f16_f32 v183, v184, v186
	v_cvt_pk_f16_f32 v184, v157, v188
	v_cvt_pk_f16_f32 v185, v185, v187
	global_store_dwordx4 v[158:159], v[182:185], off offset:256 sc1
	v_add_f32_e32 v157, v48, v128
	v_add_f32_e32 v159, v49, v129
	v_mul_f32_e32 v157, 0xbfb8aa3b, v157
	v_exp_f32_e32 v157, v157
	v_mul_f32_e32 v159, 0xbfb8aa3b, v159
	v_exp_f32_e32 v159, v159
	v_add_f32_e32 v183, v50, v130
	v_add_f32_e32 v157, 1.0, v157
	v_add_f32_e32 v156, v52, v132
	v_add_f32_e32 v158, v53, v133
	v_add_f32_e32 v182, v54, v134
	v_add_f32_e32 v184, v55, v135
	v_add_f32_e32 v185, v51, v131
	v_rcp_f32_e32 v186, v157
	v_add_f32_e32 v157, 1.0, v159
	v_mul_f32_e32 v159, 0xbfb8aa3b, v183
	v_mul_f32_e32 v156, 0xbfb8aa3b, v156
	v_mul_f32_e32 v158, 0xbfb8aa3b, v158
	v_mul_f32_e32 v182, 0xbfb8aa3b, v182
	v_mul_f32_e32 v184, 0xbfb8aa3b, v184
	v_exp_f32_e32 v159, v159
	v_mul_f32_e32 v183, 0xbfb8aa3b, v185
	v_exp_f32_e32 v156, v156
	v_exp_f32_e32 v158, v158
	v_exp_f32_e32 v182, v182
	v_exp_f32_e32 v184, v184
	v_exp_f32_e32 v183, v183
	v_rcp_f32_e32 v185, v157
	v_add_f32_e32 v157, 1.0, v159
	v_add_f32_e32 v156, 1.0, v156
	v_add_f32_e32 v158, 1.0, v158
	v_add_f32_e32 v182, 1.0, v182
	v_add_f32_e32 v184, 1.0, v184
	v_rcp_f32_e32 v159, v157
	v_add_f32_e32 v157, 1.0, v183
	v_rcp_f32_e32 v156, v156
	v_rcp_f32_e32 v158, v158
	v_rcp_f32_e32 v182, v182
	v_rcp_f32_e32 v184, v184
	v_rcp_f32_e32 v183, v157
	v_cvt_pk_f16_f32 v156, v156, v158
	v_cvt_pk_f16_f32 v157, v182, v184
	v_cvt_pk_f16_f32 v158, v186, v185
	v_cvt_pk_f16_f32 v159, v159, v183
	global_store_dwordx4 v[136:137], v[156:159], off offset:256 sc1
	s_nop 1
	v_add_f32_e32 v157, v41, v129
	v_add_f32_e32 v159, v42, v130
	v_mul_f32_e32 v157, 0xbfb8aa3b, v157
	v_add_f32_e32 v136, v44, v132
	v_add_f32_e32 v137, v40, v128
	v_add_f32_e32 v156, v45, v133
	v_add_f32_e32 v158, v46, v134
	v_add_f32_e32 v182, v47, v135
	v_add_f32_e32 v183, v43, v131
	v_exp_f32_e32 v157, v157
	v_mul_f32_e32 v159, 0xbfb8aa3b, v159
	v_mul_f32_e32 v136, 0xbfb8aa3b, v136
	v_mul_f32_e32 v156, 0xbfb8aa3b, v156
	v_mul_f32_e32 v158, 0xbfb8aa3b, v158
	v_mul_f32_e32 v182, 0xbfb8aa3b, v182
	v_mul_f32_e32 v137, 0xbfb8aa3b, v137
	v_exp_f32_e32 v159, v159
	v_mul_f32_e32 v183, 0xbfb8aa3b, v183
	v_exp_f32_e32 v136, v136
	v_exp_f32_e32 v156, v156
	v_exp_f32_e32 v158, v158
	v_exp_f32_e32 v182, v182
	v_exp_f32_e32 v137, v137
	v_exp_f32_e32 v183, v183
	v_add_f32_e32 v157, 1.0, v157
	v_rcp_f32_e32 v184, v157
	v_add_f32_e32 v157, 1.0, v159
	v_add_f32_e32 v136, 1.0, v136
	v_add_f32_e32 v156, 1.0, v156
	v_add_f32_e32 v158, 1.0, v158
	v_add_f32_e32 v182, 1.0, v182
	v_add_f32_e32 v137, 1.0, v137
	v_rcp_f32_e32 v159, v157
	v_add_f32_e32 v157, 1.0, v183
	v_rcp_f32_e32 v136, v136
	v_rcp_f32_e32 v156, v156
	v_rcp_f32_e32 v158, v158
	v_rcp_f32_e32 v182, v182
	v_rcp_f32_e32 v137, v137
	v_rcp_f32_e32 v183, v157
; __device__ __forceinline__ float fsigmoid(float x) { return __builtin_amdgcn_rcpf(1.f + __builtin_amdgcn_exp2f(-1.4426950408889634f * x)); }
;     template <int MODE> __device__ __forceinline__ void run(AccRef acc, const Unit& u, int wr, int wc, int fr, int fq) const {
;     ...
; #pragma unroll
;                         for (int e = 0; e < 8; ++e) x[e] = fsigmoid(x[e]);
;                         w.x = pkh(x[0], x[1]); w.y = pkh(x[2], x[3]); w.z = pkh(x[4], x[5]); w.w = pkh(x[6], x[7]);
;                         *(u32x4*)(WA + (size_t)row * 2048 + seg * 512 + cc) = w;
	v_cvt_pk_f16_f32 v156, v136, v156
	v_cvt_pk_f16_f32 v157, v158, v182
	v_cvt_pk_f16_f32 v158, v137, v184
	v_cvt_pk_f16_f32 v159, v159, v183
	global_store_dwordx4 v[138:139], v[156:159], off offset:256 sc1
	v_add_f32_e32 v137, v32, v128
	v_add_f32_e32 v139, v33, v129
	v_mul_f32_e32 v137, 0xbfb8aa3b, v137
	v_exp_f32_e32 v137, v137
	v_mul_f32_e32 v139, 0xbfb8aa3b, v139
	v_exp_f32_e32 v139, v139
	v_add_f32_e32 v157, v34, v130
	v_add_f32_e32 v137, 1.0, v137
	v_add_f32_e32 v136, v36, v132
	v_add_f32_e32 v138, v37, v133
	v_add_f32_e32 v156, v38, v134
	v_add_f32_e32 v158, v39, v135
	v_add_f32_e32 v159, v35, v131
	v_rcp_f32_e32 v182, v137
	v_add_f32_e32 v137, 1.0, v139
	v_mul_f32_e32 v139, 0xbfb8aa3b, v157
	v_mul_f32_e32 v136, 0xbfb8aa3b, v136
	v_mul_f32_e32 v138, 0xbfb8aa3b, v138
	v_mul_f32_e32 v156, 0xbfb8aa3b, v156
	v_mul_f32_e32 v158, 0xbfb8aa3b, v158
	v_exp_f32_e32 v139, v139
	v_mul_f32_e32 v157, 0xbfb8aa3b, v159
	v_exp_f32_e32 v136, v136
	v_exp_f32_e32 v138, v138
	v_exp_f32_e32 v156, v156
	v_exp_f32_e32 v158, v158
	v_exp_f32_e32 v157, v157
	v_rcp_f32_e32 v159, v137
	v_add_f32_e32 v137, 1.0, v139
	v_add_f32_e32 v136, 1.0, v136
	v_add_f32_e32 v138, 1.0, v138
	v_add_f32_e32 v156, 1.0, v156
	v_add_f32_e32 v158, 1.0, v158
	v_rcp_f32_e32 v139, v137
	v_add_f32_e32 v137, 1.0, v157
	v_rcp_f32_e32 v136, v136
	v_rcp_f32_e32 v138, v138
	v_rcp_f32_e32 v156, v156
	v_rcp_f32_e32 v158, v158
	v_rcp_f32_e32 v157, v137
	v_cvt_pk_f16_f32 v136, v136, v138
	v_cvt_pk_f16_f32 v137, v156, v158
	v_cvt_pk_f16_f32 v138, v182, v159
	v_cvt_pk_f16_f32 v139, v139, v157
	global_store_dwordx4 v[160:161], v[136:139], off offset:256 sc1
	s_nop 1
	v_add_f32_e32 v137, v24, v128
	v_add_f32_e32 v139, v25, v129
	v_mul_f32_e32 v137, 0xbfb8aa3b, v137
	v_exp_f32_e32 v137, v137
	v_mul_f32_e32 v139, 0xbfb8aa3b, v139
	v_exp_f32_e32 v139, v139
	v_add_f32_e32 v157, v26, v130
	v_add_f32_e32 v137, 1.0, v137
	v_add_f32_e32 v136, v28, v132
	v_add_f32_e32 v138, v29, v133
	v_add_f32_e32 v156, v30, v134
	v_add_f32_e32 v158, v31, v135
	v_add_f32_e32 v159, v27, v131
	v_rcp_f32_e32 v160, v137
	v_add_f32_e32 v137, 1.0, v139
	v_mul_f32_e32 v139, 0xbfb8aa3b, v157
	v_mul_f32_e32 v136, 0xbfb8aa3b, v136
	v_mul_f32_e32 v138, 0xbfb8aa3b, v138
	v_mul_f32_e32 v156, 0xbfb8aa3b, v156
	v_mul_f32_e32 v158, 0xbfb8aa3b, v158
	v_exp_f32_e32 v139, v139
	v_mul_f32_e32 v157, 0xbfb8aa3b, v159
	v_exp_f32_e32 v136, v136
	v_exp_f32_e32 v138, v138
	v_exp_f32_e32 v156, v156
	v_exp_f32_e32 v158, v158
	v_exp_f32_e32 v157, v157
	v_rcp_f32_e32 v159, v137
	v_add_f32_e32 v137, 1.0, v139
	v_add_f32_e32 v136, 1.0, v136
	v_add_f32_e32 v138, 1.0, v138
	v_add_f32_e32 v156, 1.0, v156
	v_add_f32_e32 v158, 1.0, v158
	v_rcp_f32_e32 v139, v137
	v_add_f32_e32 v137, 1.0, v157
	v_rcp_f32_e32 v136, v136
	v_rcp_f32_e32 v138, v138
	v_rcp_f32_e32 v156, v156
	v_rcp_f32_e32 v158, v158
	v_rcp_f32_e32 v157, v137
	v_cvt_pk_f16_f32 v136, v136, v138
	v_cvt_pk_f16_f32 v137, v156, v158
	v_cvt_pk_f16_f32 v138, v160, v159
	v_cvt_pk_f16_f32 v139, v139, v157
	global_store_dwordx4 v[162:163], v[136:139], off offset:256 sc1
	s_nop 1
	v_add_f32_e32 v137, v16, v128
	v_add_f32_e32 v139, v17, v129
	v_mul_f32_e32 v137, 0xbfb8aa3b, v137
	v_exp_f32_e32 v137, v137
	v_mul_f32_e32 v139, 0xbfb8aa3b, v139
	v_exp_f32_e32 v139, v139
	v_add_f32_e32 v157, v18, v130
	v_add_f32_e32 v137, 1.0, v137
	v_add_f32_e32 v136, v20, v132
	v_add_f32_e32 v138, v21, v133
	v_add_f32_e32 v156, v22, v134
	v_add_f32_e32 v158, v23, v135
	v_add_f32_e32 v159, v19, v131
	v_rcp_f32_e32 v160, v137
	v_add_f32_e32 v137, 1.0, v139
	v_mul_f32_e32 v139, 0xbfb8aa3b, v157
	v_mul_f32_e32 v136, 0xbfb8aa3b, v136
	v_mul_f32_e32 v138, 0xbfb8aa3b, v138
	v_mul_f32_e32 v156, 0xbfb8aa3b, v156
; __device__ __forceinline__ float fsigmoid(float x) { return __builtin_amdgcn_rcpf(1.f + __builtin_amdgcn_exp2f(-1.4426950408889634f * x)); }
;     template <int MODE> __device__ __forceinline__ void run(AccRef acc, const Unit& u, int wr, int wc, int fr, int fq) const {
;     ...
; #pragma unroll
;                         for (int e = 0; e < 8; ++e) x[e] = fsigmoid(x[e]);
;                         w.x = pkh(x[0], x[1]); w.y = pkh(x[2], x[3]); w.z = pkh(x[4], x[5]); w.w = pkh(x[6], x[7]);
;                         *(u32x4*)(WA + (size_t)row * 2048 + seg * 512 + cc) = w;
	v_mul_f32_e32 v158, 0xbfb8aa3b, v158
	v_exp_f32_e32 v139, v139
	v_mul_f32_e32 v157, 0xbfb8aa3b, v159
	v_exp_f32_e32 v136, v136
	v_exp_f32_e32 v138, v138
	v_exp_f32_e32 v156, v156
	v_exp_f32_e32 v158, v158
	v_exp_f32_e32 v157, v157
	v_rcp_f32_e32 v159, v137
	v_add_f32_e32 v137, 1.0, v139
	v_add_f32_e32 v136, 1.0, v136
	v_add_f32_e32 v138, 1.0, v138
	v_add_f32_e32 v156, 1.0, v156
	v_add_f32_e32 v158, 1.0, v158
	v_rcp_f32_e32 v139, v137
	v_add_f32_e32 v137, 1.0, v157
	v_rcp_f32_e32 v136, v136
	v_rcp_f32_e32 v138, v138
	v_rcp_f32_e32 v156, v156
	v_rcp_f32_e32 v158, v158
	v_rcp_f32_e32 v157, v137
	v_cvt_pk_f16_f32 v136, v136, v138
	v_cvt_pk_f16_f32 v137, v156, v158
	v_cvt_pk_f16_f32 v138, v160, v159
	v_cvt_pk_f16_f32 v139, v139, v157
	global_store_dwordx4 v[168:169], v[136:139], off offset:256 sc1
	s_nop 1
	v_add_f32_e32 v137, v8, v128
	v_add_f32_e32 v139, v9, v129
	v_mul_f32_e32 v137, 0xbfb8aa3b, v137
	v_exp_f32_e32 v137, v137
	v_mul_f32_e32 v139, 0xbfb8aa3b, v139
	v_exp_f32_e32 v139, v139
	v_add_f32_e32 v157, v10, v130
	v_add_f32_e32 v137, 1.0, v137
	v_add_f32_e32 v136, v12, v132
	v_add_f32_e32 v138, v13, v133
	v_add_f32_e32 v156, v14, v134
	v_add_f32_e32 v158, v15, v135
	v_add_f32_e32 v159, v11, v131
	v_rcp_f32_e32 v160, v137
	v_add_f32_e32 v137, 1.0, v139
	v_mul_f32_e32 v139, 0xbfb8aa3b, v157
	v_mul_f32_e32 v136, 0xbfb8aa3b, v136
	v_mul_f32_e32 v138, 0xbfb8aa3b, v138
	v_mul_f32_e32 v156, 0xbfb8aa3b, v156
	v_mul_f32_e32 v158, 0xbfb8aa3b, v158
	v_exp_f32_e32 v139, v139
	v_mul_f32_e32 v157, 0xbfb8aa3b, v159
	v_exp_f32_e32 v136, v136
	v_exp_f32_e32 v138, v138
	v_exp_f32_e32 v156, v156
	v_exp_f32_e32 v158, v158
	v_exp_f32_e32 v157, v157
	v_rcp_f32_e32 v159, v137
	v_add_f32_e32 v137, 1.0, v139
	v_add_f32_e32 v136, 1.0, v136
	v_add_f32_e32 v138, 1.0, v138
	v_add_f32_e32 v156, 1.0, v156
	v_add_f32_e32 v158, 1.0, v158
	v_rcp_f32_e32 v139, v137
	v_add_f32_e32 v137, 1.0, v157
	v_rcp_f32_e32 v136, v136
	v_rcp_f32_e32 v138, v138
	v_rcp_f32_e32 v156, v156
	v_rcp_f32_e32 v158, v158
	v_rcp_f32_e32 v157, v137
	v_cvt_pk_f16_f32 v136, v136, v138
	v_cvt_pk_f16_f32 v137, v156, v158
	v_cvt_pk_f16_f32 v138, v160, v159
	v_cvt_pk_f16_f32 v139, v139, v157
	global_store_dwordx4 v[170:171], v[136:139], off offset:256 sc1
	v_add_f32_e32 v128, v0, v128
	v_add_f32_e32 v129, v1, v129
	v_mul_f32_e32 v128, 0xbfb8aa3b, v128
	v_exp_f32_e32 v128, v128
	v_mul_f32_e32 v129, 0xbfb8aa3b, v129
	v_exp_f32_e32 v129, v129
	v_add_f32_e32 v130, v2, v130
	v_add_f32_e32 v128, 1.0, v128
	v_add_f32_e32 v132, v4, v132
	v_add_f32_e32 v133, v5, v133
	v_add_f32_e32 v134, v6, v134
	v_add_f32_e32 v135, v7, v135
	v_add_f32_e32 v131, v3, v131
	v_rcp_f32_e32 v136, v128
	v_add_f32_e32 v128, 1.0, v129
	v_mul_f32_e32 v129, 0xbfb8aa3b, v130
	v_mul_f32_e32 v132, 0xbfb8aa3b, v132
	v_mul_f32_e32 v133, 0xbfb8aa3b, v133
	v_mul_f32_e32 v134, 0xbfb8aa3b, v134
	v_mul_f32_e32 v135, 0xbfb8aa3b, v135
	v_exp_f32_e32 v129, v129
	v_mul_f32_e32 v130, 0xbfb8aa3b, v131
	v_exp_f32_e32 v132, v132
	v_exp_f32_e32 v133, v133
	v_exp_f32_e32 v134, v134
	v_exp_f32_e32 v135, v135
	v_exp_f32_e32 v130, v130
	v_rcp_f32_e32 v131, v128
	v_add_f32_e32 v128, 1.0, v129
	v_add_f32_e32 v132, 1.0, v132
	v_add_f32_e32 v133, 1.0, v133
	v_add_f32_e32 v134, 1.0, v134
	v_add_f32_e32 v135, 1.0, v135
	v_rcp_f32_e32 v137, v128
	v_add_f32_e32 v128, 1.0, v130
	v_rcp_f32_e32 v132, v132
	v_rcp_f32_e32 v133, v133
	v_rcp_f32_e32 v134, v134
	v_rcp_f32_e32 v135, v135
	v_rcp_f32_e32 v138, v128
	v_cvt_pk_f16_f32 v128, v132, v133
	v_cvt_pk_f16_f32 v129, v134, v135
	v_cvt_pk_f16_f32 v130, v136, v131
	v_cvt_pk_f16_f32 v131, v137, v138
	global_store_dwordx4 v[172:173], v[128:131], off offset:256 sc1

;     template <int MODE> __device__ __forceinline__ void run(AccRef acc, const Unit& u, int wr, int wc, int fr, int fq) const {
;     ...
;             if (MODE < 2) { const float* bp = (MODE == 0 ? w0 + seg * 512 : a0 + (seg - 2) * 512) + cc; const f32x4 b0 = *(const f32x4*)bp, b1 = *(const f32x4*)(bp + 4);
;                 bias[0] = b0[0]; bias[1] = b0[1]; bias[2] = b0[2]; bias[3] = b0[3]; bias[4] = b1[0]; bias[5] = b1[1]; bias[6] = b1[2]; bias[7] = b1[3]; }
;             else {
; #pragma unroll
;                 for (int e = 0; e < 8; ++e) bias[e] = 0.f; }
; #pragma unroll
;             for (int ai = 0; ai < 2; ++ai)
; #pragma unroll
;                 for (int m = 0; m < 4; ++m) {
;                     const int row = row0 + ai * 128 + m * 16;
;                     float x[8];
; #pragma unroll
;                     for (int e = 0; e < 4; ++e) { x[e] = acc[ai][bj][m][0][e] + bias[e]; x[4 + e] = acc[ai][bj][m][1][e] + bias[4 + e]; }
;                     u32x4 w;
;                     if (MODE == 0) {
; #pragma unroll
;                         for (int e = 0; e < 8; ++e) { const float sp = __logf(1.f + __expf(-x[e])); x[e] = __expf(-__expf(-sp - 0.5f)); }
.LBB0_882:
	s_lshl_b32 s0, s62, 8
	s_add_i32 s0, s0, s3
	s_lshl_b32 s1, s4, 9
	v_add_u32_e32 v138, s0, v181
	s_lshl_b32 s0, s69, 8
	s_add_i32 s4, s1, 0x800
	s_and_b32 s0, s0, 0x100
	s_ashr_i32 s5, s4, 31
	s_or_b32 s0, s0, s35
	v_readlane_b32 s16, v237, 21
	v_lshl_add_u32 v156, v180, 3, s0
	s_lshl_b64 s[0:1], s[4:5], 2
	v_readlane_b32 s28, v237, 33
	v_readlane_b32 s29, v237, 34
	s_add_u32 s0, s28, s0
	s_addc_u32 s1, s29, s1
	v_ashrrev_i32_e32 v157, 31, v156
	v_lshl_add_u64 v[136:137], v[156:157], 2, s[0:1]
	global_load_dwordx4 v[128:131], v[136:137], off offset:16
	global_load_dwordx4 v[132:135], v[136:137], off
	v_readlane_b32 s22, v237, 27
	v_readlane_b32 s23, v237, 28
	v_readlane_b32 s22, v236, 21
	v_readlane_b32 s23, v236, 22
	v_readlane_b32 s17, v237, 22
	v_readlane_b32 s18, v237, 23
	v_readlane_b32 s19, v237, 24
	v_readlane_b32 s20, v237, 25
	v_readlane_b32 s21, v237, 26
	v_readlane_b32 s24, v237, 29
	v_readlane_b32 s25, v237, 30
	v_readlane_b32 s26, v237, 31
	v_readlane_b32 s27, v237, 32
	v_readlane_b32 s30, v237, 35
	v_readlane_b32 s31, v237, 36
	s_waitcnt vmcnt(0)
	v_add_f32_e32 v139, v124, v128
	v_add_f32_e32 v120, v120, v132
	v_mul_f32_e32 v120, 0xbfb8aa3b, v120
	v_exp_f32_e32 v120, v120
	v_add_f32_e32 v159, v122, v134
	v_add_f32_e32 v158, v121, v133
	v_add_f32_e32 v124, v126, v130
	v_add_f32_e32 v120, 1.0, v120
	v_cmp_gt_f32_e32 vcc, s65, v120
	v_add_f32_e32 v126, v123, v135
	v_add_f32_e32 v121, v127, v131
	v_cndmask_b32_e64 v122, 0, 32, vcc
	v_ldexp_f32 v120, v120, v122
	v_log_f32_e32 v120, v120
	v_mul_f32_e32 v126, 0xbfb8aa3b, v126
	v_exp_f32_e32 v126, v126
	v_add_f32_e32 v125, v125, v129
	v_mul_f32_e32 v122, 0x3f317217, v120
	v_fma_f32 v122, v120, s61, -v122
	v_fmac_f32_e32 v122, 0x3377d1cf, v120
	v_fmac_f32_e32 v122, 0x3f317217, v120
	v_cmp_lt_f32_e64 s[0:1], |v120|, s66
	v_add_f32_e32 v126, 1.0, v126
	v_mul_f32_e32 v125, 0xbfb8aa3b, v125
	v_cndmask_b32_e64 v120, v120, v122, s[0:1]
	v_cndmask_b32_e32 v122, 0, v179, vcc
	v_sub_f32_e32 v120, v120, v122
	v_mul_f32_e32 v122, 0xbfb8aa3b, v158
	v_exp_f32_e32 v122, v122
	v_exp_f32_e32 v125, v125
	v_mul_f32_e32 v124, 0xbfb8aa3b, v124
	v_exp_f32_e32 v124, v124
	v_add_f32_e32 v122, 1.0, v122
	v_cmp_gt_f32_e32 vcc, s65, v122
	v_add_f32_e32 v125, 1.0, v125
	v_add_f32_e32 v124, 1.0, v124
	v_cndmask_b32_e64 v123, 0, 32, vcc
	v_ldexp_f32 v122, v122, v123
	v_log_f32_e32 v122, v122
	v_mul_f32_e32 v121, 0xbfb8aa3b, v121
	v_exp_f32_e32 v121, v121
	v_sub_f32_e32 v120, -0.5, v120
	v_mul_f32_e32 v123, 0x3f317217, v122
	v_fma_f32 v123, v122, s61, -v123
	v_fmac_f32_e32 v123, 0x3377d1cf, v122
	v_fmac_f32_e32 v123, 0x3f317217, v122
	v_cmp_lt_f32_e64 s[0:1], |v122|, s66
	v_add_f32_e32 v121, 1.0, v121
	v_mul_f32_e32 v120, 0x3fb8aa3b, v120
	v_cndmask_b32_e64 v122, v122, v123, s[0:1]
	v_cndmask_b32_e32 v123, 0, v179, vcc
	v_sub_f32_e32 v122, v122, v123
	v_mul_f32_e32 v123, 0xbfb8aa3b, v159
	v_exp_f32_e32 v123, v123
	v_sub_f32_e32 v122, -0.5, v122
	v_mul_f32_e32 v122, 0x3fb8aa3b, v122
	v_exp_f32_e32 v120, v120
	v_add_f32_e32 v123, 1.0, v123
	v_cmp_gt_f32_e32 vcc, s65, v123
	v_exp_f32_e32 v122, v122
	v_mul_f32_e32 v120, 0xbfb8aa3b, v120
	v_cndmask_b32_e64 v127, 0, 32, vcc
	v_ldexp_f32 v123, v123, v127
	v_log_f32_e32 v123, v123
	v_mul_f32_e32 v122, 0xbfb8aa3b, v122
	v_exp_f32_e32 v120, v120
	v_exp_f32_e32 v122, v122
	v_mul_f32_e32 v127, 0x3f317217, v123
	v_fma_f32 v127, v123, s61, -v127
	v_fmac_f32_e32 v127, 0x3377d1cf, v123
	v_fmac_f32_e32 v127, 0x3f317217, v123
	v_cmp_lt_f32_e64 s[0:1], |v123|, s66
	v_cvt_pk_f16_f32 v122, v120, v122
	s_nop 0
	v_cndmask_b32_e64 v123, v123, v127, s[0:1]
	v_cndmask_b32_e32 v127, 0, v179, vcc
	v_cmp_gt_f32_e32 vcc, s65, v126
	v_sub_f32_e32 v123, v123, v127
	v_sub_f32_e32 v123, -0.5, v123
	v_cndmask_b32_e64 v127, 0, 32, vcc
	v_ldexp_f32 v126, v126, v127
	v_log_f32_e32 v126, v126
	v_mul_f32_e32 v123, 0x3fb8aa3b, v123
	v_exp_f32_e32 v123, v123
	v_mul_f32_e32 v127, 0x3f317217, v126
	v_fma_f32 v127, v126, s61, -v127
	v_fmac_f32_e32 v127, 0x3377d1cf, v126
	v_fmac_f32_e32 v127, 0x3f317217, v126
	v_cmp_lt_f32_e64 s[0:1], |v126|, s66
	v_mul_f32_e32 v123, 0xbfb8aa3b, v123
	v_exp_f32_e32 v123, v123
	v_cndmask_b32_e64 v126, v126, v127, s[0:1]
	v_cndmask_b32_e32 v127, 0, v179, vcc
	v_sub_f32_e32 v126, v126, v127
	v_mul_f32_e32 v127, 0xbfb8aa3b, v139
	v_exp_f32_e32 v127, v127
	v_sub_f32_e32 v126, -0.5, v126
	v_mul_f32_e32 v126, 0x3fb8aa3b, v126
	v_exp_f32_e32 v126, v126
	v_add_f32_e32 v127, 1.0, v127
	v_cmp_gt_f32_e32 vcc, s65, v127
	v_mul_f32_e32 v126, 0xbfb8aa3b, v126
	s_nop 0
	v_cndmask_b32_e64 v139, 0, 32, vcc
	v_ldexp_f32 v127, v127, v139
	v_log_f32_e32 v127, v127
	v_exp_f32_e32 v126, v126
	v_mul_f32_e32 v139, 0x3f317217, v127
	v_fma_f32 v139, v127, s61, -v139
	v_fmac_f32_e32 v139, 0x3377d1cf, v127
	v_fmac_f32_e32 v139, 0x3f317217, v127
	v_cmp_lt_f32_e64 s[0:1], |v127|, s66
	v_cvt_pk_f16_f32 v123, v123, v126
	s_nop 0
	v_cndmask_b32_e64 v127, v127, v139, s[0:1]
	v_cndmask_b32_e32 v139, 0, v179, vcc
	v_cmp_gt_f32_e32 vcc, s65, v125
	v_sub_f32_e32 v127, v127, v139
	v_sub_f32_e32 v127, -0.5, v127
	v_cndmask_b32_e64 v139, 0, 32, vcc
	v_ldexp_f32 v125, v125, v139
	v_log_f32_e32 v125, v125
	v_mul_f32_e32 v127, 0x3fb8aa3b, v127
	v_exp_f32_e32 v127, v127
	v_mul_f32_e32 v139, 0x3f317217, v125
	v_fma_f32 v139, v125, s61, -v139
	v_fmac_f32_e32 v139, 0x3377d1cf, v125
	v_fmac_f32_e32 v139, 0x3f317217, v125
	v_cmp_lt_f32_e64 s[0:1], |v125|, s66
	v_mul_f32_e32 v127, 0xbfb8aa3b, v127
	v_exp_f32_e32 v127, v127
	v_cndmask_b32_e64 v125, v125, v139, s[0:1]
	v_cndmask_b32_e32 v139, 0, v179, vcc
	v_cmp_gt_f32_e32 vcc, s65, v124
	v_sub_f32_e32 v125, v125, v139
	v_sub_f32_e32 v125, -0.5, v125
;     template <int MODE> __device__ __forceinline__ void run(AccRef acc, const Unit& u, int wr, int wc, int fr, int fq) const {
;     ...
;                     if (MODE == 0) {
; #pragma unroll
;                         for (int e = 0; e < 8; ++e) { const float sp = __logf(1.f + __expf(-x[e])); x[e] = __expf(-__expf(-sp - 0.5f)); }
;                         w.x = pkh(x[0], x[1]); w.y = pkh(x[2], x[3]); w.z = pkh(x[4], x[5]); w.w = pkh(x[6], x[7]);
;                         *(u32x4*)(WA + (size_t)row * 2048 + seg * 512 + cc) = w;
	v_cndmask_b32_e64 v139, 0, 32, vcc
	v_ldexp_f32 v124, v124, v139
	v_log_f32_e32 v124, v124
	v_mul_f32_e32 v125, 0x3fb8aa3b, v125
	v_exp_f32_e32 v125, v125
	v_mul_f32_e32 v139, 0x3f317217, v124
	v_fma_f32 v139, v124, s61, -v139
	v_fmac_f32_e32 v139, 0x3377d1cf, v124
	v_fmac_f32_e32 v139, 0x3f317217, v124
	v_cmp_lt_f32_e64 s[0:1], |v124|, s66
	v_mul_f32_e32 v125, 0xbfb8aa3b, v125
	v_exp_f32_e32 v125, v125
	v_cndmask_b32_e64 v124, v124, v139, s[0:1]
	v_cndmask_b32_e32 v139, 0, v179, vcc
	v_sub_f32_e32 v124, v124, v139
	v_sub_f32_e32 v124, -0.5, v124
	v_mul_f32_e32 v124, 0x3fb8aa3b, v124
	v_exp_f32_e32 v124, v124
	v_cmp_gt_f32_e32 vcc, s65, v121
	v_mul_f32_e32 v124, 0xbfb8aa3b, v124
	v_exp_f32_e32 v139, v124
	v_cndmask_b32_e64 v124, 0, 32, vcc
	v_ldexp_f32 v121, v121, v124
	v_log_f32_e32 v121, v121
	s_nop 0
	v_mul_f32_e32 v124, 0x3f317217, v121
	v_fma_f32 v124, v121, s61, -v124
	v_fmac_f32_e32 v124, 0x3377d1cf, v121
	v_fmac_f32_e32 v124, 0x3f317217, v121
	v_cmp_lt_f32_e64 s[0:1], |v121|, s66
	s_nop 1
	v_cndmask_b32_e64 v121, v121, v124, s[0:1]
	v_cndmask_b32_e32 v124, 0, v179, vcc
	v_sub_f32_e32 v121, v121, v124
	v_sub_f32_e32 v121, -0.5, v121
	v_mul_f32_e32 v121, 0x3fb8aa3b, v121
	v_exp_f32_e32 v121, v121
	v_cvt_pk_f16_f32 v124, v127, v125
	v_mul_f32_e32 v121, 0xbfb8aa3b, v121
	v_exp_f32_e32 v121, v121
	s_nop 0
	v_cvt_pk_f16_f32 v125, v139, v121
	v_ashrrev_i32_e32 v139, 31, v138
	v_lshlrev_b64 v[120:121], 12, v[138:139]
	v_lshl_add_u64 v[120:121], s[48:49], 0, v[120:121]
	v_lshl_add_u64 v[120:121], s[4:5], 1, v[120:121]
	v_lshl_add_u64 v[120:121], v[156:157], 1, v[120:121]
	global_store_dwordx4 v[120:121], v[122:125], off sc1
	v_add_f32_e32 v116, v116, v132
	v_mul_f32_e32 v116, 0xbfb8aa3b, v116
	v_exp_f32_e32 v116, v116
	v_add_f32_e32 v117, v117, v133
	v_mul_f32_e32 v117, 0xbfb8aa3b, v117
	v_exp_f32_e32 v117, v117
	v_add_f32_e32 v116, 1.0, v116
	v_cmp_gt_f32_e32 vcc, s65, v116
	v_add_f32_e32 v118, v118, v134
	v_add_f32_e32 v117, 1.0, v117
	v_cndmask_b32_e64 v122, 0, 32, vcc
	v_ldexp_f32 v116, v116, v122
	v_log_f32_e32 v116, v116
	v_mul_f32_e32 v118, 0xbfb8aa3b, v118
	v_exp_f32_e32 v118, v118
	v_add_f32_e32 v119, v119, v135
	v_mul_f32_e32 v122, 0x3f317217, v116
	v_fma_f32 v122, v116, s61, -v122
	v_fmac_f32_e32 v122, 0x3377d1cf, v116
	v_fmac_f32_e32 v122, 0x3f317217, v116
	v_cmp_lt_f32_e64 s[0:1], |v116|, s66
	v_add_f32_e32 v118, 1.0, v118
	v_mul_f32_e32 v119, 0xbfb8aa3b, v119
	v_cndmask_b32_e64 v116, v116, v122, s[0:1]
	v_cndmask_b32_e32 v122, 0, v179, vcc
	v_cmp_gt_f32_e32 vcc, s65, v117
	v_sub_f32_e32 v116, v116, v122
	v_exp_f32_e32 v119, v119
	v_cndmask_b32_e64 v122, 0, 32, vcc
	v_ldexp_f32 v117, v117, v122
	v_log_f32_e32 v117, v117
	v_add_f32_e32 v119, 1.0, v119
	v_add_f32_e32 v112, v112, v128
	v_mul_f32_e32 v112, 0xbfb8aa3b, v112
	v_mul_f32_e32 v122, 0x3f317217, v117
	v_fma_f32 v122, v117, s61, -v122
	v_fmac_f32_e32 v122, 0x3377d1cf, v117
	v_fmac_f32_e32 v122, 0x3f317217, v117
	v_cmp_lt_f32_e64 s[0:1], |v117|, s66
	v_exp_f32_e32 v112, v112
	v_add_f32_e32 v113, v113, v129
	v_cndmask_b32_e64 v117, v117, v122, s[0:1]
	v_cndmask_b32_e32 v122, 0, v179, vcc
	v_cmp_gt_f32_e32 vcc, s65, v118
	v_sub_f32_e32 v117, v117, v122
	v_add_f32_e32 v112, 1.0, v112
	v_cndmask_b32_e64 v122, 0, 32, vcc
	v_ldexp_f32 v118, v118, v122
	v_log_f32_e32 v118, v118
	v_mul_f32_e32 v113, 0xbfb8aa3b, v113
	v_exp_f32_e32 v113, v113
	v_add_f32_e32 v114, v114, v130
	v_mul_f32_e32 v122, 0x3f317217, v118
	v_fma_f32 v122, v118, s61, -v122
	v_fmac_f32_e32 v122, 0x3377d1cf, v118
	v_fmac_f32_e32 v122, 0x3f317217, v118
	v_cmp_lt_f32_e64 s[0:1], |v118|, s66
	v_add_f32_e32 v113, 1.0, v113
	v_mul_f32_e32 v114, 0xbfb8aa3b, v114
	v_cndmask_b32_e64 v118, v118, v122, s[0:1]
	v_cndmask_b32_e32 v122, 0, v179, vcc
	v_cmp_gt_f32_e32 vcc, s65, v119
	v_sub_f32_e32 v118, v118, v122
	v_exp_f32_e32 v114, v114
	v_cndmask_b32_e64 v122, 0, 32, vcc
	v_ldexp_f32 v119, v119, v122
	v_log_f32_e32 v119, v119
	v_add_f32_e32 v114, 1.0, v114
	v_add_f32_e32 v115, v115, v131
	v_mul_f32_e32 v115, 0xbfb8aa3b, v115
	v_mul_f32_e32 v122, 0x3f317217, v119
	v_fma_f32 v122, v119, s61, -v122
	v_fmac_f32_e32 v122, 0x3377d1cf, v119
	v_fmac_f32_e32 v122, 0x3f317217, v119
	v_cmp_lt_f32_e64 s[0:1], |v119|, s66
	v_exp_f32_e32 v115, v115
	v_sub_f32_e32 v118, -0.5, v118
	v_cndmask_b32_e64 v119, v119, v122, s[0:1]
	v_cndmask_b32_e32 v122, 0, v179, vcc
	v_cmp_gt_f32_e32 vcc, s65, v112
	v_sub_f32_e32 v119, v119, v122
	v_add_f32_e32 v115, 1.0, v115
	v_cndmask_b32_e64 v122, 0, 32, vcc
	v_ldexp_f32 v112, v112, v122
	v_log_f32_e32 v112, v112
	v_sub_f32_e32 v119, -0.5, v119
	v_sub_f32_e32 v116, -0.5, v116
	v_sub_f32_e32 v117, -0.5, v117
	v_mul_f32_e32 v122, 0x3f317217, v112
	v_fma_f32 v122, v112, s61, -v122
	v_fmac_f32_e32 v122, 0x3377d1cf, v112
	v_fmac_f32_e32 v122, 0x3f317217, v112
	v_cmp_lt_f32_e64 s[0:1], |v112|, s66
	v_mul_f32_e32 v118, 0x3fb8aa3b, v118
	v_mul_f32_e32 v119, 0x3fb8aa3b, v119
	v_cndmask_b32_e64 v112, v112, v122, s[0:1]
	v_cndmask_b32_e32 v122, 0, v179, vcc
	v_cmp_gt_f32_e32 vcc, s65, v113
	v_sub_f32_e32 v112, v112, v122
	v_sub_f32_e32 v112, -0.5, v112
	v_cndmask_b32_e64 v122, 0, 32, vcc
	v_ldexp_f32 v113, v113, v122
	v_log_f32_e32 v113, v113
	v_mul_f32_e32 v116, 0x3fb8aa3b, v116
	v_mul_f32_e32 v117, 0x3fb8aa3b, v117
	v_exp_f32_e32 v118, v118
	v_mul_f32_e32 v122, 0x3f317217, v113
	v_fma_f32 v122, v113, s61, -v122
	v_fmac_f32_e32 v122, 0x3377d1cf, v113
	v_fmac_f32_e32 v122, 0x3f317217, v113
	v_cmp_lt_f32_e64 s[0:1], |v113|, s66
	v_exp_f32_e32 v119, v119
	v_mul_f32_e32 v112, 0x3fb8aa3b, v112
	v_cndmask_b32_e64 v113, v113, v122, s[0:1]
	v_cndmask_b32_e32 v122, 0, v179, vcc
	v_cmp_gt_f32_e32 vcc, s65, v114
;     template <int MODE> __device__ __forceinline__ void run(AccRef acc, const Unit& u, int wr, int wc, int fr, int fq) const {
;     ...
;                     if (MODE == 0) {
; #pragma unroll
;                         for (int e = 0; e < 8; ++e) { const float sp = __logf(1.f + __expf(-x[e])); x[e] = __expf(-__expf(-sp - 0.5f)); }
;                         w.x = pkh(x[0], x[1]); w.y = pkh(x[2], x[3]); w.z = pkh(x[4], x[5]); w.w = pkh(x[6], x[7]);
;                         *(u32x4*)(WA + (size_t)row * 2048 + seg * 512 + cc) = w;
	v_sub_f32_e32 v113, v113, v122
	v_sub_f32_e32 v113, -0.5, v113
	v_cndmask_b32_e64 v122, 0, 32, vcc
	v_ldexp_f32 v114, v114, v122
	v_log_f32_e32 v114, v114
	v_mul_f32_e32 v113, 0x3fb8aa3b, v113
	v_exp_f32_e32 v116, v116
	v_exp_f32_e32 v117, v117
	v_mul_f32_e32 v122, 0x3f317217, v114
	v_fma_f32 v122, v114, s61, -v122
	v_fmac_f32_e32 v122, 0x3377d1cf, v114
	v_fmac_f32_e32 v122, 0x3f317217, v114
	v_cmp_lt_f32_e64 s[0:1], |v114|, s66
	v_exp_f32_e32 v112, v112
	v_exp_f32_e32 v113, v113
	v_cndmask_b32_e64 v114, v114, v122, s[0:1]
	v_cndmask_b32_e32 v122, 0, v179, vcc
	v_cmp_gt_f32_e32 vcc, s65, v115
	v_sub_f32_e32 v114, v114, v122
	v_sub_f32_e32 v114, -0.5, v114
	v_cndmask_b32_e64 v122, 0, 32, vcc
	v_ldexp_f32 v115, v115, v122
	v_log_f32_e32 v115, v115
	v_mul_f32_e32 v114, 0x3fb8aa3b, v114
	v_exp_f32_e32 v114, v114
	v_mul_f32_e32 v118, 0xbfb8aa3b, v118
	v_mul_f32_e32 v122, 0x3f317217, v115
	v_fma_f32 v122, v115, s61, -v122
	v_fmac_f32_e32 v122, 0x3377d1cf, v115
	v_fmac_f32_e32 v122, 0x3f317217, v115
	v_cmp_lt_f32_e64 s[0:1], |v115|, s66
	v_mul_f32_e32 v119, 0xbfb8aa3b, v119
	v_mul_f32_e32 v114, 0xbfb8aa3b, v114
	v_cndmask_b32_e64 v115, v115, v122, s[0:1]
	v_cndmask_b32_e32 v122, 0, v179, vcc
	v_sub_f32_e32 v115, v115, v122
	v_sub_f32_e32 v115, -0.5, v115
	v_mul_f32_e32 v115, 0x3fb8aa3b, v115
	v_exp_f32_e32 v115, v115
	v_mul_f32_e32 v116, 0xbfb8aa3b, v116
	v_mul_f32_e32 v117, 0xbfb8aa3b, v117
	v_exp_f32_e32 v118, v118
	v_exp_f32_e32 v119, v119
	v_mul_f32_e32 v112, 0xbfb8aa3b, v112
	v_mul_f32_e32 v113, 0xbfb8aa3b, v113
	v_exp_f32_e32 v122, v114
	v_mul_f32_e32 v114, 0xbfb8aa3b, v115
	v_exp_f32_e32 v116, v116
	v_exp_f32_e32 v117, v117
	v_exp_f32_e32 v112, v112
	v_exp_f32_e32 v113, v113
	v_exp_f32_e32 v123, v114
	v_cvt_pk_f16_f32 v115, v118, v119
	v_add_co_u32_e32 v118, vcc, s39, v120
	v_cvt_pk_f16_f32 v114, v116, v117
	v_cvt_pk_f16_f32 v116, v112, v113
	v_cvt_pk_f16_f32 v117, v122, v123
	v_addc_co_u32_e32 v119, vcc, 0, v121, vcc
	v_lshl_add_u64 v[112:113], v[120:121], 0, s[58:59]
	global_store_dwordx4 v[118:119], v[114:117], off sc1
	v_add_f32_e32 v108, v108, v132
	v_mul_f32_e32 v108, 0xbfb8aa3b, v108
	v_exp_f32_e32 v108, v108
	v_add_f32_e32 v109, v109, v133
	v_mul_f32_e32 v109, 0xbfb8aa3b, v109
	v_exp_f32_e32 v109, v109
	v_add_f32_e32 v108, 1.0, v108
	v_cmp_gt_f32_e32 vcc, s65, v108
	v_add_f32_e32 v110, v110, v134
	v_add_f32_e32 v109, 1.0, v109
	v_cndmask_b32_e64 v114, 0, 32, vcc
	v_ldexp_f32 v108, v108, v114
	v_log_f32_e32 v108, v108
	v_mul_f32_e32 v110, 0xbfb8aa3b, v110
	v_exp_f32_e32 v110, v110
	v_add_f32_e32 v111, v111, v135
	v_mul_f32_e32 v114, 0x3f317217, v108
	v_fma_f32 v114, v108, s61, -v114
	v_fmac_f32_e32 v114, 0x3377d1cf, v108
	v_fmac_f32_e32 v114, 0x3f317217, v108
	v_cmp_lt_f32_e64 s[0:1], |v108|, s66
	v_add_f32_e32 v110, 1.0, v110
	v_mul_f32_e32 v111, 0xbfb8aa3b, v111
	v_cndmask_b32_e64 v108, v108, v114, s[0:1]
	v_cndmask_b32_e32 v114, 0, v179, vcc
	v_cmp_gt_f32_e32 vcc, s65, v109
	v_sub_f32_e32 v108, v108, v114
	v_exp_f32_e32 v111, v111
	v_cndmask_b32_e64 v114, 0, 32, vcc
	v_ldexp_f32 v109, v109, v114
	v_log_f32_e32 v109, v109
	v_add_f32_e32 v111, 1.0, v111
	v_add_f32_e32 v104, v104, v128
	v_mul_f32_e32 v104, 0xbfb8aa3b, v104
	v_mul_f32_e32 v114, 0x3f317217, v109
	v_fma_f32 v114, v109, s61, -v114
	v_fmac_f32_e32 v114, 0x3377d1cf, v109
	v_fmac_f32_e32 v114, 0x3f317217, v109
	v_cmp_lt_f32_e64 s[0:1], |v109|, s66
	v_exp_f32_e32 v104, v104
	v_add_f32_e32 v105, v105, v129
	v_cndmask_b32_e64 v109, v109, v114, s[0:1]
	v_cndmask_b32_e32 v114, 0, v179, vcc
	v_cmp_gt_f32_e32 vcc, s65, v110
	v_sub_f32_e32 v109, v109, v114
	v_add_f32_e32 v104, 1.0, v104
	v_cndmask_b32_e64 v114, 0, 32, vcc
	v_ldexp_f32 v110, v110, v114
	v_log_f32_e32 v110, v110
	v_mul_f32_e32 v105, 0xbfb8aa3b, v105
	v_exp_f32_e32 v105, v105
	v_add_f32_e32 v106, v106, v130
	v_mul_f32_e32 v114, 0x3f317217, v110
	v_fma_f32 v114, v110, s61, -v114
	v_fmac_f32_e32 v114, 0x3377d1cf, v110
	v_fmac_f32_e32 v114, 0x3f317217, v110
	v_cmp_lt_f32_e64 s[0:1], |v110|, s66
	v_add_f32_e32 v105, 1.0, v105
	v_mul_f32_e32 v106, 0xbfb8aa3b, v106
	v_cndmask_b32_e64 v110, v110, v114, s[0:1]
	v_cndmask_b32_e32 v114, 0, v179, vcc
	v_cmp_gt_f32_e32 vcc, s65, v111
	v_sub_f32_e32 v110, v110, v114
	v_exp_f32_e32 v106, v106
	v_cndmask_b32_e64 v114, 0, 32, vcc
	v_ldexp_f32 v111, v111, v114
	v_log_f32_e32 v111, v111
	v_add_f32_e32 v106, 1.0, v106
	v_add_f32_e32 v107, v107, v131
	v_mul_f32_e32 v107, 0xbfb8aa3b, v107
	v_mul_f32_e32 v114, 0x3f317217, v111
	v_fma_f32 v114, v111, s61, -v114
	v_fmac_f32_e32 v114, 0x3377d1cf, v111
	v_fmac_f32_e32 v114, 0x3f317217, v111
	v_cmp_lt_f32_e64 s[0:1], |v111|, s66
	v_exp_f32_e32 v107, v107
	v_sub_f32_e32 v110, -0.5, v110
	v_cndmask_b32_e64 v111, v111, v114, s[0:1]
	v_cndmask_b32_e32 v114, 0, v179, vcc
	v_cmp_gt_f32_e32 vcc, s65, v104
	v_sub_f32_e32 v111, v111, v114
	v_add_f32_e32 v107, 1.0, v107
	v_cndmask_b32_e64 v114, 0, 32, vcc
	v_ldexp_f32 v104, v104, v114
	v_log_f32_e32 v104, v104
	v_sub_f32_e32 v111, -0.5, v111
	v_sub_f32_e32 v108, -0.5, v108
	v_sub_f32_e32 v109, -0.5, v109
	v_mul_f32_e32 v114, 0x3f317217, v104
	v_fma_f32 v114, v104, s61, -v114
	v_fmac_f32_e32 v114, 0x3377d1cf, v104
	v_fmac_f32_e32 v114, 0x3f317217, v104
	v_cmp_lt_f32_e64 s[0:1], |v104|, s66
	v_mul_f32_e32 v110, 0x3fb8aa3b, v110
	v_mul_f32_e32 v111, 0x3fb8aa3b, v111
	v_cndmask_b32_e64 v104, v104, v114, s[0:1]
	v_cndmask_b32_e32 v114, 0, v179, vcc
	v_cmp_gt_f32_e32 vcc, s65, v105
	v_sub_f32_e32 v104, v104, v114
	v_sub_f32_e32 v104, -0.5, v104
	v_cndmask_b32_e64 v114, 0, 32, vcc
	v_ldexp_f32 v105, v105, v114
	v_log_f32_e32 v105, v105
	v_mul_f32_e32 v108, 0x3fb8aa3b, v108
	v_mul_f32_e32 v109, 0x3fb8aa3b, v109
;     template <int MODE> __device__ __forceinline__ void run(AccRef acc, const Unit& u, int wr, int wc, int fr, int fq) const {
;     ...
;                     if (MODE == 0) {
; #pragma unroll
;                         for (int e = 0; e < 8; ++e) { const float sp = __logf(1.f + __expf(-x[e])); x[e] = __expf(-__expf(-sp - 0.5f)); }
;                         w.x = pkh(x[0], x[1]); w.y = pkh(x[2], x[3]); w.z = pkh(x[4], x[5]); w.w = pkh(x[6], x[7]);
;                         *(u32x4*)(WA + (size_t)row * 2048 + seg * 512 + cc) = w;
	v_exp_f32_e32 v110, v110
	v_mul_f32_e32 v114, 0x3f317217, v105
	v_fma_f32 v114, v105, s61, -v114
	v_fmac_f32_e32 v114, 0x3377d1cf, v105
	v_fmac_f32_e32 v114, 0x3f317217, v105
	v_cmp_lt_f32_e64 s[0:1], |v105|, s66
	v_exp_f32_e32 v111, v111
	v_mul_f32_e32 v104, 0x3fb8aa3b, v104
	v_cndmask_b32_e64 v105, v105, v114, s[0:1]
	v_cndmask_b32_e32 v114, 0, v179, vcc
	v_cmp_gt_f32_e32 vcc, s65, v106
	v_sub_f32_e32 v105, v105, v114
	v_sub_f32_e32 v105, -0.5, v105
	v_cndmask_b32_e64 v114, 0, 32, vcc
	v_ldexp_f32 v106, v106, v114
	v_log_f32_e32 v106, v106
	v_mul_f32_e32 v105, 0x3fb8aa3b, v105
	v_exp_f32_e32 v108, v108
	v_exp_f32_e32 v109, v109
	v_mul_f32_e32 v114, 0x3f317217, v106
	v_fma_f32 v114, v106, s61, -v114
	v_fmac_f32_e32 v114, 0x3377d1cf, v106
	v_fmac_f32_e32 v114, 0x3f317217, v106
	v_cmp_lt_f32_e64 s[0:1], |v106|, s66
	v_exp_f32_e32 v104, v104
	v_exp_f32_e32 v105, v105
	v_cndmask_b32_e64 v106, v106, v114, s[0:1]
	v_cndmask_b32_e32 v114, 0, v179, vcc
	v_cmp_gt_f32_e32 vcc, s65, v107
	v_sub_f32_e32 v106, v106, v114
	v_sub_f32_e32 v106, -0.5, v106
	v_cndmask_b32_e64 v114, 0, 32, vcc
	v_ldexp_f32 v107, v107, v114
	v_log_f32_e32 v107, v107
	v_mul_f32_e32 v106, 0x3fb8aa3b, v106
	v_exp_f32_e32 v106, v106
	v_mul_f32_e32 v110, 0xbfb8aa3b, v110
	v_mul_f32_e32 v114, 0x3f317217, v107
	v_fma_f32 v114, v107, s61, -v114
	v_fmac_f32_e32 v114, 0x3377d1cf, v107
	v_fmac_f32_e32 v114, 0x3f317217, v107
	v_cmp_lt_f32_e64 s[0:1], |v107|, s66
	v_mul_f32_e32 v111, 0xbfb8aa3b, v111
	v_mul_f32_e32 v106, 0xbfb8aa3b, v106
	v_cndmask_b32_e64 v107, v107, v114, s[0:1]
	v_cndmask_b32_e32 v114, 0, v179, vcc
	v_sub_f32_e32 v107, v107, v114
	v_sub_f32_e32 v107, -0.5, v107
	v_mul_f32_e32 v107, 0x3fb8aa3b, v107
	v_exp_f32_e32 v107, v107
	v_mul_f32_e32 v108, 0xbfb8aa3b, v108
	v_mul_f32_e32 v109, 0xbfb8aa3b, v109
	v_exp_f32_e32 v110, v110
	v_exp_f32_e32 v111, v111
	v_mul_f32_e32 v104, 0xbfb8aa3b, v104
	v_mul_f32_e32 v105, 0xbfb8aa3b, v105
	v_exp_f32_e32 v114, v106
	v_mul_f32_e32 v106, 0xbfb8aa3b, v107
	v_exp_f32_e32 v108, v108
	v_exp_f32_e32 v109, v109
	v_exp_f32_e32 v104, v104
	v_exp_f32_e32 v105, v105
	v_exp_f32_e32 v115, v106
	s_mov_b32 s0, 0x20000
	v_cvt_pk_f16_f32 v107, v110, v111
	v_add_co_u32_e32 v110, vcc, s0, v120
	v_cvt_pk_f16_f32 v106, v108, v109
	v_cvt_pk_f16_f32 v108, v104, v105
	v_cvt_pk_f16_f32 v109, v114, v115
	v_addc_co_u32_e32 v111, vcc, 0, v121, vcc
	v_lshl_add_u64 v[104:105], v[120:121], 0, s[46:47]
	global_store_dwordx4 v[110:111], v[106:109], off sc1
	v_add_f32_e32 v100, v100, v132
	v_mul_f32_e32 v100, 0xbfb8aa3b, v100
	v_exp_f32_e32 v100, v100
	v_add_f32_e32 v101, v101, v133
	v_mul_f32_e32 v101, 0xbfb8aa3b, v101
	v_exp_f32_e32 v101, v101
	v_add_f32_e32 v100, 1.0, v100
	v_cmp_gt_f32_e32 vcc, s65, v100
	v_add_f32_e32 v102, v102, v134
	v_add_f32_e32 v101, 1.0, v101
	v_cndmask_b32_e64 v106, 0, 32, vcc
	v_ldexp_f32 v100, v100, v106
	v_log_f32_e32 v100, v100
	v_mul_f32_e32 v102, 0xbfb8aa3b, v102
	v_exp_f32_e32 v102, v102
	v_add_f32_e32 v103, v103, v135
	v_mul_f32_e32 v106, 0x3f317217, v100
	v_fma_f32 v106, v100, s61, -v106
	v_fmac_f32_e32 v106, 0x3377d1cf, v100
	v_fmac_f32_e32 v106, 0x3f317217, v100
	v_cmp_lt_f32_e64 s[0:1], |v100|, s66
	v_add_f32_e32 v102, 1.0, v102
	v_mul_f32_e32 v103, 0xbfb8aa3b, v103
	v_cndmask_b32_e64 v100, v100, v106, s[0:1]
	v_cndmask_b32_e32 v106, 0, v179, vcc
	v_cmp_gt_f32_e32 vcc, s65, v101
	v_sub_f32_e32 v100, v100, v106
	v_exp_f32_e32 v103, v103
	v_cndmask_b32_e64 v106, 0, 32, vcc
	v_ldexp_f32 v101, v101, v106
	v_log_f32_e32 v101, v101
	v_add_f32_e32 v103, 1.0, v103
	v_add_f32_e32 v96, v96, v128
	v_mul_f32_e32 v96, 0xbfb8aa3b, v96
	v_mul_f32_e32 v106, 0x3f317217, v101
	v_fma_f32 v106, v101, s61, -v106
	v_fmac_f32_e32 v106, 0x3377d1cf, v101
	v_fmac_f32_e32 v106, 0x3f317217, v101
	v_cmp_lt_f32_e64 s[0:1], |v101|, s66
	v_exp_f32_e32 v96, v96
	v_add_f32_e32 v97, v97, v129
	v_cndmask_b32_e64 v101, v101, v106, s[0:1]
	v_cndmask_b32_e32 v106, 0, v179, vcc
	v_cmp_gt_f32_e32 vcc, s65, v102
	v_sub_f32_e32 v101, v101, v106
	v_add_f32_e32 v96, 1.0, v96
	v_cndmask_b32_e64 v106, 0, 32, vcc
	v_ldexp_f32 v102, v102, v106
	v_log_f32_e32 v102, v102
	v_mul_f32_e32 v97, 0xbfb8aa3b, v97
	v_exp_f32_e32 v97, v97
	v_add_f32_e32 v98, v98, v130
	v_mul_f32_e32 v106, 0x3f317217, v102
	v_fma_f32 v106, v102, s61, -v106
	v_fmac_f32_e32 v106, 0x3377d1cf, v102
	v_fmac_f32_e32 v106, 0x3f317217, v102
	v_cmp_lt_f32_e64 s[0:1], |v102|, s66
	v_add_f32_e32 v97, 1.0, v97
	v_mul_f32_e32 v98, 0xbfb8aa3b, v98
	v_cndmask_b32_e64 v102, v102, v106, s[0:1]
	v_cndmask_b32_e32 v106, 0, v179, vcc
	v_cmp_gt_f32_e32 vcc, s65, v103
	v_sub_f32_e32 v102, v102, v106
	v_exp_f32_e32 v98, v98
	v_cndmask_b32_e64 v106, 0, 32, vcc
	v_ldexp_f32 v103, v103, v106
	v_log_f32_e32 v103, v103
	v_add_f32_e32 v98, 1.0, v98
	v_add_f32_e32 v99, v99, v131
	v_mul_f32_e32 v99, 0xbfb8aa3b, v99
	v_mul_f32_e32 v106, 0x3f317217, v103
	v_fma_f32 v106, v103, s61, -v106
	v_fmac_f32_e32 v106, 0x3377d1cf, v103
	v_fmac_f32_e32 v106, 0x3f317217, v103
	v_cmp_lt_f32_e64 s[0:1], |v103|, s66
	v_exp_f32_e32 v99, v99
	v_sub_f32_e32 v102, -0.5, v102
	v_cndmask_b32_e64 v103, v103, v106, s[0:1]
	v_cndmask_b32_e32 v106, 0, v179, vcc
	v_cmp_gt_f32_e32 vcc, s65, v96
	v_sub_f32_e32 v103, v103, v106
	v_add_f32_e32 v99, 1.0, v99
	v_cndmask_b32_e64 v106, 0, 32, vcc
	v_ldexp_f32 v96, v96, v106
	v_log_f32_e32 v96, v96
	v_sub_f32_e32 v103, -0.5, v103
	v_sub_f32_e32 v100, -0.5, v100
	v_sub_f32_e32 v101, -0.5, v101
	v_mul_f32_e32 v106, 0x3f317217, v96
	v_fma_f32 v106, v96, s61, -v106
	v_fmac_f32_e32 v106, 0x3377d1cf, v96
	v_fmac_f32_e32 v106, 0x3f317217, v96
	v_cmp_lt_f32_e64 s[0:1], |v96|, s66
	v_mul_f32_e32 v102, 0x3fb8aa3b, v102
;     template <int MODE> __device__ __forceinline__ void run(AccRef acc, const Unit& u, int wr, int wc, int fr, int fq) const {
;     ...
;                     if (MODE == 0) {
; #pragma unroll
;                         for (int e = 0; e < 8; ++e) { const float sp = __logf(1.f + __expf(-x[e])); x[e] = __expf(-__expf(-sp - 0.5f)); }
;                         w.x = pkh(x[0], x[1]); w.y = pkh(x[2], x[3]); w.z = pkh(x[4], x[5]); w.w = pkh(x[6], x[7]);
;                         *(u32x4*)(WA + (size_t)row * 2048 + seg * 512 + cc) = w;
	v_mul_f32_e32 v103, 0x3fb8aa3b, v103
	v_cndmask_b32_e64 v96, v96, v106, s[0:1]
	v_cndmask_b32_e32 v106, 0, v179, vcc
	v_cmp_gt_f32_e32 vcc, s65, v97
	v_sub_f32_e32 v96, v96, v106
	v_sub_f32_e32 v96, -0.5, v96
	v_cndmask_b32_e64 v106, 0, 32, vcc
	v_ldexp_f32 v97, v97, v106
	v_log_f32_e32 v97, v97
	v_mul_f32_e32 v100, 0x3fb8aa3b, v100
	v_mul_f32_e32 v101, 0x3fb8aa3b, v101
	v_exp_f32_e32 v102, v102
	v_mul_f32_e32 v106, 0x3f317217, v97
	v_fma_f32 v106, v97, s61, -v106
	v_fmac_f32_e32 v106, 0x3377d1cf, v97
	v_fmac_f32_e32 v106, 0x3f317217, v97
	v_cmp_lt_f32_e64 s[0:1], |v97|, s66
	v_exp_f32_e32 v103, v103
	v_mul_f32_e32 v96, 0x3fb8aa3b, v96
	v_cndmask_b32_e64 v97, v97, v106, s[0:1]
	v_cndmask_b32_e32 v106, 0, v179, vcc
	v_cmp_gt_f32_e32 vcc, s65, v98
	v_sub_f32_e32 v97, v97, v106
	v_sub_f32_e32 v97, -0.5, v97
	v_cndmask_b32_e64 v106, 0, 32, vcc
	v_ldexp_f32 v98, v98, v106
	v_log_f32_e32 v98, v98
	v_mul_f32_e32 v97, 0x3fb8aa3b, v97
	v_exp_f32_e32 v100, v100
	v_exp_f32_e32 v101, v101
	v_mul_f32_e32 v106, 0x3f317217, v98
	v_fma_f32 v106, v98, s61, -v106
	v_fmac_f32_e32 v106, 0x3377d1cf, v98
	v_fmac_f32_e32 v106, 0x3f317217, v98
	v_cmp_lt_f32_e64 s[0:1], |v98|, s66
	v_exp_f32_e32 v96, v96
	v_exp_f32_e32 v97, v97
	v_cndmask_b32_e64 v98, v98, v106, s[0:1]
	v_cndmask_b32_e32 v106, 0, v179, vcc
	v_cmp_gt_f32_e32 vcc, s65, v99
	v_sub_f32_e32 v98, v98, v106
	v_sub_f32_e32 v98, -0.5, v98
	v_cndmask_b32_e64 v106, 0, 32, vcc
	v_ldexp_f32 v99, v99, v106
	v_log_f32_e32 v99, v99
	v_mul_f32_e32 v98, 0x3fb8aa3b, v98
	v_exp_f32_e32 v98, v98
	v_mul_f32_e32 v102, 0xbfb8aa3b, v102
	v_mul_f32_e32 v106, 0x3f317217, v99
	v_fma_f32 v106, v99, s61, -v106
	v_fmac_f32_e32 v106, 0x3377d1cf, v99
	v_fmac_f32_e32 v106, 0x3f317217, v99
	v_cmp_lt_f32_e64 s[0:1], |v99|, s66
	v_mul_f32_e32 v103, 0xbfb8aa3b, v103
	v_mul_f32_e32 v98, 0xbfb8aa3b, v98
	v_cndmask_b32_e64 v99, v99, v106, s[0:1]
	v_cndmask_b32_e32 v106, 0, v179, vcc
	v_sub_f32_e32 v99, v99, v106
	v_sub_f32_e32 v99, -0.5, v99
	v_mul_f32_e32 v99, 0x3fb8aa3b, v99
	v_exp_f32_e32 v99, v99
	v_mul_f32_e32 v100, 0xbfb8aa3b, v100
	v_mul_f32_e32 v101, 0xbfb8aa3b, v101
	v_exp_f32_e32 v102, v102
	v_exp_f32_e32 v103, v103
	v_mul_f32_e32 v96, 0xbfb8aa3b, v96
	v_mul_f32_e32 v97, 0xbfb8aa3b, v97
	v_exp_f32_e32 v106, v98
	v_mul_f32_e32 v98, 0xbfb8aa3b, v99
	v_exp_f32_e32 v100, v100
	v_exp_f32_e32 v101, v101
	v_exp_f32_e32 v96, v96
	v_exp_f32_e32 v97, v97
	v_exp_f32_e32 v107, v98
	v_cvt_pk_f16_f32 v99, v102, v103
	v_add_co_u32_e32 v102, vcc, s38, v120
	v_cvt_pk_f16_f32 v98, v100, v101
	v_cvt_pk_f16_f32 v100, v96, v97
	v_cvt_pk_f16_f32 v101, v106, v107
	s_mov_b64 s[0:1], 0x30000
	v_addc_co_u32_e32 v103, vcc, 0, v121, vcc
	v_lshl_add_u64 v[96:97], v[120:121], 0, s[0:1]
	global_store_dwordx4 v[102:103], v[98:101], off sc1
	v_add_f32_e32 v92, v92, v132
	v_mul_f32_e32 v92, 0xbfb8aa3b, v92
	v_exp_f32_e32 v92, v92
	v_add_f32_e32 v93, v93, v133
	v_mul_f32_e32 v93, 0xbfb8aa3b, v93
	v_exp_f32_e32 v93, v93
	v_add_f32_e32 v92, 1.0, v92
	v_cmp_gt_f32_e32 vcc, s65, v92
	v_add_f32_e32 v94, v94, v134
	v_add_f32_e32 v93, 1.0, v93
	v_cndmask_b32_e64 v98, 0, 32, vcc
	v_ldexp_f32 v92, v92, v98
	v_log_f32_e32 v92, v92
	v_mul_f32_e32 v94, 0xbfb8aa3b, v94
	v_exp_f32_e32 v94, v94
	v_add_f32_e32 v95, v95, v135
	v_mul_f32_e32 v98, 0x3f317217, v92
	v_fma_f32 v98, v92, s61, -v98
	v_fmac_f32_e32 v98, 0x3377d1cf, v92
	v_fmac_f32_e32 v98, 0x3f317217, v92
	v_cmp_lt_f32_e64 s[0:1], |v92|, s66
	v_add_f32_e32 v94, 1.0, v94
	v_mul_f32_e32 v95, 0xbfb8aa3b, v95
	v_cndmask_b32_e64 v92, v92, v98, s[0:1]
	v_cndmask_b32_e32 v98, 0, v179, vcc
	v_cmp_gt_f32_e32 vcc, s65, v93
	v_sub_f32_e32 v92, v92, v98
	v_exp_f32_e32 v95, v95
	v_cndmask_b32_e64 v98, 0, 32, vcc
	v_ldexp_f32 v93, v93, v98
	v_log_f32_e32 v93, v93
	v_add_f32_e32 v95, 1.0, v95
	v_add_f32_e32 v88, v88, v128
	v_mul_f32_e32 v88, 0xbfb8aa3b, v88
	v_mul_f32_e32 v98, 0x3f317217, v93
	v_fma_f32 v98, v93, s61, -v98
	v_fmac_f32_e32 v98, 0x3377d1cf, v93
	v_fmac_f32_e32 v98, 0x3f317217, v93
	v_cmp_lt_f32_e64 s[0:1], |v93|, s66
	v_exp_f32_e32 v88, v88
	v_add_f32_e32 v89, v89, v129
	v_cndmask_b32_e64 v93, v93, v98, s[0:1]
	v_cndmask_b32_e32 v98, 0, v179, vcc
	v_cmp_gt_f32_e32 vcc, s65, v94
	v_sub_f32_e32 v93, v93, v98
	v_add_f32_e32 v88, 1.0, v88
	v_cndmask_b32_e64 v98, 0, 32, vcc
	v_ldexp_f32 v94, v94, v98
	v_log_f32_e32 v94, v94
	v_mul_f32_e32 v89, 0xbfb8aa3b, v89
	v_exp_f32_e32 v89, v89
	v_add_f32_e32 v90, v90, v130
	v_mul_f32_e32 v98, 0x3f317217, v94
	v_fma_f32 v98, v94, s61, -v98
	v_fmac_f32_e32 v98, 0x3377d1cf, v94
	v_fmac_f32_e32 v98, 0x3f317217, v94
	v_cmp_lt_f32_e64 s[0:1], |v94|, s66
	v_add_f32_e32 v89, 1.0, v89
	v_mul_f32_e32 v90, 0xbfb8aa3b, v90
	v_cndmask_b32_e64 v94, v94, v98, s[0:1]
	v_cndmask_b32_e32 v98, 0, v179, vcc
	v_cmp_gt_f32_e32 vcc, s65, v95
	v_sub_f32_e32 v94, v94, v98
	v_exp_f32_e32 v90, v90
	v_cndmask_b32_e64 v98, 0, 32, vcc
	v_ldexp_f32 v95, v95, v98
	v_log_f32_e32 v95, v95
	v_add_f32_e32 v90, 1.0, v90
	v_add_f32_e32 v91, v91, v131
	v_mul_f32_e32 v91, 0xbfb8aa3b, v91
	v_mul_f32_e32 v98, 0x3f317217, v95
	v_fma_f32 v98, v95, s61, -v98
	v_fmac_f32_e32 v98, 0x3377d1cf, v95
	v_fmac_f32_e32 v98, 0x3f317217, v95
	v_cmp_lt_f32_e64 s[0:1], |v95|, s66
	v_exp_f32_e32 v91, v91
	v_sub_f32_e32 v92, -0.5, v92
	v_cndmask_b32_e64 v95, v95, v98, s[0:1]
	v_cndmask_b32_e32 v98, 0, v179, vcc
	v_cmp_gt_f32_e32 vcc, s65, v88
	v_sub_f32_e32 v95, v95, v98
	v_add_f32_e32 v91, 1.0, v91
	v_cndmask_b32_e64 v98, 0, 32, vcc
	v_ldexp_f32 v88, v88, v98
	v_log_f32_e32 v88, v88
	v_sub_f32_e32 v93, -0.5, v93
	v_mul_f32_e32 v92, 0x3fb8aa3b, v92
	v_mul_f32_e32 v93, 0x3fb8aa3b, v93
	v_mul_f32_e32 v98, 0x3f317217, v88
	v_fma_f32 v98, v88, s61, -v98
;     template <int MODE> __device__ __forceinline__ void run(AccRef acc, const Unit& u, int wr, int wc, int fr, int fq) const {
;     ...
;                     if (MODE == 0) {
; #pragma unroll
;                         for (int e = 0; e < 8; ++e) { const float sp = __logf(1.f + __expf(-x[e])); x[e] = __expf(-__expf(-sp - 0.5f)); }
;                         w.x = pkh(x[0], x[1]); w.y = pkh(x[2], x[3]); w.z = pkh(x[4], x[5]); w.w = pkh(x[6], x[7]);
;                         *(u32x4*)(WA + (size_t)row * 2048 + seg * 512 + cc) = w;
	v_fmac_f32_e32 v98, 0x3377d1cf, v88
	v_fmac_f32_e32 v98, 0x3f317217, v88
	v_cmp_lt_f32_e64 s[0:1], |v88|, s66
	v_sub_f32_e32 v94, -0.5, v94
	v_sub_f32_e32 v95, -0.5, v95
	v_cndmask_b32_e64 v88, v88, v98, s[0:1]
	v_cndmask_b32_e32 v98, 0, v179, vcc
	v_cmp_gt_f32_e32 vcc, s65, v89
	v_sub_f32_e32 v88, v88, v98
	v_sub_f32_e32 v88, -0.5, v88
	v_cndmask_b32_e64 v98, 0, 32, vcc
	v_ldexp_f32 v89, v89, v98
	v_log_f32_e32 v89, v89
	v_mul_f32_e32 v88, 0x3fb8aa3b, v88
	v_exp_f32_e32 v92, v92
	v_exp_f32_e32 v93, v93
	v_mul_f32_e32 v98, 0x3f317217, v89
	v_fma_f32 v98, v89, s61, -v98
	v_fmac_f32_e32 v98, 0x3377d1cf, v89
	v_fmac_f32_e32 v98, 0x3f317217, v89
	v_cmp_lt_f32_e64 s[0:1], |v89|, s66
	v_mul_f32_e32 v94, 0x3fb8aa3b, v94
	v_mul_f32_e32 v95, 0x3fb8aa3b, v95
	v_cndmask_b32_e64 v89, v89, v98, s[0:1]
	v_cndmask_b32_e32 v98, 0, v179, vcc
	v_cmp_gt_f32_e32 vcc, s65, v90
	v_sub_f32_e32 v89, v89, v98
	v_sub_f32_e32 v89, -0.5, v89
	v_cndmask_b32_e64 v98, 0, 32, vcc
	v_ldexp_f32 v90, v90, v98
	v_log_f32_e32 v90, v90
	v_mul_f32_e32 v89, 0x3fb8aa3b, v89
	v_exp_f32_e32 v88, v88
	v_exp_f32_e32 v89, v89
	v_mul_f32_e32 v98, 0x3f317217, v90
	v_fma_f32 v98, v90, s61, -v98
	v_fmac_f32_e32 v98, 0x3377d1cf, v90
	v_fmac_f32_e32 v98, 0x3f317217, v90
	v_cmp_lt_f32_e64 s[0:1], |v90|, s66
	v_exp_f32_e32 v94, v94
	v_exp_f32_e32 v95, v95
	v_cndmask_b32_e64 v90, v90, v98, s[0:1]
	v_cndmask_b32_e32 v98, 0, v179, vcc
	v_cmp_gt_f32_e32 vcc, s65, v91
	v_sub_f32_e32 v90, v90, v98
	v_sub_f32_e32 v90, -0.5, v90
	v_cndmask_b32_e64 v98, 0, 32, vcc
	v_ldexp_f32 v91, v91, v98
	v_log_f32_e32 v91, v91
	v_mul_f32_e32 v90, 0x3fb8aa3b, v90
	v_exp_f32_e32 v90, v90
	v_mul_f32_e32 v92, 0xbfb8aa3b, v92
	v_mul_f32_e32 v98, 0x3f317217, v91
	v_fma_f32 v98, v91, s61, -v98
	v_fmac_f32_e32 v98, 0x3377d1cf, v91
	v_fmac_f32_e32 v98, 0x3f317217, v91
	v_cmp_lt_f32_e64 s[0:1], |v91|, s66
	v_mul_f32_e32 v93, 0xbfb8aa3b, v93
	v_mul_f32_e32 v88, 0xbfb8aa3b, v88
	v_cndmask_b32_e64 v91, v91, v98, s[0:1]
	v_cndmask_b32_e32 v98, 0, v179, vcc
	v_sub_f32_e32 v91, v91, v98
	v_sub_f32_e32 v91, -0.5, v91
	v_mul_f32_e32 v91, 0x3fb8aa3b, v91
	v_exp_f32_e32 v91, v91
	v_mul_f32_e32 v89, 0xbfb8aa3b, v89
	v_exp_f32_e32 v92, v92
	v_exp_f32_e32 v93, v93
	v_mul_f32_e32 v94, 0xbfb8aa3b, v94
	v_mul_f32_e32 v95, 0xbfb8aa3b, v95
	v_exp_f32_e32 v88, v88
	v_exp_f32_e32 v89, v89
	v_mul_f32_e32 v90, 0xbfb8aa3b, v90
	v_exp_f32_e32 v94, v94
	v_exp_f32_e32 v95, v95
	v_exp_f32_e32 v98, v90
	v_mul_f32_e32 v90, 0xbfb8aa3b, v91
	v_exp_f32_e32 v99, v90
	s_mov_b64 s[0:1], 0x80000
	v_cvt_pk_f16_f32 v90, v92, v93
	v_cvt_pk_f16_f32 v92, v88, v89
	v_lshl_add_u64 v[88:89], v[120:121], 0, s[0:1]
	s_mov_b32 s0, 0x80000
	v_cvt_pk_f16_f32 v91, v94, v95
	v_add_co_u32_e32 v94, vcc, s0, v120
	v_cvt_pk_f16_f32 v93, v98, v99
	s_nop 0
	v_addc_co_u32_e32 v95, vcc, 0, v121, vcc
	global_store_dwordx4 v[94:95], v[90:93], off sc1
	v_add_f32_e32 v84, v84, v132
	v_mul_f32_e32 v84, 0xbfb8aa3b, v84
	v_exp_f32_e32 v84, v84
	v_add_f32_e32 v85, v85, v133
	v_mul_f32_e32 v85, 0xbfb8aa3b, v85
	v_exp_f32_e32 v85, v85
	v_add_f32_e32 v84, 1.0, v84
	v_cmp_gt_f32_e32 vcc, s65, v84
	v_add_f32_e32 v86, v86, v134
	v_add_f32_e32 v85, 1.0, v85
	v_cndmask_b32_e64 v90, 0, 32, vcc
	v_ldexp_f32 v84, v84, v90
	v_log_f32_e32 v84, v84
	v_mul_f32_e32 v86, 0xbfb8aa3b, v86
	v_exp_f32_e32 v86, v86
	v_add_f32_e32 v87, v87, v135
	v_mul_f32_e32 v90, 0x3f317217, v84
	v_fma_f32 v90, v84, s61, -v90
	v_fmac_f32_e32 v90, 0x3377d1cf, v84
	v_fmac_f32_e32 v90, 0x3f317217, v84
	v_cmp_lt_f32_e64 s[0:1], |v84|, s66
	v_add_f32_e32 v86, 1.0, v86
	v_mul_f32_e32 v87, 0xbfb8aa3b, v87
	v_cndmask_b32_e64 v84, v84, v90, s[0:1]
	v_cndmask_b32_e32 v90, 0, v179, vcc
	v_cmp_gt_f32_e32 vcc, s65, v85
	v_sub_f32_e32 v84, v84, v90
	v_exp_f32_e32 v87, v87
	v_cndmask_b32_e64 v90, 0, 32, vcc
	v_ldexp_f32 v85, v85, v90
	v_log_f32_e32 v85, v85
	v_add_f32_e32 v87, 1.0, v87
	v_add_f32_e32 v80, v80, v128
	v_mul_f32_e32 v80, 0xbfb8aa3b, v80
	v_mul_f32_e32 v90, 0x3f317217, v85
	v_fma_f32 v90, v85, s61, -v90
	v_fmac_f32_e32 v90, 0x3377d1cf, v85
	v_fmac_f32_e32 v90, 0x3f317217, v85
	v_cmp_lt_f32_e64 s[0:1], |v85|, s66
	v_exp_f32_e32 v80, v80
	v_add_f32_e32 v81, v81, v129
	v_cndmask_b32_e64 v85, v85, v90, s[0:1]
	v_cndmask_b32_e32 v90, 0, v179, vcc
	v_cmp_gt_f32_e32 vcc, s65, v86
	v_sub_f32_e32 v85, v85, v90
	v_add_f32_e32 v80, 1.0, v80
	v_cndmask_b32_e64 v90, 0, 32, vcc
	v_ldexp_f32 v86, v86, v90
	v_log_f32_e32 v86, v86
	v_mul_f32_e32 v81, 0xbfb8aa3b, v81
	v_exp_f32_e32 v81, v81
	v_add_f32_e32 v82, v82, v130
	v_mul_f32_e32 v90, 0x3f317217, v86
	v_fma_f32 v90, v86, s61, -v90
	v_fmac_f32_e32 v90, 0x3377d1cf, v86
	v_fmac_f32_e32 v90, 0x3f317217, v86
	v_cmp_lt_f32_e64 s[0:1], |v86|, s66
	v_add_f32_e32 v81, 1.0, v81
	v_mul_f32_e32 v82, 0xbfb8aa3b, v82
	v_cndmask_b32_e64 v86, v86, v90, s[0:1]
	v_cndmask_b32_e32 v90, 0, v179, vcc
	v_cmp_gt_f32_e32 vcc, s65, v87
	v_sub_f32_e32 v86, v86, v90
	v_exp_f32_e32 v82, v82
	v_cndmask_b32_e64 v90, 0, 32, vcc
	v_ldexp_f32 v87, v87, v90
	v_log_f32_e32 v87, v87
	v_add_f32_e32 v82, 1.0, v82
	v_add_f32_e32 v83, v83, v131
	v_mul_f32_e32 v83, 0xbfb8aa3b, v83
	v_mul_f32_e32 v90, 0x3f317217, v87
	v_fma_f32 v90, v87, s61, -v90
	v_fmac_f32_e32 v90, 0x3377d1cf, v87
	v_fmac_f32_e32 v90, 0x3f317217, v87
	v_cmp_lt_f32_e64 s[0:1], |v87|, s66
	v_exp_f32_e32 v83, v83
	v_sub_f32_e32 v84, -0.5, v84
	v_cndmask_b32_e64 v87, v87, v90, s[0:1]
	v_cndmask_b32_e32 v90, 0, v179, vcc
	v_cmp_gt_f32_e32 vcc, s65, v80
	v_sub_f32_e32 v87, v87, v90
	v_add_f32_e32 v83, 1.0, v83
	v_cndmask_b32_e64 v90, 0, 32, vcc
	v_ldexp_f32 v80, v80, v90
	v_log_f32_e32 v80, v80
	v_sub_f32_e32 v85, -0.5, v85
	v_mul_f32_e32 v84, 0x3fb8aa3b, v84
;     template <int MODE> __device__ __forceinline__ void run(AccRef acc, const Unit& u, int wr, int wc, int fr, int fq) const {
;     ...
;                     if (MODE == 0) {
; #pragma unroll
;                         for (int e = 0; e < 8; ++e) { const float sp = __logf(1.f + __expf(-x[e])); x[e] = __expf(-__expf(-sp - 0.5f)); }
;                         w.x = pkh(x[0], x[1]); w.y = pkh(x[2], x[3]); w.z = pkh(x[4], x[5]); w.w = pkh(x[6], x[7]);
;                         *(u32x4*)(WA + (size_t)row * 2048 + seg * 512 + cc) = w;
	v_mul_f32_e32 v85, 0x3fb8aa3b, v85
	v_mul_f32_e32 v90, 0x3f317217, v80
	v_fma_f32 v90, v80, s61, -v90
	v_fmac_f32_e32 v90, 0x3377d1cf, v80
	v_fmac_f32_e32 v90, 0x3f317217, v80
	v_cmp_lt_f32_e64 s[0:1], |v80|, s66
	v_sub_f32_e32 v86, -0.5, v86
	v_sub_f32_e32 v87, -0.5, v87
	v_cndmask_b32_e64 v80, v80, v90, s[0:1]
	v_cndmask_b32_e32 v90, 0, v179, vcc
	v_cmp_gt_f32_e32 vcc, s65, v81
	v_sub_f32_e32 v80, v80, v90
	v_sub_f32_e32 v80, -0.5, v80
	v_cndmask_b32_e64 v90, 0, 32, vcc
	v_ldexp_f32 v81, v81, v90
	v_log_f32_e32 v81, v81
	v_mul_f32_e32 v80, 0x3fb8aa3b, v80
	v_exp_f32_e32 v84, v84
	v_exp_f32_e32 v85, v85
	v_mul_f32_e32 v90, 0x3f317217, v81
	v_fma_f32 v90, v81, s61, -v90
	v_fmac_f32_e32 v90, 0x3377d1cf, v81
	v_fmac_f32_e32 v90, 0x3f317217, v81
	v_cmp_lt_f32_e64 s[0:1], |v81|, s66
	v_mul_f32_e32 v86, 0x3fb8aa3b, v86
	v_mul_f32_e32 v87, 0x3fb8aa3b, v87
	v_cndmask_b32_e64 v81, v81, v90, s[0:1]
	v_cndmask_b32_e32 v90, 0, v179, vcc
	v_cmp_gt_f32_e32 vcc, s65, v82
	v_sub_f32_e32 v81, v81, v90
	v_sub_f32_e32 v81, -0.5, v81
	v_cndmask_b32_e64 v90, 0, 32, vcc
	v_ldexp_f32 v82, v82, v90
	v_log_f32_e32 v82, v82
	v_mul_f32_e32 v81, 0x3fb8aa3b, v81
	v_exp_f32_e32 v80, v80
	v_exp_f32_e32 v81, v81
	v_mul_f32_e32 v90, 0x3f317217, v82
	v_fma_f32 v90, v82, s61, -v90
	v_fmac_f32_e32 v90, 0x3377d1cf, v82
	v_fmac_f32_e32 v90, 0x3f317217, v82
	v_cmp_lt_f32_e64 s[0:1], |v82|, s66
	v_exp_f32_e32 v86, v86
	v_exp_f32_e32 v87, v87
	v_cndmask_b32_e64 v82, v82, v90, s[0:1]
	v_cndmask_b32_e32 v90, 0, v179, vcc
	v_cmp_gt_f32_e32 vcc, s65, v83
	v_sub_f32_e32 v82, v82, v90
	v_sub_f32_e32 v82, -0.5, v82
	v_cndmask_b32_e64 v90, 0, 32, vcc
	v_ldexp_f32 v83, v83, v90
	v_log_f32_e32 v83, v83
	v_mul_f32_e32 v82, 0x3fb8aa3b, v82
	v_exp_f32_e32 v82, v82
	v_mul_f32_e32 v84, 0xbfb8aa3b, v84
	v_mul_f32_e32 v90, 0x3f317217, v83
	v_fma_f32 v90, v83, s61, -v90
	v_fmac_f32_e32 v90, 0x3377d1cf, v83
	v_fmac_f32_e32 v90, 0x3f317217, v83
	v_cmp_lt_f32_e64 s[0:1], |v83|, s66
	v_mul_f32_e32 v85, 0xbfb8aa3b, v85
	v_mul_f32_e32 v80, 0xbfb8aa3b, v80
	v_cndmask_b32_e64 v83, v83, v90, s[0:1]
	v_cndmask_b32_e32 v90, 0, v179, vcc
	v_sub_f32_e32 v83, v83, v90
	v_sub_f32_e32 v83, -0.5, v83
	v_mul_f32_e32 v83, 0x3fb8aa3b, v83
	v_exp_f32_e32 v83, v83
	v_mul_f32_e32 v81, 0xbfb8aa3b, v81
	v_exp_f32_e32 v84, v84
	v_exp_f32_e32 v85, v85
	v_mul_f32_e32 v86, 0xbfb8aa3b, v86
	v_mul_f32_e32 v87, 0xbfb8aa3b, v87
	v_exp_f32_e32 v80, v80
	v_exp_f32_e32 v81, v81
	v_mul_f32_e32 v82, 0xbfb8aa3b, v82
	v_exp_f32_e32 v86, v86
	v_exp_f32_e32 v87, v87
	v_exp_f32_e32 v90, v82
	v_mul_f32_e32 v82, 0xbfb8aa3b, v83
	v_exp_f32_e32 v91, v82
	s_mov_b64 s[0:1], 0x90000
	v_cvt_pk_f16_f32 v82, v84, v85
	v_cvt_pk_f16_f32 v84, v80, v81
	v_lshl_add_u64 v[80:81], v[120:121], 0, s[0:1]
	s_mov_b32 s0, 0x90000
	v_cvt_pk_f16_f32 v83, v86, v87
	v_add_co_u32_e32 v86, vcc, s0, v120
	v_cvt_pk_f16_f32 v85, v90, v91
	s_nop 0
	v_addc_co_u32_e32 v87, vcc, 0, v121, vcc
	global_store_dwordx4 v[86:87], v[82:85], off sc1
	v_add_f32_e32 v76, v76, v132
	v_mul_f32_e32 v76, 0xbfb8aa3b, v76
	v_exp_f32_e32 v76, v76
	v_add_f32_e32 v77, v77, v133
	v_mul_f32_e32 v77, 0xbfb8aa3b, v77
	v_exp_f32_e32 v77, v77
	v_add_f32_e32 v76, 1.0, v76
	v_cmp_gt_f32_e32 vcc, s65, v76
	v_add_f32_e32 v78, v78, v134
	v_add_f32_e32 v77, 1.0, v77
	v_cndmask_b32_e64 v82, 0, 32, vcc
	v_ldexp_f32 v76, v76, v82
	v_log_f32_e32 v76, v76
	v_mul_f32_e32 v78, 0xbfb8aa3b, v78
	v_exp_f32_e32 v78, v78
	v_add_f32_e32 v79, v79, v135
	v_mul_f32_e32 v82, 0x3f317217, v76
	v_fma_f32 v82, v76, s61, -v82
	v_fmac_f32_e32 v82, 0x3377d1cf, v76
	v_fmac_f32_e32 v82, 0x3f317217, v76
	v_cmp_lt_f32_e64 s[0:1], |v76|, s66
	v_add_f32_e32 v78, 1.0, v78
	v_mul_f32_e32 v79, 0xbfb8aa3b, v79
	v_cndmask_b32_e64 v76, v76, v82, s[0:1]
	v_cndmask_b32_e32 v82, 0, v179, vcc
	v_cmp_gt_f32_e32 vcc, s65, v77
	v_sub_f32_e32 v76, v76, v82
	v_exp_f32_e32 v79, v79
	v_cndmask_b32_e64 v82, 0, 32, vcc
	v_ldexp_f32 v77, v77, v82
	v_log_f32_e32 v77, v77
	v_add_f32_e32 v79, 1.0, v79
	v_add_f32_e32 v72, v72, v128
	v_mul_f32_e32 v72, 0xbfb8aa3b, v72
	v_mul_f32_e32 v82, 0x3f317217, v77
	v_fma_f32 v82, v77, s61, -v82
	v_fmac_f32_e32 v82, 0x3377d1cf, v77
	v_fmac_f32_e32 v82, 0x3f317217, v77
	v_cmp_lt_f32_e64 s[0:1], |v77|, s66
	v_exp_f32_e32 v72, v72
	v_add_f32_e32 v73, v73, v129
	v_cndmask_b32_e64 v77, v77, v82, s[0:1]
	v_cndmask_b32_e32 v82, 0, v179, vcc
	v_cmp_gt_f32_e32 vcc, s65, v78
	v_sub_f32_e32 v77, v77, v82
	v_add_f32_e32 v72, 1.0, v72
	v_cndmask_b32_e64 v82, 0, 32, vcc
	v_ldexp_f32 v78, v78, v82
	v_log_f32_e32 v78, v78
	v_mul_f32_e32 v73, 0xbfb8aa3b, v73
	v_exp_f32_e32 v73, v73
	v_add_f32_e32 v74, v74, v130
	v_mul_f32_e32 v82, 0x3f317217, v78
	v_fma_f32 v82, v78, s61, -v82
	v_fmac_f32_e32 v82, 0x3377d1cf, v78
	v_fmac_f32_e32 v82, 0x3f317217, v78
	v_cmp_lt_f32_e64 s[0:1], |v78|, s66
	v_add_f32_e32 v73, 1.0, v73
	v_mul_f32_e32 v74, 0xbfb8aa3b, v74
	v_cndmask_b32_e64 v78, v78, v82, s[0:1]
	v_cndmask_b32_e32 v82, 0, v179, vcc
	v_cmp_gt_f32_e32 vcc, s65, v79
	v_sub_f32_e32 v78, v78, v82
	v_exp_f32_e32 v74, v74
	v_cndmask_b32_e64 v82, 0, 32, vcc
	v_ldexp_f32 v79, v79, v82
	v_log_f32_e32 v79, v79
	v_add_f32_e32 v74, 1.0, v74
	v_add_f32_e32 v75, v75, v131
	v_mul_f32_e32 v75, 0xbfb8aa3b, v75
	v_mul_f32_e32 v82, 0x3f317217, v79
	v_fma_f32 v82, v79, s61, -v82
	v_fmac_f32_e32 v82, 0x3377d1cf, v79
	v_fmac_f32_e32 v82, 0x3f317217, v79
	v_cmp_lt_f32_e64 s[0:1], |v79|, s66
	v_exp_f32_e32 v75, v75
	v_sub_f32_e32 v78, -0.5, v78
	v_cndmask_b32_e64 v79, v79, v82, s[0:1]
	v_cndmask_b32_e32 v82, 0, v179, vcc
	v_cmp_gt_f32_e32 vcc, s65, v72
	v_sub_f32_e32 v79, v79, v82
	v_add_f32_e32 v75, 1.0, v75
	v_cndmask_b32_e64 v82, 0, 32, vcc
	v_ldexp_f32 v72, v72, v82
;     template <int MODE> __device__ __forceinline__ void run(AccRef acc, const Unit& u, int wr, int wc, int fr, int fq) const {
;     ...
;                     if (MODE == 0) {
; #pragma unroll
;                         for (int e = 0; e < 8; ++e) { const float sp = __logf(1.f + __expf(-x[e])); x[e] = __expf(-__expf(-sp - 0.5f)); }
;                         w.x = pkh(x[0], x[1]); w.y = pkh(x[2], x[3]); w.z = pkh(x[4], x[5]); w.w = pkh(x[6], x[7]);
;                         *(u32x4*)(WA + (size_t)row * 2048 + seg * 512 + cc) = w;
	v_log_f32_e32 v72, v72
	v_sub_f32_e32 v79, -0.5, v79
	v_sub_f32_e32 v76, -0.5, v76
	v_sub_f32_e32 v77, -0.5, v77
	v_mul_f32_e32 v82, 0x3f317217, v72
	v_fma_f32 v82, v72, s61, -v82
	v_fmac_f32_e32 v82, 0x3377d1cf, v72
	v_fmac_f32_e32 v82, 0x3f317217, v72
	v_cmp_lt_f32_e64 s[0:1], |v72|, s66
	v_mul_f32_e32 v78, 0x3fb8aa3b, v78
	v_mul_f32_e32 v79, 0x3fb8aa3b, v79
	v_cndmask_b32_e64 v72, v72, v82, s[0:1]
	v_cndmask_b32_e32 v82, 0, v179, vcc
	v_cmp_gt_f32_e32 vcc, s65, v73
	v_sub_f32_e32 v72, v72, v82
	v_sub_f32_e32 v72, -0.5, v72
	v_cndmask_b32_e64 v82, 0, 32, vcc
	v_ldexp_f32 v73, v73, v82
	v_log_f32_e32 v73, v73
	v_mul_f32_e32 v76, 0x3fb8aa3b, v76
	v_mul_f32_e32 v77, 0x3fb8aa3b, v77
	v_exp_f32_e32 v78, v78
	v_mul_f32_e32 v82, 0x3f317217, v73
	v_fma_f32 v82, v73, s61, -v82
	v_fmac_f32_e32 v82, 0x3377d1cf, v73
	v_fmac_f32_e32 v82, 0x3f317217, v73
	v_cmp_lt_f32_e64 s[0:1], |v73|, s66
	v_exp_f32_e32 v79, v79
	v_mul_f32_e32 v72, 0x3fb8aa3b, v72
	v_cndmask_b32_e64 v73, v73, v82, s[0:1]
	v_cndmask_b32_e32 v82, 0, v179, vcc
	v_cmp_gt_f32_e32 vcc, s65, v74
	v_sub_f32_e32 v73, v73, v82
	v_sub_f32_e32 v73, -0.5, v73
	v_cndmask_b32_e64 v82, 0, 32, vcc
	v_ldexp_f32 v74, v74, v82
	v_log_f32_e32 v74, v74
	v_mul_f32_e32 v73, 0x3fb8aa3b, v73
	v_exp_f32_e32 v76, v76
	v_exp_f32_e32 v77, v77
	v_mul_f32_e32 v82, 0x3f317217, v74
	v_fma_f32 v82, v74, s61, -v82
	v_fmac_f32_e32 v82, 0x3377d1cf, v74
	v_fmac_f32_e32 v82, 0x3f317217, v74
	v_cmp_lt_f32_e64 s[0:1], |v74|, s66
	v_exp_f32_e32 v72, v72
	v_exp_f32_e32 v73, v73
	v_cndmask_b32_e64 v74, v74, v82, s[0:1]
	v_cndmask_b32_e32 v82, 0, v179, vcc
	v_cmp_gt_f32_e32 vcc, s65, v75
	v_sub_f32_e32 v74, v74, v82
	v_sub_f32_e32 v74, -0.5, v74
	v_cndmask_b32_e64 v82, 0, 32, vcc
	v_ldexp_f32 v75, v75, v82
	v_log_f32_e32 v75, v75
	v_mul_f32_e32 v74, 0x3fb8aa3b, v74
	v_exp_f32_e32 v74, v74
	v_mul_f32_e32 v78, 0xbfb8aa3b, v78
	v_mul_f32_e32 v82, 0x3f317217, v75
	v_fma_f32 v82, v75, s61, -v82
	v_fmac_f32_e32 v82, 0x3377d1cf, v75
	v_fmac_f32_e32 v82, 0x3f317217, v75
	v_cmp_lt_f32_e64 s[0:1], |v75|, s66
	v_mul_f32_e32 v79, 0xbfb8aa3b, v79
	v_mul_f32_e32 v74, 0xbfb8aa3b, v74
	v_cndmask_b32_e64 v75, v75, v82, s[0:1]
	v_cndmask_b32_e32 v82, 0, v179, vcc
	v_sub_f32_e32 v75, v75, v82
	v_sub_f32_e32 v75, -0.5, v75
	v_mul_f32_e32 v75, 0x3fb8aa3b, v75
	v_exp_f32_e32 v75, v75
	v_mul_f32_e32 v76, 0xbfb8aa3b, v76
	v_mul_f32_e32 v77, 0xbfb8aa3b, v77
	v_exp_f32_e32 v78, v78
	v_exp_f32_e32 v79, v79
	v_mul_f32_e32 v72, 0xbfb8aa3b, v72
	v_mul_f32_e32 v73, 0xbfb8aa3b, v73
	v_exp_f32_e32 v82, v74
	v_mul_f32_e32 v74, 0xbfb8aa3b, v75
	v_exp_f32_e32 v76, v76
	v_exp_f32_e32 v77, v77
	v_exp_f32_e32 v72, v72
	v_exp_f32_e32 v73, v73
	v_exp_f32_e32 v83, v74
	v_cvt_pk_f16_f32 v75, v78, v79
	v_add_co_u32_e32 v78, vcc, s71, v120
	v_cvt_pk_f16_f32 v74, v76, v77
	v_cvt_pk_f16_f32 v76, v72, v73
	v_cvt_pk_f16_f32 v77, v82, v83
	s_mov_b64 s[0:1], 0xa0000
	v_addc_co_u32_e32 v79, vcc, 0, v121, vcc
	v_lshl_add_u64 v[72:73], v[120:121], 0, s[0:1]
	global_store_dwordx4 v[78:79], v[74:77], off sc1
	v_add_f32_e32 v68, v68, v132
	v_mul_f32_e32 v68, 0xbfb8aa3b, v68
	v_exp_f32_e32 v68, v68
	v_add_f32_e32 v69, v69, v133
	v_mul_f32_e32 v69, 0xbfb8aa3b, v69
	v_exp_f32_e32 v69, v69
	v_add_f32_e32 v68, 1.0, v68
	v_cmp_gt_f32_e32 vcc, s65, v68
	v_add_f32_e32 v70, v70, v134
	v_add_f32_e32 v69, 1.0, v69
	v_cndmask_b32_e64 v74, 0, 32, vcc
	v_ldexp_f32 v68, v68, v74
	v_log_f32_e32 v68, v68
	v_mul_f32_e32 v70, 0xbfb8aa3b, v70
	v_exp_f32_e32 v70, v70
	v_add_f32_e32 v71, v71, v135
	v_mul_f32_e32 v74, 0x3f317217, v68
	v_fma_f32 v74, v68, s61, -v74
	v_fmac_f32_e32 v74, 0x3377d1cf, v68
	v_fmac_f32_e32 v74, 0x3f317217, v68
	v_cmp_lt_f32_e64 s[0:1], |v68|, s66
	v_add_f32_e32 v70, 1.0, v70
	v_mul_f32_e32 v71, 0xbfb8aa3b, v71
	v_cndmask_b32_e64 v68, v68, v74, s[0:1]
	v_cndmask_b32_e32 v74, 0, v179, vcc
	v_cmp_gt_f32_e32 vcc, s65, v69
	v_sub_f32_e32 v68, v68, v74
	v_exp_f32_e32 v71, v71
	v_cndmask_b32_e64 v74, 0, 32, vcc
	v_ldexp_f32 v69, v69, v74
	v_log_f32_e32 v69, v69
	v_add_f32_e32 v71, 1.0, v71
	v_add_f32_e32 v64, v64, v128
	v_mul_f32_e32 v64, 0xbfb8aa3b, v64
	v_mul_f32_e32 v74, 0x3f317217, v69
	v_fma_f32 v74, v69, s61, -v74
	v_fmac_f32_e32 v74, 0x3377d1cf, v69
	v_fmac_f32_e32 v74, 0x3f317217, v69
	v_cmp_lt_f32_e64 s[0:1], |v69|, s66
	v_exp_f32_e32 v64, v64
	v_add_f32_e32 v65, v65, v129
	v_cndmask_b32_e64 v69, v69, v74, s[0:1]
	v_cndmask_b32_e32 v74, 0, v179, vcc
	v_cmp_gt_f32_e32 vcc, s65, v70
	v_sub_f32_e32 v69, v69, v74
	v_add_f32_e32 v64, 1.0, v64
	v_cndmask_b32_e64 v74, 0, 32, vcc
	v_ldexp_f32 v70, v70, v74
	v_log_f32_e32 v70, v70
	v_mul_f32_e32 v65, 0xbfb8aa3b, v65
	v_exp_f32_e32 v65, v65
	v_add_f32_e32 v66, v66, v130
	v_mul_f32_e32 v74, 0x3f317217, v70
	v_fma_f32 v74, v70, s61, -v74
	v_fmac_f32_e32 v74, 0x3377d1cf, v70
	v_fmac_f32_e32 v74, 0x3f317217, v70
	v_cmp_lt_f32_e64 s[0:1], |v70|, s66
	v_add_f32_e32 v65, 1.0, v65
	v_mul_f32_e32 v66, 0xbfb8aa3b, v66
	v_cndmask_b32_e64 v70, v70, v74, s[0:1]
	v_cndmask_b32_e32 v74, 0, v179, vcc
	v_cmp_gt_f32_e32 vcc, s65, v71
	v_sub_f32_e32 v70, v70, v74
	v_exp_f32_e32 v66, v66
	v_cndmask_b32_e64 v74, 0, 32, vcc
	v_ldexp_f32 v71, v71, v74
	v_log_f32_e32 v71, v71
	v_add_f32_e32 v66, 1.0, v66
	v_add_f32_e32 v67, v67, v131
	v_mul_f32_e32 v67, 0xbfb8aa3b, v67
	v_mul_f32_e32 v74, 0x3f317217, v71
	v_fma_f32 v74, v71, s61, -v74
	v_fmac_f32_e32 v74, 0x3377d1cf, v71
	v_fmac_f32_e32 v74, 0x3f317217, v71
	v_cmp_lt_f32_e64 s[0:1], |v71|, s66
	v_exp_f32_e32 v67, v67
	v_sub_f32_e32 v68, -0.5, v68
	v_cndmask_b32_e64 v71, v71, v74, s[0:1]
	v_cndmask_b32_e32 v74, 0, v179, vcc
	v_cmp_gt_f32_e32 vcc, s65, v64
	v_sub_f32_e32 v71, v71, v74
	v_sub_f32_e32 v69, -0.5, v69
;     template <int MODE> __device__ __forceinline__ void run(AccRef acc, const Unit& u, int wr, int wc, int fr, int fq) const {
;     ...
;             if (MODE < 2) { const float* bp = (MODE == 0 ? w0 + seg * 512 : a0 + (seg - 2) * 512) + cc; const f32x4 b0 = *(const f32x4*)bp, b1 = *(const f32x4*)(bp + 4);
;                 bias[0] = b0[0]; bias[1] = b0[1]; bias[2] = b0[2]; bias[3] = b0[3]; bias[4] = b1[0]; bias[5] = b1[1]; bias[6] = b1[2]; bias[7] = b1[3]; }
;     ...
;                     if (MODE == 0) {
; #pragma unroll
;                         for (int e = 0; e < 8; ++e) { const float sp = __logf(1.f + __expf(-x[e])); x[e] = __expf(-__expf(-sp - 0.5f)); }
;                         w.x = pkh(x[0], x[1]); w.y = pkh(x[2], x[3]); w.z = pkh(x[4], x[5]); w.w = pkh(x[6], x[7]);
;                         *(u32x4*)(WA + (size_t)row * 2048 + seg * 512 + cc) = w;
	v_cndmask_b32_e64 v74, 0, 32, vcc
	v_ldexp_f32 v64, v64, v74
	v_log_f32_e32 v64, v64
	v_mul_f32_e32 v68, 0x3fb8aa3b, v68
	v_mul_f32_e32 v69, 0x3fb8aa3b, v69
	v_sub_f32_e32 v70, -0.5, v70
	v_mul_f32_e32 v74, 0x3f317217, v64
	v_fma_f32 v74, v64, s61, -v74
	v_fmac_f32_e32 v74, 0x3377d1cf, v64
	v_fmac_f32_e32 v74, 0x3f317217, v64
	v_cmp_lt_f32_e64 s[0:1], |v64|, s66
	v_sub_f32_e32 v71, -0.5, v71
	v_exp_f32_e32 v68, v68
	v_cndmask_b32_e64 v64, v64, v74, s[0:1]
	v_cndmask_b32_e32 v74, 0, v179, vcc
	v_cmp_gt_f32_e32 vcc, s65, v65
	v_sub_f32_e32 v64, v64, v74
	v_sub_f32_e32 v64, -0.5, v64
	v_cndmask_b32_e64 v74, 0, 32, vcc
	v_ldexp_f32 v65, v65, v74
	v_log_f32_e32 v65, v65
	v_mul_f32_e32 v64, 0x3fb8aa3b, v64
	v_exp_f32_e32 v64, v64
	v_exp_f32_e32 v69, v69
	v_mul_f32_e32 v74, 0x3f317217, v65
	v_fma_f32 v74, v65, s61, -v74
	v_fmac_f32_e32 v74, 0x3377d1cf, v65
	v_fmac_f32_e32 v74, 0x3f317217, v65
	v_cmp_lt_f32_e64 s[0:1], |v65|, s66
	v_mul_f32_e32 v64, 0xbfb8aa3b, v64
	v_mul_f32_e32 v70, 0x3fb8aa3b, v70
	v_cndmask_b32_e64 v65, v65, v74, s[0:1]
	v_cndmask_b32_e32 v74, 0, v179, vcc
	v_sub_f32_e32 v65, v65, v74
	v_cmp_gt_f32_e32 vcc, s65, v66
	v_sub_f32_e32 v65, -0.5, v65
	v_mul_f32_e32 v65, 0x3fb8aa3b, v65
	v_cndmask_b32_e64 v74, 0, 32, vcc
	v_ldexp_f32 v66, v66, v74
	v_exp_f32_e32 v65, v65
	v_log_f32_e32 v66, v66
	v_exp_f32_e32 v74, v64
	v_mul_f32_e32 v71, 0x3fb8aa3b, v71
	v_mul_f32_e32 v64, 0xbfb8aa3b, v65
	v_mul_f32_e32 v65, 0x3f317217, v66
	v_fma_f32 v65, v66, s61, -v65
	v_fmac_f32_e32 v65, 0x3377d1cf, v66
	v_fmac_f32_e32 v65, 0x3f317217, v66
	v_cmp_lt_f32_e64 s[0:1], |v66|, s66
	v_exp_f32_e32 v70, v70
	v_exp_f32_e32 v71, v71
	v_cndmask_b32_e64 v65, v66, v65, s[0:1]
	v_cndmask_b32_e32 v66, 0, v179, vcc
	v_sub_f32_e32 v65, v65, v66
	v_add_f32_e32 v66, 1.0, v67
	v_cmp_gt_f32_e32 vcc, s65, v66
	v_sub_f32_e32 v65, -0.5, v65
	v_mul_f32_e32 v65, 0x3fb8aa3b, v65
	v_cndmask_b32_e64 v67, 0, 32, vcc
	v_ldexp_f32 v66, v66, v67
	v_log_f32_e32 v66, v66
	v_exp_f32_e32 v65, v65
	v_mul_f32_e32 v68, 0xbfb8aa3b, v68
	v_mul_f32_e32 v69, 0xbfb8aa3b, v69
	v_mul_f32_e32 v67, 0x3f317217, v66
	v_fma_f32 v67, v66, s61, -v67
	v_fmac_f32_e32 v67, 0x3377d1cf, v66
	v_fmac_f32_e32 v67, 0x3f317217, v66
	v_cmp_lt_f32_e64 s[0:1], |v66|, s66
	v_exp_f32_e32 v68, v68
	v_exp_f32_e32 v69, v69
	v_cndmask_b32_e64 v66, v66, v67, s[0:1]
	v_cndmask_b32_e32 v67, 0, v179, vcc
	v_sub_f32_e32 v66, v66, v67
	v_sub_f32_e32 v66, -0.5, v66
	v_mul_f32_e32 v66, 0x3fb8aa3b, v66
	v_exp_f32_e32 v66, v66
	v_exp_f32_e32 v67, v64
	v_mul_f32_e32 v64, 0xbfb8aa3b, v65
	v_mul_f32_e32 v70, 0xbfb8aa3b, v70
	v_mul_f32_e32 v71, 0xbfb8aa3b, v71
	v_exp_f32_e32 v75, v64
	v_mul_f32_e32 v64, 0xbfb8aa3b, v66
	v_exp_f32_e32 v70, v70
	v_exp_f32_e32 v71, v71
	v_exp_f32_e32 v76, v64
	v_cvt_pk_f16_f32 v64, v68, v69
	v_add_co_u32_e32 v68, vcc, s64, v120
	v_cvt_pk_f16_f32 v65, v70, v71
	v_cvt_pk_f16_f32 v66, v74, v67
	v_cvt_pk_f16_f32 v67, v75, v76
	s_mov_b64 s[0:1], 0xb0000
	v_addc_co_u32_e32 v69, vcc, 0, v121, vcc
	v_lshl_add_u64 v[74:75], v[120:121], 0, s[0:1]
	global_store_dwordx4 v[68:69], v[64:67], off sc1
	global_load_dwordx4 v[64:67], v[136:137], off offset:528
	global_load_dwordx4 v[68:71], v[136:137], off offset:512
	s_waitcnt vmcnt(0)
	v_add_f32_e32 v77, v56, v64
	v_add_f32_e32 v76, v60, v68
	v_mul_f32_e32 v56, 0xbfb8aa3b, v76
	v_exp_f32_e32 v56, v56
	v_add_f32_e32 v60, v58, v66
	v_add_f32_e32 v61, v61, v69
	v_add_f32_e32 v78, v57, v65
	v_add_f32_e32 v56, 1.0, v56
	v_cmp_gt_f32_e32 vcc, s65, v56
	v_add_f32_e32 v57, v59, v67
	v_add_f32_e32 v62, v62, v70
	v_cndmask_b32_e64 v58, 0, 32, vcc
	v_ldexp_f32 v56, v56, v58
	v_log_f32_e32 v56, v56
	v_add_f32_e32 v63, v63, v71
	v_mul_f32_e32 v60, 0xbfb8aa3b, v60
	v_exp_f32_e32 v60, v60
	v_mul_f32_e32 v58, 0x3f317217, v56
	v_fma_f32 v58, v56, s61, -v58
	v_fmac_f32_e32 v58, 0x3377d1cf, v56
	v_fmac_f32_e32 v58, 0x3f317217, v56
	v_cmp_lt_f32_e64 s[0:1], |v56|, s66
	v_add_f32_e32 v60, 1.0, v60
	v_mul_f32_e32 v57, 0xbfb8aa3b, v57
	v_cndmask_b32_e64 v56, v56, v58, s[0:1]
	v_cndmask_b32_e32 v58, 0, v179, vcc
	v_sub_f32_e32 v56, v56, v58
	v_mul_f32_e32 v58, 0xbfb8aa3b, v61
	v_exp_f32_e32 v58, v58
	v_exp_f32_e32 v57, v57
	v_sub_f32_e32 v56, -0.5, v56
	v_mul_f32_e32 v56, 0x3fb8aa3b, v56
	v_add_f32_e32 v58, 1.0, v58
	v_cmp_gt_f32_e32 vcc, s65, v58
	v_add_f32_e32 v57, 1.0, v57
	v_exp_f32_e32 v56, v56
	v_cndmask_b32_e64 v59, 0, 32, vcc
	v_ldexp_f32 v58, v58, v59
	v_log_f32_e32 v58, v58
	v_mul_f32_e32 v56, 0xbfb8aa3b, v56
	v_exp_f32_e32 v56, v56
	v_mul_f32_e32 v59, 0x3f317217, v58
	v_fma_f32 v59, v58, s61, -v59
	v_fmac_f32_e32 v59, 0x3377d1cf, v58
	v_fmac_f32_e32 v59, 0x3f317217, v58
	v_cmp_lt_f32_e64 s[0:1], |v58|, s66
	s_nop 1
	v_cndmask_b32_e64 v58, v58, v59, s[0:1]
	v_cndmask_b32_e32 v59, 0, v179, vcc
	v_sub_f32_e32 v58, v58, v59
	v_mul_f32_e32 v59, 0xbfb8aa3b, v62
	v_exp_f32_e32 v59, v59
	v_sub_f32_e32 v58, -0.5, v58
	v_mul_f32_e32 v58, 0x3fb8aa3b, v58
	v_exp_f32_e32 v58, v58
	v_add_f32_e32 v59, 1.0, v59
	v_cmp_gt_f32_e32 vcc, s65, v59
	v_mul_f32_e32 v58, 0xbfb8aa3b, v58
	s_nop 0
	v_cndmask_b32_e64 v61, 0, 32, vcc
	v_ldexp_f32 v59, v59, v61
	v_log_f32_e32 v59, v59
	v_exp_f32_e32 v58, v58
	v_mul_f32_e32 v61, 0x3f317217, v59
	v_fma_f32 v61, v59, s61, -v61
	v_fmac_f32_e32 v61, 0x3377d1cf, v59
	v_fmac_f32_e32 v61, 0x3f317217, v59
	v_cmp_lt_f32_e64 s[0:1], |v59|, s66
	v_cvt_pk_f16_f32 v56, v56, v58
	s_nop 0
	v_cndmask_b32_e64 v59, v59, v61, s[0:1]
	v_cndmask_b32_e32 v61, 0, v179, vcc
	v_sub_f32_e32 v59, v59, v61
	v_mul_f32_e32 v61, 0xbfb8aa3b, v63
	v_exp_f32_e32 v61, v61
	v_sub_f32_e32 v59, -0.5, v59
	v_mul_f32_e32 v59, 0x3fb8aa3b, v59
	v_exp_f32_e32 v59, v59
	v_add_f32_e32 v61, 1.0, v61
;     template <int MODE> __device__ __forceinline__ void run(AccRef acc, const Unit& u, int wr, int wc, int fr, int fq) const {
;     ...
;                     if (MODE == 0) {
; #pragma unroll
;                         for (int e = 0; e < 8; ++e) { const float sp = __logf(1.f + __expf(-x[e])); x[e] = __expf(-__expf(-sp - 0.5f)); }
;                         w.x = pkh(x[0], x[1]); w.y = pkh(x[2], x[3]); w.z = pkh(x[4], x[5]); w.w = pkh(x[6], x[7]);
;                         *(u32x4*)(WA + (size_t)row * 2048 + seg * 512 + cc) = w;
	v_cmp_gt_f32_e32 vcc, s65, v61
	v_mul_f32_e32 v59, 0xbfb8aa3b, v59
	s_nop 0
	v_cndmask_b32_e64 v62, 0, 32, vcc
	v_ldexp_f32 v61, v61, v62
	v_log_f32_e32 v61, v61
	v_exp_f32_e32 v59, v59
	v_mul_f32_e32 v62, 0x3f317217, v61
	v_fma_f32 v62, v61, s61, -v62
	v_fmac_f32_e32 v62, 0x3377d1cf, v61
	v_fmac_f32_e32 v62, 0x3f317217, v61
	v_cmp_lt_f32_e64 s[0:1], |v61|, s66
	s_nop 1
	v_cndmask_b32_e64 v61, v61, v62, s[0:1]
	v_cndmask_b32_e32 v62, 0, v179, vcc
	v_sub_f32_e32 v61, v61, v62
	v_mul_f32_e32 v62, 0xbfb8aa3b, v77
	v_exp_f32_e32 v62, v62
	v_sub_f32_e32 v61, -0.5, v61
	v_mul_f32_e32 v61, 0x3fb8aa3b, v61
	v_exp_f32_e32 v61, v61
	v_add_f32_e32 v62, 1.0, v62
	v_cmp_gt_f32_e32 vcc, s65, v62
	v_mul_f32_e32 v61, 0xbfb8aa3b, v61
	s_nop 0
	v_cndmask_b32_e64 v63, 0, 32, vcc
	v_ldexp_f32 v62, v62, v63
	v_log_f32_e32 v62, v62
	v_exp_f32_e32 v61, v61
	v_mul_f32_e32 v63, 0x3f317217, v62
	v_fma_f32 v63, v62, s61, -v63
	v_fmac_f32_e32 v63, 0x3377d1cf, v62
	v_fmac_f32_e32 v63, 0x3f317217, v62
	v_cmp_lt_f32_e64 s[0:1], |v62|, s66
	s_nop 1
	v_cndmask_b32_e64 v62, v62, v63, s[0:1]
	v_cndmask_b32_e32 v63, 0, v179, vcc
	v_sub_f32_e32 v62, v62, v63
	v_mul_f32_e32 v63, 0xbfb8aa3b, v78
	v_exp_f32_e32 v63, v63
	v_sub_f32_e32 v62, -0.5, v62
	v_mul_f32_e32 v62, 0x3fb8aa3b, v62
	v_exp_f32_e32 v62, v62
	v_add_f32_e32 v63, 1.0, v63
	v_cmp_gt_f32_e32 vcc, s65, v63
	v_mul_f32_e32 v62, 0xbfb8aa3b, v62
	s_nop 0
	v_cndmask_b32_e64 v76, 0, 32, vcc
	v_ldexp_f32 v63, v63, v76
	v_log_f32_e32 v63, v63
	v_exp_f32_e32 v62, v62
	v_mul_f32_e32 v76, 0x3f317217, v63
	v_fma_f32 v76, v63, s61, -v76
	v_fmac_f32_e32 v76, 0x3377d1cf, v63
	v_fmac_f32_e32 v76, 0x3f317217, v63
	v_cmp_lt_f32_e64 s[0:1], |v63|, s66
	s_nop 1
	v_cndmask_b32_e64 v63, v63, v76, s[0:1]
	v_cndmask_b32_e32 v76, 0, v179, vcc
	v_cmp_gt_f32_e32 vcc, s65, v60
	v_sub_f32_e32 v63, v63, v76
	v_sub_f32_e32 v63, -0.5, v63
	v_cndmask_b32_e64 v76, 0, 32, vcc
	v_ldexp_f32 v60, v60, v76
	v_log_f32_e32 v60, v60
	v_mul_f32_e32 v63, 0x3fb8aa3b, v63
	v_exp_f32_e32 v63, v63
	v_mul_f32_e32 v76, 0x3f317217, v60
	v_fma_f32 v76, v60, s61, -v76
	v_fmac_f32_e32 v76, 0x3377d1cf, v60
	v_fmac_f32_e32 v76, 0x3f317217, v60
	v_cmp_lt_f32_e64 s[0:1], |v60|, s66
	v_mul_f32_e32 v63, 0xbfb8aa3b, v63
	v_exp_f32_e32 v63, v63
	v_cndmask_b32_e64 v60, v60, v76, s[0:1]
	v_cndmask_b32_e32 v76, 0, v179, vcc
	v_cmp_gt_f32_e32 vcc, s65, v57
	v_sub_f32_e32 v60, v60, v76
	v_sub_f32_e32 v60, -0.5, v60
	v_cndmask_b32_e64 v76, 0, 32, vcc
	v_ldexp_f32 v57, v57, v76
	v_log_f32_e32 v57, v57
	v_mul_f32_e32 v60, 0x3fb8aa3b, v60
	v_exp_f32_e32 v60, v60
	v_cvt_pk_f16_f32 v58, v62, v63
	v_mul_f32_e32 v76, 0x3f317217, v57
	v_fma_f32 v76, v57, s61, -v76
	v_fmac_f32_e32 v76, 0x3377d1cf, v57
	v_fmac_f32_e32 v76, 0x3f317217, v57
	v_cmp_lt_f32_e64 s[0:1], |v57|, s66
	v_mul_f32_e32 v60, 0xbfb8aa3b, v60
	v_exp_f32_e32 v60, v60
	v_cndmask_b32_e64 v57, v57, v76, s[0:1]
	v_cndmask_b32_e32 v76, 0, v179, vcc
	v_sub_f32_e32 v57, v57, v76
	v_sub_f32_e32 v57, -0.5, v57
	v_mul_f32_e32 v57, 0x3fb8aa3b, v57
	v_exp_f32_e32 v57, v57
	s_nop 0
	v_mul_f32_e32 v57, 0xbfb8aa3b, v57
	v_exp_f32_e32 v76, v57
	v_cvt_pk_f16_f32 v57, v59, v61
	v_cvt_pk_f16_f32 v59, v60, v76
	global_store_dwordx4 v[120:121], v[56:59], off offset:256 sc1
	v_add_f32_e32 v52, v52, v68
	v_mul_f32_e32 v52, 0xbfb8aa3b, v52
	v_exp_f32_e32 v52, v52
	v_add_f32_e32 v53, v53, v69
	v_mul_f32_e32 v53, 0xbfb8aa3b, v53
	v_exp_f32_e32 v53, v53
	v_add_f32_e32 v52, 1.0, v52
	v_cmp_gt_f32_e32 vcc, s65, v52
	v_add_f32_e32 v54, v54, v70
	v_add_f32_e32 v53, 1.0, v53
	v_cndmask_b32_e64 v56, 0, 32, vcc
	v_ldexp_f32 v52, v52, v56
	v_log_f32_e32 v52, v52
	v_mul_f32_e32 v54, 0xbfb8aa3b, v54
	v_exp_f32_e32 v54, v54
	v_add_f32_e32 v55, v55, v71
	v_mul_f32_e32 v56, 0x3f317217, v52
	v_fma_f32 v56, v52, s61, -v56
	v_fmac_f32_e32 v56, 0x3377d1cf, v52
	v_fmac_f32_e32 v56, 0x3f317217, v52
	v_cmp_lt_f32_e64 s[0:1], |v52|, s66
	v_add_f32_e32 v54, 1.0, v54
	v_mul_f32_e32 v55, 0xbfb8aa3b, v55
	v_cndmask_b32_e64 v52, v52, v56, s[0:1]
	v_cndmask_b32_e32 v56, 0, v179, vcc
	v_cmp_gt_f32_e32 vcc, s65, v53
	v_sub_f32_e32 v52, v52, v56
	v_exp_f32_e32 v55, v55
	v_cndmask_b32_e64 v56, 0, 32, vcc
	v_ldexp_f32 v53, v53, v56
	v_log_f32_e32 v53, v53
	v_add_f32_e32 v55, 1.0, v55
	v_add_f32_e32 v48, v48, v64
	v_mul_f32_e32 v48, 0xbfb8aa3b, v48
	v_mul_f32_e32 v56, 0x3f317217, v53
	v_fma_f32 v56, v53, s61, -v56
	v_fmac_f32_e32 v56, 0x3377d1cf, v53
	v_fmac_f32_e32 v56, 0x3f317217, v53
	v_cmp_lt_f32_e64 s[0:1], |v53|, s66
	v_exp_f32_e32 v48, v48
	v_add_f32_e32 v49, v49, v65
	v_cndmask_b32_e64 v53, v53, v56, s[0:1]
	v_cndmask_b32_e32 v56, 0, v179, vcc
	v_cmp_gt_f32_e32 vcc, s65, v54
	v_sub_f32_e32 v53, v53, v56
	v_add_f32_e32 v48, 1.0, v48
	v_cndmask_b32_e64 v56, 0, 32, vcc
	v_ldexp_f32 v54, v54, v56
	v_log_f32_e32 v54, v54
	v_mul_f32_e32 v49, 0xbfb8aa3b, v49
	v_exp_f32_e32 v49, v49
	v_add_f32_e32 v50, v50, v66
	v_mul_f32_e32 v56, 0x3f317217, v54
	v_fma_f32 v56, v54, s61, -v56
	v_fmac_f32_e32 v56, 0x3377d1cf, v54
	v_fmac_f32_e32 v56, 0x3f317217, v54
	v_cmp_lt_f32_e64 s[0:1], |v54|, s66
	v_add_f32_e32 v49, 1.0, v49
	v_mul_f32_e32 v50, 0xbfb8aa3b, v50
	v_cndmask_b32_e64 v54, v54, v56, s[0:1]
	v_cndmask_b32_e32 v56, 0, v179, vcc
	v_cmp_gt_f32_e32 vcc, s65, v55
	v_sub_f32_e32 v54, v54, v56
	v_exp_f32_e32 v50, v50
	v_cndmask_b32_e64 v56, 0, 32, vcc
	v_ldexp_f32 v55, v55, v56
	v_log_f32_e32 v55, v55
	v_add_f32_e32 v50, 1.0, v50
	v_add_f32_e32 v51, v51, v67
	v_mul_f32_e32 v51, 0xbfb8aa3b, v51
	v_mul_f32_e32 v56, 0x3f317217, v55
	v_fma_f32 v56, v55, s61, -v56
	v_fmac_f32_e32 v56, 0x3377d1cf, v55
	v_fmac_f32_e32 v56, 0x3f317217, v55
	v_cmp_lt_f32_e64 s[0:1], |v55|, s66
	v_exp_f32_e32 v51, v51
;     template <int MODE> __device__ __forceinline__ void run(AccRef acc, const Unit& u, int wr, int wc, int fr, int fq) const {
;     ...
;                     if (MODE == 0) {
; #pragma unroll
;                         for (int e = 0; e < 8; ++e) { const float sp = __logf(1.f + __expf(-x[e])); x[e] = __expf(-__expf(-sp - 0.5f)); }
;                         w.x = pkh(x[0], x[1]); w.y = pkh(x[2], x[3]); w.z = pkh(x[4], x[5]); w.w = pkh(x[6], x[7]);
;                         *(u32x4*)(WA + (size_t)row * 2048 + seg * 512 + cc) = w;
	v_sub_f32_e32 v52, -0.5, v52
	v_cndmask_b32_e64 v55, v55, v56, s[0:1]
	v_cndmask_b32_e32 v56, 0, v179, vcc
	v_cmp_gt_f32_e32 vcc, s65, v48
	v_sub_f32_e32 v55, v55, v56
	v_sub_f32_e32 v53, -0.5, v53
	v_cndmask_b32_e64 v56, 0, 32, vcc
	v_ldexp_f32 v48, v48, v56
	v_log_f32_e32 v48, v48
	v_sub_f32_e32 v54, -0.5, v54
	v_sub_f32_e32 v55, -0.5, v55
	v_mul_f32_e32 v52, 0x3fb8aa3b, v52
	v_mul_f32_e32 v56, 0x3f317217, v48
	v_fma_f32 v56, v48, s61, -v56
	v_fmac_f32_e32 v56, 0x3377d1cf, v48
	v_fmac_f32_e32 v56, 0x3f317217, v48
	v_cmp_lt_f32_e64 s[0:1], |v48|, s66
	v_mul_f32_e32 v53, 0x3fb8aa3b, v53
	v_mul_f32_e32 v54, 0x3fb8aa3b, v54
	v_cndmask_b32_e64 v48, v48, v56, s[0:1]
	v_cndmask_b32_e32 v56, 0, v179, vcc
	v_cmp_gt_f32_e32 vcc, s65, v49
	v_sub_f32_e32 v48, v48, v56
	v_sub_f32_e32 v48, -0.5, v48
	v_cndmask_b32_e64 v56, 0, 32, vcc
	v_ldexp_f32 v49, v49, v56
	v_log_f32_e32 v49, v49
	v_mul_f32_e32 v48, 0x3fb8aa3b, v48
	v_exp_f32_e32 v48, v48
	v_mul_f32_e32 v55, 0x3fb8aa3b, v55
	v_mul_f32_e32 v56, 0x3f317217, v49
	v_fma_f32 v56, v49, s61, -v56
	v_fmac_f32_e32 v56, 0x3377d1cf, v49
	v_fmac_f32_e32 v56, 0x3f317217, v49
	v_cmp_lt_f32_e64 s[0:1], |v49|, s66
	v_mul_f32_e32 v48, 0xbfb8aa3b, v48
	v_exp_f32_e32 v52, v52
	v_cndmask_b32_e64 v49, v49, v56, s[0:1]
	v_cndmask_b32_e32 v56, 0, v179, vcc
	v_sub_f32_e32 v49, v49, v56
	v_cmp_gt_f32_e32 vcc, s65, v50
	v_sub_f32_e32 v49, -0.5, v49
	v_mul_f32_e32 v49, 0x3fb8aa3b, v49
	v_cndmask_b32_e64 v56, 0, 32, vcc
	v_ldexp_f32 v50, v50, v56
	v_exp_f32_e32 v49, v49
	v_log_f32_e32 v50, v50
	v_exp_f32_e32 v56, v48
	v_exp_f32_e32 v53, v53
	v_mul_f32_e32 v48, 0xbfb8aa3b, v49
	v_mul_f32_e32 v49, 0x3f317217, v50
	v_fma_f32 v49, v50, s61, -v49
	v_fmac_f32_e32 v49, 0x3377d1cf, v50
	v_fmac_f32_e32 v49, 0x3f317217, v50
	v_cmp_lt_f32_e64 s[0:1], |v50|, s66
	v_exp_f32_e32 v54, v54
	v_exp_f32_e32 v55, v55
	v_cndmask_b32_e64 v49, v50, v49, s[0:1]
	v_cndmask_b32_e32 v50, 0, v179, vcc
	v_sub_f32_e32 v49, v49, v50
	v_add_f32_e32 v50, 1.0, v51
	v_cmp_gt_f32_e32 vcc, s65, v50
	v_sub_f32_e32 v49, -0.5, v49
	v_mul_f32_e32 v49, 0x3fb8aa3b, v49
	v_cndmask_b32_e64 v51, 0, 32, vcc
	v_ldexp_f32 v50, v50, v51
	v_log_f32_e32 v50, v50
	v_exp_f32_e32 v49, v49
	v_mul_f32_e32 v52, 0xbfb8aa3b, v52
	v_mul_f32_e32 v53, 0xbfb8aa3b, v53
	v_mul_f32_e32 v51, 0x3f317217, v50
	v_fma_f32 v51, v50, s61, -v51
	v_fmac_f32_e32 v51, 0x3377d1cf, v50
	v_fmac_f32_e32 v51, 0x3f317217, v50
	v_cmp_lt_f32_e64 s[0:1], |v50|, s66
	v_mul_f32_e32 v54, 0xbfb8aa3b, v54
	v_mul_f32_e32 v55, 0xbfb8aa3b, v55
	v_cndmask_b32_e64 v50, v50, v51, s[0:1]
	v_cndmask_b32_e32 v51, 0, v179, vcc
	v_sub_f32_e32 v50, v50, v51
	v_sub_f32_e32 v50, -0.5, v50
	v_mul_f32_e32 v50, 0x3fb8aa3b, v50
	v_exp_f32_e32 v50, v50
	v_exp_f32_e32 v51, v48
	v_mul_f32_e32 v48, 0xbfb8aa3b, v49
	v_exp_f32_e32 v57, v48
	v_mul_f32_e32 v48, 0xbfb8aa3b, v50
	v_exp_f32_e32 v52, v52
	v_exp_f32_e32 v53, v53
	v_exp_f32_e32 v54, v54
	v_exp_f32_e32 v55, v55
	v_exp_f32_e32 v58, v48
	v_cvt_pk_f16_f32 v48, v52, v53
	v_cvt_pk_f16_f32 v49, v54, v55
	v_cvt_pk_f16_f32 v50, v56, v51
	v_cvt_pk_f16_f32 v51, v57, v58
	global_store_dwordx4 v[112:113], v[48:51], off offset:256 sc1
	v_add_f32_e32 v44, v44, v68
	v_mul_f32_e32 v44, 0xbfb8aa3b, v44
	v_exp_f32_e32 v44, v44
	v_add_f32_e32 v45, v45, v69
	v_mul_f32_e32 v45, 0xbfb8aa3b, v45
	v_exp_f32_e32 v45, v45
	v_add_f32_e32 v44, 1.0, v44
	v_cmp_gt_f32_e32 vcc, s65, v44
	v_add_f32_e32 v46, v46, v70
	v_add_f32_e32 v45, 1.0, v45
	v_cndmask_b32_e64 v48, 0, 32, vcc
	v_ldexp_f32 v44, v44, v48
	v_log_f32_e32 v44, v44
	v_mul_f32_e32 v46, 0xbfb8aa3b, v46
	v_exp_f32_e32 v46, v46
	v_add_f32_e32 v47, v47, v71
	v_mul_f32_e32 v48, 0x3f317217, v44
	v_fma_f32 v48, v44, s61, -v48
	v_fmac_f32_e32 v48, 0x3377d1cf, v44
	v_fmac_f32_e32 v48, 0x3f317217, v44
	v_cmp_lt_f32_e64 s[0:1], |v44|, s66
	v_add_f32_e32 v46, 1.0, v46
	v_mul_f32_e32 v47, 0xbfb8aa3b, v47
	v_cndmask_b32_e64 v44, v44, v48, s[0:1]
	v_cndmask_b32_e32 v48, 0, v179, vcc
	v_cmp_gt_f32_e32 vcc, s65, v45
	v_sub_f32_e32 v44, v44, v48
	v_exp_f32_e32 v47, v47
	v_cndmask_b32_e64 v48, 0, 32, vcc
	v_ldexp_f32 v45, v45, v48
	v_log_f32_e32 v45, v45
	v_add_f32_e32 v47, 1.0, v47
	v_add_f32_e32 v40, v40, v64
	v_mul_f32_e32 v40, 0xbfb8aa3b, v40
	v_mul_f32_e32 v48, 0x3f317217, v45
	v_fma_f32 v48, v45, s61, -v48
	v_fmac_f32_e32 v48, 0x3377d1cf, v45
	v_fmac_f32_e32 v48, 0x3f317217, v45
	v_cmp_lt_f32_e64 s[0:1], |v45|, s66
	v_exp_f32_e32 v40, v40
	v_add_f32_e32 v41, v41, v65
	v_cndmask_b32_e64 v45, v45, v48, s[0:1]
	v_cndmask_b32_e32 v48, 0, v179, vcc
	v_cmp_gt_f32_e32 vcc, s65, v46
	v_sub_f32_e32 v45, v45, v48
	v_add_f32_e32 v40, 1.0, v40
	v_cndmask_b32_e64 v48, 0, 32, vcc
	v_ldexp_f32 v46, v46, v48
	v_log_f32_e32 v46, v46
	v_mul_f32_e32 v41, 0xbfb8aa3b, v41
	v_exp_f32_e32 v41, v41
	v_add_f32_e32 v42, v42, v66
	v_mul_f32_e32 v48, 0x3f317217, v46
	v_fma_f32 v48, v46, s61, -v48
	v_fmac_f32_e32 v48, 0x3377d1cf, v46
	v_fmac_f32_e32 v48, 0x3f317217, v46
	v_cmp_lt_f32_e64 s[0:1], |v46|, s66
	v_add_f32_e32 v41, 1.0, v41
	v_mul_f32_e32 v42, 0xbfb8aa3b, v42
	v_cndmask_b32_e64 v46, v46, v48, s[0:1]
	v_cndmask_b32_e32 v48, 0, v179, vcc
	v_cmp_gt_f32_e32 vcc, s65, v47
	v_sub_f32_e32 v46, v46, v48
	v_exp_f32_e32 v42, v42
	v_cndmask_b32_e64 v48, 0, 32, vcc
	v_ldexp_f32 v47, v47, v48
	v_log_f32_e32 v47, v47
	v_add_f32_e32 v42, 1.0, v42
	v_add_f32_e32 v43, v43, v67
	v_mul_f32_e32 v43, 0xbfb8aa3b, v43
	v_mul_f32_e32 v48, 0x3f317217, v47
	v_fma_f32 v48, v47, s61, -v48
	v_fmac_f32_e32 v48, 0x3377d1cf, v47
	v_fmac_f32_e32 v48, 0x3f317217, v47
	v_cmp_lt_f32_e64 s[0:1], |v47|, s66
	v_exp_f32_e32 v43, v43
	v_sub_f32_e32 v44, -0.5, v44
	v_cndmask_b32_e64 v47, v47, v48, s[0:1]
;     template <int MODE> __device__ __forceinline__ void run(AccRef acc, const Unit& u, int wr, int wc, int fr, int fq) const {
;     ...
;                     if (MODE == 0) {
; #pragma unroll
;                         for (int e = 0; e < 8; ++e) { const float sp = __logf(1.f + __expf(-x[e])); x[e] = __expf(-__expf(-sp - 0.5f)); }
;                         w.x = pkh(x[0], x[1]); w.y = pkh(x[2], x[3]); w.z = pkh(x[4], x[5]); w.w = pkh(x[6], x[7]);
;                         *(u32x4*)(WA + (size_t)row * 2048 + seg * 512 + cc) = w;
	v_cndmask_b32_e32 v48, 0, v179, vcc
	v_cmp_gt_f32_e32 vcc, s65, v40
	v_sub_f32_e32 v47, v47, v48
	v_sub_f32_e32 v45, -0.5, v45
	v_cndmask_b32_e64 v48, 0, 32, vcc
	v_ldexp_f32 v40, v40, v48
	v_log_f32_e32 v40, v40
	v_sub_f32_e32 v46, -0.5, v46
	v_sub_f32_e32 v47, -0.5, v47
	v_mul_f32_e32 v44, 0x3fb8aa3b, v44
	v_mul_f32_e32 v48, 0x3f317217, v40
	v_fma_f32 v48, v40, s61, -v48
	v_fmac_f32_e32 v48, 0x3377d1cf, v40
	v_fmac_f32_e32 v48, 0x3f317217, v40
	v_cmp_lt_f32_e64 s[0:1], |v40|, s66
	v_mul_f32_e32 v45, 0x3fb8aa3b, v45
	v_mul_f32_e32 v46, 0x3fb8aa3b, v46
	v_cndmask_b32_e64 v40, v40, v48, s[0:1]
	v_cndmask_b32_e32 v48, 0, v179, vcc
	v_cmp_gt_f32_e32 vcc, s65, v41
	v_sub_f32_e32 v40, v40, v48
	v_sub_f32_e32 v40, -0.5, v40
	v_cndmask_b32_e64 v48, 0, 32, vcc
	v_ldexp_f32 v41, v41, v48
	v_log_f32_e32 v41, v41
	v_mul_f32_e32 v40, 0x3fb8aa3b, v40
	v_exp_f32_e32 v40, v40
	v_mul_f32_e32 v47, 0x3fb8aa3b, v47
	v_mul_f32_e32 v48, 0x3f317217, v41
	v_fma_f32 v48, v41, s61, -v48
	v_fmac_f32_e32 v48, 0x3377d1cf, v41
	v_fmac_f32_e32 v48, 0x3f317217, v41
	v_cmp_lt_f32_e64 s[0:1], |v41|, s66
	v_mul_f32_e32 v40, 0xbfb8aa3b, v40
	v_exp_f32_e32 v44, v44
	v_cndmask_b32_e64 v41, v41, v48, s[0:1]
	v_cndmask_b32_e32 v48, 0, v179, vcc
	v_sub_f32_e32 v41, v41, v48
	v_cmp_gt_f32_e32 vcc, s65, v42
	v_sub_f32_e32 v41, -0.5, v41
	v_mul_f32_e32 v41, 0x3fb8aa3b, v41
	v_cndmask_b32_e64 v48, 0, 32, vcc
	v_ldexp_f32 v42, v42, v48
	v_exp_f32_e32 v41, v41
	v_log_f32_e32 v42, v42
	v_exp_f32_e32 v48, v40
	v_exp_f32_e32 v45, v45
	v_mul_f32_e32 v40, 0xbfb8aa3b, v41
	v_mul_f32_e32 v41, 0x3f317217, v42
	v_fma_f32 v41, v42, s61, -v41
	v_fmac_f32_e32 v41, 0x3377d1cf, v42
	v_fmac_f32_e32 v41, 0x3f317217, v42
	v_cmp_lt_f32_e64 s[0:1], |v42|, s66
	v_exp_f32_e32 v46, v46
	v_exp_f32_e32 v47, v47
	v_cndmask_b32_e64 v41, v42, v41, s[0:1]
	v_cndmask_b32_e32 v42, 0, v179, vcc
	v_sub_f32_e32 v41, v41, v42
	v_add_f32_e32 v42, 1.0, v43
	v_cmp_gt_f32_e32 vcc, s65, v42
	v_sub_f32_e32 v41, -0.5, v41
	v_mul_f32_e32 v41, 0x3fb8aa3b, v41
	v_cndmask_b32_e64 v43, 0, 32, vcc
	v_ldexp_f32 v42, v42, v43
	v_log_f32_e32 v42, v42
	v_exp_f32_e32 v41, v41
	v_mul_f32_e32 v44, 0xbfb8aa3b, v44
	v_mul_f32_e32 v45, 0xbfb8aa3b, v45
	v_mul_f32_e32 v43, 0x3f317217, v42
	v_fma_f32 v43, v42, s61, -v43
	v_fmac_f32_e32 v43, 0x3377d1cf, v42
	v_fmac_f32_e32 v43, 0x3f317217, v42
	v_cmp_lt_f32_e64 s[0:1], |v42|, s66
	v_mul_f32_e32 v46, 0xbfb8aa3b, v46
	v_mul_f32_e32 v47, 0xbfb8aa3b, v47
	v_cndmask_b32_e64 v42, v42, v43, s[0:1]
	v_cndmask_b32_e32 v43, 0, v179, vcc
	v_sub_f32_e32 v42, v42, v43
	v_sub_f32_e32 v42, -0.5, v42
	v_mul_f32_e32 v42, 0x3fb8aa3b, v42
	v_exp_f32_e32 v42, v42
	v_exp_f32_e32 v43, v40
	v_mul_f32_e32 v40, 0xbfb8aa3b, v41
	v_exp_f32_e32 v49, v40
	v_mul_f32_e32 v40, 0xbfb8aa3b, v42
	v_exp_f32_e32 v44, v44
	v_exp_f32_e32 v45, v45
	v_exp_f32_e32 v46, v46
	v_exp_f32_e32 v47, v47
	v_exp_f32_e32 v50, v40
	v_cvt_pk_f16_f32 v40, v44, v45
	v_cvt_pk_f16_f32 v41, v46, v47
	v_cvt_pk_f16_f32 v42, v48, v43
	v_cvt_pk_f16_f32 v43, v49, v50
	global_store_dwordx4 v[104:105], v[40:43], off offset:256 sc1
	v_add_f32_e32 v36, v36, v68
	v_mul_f32_e32 v36, 0xbfb8aa3b, v36
	v_exp_f32_e32 v36, v36
	v_add_f32_e32 v37, v37, v69
	v_mul_f32_e32 v37, 0xbfb8aa3b, v37
	v_exp_f32_e32 v37, v37
	v_add_f32_e32 v36, 1.0, v36
	v_cmp_gt_f32_e32 vcc, s65, v36
	v_add_f32_e32 v38, v38, v70
	v_add_f32_e32 v37, 1.0, v37
	v_cndmask_b32_e64 v40, 0, 32, vcc
	v_ldexp_f32 v36, v36, v40
	v_log_f32_e32 v36, v36
	v_mul_f32_e32 v38, 0xbfb8aa3b, v38
	v_exp_f32_e32 v38, v38
	v_add_f32_e32 v39, v39, v71
	v_mul_f32_e32 v40, 0x3f317217, v36
	v_fma_f32 v40, v36, s61, -v40
	v_fmac_f32_e32 v40, 0x3377d1cf, v36
	v_fmac_f32_e32 v40, 0x3f317217, v36
	v_cmp_lt_f32_e64 s[0:1], |v36|, s66
	v_add_f32_e32 v38, 1.0, v38
	v_mul_f32_e32 v39, 0xbfb8aa3b, v39
	v_cndmask_b32_e64 v36, v36, v40, s[0:1]
	v_cndmask_b32_e32 v40, 0, v179, vcc
	v_cmp_gt_f32_e32 vcc, s65, v37
	v_sub_f32_e32 v36, v36, v40
	v_exp_f32_e32 v39, v39
	v_cndmask_b32_e64 v40, 0, 32, vcc
	v_ldexp_f32 v37, v37, v40
	v_log_f32_e32 v37, v37
	v_add_f32_e32 v39, 1.0, v39
	v_add_f32_e32 v32, v32, v64
	v_mul_f32_e32 v32, 0xbfb8aa3b, v32
	v_mul_f32_e32 v40, 0x3f317217, v37
	v_fma_f32 v40, v37, s61, -v40
	v_fmac_f32_e32 v40, 0x3377d1cf, v37
	v_fmac_f32_e32 v40, 0x3f317217, v37
	v_cmp_lt_f32_e64 s[0:1], |v37|, s66
	v_exp_f32_e32 v32, v32
	v_add_f32_e32 v33, v33, v65
	v_cndmask_b32_e64 v37, v37, v40, s[0:1]
	v_cndmask_b32_e32 v40, 0, v179, vcc
	v_cmp_gt_f32_e32 vcc, s65, v38
	v_sub_f32_e32 v37, v37, v40
	v_add_f32_e32 v32, 1.0, v32
	v_cndmask_b32_e64 v40, 0, 32, vcc
	v_ldexp_f32 v38, v38, v40
	v_log_f32_e32 v38, v38
	v_mul_f32_e32 v33, 0xbfb8aa3b, v33
	v_exp_f32_e32 v33, v33
	v_add_f32_e32 v34, v34, v66
	v_mul_f32_e32 v40, 0x3f317217, v38
	v_fma_f32 v40, v38, s61, -v40
	v_fmac_f32_e32 v40, 0x3377d1cf, v38
	v_fmac_f32_e32 v40, 0x3f317217, v38
	v_cmp_lt_f32_e64 s[0:1], |v38|, s66
	v_add_f32_e32 v33, 1.0, v33
	v_mul_f32_e32 v34, 0xbfb8aa3b, v34
	v_cndmask_b32_e64 v38, v38, v40, s[0:1]
	v_cndmask_b32_e32 v40, 0, v179, vcc
	v_cmp_gt_f32_e32 vcc, s65, v39
	v_sub_f32_e32 v38, v38, v40
	v_exp_f32_e32 v34, v34
	v_cndmask_b32_e64 v40, 0, 32, vcc
	v_ldexp_f32 v39, v39, v40
	v_log_f32_e32 v39, v39
	v_add_f32_e32 v34, 1.0, v34
	v_add_f32_e32 v35, v35, v67
	v_mul_f32_e32 v35, 0xbfb8aa3b, v35
	v_mul_f32_e32 v40, 0x3f317217, v39
	v_fma_f32 v40, v39, s61, -v40
	v_fmac_f32_e32 v40, 0x3377d1cf, v39
	v_fmac_f32_e32 v40, 0x3f317217, v39
	v_cmp_lt_f32_e64 s[0:1], |v39|, s66
	v_exp_f32_e32 v35, v35
	v_sub_f32_e32 v36, -0.5, v36
	v_cndmask_b32_e64 v39, v39, v40, s[0:1]
	v_cndmask_b32_e32 v40, 0, v179, vcc
	v_cmp_gt_f32_e32 vcc, s65, v32
;     template <int MODE> __device__ __forceinline__ void run(AccRef acc, const Unit& u, int wr, int wc, int fr, int fq) const {
;     ...
;                     if (MODE == 0) {
; #pragma unroll
;                         for (int e = 0; e < 8; ++e) { const float sp = __logf(1.f + __expf(-x[e])); x[e] = __expf(-__expf(-sp - 0.5f)); }
;                         w.x = pkh(x[0], x[1]); w.y = pkh(x[2], x[3]); w.z = pkh(x[4], x[5]); w.w = pkh(x[6], x[7]);
;                         *(u32x4*)(WA + (size_t)row * 2048 + seg * 512 + cc) = w;
	v_sub_f32_e32 v39, v39, v40
	v_sub_f32_e32 v37, -0.5, v37
	v_cndmask_b32_e64 v40, 0, 32, vcc
	v_ldexp_f32 v32, v32, v40
	v_log_f32_e32 v32, v32
	v_sub_f32_e32 v38, -0.5, v38
	v_sub_f32_e32 v39, -0.5, v39
	v_mul_f32_e32 v36, 0x3fb8aa3b, v36
	v_mul_f32_e32 v40, 0x3f317217, v32
	v_fma_f32 v40, v32, s61, -v40
	v_fmac_f32_e32 v40, 0x3377d1cf, v32
	v_fmac_f32_e32 v40, 0x3f317217, v32
	v_cmp_lt_f32_e64 s[0:1], |v32|, s66
	v_mul_f32_e32 v37, 0x3fb8aa3b, v37
	v_mul_f32_e32 v38, 0x3fb8aa3b, v38
	v_cndmask_b32_e64 v32, v32, v40, s[0:1]
	v_cndmask_b32_e32 v40, 0, v179, vcc
	v_cmp_gt_f32_e32 vcc, s65, v33
	v_sub_f32_e32 v32, v32, v40
	v_sub_f32_e32 v32, -0.5, v32
	v_cndmask_b32_e64 v40, 0, 32, vcc
	v_ldexp_f32 v33, v33, v40
	v_log_f32_e32 v33, v33
	v_mul_f32_e32 v32, 0x3fb8aa3b, v32
	v_exp_f32_e32 v32, v32
	v_mul_f32_e32 v39, 0x3fb8aa3b, v39
	v_mul_f32_e32 v40, 0x3f317217, v33
	v_fma_f32 v40, v33, s61, -v40
	v_fmac_f32_e32 v40, 0x3377d1cf, v33
	v_fmac_f32_e32 v40, 0x3f317217, v33
	v_cmp_lt_f32_e64 s[0:1], |v33|, s66
	v_mul_f32_e32 v32, 0xbfb8aa3b, v32
	v_exp_f32_e32 v36, v36
	v_cndmask_b32_e64 v33, v33, v40, s[0:1]
	v_cndmask_b32_e32 v40, 0, v179, vcc
	v_sub_f32_e32 v33, v33, v40
	v_cmp_gt_f32_e32 vcc, s65, v34
	v_sub_f32_e32 v33, -0.5, v33
	v_mul_f32_e32 v33, 0x3fb8aa3b, v33
	v_cndmask_b32_e64 v40, 0, 32, vcc
	v_ldexp_f32 v34, v34, v40
	v_exp_f32_e32 v33, v33
	v_log_f32_e32 v34, v34
	v_exp_f32_e32 v40, v32
	v_exp_f32_e32 v37, v37
	v_mul_f32_e32 v32, 0xbfb8aa3b, v33
	v_mul_f32_e32 v33, 0x3f317217, v34
	v_fma_f32 v33, v34, s61, -v33
	v_fmac_f32_e32 v33, 0x3377d1cf, v34
	v_fmac_f32_e32 v33, 0x3f317217, v34
	v_cmp_lt_f32_e64 s[0:1], |v34|, s66
	v_exp_f32_e32 v38, v38
	v_exp_f32_e32 v39, v39
	v_cndmask_b32_e64 v33, v34, v33, s[0:1]
	v_cndmask_b32_e32 v34, 0, v179, vcc
	v_sub_f32_e32 v33, v33, v34
	v_add_f32_e32 v34, 1.0, v35
	v_cmp_gt_f32_e32 vcc, s65, v34
	v_sub_f32_e32 v33, -0.5, v33
	v_mul_f32_e32 v33, 0x3fb8aa3b, v33
	v_cndmask_b32_e64 v35, 0, 32, vcc
	v_ldexp_f32 v34, v34, v35
	v_log_f32_e32 v34, v34
	v_exp_f32_e32 v33, v33
	v_mul_f32_e32 v36, 0xbfb8aa3b, v36
	v_mul_f32_e32 v37, 0xbfb8aa3b, v37
	v_mul_f32_e32 v35, 0x3f317217, v34
	v_fma_f32 v35, v34, s61, -v35
	v_fmac_f32_e32 v35, 0x3377d1cf, v34
	v_fmac_f32_e32 v35, 0x3f317217, v34
	v_cmp_lt_f32_e64 s[0:1], |v34|, s66
	v_mul_f32_e32 v38, 0xbfb8aa3b, v38
	v_mul_f32_e32 v39, 0xbfb8aa3b, v39
	v_cndmask_b32_e64 v34, v34, v35, s[0:1]
	v_cndmask_b32_e32 v35, 0, v179, vcc
	v_sub_f32_e32 v34, v34, v35
	v_sub_f32_e32 v34, -0.5, v34
	v_mul_f32_e32 v34, 0x3fb8aa3b, v34
	v_exp_f32_e32 v34, v34
	v_exp_f32_e32 v35, v32
	v_mul_f32_e32 v32, 0xbfb8aa3b, v33
	v_exp_f32_e32 v41, v32
	v_mul_f32_e32 v32, 0xbfb8aa3b, v34
	v_exp_f32_e32 v36, v36
	v_exp_f32_e32 v37, v37
	v_exp_f32_e32 v38, v38
	v_exp_f32_e32 v39, v39
	v_exp_f32_e32 v42, v32
	v_cvt_pk_f16_f32 v32, v36, v37
	v_cvt_pk_f16_f32 v33, v38, v39
	v_cvt_pk_f16_f32 v34, v40, v35
	v_cvt_pk_f16_f32 v35, v41, v42
	global_store_dwordx4 v[96:97], v[32:35], off offset:256 sc1
	v_add_f32_e32 v28, v28, v68
	v_mul_f32_e32 v28, 0xbfb8aa3b, v28
	v_exp_f32_e32 v28, v28
	v_add_f32_e32 v29, v29, v69
	v_mul_f32_e32 v29, 0xbfb8aa3b, v29
	v_exp_f32_e32 v29, v29
	v_add_f32_e32 v28, 1.0, v28
	v_cmp_gt_f32_e32 vcc, s65, v28
	v_add_f32_e32 v30, v30, v70
	v_add_f32_e32 v29, 1.0, v29
	v_cndmask_b32_e64 v32, 0, 32, vcc
	v_ldexp_f32 v28, v28, v32
	v_log_f32_e32 v28, v28
	v_mul_f32_e32 v30, 0xbfb8aa3b, v30
	v_exp_f32_e32 v30, v30
	v_add_f32_e32 v31, v31, v71
	v_mul_f32_e32 v32, 0x3f317217, v28
	v_fma_f32 v32, v28, s61, -v32
	v_fmac_f32_e32 v32, 0x3377d1cf, v28
	v_fmac_f32_e32 v32, 0x3f317217, v28
	v_cmp_lt_f32_e64 s[0:1], |v28|, s66
	v_add_f32_e32 v30, 1.0, v30
	v_mul_f32_e32 v31, 0xbfb8aa3b, v31
	v_cndmask_b32_e64 v28, v28, v32, s[0:1]
	v_cndmask_b32_e32 v32, 0, v179, vcc
	v_cmp_gt_f32_e32 vcc, s65, v29
	v_sub_f32_e32 v28, v28, v32
	v_exp_f32_e32 v31, v31
	v_cndmask_b32_e64 v32, 0, 32, vcc
	v_ldexp_f32 v29, v29, v32
	v_log_f32_e32 v29, v29
	v_add_f32_e32 v31, 1.0, v31
	v_add_f32_e32 v24, v24, v64
	v_mul_f32_e32 v24, 0xbfb8aa3b, v24
	v_mul_f32_e32 v32, 0x3f317217, v29
	v_fma_f32 v32, v29, s61, -v32
	v_fmac_f32_e32 v32, 0x3377d1cf, v29
	v_fmac_f32_e32 v32, 0x3f317217, v29
	v_cmp_lt_f32_e64 s[0:1], |v29|, s66
	v_exp_f32_e32 v24, v24
	v_add_f32_e32 v25, v25, v65
	v_cndmask_b32_e64 v29, v29, v32, s[0:1]
	v_cndmask_b32_e32 v32, 0, v179, vcc
	v_cmp_gt_f32_e32 vcc, s65, v30
	v_sub_f32_e32 v29, v29, v32
	v_add_f32_e32 v24, 1.0, v24
	v_cndmask_b32_e64 v32, 0, 32, vcc
	v_ldexp_f32 v30, v30, v32
	v_log_f32_e32 v30, v30
	v_mul_f32_e32 v25, 0xbfb8aa3b, v25
	v_exp_f32_e32 v25, v25
	v_add_f32_e32 v26, v26, v66
	v_mul_f32_e32 v32, 0x3f317217, v30
	v_fma_f32 v32, v30, s61, -v32
	v_fmac_f32_e32 v32, 0x3377d1cf, v30
	v_fmac_f32_e32 v32, 0x3f317217, v30
	v_cmp_lt_f32_e64 s[0:1], |v30|, s66
	v_add_f32_e32 v25, 1.0, v25
	v_mul_f32_e32 v26, 0xbfb8aa3b, v26
	v_cndmask_b32_e64 v30, v30, v32, s[0:1]
	v_cndmask_b32_e32 v32, 0, v179, vcc
	v_cmp_gt_f32_e32 vcc, s65, v31
	v_sub_f32_e32 v30, v30, v32
	v_exp_f32_e32 v26, v26
	v_cndmask_b32_e64 v32, 0, 32, vcc
	v_ldexp_f32 v31, v31, v32
	v_log_f32_e32 v31, v31
	v_add_f32_e32 v26, 1.0, v26
	v_add_f32_e32 v27, v27, v67
	v_mul_f32_e32 v27, 0xbfb8aa3b, v27
	v_mul_f32_e32 v32, 0x3f317217, v31
	v_fma_f32 v32, v31, s61, -v32
	v_fmac_f32_e32 v32, 0x3377d1cf, v31
	v_fmac_f32_e32 v32, 0x3f317217, v31
	v_cmp_lt_f32_e64 s[0:1], |v31|, s66
	v_exp_f32_e32 v27, v27
	v_sub_f32_e32 v28, -0.5, v28
	v_cndmask_b32_e64 v31, v31, v32, s[0:1]
	v_cndmask_b32_e32 v32, 0, v179, vcc
	v_cmp_gt_f32_e32 vcc, s65, v24
	v_sub_f32_e32 v31, v31, v32
	v_sub_f32_e32 v29, -0.5, v29
	v_cndmask_b32_e64 v32, 0, 32, vcc
;     template <int MODE> __device__ __forceinline__ void run(AccRef acc, const Unit& u, int wr, int wc, int fr, int fq) const {
;     ...
;                 for (int m = 0; m < 4; ++m) {
;                     const int row = row0 + ai * 128 + m * 16;
;                     float x[8];
; #pragma unroll
;                     for (int e = 0; e < 4; ++e) { x[e] = acc[ai][bj][m][0][e] + bias[e]; x[4 + e] = acc[ai][bj][m][1][e] + bias[4 + e]; }
;                     u32x4 w;
;                     if (MODE == 0) {
; #pragma unroll
;                         for (int e = 0; e < 8; ++e) { const float sp = __logf(1.f + __expf(-x[e])); x[e] = __expf(-__expf(-sp - 0.5f)); }
;                         w.x = pkh(x[0], x[1]); w.y = pkh(x[2], x[3]); w.z = pkh(x[4], x[5]); w.w = pkh(x[6], x[7]);
;                         *(u32x4*)(WA + (size_t)row * 2048 + seg * 512 + cc) = w;
	v_ldexp_f32 v24, v24, v32
	v_log_f32_e32 v24, v24
	v_sub_f32_e32 v30, -0.5, v30
	v_sub_f32_e32 v31, -0.5, v31
	v_mul_f32_e32 v28, 0x3fb8aa3b, v28
	v_mul_f32_e32 v32, 0x3f317217, v24
	v_fma_f32 v32, v24, s61, -v32
	v_fmac_f32_e32 v32, 0x3377d1cf, v24
	v_fmac_f32_e32 v32, 0x3f317217, v24
	v_cmp_lt_f32_e64 s[0:1], |v24|, s66
	v_mul_f32_e32 v29, 0x3fb8aa3b, v29
	v_mul_f32_e32 v30, 0x3fb8aa3b, v30
	v_cndmask_b32_e64 v24, v24, v32, s[0:1]
	v_cndmask_b32_e32 v32, 0, v179, vcc
	v_cmp_gt_f32_e32 vcc, s65, v25
	v_sub_f32_e32 v24, v24, v32
	v_sub_f32_e32 v24, -0.5, v24
	v_cndmask_b32_e64 v32, 0, 32, vcc
	v_ldexp_f32 v25, v25, v32
	v_log_f32_e32 v25, v25
	v_mul_f32_e32 v24, 0x3fb8aa3b, v24
	v_exp_f32_e32 v24, v24
	v_mul_f32_e32 v31, 0x3fb8aa3b, v31
	v_mul_f32_e32 v32, 0x3f317217, v25
	v_fma_f32 v32, v25, s61, -v32
	v_fmac_f32_e32 v32, 0x3377d1cf, v25
	v_fmac_f32_e32 v32, 0x3f317217, v25
	v_cmp_lt_f32_e64 s[0:1], |v25|, s66
	v_mul_f32_e32 v24, 0xbfb8aa3b, v24
	v_exp_f32_e32 v28, v28
	v_cndmask_b32_e64 v25, v25, v32, s[0:1]
	v_cndmask_b32_e32 v32, 0, v179, vcc
	v_sub_f32_e32 v25, v25, v32
	v_cmp_gt_f32_e32 vcc, s65, v26
	v_sub_f32_e32 v25, -0.5, v25
	v_mul_f32_e32 v25, 0x3fb8aa3b, v25
	v_cndmask_b32_e64 v32, 0, 32, vcc
	v_ldexp_f32 v26, v26, v32
	v_exp_f32_e32 v25, v25
	v_log_f32_e32 v26, v26
	v_exp_f32_e32 v32, v24
	v_exp_f32_e32 v29, v29
	v_mul_f32_e32 v24, 0xbfb8aa3b, v25
	v_mul_f32_e32 v25, 0x3f317217, v26
	v_fma_f32 v25, v26, s61, -v25
	v_fmac_f32_e32 v25, 0x3377d1cf, v26
	v_fmac_f32_e32 v25, 0x3f317217, v26
	v_cmp_lt_f32_e64 s[0:1], |v26|, s66
	v_exp_f32_e32 v30, v30
	v_exp_f32_e32 v31, v31
	v_cndmask_b32_e64 v25, v26, v25, s[0:1]
	v_cndmask_b32_e32 v26, 0, v179, vcc
	v_sub_f32_e32 v25, v25, v26
	v_add_f32_e32 v26, 1.0, v27
	v_cmp_gt_f32_e32 vcc, s65, v26
	v_sub_f32_e32 v25, -0.5, v25
	v_mul_f32_e32 v25, 0x3fb8aa3b, v25
	v_cndmask_b32_e64 v27, 0, 32, vcc
	v_ldexp_f32 v26, v26, v27
	v_log_f32_e32 v26, v26
	v_exp_f32_e32 v25, v25
	v_mul_f32_e32 v28, 0xbfb8aa3b, v28
	v_mul_f32_e32 v29, 0xbfb8aa3b, v29
	v_mul_f32_e32 v27, 0x3f317217, v26
	v_fma_f32 v27, v26, s61, -v27
	v_fmac_f32_e32 v27, 0x3377d1cf, v26
	v_fmac_f32_e32 v27, 0x3f317217, v26
	v_cmp_lt_f32_e64 s[0:1], |v26|, s66
	v_mul_f32_e32 v30, 0xbfb8aa3b, v30
	v_mul_f32_e32 v31, 0xbfb8aa3b, v31
	v_cndmask_b32_e64 v26, v26, v27, s[0:1]
	v_cndmask_b32_e32 v27, 0, v179, vcc
	v_sub_f32_e32 v26, v26, v27
	v_sub_f32_e32 v26, -0.5, v26
	v_mul_f32_e32 v26, 0x3fb8aa3b, v26
	v_exp_f32_e32 v26, v26
	v_exp_f32_e32 v27, v24
	v_mul_f32_e32 v24, 0xbfb8aa3b, v25
	v_exp_f32_e32 v33, v24
	v_mul_f32_e32 v24, 0xbfb8aa3b, v26
	v_exp_f32_e32 v28, v28
	v_exp_f32_e32 v29, v29
	v_exp_f32_e32 v30, v30
	v_exp_f32_e32 v31, v31
	v_exp_f32_e32 v34, v24
	v_cvt_pk_f16_f32 v24, v28, v29
	v_cvt_pk_f16_f32 v25, v30, v31
	v_cvt_pk_f16_f32 v26, v32, v27
	v_cvt_pk_f16_f32 v27, v33, v34
	global_store_dwordx4 v[88:89], v[24:27], off offset:256 sc1
	v_add_f32_e32 v20, v20, v68
	v_mul_f32_e32 v20, 0xbfb8aa3b, v20
	v_exp_f32_e32 v20, v20
	v_add_f32_e32 v21, v21, v69
	v_mul_f32_e32 v21, 0xbfb8aa3b, v21
	v_exp_f32_e32 v21, v21
	v_add_f32_e32 v20, 1.0, v20
	v_cmp_gt_f32_e32 vcc, s65, v20
	v_add_f32_e32 v22, v22, v70
	v_add_f32_e32 v21, 1.0, v21
	v_cndmask_b32_e64 v24, 0, 32, vcc
	v_ldexp_f32 v20, v20, v24
	v_log_f32_e32 v20, v20
	v_mul_f32_e32 v22, 0xbfb8aa3b, v22
	v_exp_f32_e32 v22, v22
	v_add_f32_e32 v23, v23, v71
	v_mul_f32_e32 v24, 0x3f317217, v20
	v_fma_f32 v24, v20, s61, -v24
	v_fmac_f32_e32 v24, 0x3377d1cf, v20
	v_fmac_f32_e32 v24, 0x3f317217, v20
	v_cmp_lt_f32_e64 s[0:1], |v20|, s66
	v_add_f32_e32 v22, 1.0, v22
	v_mul_f32_e32 v23, 0xbfb8aa3b, v23
	v_cndmask_b32_e64 v20, v20, v24, s[0:1]
	v_cndmask_b32_e32 v24, 0, v179, vcc
	v_cmp_gt_f32_e32 vcc, s65, v21
	v_sub_f32_e32 v20, v20, v24
	v_exp_f32_e32 v23, v23
	v_cndmask_b32_e64 v24, 0, 32, vcc
	v_ldexp_f32 v21, v21, v24
	v_log_f32_e32 v21, v21
	v_add_f32_e32 v23, 1.0, v23
	v_add_f32_e32 v16, v16, v64
	v_mul_f32_e32 v16, 0xbfb8aa3b, v16
	v_mul_f32_e32 v24, 0x3f317217, v21
	v_fma_f32 v24, v21, s61, -v24
	v_fmac_f32_e32 v24, 0x3377d1cf, v21
	v_fmac_f32_e32 v24, 0x3f317217, v21
	v_cmp_lt_f32_e64 s[0:1], |v21|, s66
	v_exp_f32_e32 v16, v16
	v_add_f32_e32 v17, v17, v65
	v_cndmask_b32_e64 v21, v21, v24, s[0:1]
	v_cndmask_b32_e32 v24, 0, v179, vcc
	v_cmp_gt_f32_e32 vcc, s65, v22
	v_sub_f32_e32 v21, v21, v24
	v_add_f32_e32 v16, 1.0, v16
	v_cndmask_b32_e64 v24, 0, 32, vcc
	v_ldexp_f32 v22, v22, v24
	v_log_f32_e32 v22, v22
	v_mul_f32_e32 v17, 0xbfb8aa3b, v17
	v_exp_f32_e32 v17, v17
	v_add_f32_e32 v18, v18, v66
	v_mul_f32_e32 v24, 0x3f317217, v22
	v_fma_f32 v24, v22, s61, -v24
	v_fmac_f32_e32 v24, 0x3377d1cf, v22
	v_fmac_f32_e32 v24, 0x3f317217, v22
	v_cmp_lt_f32_e64 s[0:1], |v22|, s66
	v_add_f32_e32 v17, 1.0, v17
	v_mul_f32_e32 v18, 0xbfb8aa3b, v18
	v_cndmask_b32_e64 v22, v22, v24, s[0:1]
	v_cndmask_b32_e32 v24, 0, v179, vcc
	v_cmp_gt_f32_e32 vcc, s65, v23
	v_sub_f32_e32 v22, v22, v24
	v_exp_f32_e32 v18, v18
	v_cndmask_b32_e64 v24, 0, 32, vcc
	v_ldexp_f32 v23, v23, v24
	v_log_f32_e32 v23, v23
	v_add_f32_e32 v18, 1.0, v18
	v_add_f32_e32 v19, v19, v67
	v_mul_f32_e32 v19, 0xbfb8aa3b, v19
	v_mul_f32_e32 v24, 0x3f317217, v23
	v_fma_f32 v24, v23, s61, -v24
	v_fmac_f32_e32 v24, 0x3377d1cf, v23
	v_fmac_f32_e32 v24, 0x3f317217, v23
	v_cmp_lt_f32_e64 s[0:1], |v23|, s66
	v_exp_f32_e32 v19, v19
	v_sub_f32_e32 v20, -0.5, v20
	v_cndmask_b32_e64 v23, v23, v24, s[0:1]
	v_cndmask_b32_e32 v24, 0, v179, vcc
	v_cmp_gt_f32_e32 vcc, s65, v16
	v_sub_f32_e32 v23, v23, v24
	v_sub_f32_e32 v21, -0.5, v21
	v_cndmask_b32_e64 v24, 0, 32, vcc
	v_ldexp_f32 v16, v16, v24
	v_log_f32_e32 v16, v16
	v_sub_f32_e32 v22, -0.5, v22
;     template <int MODE> __device__ __forceinline__ void run(AccRef acc, const Unit& u, int wr, int wc, int fr, int fq) const {
;     ...
;                 for (int m = 0; m < 4; ++m) {
;                     const int row = row0 + ai * 128 + m * 16;
;                     float x[8];
; #pragma unroll
;                     for (int e = 0; e < 4; ++e) { x[e] = acc[ai][bj][m][0][e] + bias[e]; x[4 + e] = acc[ai][bj][m][1][e] + bias[4 + e]; }
;                     u32x4 w;
;                     if (MODE == 0) {
; #pragma unroll
;                         for (int e = 0; e < 8; ++e) { const float sp = __logf(1.f + __expf(-x[e])); x[e] = __expf(-__expf(-sp - 0.5f)); }
;                         w.x = pkh(x[0], x[1]); w.y = pkh(x[2], x[3]); w.z = pkh(x[4], x[5]); w.w = pkh(x[6], x[7]);
;                         *(u32x4*)(WA + (size_t)row * 2048 + seg * 512 + cc) = w;
	v_sub_f32_e32 v23, -0.5, v23
	v_mul_f32_e32 v20, 0x3fb8aa3b, v20
	v_mul_f32_e32 v24, 0x3f317217, v16
	v_fma_f32 v24, v16, s61, -v24
	v_fmac_f32_e32 v24, 0x3377d1cf, v16
	v_fmac_f32_e32 v24, 0x3f317217, v16
	v_cmp_lt_f32_e64 s[0:1], |v16|, s66
	v_mul_f32_e32 v21, 0x3fb8aa3b, v21
	v_mul_f32_e32 v22, 0x3fb8aa3b, v22
	v_cndmask_b32_e64 v16, v16, v24, s[0:1]
	v_cndmask_b32_e32 v24, 0, v179, vcc
	v_cmp_gt_f32_e32 vcc, s65, v17
	v_sub_f32_e32 v16, v16, v24
	v_sub_f32_e32 v16, -0.5, v16
	v_cndmask_b32_e64 v24, 0, 32, vcc
	v_ldexp_f32 v17, v17, v24
	v_log_f32_e32 v17, v17
	v_mul_f32_e32 v16, 0x3fb8aa3b, v16
	v_exp_f32_e32 v16, v16
	v_mul_f32_e32 v23, 0x3fb8aa3b, v23
	v_mul_f32_e32 v24, 0x3f317217, v17
	v_fma_f32 v24, v17, s61, -v24
	v_fmac_f32_e32 v24, 0x3377d1cf, v17
	v_fmac_f32_e32 v24, 0x3f317217, v17
	v_cmp_lt_f32_e64 s[0:1], |v17|, s66
	v_mul_f32_e32 v16, 0xbfb8aa3b, v16
	v_exp_f32_e32 v20, v20
	v_cndmask_b32_e64 v17, v17, v24, s[0:1]
	v_cndmask_b32_e32 v24, 0, v179, vcc
	v_sub_f32_e32 v17, v17, v24
	v_cmp_gt_f32_e32 vcc, s65, v18
	v_sub_f32_e32 v17, -0.5, v17
	v_mul_f32_e32 v17, 0x3fb8aa3b, v17
	v_cndmask_b32_e64 v24, 0, 32, vcc
	v_ldexp_f32 v18, v18, v24
	v_exp_f32_e32 v17, v17
	v_log_f32_e32 v18, v18
	v_exp_f32_e32 v24, v16
	v_exp_f32_e32 v21, v21
	v_mul_f32_e32 v16, 0xbfb8aa3b, v17
	v_mul_f32_e32 v17, 0x3f317217, v18
	v_fma_f32 v17, v18, s61, -v17
	v_fmac_f32_e32 v17, 0x3377d1cf, v18
	v_fmac_f32_e32 v17, 0x3f317217, v18
	v_cmp_lt_f32_e64 s[0:1], |v18|, s66
	v_exp_f32_e32 v22, v22
	v_exp_f32_e32 v23, v23
	v_cndmask_b32_e64 v17, v18, v17, s[0:1]
	v_cndmask_b32_e32 v18, 0, v179, vcc
	v_sub_f32_e32 v17, v17, v18
	v_add_f32_e32 v18, 1.0, v19
	v_cmp_gt_f32_e32 vcc, s65, v18
	v_sub_f32_e32 v17, -0.5, v17
	v_mul_f32_e32 v17, 0x3fb8aa3b, v17
	v_cndmask_b32_e64 v19, 0, 32, vcc
	v_ldexp_f32 v18, v18, v19
	v_log_f32_e32 v18, v18
	v_exp_f32_e32 v17, v17
	v_mul_f32_e32 v20, 0xbfb8aa3b, v20
	v_mul_f32_e32 v21, 0xbfb8aa3b, v21
	v_mul_f32_e32 v19, 0x3f317217, v18
	v_fma_f32 v19, v18, s61, -v19
	v_fmac_f32_e32 v19, 0x3377d1cf, v18
	v_fmac_f32_e32 v19, 0x3f317217, v18
	v_cmp_lt_f32_e64 s[0:1], |v18|, s66
	v_mul_f32_e32 v22, 0xbfb8aa3b, v22
	v_mul_f32_e32 v23, 0xbfb8aa3b, v23
	v_cndmask_b32_e64 v18, v18, v19, s[0:1]
	v_cndmask_b32_e32 v19, 0, v179, vcc
	v_sub_f32_e32 v18, v18, v19
	v_sub_f32_e32 v18, -0.5, v18
	v_mul_f32_e32 v18, 0x3fb8aa3b, v18
	v_exp_f32_e32 v18, v18
	v_exp_f32_e32 v19, v16
	v_mul_f32_e32 v16, 0xbfb8aa3b, v17
	v_exp_f32_e32 v25, v16
	v_mul_f32_e32 v16, 0xbfb8aa3b, v18
	v_exp_f32_e32 v20, v20
	v_exp_f32_e32 v21, v21
	v_exp_f32_e32 v22, v22
	v_exp_f32_e32 v23, v23
	v_exp_f32_e32 v26, v16
	v_cvt_pk_f16_f32 v16, v20, v21
	v_cvt_pk_f16_f32 v17, v22, v23
	v_cvt_pk_f16_f32 v18, v24, v19
	v_cvt_pk_f16_f32 v19, v25, v26
	global_store_dwordx4 v[80:81], v[16:19], off offset:256 sc1
	v_add_f32_e32 v12, v12, v68
	v_mul_f32_e32 v12, 0xbfb8aa3b, v12
	v_exp_f32_e32 v12, v12
	v_add_f32_e32 v13, v13, v69
	v_mul_f32_e32 v13, 0xbfb8aa3b, v13
	v_exp_f32_e32 v13, v13
	v_add_f32_e32 v12, 1.0, v12
	v_cmp_gt_f32_e32 vcc, s65, v12
	v_add_f32_e32 v14, v14, v70
	v_add_f32_e32 v13, 1.0, v13
	v_cndmask_b32_e64 v16, 0, 32, vcc
	v_ldexp_f32 v12, v12, v16
	v_log_f32_e32 v12, v12
	v_mul_f32_e32 v14, 0xbfb8aa3b, v14
	v_exp_f32_e32 v14, v14
	v_add_f32_e32 v15, v15, v71
	v_mul_f32_e32 v16, 0x3f317217, v12
	v_fma_f32 v16, v12, s61, -v16
	v_fmac_f32_e32 v16, 0x3377d1cf, v12
	v_fmac_f32_e32 v16, 0x3f317217, v12
	v_cmp_lt_f32_e64 s[0:1], |v12|, s66
	v_add_f32_e32 v14, 1.0, v14
	v_mul_f32_e32 v15, 0xbfb8aa3b, v15
	v_cndmask_b32_e64 v12, v12, v16, s[0:1]
	v_cndmask_b32_e32 v16, 0, v179, vcc
	v_cmp_gt_f32_e32 vcc, s65, v13
	v_sub_f32_e32 v12, v12, v16
	v_exp_f32_e32 v15, v15
	v_cndmask_b32_e64 v16, 0, 32, vcc
	v_ldexp_f32 v13, v13, v16
	v_log_f32_e32 v13, v13
	v_add_f32_e32 v15, 1.0, v15
	v_add_f32_e32 v8, v8, v64
	v_mul_f32_e32 v8, 0xbfb8aa3b, v8
	v_mul_f32_e32 v16, 0x3f317217, v13
	v_fma_f32 v16, v13, s61, -v16
	v_fmac_f32_e32 v16, 0x3377d1cf, v13
	v_fmac_f32_e32 v16, 0x3f317217, v13
	v_cmp_lt_f32_e64 s[0:1], |v13|, s66
	v_exp_f32_e32 v8, v8
	v_add_f32_e32 v9, v9, v65
	v_cndmask_b32_e64 v13, v13, v16, s[0:1]
	v_cndmask_b32_e32 v16, 0, v179, vcc
	v_cmp_gt_f32_e32 vcc, s65, v14
	v_sub_f32_e32 v13, v13, v16
	v_add_f32_e32 v8, 1.0, v8
	v_cndmask_b32_e64 v16, 0, 32, vcc
	v_ldexp_f32 v14, v14, v16
	v_log_f32_e32 v14, v14
	v_mul_f32_e32 v9, 0xbfb8aa3b, v9
	v_exp_f32_e32 v9, v9
	v_add_f32_e32 v10, v10, v66
	v_mul_f32_e32 v16, 0x3f317217, v14
	v_fma_f32 v16, v14, s61, -v16
	v_fmac_f32_e32 v16, 0x3377d1cf, v14
	v_fmac_f32_e32 v16, 0x3f317217, v14
	v_cmp_lt_f32_e64 s[0:1], |v14|, s66
	v_add_f32_e32 v9, 1.0, v9
	v_mul_f32_e32 v10, 0xbfb8aa3b, v10
	v_cndmask_b32_e64 v14, v14, v16, s[0:1]
	v_cndmask_b32_e32 v16, 0, v179, vcc
	v_cmp_gt_f32_e32 vcc, s65, v15
	v_sub_f32_e32 v14, v14, v16
	v_exp_f32_e32 v10, v10
	v_cndmask_b32_e64 v16, 0, 32, vcc
	v_ldexp_f32 v15, v15, v16
	v_log_f32_e32 v15, v15
	v_add_f32_e32 v10, 1.0, v10
	v_add_f32_e32 v11, v11, v67
	v_mul_f32_e32 v11, 0xbfb8aa3b, v11
	v_mul_f32_e32 v16, 0x3f317217, v15
	v_fma_f32 v16, v15, s61, -v16
	v_fmac_f32_e32 v16, 0x3377d1cf, v15
	v_fmac_f32_e32 v16, 0x3f317217, v15
	v_cmp_lt_f32_e64 s[0:1], |v15|, s66
	v_exp_f32_e32 v11, v11
	v_sub_f32_e32 v12, -0.5, v12
	v_cndmask_b32_e64 v15, v15, v16, s[0:1]
	v_cndmask_b32_e32 v16, 0, v179, vcc
	v_cmp_gt_f32_e32 vcc, s65, v8
	v_sub_f32_e32 v15, v15, v16
	v_sub_f32_e32 v13, -0.5, v13
	v_cndmask_b32_e64 v16, 0, 32, vcc
	v_ldexp_f32 v8, v8, v16
	v_log_f32_e32 v8, v8
	v_sub_f32_e32 v14, -0.5, v14
	v_sub_f32_e32 v15, -0.5, v15
	v_mul_f32_e32 v12, 0x3fb8aa3b, v12
	v_mul_f32_e32 v16, 0x3f317217, v8
;     template <int MODE> __device__ __forceinline__ void run(AccRef acc, const Unit& u, int wr, int wc, int fr, int fq) const {
;     ...
;                 for (int m = 0; m < 4; ++m) {
;                     const int row = row0 + ai * 128 + m * 16;
;                     float x[8];
; #pragma unroll
;                     for (int e = 0; e < 4; ++e) { x[e] = acc[ai][bj][m][0][e] + bias[e]; x[4 + e] = acc[ai][bj][m][1][e] + bias[4 + e]; }
;                     u32x4 w;
;                     if (MODE == 0) {
; #pragma unroll
;                         for (int e = 0; e < 8; ++e) { const float sp = __logf(1.f + __expf(-x[e])); x[e] = __expf(-__expf(-sp - 0.5f)); }
;                         w.x = pkh(x[0], x[1]); w.y = pkh(x[2], x[3]); w.z = pkh(x[4], x[5]); w.w = pkh(x[6], x[7]);
;                         *(u32x4*)(WA + (size_t)row * 2048 + seg * 512 + cc) = w;
	v_fma_f32 v16, v8, s61, -v16
	v_fmac_f32_e32 v16, 0x3377d1cf, v8
	v_fmac_f32_e32 v16, 0x3f317217, v8
	v_cmp_lt_f32_e64 s[0:1], |v8|, s66
	v_mul_f32_e32 v13, 0x3fb8aa3b, v13
	v_mul_f32_e32 v14, 0x3fb8aa3b, v14
	v_cndmask_b32_e64 v8, v8, v16, s[0:1]
	v_cndmask_b32_e32 v16, 0, v179, vcc
	v_cmp_gt_f32_e32 vcc, s65, v9
	v_sub_f32_e32 v8, v8, v16
	v_sub_f32_e32 v8, -0.5, v8
	v_cndmask_b32_e64 v16, 0, 32, vcc
	v_ldexp_f32 v9, v9, v16
	v_log_f32_e32 v9, v9
	v_mul_f32_e32 v8, 0x3fb8aa3b, v8
	v_exp_f32_e32 v8, v8
	v_mul_f32_e32 v15, 0x3fb8aa3b, v15
	v_mul_f32_e32 v16, 0x3f317217, v9
	v_fma_f32 v16, v9, s61, -v16
	v_fmac_f32_e32 v16, 0x3377d1cf, v9
	v_fmac_f32_e32 v16, 0x3f317217, v9
	v_cmp_lt_f32_e64 s[0:1], |v9|, s66
	v_mul_f32_e32 v8, 0xbfb8aa3b, v8
	v_exp_f32_e32 v12, v12
	v_cndmask_b32_e64 v9, v9, v16, s[0:1]
	v_cndmask_b32_e32 v16, 0, v179, vcc
	v_sub_f32_e32 v9, v9, v16
	v_cmp_gt_f32_e32 vcc, s65, v10
	v_sub_f32_e32 v9, -0.5, v9
	v_mul_f32_e32 v9, 0x3fb8aa3b, v9
	v_cndmask_b32_e64 v16, 0, 32, vcc
	v_ldexp_f32 v10, v10, v16
	v_exp_f32_e32 v9, v9
	v_log_f32_e32 v10, v10
	v_exp_f32_e32 v16, v8
	v_exp_f32_e32 v13, v13
	v_mul_f32_e32 v8, 0xbfb8aa3b, v9
	v_mul_f32_e32 v9, 0x3f317217, v10
	v_fma_f32 v9, v10, s61, -v9
	v_fmac_f32_e32 v9, 0x3377d1cf, v10
	v_fmac_f32_e32 v9, 0x3f317217, v10
	v_cmp_lt_f32_e64 s[0:1], |v10|, s66
	v_exp_f32_e32 v14, v14
	v_exp_f32_e32 v15, v15
	v_cndmask_b32_e64 v9, v10, v9, s[0:1]
	v_cndmask_b32_e32 v10, 0, v179, vcc
	v_sub_f32_e32 v9, v9, v10
	v_add_f32_e32 v10, 1.0, v11
	v_cmp_gt_f32_e32 vcc, s65, v10
	v_sub_f32_e32 v9, -0.5, v9
	v_mul_f32_e32 v9, 0x3fb8aa3b, v9
	v_cndmask_b32_e64 v11, 0, 32, vcc
	v_ldexp_f32 v10, v10, v11
	v_log_f32_e32 v10, v10
	v_exp_f32_e32 v9, v9
	v_mul_f32_e32 v12, 0xbfb8aa3b, v12
	v_mul_f32_e32 v13, 0xbfb8aa3b, v13
	v_mul_f32_e32 v11, 0x3f317217, v10
	v_fma_f32 v11, v10, s61, -v11
	v_fmac_f32_e32 v11, 0x3377d1cf, v10
	v_fmac_f32_e32 v11, 0x3f317217, v10
	v_cmp_lt_f32_e64 s[0:1], |v10|, s66
	v_mul_f32_e32 v14, 0xbfb8aa3b, v14
	v_mul_f32_e32 v15, 0xbfb8aa3b, v15
	v_cndmask_b32_e64 v10, v10, v11, s[0:1]
	v_cndmask_b32_e32 v11, 0, v179, vcc
	v_sub_f32_e32 v10, v10, v11
	v_sub_f32_e32 v10, -0.5, v10
	v_mul_f32_e32 v10, 0x3fb8aa3b, v10
	v_exp_f32_e32 v10, v10
	v_exp_f32_e32 v11, v8
	v_mul_f32_e32 v8, 0xbfb8aa3b, v9
	v_exp_f32_e32 v17, v8
	v_mul_f32_e32 v8, 0xbfb8aa3b, v10
	v_exp_f32_e32 v12, v12
	v_exp_f32_e32 v13, v13
	v_exp_f32_e32 v14, v14
	v_exp_f32_e32 v15, v15
	v_exp_f32_e32 v18, v8
	v_cvt_pk_f16_f32 v8, v12, v13
	v_cvt_pk_f16_f32 v9, v14, v15
	v_cvt_pk_f16_f32 v10, v16, v11
	v_cvt_pk_f16_f32 v11, v17, v18
	global_store_dwordx4 v[72:73], v[8:11], off offset:256 sc1
	v_add_f32_e32 v4, v4, v68
	v_mul_f32_e32 v4, 0xbfb8aa3b, v4
	v_exp_f32_e32 v4, v4
	v_add_f32_e32 v5, v5, v69
	v_mul_f32_e32 v5, 0xbfb8aa3b, v5
	v_exp_f32_e32 v5, v5
	v_add_f32_e32 v4, 1.0, v4
	v_cmp_gt_f32_e32 vcc, s65, v4
	v_add_f32_e32 v6, v6, v70
	v_add_f32_e32 v5, 1.0, v5
	v_cndmask_b32_e64 v8, 0, 32, vcc
	v_ldexp_f32 v4, v4, v8
	v_log_f32_e32 v4, v4
	v_mul_f32_e32 v6, 0xbfb8aa3b, v6
	v_exp_f32_e32 v6, v6
	v_add_f32_e32 v7, v7, v71
	v_mul_f32_e32 v8, 0x3f317217, v4
	v_fma_f32 v8, v4, s61, -v8
	v_fmac_f32_e32 v8, 0x3377d1cf, v4
	v_fmac_f32_e32 v8, 0x3f317217, v4
	v_cmp_lt_f32_e64 s[0:1], |v4|, s66
	v_add_f32_e32 v6, 1.0, v6
	v_mul_f32_e32 v7, 0xbfb8aa3b, v7
	v_cndmask_b32_e64 v4, v4, v8, s[0:1]
	v_cndmask_b32_e32 v8, 0, v179, vcc
	v_cmp_gt_f32_e32 vcc, s65, v5
	v_sub_f32_e32 v4, v4, v8
	v_exp_f32_e32 v7, v7
	v_cndmask_b32_e64 v8, 0, 32, vcc
	v_ldexp_f32 v5, v5, v8
	v_log_f32_e32 v5, v5
	v_add_f32_e32 v7, 1.0, v7
	v_add_f32_e32 v0, v0, v64
	v_mul_f32_e32 v0, 0xbfb8aa3b, v0
	v_mul_f32_e32 v8, 0x3f317217, v5
	v_fma_f32 v8, v5, s61, -v8
	v_fmac_f32_e32 v8, 0x3377d1cf, v5
	v_fmac_f32_e32 v8, 0x3f317217, v5
	v_cmp_lt_f32_e64 s[0:1], |v5|, s66
	v_exp_f32_e32 v0, v0
	v_add_f32_e32 v1, v1, v65
	v_cndmask_b32_e64 v5, v5, v8, s[0:1]
	v_cndmask_b32_e32 v8, 0, v179, vcc
	v_cmp_gt_f32_e32 vcc, s65, v6
;     template <int MODE> __device__ __forceinline__ void run(AccRef acc, const Unit& u, int wr, int wc, int fr, int fq) const {
;     ...
;             for (int ai = 0; ai < 2; ++ai)
; #pragma unroll
;                 for (int m = 0; m < 4; ++m) {
;                     const int row = row0 + ai * 128 + m * 16;
;                     float x[8];
; #pragma unroll
;                     for (int e = 0; e < 4; ++e) { x[e] = acc[ai][bj][m][0][e] + bias[e]; x[4 + e] = acc[ai][bj][m][1][e] + bias[4 + e]; }
;                     u32x4 w;
;                     if (MODE == 0) {
; #pragma unroll
;                         for (int e = 0; e < 8; ++e) { const float sp = __logf(1.f + __expf(-x[e])); x[e] = __expf(-__expf(-sp - 0.5f)); }
;                         w.x = pkh(x[0], x[1]); w.y = pkh(x[2], x[3]); w.z = pkh(x[4], x[5]); w.w = pkh(x[6], x[7]);
;                         *(u32x4*)(WA + (size_t)row * 2048 + seg * 512 + cc) = w;
	v_sub_f32_e32 v5, v5, v8
	v_add_f32_e32 v0, 1.0, v0
	v_cndmask_b32_e64 v8, 0, 32, vcc
	v_ldexp_f32 v6, v6, v8
	v_log_f32_e32 v6, v6
	v_mul_f32_e32 v1, 0xbfb8aa3b, v1
	v_exp_f32_e32 v1, v1
	v_add_f32_e32 v2, v2, v66
	v_mul_f32_e32 v8, 0x3f317217, v6
	v_fma_f32 v8, v6, s61, -v8
	v_fmac_f32_e32 v8, 0x3377d1cf, v6
	v_fmac_f32_e32 v8, 0x3f317217, v6
	v_cmp_lt_f32_e64 s[0:1], |v6|, s66
	v_add_f32_e32 v1, 1.0, v1
	v_mul_f32_e32 v2, 0xbfb8aa3b, v2
	v_cndmask_b32_e64 v6, v6, v8, s[0:1]
	v_cndmask_b32_e32 v8, 0, v179, vcc
	v_cmp_gt_f32_e32 vcc, s65, v7
	v_sub_f32_e32 v6, v6, v8
	v_exp_f32_e32 v2, v2
	v_cndmask_b32_e64 v8, 0, 32, vcc
	v_ldexp_f32 v7, v7, v8
	v_log_f32_e32 v7, v7
	v_add_f32_e32 v2, 1.0, v2
	v_add_f32_e32 v3, v3, v67
	v_mul_f32_e32 v3, 0xbfb8aa3b, v3
	v_mul_f32_e32 v8, 0x3f317217, v7
	v_fma_f32 v8, v7, s61, -v8
	v_fmac_f32_e32 v8, 0x3377d1cf, v7
	v_fmac_f32_e32 v8, 0x3f317217, v7
	v_cmp_lt_f32_e64 s[0:1], |v7|, s66
	v_exp_f32_e32 v3, v3
	v_sub_f32_e32 v4, -0.5, v4
	v_cndmask_b32_e64 v7, v7, v8, s[0:1]
	v_cndmask_b32_e32 v8, 0, v179, vcc
	v_cmp_gt_f32_e32 vcc, s65, v0
	v_sub_f32_e32 v7, v7, v8
	v_sub_f32_e32 v5, -0.5, v5
	v_cndmask_b32_e64 v8, 0, 32, vcc
	v_ldexp_f32 v0, v0, v8
	v_log_f32_e32 v0, v0
	v_sub_f32_e32 v6, -0.5, v6
	v_sub_f32_e32 v7, -0.5, v7
	v_mul_f32_e32 v4, 0x3fb8aa3b, v4
	v_mul_f32_e32 v8, 0x3f317217, v0
	v_fma_f32 v8, v0, s61, -v8
	v_fmac_f32_e32 v8, 0x3377d1cf, v0
	v_fmac_f32_e32 v8, 0x3f317217, v0
	v_cmp_lt_f32_e64 s[0:1], |v0|, s66
	v_mul_f32_e32 v5, 0x3fb8aa3b, v5
	v_mul_f32_e32 v6, 0x3fb8aa3b, v6
	v_cndmask_b32_e64 v0, v0, v8, s[0:1]
	v_cndmask_b32_e32 v8, 0, v179, vcc
	v_cmp_gt_f32_e32 vcc, s65, v1
	v_sub_f32_e32 v0, v0, v8
	v_sub_f32_e32 v0, -0.5, v0
	v_cndmask_b32_e64 v8, 0, 32, vcc
	v_ldexp_f32 v1, v1, v8
	v_log_f32_e32 v1, v1
	v_mul_f32_e32 v0, 0x3fb8aa3b, v0
	v_exp_f32_e32 v0, v0
	v_mul_f32_e32 v7, 0x3fb8aa3b, v7
	v_mul_f32_e32 v8, 0x3f317217, v1
	v_fma_f32 v8, v1, s61, -v8
	v_fmac_f32_e32 v8, 0x3377d1cf, v1
	v_fmac_f32_e32 v8, 0x3f317217, v1
	v_cmp_lt_f32_e64 s[0:1], |v1|, s66
	v_mul_f32_e32 v0, 0xbfb8aa3b, v0
	v_exp_f32_e32 v4, v4
	v_cndmask_b32_e64 v1, v1, v8, s[0:1]
	v_cndmask_b32_e32 v8, 0, v179, vcc
	v_sub_f32_e32 v1, v1, v8
	v_cmp_gt_f32_e32 vcc, s65, v2
	v_sub_f32_e32 v1, -0.5, v1
	v_mul_f32_e32 v1, 0x3fb8aa3b, v1
	v_cndmask_b32_e64 v8, 0, 32, vcc
	v_ldexp_f32 v2, v2, v8
	v_exp_f32_e32 v1, v1
	v_log_f32_e32 v2, v2
	v_exp_f32_e32 v8, v0
	v_exp_f32_e32 v5, v5
	v_mul_f32_e32 v0, 0xbfb8aa3b, v1
	v_mul_f32_e32 v1, 0x3f317217, v2
	v_fma_f32 v1, v2, s61, -v1
	v_fmac_f32_e32 v1, 0x3377d1cf, v2
	v_fmac_f32_e32 v1, 0x3f317217, v2
	v_cmp_lt_f32_e64 s[0:1], |v2|, s66
	v_exp_f32_e32 v6, v6
	v_exp_f32_e32 v7, v7
	v_cndmask_b32_e64 v1, v2, v1, s[0:1]
	v_cndmask_b32_e32 v2, 0, v179, vcc
	v_sub_f32_e32 v1, v1, v2
	v_add_f32_e32 v2, 1.0, v3
	v_cmp_gt_f32_e32 vcc, s65, v2
	v_sub_f32_e32 v1, -0.5, v1
	v_mul_f32_e32 v1, 0x3fb8aa3b, v1
	v_cndmask_b32_e64 v3, 0, 32, vcc
	v_ldexp_f32 v2, v2, v3
	v_log_f32_e32 v2, v2
	v_exp_f32_e32 v1, v1
	v_mul_f32_e32 v4, 0xbfb8aa3b, v4
	v_mul_f32_e32 v5, 0xbfb8aa3b, v5
	v_mul_f32_e32 v3, 0x3f317217, v2
	v_fma_f32 v3, v2, s61, -v3
	v_fmac_f32_e32 v3, 0x3377d1cf, v2
	v_fmac_f32_e32 v3, 0x3f317217, v2
	v_cmp_lt_f32_e64 s[0:1], |v2|, s66
	v_mul_f32_e32 v6, 0xbfb8aa3b, v6
	v_mul_f32_e32 v7, 0xbfb8aa3b, v7
	v_cndmask_b32_e64 v2, v2, v3, s[0:1]
	v_cndmask_b32_e32 v3, 0, v179, vcc
	v_sub_f32_e32 v2, v2, v3
	v_sub_f32_e32 v2, -0.5, v2
	v_mul_f32_e32 v2, 0x3fb8aa3b, v2
	v_exp_f32_e32 v2, v2
	v_exp_f32_e32 v3, v0
	v_mul_f32_e32 v0, 0xbfb8aa3b, v1
	v_exp_f32_e32 v9, v0
	v_mul_f32_e32 v0, 0xbfb8aa3b, v2
	v_exp_f32_e32 v4, v4
	v_exp_f32_e32 v5, v5
	v_exp_f32_e32 v6, v6
	v_exp_f32_e32 v7, v7
	v_exp_f32_e32 v10, v0
	v_cvt_pk_f16_f32 v0, v4, v5
	v_cvt_pk_f16_f32 v1, v6, v7
	v_cvt_pk_f16_f32 v2, v8, v3
	v_cvt_pk_f16_f32 v3, v9, v10
	global_store_dwordx4 v[74:75], v[0:3], off offset:256 sc1
	s_and_b64 vcc, exec, s[6:7]
	s_mov_b64 s[0:1], -1
	s_cbranch_vccnz .LBB0_862

; __device__ __forceinline__ void unpack8bf(const u32x4 w, float* f) { f[0] = bflo(w.x); f[1] = bfhi(w.x); f[2] = bflo(w.y); f[3] = bfhi(w.y); f[4] = bflo(w.z); f[5] = bfhi(w.z); f[6] = bflo(w.w); f[7] = bfhi(w.w); }
; __device__ __forceinline__ float sum8(float v) { v += __shfl_xor(v, 1); v += __shfl_xor(v, 2); v += __shfl_xor(v, 4); return v; }
; __device__ __forceinline__ void p10_row(const P& p, int row, int lane) {
;     ...
;     { const int c = lane * 8; const int pos = seq_pos(row), L = row < TP ? 8192 : 16384; const bool hasp = pos > 0, hasn = pos < L - 1;
;       const float* mu = p.in[13];
;       const bf16_t* zr = (const bf16_t*)(ws + WS_ZRKV) + (size_t)row * 1536 + c;
;       float v[8];
;       shift8(zr + 1024, 1536, hasp, hasn, mu + 1024 + c, mu + 1920 + 1024 + c, v);
;       float g[8]; unpack8bf(*(const u32x4*)(mix + 512 + c), g);
;       const bf16_t* yp = (const bf16_t*)(ws + WS_Y) + (size_t)row * 512 + c;
;       float y[8], yb2[8]; unpack8bf(*(const u32x4*)yp, y); unpack8bf(*(const u32x4*)(yp + (size_t)T * 512), yb2);
; #pragma unroll
;       for (int e = 0; e < 8; ++e) y[e] += yb2[e];
;       float s = 0.f;
; #pragma unroll
;       for (int e = 0; e < 8; ++e) s += y[e];
;       const float mean = sum8(s) * (1.f / 64.f); float q = 0.f;
; #pragma unroll
;       for (int e = 0; e < 8; ++e) { y[e] -= mean; q += y[e] * y[e]; }
;       const float rstd = 1.0f / sqrtf(sum8(q) * (1.f / 64.f) + LNX_EPS);
;       const float* lw = p.in[22] + c; const float* lb = p.in[23] + c;
;       const float* bsp = (const float*)(ws + WS_BS) + (size_t)row * 8 + (lane >> 3);
;       const float bs = bsp[0] + bsp[(size_t)T * 8];
.LBB0_1169:
	v_lshl_add_u64 v[6:7], s[50:51], 0, v[38:39]
	v_add_co_u32_e32 v8, vcc, s16, v6
	global_load_dwordx4 v[64:67], v[30:31], off
	global_load_dwordx4 v[68:71], v[28:29], off
	global_load_dwordx4 v[14:17], v[30:31], off offset:16
	global_load_dwordx4 v[10:13], v[28:29], off offset:16
	v_addc_co_u32_e32 v9, vcc, 0, v7, vcc
	v_add_co_u32_e32 v6, vcc, s17, v6
	s_waitcnt vmcnt(4)
	v_lshlrev_b32_e32 v47, 16, v23
	v_addc_co_u32_e32 v7, vcc, 0, v7, vcc
	global_load_dwordx4 v[72:75], v[6:7], off
	global_load_dwordx4 v[76:79], v[8:9], off
	v_add_co_u32_e32 v44, vcc, s3, v4
	v_lshlrev_b32_e32 v8, 16, v22
	s_nop 0
	v_addc_co_u32_e32 v45, vcc, 0, v5, vcc
	global_load_dwordx4 v[4:7], v[44:45], off offset:1024
	v_and_b32_e32 v9, 0xffff0000, v22
	v_and_b32_e32 v51, 0xffff0000, v23
	v_lshlrev_b32_e32 v63, 16, v24
	v_and_b32_e32 v80, 0xffff0000, v24
	v_lshlrev_b32_e32 v83, 16, v0
	v_lshlrev_b32_e32 v24, 16, v18
	v_and_b32_e32 v23, 0xffff0000, v18
	v_and_b32_e32 v22, 0xffff0000, v0
	v_lshlrev_b32_e32 v84, 16, v1
	v_and_b32_e32 v18, 0xffff0000, v1
	v_lshl_add_u64 v[0:1], s[50:51], 0, v[36:37]
	v_lshlrev_b32_e32 v50, 16, v20
	v_and_b32_e32 v49, 0xffff0000, v20
	v_lshlrev_b32_e32 v20, 16, v21
	v_and_b32_e32 v81, 0xffff0000, v21
	v_sub_f32_e32 v21, v8, v24
	v_add_co_u32_e32 v8, vcc, s18, v0
	v_sub_f32_e32 v86, v9, v23
	s_nop 0
	v_addc_co_u32_e32 v9, vcc, 0, v1, vcc
	v_lshlrev_b32_e32 v85, 16, v2
	v_and_b32_e32 v48, 0xffff0000, v2
	v_add_co_u32_e32 v0, vcc, s19, v0
	v_sub_f32_e32 v63, v63, v50
	v_sub_f32_e32 v85, v85, v50
	v_sub_f32_e32 v93, v48, v49
	v_addc_co_u32_e32 v1, vcc, 0, v1, vcc
	global_load_dword v99, v[8:9], off
	s_nop 0
	global_load_dword v1, v[0:1], off
	v_lshlrev_b32_e32 v2, 16, v3
	v_lshlrev_b32_e32 v46, 16, v19
	v_and_b32_e32 v19, 0xffff0000, v19
	v_sub_f32_e32 v2, v2, v20
	v_lshlrev_b32_e32 v82, 16, v25
	v_sub_f32_e32 v47, v47, v46
	v_sub_f32_e32 v51, v51, v19
	v_sub_f32_e32 v89, v84, v46
	v_sub_f32_e32 v95, v82, v20
	v_sub_f32_e32 v80, v80, v49
	v_cmp_lt_i32_e32 vcc, v57, v56
	v_sub_f32_e32 v83, v83, v24
	v_sub_f32_e32 v87, v22, v23
	v_sub_f32_e32 v91, v18, v19
	v_and_b32_e32 v25, 0xffff0000, v25
	s_add_i32 s20, s20, s88
	v_lshl_add_u64 v[36:37], v[36:37], 0, s[4:5]
	v_lshl_add_u64 v[38:39], v[38:39], 0, s[8:9]
	v_lshl_add_u64 v[40:41], v[40:41], 0, s[10:11]
	s_cmp_gt_i32 s20, 0xbfff
	v_lshl_add_u64 v[42:43], v[42:43], 0, s[12:13]
	s_waitcnt vmcnt(8)
	v_mul_f32_e32 v82, v21, v64
	v_mul_f32_e32 v84, v86, v65
	s_waitcnt vmcnt(6)
	v_mul_f32_e32 v96, v63, v14
	s_waitcnt vmcnt(5)
	v_mul_f32_e32 v98, v85, v10
	v_mul_f32_e32 v14, v93, v11
	v_mul_f32_e32 v2, v2, v12
	v_mul_f32_e32 v88, v47, v66
	v_mul_f32_e32 v92, v51, v67
	v_mul_f32_e32 v100, v80, v15
	v_mul_f32_e32 v0, v68, v83
	s_waitcnt vmcnt(4)
	v_lshlrev_b32_e32 v9, 16, v72
	s_waitcnt vmcnt(3)
	v_lshlrev_b32_e32 v11, 16, v76
	v_and_b32_e32 v8, 0xffff0000, v72
	v_and_b32_e32 v10, 0xffff0000, v76
	v_pk_add_f32 v[102:103], v[10:11], v[8:9]
	v_lshlrev_b32_e32 v9, 16, v73
	v_lshlrev_b32_e32 v11, 16, v77
	v_and_b32_e32 v8, 0xffff0000, v73
	v_and_b32_e32 v10, 0xffff0000, v77
	v_pk_add_f32 v[76:77], v[10:11], v[8:9]
	v_lshlrev_b32_e32 v9, 16, v74
	v_lshlrev_b32_e32 v11, 16, v78
	v_and_b32_e32 v8, 0xffff0000, v74
	v_and_b32_e32 v10, 0xffff0000, v78
	v_pk_add_f32 v[104:105], v[10:11], v[8:9]
	global_load_dwordx4 v[8:11], v[32:33], off offset:16
	v_add_f32_e32 v12, 0, v103
	v_lshlrev_b32_e32 v65, 16, v75
	v_lshlrev_b32_e32 v67, 16, v79
	v_and_b32_e32 v64, 0xffff0000, v75
	v_and_b32_e32 v66, 0xffff0000, v79
	v_add_f32_e32 v12, v102, v12
	v_pk_add_f32 v[78:79], v[66:67], v[64:65]
	v_add_f32_e32 v12, v77, v12
	global_load_dwordx4 v[64:67], v[32:33], off
	v_add_f32_e32 v12, v76, v12
	v_add_f32_e32 v12, v105, v12
	v_add_f32_e32 v12, v104, v12
	v_add_f32_e32 v12, v79, v12
	v_add_f32_e32 v15, v78, v12
	v_cndmask_b32_e32 v12, v54, v57, vcc
	v_lshlrev_b32_e32 v63, 2, v12
	ds_bpermute_b32 v21, v63, v15
	v_mul_f32_e32 v86, v87, v69
	v_mul_f32_e32 v90, v89, v70
	v_mul_f32_e32 v94, v91, v71
	global_load_dwordx4 v[68:71], v[34:35], off offset:16
	global_load_dwordx4 v[72:75], v[34:35], off
	v_and_b32_e32 v80, 0xffff0000, v3
	v_sub_f32_e32 v3, v25, v81
	v_cmp_lt_i32_e32 vcc, v58, v56
	v_mul_f32_e32 v12, v3, v17
	s_waitcnt lgkmcnt(0)
	v_add_f32_e32 v15, v15, v21
	v_cndmask_b32_e32 v17, v54, v58, vcc
	v_lshlrev_b32_e32 v83, 2, v17
	ds_bpermute_b32 v17, v83, v15
	v_sub_f32_e32 v3, v80, v81
	v_cmp_lt_i32_e32 vcc, v59, v56
	v_mul_f32_e32 v106, v3, v13
	s_waitcnt vmcnt(6)
	v_lshlrev_b32_e32 v3, 16, v4
	v_cndmask_b32_e32 v13, v54, v59, vcc
	v_and_b32_e32 v91, 0xffff0000, v4
	s_waitcnt lgkmcnt(0)
	v_add_f32_e32 v4, v15, v17
	v_lshlrev_b32_e32 v15, 2, v13
	ds_bpermute_b32 v13, v15, v4
	v_mul_f32_e32 v16, v95, v16
	v_mov_b32_e32 v17, v79
	v_lshlrev_b32_e32 v93, 16, v5
	v_and_b32_e32 v107, 0xffff0000, v5
	s_waitcnt lgkmcnt(0)
	v_add_f32_e32 v4, v4, v13
	v_mul_f32_e32 v21, 0x3c800000, v4
	v_pk_add_f32 v[4:5], v[16:17], v[20:21]
	v_pk_add_f32 v[16:17], v[16:17], v[20:21] neg_lo:[0,1] neg_hi:[0,1]
	v_mov_b32_e32 v13, v78
	v_mov_b32_e32 v20, v81
	v_pk_add_f32 v[78:79], v[12:13], v[20:21] neg_lo:[0,1] neg_hi:[0,1]
	v_mov_b32_e32 v101, v104
	v_mov_b32_e32 v20, v49
	v_mov_b32_e32 v97, v105
	v_pk_add_f32 v[104:105], v[100:101], v[20:21] neg_lo:[0,1] neg_hi:[0,1]
	v_mov_b32_e32 v20, v19
	v_mov_b32_e32 v25, v21
	v_pk_add_f32 v[116:117], v[76:77], v[20:21] op_sel_hi:[0,1] neg_lo:[0,1] neg_hi:[0,1]
	v_pk_add_f32 v[118:119], v[102:103], v[24:25] neg_lo:[0,1] neg_hi:[0,1]
	v_mov_b32_e32 v20, v23
	v_lshlrev_b32_e32 v120, 16, v6
	v_and_b32_e32 v121, 0xffff0000, v6
	v_mov_b32_e32 v51, v21
	v_mov_b32_e32 v47, v21
	v_pk_add_f32 v[20:21], v[102:103], v[20:21] op_sel_hi:[0,1] neg_lo:[0,1] neg_hi:[0,1]
	v_mul_f32_e32 v6, v119, v119
	v_pk_add_f32 v[110:111], v[96:97], v[50:51] neg_lo:[0,1] neg_hi:[0,1]
	v_pk_add_f32 v[114:115], v[76:77], v[46:47] neg_lo:[0,1] neg_hi:[0,1]
	v_fmac_f32_e32 v6, v21, v21
	v_mov_b32_e32 v112, v105
	v_mov_b32_e32 v113, v111
	v_fmac_f32_e32 v6, v115, v115
	v_pk_mul_f32 v[112:113], v[112:113], v[112:113]
	v_fmac_f32_e32 v6, v117, v117
	v_mov_b32_e32 v108, v79
	v_mov_b32_e32 v109, v17
	v_add_f32_e32 v6, v113, v6
	v_pk_mul_f32 v[108:109], v[108:109], v[108:109]
	v_add_f32_e32 v6, v112, v6
	v_add_f32_e32 v6, v109, v6
	v_add_f32_e32 v76, v108, v6
	ds_bpermute_b32 v63, v63, v76
	s_waitcnt vmcnt(4)
; __device__ __forceinline__ unsigned pkbf(float lo, float hi) { return pg8::cvt_pk_bf16(lo, hi); }
; __device__ __forceinline__ float sum8(float v) { v += __shfl_xor(v, 1); v += __shfl_xor(v, 2); v += __shfl_xor(v, 4); return v; }
; __device__ __forceinline__ void p10_row(const P& p, int row, int lane) {
;     ...
;       const float mean = sum8(s) * (1.f / 64.f); float q = 0.f;
; #pragma unroll
;       for (int e = 0; e < 8; ++e) { y[e] -= mean; q += y[e] * y[e]; }
;       const float rstd = 1.0f / sqrtf(sum8(q) * (1.f / 64.f) + LNX_EPS);
;       const float* lw = p.in[22] + c; const float* lb = p.in[23] + c;
;       const float* bsp = (const float*)(ws + WS_BS) + (size_t)row * 8 + (lane >> 3);
;       const float bs = bsp[0] + bsp[(size_t)T * 8];
;       float o[8];
; #pragma unroll
;       for (int e = 0; e < 8; ++e) o[e] = (y[e] * rstd * lw[e] + lb[e] + bs * v[e]) * g[e];
;       u32x4 w; w.x = pkbf(o[0], o[1]); w.y = pkbf(o[2], o[3]); w.z = pkbf(o[4], o[5]); w.w = pkbf(o[6], o[7]);
;       *(u32x4*)(mix + 512 + c) = w; }
	v_add_f32_e32 v6, v99, v1
	v_lshlrev_b32_e32 v122, 16, v7
	v_and_b32_e32 v102, 0xffff0000, v7
	s_waitcnt vmcnt(3)
	v_mov_b32_e32 v7, v10
	s_waitcnt lgkmcnt(0)
	v_add_f32_e32 v1, v76, v63
	ds_bpermute_b32 v10, v83, v1
	v_pk_add_f32 v[12:13], v[12:13], v[80:81] op_sel:[0,1] op_sel_hi:[1,0]
	v_mov_b32_e32 v81, v8
	v_mov_b32_e32 v83, v103
	v_pk_add_f32 v[24:25], v[82:83], v[24:25]
	s_waitcnt lgkmcnt(0)
	v_add_f32_e32 v1, v1, v10
	ds_bpermute_b32 v8, v15, v1
	s_waitcnt vmcnt(2)
	v_mov_b32_e32 v83, v64
	v_pk_add_f32 v[22:23], v[84:85], v[22:23] op_sel:[0,1] op_sel_hi:[1,0]
	v_mov_b32_e32 v82, v6
	v_mov_b32_e32 v89, v77
	s_waitcnt lgkmcnt(0)
	v_add_f32_e32 v1, v1, v8
	v_fmamk_f32 v1, v1, 0x3c800000, v55
	v_mul_f32_e32 v8, 0x4f800000, v1
	v_cmp_gt_f32_e32 vcc, s14, v1
	v_pk_add_f32 v[46:47], v[88:89], v[46:47]
	v_mov_b32_e32 v76, v6
	v_cndmask_b32_e32 v1, v1, v8, vcc
	v_sqrt_f32_e32 v8, v1
	v_mov_b32_e32 v77, v66
	v_pk_add_f32 v[18:19], v[92:93], v[18:19] op_sel:[0,1] op_sel_hi:[1,0]
	v_mov_b32_e32 v66, v6
	v_add_u32_e32 v10, -1, v8
	v_fma_f32 v15, -v10, v8, v1
	v_cmp_ge_f32_e64 s[0:1], 0, v15
	v_add_u32_e32 v15, 1, v8
	v_pk_add_f32 v[50:51], v[96:97], v[50:51]
	v_cndmask_b32_e64 v10, v8, v10, s[0:1]
	v_fma_f32 v8, -v15, v8, v1
	v_cmp_lt_f32_e64 s[0:1], 0, v8
	v_mov_b32_e32 v80, v6
	v_pk_add_f32 v[48:49], v[100:101], v[48:49] op_sel:[0,1] op_sel_hi:[1,0]
	v_cndmask_b32_e64 v8, v10, v15, s[0:1]
	v_mul_f32_e32 v10, 0x37800000, v8
	v_cndmask_b32_e32 v8, v8, v10, vcc
	v_cmp_class_f32_e32 vcc, v1, v53
	s_nop 1
	v_cndmask_b32_e32 v1, v8, v1, vcc
	v_div_scale_f32 v8, s[0:1], v1, v1, 1.0
	v_rcp_f32_e32 v10, v8
	s_nop 0
	v_fma_f32 v15, -v8, v10, 1.0
	v_fmac_f32_e32 v10, v15, v10
	v_div_scale_f32 v15, vcc, 1.0, v1, 1.0
	v_mul_f32_e32 v63, v15, v10
	v_fma_f32 v64, -v8, v63, v15
	v_fmac_f32_e32 v63, v64, v10
	v_fma_f32 v8, -v8, v63, v15
	v_div_fmas_f32 v8, v8, v10, v63
	v_div_fixup_f32 v1, v8, v1, 1.0
	v_pk_add_f32 v[24:25], v[24:25], v[0:1]
	v_pk_mul_f32 v[84:85], v[118:119], v[0:1]
	v_mov_b32_e32 v87, v1
	v_mov_b32_e32 v25, v85
	v_pk_mul_f32 v[24:25], v[82:83], v[24:25]
	v_pk_add_f32 v[22:23], v[22:23], v[86:87]
	v_pk_mul_f32 v[20:21], v[20:21], v[86:87]
	s_waitcnt vmcnt(0)
	v_add_f32_e32 v0, v72, v25
	v_mov_b32_e32 v23, v21
	v_mov_b32_e32 v64, v6
	v_add_f32_e32 v0, v24, v0
	v_pk_mul_f32 v[20:21], v[64:65], v[22:23]
	v_mul_f32_e32 v10, v0, v3
	v_add_f32_e32 v0, v73, v21
	v_add_f32_e32 v0, v20, v0
	v_mul_f32_e32 v24, v0, v91
	v_mov_b32_e32 v91, v1
	v_pk_add_f32 v[20:21], v[46:47], v[90:91]
	v_pk_mul_f32 v[22:23], v[114:115], v[90:91]
	v_mov_b32_e32 v95, v1
	v_mov_b32_e32 v21, v23
	v_pk_mul_f32 v[20:21], v[76:77], v[20:21]
	v_pk_add_f32 v[18:19], v[18:19], v[94:95]
	v_add_f32_e32 v0, v74, v21
	v_add_f32_e32 v0, v20, v0
	v_pk_mul_f32 v[20:21], v[116:117], v[94:95]
	v_mul_f32_e32 v22, v0, v93
	v_mov_b32_e32 v19, v21
	v_pk_mul_f32 v[18:19], v[66:67], v[18:19]
	v_mov_b32_e32 v99, v1
	v_add_f32_e32 v0, v75, v19
	v_add_f32_e32 v0, v18, v0
	v_pk_add_f32 v[18:19], v[50:51], v[98:99]
	v_pk_mul_f32 v[20:21], v[110:111], v[98:99]
	v_mul_f32_e32 v23, v0, v107
	v_mov_b32_e32 v19, v21
	v_pk_mul_f32 v[18:19], v[80:81], v[18:19]
	v_mov_b32_e32 v15, v1
	v_add_f32_e32 v0, v68, v19
	v_add_f32_e32 v0, v18, v0
	v_pk_add_f32 v[18:19], v[48:49], v[14:15]
	v_pk_mul_f32 v[14:15], v[104:105], v[14:15]
	v_mov_b32_e32 v8, v6
	v_mov_b32_e32 v19, v15
	v_mov_b32_e32 v3, v1
	v_pk_mul_f32 v[8:9], v[8:9], v[18:19]
	v_pk_add_f32 v[4:5], v[4:5], v[2:3]
	v_pk_mul_f32 v[2:3], v[16:17], v[2:3]
	v_mul_f32_e32 v20, v0, v120
	v_add_f32_e32 v0, v69, v9
	v_mov_b32_e32 v5, v3
	v_add_f32_e32 v0, v8, v0
	v_pk_mul_f32 v[2:3], v[6:7], v[4:5]
	v_mul_f32_e32 v8, v0, v121
	v_add_f32_e32 v0, v70, v3
	v_add_f32_e32 v0, v2, v0
	v_mov_b32_e32 v107, v1
	v_mul_f32_e32 v4, v0, v122
	v_pk_add_f32 v[0:1], v[12:13], v[106:107]
	v_pk_mul_f32 v[2:3], v[78:79], v[106:107]
	v_mov_b32_e32 v7, v11
	v_mov_b32_e32 v1, v3
	v_pk_mul_f32 v[0:1], v[6:7], v[0:1]
	s_nop 0
	v_add_f32_e32 v1, v71, v1
	v_add_f32_e32 v0, v0, v1
	v_mul_f32_e32 v3, v0, v102
	v_cvt_pk_bf16_f32 v0, v10, v24
	v_cvt_pk_bf16_f32 v1, v22, v23
	v_cvt_pk_bf16_f32 v2, v20, v8
	v_cvt_pk_bf16_f32 v3, v4, v3
	global_store_dwordx4 v[44:45], v[0:3], off offset:1024 sc1
	s_cbranch_scc1 .LBB0_1177
; __device__ __forceinline__ unsigned pkbf(float lo, float hi) { return pg8::cvt_pk_bf16(lo, hi); }
; __device__ __forceinline__ void unpack8bf(const u32x4 w, float* f) { f[0] = bflo(w.x); f[1] = bfhi(w.x); f[2] = bflo(w.y); f[3] = bfhi(w.y); f[4] = bflo(w.z); f[5] = bfhi(w.z); f[6] = bflo(w.w); f[7] = bfhi(w.w); }
; __device__ __forceinline__ void p10_att_row(const P& p, int row, int lane) {
;     unsigned char* ws = p.ws;
;     bf16_t* mix = (bf16_t*)(ws + WS_MIX) + (size_t)row * 1024;
;     { u32x4* q = (u32x4*)(mix + lane * 8); const u32x4 w = *q; float f[8]; unpack8bf(w, f); float s = 0.f;
; #pragma unroll
;       for (int e = 0; e < 8; ++e) s += f[e] * f[e];
;       const float rstd = 1.0f / sqrtf(wave_sum(s) * (1.f / 512.f) + NORM_EPS); const float* g = p.in[12] + lane * 8;
; #pragma unroll
;       for (int e = 0; e < 8; ++e) f[e] = f[e] * rstd * g[e];
;       u32x4 o; o.x = pkbf(f[0], f[1]); o.y = pkbf(f[2], f[3]); o.z = pkbf(f[4], f[5]); o.w = pkbf(f[6], f[7]); *q = o; }
; }
.LBB0_1170:
	s_and_b64 vcc, exec, s[6:7]
	v_lshl_add_u64 v[4:5], s[50:51], 0, v[40:41]
	s_cbranch_vccnz .LBB0_1172
	v_add_co_u32_e32 v10, vcc, 0x12000000, v4
	global_load_dwordx4 v[6:9], v[26:27], off
	s_nop 0
	v_addc_co_u32_e32 v11, vcc, 0, v5, vcc
	global_load_dwordx4 v[0:3], v[10:11], off
	v_cmp_lt_i32_e32 vcc, v57, v56
	s_waitcnt vmcnt(0)
	v_lshlrev_b32_e32 v13, 16, v0
	v_and_b32_e32 v14, 0xffff0000, v0
	v_lshlrev_b32_e32 v15, 16, v1
	v_and_b32_e32 v16, 0xffff0000, v1
	v_lshlrev_b32_e32 v17, 16, v2
	v_and_b32_e32 v18, 0xffff0000, v2
	v_lshlrev_b32_e32 v19, 16, v3
	v_and_b32_e32 v20, 0xffff0000, v3
	global_load_dwordx4 v[0:3], v[26:27], off offset:16
	v_mul_f32_e32 v21, v14, v14
	v_fmac_f32_e32 v21, v13, v13
	v_fmac_f32_e32 v21, v15, v15
	v_fmac_f32_e32 v21, v16, v16
	v_fmac_f32_e32 v21, v17, v17
	v_fmac_f32_e32 v21, v18, v18
	v_cndmask_b32_e32 v12, v54, v57, vcc
	v_fmac_f32_e32 v21, v19, v19
	v_lshlrev_b32_e32 v12, 2, v12
	v_fmac_f32_e32 v21, v20, v20
	ds_bpermute_b32 v12, v12, v21
	v_cmp_lt_i32_e32 vcc, v58, v56
	s_waitcnt lgkmcnt(0)
	v_add_f32_e32 v12, v21, v12
	v_cndmask_b32_e32 v22, v54, v58, vcc
	v_lshlrev_b32_e32 v22, 2, v22
	ds_bpermute_b32 v21, v22, v12
	v_cmp_lt_i32_e32 vcc, v59, v56
	s_waitcnt lgkmcnt(0)
	v_add_f32_e32 v12, v12, v21
	v_cndmask_b32_e32 v22, v54, v59, vcc
	v_lshlrev_b32_e32 v22, 2, v22
	ds_bpermute_b32 v21, v22, v12
	v_cmp_lt_i32_e32 vcc, v60, v56
	s_waitcnt lgkmcnt(0)
	v_add_f32_e32 v12, v12, v21
	v_cndmask_b32_e32 v22, v54, v60, vcc
	v_lshlrev_b32_e32 v22, 2, v22
	ds_bpermute_b32 v21, v22, v12
	v_cmp_lt_i32_e32 vcc, v61, v56
	s_waitcnt lgkmcnt(0)
	v_add_f32_e32 v12, v12, v21
	v_cndmask_b32_e32 v22, v54, v61, vcc
	v_lshlrev_b32_e32 v22, 2, v22
	ds_bpermute_b32 v21, v22, v12
	v_cmp_lt_i32_e32 vcc, v62, v56
	s_waitcnt lgkmcnt(0)
	v_add_f32_e32 v12, v12, v21
	v_cndmask_b32_e32 v22, v54, v62, vcc
	v_lshlrev_b32_e32 v22, 2, v22
	ds_bpermute_b32 v21, v22, v12
	s_waitcnt lgkmcnt(0)
	v_add_f32_e32 v12, v12, v21
	v_fmamk_f32 v12, v12, 0x3b000000, v52
	v_mul_f32_e32 v21, 0x4f800000, v12
	v_cmp_gt_f32_e32 vcc, s14, v12
	s_nop 1
	v_cndmask_b32_e32 v12, v12, v21, vcc
	v_sqrt_f32_e32 v21, v12
	s_nop 0
	v_add_u32_e32 v22, -1, v21
	v_add_u32_e32 v23, 1, v21
	v_fma_f32 v24, -v22, v21, v12
	v_fma_f32 v25, -v23, v21, v12
	v_cmp_ge_f32_e64 s[0:1], 0, v24
	s_nop 1
	v_cndmask_b32_e64 v21, v21, v22, s[0:1]
	v_cmp_lt_f32_e64 s[0:1], 0, v25
	s_nop 1
	v_cndmask_b32_e64 v21, v21, v23, s[0:1]
	v_mul_f32_e32 v22, 0x37800000, v21
	v_cndmask_b32_e32 v21, v21, v22, vcc
	v_cmp_class_f32_e32 vcc, v12, v53
	s_nop 1
	v_cndmask_b32_e32 v12, v21, v12, vcc
	v_div_scale_f32 v21, s[0:1], v12, v12, 1.0
	v_rcp_f32_e32 v22, v21
	v_div_scale_f32 v23, vcc, 1.0, v12, 1.0
	v_fma_f32 v24, -v21, v22, 1.0
	v_fmac_f32_e32 v22, v24, v22
	v_mul_f32_e32 v24, v23, v22
	v_fma_f32 v25, -v21, v24, v23
	v_fmac_f32_e32 v24, v25, v22
	v_fma_f32 v21, -v21, v24, v23
	v_div_fmas_f32 v21, v21, v22, v24
	v_div_fixup_f32 v12, v21, v12, 1.0
	v_mul_f32_e32 v13, v12, v13
	v_mul_f32_e32 v14, v12, v14
	v_mul_f32_e32 v15, v12, v15
	v_mul_f32_e32 v16, v12, v16
	v_mul_f32_e32 v17, v12, v17
	v_mul_f32_e32 v18, v12, v18
	v_mul_f32_e32 v19, v12, v19
	v_mul_f32_e32 v12, v12, v20
	s_waitcnt vmcnt(0)
	v_mul_f32_e32 v3, v3, v12
	v_mul_f32_e32 v6, v6, v13
	v_mul_f32_e32 v7, v7, v14
	v_mul_f32_e32 v8, v8, v15
	v_mul_f32_e32 v9, v9, v16
	v_mul_f32_e32 v13, v0, v17
	v_mul_f32_e32 v14, v1, v18
	v_mul_f32_e32 v15, v2, v19
	v_cvt_pk_bf16_f32 v0, v6, v7
	v_cvt_pk_bf16_f32 v1, v8, v9
	v_cvt_pk_bf16_f32 v2, v13, v14
	v_cvt_pk_bf16_f32 v3, v15, v3
	global_store_dwordx4 v[10:11], v[0:3], off sc1

; __device__ __forceinline__ unsigned pkbf(float lo, float hi) { return pg8::cvt_pk_bf16(lo, hi); }
; __device__ __forceinline__ void unpack8bf(const u32x4 w, float* f) { f[0] = bflo(w.x); f[1] = bfhi(w.x); f[2] = bflo(w.y); f[3] = bfhi(w.y); f[4] = bflo(w.z); f[5] = bfhi(w.z); f[6] = bflo(w.w); f[7] = bfhi(w.w); }
;     __device__ __forceinline__ void operator()(AccRef acc, const Unit& u, int wr, int wc, int fr, int fq) const {
;     ...
;         const int row0 = u.pm * 256 + wr * 64 + fr, col0 = u.pn * 256 + wc * 32 + 8 * fq;
;         const float* xb = (u.pm * 256 < TP) ? xp : xs - (size_t)TP * DM;
; #pragma unroll
;         for (int ai = 0; ai < 2; ++ai)
; #pragma unroll
;             for (int m = 0; m < 4; ++m)
; #pragma unroll
;                 for (int bj = 0; bj < 2; ++bj) {
;                     const size_t off = (size_t)(row0 + ai * 128 + m * 16) * DM + col0 + bj * 128;
;                     const f32x4 x0 = *(const f32x4*)(xb + off), x1 = *(const f32x4*)(xb + off + 4);
;                     const u32x4 dw = *(const u32x4*)(D1 + off); float d[8]; unpack8bf(dw, d);
;                     float o[8];
; #pragma unroll
;                     for (int e = 0; e < 4; ++e) { o[e] = x0[e] + d[e] + acc[ai][bj][m][0][e]; o[4 + e] = x1[e] + d[4 + e] + acc[ai][bj][m][1][e]; }
;                     u32x4 w; w.x = pkbf(o[0], o[1]); w.y = pkbf(o[2], o[3]); w.z = pkbf(o[4], o[5]); w.w = pkbf(o[6], o[7]);
;                     *(u32x4*)(D1 + off) = w;
;                 }
.LBB0_1244:
	v_mov_b32_e32 v147, v148
	v_mov_b32_e32 v146, v129
	s_lshl_b32 s4, s58, 8
	s_add_i32 s4, s4, s68
	v_add_u32_e32 v146, s4, v146
	s_lshl_b32 s4, s78, 8
	s_or_b32 s4, s4, s69
	v_lshl_add_u32 v154, v147, 3, s4
	v_ashrrev_i32_e32 v147, 31, v146
	v_ashrrev_i32_e32 v155, 31, v154
	v_lshlrev_b64 v[146:147], 10, v[146:147]
	v_readlane_b32 s4, v237, 5
	v_lshl_add_u64 v[146:147], v[146:147], 0, v[154:155]
	s_cmpk_lt_i32 s58, 0x80
	v_readlane_b32 s5, v237, 6
	v_lshl_add_u64 v[162:163], v[146:147], 1, s[30:31]
	s_cselect_b32 s5, s5, s72
	s_cselect_b32 s4, s4, s71
	global_load_dwordx4 v[154:157], v[162:163], off
	v_lshl_add_u64 v[172:173], v[146:147], 2, s[4:5]
	global_load_dwordx4 v[158:161], v[172:173], off nt
	global_load_dwordx4 v[168:171], v[172:173], off offset:16 nt
	v_readlane_b32 s10, v237, 11
	v_readlane_b32 s11, v237, 12
	s_mov_b64 s[10:11], 0x4000
	s_and_b64 vcc, exec, s[46:47]
	v_readlane_b32 s6, v237, 7
	v_readlane_b32 s7, v237, 8
	v_readlane_b32 s8, v237, 9
	v_readlane_b32 s9, v237, 10
	v_readlane_b32 s12, v237, 13
	v_readlane_b32 s13, v237, 14
	v_readlane_b32 s14, v237, 15
	v_readlane_b32 s15, v237, 16
	v_readlane_b32 s16, v237, 17
	v_readlane_b32 s17, v237, 18
	v_readlane_b32 s18, v237, 19
	v_readlane_b32 s19, v237, 20
	s_waitcnt vmcnt(0)
	v_lshlrev_b32_e32 v153, 16, v154
	v_and_b32_e32 v154, 0xffff0000, v154
	v_lshlrev_b32_e32 v165, 16, v155
	v_and_b32_e32 v155, 0xffff0000, v155
	v_lshlrev_b32_e32 v166, 16, v156
	v_and_b32_e32 v156, 0xffff0000, v156
	v_lshlrev_b32_e32 v174, 16, v157
	v_and_b32_e32 v157, 0xffff0000, v157
	v_add_f32_e32 v153, v158, v153
	v_add_f32_e32 v158, v168, v166
	v_add_f32_e32 v154, v159, v154
	v_add_f32_e32 v156, v169, v156
	v_add_f32_e32 v159, v160, v165
	v_add_f32_e32 v160, v170, v174
	v_add_f32_e32 v155, v161, v155
	v_add_f32_e32 v157, v171, v157
	v_add_f32_e32 v120, v120, v153
	v_add_f32_e32 v124, v124, v158
	v_add_f32_e32 v121, v121, v154
	v_add_f32_e32 v125, v125, v156
	v_add_f32_e32 v122, v122, v159
	v_add_f32_e32 v126, v126, v160
	v_add_f32_e32 v123, v123, v155
	v_add_f32_e32 v127, v127, v157
	v_cvt_pk_bf16_f32 v120, v120, v121
	v_cvt_pk_bf16_f32 v121, v122, v123
	v_cvt_pk_bf16_f32 v122, v124, v125
	v_cvt_pk_bf16_f32 v123, v126, v127
	global_load_dwordx4 v[124:127], v[162:163], off offset:256
	v_lshl_add_u64 v[158:159], v[146:147], 0, s[10:11]
	global_store_dwordx4 v[162:163], v[120:123], off sc1
	global_load_dwordx4 v[120:123], v[172:173], off offset:512 nt
	s_nop 0
	global_load_dwordx4 v[154:157], v[172:173], off offset:528 nt
	v_lshl_add_u64 v[160:161], v[158:159], 1, s[30:31]
	s_waitcnt vmcnt(0)
	v_lshlrev_b32_e32 v153, 16, v124
	v_and_b32_e32 v124, 0xffff0000, v124
	v_lshlrev_b32_e32 v165, 16, v125
	v_and_b32_e32 v125, 0xffff0000, v125
	v_lshlrev_b32_e32 v166, 16, v126
	v_and_b32_e32 v126, 0xffff0000, v126
	v_lshlrev_b32_e32 v168, 16, v127
	v_and_b32_e32 v127, 0xffff0000, v127
	v_add_f32_e32 v120, v120, v153
	v_add_f32_e32 v153, v154, v166
	v_add_f32_e32 v121, v121, v124
	v_add_f32_e32 v124, v155, v126
	v_add_f32_e32 v122, v122, v165
	v_add_f32_e32 v126, v156, v168
	v_add_f32_e32 v123, v123, v125
	v_add_f32_e32 v125, v157, v127
	v_add_f32_e32 v116, v116, v120
	v_add_f32_e32 v120, v112, v153
	v_add_f32_e32 v112, v117, v121
	v_add_f32_e32 v117, v113, v124
	v_add_f32_e32 v113, v118, v122
	v_add_f32_e32 v118, v114, v126
	v_add_f32_e32 v114, v119, v123
	v_add_f32_e32 v115, v115, v125
	v_cvt_pk_bf16_f32 v112, v116, v112
	v_cvt_pk_bf16_f32 v113, v113, v114
	v_cvt_pk_bf16_f32 v114, v120, v117
	v_cvt_pk_bf16_f32 v115, v118, v115
	global_store_dwordx4 v[162:163], v[112:115], off offset:256 sc1
	global_load_dwordx4 v[112:115], v[160:161], off
	v_lshl_add_u64 v[124:125], v[158:159], 2, s[4:5]
	global_load_dwordx4 v[116:119], v[124:125], off nt
	global_load_dwordx4 v[120:123], v[124:125], off offset:16 nt
	s_waitcnt vmcnt(0)
	v_lshlrev_b32_e32 v126, 16, v112
	v_and_b32_e32 v112, 0xffff0000, v112
	v_lshlrev_b32_e32 v127, 16, v113
	v_and_b32_e32 v113, 0xffff0000, v113
	v_lshlrev_b32_e32 v153, 16, v114
	v_and_b32_e32 v114, 0xffff0000, v114
	v_lshlrev_b32_e32 v154, 16, v115
	v_and_b32_e32 v115, 0xffff0000, v115
	v_add_f32_e32 v116, v116, v126
	v_add_f32_e32 v120, v120, v153
	v_add_f32_e32 v112, v117, v112
	v_add_f32_e32 v114, v121, v114
	v_add_f32_e32 v117, v118, v127
	v_add_f32_e32 v118, v122, v154
	v_add_f32_e32 v113, v119, v113
	v_add_f32_e32 v115, v123, v115
	v_add_f32_e32 v108, v108, v116
	v_add_f32_e32 v116, v104, v120
	v_add_f32_e32 v104, v109, v112
	v_add_f32_e32 v109, v105, v114
	v_add_f32_e32 v105, v110, v117
	v_add_f32_e32 v110, v106, v118
	v_add_f32_e32 v106, v111, v113
	v_add_f32_e32 v107, v107, v115
	v_cvt_pk_bf16_f32 v104, v108, v104
	v_cvt_pk_bf16_f32 v105, v105, v106
	v_cvt_pk_bf16_f32 v106, v116, v109
	v_cvt_pk_bf16_f32 v107, v110, v107
	global_load_dwordx4 v[108:111], v[160:161], off offset:256
	v_lshl_add_u64 v[116:117], v[146:147], 0, s[24:25]
	global_store_dwordx4 v[160:161], v[104:107], off sc1
	global_load_dwordx4 v[104:107], v[124:125], off offset:512 nt
	s_nop 0
	global_load_dwordx4 v[112:115], v[124:125], off offset:528 nt
	v_lshl_add_u64 v[118:119], v[116:117], 1, s[30:31]
	s_waitcnt vmcnt(0)
; __device__ __forceinline__ unsigned pkbf(float lo, float hi) { return pg8::cvt_pk_bf16(lo, hi); }
; __device__ __forceinline__ void unpack8bf(const u32x4 w, float* f) { f[0] = bflo(w.x); f[1] = bfhi(w.x); f[2] = bflo(w.y); f[3] = bfhi(w.y); f[4] = bflo(w.z); f[5] = bfhi(w.z); f[6] = bflo(w.w); f[7] = bfhi(w.w); }
;     __device__ __forceinline__ void operator()(AccRef acc, const Unit& u, int wr, int wc, int fr, int fq) const {
;     ...
;                 for (int bj = 0; bj < 2; ++bj) {
;                     const size_t off = (size_t)(row0 + ai * 128 + m * 16) * DM + col0 + bj * 128;
;                     const f32x4 x0 = *(const f32x4*)(xb + off), x1 = *(const f32x4*)(xb + off + 4);
;                     const u32x4 dw = *(const u32x4*)(D1 + off); float d[8]; unpack8bf(dw, d);
;                     float o[8];
; #pragma unroll
;                     for (int e = 0; e < 4; ++e) { o[e] = x0[e] + d[e] + acc[ai][bj][m][0][e]; o[4 + e] = x1[e] + d[4 + e] + acc[ai][bj][m][1][e]; }
;                     u32x4 w; w.x = pkbf(o[0], o[1]); w.y = pkbf(o[2], o[3]); w.z = pkbf(o[4], o[5]); w.w = pkbf(o[6], o[7]);
;                     *(u32x4*)(D1 + off) = w;
;                 }
	v_lshlrev_b32_e32 v120, 16, v108
	v_and_b32_e32 v108, 0xffff0000, v108
	v_lshlrev_b32_e32 v121, 16, v109
	v_and_b32_e32 v109, 0xffff0000, v109
	v_lshlrev_b32_e32 v122, 16, v110
	v_and_b32_e32 v110, 0xffff0000, v110
	v_lshlrev_b32_e32 v123, 16, v111
	v_and_b32_e32 v111, 0xffff0000, v111
	v_add_f32_e32 v104, v104, v120
	v_add_f32_e32 v112, v112, v122
	v_add_f32_e32 v105, v105, v108
	v_add_f32_e32 v108, v113, v110
	v_add_f32_e32 v106, v106, v121
	v_add_f32_e32 v110, v114, v123
	v_add_f32_e32 v107, v107, v109
	v_add_f32_e32 v109, v115, v111
	v_add_f32_e32 v100, v100, v104
	v_add_f32_e32 v104, v96, v112
	v_add_f32_e32 v96, v101, v105
	v_add_f32_e32 v101, v97, v108
	v_add_f32_e32 v97, v102, v106
	v_add_f32_e32 v102, v98, v110
	v_add_f32_e32 v98, v103, v107
	v_add_f32_e32 v99, v99, v109
	v_cvt_pk_bf16_f32 v96, v100, v96
	v_cvt_pk_bf16_f32 v97, v97, v98
	v_cvt_pk_bf16_f32 v98, v104, v101
	v_cvt_pk_bf16_f32 v99, v102, v99
	global_store_dwordx4 v[160:161], v[96:99], off offset:256 sc1
	global_load_dwordx4 v[96:99], v[118:119], off
	v_lshl_add_u64 v[108:109], v[116:117], 2, s[4:5]
	global_load_dwordx4 v[100:103], v[108:109], off nt
	global_load_dwordx4 v[104:107], v[108:109], off offset:16 nt
	s_waitcnt vmcnt(0)
	v_lshlrev_b32_e32 v110, 16, v96
	v_and_b32_e32 v96, 0xffff0000, v96
	v_lshlrev_b32_e32 v111, 16, v97
	v_and_b32_e32 v97, 0xffff0000, v97
	v_lshlrev_b32_e32 v112, 16, v98
	v_and_b32_e32 v98, 0xffff0000, v98
	v_lshlrev_b32_e32 v113, 16, v99
	v_and_b32_e32 v99, 0xffff0000, v99
	v_add_f32_e32 v100, v100, v110
	v_add_f32_e32 v104, v104, v112
	v_add_f32_e32 v96, v101, v96
	v_add_f32_e32 v98, v105, v98
	v_add_f32_e32 v101, v102, v111
	v_add_f32_e32 v102, v106, v113
	v_add_f32_e32 v97, v103, v97
	v_add_f32_e32 v99, v107, v99
	v_add_f32_e32 v92, v92, v100
	v_add_f32_e32 v100, v88, v104
	v_add_f32_e32 v88, v93, v96
	v_add_f32_e32 v93, v89, v98
	v_add_f32_e32 v89, v94, v101
	v_add_f32_e32 v94, v90, v102
	v_add_f32_e32 v90, v95, v97
	v_add_f32_e32 v91, v91, v99
	v_cvt_pk_bf16_f32 v88, v92, v88
	v_cvt_pk_bf16_f32 v89, v89, v90
	v_cvt_pk_bf16_f32 v90, v100, v93
	v_cvt_pk_bf16_f32 v91, v94, v91
	global_load_dwordx4 v[92:95], v[118:119], off offset:256
	v_lshl_add_u64 v[100:101], v[146:147], 0, s[26:27]
	global_store_dwordx4 v[118:119], v[88:91], off sc1
	global_load_dwordx4 v[88:91], v[108:109], off offset:512 nt
	s_nop 0
	global_load_dwordx4 v[96:99], v[108:109], off offset:528 nt
	v_lshl_add_u64 v[102:103], v[100:101], 1, s[30:31]
	s_waitcnt vmcnt(0)
	v_lshlrev_b32_e32 v104, 16, v92
	v_and_b32_e32 v92, 0xffff0000, v92
	v_lshlrev_b32_e32 v105, 16, v93
	v_and_b32_e32 v93, 0xffff0000, v93
	v_lshlrev_b32_e32 v106, 16, v94
	v_and_b32_e32 v94, 0xffff0000, v94
	v_lshlrev_b32_e32 v107, 16, v95
	v_and_b32_e32 v95, 0xffff0000, v95
	v_add_f32_e32 v88, v88, v104
	v_add_f32_e32 v96, v96, v106
	v_add_f32_e32 v89, v89, v92
	v_add_f32_e32 v92, v97, v94
	v_add_f32_e32 v90, v90, v105
	v_add_f32_e32 v94, v98, v107
	v_add_f32_e32 v91, v91, v93
	v_add_f32_e32 v93, v99, v95
	v_add_f32_e32 v84, v84, v88
	v_add_f32_e32 v88, v80, v96
	v_add_f32_e32 v80, v85, v89
	v_add_f32_e32 v85, v81, v92
	v_add_f32_e32 v81, v86, v90
	v_add_f32_e32 v86, v82, v94
	v_add_f32_e32 v82, v87, v91
	v_add_f32_e32 v83, v83, v93
	v_cvt_pk_bf16_f32 v80, v84, v80
	v_cvt_pk_bf16_f32 v81, v81, v82
	v_cvt_pk_bf16_f32 v82, v88, v85
	v_cvt_pk_bf16_f32 v83, v86, v83
	global_store_dwordx4 v[118:119], v[80:83], off offset:256 sc1
	global_load_dwordx4 v[80:83], v[102:103], off
	v_lshl_add_u64 v[92:93], v[100:101], 2, s[4:5]
	global_load_dwordx4 v[84:87], v[92:93], off nt
	global_load_dwordx4 v[88:91], v[92:93], off offset:16 nt
	s_waitcnt vmcnt(0)
	v_lshlrev_b32_e32 v94, 16, v80
	v_and_b32_e32 v80, 0xffff0000, v80
	v_lshlrev_b32_e32 v95, 16, v81
	v_and_b32_e32 v81, 0xffff0000, v81
	v_lshlrev_b32_e32 v96, 16, v82
	v_and_b32_e32 v82, 0xffff0000, v82
	v_lshlrev_b32_e32 v97, 16, v83
	v_and_b32_e32 v83, 0xffff0000, v83
	v_add_f32_e32 v84, v84, v94
	v_add_f32_e32 v88, v88, v96
	v_add_f32_e32 v80, v85, v80
	v_add_f32_e32 v82, v89, v82
	v_add_f32_e32 v85, v86, v95
	v_add_f32_e32 v86, v90, v97
	v_add_f32_e32 v81, v87, v81
	v_add_f32_e32 v83, v91, v83
	v_add_f32_e32 v76, v76, v84
	v_add_f32_e32 v84, v72, v88
	v_add_f32_e32 v72, v77, v80
	v_add_f32_e32 v77, v73, v82
	v_add_f32_e32 v73, v78, v85
	v_add_f32_e32 v78, v74, v86
	v_add_f32_e32 v74, v79, v81
	v_add_f32_e32 v75, v75, v83
	v_cvt_pk_bf16_f32 v72, v76, v72
	v_cvt_pk_bf16_f32 v73, v73, v74
	v_cvt_pk_bf16_f32 v74, v84, v77
	v_cvt_pk_bf16_f32 v75, v78, v75
	global_load_dwordx4 v[76:79], v[102:103], off offset:256
	v_lshl_add_u64 v[84:85], v[146:147], 0, s[28:29]
	global_store_dwordx4 v[102:103], v[72:75], off sc1
	global_load_dwordx4 v[72:75], v[92:93], off offset:512 nt
	s_nop 0
	global_load_dwordx4 v[80:83], v[92:93], off offset:528 nt
	v_lshl_add_u64 v[86:87], v[84:85], 1, s[30:31]
	s_waitcnt vmcnt(0)
	v_lshlrev_b32_e32 v88, 16, v76
	v_and_b32_e32 v76, 0xffff0000, v76
	v_lshlrev_b32_e32 v89, 16, v77
	v_and_b32_e32 v77, 0xffff0000, v77
	v_lshlrev_b32_e32 v90, 16, v78
	v_and_b32_e32 v78, 0xffff0000, v78
	v_lshlrev_b32_e32 v91, 16, v79
	v_and_b32_e32 v79, 0xffff0000, v79
	v_add_f32_e32 v72, v72, v88
	v_add_f32_e32 v80, v80, v90
	v_add_f32_e32 v73, v73, v76
	v_add_f32_e32 v76, v81, v78
	v_add_f32_e32 v74, v74, v89
	v_add_f32_e32 v78, v82, v91
	v_add_f32_e32 v75, v75, v77
	v_add_f32_e32 v77, v83, v79
	v_add_f32_e32 v68, v68, v72
	v_add_f32_e32 v72, v64, v80
	v_add_f32_e32 v64, v69, v73
	v_add_f32_e32 v69, v65, v76
	v_add_f32_e32 v65, v70, v74
	v_add_f32_e32 v70, v66, v78
	v_add_f32_e32 v66, v71, v75
	v_add_f32_e32 v67, v67, v77
	v_cvt_pk_bf16_f32 v64, v68, v64
	v_cvt_pk_bf16_f32 v65, v65, v66
	v_cvt_pk_bf16_f32 v66, v72, v69
	v_cvt_pk_bf16_f32 v67, v70, v67
	global_store_dwordx4 v[102:103], v[64:67], off offset:256 sc1
	global_load_dwordx4 v[64:67], v[86:87], off
	v_lshl_add_u64 v[76:77], v[84:85], 2, s[4:5]
	global_load_dwordx4 v[68:71], v[76:77], off nt
	global_load_dwordx4 v[72:75], v[76:77], off offset:16 nt
	s_waitcnt vmcnt(0)
; __device__ __forceinline__ unsigned pkbf(float lo, float hi) { return pg8::cvt_pk_bf16(lo, hi); }
; __device__ __forceinline__ void unpack8bf(const u32x4 w, float* f) { f[0] = bflo(w.x); f[1] = bfhi(w.x); f[2] = bflo(w.y); f[3] = bfhi(w.y); f[4] = bflo(w.z); f[5] = bfhi(w.z); f[6] = bflo(w.w); f[7] = bfhi(w.w); }
;     __device__ __forceinline__ void operator()(AccRef acc, const Unit& u, int wr, int wc, int fr, int fq) const {
;     ...
;                 for (int bj = 0; bj < 2; ++bj) {
;                     const size_t off = (size_t)(row0 + ai * 128 + m * 16) * DM + col0 + bj * 128;
;                     const f32x4 x0 = *(const f32x4*)(xb + off), x1 = *(const f32x4*)(xb + off + 4);
;                     const u32x4 dw = *(const u32x4*)(D1 + off); float d[8]; unpack8bf(dw, d);
;                     float o[8];
; #pragma unroll
;                     for (int e = 0; e < 4; ++e) { o[e] = x0[e] + d[e] + acc[ai][bj][m][0][e]; o[4 + e] = x1[e] + d[4 + e] + acc[ai][bj][m][1][e]; }
;                     u32x4 w; w.x = pkbf(o[0], o[1]); w.y = pkbf(o[2], o[3]); w.z = pkbf(o[4], o[5]); w.w = pkbf(o[6], o[7]);
;                     *(u32x4*)(D1 + off) = w;
;                 }
	v_lshlrev_b32_e32 v78, 16, v64
	v_and_b32_e32 v64, 0xffff0000, v64
	v_lshlrev_b32_e32 v79, 16, v65
	v_and_b32_e32 v65, 0xffff0000, v65
	v_lshlrev_b32_e32 v80, 16, v66
	v_and_b32_e32 v66, 0xffff0000, v66
	v_lshlrev_b32_e32 v81, 16, v67
	v_and_b32_e32 v67, 0xffff0000, v67
	v_add_f32_e32 v68, v68, v78
	v_add_f32_e32 v72, v72, v80
	v_add_f32_e32 v64, v69, v64
	v_add_f32_e32 v66, v73, v66
	v_add_f32_e32 v69, v70, v79
	v_add_f32_e32 v70, v74, v81
	v_add_f32_e32 v65, v71, v65
	v_add_f32_e32 v67, v75, v67
	v_add_f32_e32 v60, v60, v68
	v_add_f32_e32 v68, v56, v72
	v_add_f32_e32 v56, v61, v64
	v_add_f32_e32 v61, v57, v66
	v_add_f32_e32 v57, v62, v69
	v_add_f32_e32 v62, v58, v70
	v_add_f32_e32 v58, v63, v65
	v_add_f32_e32 v59, v59, v67
	v_cvt_pk_bf16_f32 v56, v60, v56
	v_cvt_pk_bf16_f32 v57, v57, v58
	v_cvt_pk_bf16_f32 v58, v68, v61
	v_cvt_pk_bf16_f32 v59, v62, v59
	global_load_dwordx4 v[60:63], v[86:87], off offset:256
	v_lshl_add_u64 v[68:69], v[146:147], 0, s[36:37]
	global_store_dwordx4 v[86:87], v[56:59], off sc1
	global_load_dwordx4 v[56:59], v[76:77], off offset:512 nt
	s_nop 0
	global_load_dwordx4 v[64:67], v[76:77], off offset:528 nt
	v_lshl_add_u64 v[70:71], v[68:69], 1, s[30:31]
	s_waitcnt vmcnt(0)
	v_lshlrev_b32_e32 v72, 16, v60
	v_and_b32_e32 v60, 0xffff0000, v60
	v_lshlrev_b32_e32 v73, 16, v61
	v_and_b32_e32 v61, 0xffff0000, v61
	v_lshlrev_b32_e32 v74, 16, v62
	v_and_b32_e32 v62, 0xffff0000, v62
	v_lshlrev_b32_e32 v75, 16, v63
	v_and_b32_e32 v63, 0xffff0000, v63
	v_add_f32_e32 v56, v56, v72
	v_add_f32_e32 v64, v64, v74
	v_add_f32_e32 v57, v57, v60
	v_add_f32_e32 v60, v65, v62
	v_add_f32_e32 v58, v58, v73
	v_add_f32_e32 v62, v66, v75
	v_add_f32_e32 v59, v59, v61
	v_add_f32_e32 v61, v67, v63
	v_add_f32_e32 v52, v52, v56
	v_add_f32_e32 v56, v48, v64
	v_add_f32_e32 v48, v53, v57
	v_add_f32_e32 v53, v49, v60
	v_add_f32_e32 v49, v54, v58
	v_add_f32_e32 v54, v50, v62
	v_add_f32_e32 v50, v55, v59
	v_add_f32_e32 v51, v51, v61
	v_cvt_pk_bf16_f32 v48, v52, v48
	v_cvt_pk_bf16_f32 v49, v49, v50
	v_cvt_pk_bf16_f32 v50, v56, v53
	v_cvt_pk_bf16_f32 v51, v54, v51
	global_store_dwordx4 v[86:87], v[48:51], off offset:256 sc1
	global_load_dwordx4 v[48:51], v[70:71], off
	v_lshl_add_u64 v[60:61], v[68:69], 2, s[4:5]
	global_load_dwordx4 v[52:55], v[60:61], off nt
	global_load_dwordx4 v[56:59], v[60:61], off offset:16 nt
	s_waitcnt vmcnt(0)
	v_lshlrev_b32_e32 v62, 16, v48
	v_and_b32_e32 v48, 0xffff0000, v48
	v_lshlrev_b32_e32 v63, 16, v49
	v_and_b32_e32 v49, 0xffff0000, v49
	v_lshlrev_b32_e32 v64, 16, v50
	v_and_b32_e32 v50, 0xffff0000, v50
	v_lshlrev_b32_e32 v65, 16, v51
	v_and_b32_e32 v51, 0xffff0000, v51
	v_add_f32_e32 v52, v52, v62
	v_add_f32_e32 v56, v56, v64
	v_add_f32_e32 v48, v53, v48
	v_add_f32_e32 v50, v57, v50
	v_add_f32_e32 v53, v54, v63
	v_add_f32_e32 v54, v58, v65
	v_add_f32_e32 v49, v55, v49
	v_add_f32_e32 v51, v59, v51
	v_add_f32_e32 v44, v44, v52
	v_add_f32_e32 v52, v40, v56
	v_add_f32_e32 v40, v45, v48
	v_add_f32_e32 v45, v41, v50
	v_add_f32_e32 v41, v46, v53
	v_add_f32_e32 v46, v42, v54
	v_add_f32_e32 v42, v47, v49
	v_add_f32_e32 v43, v43, v51
	v_cvt_pk_bf16_f32 v40, v44, v40
	v_cvt_pk_bf16_f32 v41, v41, v42
	v_cvt_pk_bf16_f32 v42, v52, v45
	v_cvt_pk_bf16_f32 v43, v46, v43
	global_load_dwordx4 v[44:47], v[70:71], off offset:256
	v_lshl_add_u64 v[52:53], v[146:147], 0, s[40:41]
	global_store_dwordx4 v[70:71], v[40:43], off sc1
	global_load_dwordx4 v[40:43], v[60:61], off offset:512 nt
	s_nop 0
	global_load_dwordx4 v[48:51], v[60:61], off offset:528 nt
	v_lshl_add_u64 v[54:55], v[52:53], 1, s[30:31]
	s_waitcnt vmcnt(0)
	v_lshlrev_b32_e32 v56, 16, v44
	v_and_b32_e32 v44, 0xffff0000, v44
	v_lshlrev_b32_e32 v57, 16, v45
	v_and_b32_e32 v45, 0xffff0000, v45
	v_lshlrev_b32_e32 v58, 16, v46
	v_and_b32_e32 v46, 0xffff0000, v46
	v_lshlrev_b32_e32 v59, 16, v47
	v_and_b32_e32 v47, 0xffff0000, v47
	v_add_f32_e32 v40, v40, v56
	v_add_f32_e32 v48, v48, v58
	v_add_f32_e32 v41, v41, v44
	v_add_f32_e32 v44, v49, v46
	v_add_f32_e32 v42, v42, v57
	v_add_f32_e32 v46, v50, v59
	v_add_f32_e32 v43, v43, v45
	v_add_f32_e32 v45, v51, v47
	v_add_f32_e32 v36, v36, v40
	v_add_f32_e32 v40, v32, v48
	v_add_f32_e32 v32, v37, v41
	v_add_f32_e32 v37, v33, v44
	v_add_f32_e32 v33, v38, v42
	v_add_f32_e32 v38, v34, v46
	v_add_f32_e32 v34, v39, v43
	v_add_f32_e32 v35, v35, v45
	v_cvt_pk_bf16_f32 v32, v36, v32
	v_cvt_pk_bf16_f32 v33, v33, v34
	v_cvt_pk_bf16_f32 v34, v40, v37
	v_cvt_pk_bf16_f32 v35, v38, v35
	global_store_dwordx4 v[70:71], v[32:35], off offset:256 sc1
	global_load_dwordx4 v[32:35], v[54:55], off
	v_lshl_add_u64 v[44:45], v[52:53], 2, s[4:5]
	global_load_dwordx4 v[36:39], v[44:45], off nt
	global_load_dwordx4 v[40:43], v[44:45], off offset:16 nt
	s_waitcnt vmcnt(0)
; __device__ __forceinline__ unsigned pkbf(float lo, float hi) { return pg8::cvt_pk_bf16(lo, hi); }
; __device__ __forceinline__ void unpack8bf(const u32x4 w, float* f) { f[0] = bflo(w.x); f[1] = bfhi(w.x); f[2] = bflo(w.y); f[3] = bfhi(w.y); f[4] = bflo(w.z); f[5] = bfhi(w.z); f[6] = bflo(w.w); f[7] = bfhi(w.w); }
;     __device__ __forceinline__ void operator()(AccRef acc, const Unit& u, int wr, int wc, int fr, int fq) const {
;     ...
;                 for (int bj = 0; bj < 2; ++bj) {
;                     const size_t off = (size_t)(row0 + ai * 128 + m * 16) * DM + col0 + bj * 128;
;                     const f32x4 x0 = *(const f32x4*)(xb + off), x1 = *(const f32x4*)(xb + off + 4);
;                     const u32x4 dw = *(const u32x4*)(D1 + off); float d[8]; unpack8bf(dw, d);
;                     float o[8];
; #pragma unroll
;                     for (int e = 0; e < 4; ++e) { o[e] = x0[e] + d[e] + acc[ai][bj][m][0][e]; o[4 + e] = x1[e] + d[4 + e] + acc[ai][bj][m][1][e]; }
;                     u32x4 w; w.x = pkbf(o[0], o[1]); w.y = pkbf(o[2], o[3]); w.z = pkbf(o[4], o[5]); w.w = pkbf(o[6], o[7]);
;                     *(u32x4*)(D1 + off) = w;
;                 }
	v_lshlrev_b32_e32 v46, 16, v32
	v_and_b32_e32 v32, 0xffff0000, v32
	v_lshlrev_b32_e32 v47, 16, v33
	v_and_b32_e32 v33, 0xffff0000, v33
	v_lshlrev_b32_e32 v48, 16, v34
	v_and_b32_e32 v34, 0xffff0000, v34
	v_lshlrev_b32_e32 v49, 16, v35
	v_and_b32_e32 v35, 0xffff0000, v35
	v_add_f32_e32 v36, v36, v46
	v_add_f32_e32 v40, v40, v48
	v_add_f32_e32 v32, v37, v32
	v_add_f32_e32 v34, v41, v34
	v_add_f32_e32 v37, v38, v47
	v_add_f32_e32 v38, v42, v49
	v_add_f32_e32 v33, v39, v33
	v_add_f32_e32 v35, v43, v35
	v_add_f32_e32 v28, v28, v36
	v_add_f32_e32 v36, v24, v40
	v_add_f32_e32 v24, v29, v32
	v_add_f32_e32 v29, v25, v34
	v_add_f32_e32 v25, v30, v37
	v_add_f32_e32 v30, v26, v38
	v_add_f32_e32 v26, v31, v33
	v_add_f32_e32 v27, v27, v35
	v_cvt_pk_bf16_f32 v24, v28, v24
	v_cvt_pk_bf16_f32 v25, v25, v26
	v_cvt_pk_bf16_f32 v26, v36, v29
	v_cvt_pk_bf16_f32 v27, v30, v27
	global_load_dwordx4 v[28:31], v[54:55], off offset:256
	v_lshl_add_u64 v[36:37], v[146:147], 0, s[42:43]
	global_store_dwordx4 v[54:55], v[24:27], off sc1
	global_load_dwordx4 v[24:27], v[44:45], off offset:512 nt
	s_nop 0
	global_load_dwordx4 v[32:35], v[44:45], off offset:528 nt
	v_lshl_add_u64 v[38:39], v[36:37], 1, s[30:31]
	s_waitcnt vmcnt(0)
	v_lshlrev_b32_e32 v40, 16, v28
	v_and_b32_e32 v28, 0xffff0000, v28
	v_lshlrev_b32_e32 v41, 16, v29
	v_and_b32_e32 v29, 0xffff0000, v29
	v_lshlrev_b32_e32 v42, 16, v30
	v_and_b32_e32 v30, 0xffff0000, v30
	v_lshlrev_b32_e32 v43, 16, v31
	v_and_b32_e32 v31, 0xffff0000, v31
	v_add_f32_e32 v24, v24, v40
	v_add_f32_e32 v32, v32, v42
	v_add_f32_e32 v25, v25, v28
	v_add_f32_e32 v28, v33, v30
	v_add_f32_e32 v26, v26, v41
	v_add_f32_e32 v30, v34, v43
	v_add_f32_e32 v27, v27, v29
	v_add_f32_e32 v29, v35, v31
	v_add_f32_e32 v20, v20, v24
	v_add_f32_e32 v24, v16, v32
	v_add_f32_e32 v16, v21, v25
	v_add_f32_e32 v21, v17, v28
	v_add_f32_e32 v17, v22, v26
	v_add_f32_e32 v22, v18, v30
	v_add_f32_e32 v18, v23, v27
	v_add_f32_e32 v19, v19, v29
	v_cvt_pk_bf16_f32 v16, v20, v16
	v_cvt_pk_bf16_f32 v17, v17, v18
	v_cvt_pk_bf16_f32 v18, v24, v21
	v_cvt_pk_bf16_f32 v19, v22, v19
	global_store_dwordx4 v[54:55], v[16:19], off offset:256 sc1
	global_load_dwordx4 v[16:19], v[38:39], off
	v_lshl_add_u64 v[28:29], v[36:37], 2, s[4:5]
	global_load_dwordx4 v[20:23], v[28:29], off nt
	global_load_dwordx4 v[24:27], v[28:29], off offset:16 nt
	s_mov_b64 s[4:5], -1
	s_waitcnt vmcnt(0)
	v_lshlrev_b32_e32 v30, 16, v16
	v_and_b32_e32 v16, 0xffff0000, v16
	v_lshlrev_b32_e32 v31, 16, v17
	v_and_b32_e32 v17, 0xffff0000, v17
	v_lshlrev_b32_e32 v32, 16, v18
	v_and_b32_e32 v18, 0xffff0000, v18
	v_lshlrev_b32_e32 v33, 16, v19
	v_and_b32_e32 v19, 0xffff0000, v19
	v_add_f32_e32 v20, v20, v30
	v_add_f32_e32 v24, v24, v32
	v_add_f32_e32 v16, v21, v16
	v_add_f32_e32 v18, v25, v18
	v_add_f32_e32 v21, v22, v31
	v_add_f32_e32 v22, v26, v33
	v_add_f32_e32 v17, v23, v17
	v_add_f32_e32 v19, v27, v19
	v_add_f32_e32 v12, v12, v20
	v_add_f32_e32 v20, v8, v24
	v_add_f32_e32 v8, v13, v16
	v_add_f32_e32 v13, v9, v18
	v_add_f32_e32 v9, v14, v21
	v_add_f32_e32 v14, v10, v22
	v_add_f32_e32 v10, v15, v17
	v_add_f32_e32 v11, v11, v19
	v_cvt_pk_bf16_f32 v8, v12, v8
	v_cvt_pk_bf16_f32 v9, v9, v10
	v_cvt_pk_bf16_f32 v10, v20, v13
	v_cvt_pk_bf16_f32 v11, v14, v11
	global_load_dwordx4 v[12:15], v[38:39], off offset:256
	s_waitcnt vmcnt(0)
	v_lshlrev_b32_e32 v20, 16, v12
	global_store_dwordx4 v[38:39], v[8:11], off sc1
	global_load_dwordx4 v[8:11], v[28:29], off offset:512 nt
	s_nop 0
	global_load_dwordx4 v[16:19], v[28:29], off offset:528 nt
	v_and_b32_e32 v12, 0xffff0000, v12
	v_lshlrev_b32_e32 v21, 16, v13
	v_and_b32_e32 v13, 0xffff0000, v13
	v_lshlrev_b32_e32 v22, 16, v14
	v_and_b32_e32 v14, 0xffff0000, v14
	v_lshlrev_b32_e32 v23, 16, v15
	v_and_b32_e32 v15, 0xffff0000, v15
	s_waitcnt vmcnt(0)
	v_add_f32_e32 v8, v8, v20
	v_add_f32_e32 v16, v16, v22
	v_add_f32_e32 v9, v9, v12
	v_add_f32_e32 v12, v17, v14
	v_add_f32_e32 v10, v10, v21
	v_add_f32_e32 v14, v18, v23
	v_add_f32_e32 v11, v11, v13
	v_add_f32_e32 v13, v19, v15
	v_add_f32_e32 v4, v4, v8
	v_add_f32_e32 v8, v0, v16
	v_add_f32_e32 v0, v5, v9
	v_add_f32_e32 v5, v1, v12
	v_add_f32_e32 v1, v6, v10
	v_add_f32_e32 v6, v2, v14
	v_add_f32_e32 v2, v7, v11
	v_add_f32_e32 v3, v3, v13
	v_cvt_pk_bf16_f32 v0, v4, v0
	v_cvt_pk_bf16_f32 v1, v1, v2
	v_cvt_pk_bf16_f32 v2, v8, v5
	v_cvt_pk_bf16_f32 v3, v6, v3
	global_store_dwordx4 v[38:39], v[0:3], off offset:256 sc1
	s_cbranch_vccnz .LBB0_1234
	s_andn2_b64 vcc, exec, s[94:95]
	s_cbranch_vccnz .LBB0_1233
	s_barrier
	s_branch .LBB0_1233

; __device__ __forceinline__ unsigned pkbf(float lo, float hi) { return pg8::cvt_pk_bf16(lo, hi); }
; __device__ __forceinline__ void unpack8bf(const u32x4 w, float* f) { f[0] = bflo(w.x); f[1] = bfhi(w.x); f[2] = bflo(w.y); f[3] = bfhi(w.y); f[4] = bflo(w.z); f[5] = bfhi(w.z); f[6] = bflo(w.w); f[7] = bfhi(w.w); }
; __device__ __forceinline__ void norm_row_bf(const bf16_t* src, const float* gain, bf16_t* ob, float* of, int lane) {
;     float v[16]; float s = 0.f;
;     const u32x4 w0 = *((const u32x4*)src + lane), w1 = *((const u32x4*)src + lane + 64);
;     unpack8bf(w0, v); unpack8bf(w1, v + 8);
; #pragma unroll
;     for (int e = 0; e < 16; ++e) s += v[e] * v[e];
;     const float rstd = 1.0f / sqrtf(wave_sum(s) * (1.f / DM) + NORM_EPS);
; #pragma unroll
;     for (int h = 0; h < 2; ++h) { const float* g = gain + h * 512 + lane * 8; const f32x4 g0 = *(const f32x4*)g, g1 = *(const f32x4*)(g + 4);
;         float o[8];
; #pragma unroll
;         for (int e = 0; e < 4; ++e) { o[e] = v[h * 8 + e] * rstd * g0[e]; o[4 + e] = v[h * 8 + 4 + e] * rstd * g1[e]; }
;         if (ob) { u32x4 w; w.x = pkbf(o[0], o[1]); w.y = pkbf(o[2], o[3]); w.z = pkbf(o[4], o[5]); w.w = pkbf(o[6], o[7]); *((u32x4*)ob + lane + 64 * h) = w; }
;         else { const f32x4 a = {o[0], o[1], o[2], o[3]}, b = {o[4], o[5], o[6], o[7]}; *(f32x4*)(of + h * 512 + lane * 8) = a; *(f32x4*)(of + h * 512 + lane * 8 + 4) = b; } }
; }
.LBB0_1302:
	v_add_co_u32_e32 v12, vcc, 0xe9800000, v2
	s_add_i32 s6, s6, s88
	s_nop 0
	v_addc_co_u32_e32 v13, vcc, -1, v3, vcc
	global_load_dwordx4 v[12:15], v[12:13], off
	v_add_co_u32_e32 v28, vcc, 0xe9801000, v2
	s_cmp_gt_i32 s6, 0xbfff
	s_nop 0
	v_addc_co_u32_e32 v29, vcc, -1, v3, vcc
	global_load_dwordx4 v[16:19], v[28:29], off offset:-3072
	global_load_dwordx4 v[20:23], v[0:1], off offset:16
	global_load_dwordx4 v[24:27], v[0:1], off
	s_waitcnt vmcnt(3)
	v_lshlrev_b32_e32 v28, 16, v12
	v_and_b32_e32 v12, 0xffff0000, v12
	v_lshlrev_b32_e32 v29, 16, v13
	v_and_b32_e32 v13, 0xffff0000, v13
	s_waitcnt vmcnt(2)
	v_lshlrev_b32_e32 v32, 16, v16
	v_and_b32_e32 v33, 0xffff0000, v16
	v_mul_f32_e32 v16, v12, v12
	v_fmac_f32_e32 v16, v28, v28
	v_fmac_f32_e32 v16, v29, v29
	v_lshlrev_b32_e32 v30, 16, v14
	v_fmac_f32_e32 v16, v13, v13
	v_and_b32_e32 v14, 0xffff0000, v14
	v_fmac_f32_e32 v16, v30, v30
	v_lshlrev_b32_e32 v31, 16, v15
	v_fmac_f32_e32 v16, v14, v14
	v_and_b32_e32 v15, 0xffff0000, v15
	v_fmac_f32_e32 v16, v31, v31
	v_fmac_f32_e32 v16, v15, v15
	v_fmac_f32_e32 v16, v32, v32
	v_lshlrev_b32_e32 v34, 16, v17
	v_fmac_f32_e32 v16, v33, v33
	v_and_b32_e32 v35, 0xffff0000, v17
	v_fmac_f32_e32 v16, v34, v34
	v_lshlrev_b32_e32 v36, 16, v18
	v_fmac_f32_e32 v16, v35, v35
	v_and_b32_e32 v37, 0xffff0000, v18
	v_fmac_f32_e32 v16, v36, v36
	v_lshlrev_b32_e32 v38, 16, v19
	v_fmac_f32_e32 v16, v37, v37
	v_and_b32_e32 v39, 0xffff0000, v19
	v_fmac_f32_e32 v16, v38, v38
	v_fmac_f32_e32 v16, v39, v39
	ds_bpermute_b32 v17, v4, v16
	s_waitcnt lgkmcnt(0)
	v_add_f32_e32 v16, v16, v17
	ds_bpermute_b32 v17, v5, v16
	s_waitcnt lgkmcnt(0)
	v_add_f32_e32 v16, v16, v17
	ds_bpermute_b32 v17, v6, v16
	s_waitcnt lgkmcnt(0)
	v_add_f32_e32 v16, v16, v17
	ds_bpermute_b32 v17, v7, v16
	s_waitcnt lgkmcnt(0)
	v_add_f32_e32 v16, v16, v17
	ds_bpermute_b32 v17, v8, v16
	s_waitcnt lgkmcnt(0)
	v_add_f32_e32 v16, v16, v17
	ds_bpermute_b32 v17, v9, v16
	s_waitcnt lgkmcnt(0)
	v_add_f32_e32 v16, v16, v17
	v_fmamk_f32 v16, v16, 0x3a800000, v10
	v_mul_f32_e32 v17, 0x4f800000, v16
	v_cmp_gt_f32_e32 vcc, s3, v16
	s_nop 1
	v_cndmask_b32_e32 v16, v16, v17, vcc
	v_sqrt_f32_e32 v17, v16
	s_nop 0
	v_add_u32_e32 v18, -1, v17
	v_add_u32_e32 v19, 1, v17
	v_fma_f32 v40, -v18, v17, v16
	v_fma_f32 v41, -v19, v17, v16
	v_cmp_ge_f32_e64 s[0:1], 0, v40
	s_nop 1
	v_cndmask_b32_e64 v17, v17, v18, s[0:1]
	v_cmp_lt_f32_e64 s[0:1], 0, v41
	s_nop 1
	v_cndmask_b32_e64 v17, v17, v19, s[0:1]
	v_mul_f32_e32 v18, 0x37800000, v17
	v_cndmask_b32_e32 v17, v17, v18, vcc
	v_cmp_class_f32_e32 vcc, v16, v11
	s_nop 1
	v_cndmask_b32_e32 v16, v17, v16, vcc
	v_div_scale_f32 v17, s[0:1], v16, v16, 1.0
	v_rcp_f32_e32 v18, v17
	v_div_scale_f32 v19, vcc, 1.0, v16, 1.0
	v_fma_f32 v40, -v17, v18, 1.0
	v_fmac_f32_e32 v18, v40, v18
	v_mul_f32_e32 v40, v19, v18
	v_fma_f32 v41, -v17, v40, v19
	v_fmac_f32_e32 v40, v41, v18
	v_fma_f32 v17, -v17, v40, v19
	v_div_fmas_f32 v17, v17, v18, v40
	v_div_fixup_f32 v40, v17, v16, 1.0
	v_mul_f32_e32 v12, v40, v12
	v_mul_f32_e32 v14, v40, v14
	v_mul_f32_e32 v13, v40, v13
	v_mul_f32_e32 v15, v40, v15
	v_mul_f32_e32 v16, v40, v28
	v_mul_f32_e32 v17, v40, v30
	v_mul_f32_e32 v18, v40, v29
	v_mul_f32_e32 v19, v40, v31
	s_waitcnt vmcnt(0)
	v_mul_f32_e32 v12, v25, v12
	v_mul_f32_e32 v14, v21, v14
	v_mul_f32_e32 v13, v27, v13
	v_mul_f32_e32 v15, v23, v15
	v_mul_f32_e32 v16, v24, v16
	v_mul_f32_e32 v17, v20, v17
	v_mul_f32_e32 v18, v26, v18
	v_mul_f32_e32 v19, v22, v19
	v_cvt_pk_bf16_f32 v12, v16, v12
	v_cvt_pk_bf16_f32 v13, v18, v13
	v_cvt_pk_bf16_f32 v14, v17, v14
	v_cvt_pk_bf16_f32 v15, v19, v15
	global_store_dwordx4 v[2:3], v[12:15], off sc1
	global_load_dwordx4 v[12:15], v[0:1], off offset:2048
	s_nop 0
	global_load_dwordx4 v[16:19], v[0:1], off offset:2064
	v_mul_f32_e32 v20, v40, v32
	v_mul_f32_e32 v22, v40, v33
	v_mul_f32_e32 v24, v40, v34
	v_mul_f32_e32 v26, v40, v35
	v_mul_f32_e32 v21, v40, v36
	v_mul_f32_e32 v23, v40, v37
	v_mul_f32_e32 v25, v40, v38
	v_mul_f32_e32 v27, v40, v39
	s_waitcnt vmcnt(1)
	v_mul_f32_e32 v12, v12, v20
	v_mul_f32_e32 v13, v13, v22
	v_mul_f32_e32 v14, v14, v24
	v_mul_f32_e32 v15, v15, v26
	s_waitcnt vmcnt(0)
	v_mul_f32_e32 v16, v16, v21
	v_mul_f32_e32 v17, v17, v23
	v_mul_f32_e32 v18, v18, v25
	v_mul_f32_e32 v19, v19, v27
	v_cvt_pk_bf16_f32 v12, v12, v13
	v_cvt_pk_bf16_f32 v13, v14, v15
	v_cvt_pk_bf16_f32 v14, v16, v17
	v_cvt_pk_bf16_f32 v15, v18, v19
	global_store_dwordx4 v[2:3], v[12:15], off offset:1024 sc1
	v_lshl_add_u64 v[2:3], v[2:3], 0, s[4:5]
	s_cbranch_scc0 .LBB0_1302

; __device__ __forceinline__ unsigned pkbf(float lo, float hi) { return pg8::cvt_pk_bf16(lo, hi); }
; __device__ __forceinline__ void unpack8bf(const u32x4 w, float* f) { f[0] = bflo(w.x); f[1] = bfhi(w.x); f[2] = bflo(w.y); f[3] = bfhi(w.y); f[4] = bflo(w.z); f[5] = bfhi(w.z); f[6] = bflo(w.w); f[7] = bfhi(w.w); }
;     __device__ __forceinline__ void operator()(AccRef acc, const Unit& u, int wr, int wc, int fr, int fq) const {
;     ...
;         const int row0 = u.pm * 256 + wr * 64 + fr, col0 = u.pn * 256 + wc * 32 + 8 * fq;
; #pragma unroll
;         for (int ai = 0; ai < 2; ++ai)
; #pragma unroll
;             for (int m = 0; m < 4; ++m)
; #pragma unroll
;                 for (int bj = 0; bj < 2; ++bj) {
;                     const size_t off = (size_t)(row0 + ai * 128 + m * 16) * DM + col0 + bj * 128;
;                     const u32x4 hw = *(const u32x4*)(Hb + off); float h[8]; unpack8bf(hw, h);
; #pragma unroll
;                     for (int e = 0; e < 4; ++e) { h[e] += 0.5f * acc[ai][bj][m][0][e]; h[4 + e] += 0.5f * acc[ai][bj][m][1][e]; }
;                     u32x4 w; w.x = pkbf(h[0], h[1]); w.y = pkbf(h[2], h[3]); w.z = pkbf(h[4], h[5]); w.w = pkbf(h[6], h[7]);
;                     *(u32x4*)(Hb + off) = w;
;                 }
.LBB0_1443:
	v_mov_b32_e32 v146, v129
	v_mov_b32_e32 v147, v148
	s_lshl_b32 s14, s77, 8
	s_add_i32 s14, s14, s64
	v_add_u32_e32 v146, s14, v146
	s_lshl_b32 s14, s78, 8
	s_or_b32 s14, s14, s65
	v_lshl_add_u32 v154, v147, 3, s14
	v_ashrrev_i32_e32 v147, 31, v146
	v_lshlrev_b64 v[146:147], 11, v[146:147]
	v_ashrrev_i32_e32 v155, 31, v154
	v_lshl_add_u64 v[146:147], s[30:31], 0, v[146:147]
	v_lshl_add_u64 v[146:147], v[154:155], 1, v[146:147]
	global_load_dwordx4 v[154:157], v[146:147], off
	s_waitcnt vmcnt(0)
	v_lshlrev_b32_e32 v153, 16, v154
	v_and_b32_e32 v154, 0xffff0000, v154
	v_lshlrev_b32_e32 v158, 16, v155
	v_and_b32_e32 v155, 0xffff0000, v155
	v_lshlrev_b32_e32 v159, 16, v156
	v_and_b32_e32 v156, 0xffff0000, v156
	v_lshlrev_b32_e32 v160, 16, v157
	v_and_b32_e32 v157, 0xffff0000, v157
	v_fmac_f32_e32 v153, 0.5, v120
	v_fmac_f32_e32 v159, 0.5, v124
	v_fmac_f32_e32 v154, 0.5, v121
	v_fmac_f32_e32 v156, 0.5, v125
	v_fmac_f32_e32 v158, 0.5, v122
	v_fmac_f32_e32 v160, 0.5, v126
	v_fmac_f32_e32 v155, 0.5, v123
	v_fmac_f32_e32 v157, 0.5, v127
	v_cvt_pk_bf16_f32 v120, v153, v154
	v_cvt_pk_bf16_f32 v121, v158, v155
	v_cvt_pk_bf16_f32 v122, v159, v156
	v_cvt_pk_bf16_f32 v123, v160, v157
	global_load_dwordx4 v[124:127], v[146:147], off offset:256
	v_add_co_u32_e32 v154, vcc, s67, v146
	global_store_dwordx4 v[146:147], v[120:123], off sc1
	s_nop 0
	v_addc_co_u32_e32 v155, vcc, 0, v147, vcc
	s_waitcnt vmcnt(0)
	v_lshlrev_b32_e32 v120, 16, v124
	v_and_b32_e32 v121, 0xffff0000, v124
	v_lshlrev_b32_e32 v122, 16, v125
	v_and_b32_e32 v123, 0xffff0000, v125
	v_lshlrev_b32_e32 v124, 16, v126
	v_and_b32_e32 v125, 0xffff0000, v126
	v_lshlrev_b32_e32 v126, 16, v127
	v_and_b32_e32 v127, 0xffff0000, v127
	v_fmac_f32_e32 v120, 0.5, v116
	v_fmac_f32_e32 v124, 0.5, v112
	v_fmac_f32_e32 v121, 0.5, v117
	v_fmac_f32_e32 v125, 0.5, v113
	v_fmac_f32_e32 v122, 0.5, v118
	v_fmac_f32_e32 v126, 0.5, v114
	v_fmac_f32_e32 v123, 0.5, v119
	v_fmac_f32_e32 v127, 0.5, v115
	v_cvt_pk_bf16_f32 v112, v120, v121
	v_cvt_pk_bf16_f32 v113, v122, v123
	v_cvt_pk_bf16_f32 v114, v124, v125
	v_cvt_pk_bf16_f32 v115, v126, v127
	global_load_dwordx4 v[116:119], v[154:155], off
	v_lshl_add_u64 v[120:121], v[146:147], 0, s[20:21]
	global_store_dwordx4 v[146:147], v[112:115], off offset:256 sc1
	s_waitcnt vmcnt(0)
	s_nop 0
	v_lshlrev_b32_e32 v112, 16, v116
	v_and_b32_e32 v113, 0xffff0000, v116
	v_lshlrev_b32_e32 v114, 16, v117
	v_and_b32_e32 v115, 0xffff0000, v117
	v_lshlrev_b32_e32 v116, 16, v118
	v_and_b32_e32 v117, 0xffff0000, v118
	v_lshlrev_b32_e32 v118, 16, v119
	v_and_b32_e32 v119, 0xffff0000, v119
	v_fmac_f32_e32 v112, 0.5, v108
	v_fmac_f32_e32 v116, 0.5, v104
	v_fmac_f32_e32 v113, 0.5, v109
	v_fmac_f32_e32 v117, 0.5, v105
	v_fmac_f32_e32 v114, 0.5, v110
	v_fmac_f32_e32 v118, 0.5, v106
	v_fmac_f32_e32 v115, 0.5, v111
	v_fmac_f32_e32 v119, 0.5, v107
	v_cvt_pk_bf16_f32 v104, v112, v113
	v_cvt_pk_bf16_f32 v105, v114, v115
	v_cvt_pk_bf16_f32 v106, v116, v117
	v_cvt_pk_bf16_f32 v107, v118, v119
	global_load_dwordx4 v[108:111], v[120:121], off offset:256
	v_add_co_u32_e32 v112, vcc, s60, v146
	global_store_dwordx4 v[154:155], v[104:107], off sc1
	s_nop 0
	v_addc_co_u32_e32 v113, vcc, 0, v147, vcc
	s_waitcnt vmcnt(0)
	v_lshlrev_b32_e32 v104, 16, v108
	v_and_b32_e32 v105, 0xffff0000, v108
	v_lshlrev_b32_e32 v106, 16, v109
	v_and_b32_e32 v107, 0xffff0000, v109
	v_lshlrev_b32_e32 v108, 16, v110
	v_and_b32_e32 v109, 0xffff0000, v110
	v_lshlrev_b32_e32 v110, 16, v111
	v_and_b32_e32 v111, 0xffff0000, v111
	v_fmac_f32_e32 v104, 0.5, v100
	v_fmac_f32_e32 v108, 0.5, v96
	v_fmac_f32_e32 v105, 0.5, v101
	v_fmac_f32_e32 v109, 0.5, v97
	v_fmac_f32_e32 v106, 0.5, v102
	v_fmac_f32_e32 v110, 0.5, v98
	v_fmac_f32_e32 v107, 0.5, v103
	v_fmac_f32_e32 v111, 0.5, v99
	v_cvt_pk_bf16_f32 v96, v104, v105
	v_cvt_pk_bf16_f32 v97, v106, v107
	v_cvt_pk_bf16_f32 v98, v108, v109
	v_cvt_pk_bf16_f32 v99, v110, v111
	global_load_dwordx4 v[100:103], v[112:113], off
	v_lshl_add_u64 v[104:105], v[146:147], 0, s[24:25]
	global_store_dwordx4 v[120:121], v[96:99], off offset:256 sc1
	s_waitcnt vmcnt(0)
	s_nop 0
	v_lshlrev_b32_e32 v96, 16, v100
	v_and_b32_e32 v97, 0xffff0000, v100
	v_lshlrev_b32_e32 v98, 16, v101
	v_and_b32_e32 v99, 0xffff0000, v101
	v_lshlrev_b32_e32 v100, 16, v102
	v_and_b32_e32 v101, 0xffff0000, v102
	v_lshlrev_b32_e32 v102, 16, v103
	v_and_b32_e32 v103, 0xffff0000, v103
	v_fmac_f32_e32 v96, 0.5, v92
	v_fmac_f32_e32 v100, 0.5, v88
	v_fmac_f32_e32 v97, 0.5, v93
	v_fmac_f32_e32 v101, 0.5, v89
	v_fmac_f32_e32 v98, 0.5, v94
	v_fmac_f32_e32 v102, 0.5, v90
	v_fmac_f32_e32 v99, 0.5, v95
	v_fmac_f32_e32 v103, 0.5, v91
	v_cvt_pk_bf16_f32 v88, v96, v97
	v_cvt_pk_bf16_f32 v89, v98, v99
	v_cvt_pk_bf16_f32 v90, v100, v101
	v_cvt_pk_bf16_f32 v91, v102, v103
	global_load_dwordx4 v[92:95], v[104:105], off offset:256
	v_add_co_u32_e32 v96, vcc, s66, v146
	global_store_dwordx4 v[112:113], v[88:91], off sc1
	s_nop 0
	v_addc_co_u32_e32 v97, vcc, 0, v147, vcc
	s_waitcnt vmcnt(0)
	v_lshlrev_b32_e32 v88, 16, v92
	v_and_b32_e32 v89, 0xffff0000, v92
	v_lshlrev_b32_e32 v90, 16, v93
	v_and_b32_e32 v91, 0xffff0000, v93
	v_lshlrev_b32_e32 v92, 16, v94
	v_and_b32_e32 v93, 0xffff0000, v94
	v_lshlrev_b32_e32 v94, 16, v95
	v_and_b32_e32 v95, 0xffff0000, v95
	v_fmac_f32_e32 v88, 0.5, v84
	v_fmac_f32_e32 v92, 0.5, v80
	v_fmac_f32_e32 v89, 0.5, v85
	v_fmac_f32_e32 v93, 0.5, v81
	v_fmac_f32_e32 v90, 0.5, v86
	v_fmac_f32_e32 v94, 0.5, v82
	v_fmac_f32_e32 v91, 0.5, v87
	v_fmac_f32_e32 v95, 0.5, v83
	v_cvt_pk_bf16_f32 v80, v88, v89
	v_cvt_pk_bf16_f32 v81, v90, v91
	v_cvt_pk_bf16_f32 v82, v92, v93
	v_cvt_pk_bf16_f32 v83, v94, v95
	global_load_dwordx4 v[84:87], v[96:97], off
	v_lshl_add_u64 v[88:89], v[146:147], 0, s[26:27]
	global_store_dwordx4 v[104:105], v[80:83], off offset:256 sc1
	s_waitcnt vmcnt(0)
; __device__ __forceinline__ unsigned pkbf(float lo, float hi) { return pg8::cvt_pk_bf16(lo, hi); }
; __device__ __forceinline__ void unpack8bf(const u32x4 w, float* f) { f[0] = bflo(w.x); f[1] = bfhi(w.x); f[2] = bflo(w.y); f[3] = bfhi(w.y); f[4] = bflo(w.z); f[5] = bfhi(w.z); f[6] = bflo(w.w); f[7] = bfhi(w.w); }
;     __device__ __forceinline__ void operator()(AccRef acc, const Unit& u, int wr, int wc, int fr, int fq) const {
;     ...
;                 for (int bj = 0; bj < 2; ++bj) {
;                     const size_t off = (size_t)(row0 + ai * 128 + m * 16) * DM + col0 + bj * 128;
;                     const u32x4 hw = *(const u32x4*)(Hb + off); float h[8]; unpack8bf(hw, h);
; #pragma unroll
;                     for (int e = 0; e < 4; ++e) { h[e] += 0.5f * acc[ai][bj][m][0][e]; h[4 + e] += 0.5f * acc[ai][bj][m][1][e]; }
;                     u32x4 w; w.x = pkbf(h[0], h[1]); w.y = pkbf(h[2], h[3]); w.z = pkbf(h[4], h[5]); w.w = pkbf(h[6], h[7]);
;                     *(u32x4*)(Hb + off) = w;
;                 }
	s_nop 0
	v_lshlrev_b32_e32 v80, 16, v84
	v_and_b32_e32 v81, 0xffff0000, v84
	v_lshlrev_b32_e32 v82, 16, v85
	v_and_b32_e32 v83, 0xffff0000, v85
	v_lshlrev_b32_e32 v84, 16, v86
	v_and_b32_e32 v85, 0xffff0000, v86
	v_lshlrev_b32_e32 v86, 16, v87
	v_and_b32_e32 v87, 0xffff0000, v87
	v_fmac_f32_e32 v80, 0.5, v76
	v_fmac_f32_e32 v84, 0.5, v72
	v_fmac_f32_e32 v81, 0.5, v77
	v_fmac_f32_e32 v85, 0.5, v73
	v_fmac_f32_e32 v82, 0.5, v78
	v_fmac_f32_e32 v86, 0.5, v74
	v_fmac_f32_e32 v83, 0.5, v79
	v_fmac_f32_e32 v87, 0.5, v75
	v_cvt_pk_bf16_f32 v72, v80, v81
	v_cvt_pk_bf16_f32 v73, v82, v83
	v_cvt_pk_bf16_f32 v74, v84, v85
	v_cvt_pk_bf16_f32 v75, v86, v87
	global_load_dwordx4 v[76:79], v[88:89], off offset:256
	v_add_co_u32_e32 v80, vcc, s71, v146
	global_store_dwordx4 v[96:97], v[72:75], off sc1
	s_nop 0
	v_addc_co_u32_e32 v81, vcc, 0, v147, vcc
	s_waitcnt vmcnt(0)
	v_lshlrev_b32_e32 v72, 16, v76
	v_and_b32_e32 v73, 0xffff0000, v76
	v_lshlrev_b32_e32 v74, 16, v77
	v_and_b32_e32 v75, 0xffff0000, v77
	v_lshlrev_b32_e32 v76, 16, v78
	v_and_b32_e32 v77, 0xffff0000, v78
	v_lshlrev_b32_e32 v78, 16, v79
	v_and_b32_e32 v79, 0xffff0000, v79
	v_fmac_f32_e32 v72, 0.5, v68
	v_fmac_f32_e32 v76, 0.5, v64
	v_fmac_f32_e32 v73, 0.5, v69
	v_fmac_f32_e32 v77, 0.5, v65
	v_fmac_f32_e32 v74, 0.5, v70
	v_fmac_f32_e32 v78, 0.5, v66
	v_fmac_f32_e32 v75, 0.5, v71
	v_fmac_f32_e32 v79, 0.5, v67
	v_cvt_pk_bf16_f32 v64, v72, v73
	v_cvt_pk_bf16_f32 v65, v74, v75
	v_cvt_pk_bf16_f32 v66, v76, v77
	v_cvt_pk_bf16_f32 v67, v78, v79
	global_load_dwordx4 v[68:71], v[80:81], off
	v_lshl_add_u64 v[72:73], v[146:147], 0, s[28:29]
	global_store_dwordx4 v[88:89], v[64:67], off offset:256 sc1
	s_waitcnt vmcnt(0)
	s_nop 0
	v_lshlrev_b32_e32 v64, 16, v68
	v_and_b32_e32 v65, 0xffff0000, v68
	v_lshlrev_b32_e32 v66, 16, v69
	v_and_b32_e32 v67, 0xffff0000, v69
	v_lshlrev_b32_e32 v68, 16, v70
	v_and_b32_e32 v69, 0xffff0000, v70
	v_lshlrev_b32_e32 v70, 16, v71
	v_and_b32_e32 v71, 0xffff0000, v71
	v_fmac_f32_e32 v64, 0.5, v60
	v_fmac_f32_e32 v68, 0.5, v56
	v_fmac_f32_e32 v65, 0.5, v61
	v_fmac_f32_e32 v69, 0.5, v57
	v_fmac_f32_e32 v66, 0.5, v62
	v_fmac_f32_e32 v70, 0.5, v58
	v_fmac_f32_e32 v67, 0.5, v63
	v_fmac_f32_e32 v71, 0.5, v59
	v_cvt_pk_bf16_f32 v56, v64, v65
	v_cvt_pk_bf16_f32 v57, v66, v67
	v_cvt_pk_bf16_f32 v58, v68, v69
	v_cvt_pk_bf16_f32 v59, v70, v71
	global_load_dwordx4 v[60:63], v[72:73], off offset:256
	v_add_co_u32_e32 v64, vcc, s72, v146
	global_store_dwordx4 v[80:81], v[56:59], off sc1
	s_nop 0
	v_addc_co_u32_e32 v65, vcc, 0, v147, vcc
	s_waitcnt vmcnt(0)
	v_lshlrev_b32_e32 v56, 16, v60
	v_and_b32_e32 v57, 0xffff0000, v60
	v_lshlrev_b32_e32 v58, 16, v61
	v_and_b32_e32 v59, 0xffff0000, v61
	v_lshlrev_b32_e32 v60, 16, v62
	v_and_b32_e32 v61, 0xffff0000, v62
	v_lshlrev_b32_e32 v62, 16, v63
	v_and_b32_e32 v63, 0xffff0000, v63
	v_fmac_f32_e32 v56, 0.5, v52
	v_fmac_f32_e32 v60, 0.5, v48
	v_fmac_f32_e32 v57, 0.5, v53
	v_fmac_f32_e32 v61, 0.5, v49
	v_fmac_f32_e32 v58, 0.5, v54
	v_fmac_f32_e32 v62, 0.5, v50
	v_fmac_f32_e32 v59, 0.5, v55
	v_fmac_f32_e32 v63, 0.5, v51
	v_cvt_pk_bf16_f32 v48, v56, v57
	v_cvt_pk_bf16_f32 v49, v58, v59
	v_cvt_pk_bf16_f32 v50, v60, v61
	v_cvt_pk_bf16_f32 v51, v62, v63
	global_load_dwordx4 v[52:55], v[64:65], off
	v_lshl_add_u64 v[56:57], v[146:147], 0, s[36:37]
	global_store_dwordx4 v[72:73], v[48:51], off offset:256 sc1
	s_waitcnt vmcnt(0)
	s_nop 0
	v_lshlrev_b32_e32 v48, 16, v52
	v_and_b32_e32 v49, 0xffff0000, v52
	v_lshlrev_b32_e32 v50, 16, v53
	v_and_b32_e32 v51, 0xffff0000, v53
	v_lshlrev_b32_e32 v52, 16, v54
	v_and_b32_e32 v53, 0xffff0000, v54
	v_lshlrev_b32_e32 v54, 16, v55
	v_and_b32_e32 v55, 0xffff0000, v55
	v_fmac_f32_e32 v48, 0.5, v44
	v_fmac_f32_e32 v52, 0.5, v40
	v_fmac_f32_e32 v49, 0.5, v45
	v_fmac_f32_e32 v53, 0.5, v41
	v_fmac_f32_e32 v50, 0.5, v46
	v_fmac_f32_e32 v54, 0.5, v42
	v_fmac_f32_e32 v51, 0.5, v47
	v_fmac_f32_e32 v55, 0.5, v43
	v_cvt_pk_bf16_f32 v40, v48, v49
	v_cvt_pk_bf16_f32 v41, v50, v51
	v_cvt_pk_bf16_f32 v42, v52, v53
	v_cvt_pk_bf16_f32 v43, v54, v55
	global_load_dwordx4 v[44:47], v[56:57], off offset:256
	v_add_co_u32_e32 v48, vcc, s73, v146
	global_store_dwordx4 v[64:65], v[40:43], off sc1
	s_nop 0
	v_addc_co_u32_e32 v49, vcc, 0, v147, vcc
	s_waitcnt vmcnt(0)
; __device__ __forceinline__ unsigned pkbf(float lo, float hi) { return pg8::cvt_pk_bf16(lo, hi); }
; __device__ __forceinline__ void unpack8bf(const u32x4 w, float* f) { f[0] = bflo(w.x); f[1] = bfhi(w.x); f[2] = bflo(w.y); f[3] = bfhi(w.y); f[4] = bflo(w.z); f[5] = bfhi(w.z); f[6] = bflo(w.w); f[7] = bfhi(w.w); }
;     __device__ __forceinline__ void operator()(AccRef acc, const Unit& u, int wr, int wc, int fr, int fq) const {
;     ...
;                 for (int bj = 0; bj < 2; ++bj) {
;                     const size_t off = (size_t)(row0 + ai * 128 + m * 16) * DM + col0 + bj * 128;
;                     const u32x4 hw = *(const u32x4*)(Hb + off); float h[8]; unpack8bf(hw, h);
; #pragma unroll
;                     for (int e = 0; e < 4; ++e) { h[e] += 0.5f * acc[ai][bj][m][0][e]; h[4 + e] += 0.5f * acc[ai][bj][m][1][e]; }
;                     u32x4 w; w.x = pkbf(h[0], h[1]); w.y = pkbf(h[2], h[3]); w.z = pkbf(h[4], h[5]); w.w = pkbf(h[6], h[7]);
;                     *(u32x4*)(Hb + off) = w;
;                 }
	v_lshlrev_b32_e32 v40, 16, v44
	v_and_b32_e32 v41, 0xffff0000, v44
	v_lshlrev_b32_e32 v42, 16, v45
	v_and_b32_e32 v43, 0xffff0000, v45
	v_lshlrev_b32_e32 v44, 16, v46
	v_and_b32_e32 v45, 0xffff0000, v46
	v_lshlrev_b32_e32 v46, 16, v47
	v_and_b32_e32 v47, 0xffff0000, v47
	v_fmac_f32_e32 v40, 0.5, v36
	v_fmac_f32_e32 v44, 0.5, v32
	v_fmac_f32_e32 v41, 0.5, v37
	v_fmac_f32_e32 v45, 0.5, v33
	v_fmac_f32_e32 v42, 0.5, v38
	v_fmac_f32_e32 v46, 0.5, v34
	v_fmac_f32_e32 v43, 0.5, v39
	v_fmac_f32_e32 v47, 0.5, v35
	v_cvt_pk_bf16_f32 v32, v40, v41
	v_cvt_pk_bf16_f32 v33, v42, v43
	v_cvt_pk_bf16_f32 v34, v44, v45
	v_cvt_pk_bf16_f32 v35, v46, v47
	global_load_dwordx4 v[36:39], v[48:49], off
	v_lshl_add_u64 v[40:41], v[146:147], 0, s[38:39]
	global_store_dwordx4 v[56:57], v[32:35], off offset:256 sc1
	s_waitcnt vmcnt(0)
	s_nop 0
	v_lshlrev_b32_e32 v32, 16, v36
	v_and_b32_e32 v33, 0xffff0000, v36
	v_lshlrev_b32_e32 v34, 16, v37
	v_and_b32_e32 v35, 0xffff0000, v37
	v_lshlrev_b32_e32 v36, 16, v38
	v_and_b32_e32 v37, 0xffff0000, v38
	v_lshlrev_b32_e32 v38, 16, v39
	v_and_b32_e32 v39, 0xffff0000, v39
	v_fmac_f32_e32 v32, 0.5, v28
	v_fmac_f32_e32 v36, 0.5, v24
	v_fmac_f32_e32 v33, 0.5, v29
	v_fmac_f32_e32 v37, 0.5, v25
	v_fmac_f32_e32 v34, 0.5, v30
	v_fmac_f32_e32 v38, 0.5, v26
	v_fmac_f32_e32 v35, 0.5, v31
	v_fmac_f32_e32 v39, 0.5, v27
	v_cvt_pk_bf16_f32 v24, v32, v33
	v_cvt_pk_bf16_f32 v25, v34, v35
	v_cvt_pk_bf16_f32 v26, v36, v37
	v_cvt_pk_bf16_f32 v27, v38, v39
	global_load_dwordx4 v[28:31], v[40:41], off offset:256
	v_add_co_u32_e32 v32, vcc, s74, v146
	global_store_dwordx4 v[48:49], v[24:27], off sc1
	s_nop 0
	v_addc_co_u32_e32 v33, vcc, 0, v147, vcc
	s_and_b64 vcc, exec, s[4:5]
	s_mov_b64 s[4:5], -1
	s_waitcnt vmcnt(0)
	v_lshlrev_b32_e32 v24, 16, v28
	v_and_b32_e32 v25, 0xffff0000, v28
	v_lshlrev_b32_e32 v26, 16, v29
	v_and_b32_e32 v27, 0xffff0000, v29
	v_lshlrev_b32_e32 v28, 16, v30
	v_and_b32_e32 v29, 0xffff0000, v30
	v_lshlrev_b32_e32 v30, 16, v31
	v_and_b32_e32 v31, 0xffff0000, v31
	v_fmac_f32_e32 v24, 0.5, v20
	v_fmac_f32_e32 v28, 0.5, v16
	v_fmac_f32_e32 v25, 0.5, v21
	v_fmac_f32_e32 v29, 0.5, v17
	v_fmac_f32_e32 v26, 0.5, v22
	v_fmac_f32_e32 v30, 0.5, v18
	v_fmac_f32_e32 v27, 0.5, v23
	v_fmac_f32_e32 v31, 0.5, v19
	v_cvt_pk_bf16_f32 v16, v24, v25
	v_cvt_pk_bf16_f32 v17, v26, v27
	v_cvt_pk_bf16_f32 v18, v28, v29
	v_cvt_pk_bf16_f32 v19, v30, v31
	global_load_dwordx4 v[20:23], v[32:33], off
	v_lshl_add_u64 v[24:25], v[146:147], 0, s[40:41]
	global_store_dwordx4 v[40:41], v[16:19], off offset:256 sc1
	s_waitcnt vmcnt(0)
	s_nop 0
	v_lshlrev_b32_e32 v16, 16, v20
	v_and_b32_e32 v17, 0xffff0000, v20
	v_lshlrev_b32_e32 v18, 16, v21
	v_and_b32_e32 v19, 0xffff0000, v21
	v_lshlrev_b32_e32 v20, 16, v22
	v_and_b32_e32 v21, 0xffff0000, v22
	v_lshlrev_b32_e32 v22, 16, v23
	v_and_b32_e32 v23, 0xffff0000, v23
	v_fmac_f32_e32 v16, 0.5, v12
	v_fmac_f32_e32 v20, 0.5, v8
	v_fmac_f32_e32 v17, 0.5, v13
	v_fmac_f32_e32 v21, 0.5, v9
	v_fmac_f32_e32 v18, 0.5, v14
	v_fmac_f32_e32 v22, 0.5, v10
	v_fmac_f32_e32 v19, 0.5, v15
	v_fmac_f32_e32 v23, 0.5, v11
	v_cvt_pk_bf16_f32 v8, v16, v17
	v_cvt_pk_bf16_f32 v9, v18, v19
	v_cvt_pk_bf16_f32 v10, v20, v21
	v_cvt_pk_bf16_f32 v11, v22, v23
	global_load_dwordx4 v[12:15], v[24:25], off offset:256
	s_nop 0
	global_store_dwordx4 v[32:33], v[8:11], off sc1
	s_waitcnt vmcnt(0)
	s_nop 0
	v_lshlrev_b32_e32 v8, 16, v12
	v_and_b32_e32 v9, 0xffff0000, v12
	v_lshlrev_b32_e32 v10, 16, v13
	v_and_b32_e32 v11, 0xffff0000, v13
	v_lshlrev_b32_e32 v12, 16, v14
	v_and_b32_e32 v13, 0xffff0000, v14
	v_lshlrev_b32_e32 v14, 16, v15
	v_and_b32_e32 v15, 0xffff0000, v15
	v_fmac_f32_e32 v8, 0.5, v4
	v_fmac_f32_e32 v12, 0.5, v0
	v_fmac_f32_e32 v9, 0.5, v5
	v_fmac_f32_e32 v13, 0.5, v1
	v_fmac_f32_e32 v10, 0.5, v6
	v_fmac_f32_e32 v14, 0.5, v2
	v_fmac_f32_e32 v11, 0.5, v7
	v_fmac_f32_e32 v15, 0.5, v3
	v_cvt_pk_bf16_f32 v0, v8, v9
	v_cvt_pk_bf16_f32 v1, v10, v11
	v_cvt_pk_bf16_f32 v2, v12, v13
	v_cvt_pk_bf16_f32 v3, v14, v15
	global_store_dwordx4 v[24:25], v[0:3], off offset:256 sc1
	s_cbranch_vccnz .LBB0_1431
	s_andn2_b64 vcc, exec, s[10:11]
	s_cbranch_vccnz .LBB0_1430
	s_barrier
	s_branch .LBB0_1430
